# trim dead epilogue VALU (canonicalize, DPP old-init), hoist P0 gain loads, drop duplicate lgkmcnt waits
# speedup vs baseline: 1.0374x; 1.0044x over previous
; __device__ __forceinline__ void norm_row(const float* xrow, const float* g, bf16_t* orow, float* xcopy, int lane) {
;     f32x4 v[8]; float s = 0.f;
; #pragma unroll
;     for (int j = 0; j < 4; ++j) { v[2 * j] = ((const f32x4*)xrow)[2 * (lane + 64 * j)]; v[2 * j + 1] = ((const f32x4*)xrow)[2 * (lane + 64 * j) + 1]; }
; #pragma unroll
;     for (int j = 0; j < 8; ++j) s += (v[j][0] * v[j][0] + v[j][1] * v[j][1]) + (v[j][2] * v[j][2] + v[j][3] * v[j][3]);
;     if (xcopy) {
; #pragma unroll
;         for (int j = 0; j < 4; ++j) { ((f32x4*)xcopy)[2 * (lane + 64 * j)] = v[2 * j]; ((f32x4*)xcopy)[2 * (lane + 64 * j) + 1] = v[2 * j + 1]; } }
;     const float rinv = 1.0f / sqrtf(wave_sum(s) * (1.f / D) + EPS);
; __global__ void __launch_bounds__(NTHREADS, 2) fwd_megakernel(Params P) {
;     ...
;         _Pragma("unroll 1") for (int rp_ = 0; rp_ < REP_PREP; ++rp_) for (int row = gw; row < M; row += ngw) {
;             const float* xr = row < 8192 ? kp->in[I_XP] + (size_t)row * D : kp->in[I_XS] + (size_t)(row - 8192) * D;
;             norm_row(xr, kp->in[I_ATTN_NORM], H + (size_t)row * D, nullptr, lane);
.LBB0_34:
	v_lshl_add_u64 v[90:91], s[34:35], 0, v[26:27]
	v_add_co_u32_e32 v100, vcc, s38, v90
	s_nop 1
	global_load_dwordx4 v[108:111], v26, s[34:35]
	global_load_dwordx4 v[112:115], v26, s[34:35] offset:16
	global_load_dwordx4 v[116:119], v26, s[34:35] offset:2048
	global_load_dwordx4 v[120:123], v26, s[34:35] offset:2064
	v_addc_co_u32_e32 v101, vcc, 0, v91, vcc
	s_nop 1
	global_load_dwordx4 v[124:127], v[100:101], off
	v_lshl_add_u64 v[102:103], v[90:91], 0, s[28:29]
	global_load_dwordx4 v[128:131], v[102:103], off offset:16
	global_load_dwordx4 v[132:135], v[100:101], off offset:2048
	v_lshl_add_u64 v[104:105], v[90:91], 0, s[30:31]
	global_load_dwordx4 v[136:139], v[104:105], off offset:16
	global_load_dwordx4 v[140:143], v[28:29], off
	global_load_dwordx4 v[148:151], v[28:29], off offset:16
	global_load_dwordx4 v[152:155], v[30:31], off
	global_load_dwordx4 v[156:159], v[30:31], off offset:16
	global_load_dwordx4 v[160:163], v[32:33], off
	global_load_dwordx4 v[164:167], v[32:33], off offset:16
	global_load_dwordx4 v[168:171], v[34:35], off
	global_load_dwordx4 v[172:175], v[34:35], off offset:16
	v_lshl_add_u64 v[4:5], s[34:35], 0, v[26:27]
	v_add_co_u32_e32 v6, vcc, s38, v4
	s_waitcnt vmcnt(15)
	s_nop 0
	v_mov_b64_e32 v[46:47], v[108:109]
	v_mov_b64_e32 v[48:49], v[110:111]
	s_nop 1
	s_waitcnt vmcnt(14)
	s_nop 0
	v_mov_b64_e32 v[50:51], v[112:113]
	v_mov_b64_e32 v[52:53], v[114:115]
	s_nop 1
	s_waitcnt vmcnt(13)
	s_nop 0
	v_mov_b64_e32 v[20:21], v[116:117]
	v_mov_b64_e32 v[22:23], v[118:119]
	s_nop 1
	s_waitcnt vmcnt(12)
	s_nop 0
	v_mov_b64_e32 v[16:17], v[120:121]
	v_mov_b64_e32 v[18:19], v[122:123]
	s_nop 1
	v_addc_co_u32_e32 v7, vcc, 0, v5, vcc
	s_waitcnt vmcnt(11)
	s_nop 0
	v_mov_b64_e32 v[12:13], v[124:125]
	v_mov_b64_e32 v[14:15], v[126:127]
	s_nop 1
	v_lshl_add_u64 v[54:55], v[4:5], 0, s[28:29]
	s_waitcnt vmcnt(10)
	s_nop 0
	v_mov_b64_e32 v[8:9], v[128:129]
	v_mov_b64_e32 v[10:11], v[130:131]
	s_nop 1
	s_waitcnt vmcnt(9)
	s_nop 0
	v_mov_b64_e32 v[0:1], v[132:133]
	v_mov_b64_e32 v[2:3], v[134:135]
	s_nop 1
	v_lshl_add_u64 v[58:59], v[4:5], 0, s[30:31]
	s_waitcnt vmcnt(8)
	s_nop 0
	v_mov_b64_e32 v[4:5], v[136:137]
	v_mov_b64_e32 v[6:7], v[138:139]
	s_nop 1
	s_waitcnt vmcnt(7)
	s_nop 0
	v_mov_b64_e32 v[54:55], v[140:141]
	v_mov_b64_e32 v[56:57], v[142:143]
	s_nop 1
	s_lshl_b64 s[34:35], s[4:5], 12
	s_add_u32 s10, s10, s26
	s_addc_u32 s11, s11, s27
	s_add_u32 s16, s16, s18
	s_addc_u32 s17, s17, s19
	s_cmpk_gt_i32 s10, 0x3fff
	v_mul_f32_e32 v45, v47, v47
	v_mul_f32_e32 v58, v49, v49
	v_mul_f32_e32 v59, v51, v51
	v_mul_f32_e32 v60, v53, v53
	v_mul_f32_e32 v61, v21, v21
	v_mul_f32_e32 v62, v23, v23
	v_fmac_f32_e32 v45, v46, v46
	v_fmac_f32_e32 v58, v48, v48
	v_fmac_f32_e32 v59, v50, v50
	v_fmac_f32_e32 v60, v52, v52
	v_mul_f32_e32 v63, v17, v17
	v_mul_f32_e32 v64, v19, v19
	v_fmac_f32_e32 v61, v20, v20
	v_fmac_f32_e32 v62, v22, v22
	v_add_f32_e32 v45, v45, v58
	v_add_f32_e32 v58, v59, v60
	v_fmac_f32_e32 v63, v16, v16
	v_fmac_f32_e32 v64, v18, v18
	v_add_f32_e32 v59, v61, v62
	v_add_f32_e32 v45, v45, v58
	v_mul_f32_e32 v58, v13, v13
	v_mul_f32_e32 v61, v15, v15
	v_add_f32_e32 v60, v63, v64
	v_mul_f32_e32 v62, v9, v9
	v_mul_f32_e32 v63, v11, v11
	v_add_f32_e32 v45, v45, v59
	v_fmac_f32_e32 v58, v12, v12
	v_fmac_f32_e32 v61, v14, v14
	v_mul_f32_e32 v64, v1, v1
	v_mul_f32_e32 v65, v3, v3
	v_fmac_f32_e32 v62, v8, v8
	v_fmac_f32_e32 v63, v10, v10
	v_add_f32_e32 v45, v45, v60
	v_add_f32_e32 v58, v58, v61
	v_mul_f32_e32 v66, v5, v5
	v_mul_f32_e32 v67, v7, v7
	v_fmac_f32_e32 v64, v0, v0
	v_fmac_f32_e32 v65, v2, v2
	v_add_f32_e32 v59, v62, v63
	v_add_f32_e32 v45, v45, v58
	v_fmac_f32_e32 v66, v4, v4
	v_fmac_f32_e32 v67, v6, v6
	v_add_f32_e32 v60, v64, v65
	v_add_f32_e32 v45, v45, v59
	v_add_f32_e32 v61, v66, v67
	v_add_f32_e32 v45, v45, v60
	v_add_f32_e32 v45, v45, v61
	s_waitcnt vmcnt(6)
	s_nop 0
	v_mov_b64_e32 v[58:59], v[148:149]
	v_mov_b64_e32 v[60:61], v[150:151]
	s_nop 1
	ds_bpermute_b32 v62, v25, v45
	s_waitcnt lgkmcnt(0)
	v_add_f32_e32 v45, v45, v62
	ds_bpermute_b32 v62, v38, v45
	s_waitcnt lgkmcnt(0)
	v_add_f32_e32 v45, v45, v62
	ds_bpermute_b32 v62, v39, v45
	s_waitcnt lgkmcnt(0)
	v_add_f32_e32 v45, v45, v62
	ds_bpermute_b32 v62, v40, v45
	s_waitcnt lgkmcnt(0)
	v_add_f32_e32 v45, v45, v62
	ds_bpermute_b32 v62, v41, v45
	s_waitcnt lgkmcnt(0)
; __device__ __forceinline__ unsigned cvt_pk_bf16(float lo, float hi) { unsigned r; asm volatile("v_cvt_pk_bf16_f32 %0, %1, %2" : "=v"(r) : "v"(lo), "v"(hi)); return r; }
; __device__ __forceinline__ void norm_row(const float* xrow, const float* g, bf16_t* orow, float* xcopy, int lane) {
;     ...
;     const float rinv = 1.0f / sqrtf(wave_sum(s) * (1.f / D) + EPS);
; #pragma unroll
;     for (int j = 0; j < 4; ++j) { const f32x4 g0 = ((const f32x4*)g)[2 * (lane + 64 * j)], g1 = ((const f32x4*)g)[2 * (lane + 64 * j) + 1]; const f32x4 a = v[2 * j], c = v[2 * j + 1];
;         u32x4 w; w.x = cvt_pk_bf16(a[0] * rinv * g0[0], a[1] * rinv * g0[1]); w.y = cvt_pk_bf16(a[2] * rinv * g0[2], a[3] * rinv * g0[3]);
;         w.z = cvt_pk_bf16(c[0] * rinv * g1[0], c[1] * rinv * g1[1]); w.w = cvt_pk_bf16(c[2] * rinv * g1[2], c[3] * rinv * g1[3]);
;         ((u32x4*)orow)[lane + 64 * j] = w; }
	v_add_f32_e32 v45, v45, v62
	ds_bpermute_b32 v62, v42, v45
	s_waitcnt lgkmcnt(0)
	v_add_f32_e32 v45, v45, v62
	v_fmamk_f32 v45, v45, 0x3a000000, v43
	v_mul_f32_e32 v62, 0x4f800000, v45
	v_cmp_gt_f32_e32 vcc, s39, v45
	s_nop 1
	v_cndmask_b32_e32 v45, v45, v62, vcc
	v_sqrt_f32_e32 v62, v45
	s_nop 0
	v_add_u32_e32 v63, -1, v62
	v_add_u32_e32 v64, 1, v62
	v_fma_f32 v65, -v63, v62, v45
	v_fma_f32 v66, -v64, v62, v45
	v_cmp_ge_f32_e64 s[4:5], 0, v65
	s_nop 1
	v_cndmask_b32_e64 v62, v62, v63, s[4:5]
	v_cmp_lt_f32_e64 s[4:5], 0, v66
	s_nop 1
	v_cndmask_b32_e64 v62, v62, v64, s[4:5]
	v_mul_f32_e32 v63, 0x37800000, v62
	v_cndmask_b32_e32 v62, v62, v63, vcc
	v_cmp_class_f32_e32 vcc, v45, v44
	s_nop 1
	v_cndmask_b32_e32 v45, v62, v45, vcc
	v_div_scale_f32 v64, s[4:5], v45, v45, 1.0
	v_rcp_f32_e32 v65, v64
	v_div_scale_f32 v66, vcc, 1.0, v45, 1.0
	v_lshl_add_u64 v[62:63], v[36:37], 0, s[34:35]
	v_fma_f32 v67, -v64, v65, 1.0
	v_fmac_f32_e32 v65, v67, v65
	v_mul_f32_e32 v67, v66, v65
	v_fma_f32 v68, -v64, v67, v66
	v_fmac_f32_e32 v67, v68, v65
	v_fma_f32 v64, -v64, v67, v66
	v_div_fmas_f32 v64, v64, v65, v67
	v_div_fixup_f32 v45, v64, v45, 1.0
	v_mul_f32_e32 v46, v46, v45
	v_mul_f32_e32 v47, v47, v45
	v_mul_f32_e32 v48, v48, v45
	v_mul_f32_e32 v49, v49, v45
	v_mul_f32_e32 v50, v50, v45
	v_mul_f32_e32 v51, v51, v45
	v_mul_f32_e32 v52, v52, v45
	v_mul_f32_e32 v53, v53, v45
	v_mul_f32_e32 v46, v54, v46
	v_mul_f32_e32 v47, v55, v47
	v_mul_f32_e32 v48, v56, v48
	v_mul_f32_e32 v49, v57, v49
	v_mul_f32_e32 v50, v58, v50
	v_mul_f32_e32 v51, v59, v51
	v_mul_f32_e32 v52, v60, v52
	v_mul_f32_e32 v53, v61, v53
	v_cvt_pk_bf16_f32 v46, v46, v47
	v_cvt_pk_bf16_f32 v47, v48, v49
	v_cvt_pk_bf16_f32 v48, v50, v51
	v_cvt_pk_bf16_f32 v49, v52, v53
	global_store_dwordx4 v[62:63], v[46:49], off
	s_waitcnt vmcnt(6)
	s_nop 0
	v_mov_b64_e32 v[46:47], v[152:153]
	v_mov_b64_e32 v[48:49], v[154:155]
	s_nop 1
	s_nop 0
	s_waitcnt vmcnt(5)
	s_nop 0
	v_mov_b64_e32 v[50:51], v[156:157]
	v_mov_b64_e32 v[52:53], v[158:159]
	s_nop 1
	v_mul_f32_e32 v19, v19, v45
	v_mul_f32_e32 v20, v20, v45
	v_mul_f32_e32 v21, v21, v45
	v_mul_f32_e32 v22, v22, v45
	v_mul_f32_e32 v23, v23, v45
	v_mul_f32_e32 v16, v16, v45
	v_mul_f32_e32 v17, v17, v45
	v_mul_f32_e32 v18, v18, v45
	v_mul_f32_e32 v11, v11, v45
	v_mul_f32_e32 v12, v12, v45
	v_mul_f32_e32 v13, v13, v45
	v_mul_f32_e32 v14, v14, v45
	v_mul_f32_e32 v15, v15, v45
	v_mul_f32_e32 v8, v8, v45
	v_mul_f32_e32 v9, v9, v45
	v_mul_f32_e32 v10, v10, v45
	v_mul_f32_e32 v0, v0, v45
	v_mul_f32_e32 v1, v1, v45
	v_mul_f32_e32 v2, v2, v45
	v_mul_f32_e32 v3, v3, v45
	v_mul_f32_e32 v4, v4, v45
	v_mul_f32_e32 v5, v5, v45
	v_mul_f32_e32 v6, v6, v45
	v_mul_f32_e32 v7, v7, v45
	v_mul_f32_e32 v20, v20, v46
	v_mul_f32_e32 v19, v19, v53
	v_mul_f32_e32 v21, v21, v47
	v_mul_f32_e32 v22, v22, v48
	v_mul_f32_e32 v23, v23, v49
	v_mul_f32_e32 v46, v16, v50
	v_mul_f32_e32 v47, v17, v51
	v_mul_f32_e32 v48, v18, v52
	v_cvt_pk_bf16_f32 v16, v20, v21
	v_cvt_pk_bf16_f32 v17, v22, v23
	v_cvt_pk_bf16_f32 v18, v46, v47
	v_cvt_pk_bf16_f32 v19, v48, v19
	global_store_dwordx4 v[62:63], v[16:19], off offset:1024
	s_waitcnt vmcnt(5)
	s_nop 0
	v_mov_b64_e32 v[16:17], v[160:161]
	v_mov_b64_e32 v[18:19], v[162:163]
	s_nop 1
	s_nop 0
	s_waitcnt vmcnt(4)
	s_nop 0
	v_mov_b64_e32 v[20:21], v[164:165]
	v_mov_b64_e32 v[22:23], v[166:167]
	s_nop 1
	v_mul_f32_e32 v12, v12, v16
	v_mul_f32_e32 v11, v11, v23
	v_mul_f32_e32 v13, v13, v17
	v_mul_f32_e32 v14, v14, v18
	v_mul_f32_e32 v15, v15, v19
	v_mul_f32_e32 v16, v8, v20
	v_mul_f32_e32 v17, v9, v21
	v_mul_f32_e32 v18, v10, v22
	v_cvt_pk_bf16_f32 v8, v12, v13
	v_cvt_pk_bf16_f32 v9, v14, v15
	v_cvt_pk_bf16_f32 v10, v16, v17
	v_cvt_pk_bf16_f32 v11, v18, v11
	global_store_dwordx4 v[62:63], v[8:11], off offset:2048
	s_waitcnt vmcnt(4)
	s_nop 0
	v_mov_b64_e32 v[8:9], v[168:169]
	v_mov_b64_e32 v[10:11], v[170:171]
	s_nop 1
	s_nop 0
	s_waitcnt vmcnt(3)
	s_nop 0
	v_mov_b64_e32 v[12:13], v[172:173]
	v_mov_b64_e32 v[14:15], v[174:175]
	s_nop 1
	v_mul_f32_e32 v0, v0, v8
	v_mul_f32_e32 v1, v1, v9
	v_mul_f32_e32 v2, v2, v10
	v_mul_f32_e32 v3, v3, v11
	v_mul_f32_e32 v4, v4, v12
	v_mul_f32_e32 v5, v5, v13
	v_mul_f32_e32 v6, v6, v14
	v_mul_f32_e32 v7, v7, v15
	v_cvt_pk_bf16_f32 v0, v0, v1
	v_cvt_pk_bf16_f32 v1, v2, v3
	v_cvt_pk_bf16_f32 v2, v4, v5
	v_cvt_pk_bf16_f32 v3, v6, v7
	global_store_dwordx4 v[62:63], v[0:3], off offset:3072
	s_cbranch_scc1 .LBB0_39

; #define PG8_STAGE(bufoff, gbase, voff) do { _Pragma("unroll") for (int _i = 0; _i < 2; ++_i) \
;         __builtin_amdgcn_global_load_lds((const unsigned*)((const char*)(gbase) + (voff)[_i]), (LAS unsigned*)(lds + (bufoff) + ldsw + _i * 8192), 16, 0, 0); } while (0)
; #define PG8_LDA(dst, b, h) do { _Pragma("unroll") for (int m = 0; m < 4; ++m) _Pragma("unroll") for (int k = 0; k < 2; ++k) dst[m][k] = *(const LAS bf16x8*)(lds + PG8_SA(b, h) + aoff + m * 2048 + k * 1024); } while (0)
; #define PG8_LDB(dst, b, h) do { _Pragma("unroll") for (int n = 0; n < 2; ++n) _Pragma("unroll") for (int k = 0; k < 2; ++k) dst[n][k] = *(const LAS bf16x8*)(lds + PG8_SB(b, h) + boff + n * 2048 + k * 1024); } while (0)
; #define PG8_MMA(ai, bj, At, Bt) do { __builtin_amdgcn_s_setprio(1); _Pragma("unroll") for (int m = 0; m < 4; ++m) _Pragma("unroll") for (int n = 0; n < 2; ++n) _Pragma("unroll") for (int k = 0; k < 2; ++k) \
;         acc[ai][bj][m][n] = __builtin_amdgcn_mfma_f32_16x16x32_bf16(Bt[n][k], At[m][k], acc[ai][bj][m][n], 0, 0, 0); __builtin_amdgcn_s_setprio(0); } while (0)
; #define PG8_WAIT_V(n) asm volatile("s_waitcnt vmcnt(" #n ")" ::: "memory")
; #define PG8_WAIT_L(n) asm volatile("s_waitcnt lgkmcnt(" #n ")" ::: "memory")
; #define PG8_BAR __builtin_amdgcn_s_barrier()
; template <class Epi>
; __device__ __forceinline__ void gemm_phase(LAS unsigned char* lds, const Gemm g, const StaticOrder& S, const Epi& E) {
;     ...
;         for (int t = 0; t < nt; t += 2) {
;             const bool last = (t == nt - 2);
;             const char* a1 = cA + (size_t)(t + 1) * kstep;
;             const char* a2 = last ? nA : cA + (size_t)(t + 2) * kstep; const char* b2 = last ? nB : cB + (size_t)(t + 2) * kstep;
;             const char* a3 = a2 + kstep; const char* b3 = b2 + kstep;
;             PG8_LDB(B0, 0, 0); PG8_SCHED; PG8_LDA(At, 0, 0); PG8_STAGE(PG8_SA(1, 1), a1 + hstep, voffA);
;             PG8_WAIT_L(8); PG8_BAR; PG8_WAIT_L(0); PG8_MMA(0, 0, At, B0); PG8_BAR; PG8_SCHED;
;             PG8_LDB(B1, 0, 1); PG8_STAGE(PG8_SB(0, 0), b2, voffB0);
;             PG8_BAR; PG8_WAIT_L(0); PG8_MMA(0, 1, At, B1); PG8_BAR;
;             PG8_LDA(At, 0, 1); PG8_STAGE(PG8_SA(0, 0), a2, voffA);
;             PG8_BAR; PG8_WAIT_L(0); PG8_MMA(1, 0, At, B0); PG8_BAR; PG8_SCHED;
;             PG8_STAGE(PG8_SB(0, 1), b2, voffB1);
;             PG8_WAIT_V(6); PG8_BAR; PG8_MMA(1, 1, At, B1); PG8_BAR;
.LBB0_107:
	ds_read_b128 v[162:165], v158
	ds_read_b128 v[166:169], v158 offset:1024
	ds_read_b128 v[170:173], v158 offset:2048
	ds_read_b128 v[174:177], v158 offset:3072
	s_add_u32 s33, s34, 0xfff80080
	s_addc_u32 s36, s35, -1
	s_cmp_eq_u32 s63, 28
	s_cselect_b32 s37, s13, s36
	s_cselect_b32 s36, s59, s33
	s_cselect_b32 s39, s11, s62
	s_cselect_b32 s38, s60, s61
	v_lshl_add_u64 v[212:213], s[34:35], 0, v[140:141]
	s_add_i32 m0, s31, 0xc000
	ds_read_b128 v[178:181], v159
	ds_read_b128 v[182:185], v159 offset:1024
	ds_read_b128 v[186:189], v159 offset:2048
	ds_read_b128 v[190:193], v159 offset:3072
	ds_read_b128 v[194:197], v159 offset:4096
	ds_read_b128 v[198:201], v159 offset:5120
	ds_read_b128 v[204:207], v159 offset:6144
	ds_read_b128 v[208:211], v159 offset:7168
	global_load_lds_dwordx4 v[212:213], off
	v_lshl_add_u64 v[212:213], s[34:35], 0, v[142:143]
	s_add_i32 m0, s31, 0xe000
	s_nop 0
	global_load_lds_dwordx4 v[212:213], off
	s_waitcnt lgkmcnt(8)
	s_barrier
	s_waitcnt lgkmcnt(0)
	v_mfma_f32_16x16x32_bf16 v[124:127], v[162:165], v[178:181], v[124:127]
	v_mfma_f32_16x16x32_bf16 v[120:123], v[170:173], v[178:181], v[120:123]
	v_mfma_f32_16x16x32_bf16 v[108:111], v[162:165], v[186:189], v[108:111]
	v_mfma_f32_16x16x32_bf16 v[104:107], v[170:173], v[186:189], v[104:107]
	v_mfma_f32_16x16x32_bf16 v[92:95], v[162:165], v[194:197], v[92:95]
	v_mfma_f32_16x16x32_bf16 v[88:91], v[170:173], v[194:197], v[88:91]
	v_mfma_f32_16x16x32_bf16 v[76:79], v[162:165], v[204:207], v[76:79]
	v_mfma_f32_16x16x32_bf16 v[72:75], v[170:173], v[204:207], v[72:75]
	v_mfma_f32_16x16x32_bf16 v[124:127], v[166:169], v[182:185], v[124:127]
	v_mfma_f32_16x16x32_bf16 v[120:123], v[174:177], v[182:185], v[120:123]
	v_mfma_f32_16x16x32_bf16 v[108:111], v[166:169], v[190:193], v[108:111]
	v_mfma_f32_16x16x32_bf16 v[104:107], v[174:177], v[190:193], v[104:107]
	v_mfma_f32_16x16x32_bf16 v[92:95], v[166:169], v[198:201], v[92:95]
	v_mfma_f32_16x16x32_bf16 v[88:91], v[174:177], v[198:201], v[88:91]
	v_mfma_f32_16x16x32_bf16 v[76:79], v[166:169], v[208:211], v[76:79]
	v_mfma_f32_16x16x32_bf16 v[72:75], v[174:177], v[208:211], v[72:75]
	s_barrier
	s_add_i32 s33, s56, s44
	v_lshl_add_u64 v[228:229], s[38:39], 0, v[134:135]
	s_mov_b32 m0, s33
	ds_read_b128 v[212:215], v160
	ds_read_b128 v[216:219], v160 offset:1024
	ds_read_b128 v[220:223], v160 offset:2048
	ds_read_b128 v[224:227], v160 offset:3072
	global_load_lds_dwordx4 v[228:229], off
	v_lshl_add_u64 v[230:231], s[38:39], 0, v[128:129]
	s_add_i32 m0, s33, 0x2000
	s_nop 0
	global_load_lds_dwordx4 v[230:231], off
	s_barrier
	s_waitcnt lgkmcnt(0)
	v_mfma_f32_16x16x32_bf16 v[116:119], v[212:215], v[178:181], v[116:119]
	v_mfma_f32_16x16x32_bf16 v[112:115], v[220:223], v[178:181], v[112:115]
	v_mfma_f32_16x16x32_bf16 v[100:103], v[212:215], v[186:189], v[100:103]
	v_mfma_f32_16x16x32_bf16 v[96:99], v[220:223], v[186:189], v[96:99]
	v_mfma_f32_16x16x32_bf16 v[84:87], v[212:215], v[194:197], v[84:87]
	v_mfma_f32_16x16x32_bf16 v[80:83], v[220:223], v[194:197], v[80:83]
	v_mfma_f32_16x16x32_bf16 v[68:71], v[212:215], v[204:207], v[68:71]
	v_mfma_f32_16x16x32_bf16 v[64:67], v[220:223], v[204:207], v[64:67]
	v_mfma_f32_16x16x32_bf16 v[116:119], v[216:219], v[182:185], v[116:119]
	v_mfma_f32_16x16x32_bf16 v[112:115], v[224:227], v[182:185], v[112:115]
	v_mfma_f32_16x16x32_bf16 v[100:103], v[216:219], v[190:193], v[100:103]
	v_mfma_f32_16x16x32_bf16 v[96:99], v[224:227], v[190:193], v[96:99]
	v_mfma_f32_16x16x32_bf16 v[84:87], v[216:219], v[198:201], v[84:87]
	v_mfma_f32_16x16x32_bf16 v[80:83], v[224:227], v[198:201], v[80:83]
	v_mfma_f32_16x16x32_bf16 v[68:71], v[216:219], v[208:211], v[68:71]
	v_mfma_f32_16x16x32_bf16 v[64:67], v[224:227], v[208:211], v[64:67]
	s_mov_b32 m0, s31
	v_lshl_add_u64 v[232:233], s[36:37], 0, v[138:139]
	s_barrier
	ds_read_b128 v[178:181], v159 offset:16384
	ds_read_b128 v[182:185], v159 offset:17408
	ds_read_b128 v[186:189], v159 offset:18432
	ds_read_b128 v[190:193], v159 offset:19456
	ds_read_b128 v[194:197], v159 offset:20480
	ds_read_b128 v[198:201], v159 offset:21504
	ds_read_b128 v[204:207], v159 offset:22528
	ds_read_b128 v[208:211], v159 offset:23552
	global_load_lds_dwordx4 v[232:233], off
	v_lshl_add_u64 v[234:235], s[36:37], 0, v[132:133]
	s_mov_b32 m0, s46
	s_nop 0
	global_load_lds_dwordx4 v[234:235], off
	s_barrier
	s_waitcnt lgkmcnt(0)
	v_mfma_f32_16x16x32_bf16 v[60:63], v[162:165], v[178:181], v[60:63]
	v_mfma_f32_16x16x32_bf16 v[56:59], v[170:173], v[178:181], v[56:59]
	v_mfma_f32_16x16x32_bf16 v[44:47], v[162:165], v[186:189], v[44:47]
	v_mfma_f32_16x16x32_bf16 v[40:43], v[170:173], v[186:189], v[40:43]
	v_mfma_f32_16x16x32_bf16 v[28:31], v[162:165], v[194:197], v[28:31]
	v_mfma_f32_16x16x32_bf16 v[24:27], v[170:173], v[194:197], v[24:27]
	v_mfma_f32_16x16x32_bf16 v[12:15], v[162:165], v[204:207], v[12:15]
	v_mfma_f32_16x16x32_bf16 v[8:11], v[170:173], v[204:207], v[8:11]
	v_mfma_f32_16x16x32_bf16 v[60:63], v[166:169], v[182:185], v[60:63]
	v_mfma_f32_16x16x32_bf16 v[56:59], v[174:177], v[182:185], v[56:59]
	v_mfma_f32_16x16x32_bf16 v[44:47], v[166:169], v[190:193], v[44:47]
	v_mfma_f32_16x16x32_bf16 v[40:43], v[174:177], v[190:193], v[40:43]
	v_mfma_f32_16x16x32_bf16 v[28:31], v[166:169], v[198:201], v[28:31]
	v_mfma_f32_16x16x32_bf16 v[24:27], v[174:177], v[198:201], v[24:27]
	v_mfma_f32_16x16x32_bf16 v[12:15], v[166:169], v[208:211], v[12:15]
	v_mfma_f32_16x16x32_bf16 v[8:11], v[174:177], v[208:211], v[8:11]
	s_barrier
	s_add_i32 s33, s57, s44
	v_lshl_add_u64 v[236:237], s[38:39], 0, v[136:137]
	s_mov_b32 m0, s33
	v_lshl_add_u64 v[238:239], s[38:39], 0, v[130:131]
	global_load_lds_dwordx4 v[236:237], off
	s_add_i32 m0, s33, 0x2000
	s_nop 0
	global_load_lds_dwordx4 v[238:239], off
	s_waitcnt vmcnt(6)
	s_barrier
; #define PG8_STAGE(bufoff, gbase, voff) do { _Pragma("unroll") for (int _i = 0; _i < 2; ++_i) \
;         __builtin_amdgcn_global_load_lds((const unsigned*)((const char*)(gbase) + (voff)[_i]), (LAS unsigned*)(lds + (bufoff) + ldsw + _i * 8192), 16, 0, 0); } while (0)
; #define PG8_LDA(dst, b, h) do { _Pragma("unroll") for (int m = 0; m < 4; ++m) _Pragma("unroll") for (int k = 0; k < 2; ++k) dst[m][k] = *(const LAS bf16x8*)(lds + PG8_SA(b, h) + aoff + m * 2048 + k * 1024); } while (0)
; #define PG8_LDB(dst, b, h) do { _Pragma("unroll") for (int n = 0; n < 2; ++n) _Pragma("unroll") for (int k = 0; k < 2; ++k) dst[n][k] = *(const LAS bf16x8*)(lds + PG8_SB(b, h) + boff + n * 2048 + k * 1024); } while (0)
; #define PG8_MMA(ai, bj, At, Bt) do { __builtin_amdgcn_s_setprio(1); _Pragma("unroll") for (int m = 0; m < 4; ++m) _Pragma("unroll") for (int n = 0; n < 2; ++n) _Pragma("unroll") for (int k = 0; k < 2; ++k) \
;         acc[ai][bj][m][n] = __builtin_amdgcn_mfma_f32_16x16x32_bf16(Bt[n][k], At[m][k], acc[ai][bj][m][n], 0, 0, 0); __builtin_amdgcn_s_setprio(0); } while (0)
; #define PG8_WAIT_V(n) asm volatile("s_waitcnt vmcnt(" #n ")" ::: "memory")
; #define PG8_WAIT_L(n) asm volatile("s_waitcnt lgkmcnt(" #n ")" ::: "memory")
; #define PG8_BAR __builtin_amdgcn_s_barrier()
; #define PG8_SCHED __builtin_amdgcn_sched_barrier(0)
; template <class Epi>
; __device__ __forceinline__ void gemm_phase(LAS unsigned char* lds, const Gemm g, const StaticOrder& S, const Epi& E) {
;     ...
;             PG8_WAIT_V(6); PG8_BAR; PG8_MMA(1, 1, At, B1); PG8_BAR;
;             PG8_LDB(B0, 1, 0); PG8_SCHED; PG8_LDA(At, 1, 0); PG8_STAGE(PG8_SA(0, 1), a2 + hstep, voffA);
;             PG8_WAIT_L(8); PG8_BAR; PG8_WAIT_L(0); PG8_MMA(0, 0, At, B0); PG8_BAR; PG8_SCHED;
;             PG8_LDB(B1, 1, 1); PG8_STAGE(PG8_SB(1, 0), b3, voffB0);
;             PG8_BAR; PG8_WAIT_L(0); PG8_MMA(0, 1, At, B1); PG8_BAR;
;             PG8_LDA(At, 1, 1); PG8_STAGE(PG8_SA(1, 0), a3, voffA);
;             PG8_BAR; PG8_WAIT_L(0); PG8_MMA(1, 0, At, B0); PG8_BAR; PG8_SCHED;
;             PG8_STAGE(PG8_SB(1, 1), b3, voffB1);
	v_mfma_f32_16x16x32_bf16 v[52:55], v[212:215], v[178:181], v[52:55]
	v_mfma_f32_16x16x32_bf16 v[48:51], v[220:223], v[178:181], v[48:51]
	v_mfma_f32_16x16x32_bf16 v[36:39], v[212:215], v[186:189], v[36:39]
	v_mfma_f32_16x16x32_bf16 v[32:35], v[220:223], v[186:189], v[32:35]
	v_mfma_f32_16x16x32_bf16 v[20:23], v[212:215], v[194:197], v[20:23]
	v_mfma_f32_16x16x32_bf16 v[16:19], v[220:223], v[194:197], v[16:19]
	v_mfma_f32_16x16x32_bf16 v[4:7], v[212:215], v[204:207], v[4:7]
	v_mfma_f32_16x16x32_bf16 v[0:3], v[220:223], v[204:207], v[0:3]
	v_mfma_f32_16x16x32_bf16 v[52:55], v[216:219], v[182:185], v[52:55]
	v_mfma_f32_16x16x32_bf16 v[48:51], v[224:227], v[182:185], v[48:51]
	v_mfma_f32_16x16x32_bf16 v[36:39], v[216:219], v[190:193], v[36:39]
	v_mfma_f32_16x16x32_bf16 v[32:35], v[224:227], v[190:193], v[32:35]
	v_mfma_f32_16x16x32_bf16 v[20:23], v[216:219], v[198:201], v[20:23]
	v_mfma_f32_16x16x32_bf16 v[16:19], v[224:227], v[198:201], v[16:19]
	v_mfma_f32_16x16x32_bf16 v[4:7], v[216:219], v[208:211], v[4:7]
	v_mfma_f32_16x16x32_bf16 v[0:3], v[224:227], v[208:211], v[0:3]
	s_add_i32 s33, 0, 0x18000
	v_add_u32_e32 v161, s33, v148
	s_barrier
	ds_read_b128 v[162:165], v161
	ds_read_b128 v[166:169], v161 offset:1024
	ds_read_b128 v[170:173], v161 offset:2048
	ds_read_b128 v[174:177], v161 offset:3072
	s_add_u32 s36, s36, 0x80000
	s_addc_u32 s37, s37, 0
	s_mov_b32 m0, s47
	v_lshl_add_u64 v[212:213], s[36:37], 0, v[138:139]
	ds_read_b128 v[178:181], v159 offset:32768
	ds_read_b128 v[182:185], v159 offset:33792
	ds_read_b128 v[186:189], v159 offset:34816
	ds_read_b128 v[190:193], v159 offset:35840
	ds_read_b128 v[194:197], v159 offset:36864
	ds_read_b128 v[198:201], v159 offset:37888
	ds_read_b128 v[204:207], v159 offset:38912
	ds_read_b128 v[208:211], v159 offset:39936
	global_load_lds_dwordx4 v[212:213], off
	v_lshl_add_u64 v[212:213], s[36:37], 0, v[132:133]
	s_mov_b32 m0, s48
	s_nop 0
	global_load_lds_dwordx4 v[212:213], off
	s_waitcnt lgkmcnt(8)
	s_barrier
	s_waitcnt lgkmcnt(0)
	v_mfma_f32_16x16x32_bf16 v[124:127], v[162:165], v[178:181], v[124:127]
	v_mfma_f32_16x16x32_bf16 v[120:123], v[170:173], v[178:181], v[120:123]
	v_mfma_f32_16x16x32_bf16 v[108:111], v[162:165], v[186:189], v[108:111]
	v_mfma_f32_16x16x32_bf16 v[104:107], v[170:173], v[186:189], v[104:107]
	v_mfma_f32_16x16x32_bf16 v[92:95], v[162:165], v[194:197], v[92:95]
	v_mfma_f32_16x16x32_bf16 v[88:91], v[170:173], v[194:197], v[88:91]
	v_mfma_f32_16x16x32_bf16 v[76:79], v[162:165], v[204:207], v[76:79]
	v_mfma_f32_16x16x32_bf16 v[72:75], v[170:173], v[204:207], v[72:75]
	v_mfma_f32_16x16x32_bf16 v[124:127], v[166:169], v[182:185], v[124:127]
	v_mfma_f32_16x16x32_bf16 v[120:123], v[174:177], v[182:185], v[120:123]
	v_mfma_f32_16x16x32_bf16 v[108:111], v[166:169], v[190:193], v[108:111]
	v_mfma_f32_16x16x32_bf16 v[104:107], v[174:177], v[190:193], v[104:107]
	v_mfma_f32_16x16x32_bf16 v[92:95], v[166:169], v[198:201], v[92:95]
	v_mfma_f32_16x16x32_bf16 v[88:91], v[174:177], v[198:201], v[88:91]
	v_mfma_f32_16x16x32_bf16 v[76:79], v[166:169], v[208:211], v[76:79]
	v_mfma_f32_16x16x32_bf16 v[72:75], v[174:177], v[208:211], v[72:75]
	s_barrier
	s_add_i32 s36, 0, 0x1c000
	s_add_i32 s33, s33, s44
	v_add_u32_e32 v161, s36, v148
	v_lshl_add_u64 v[228:229], v[228:229], 0, s[8:9]
	s_mov_b32 m0, s33
	ds_read_b128 v[212:215], v161
	ds_read_b128 v[216:219], v161 offset:1024
	ds_read_b128 v[220:223], v161 offset:2048
	ds_read_b128 v[224:227], v161 offset:3072
	global_load_lds_dwordx4 v[228:229], off
	v_lshl_add_u64 v[228:229], v[230:231], 0, s[8:9]
	s_add_i32 m0, s33, 0x2000
	s_nop 0
	global_load_lds_dwordx4 v[228:229], off
	s_barrier
	s_waitcnt lgkmcnt(0)
	v_mfma_f32_16x16x32_bf16 v[116:119], v[212:215], v[178:181], v[116:119]
	v_mfma_f32_16x16x32_bf16 v[112:115], v[220:223], v[178:181], v[112:115]
	v_mfma_f32_16x16x32_bf16 v[100:103], v[212:215], v[186:189], v[100:103]
	v_mfma_f32_16x16x32_bf16 v[96:99], v[220:223], v[186:189], v[96:99]
	v_mfma_f32_16x16x32_bf16 v[84:87], v[212:215], v[194:197], v[84:87]
	v_mfma_f32_16x16x32_bf16 v[80:83], v[220:223], v[194:197], v[80:83]
	v_mfma_f32_16x16x32_bf16 v[68:71], v[212:215], v[204:207], v[68:71]
	v_mfma_f32_16x16x32_bf16 v[64:67], v[220:223], v[204:207], v[64:67]
	v_mfma_f32_16x16x32_bf16 v[116:119], v[216:219], v[182:185], v[116:119]
	v_mfma_f32_16x16x32_bf16 v[112:115], v[224:227], v[182:185], v[112:115]
	v_mfma_f32_16x16x32_bf16 v[100:103], v[216:219], v[190:193], v[100:103]
	v_mfma_f32_16x16x32_bf16 v[96:99], v[224:227], v[190:193], v[96:99]
	v_mfma_f32_16x16x32_bf16 v[84:87], v[216:219], v[198:201], v[84:87]
	v_mfma_f32_16x16x32_bf16 v[80:83], v[224:227], v[198:201], v[80:83]
	v_mfma_f32_16x16x32_bf16 v[68:71], v[216:219], v[208:211], v[68:71]
	v_mfma_f32_16x16x32_bf16 v[64:67], v[224:227], v[208:211], v[64:67]
	s_mov_b32 m0, s51
	v_lshl_add_u64 v[228:229], v[232:233], 0, s[8:9]
	s_barrier
	ds_read_b128 v[178:181], v159 offset:49152
	ds_read_b128 v[182:185], v159 offset:50176
	ds_read_b128 v[186:189], v159 offset:51200
	ds_read_b128 v[190:193], v159 offset:52224
	ds_read_b128 v[194:197], v159 offset:53248
	ds_read_b128 v[198:201], v159 offset:54272
	ds_read_b128 v[204:207], v159 offset:55296
	ds_read_b128 v[208:211], v159 offset:56320
	global_load_lds_dwordx4 v[228:229], off
	v_lshl_add_u64 v[228:229], v[234:235], 0, s[8:9]
	s_mov_b32 m0, s52
	s_nop 0
	global_load_lds_dwordx4 v[228:229], off
	s_barrier
; #define PG8_BAR __builtin_amdgcn_s_barrier()
; __device__ __forceinline__ unsigned dpp_ror8(unsigned x) { return (unsigned)__builtin_amdgcn_update_dpp(0, (int)x, 0x128, 0xf, 0xf, false); }
; __device__ __forceinline__ void store_pair_lines(bf16_t* O, int ldc, int row, int fr, int col0, u32x4 wA, u32x4 wB) {
;     const u32x4 sA = {dpp_ror8(wA.x), dpp_ror8(wA.y), dpp_ror8(wA.z), dpp_ror8(wA.w)}, sB = {dpp_ror8(wB.x), dpp_ror8(wB.y), dpp_ror8(wB.z), dpp_ror8(wB.w)};
;     const bool lo = fr < 8;
;     const u32x4 o1 = lo ? wA : sB, o2 = lo ? sA : wB;
;     const int r1 = row - fr + (fr & 7), cb = col0 + (lo ? 0 : 8);
;     *(u32x4*)(O + (size_t)r1 * ldc + cb) = o1;
;     *(u32x4*)(O + (size_t)(r1 + 8) * ldc + cb) = o2;
; }
;     const bool lo = fr < 8;
;     const int r1 = row - fr + (fr & 7), cb = col0 + (lo ? 0 : boff);
;     const u32x4 l1 = *(const u32x4*)(P + (size_t)r1 * ld + cb), l2 = *(const u32x4*)(P + (size_t)(r1 + 8) * ld + cb);
;     const u32x4 s1 = {dpp_ror8(l1.x), dpp_ror8(l1.y), dpp_ror8(l1.z), dpp_ror8(l1.w)}, s2 = {dpp_ror8(l2.x), dpp_ror8(l2.y), dpp_ror8(l2.z), dpp_ror8(l2.w)};
;     wA = lo ? l1 : s2; wB = lo ? s1 : l2;
; }
;     __device__ __forceinline__ void operator()(const f32x4 (&acc)[2][2][4][2], const Unit& u, int wr, int wc, int fr, int fq) const {
;         const int row0 = u.pm * BM + wr * 64 + fr; const int col0 = u.pn * BM + wc * 64 + 16 * fq;
; #pragma unroll
;         for (int ai = 0; ai < 2; ++ai)
; #pragma unroll
;             for (int m = 0; m < 4; ++m) { const int row = row0 + ai * HALF + m * 16;
;                 const float rs = ssin ? __builtin_amdgcn_rsqf(ssin[row] * (1.f / D) + EPS) : 1.0f; float sq = 0.f; u32x4 w[2];
; #pragma unroll
;                 for (int bj = 0; bj < 2; ++bj) { f32x4 v0 = acc[ai][bj][m][0] * rs, v1 = acc[ai][bj][m][1] * rs;
;                     if (ACT == 1) {
; #pragma unroll
; template <class Epi>
; __device__ __forceinline__ void gemm_phase(LAS unsigned char* lds, const Gemm g, const StaticOrder& S, const Epi& E) {
;     ...
;             PG8_BAR; PG8_WAIT_L(0); PG8_MMA(0, 1, At, B1); PG8_BAR;
;             PG8_LDA(At, 1, 1); PG8_STAGE(PG8_SA(1, 0), a3, voffA);
;             PG8_BAR; PG8_WAIT_L(0); PG8_MMA(1, 0, At, B0); PG8_BAR; PG8_SCHED;
;             PG8_STAGE(PG8_SB(1, 1), b3, voffB1);
;             PG8_WAIT_V(6); PG8_BAR; PG8_MMA(1, 1, At, B1); PG8_BAR;
;         }
	s_waitcnt lgkmcnt(0)
	v_mfma_f32_16x16x32_bf16 v[60:63], v[162:165], v[178:181], v[60:63]
	v_mfma_f32_16x16x32_bf16 v[56:59], v[170:173], v[178:181], v[56:59]
	v_mfma_f32_16x16x32_bf16 v[44:47], v[162:165], v[186:189], v[44:47]
	v_mfma_f32_16x16x32_bf16 v[40:43], v[170:173], v[186:189], v[40:43]
	v_mfma_f32_16x16x32_bf16 v[28:31], v[162:165], v[194:197], v[28:31]
	v_mfma_f32_16x16x32_bf16 v[24:27], v[170:173], v[194:197], v[24:27]
	v_mfma_f32_16x16x32_bf16 v[12:15], v[162:165], v[204:207], v[12:15]
	v_mfma_f32_16x16x32_bf16 v[8:11], v[170:173], v[204:207], v[8:11]
	v_mfma_f32_16x16x32_bf16 v[60:63], v[166:169], v[182:185], v[60:63]
	v_mfma_f32_16x16x32_bf16 v[56:59], v[174:177], v[182:185], v[56:59]
	v_mfma_f32_16x16x32_bf16 v[44:47], v[166:169], v[190:193], v[44:47]
	v_mfma_f32_16x16x32_bf16 v[40:43], v[174:177], v[190:193], v[40:43]
	v_mfma_f32_16x16x32_bf16 v[28:31], v[166:169], v[198:201], v[28:31]
	v_mfma_f32_16x16x32_bf16 v[24:27], v[174:177], v[198:201], v[24:27]
	v_mfma_f32_16x16x32_bf16 v[12:15], v[166:169], v[208:211], v[12:15]
	v_mfma_f32_16x16x32_bf16 v[8:11], v[174:177], v[208:211], v[8:11]
	s_barrier
	s_add_i32 s33, s36, s44
	v_lshl_add_u64 v[162:163], v[236:237], 0, s[8:9]
	s_mov_b32 m0, s33
	s_nop 0
	global_load_lds_dwordx4 v[162:163], off
	v_lshl_add_u64 v[162:163], v[238:239], 0, s[8:9]
	s_add_i32 m0, s33, 0x2000
	s_nop 0
	global_load_lds_dwordx4 v[162:163], off
	s_waitcnt vmcnt(6)
	s_barrier
	v_mfma_f32_16x16x32_bf16 v[52:55], v[212:215], v[178:181], v[52:55]
	v_mfma_f32_16x16x32_bf16 v[48:51], v[220:223], v[178:181], v[48:51]
	v_mfma_f32_16x16x32_bf16 v[36:39], v[212:215], v[186:189], v[36:39]
	v_mfma_f32_16x16x32_bf16 v[32:35], v[220:223], v[186:189], v[32:35]
	v_mfma_f32_16x16x32_bf16 v[20:23], v[212:215], v[194:197], v[20:23]
	v_mfma_f32_16x16x32_bf16 v[16:19], v[220:223], v[194:197], v[16:19]
	v_mfma_f32_16x16x32_bf16 v[4:7], v[212:215], v[204:207], v[4:7]
	v_mfma_f32_16x16x32_bf16 v[0:3], v[220:223], v[204:207], v[0:3]
	v_mfma_f32_16x16x32_bf16 v[52:55], v[216:219], v[182:185], v[52:55]
	v_mfma_f32_16x16x32_bf16 v[48:51], v[224:227], v[182:185], v[48:51]
	v_mfma_f32_16x16x32_bf16 v[36:39], v[216:219], v[190:193], v[36:39]
	v_mfma_f32_16x16x32_bf16 v[32:35], v[224:227], v[190:193], v[32:35]
	v_mfma_f32_16x16x32_bf16 v[20:23], v[216:219], v[198:201], v[20:23]
	v_mfma_f32_16x16x32_bf16 v[16:19], v[224:227], v[198:201], v[16:19]
	v_mfma_f32_16x16x32_bf16 v[4:7], v[216:219], v[208:211], v[4:7]
	v_mfma_f32_16x16x32_bf16 v[0:3], v[224:227], v[208:211], v[0:3]
	s_add_i32 s63, s63, 2
	s_add_u32 s34, s34, 0x100
	s_addc_u32 s35, s35, 0
	s_add_u32 s61, s61, 0x100
	s_addc_u32 s62, s62, 0
	s_cmp_gt_u32 s63, 29
	s_barrier
	s_cbranch_scc0 .LBB0_107
	s_lshl_b32 s11, s30, 8
	v_cvt_pk_bf16_f32 v124, v124, v125
	v_cvt_pk_bf16_f32 v125, v126, v127
	v_cvt_pk_bf16_f32 v120, v120, v121
	v_cvt_pk_bf16_f32 v121, v122, v123
	v_cvt_pk_bf16_f32 v122, v116, v117
	v_cvt_pk_bf16_f32 v119, v118, v119
	s_add_i32 s11, s11, s53
	v_cvt_pk_bf16_f32 v112, v112, v113
	v_cvt_pk_bf16_f32 v113, v114, v115
	v_mov_b32_dpp v118, v124 row_ror:8 row_mask:0xf bank_mask:0xf
	v_mov_b32_dpp v123, v125 row_ror:8 row_mask:0xf bank_mask:0xf
	v_mov_b32_dpp v114, v122 row_ror:8 row_mask:0xf bank_mask:0xf
	v_cndmask_b32_e64 v118, v122, v118, s[4:5]
	v_or_b32_e32 v122, s11, v149
	v_lshl_or_b32 v162, s58, 8, v157
	v_mov_b32_dpp v126, v120 row_ror:8 row_mask:0xf bank_mask:0xf
	v_mov_b32_dpp v127, v121 row_ror:8 row_mask:0xf bank_mask:0xf
	v_mov_b32_dpp v115, v119 row_ror:8 row_mask:0xf bank_mask:0xf
	v_mov_b32_dpp v116, v112 row_ror:8 row_mask:0xf bank_mask:0xf
	v_mov_b32_dpp v117, v113 row_ror:8 row_mask:0xf bank_mask:0xf
	v_cndmask_b32_e64 v119, v119, v123, s[4:5]
	v_ashrrev_i32_e32 v123, 31, v122
	v_ashrrev_i32_e32 v163, 31, v162
	v_cndmask_b32_e64 v116, v116, v120, s[4:5]
	v_cndmask_b32_e64 v117, v117, v121, s[4:5]
	v_cndmask_b32_e64 v120, v112, v126, s[4:5]
	v_cndmask_b32_e64 v121, v113, v127, s[4:5]
	v_lshlrev_b64 v[112:113], 13, v[122:123]
	v_cndmask_b32_e64 v114, v114, v124, s[4:5]
	v_cndmask_b32_e64 v115, v115, v125, s[4:5]
	v_lshl_add_u64 v[124:125], s[6:7], 0, v[112:113]
	v_lshlrev_b64 v[112:113], 1, v[162:163]
	v_lshl_add_u64 v[124:125], v[124:125], 0, v[112:113]
	global_store_dwordx4 v[124:125], v[114:117], off
	v_or_b32_e32 v161, s11, v147
	s_mov_b32 s58, s10
	v_or_b32_e32 v114, 8, v122
	v_ashrrev_i32_e32 v115, 31, v114
	v_lshlrev_b64 v[114:115], 13, v[114:115]
	v_lshl_add_u64 v[114:115], s[6:7], 0, v[114:115]
	v_lshl_add_u64 v[114:115], v[114:115], 0, v[112:113]
	global_store_dwordx4 v[114:115], v[118:121], off
	v_cvt_pk_bf16_f32 v108, v108, v109
	v_cvt_pk_bf16_f32 v109, v110, v111
	v_cvt_pk_bf16_f32 v104, v104, v105
	v_cvt_pk_bf16_f32 v105, v106, v107
	v_cvt_pk_bf16_f32 v100, v100, v101
	v_cvt_pk_bf16_f32 v101, v102, v103
	v_cvt_pk_bf16_f32 v102, v96, v97
	v_cvt_pk_bf16_f32 v103, v98, v99
	v_mov_b32_e32 v98, 0
	v_mov_b32_dpp v98, v102 row_ror:8 row_mask:0xf bank_mask:0xf
	v_mov_b32_dpp v110, v104 row_ror:8 row_mask:0xf bank_mask:0xf
	v_mov_b32_dpp v99, v103 row_ror:8 row_mask:0xf bank_mask:0xf
	v_cndmask_b32_e64 v98, v98, v104, s[4:5]
	v_add_u32_e32 v104, v150, v161
	v_mov_b32_dpp v111, v105 row_ror:8 row_mask:0xf bank_mask:0xf
	v_cndmask_b32_e64 v99, v99, v105, s[4:5]
	v_ashrrev_i32_e32 v105, 31, v104
	v_lshlrev_b64 v[104:105], 13, v[104:105]
	v_mov_b32_dpp v96, v100 row_ror:8 row_mask:0xf bank_mask:0xf
	v_mov_b32_dpp v97, v101 row_ror:8 row_mask:0xf bank_mask:0xf
	v_lshl_add_u64 v[104:105], s[6:7], 0, v[104:105]
	v_cndmask_b32_e64 v96, v96, v108, s[4:5]
	v_cndmask_b32_e64 v97, v97, v109, s[4:5]
	v_lshl_add_u64 v[104:105], v[104:105], 0, v[112:113]
; __device__ __forceinline__ unsigned cvt_pk_bf16(float lo, float hi) { unsigned r; asm volatile("v_cvt_pk_bf16_f32 %0, %1, %2" : "=v"(r) : "v"(lo), "v"(hi)); return r; }
; __device__ __forceinline__ unsigned dpp_ror8(unsigned x) { return (unsigned)__builtin_amdgcn_update_dpp(0, (int)x, 0x128, 0xf, 0xf, false); }
; __device__ __forceinline__ void store_pair_lines(bf16_t* O, int ldc, int row, int fr, int col0, u32x4 wA, u32x4 wB) {
;     const u32x4 sA = {dpp_ror8(wA.x), dpp_ror8(wA.y), dpp_ror8(wA.z), dpp_ror8(wA.w)}, sB = {dpp_ror8(wB.x), dpp_ror8(wB.y), dpp_ror8(wB.z), dpp_ror8(wB.w)};
;     const bool lo = fr < 8;
;     const u32x4 o1 = lo ? wA : sB, o2 = lo ? sA : wB;
;     const int r1 = row - fr + (fr & 7), cb = col0 + (lo ? 0 : 8);
;     *(u32x4*)(O + (size_t)r1 * ldc + cb) = o1;
;     *(u32x4*)(O + (size_t)(r1 + 8) * ldc + cb) = o2;
; }
;     __device__ __forceinline__ void operator()(const f32x4 (&acc)[2][2][4][2], const Unit& u, int wr, int wc, int fr, int fq) const {
;     ...
;             for (int m = 0; m < 4; ++m) { const int row = row0 + ai * HALF + m * 16;
;                 const float rs = ssin ? __builtin_amdgcn_rsqf(ssin[row] * (1.f / D) + EPS) : 1.0f; float sq = 0.f; u32x4 w[2];
; #pragma unroll
;                 for (int bj = 0; bj < 2; ++bj) { f32x4 v0 = acc[ai][bj][m][0] * rs, v1 = acc[ai][bj][m][1] * rs;
;                     if (ACT == 1) {
; #pragma unroll
;                         for (int j = 0; j < 4; ++j) { const float a = fmaxf(v0[j], 0.f), b = fmaxf(v1[j], 0.f); v0[j] = a * a; v1[j] = b * b; } }
;                     sq += (v0[0] * v0[0] + v0[1] * v0[1]) + (v0[2] * v0[2] + v0[3] * v0[3]) + (v1[0] * v1[0] + v1[1] * v1[1]) + (v1[2] * v1[2] + v1[3] * v1[3]);
;                     w[bj].x = cvt_pk_bf16(v0[0], v0[1]); w[bj].y = cvt_pk_bf16(v0[2], v0[3]); w[bj].z = cvt_pk_bf16(v1[0], v1[1]); w[bj].w = cvt_pk_bf16(v1[2], v1[3]); }
;                 store_pair_lines(O, ldc, row, fr, col0, w[0], w[1]);
;                 if (ssout) { sq += __shfl_xor(sq, 16); sq += __shfl_xor(sq, 32); if (fq == 0) unsafeAtomicAdd(ssout + row, sq); } }
	v_mov_b32_dpp v106, v108 row_ror:8 row_mask:0xf bank_mask:0xf
	v_mov_b32_dpp v107, v109 row_ror:8 row_mask:0xf bank_mask:0xf
	global_store_dwordx4 v[104:105], v[96:99], off
	v_cndmask_b32_e64 v100, v100, v106, s[4:5]
	v_cndmask_b32_e64 v101, v101, v107, s[4:5]
	v_add_co_u32_e32 v96, vcc, s49, v104
	v_cndmask_b32_e64 v102, v102, v110, s[4:5]
	v_cndmask_b32_e64 v103, v103, v111, s[4:5]
	v_addc_co_u32_e32 v97, vcc, 0, v105, vcc
	global_store_dwordx4 v[96:97], v[100:103], off
	v_cvt_pk_bf16_f32 v92, v92, v93
	v_cvt_pk_bf16_f32 v93, v94, v95
	v_cvt_pk_bf16_f32 v88, v88, v89
	v_cvt_pk_bf16_f32 v89, v90, v91
	v_cvt_pk_bf16_f32 v84, v84, v85
	v_cvt_pk_bf16_f32 v85, v86, v87
	v_cvt_pk_bf16_f32 v86, v80, v81
	v_cvt_pk_bf16_f32 v87, v82, v83
	v_mov_b32_e32 v82, 0
	v_mov_b32_dpp v82, v86 row_ror:8 row_mask:0xf bank_mask:0xf
	v_mov_b32_dpp v94, v88 row_ror:8 row_mask:0xf bank_mask:0xf
	v_mov_b32_dpp v83, v87 row_ror:8 row_mask:0xf bank_mask:0xf
	v_cndmask_b32_e64 v82, v82, v88, s[4:5]
	v_add_u32_e32 v88, v151, v161
	v_mov_b32_dpp v95, v89 row_ror:8 row_mask:0xf bank_mask:0xf
	v_cndmask_b32_e64 v83, v83, v89, s[4:5]
	v_ashrrev_i32_e32 v89, 31, v88
	v_lshlrev_b64 v[88:89], 13, v[88:89]
	v_mov_b32_dpp v80, v84 row_ror:8 row_mask:0xf bank_mask:0xf
	v_mov_b32_dpp v81, v85 row_ror:8 row_mask:0xf bank_mask:0xf
	v_lshl_add_u64 v[88:89], s[6:7], 0, v[88:89]
	v_cndmask_b32_e64 v80, v80, v92, s[4:5]
	v_cndmask_b32_e64 v81, v81, v93, s[4:5]
	v_lshl_add_u64 v[88:89], v[88:89], 0, v[112:113]
	v_mov_b32_dpp v90, v92 row_ror:8 row_mask:0xf bank_mask:0xf
	v_mov_b32_dpp v91, v93 row_ror:8 row_mask:0xf bank_mask:0xf
	global_store_dwordx4 v[88:89], v[80:83], off
	v_cndmask_b32_e64 v84, v84, v90, s[4:5]
	v_cndmask_b32_e64 v85, v85, v91, s[4:5]
	v_add_co_u32_e32 v80, vcc, s49, v88
	v_cndmask_b32_e64 v86, v86, v94, s[4:5]
	v_cndmask_b32_e64 v87, v87, v95, s[4:5]
	v_addc_co_u32_e32 v81, vcc, 0, v89, vcc
	global_store_dwordx4 v[80:81], v[84:87], off
	v_cvt_pk_bf16_f32 v76, v76, v77
	v_cvt_pk_bf16_f32 v77, v78, v79
	v_cvt_pk_bf16_f32 v72, v72, v73
	v_cvt_pk_bf16_f32 v73, v74, v75
	v_cvt_pk_bf16_f32 v68, v68, v69
	v_cvt_pk_bf16_f32 v69, v70, v71
	v_cvt_pk_bf16_f32 v70, v64, v65
	v_cvt_pk_bf16_f32 v71, v66, v67
	v_mov_b32_e32 v66, 0
	v_mov_b32_dpp v66, v70 row_ror:8 row_mask:0xf bank_mask:0xf
	v_mov_b32_dpp v78, v72 row_ror:8 row_mask:0xf bank_mask:0xf
	v_mov_b32_dpp v67, v71 row_ror:8 row_mask:0xf bank_mask:0xf
	v_cndmask_b32_e64 v66, v66, v72, s[4:5]
	v_add_u32_e32 v72, v152, v161
	v_mov_b32_dpp v79, v73 row_ror:8 row_mask:0xf bank_mask:0xf
	v_cndmask_b32_e64 v67, v67, v73, s[4:5]
	v_ashrrev_i32_e32 v73, 31, v72
	v_lshlrev_b64 v[72:73], 13, v[72:73]
	v_mov_b32_dpp v64, v68 row_ror:8 row_mask:0xf bank_mask:0xf
	v_mov_b32_dpp v65, v69 row_ror:8 row_mask:0xf bank_mask:0xf
	v_lshl_add_u64 v[72:73], s[6:7], 0, v[72:73]
	v_cndmask_b32_e64 v64, v64, v76, s[4:5]
	v_cndmask_b32_e64 v65, v65, v77, s[4:5]
	v_lshl_add_u64 v[72:73], v[72:73], 0, v[112:113]
	v_mov_b32_dpp v74, v76 row_ror:8 row_mask:0xf bank_mask:0xf
	v_mov_b32_dpp v75, v77 row_ror:8 row_mask:0xf bank_mask:0xf
	global_store_dwordx4 v[72:73], v[64:67], off
	v_cndmask_b32_e64 v68, v68, v74, s[4:5]
	v_cndmask_b32_e64 v69, v69, v75, s[4:5]
	v_add_co_u32_e32 v64, vcc, s49, v72
	v_cndmask_b32_e64 v70, v70, v78, s[4:5]
	v_cndmask_b32_e64 v71, v71, v79, s[4:5]
	v_addc_co_u32_e32 v65, vcc, 0, v73, vcc
	global_store_dwordx4 v[64:65], v[68:71], off
	v_cvt_pk_bf16_f32 v60, v60, v61
	v_cvt_pk_bf16_f32 v61, v62, v63
	v_cvt_pk_bf16_f32 v56, v56, v57
	v_cvt_pk_bf16_f32 v57, v58, v59
	v_cvt_pk_bf16_f32 v52, v52, v53
	v_cvt_pk_bf16_f32 v53, v54, v55
	v_cvt_pk_bf16_f32 v54, v48, v49
	v_cvt_pk_bf16_f32 v55, v50, v51
	v_mov_b32_e32 v50, 0
	v_mov_b32_dpp v50, v54 row_ror:8 row_mask:0xf bank_mask:0xf
	v_mov_b32_dpp v62, v56 row_ror:8 row_mask:0xf bank_mask:0xf
	v_mov_b32_dpp v51, v55 row_ror:8 row_mask:0xf bank_mask:0xf
	v_cndmask_b32_e64 v50, v50, v56, s[4:5]
	v_add_u32_e32 v56, v153, v161
	v_mov_b32_dpp v63, v57 row_ror:8 row_mask:0xf bank_mask:0xf
	v_cndmask_b32_e64 v51, v51, v57, s[4:5]
	v_ashrrev_i32_e32 v57, 31, v56
	v_lshlrev_b64 v[56:57], 13, v[56:57]
	v_mov_b32_dpp v48, v52 row_ror:8 row_mask:0xf bank_mask:0xf
	v_mov_b32_dpp v49, v53 row_ror:8 row_mask:0xf bank_mask:0xf
	v_lshl_add_u64 v[56:57], s[6:7], 0, v[56:57]
	v_cndmask_b32_e64 v48, v48, v60, s[4:5]
	v_cndmask_b32_e64 v49, v49, v61, s[4:5]
	v_lshl_add_u64 v[56:57], v[56:57], 0, v[112:113]
	v_mov_b32_dpp v58, v60 row_ror:8 row_mask:0xf bank_mask:0xf
	v_mov_b32_dpp v59, v61 row_ror:8 row_mask:0xf bank_mask:0xf
	global_store_dwordx4 v[56:57], v[48:51], off
	v_cndmask_b32_e64 v52, v52, v58, s[4:5]
	v_cndmask_b32_e64 v53, v53, v59, s[4:5]
	v_add_co_u32_e32 v48, vcc, s49, v56
; __device__ __forceinline__ unsigned cvt_pk_bf16(float lo, float hi) { unsigned r; asm volatile("v_cvt_pk_bf16_f32 %0, %1, %2" : "=v"(r) : "v"(lo), "v"(hi)); return r; }
; #define PG8_WAIT_V(n) asm volatile("s_waitcnt vmcnt(" #n ")" ::: "memory")
; #define PG8_BAR __builtin_amdgcn_s_barrier()
;     __device__ __forceinline__ void operator()(const f32x4 (&acc)[2][2][4][2], const Unit& u, int wr, int wc, int fr, int fq) const {
;     ...
;             for (int m = 0; m < 4; ++m) { const int row = row0 + ai * HALF + m * 16;
;                 const float rs = ssin ? __builtin_amdgcn_rsqf(ssin[row] * (1.f / D) + EPS) : 1.0f; float sq = 0.f; u32x4 w[2];
; #pragma unroll
;                 for (int bj = 0; bj < 2; ++bj) { f32x4 v0 = acc[ai][bj][m][0] * rs, v1 = acc[ai][bj][m][1] * rs;
;                     if (ACT == 1) {
; #pragma unroll
;                         for (int j = 0; j < 4; ++j) { const float a = fmaxf(v0[j], 0.f), b = fmaxf(v1[j], 0.f); v0[j] = a * a; v1[j] = b * b; } }
;                     sq += (v0[0] * v0[0] + v0[1] * v0[1]) + (v0[2] * v0[2] + v0[3] * v0[3]) + (v1[0] * v1[0] + v1[1] * v1[1]) + (v1[2] * v1[2] + v1[3] * v1[3]);
;                     w[bj].x = cvt_pk_bf16(v0[0], v0[1]); w[bj].y = cvt_pk_bf16(v0[2], v0[3]); w[bj].z = cvt_pk_bf16(v1[0], v1[1]); w[bj].w = cvt_pk_bf16(v1[2], v1[3]); }
;                 store_pair_lines(O, ldc, row, fr, col0, w[0], w[1]);
;                 if (ssout) { sq += __shfl_xor(sq, 16); sq += __shfl_xor(sq, 32); if (fq == 0) unsafeAtomicAdd(ssout + row, sq); } }
; template <class Epi>
; __device__ __forceinline__ void gemm_phase(LAS unsigned char* lds, const Gemm g, const StaticOrder& S, const Epi& E) {
;     ...
;         if (!has_next) break;
; #pragma unroll
;         for (int a = 0; a < 2; ++a)
; #pragma unroll
;             for (int b = 0; b < 2; ++b)
; #pragma unroll
;                 for (int m = 0; m < 4; ++m)
; #pragma unroll
;                     for (int n = 0; n < 2; ++n) acc[a][b][m][n] = (f32x4){0.f, 0.f, 0.f, 0.f};
;         cur = nxt; cA = nA; cB = nB; ++ui;
;     }
;     PG8_WAIT_V(0);
;     if (wr == 0) PG8_BAR;
;     PG8_BAR;
	v_cndmask_b32_e64 v54, v54, v62, s[4:5]
	v_cndmask_b32_e64 v55, v55, v63, s[4:5]
	v_addc_co_u32_e32 v49, vcc, 0, v57, vcc
	global_store_dwordx4 v[48:49], v[52:55], off
	v_cvt_pk_bf16_f32 v44, v44, v45
	v_cvt_pk_bf16_f32 v45, v46, v47
	v_cvt_pk_bf16_f32 v40, v40, v41
	v_cvt_pk_bf16_f32 v41, v42, v43
	v_cvt_pk_bf16_f32 v36, v36, v37
	v_cvt_pk_bf16_f32 v37, v38, v39
	v_cvt_pk_bf16_f32 v38, v32, v33
	v_cvt_pk_bf16_f32 v39, v34, v35
	v_mov_b32_e32 v34, 0
	v_mov_b32_dpp v34, v38 row_ror:8 row_mask:0xf bank_mask:0xf
	v_mov_b32_dpp v46, v40 row_ror:8 row_mask:0xf bank_mask:0xf
	v_mov_b32_dpp v35, v39 row_ror:8 row_mask:0xf bank_mask:0xf
	v_cndmask_b32_e64 v34, v34, v40, s[4:5]
	v_add_u32_e32 v40, v154, v161
	v_mov_b32_dpp v47, v41 row_ror:8 row_mask:0xf bank_mask:0xf
	v_cndmask_b32_e64 v35, v35, v41, s[4:5]
	v_ashrrev_i32_e32 v41, 31, v40
	v_lshlrev_b64 v[40:41], 13, v[40:41]
	v_mov_b32_dpp v32, v36 row_ror:8 row_mask:0xf bank_mask:0xf
	v_mov_b32_dpp v33, v37 row_ror:8 row_mask:0xf bank_mask:0xf
	v_lshl_add_u64 v[40:41], s[6:7], 0, v[40:41]
	v_cndmask_b32_e64 v32, v32, v44, s[4:5]
	v_cndmask_b32_e64 v33, v33, v45, s[4:5]
	v_lshl_add_u64 v[40:41], v[40:41], 0, v[112:113]
	v_mov_b32_dpp v42, v44 row_ror:8 row_mask:0xf bank_mask:0xf
	v_mov_b32_dpp v43, v45 row_ror:8 row_mask:0xf bank_mask:0xf
	global_store_dwordx4 v[40:41], v[32:35], off
	v_cndmask_b32_e64 v36, v36, v42, s[4:5]
	v_cndmask_b32_e64 v37, v37, v43, s[4:5]
	v_add_co_u32_e32 v32, vcc, s49, v40
	v_cndmask_b32_e64 v38, v38, v46, s[4:5]
	v_cndmask_b32_e64 v39, v39, v47, s[4:5]
	v_addc_co_u32_e32 v33, vcc, 0, v41, vcc
	global_store_dwordx4 v[32:33], v[36:39], off
	v_cvt_pk_bf16_f32 v28, v28, v29
	v_cvt_pk_bf16_f32 v29, v30, v31
	v_cvt_pk_bf16_f32 v24, v24, v25
	v_cvt_pk_bf16_f32 v25, v26, v27
	v_cvt_pk_bf16_f32 v20, v20, v21
	v_cvt_pk_bf16_f32 v21, v22, v23
	v_cvt_pk_bf16_f32 v22, v16, v17
	v_cvt_pk_bf16_f32 v23, v18, v19
	v_mov_b32_e32 v18, 0
	v_mov_b32_dpp v18, v22 row_ror:8 row_mask:0xf bank_mask:0xf
	v_mov_b32_dpp v30, v24 row_ror:8 row_mask:0xf bank_mask:0xf
	v_mov_b32_dpp v19, v23 row_ror:8 row_mask:0xf bank_mask:0xf
	v_cndmask_b32_e64 v18, v18, v24, s[4:5]
	v_add_u32_e32 v24, v155, v161
	v_mov_b32_dpp v31, v25 row_ror:8 row_mask:0xf bank_mask:0xf
	v_cndmask_b32_e64 v19, v19, v25, s[4:5]
	v_ashrrev_i32_e32 v25, 31, v24
	v_lshlrev_b64 v[24:25], 13, v[24:25]
	v_mov_b32_dpp v16, v20 row_ror:8 row_mask:0xf bank_mask:0xf
	v_mov_b32_dpp v17, v21 row_ror:8 row_mask:0xf bank_mask:0xf
	v_lshl_add_u64 v[24:25], s[6:7], 0, v[24:25]
	v_cndmask_b32_e64 v16, v16, v28, s[4:5]
	v_cndmask_b32_e64 v17, v17, v29, s[4:5]
	v_lshl_add_u64 v[24:25], v[24:25], 0, v[112:113]
	v_mov_b32_dpp v26, v28 row_ror:8 row_mask:0xf bank_mask:0xf
	v_mov_b32_dpp v27, v29 row_ror:8 row_mask:0xf bank_mask:0xf
	global_store_dwordx4 v[24:25], v[16:19], off
	v_cndmask_b32_e64 v20, v20, v26, s[4:5]
	v_cndmask_b32_e64 v21, v21, v27, s[4:5]
	v_add_co_u32_e32 v16, vcc, s49, v24
	v_cndmask_b32_e64 v22, v22, v30, s[4:5]
	v_cndmask_b32_e64 v23, v23, v31, s[4:5]
	v_addc_co_u32_e32 v17, vcc, 0, v25, vcc
	global_store_dwordx4 v[16:17], v[20:23], off
	v_cvt_pk_bf16_f32 v12, v12, v13
	v_cvt_pk_bf16_f32 v13, v14, v15
	v_cvt_pk_bf16_f32 v8, v8, v9
	v_cvt_pk_bf16_f32 v9, v10, v11
	v_cvt_pk_bf16_f32 v4, v4, v5
	v_cvt_pk_bf16_f32 v5, v6, v7
	v_cvt_pk_bf16_f32 v6, v0, v1
	v_cvt_pk_bf16_f32 v7, v2, v3
	v_mov_b32_e32 v2, 0
	v_mov_b32_dpp v2, v6 row_ror:8 row_mask:0xf bank_mask:0xf
	v_mov_b32_dpp v14, v8 row_ror:8 row_mask:0xf bank_mask:0xf
	v_mov_b32_dpp v3, v7 row_ror:8 row_mask:0xf bank_mask:0xf
	v_cndmask_b32_e64 v2, v2, v8, s[4:5]
	v_add_u32_e32 v8, v156, v161
	v_mov_b32_dpp v15, v9 row_ror:8 row_mask:0xf bank_mask:0xf
	v_cndmask_b32_e64 v3, v3, v9, s[4:5]
	v_ashrrev_i32_e32 v9, 31, v8
	v_lshlrev_b64 v[8:9], 13, v[8:9]
	v_mov_b32_dpp v0, v4 row_ror:8 row_mask:0xf bank_mask:0xf
	v_mov_b32_dpp v1, v5 row_ror:8 row_mask:0xf bank_mask:0xf
	v_lshl_add_u64 v[8:9], s[6:7], 0, v[8:9]
	v_cndmask_b32_e64 v0, v0, v12, s[4:5]
	v_cndmask_b32_e64 v1, v1, v13, s[4:5]
	v_lshl_add_u64 v[8:9], v[8:9], 0, v[112:113]
	global_store_dwordx4 v[8:9], v[0:3], off
	v_mov_b32_dpp v10, v12 row_ror:8 row_mask:0xf bank_mask:0xf
	v_mov_b32_dpp v11, v13 row_ror:8 row_mask:0xf bank_mask:0xf
	v_add_co_u32_e32 v0, vcc, 0x10000, v8
	v_cndmask_b32_e64 v4, v4, v10, s[4:5]
	s_nop 0
	v_addc_co_u32_e32 v1, vcc, 0, v9, vcc
	v_cndmask_b32_e64 v5, v5, v11, s[4:5]
	v_cndmask_b32_e64 v6, v6, v14, s[4:5]
	v_cndmask_b32_e64 v7, v7, v15, s[4:5]
	s_and_b64 vcc, exec, s[18:19]
	s_mov_b32 s30, s12
	s_mov_b64 s[36:37], s[28:29]
	s_mov_b64 s[34:35], s[16:17]
	global_store_dwordx4 v[0:1], v[4:7], off
	s_cbranch_vccz .LBB0_103
	s_waitcnt vmcnt(0)
	s_cmpk_gt_u32 s27, 0xff
	s_cbranch_scc1 .LBB0_111
	s_barrier

; #define PG8_STAGE(bufoff, gbase, voff) do { _Pragma("unroll") for (int _i = 0; _i < 2; ++_i) \
;         __builtin_amdgcn_global_load_lds((const unsigned*)((const char*)(gbase) + (voff)[_i]), (LAS unsigned*)(lds + (bufoff) + ldsw + _i * 8192), 16, 0, 0); } while (0)
; #define PG8_LDA(dst, b, h) do { _Pragma("unroll") for (int m = 0; m < 4; ++m) _Pragma("unroll") for (int k = 0; k < 2; ++k) dst[m][k] = *(const LAS bf16x8*)(lds + PG8_SA(b, h) + aoff + m * 2048 + k * 1024); } while (0)
; #define PG8_LDB(dst, b, h) do { _Pragma("unroll") for (int n = 0; n < 2; ++n) _Pragma("unroll") for (int k = 0; k < 2; ++k) dst[n][k] = *(const LAS bf16x8*)(lds + PG8_SB(b, h) + boff + n * 2048 + k * 1024); } while (0)
; #define PG8_MMA(ai, bj, At, Bt) do { __builtin_amdgcn_s_setprio(1); _Pragma("unroll") for (int m = 0; m < 4; ++m) _Pragma("unroll") for (int n = 0; n < 2; ++n) _Pragma("unroll") for (int k = 0; k < 2; ++k) \
;         acc[ai][bj][m][n] = __builtin_amdgcn_mfma_f32_16x16x32_bf16(Bt[n][k], At[m][k], acc[ai][bj][m][n], 0, 0, 0); __builtin_amdgcn_s_setprio(0); } while (0)
; #define PG8_WAIT_V(n) asm volatile("s_waitcnt vmcnt(" #n ")" ::: "memory")
; #define PG8_WAIT_L(n) asm volatile("s_waitcnt lgkmcnt(" #n ")" ::: "memory")
; #define PG8_BAR __builtin_amdgcn_s_barrier()
; template <class Epi>
; __device__ __forceinline__ void gemm_phase(LAS unsigned char* lds, const Gemm g, const StaticOrder& S, const Epi& E) {
;     ...
;         for (int t = 0; t < nt; t += 2) {
;             const bool last = (t == nt - 2);
;             const char* a1 = cA + (size_t)(t + 1) * kstep;
;             const char* a2 = last ? nA : cA + (size_t)(t + 2) * kstep; const char* b2 = last ? nB : cB + (size_t)(t + 2) * kstep;
;             const char* a3 = a2 + kstep; const char* b3 = b2 + kstep;
;             PG8_LDB(B0, 0, 0); PG8_SCHED; PG8_LDA(At, 0, 0); PG8_STAGE(PG8_SA(1, 1), a1 + hstep, voffA);
;             PG8_WAIT_L(8); PG8_BAR; PG8_WAIT_L(0); PG8_MMA(0, 0, At, B0); PG8_BAR; PG8_SCHED;
;             PG8_LDB(B1, 0, 1); PG8_STAGE(PG8_SB(0, 0), b2, voffB0);
;             PG8_BAR; PG8_WAIT_L(0); PG8_MMA(0, 1, At, B1); PG8_BAR;
;             PG8_LDA(At, 0, 1); PG8_STAGE(PG8_SA(0, 0), a2, voffA);
;             PG8_BAR; PG8_WAIT_L(0); PG8_MMA(1, 0, At, B0); PG8_BAR; PG8_SCHED;
;             PG8_STAGE(PG8_SB(0, 1), b2, voffB1);
;             PG8_WAIT_V(6); PG8_BAR; PG8_MMA(1, 1, At, B1); PG8_BAR;
.LBB0_234:
	ds_read_b128 v[160:163], v157
	ds_read_b128 v[164:167], v157 offset:1024
	ds_read_b128 v[168:171], v157 offset:2048
	ds_read_b128 v[172:175], v157 offset:3072
	s_add_u32 s33, s38, 0xfffe0080
	s_addc_u32 s40, s39, -1
	s_cmp_eq_u32 s68, 4
	s_cselect_b32 s41, s17, s40
	s_cselect_b32 s40, s64, s33
	s_cselect_b32 s43, s11, s67
	s_cselect_b32 s42, s65, s66
	v_lshl_add_u64 v[200:201], s[38:39], 0, v[140:141]
	s_add_i32 m0, s37, 0xc000
	ds_read_b128 v[176:179], v158
	ds_read_b128 v[180:183], v158 offset:1024
	ds_read_b128 v[184:187], v158 offset:2048
	ds_read_b128 v[188:191], v158 offset:3072
	ds_read_b128 v[192:195], v158 offset:4096
	ds_read_b128 v[196:199], v158 offset:5120
	ds_read_b128 v[204:207], v158 offset:6144
	ds_read_b128 v[208:211], v158 offset:7168
	global_load_lds_dwordx4 v[200:201], off
	v_lshl_add_u64 v[200:201], s[38:39], 0, v[142:143]
	s_add_i32 m0, s37, 0xe000
	s_nop 0
	global_load_lds_dwordx4 v[200:201], off
	s_waitcnt lgkmcnt(8)
	s_barrier
	s_waitcnt lgkmcnt(0)
	v_mfma_f32_16x16x32_bf16 v[124:127], v[160:163], v[176:179], v[124:127]
	v_mfma_f32_16x16x32_bf16 v[120:123], v[168:171], v[176:179], v[120:123]
	v_mfma_f32_16x16x32_bf16 v[108:111], v[160:163], v[184:187], v[108:111]
	v_mfma_f32_16x16x32_bf16 v[104:107], v[168:171], v[184:187], v[104:107]
	v_mfma_f32_16x16x32_bf16 v[92:95], v[160:163], v[192:195], v[92:95]
	v_mfma_f32_16x16x32_bf16 v[88:91], v[168:171], v[192:195], v[88:91]
	v_mfma_f32_16x16x32_bf16 v[76:79], v[160:163], v[204:207], v[76:79]
	v_mfma_f32_16x16x32_bf16 v[72:75], v[168:171], v[204:207], v[72:75]
	v_mfma_f32_16x16x32_bf16 v[124:127], v[164:167], v[180:183], v[124:127]
	v_mfma_f32_16x16x32_bf16 v[120:123], v[172:175], v[180:183], v[120:123]
	v_mfma_f32_16x16x32_bf16 v[108:111], v[164:167], v[188:191], v[108:111]
	v_mfma_f32_16x16x32_bf16 v[104:107], v[172:175], v[188:191], v[104:107]
	v_mfma_f32_16x16x32_bf16 v[92:95], v[164:167], v[196:199], v[92:95]
	v_mfma_f32_16x16x32_bf16 v[88:91], v[172:175], v[196:199], v[88:91]
	v_mfma_f32_16x16x32_bf16 v[76:79], v[164:167], v[208:211], v[76:79]
	v_mfma_f32_16x16x32_bf16 v[72:75], v[172:175], v[208:211], v[72:75]
	s_barrier
	s_add_i32 s33, s60, s49
	v_lshl_add_u64 v[200:201], s[42:43], 0, v[134:135]
	s_mov_b32 m0, s33
	ds_read_b128 v[212:215], v159
	ds_read_b128 v[216:219], v159 offset:1024
	ds_read_b128 v[220:223], v159 offset:2048
	ds_read_b128 v[224:227], v159 offset:3072
	global_load_lds_dwordx4 v[200:201], off
	v_lshl_add_u64 v[228:229], s[42:43], 0, v[128:129]
	s_add_i32 m0, s33, 0x2000
	s_nop 0
	global_load_lds_dwordx4 v[228:229], off
	s_barrier
	s_waitcnt lgkmcnt(0)
	v_mfma_f32_16x16x32_bf16 v[116:119], v[212:215], v[176:179], v[116:119]
	v_mfma_f32_16x16x32_bf16 v[112:115], v[220:223], v[176:179], v[112:115]
	v_mfma_f32_16x16x32_bf16 v[100:103], v[212:215], v[184:187], v[100:103]
	v_mfma_f32_16x16x32_bf16 v[96:99], v[220:223], v[184:187], v[96:99]
	v_mfma_f32_16x16x32_bf16 v[84:87], v[212:215], v[192:195], v[84:87]
	v_mfma_f32_16x16x32_bf16 v[80:83], v[220:223], v[192:195], v[80:83]
	v_mfma_f32_16x16x32_bf16 v[68:71], v[212:215], v[204:207], v[68:71]
	v_mfma_f32_16x16x32_bf16 v[64:67], v[220:223], v[204:207], v[64:67]
	v_mfma_f32_16x16x32_bf16 v[116:119], v[216:219], v[180:183], v[116:119]
	v_mfma_f32_16x16x32_bf16 v[112:115], v[224:227], v[180:183], v[112:115]
	v_mfma_f32_16x16x32_bf16 v[100:103], v[216:219], v[188:191], v[100:103]
	v_mfma_f32_16x16x32_bf16 v[96:99], v[224:227], v[188:191], v[96:99]
	v_mfma_f32_16x16x32_bf16 v[84:87], v[216:219], v[196:199], v[84:87]
	v_mfma_f32_16x16x32_bf16 v[80:83], v[224:227], v[196:199], v[80:83]
	v_mfma_f32_16x16x32_bf16 v[68:71], v[216:219], v[208:211], v[68:71]
	v_mfma_f32_16x16x32_bf16 v[64:67], v[224:227], v[208:211], v[64:67]
	s_mov_b32 m0, s37
	v_lshl_add_u64 v[230:231], s[40:41], 0, v[138:139]
	s_barrier
	ds_read_b128 v[176:179], v158 offset:16384
	ds_read_b128 v[180:183], v158 offset:17408
	ds_read_b128 v[184:187], v158 offset:18432
	ds_read_b128 v[188:191], v158 offset:19456
	ds_read_b128 v[192:195], v158 offset:20480
	ds_read_b128 v[196:199], v158 offset:21504
	ds_read_b128 v[204:207], v158 offset:22528
	ds_read_b128 v[208:211], v158 offset:23552
	global_load_lds_dwordx4 v[230:231], off
	v_lshl_add_u64 v[232:233], s[40:41], 0, v[132:133]
	s_mov_b32 m0, s51
	s_nop 0
	global_load_lds_dwordx4 v[232:233], off
	s_barrier
	s_waitcnt lgkmcnt(0)
	v_mfma_f32_16x16x32_bf16 v[60:63], v[160:163], v[176:179], v[60:63]
	v_mfma_f32_16x16x32_bf16 v[56:59], v[168:171], v[176:179], v[56:59]
	v_mfma_f32_16x16x32_bf16 v[44:47], v[160:163], v[184:187], v[44:47]
	v_mfma_f32_16x16x32_bf16 v[40:43], v[168:171], v[184:187], v[40:43]
	v_mfma_f32_16x16x32_bf16 v[28:31], v[160:163], v[192:195], v[28:31]
	v_mfma_f32_16x16x32_bf16 v[24:27], v[168:171], v[192:195], v[24:27]
	v_mfma_f32_16x16x32_bf16 v[12:15], v[160:163], v[204:207], v[12:15]
	v_mfma_f32_16x16x32_bf16 v[8:11], v[168:171], v[204:207], v[8:11]
	v_mfma_f32_16x16x32_bf16 v[60:63], v[164:167], v[180:183], v[60:63]
	v_mfma_f32_16x16x32_bf16 v[56:59], v[172:175], v[180:183], v[56:59]
	v_mfma_f32_16x16x32_bf16 v[44:47], v[164:167], v[188:191], v[44:47]
	v_mfma_f32_16x16x32_bf16 v[40:43], v[172:175], v[188:191], v[40:43]
	v_mfma_f32_16x16x32_bf16 v[28:31], v[164:167], v[196:199], v[28:31]
	v_mfma_f32_16x16x32_bf16 v[24:27], v[172:175], v[196:199], v[24:27]
	v_mfma_f32_16x16x32_bf16 v[12:15], v[164:167], v[208:211], v[12:15]
	v_mfma_f32_16x16x32_bf16 v[8:11], v[172:175], v[208:211], v[8:11]
	s_barrier
	s_add_i32 s33, s61, s49
	v_lshl_add_u64 v[234:235], s[42:43], 0, v[136:137]
	s_mov_b32 m0, s33
	v_lshl_add_u64 v[236:237], s[42:43], 0, v[130:131]
	global_load_lds_dwordx4 v[234:235], off
	s_add_i32 m0, s33, 0x2000
	s_nop 0
	global_load_lds_dwordx4 v[236:237], off
	s_waitcnt vmcnt(6)
	s_barrier
; #define PG8_STAGE(bufoff, gbase, voff) do { _Pragma("unroll") for (int _i = 0; _i < 2; ++_i) \
;         __builtin_amdgcn_global_load_lds((const unsigned*)((const char*)(gbase) + (voff)[_i]), (LAS unsigned*)(lds + (bufoff) + ldsw + _i * 8192), 16, 0, 0); } while (0)
; #define PG8_LDA(dst, b, h) do { _Pragma("unroll") for (int m = 0; m < 4; ++m) _Pragma("unroll") for (int k = 0; k < 2; ++k) dst[m][k] = *(const LAS bf16x8*)(lds + PG8_SA(b, h) + aoff + m * 2048 + k * 1024); } while (0)
; #define PG8_LDB(dst, b, h) do { _Pragma("unroll") for (int n = 0; n < 2; ++n) _Pragma("unroll") for (int k = 0; k < 2; ++k) dst[n][k] = *(const LAS bf16x8*)(lds + PG8_SB(b, h) + boff + n * 2048 + k * 1024); } while (0)
; #define PG8_MMA(ai, bj, At, Bt) do { __builtin_amdgcn_s_setprio(1); _Pragma("unroll") for (int m = 0; m < 4; ++m) _Pragma("unroll") for (int n = 0; n < 2; ++n) _Pragma("unroll") for (int k = 0; k < 2; ++k) \
;         acc[ai][bj][m][n] = __builtin_amdgcn_mfma_f32_16x16x32_bf16(Bt[n][k], At[m][k], acc[ai][bj][m][n], 0, 0, 0); __builtin_amdgcn_s_setprio(0); } while (0)
; #define PG8_WAIT_V(n) asm volatile("s_waitcnt vmcnt(" #n ")" ::: "memory")
; #define PG8_WAIT_L(n) asm volatile("s_waitcnt lgkmcnt(" #n ")" ::: "memory")
; #define PG8_BAR __builtin_amdgcn_s_barrier()
; #define PG8_SCHED __builtin_amdgcn_sched_barrier(0)
; template <class Epi>
; __device__ __forceinline__ void gemm_phase(LAS unsigned char* lds, const Gemm g, const StaticOrder& S, const Epi& E) {
;     ...
;             PG8_WAIT_V(6); PG8_BAR; PG8_MMA(1, 1, At, B1); PG8_BAR;
;             PG8_LDB(B0, 1, 0); PG8_SCHED; PG8_LDA(At, 1, 0); PG8_STAGE(PG8_SA(0, 1), a2 + hstep, voffA);
;             PG8_WAIT_L(8); PG8_BAR; PG8_WAIT_L(0); PG8_MMA(0, 0, At, B0); PG8_BAR; PG8_SCHED;
;             PG8_LDB(B1, 1, 1); PG8_STAGE(PG8_SB(1, 0), b3, voffB0);
;             PG8_BAR; PG8_WAIT_L(0); PG8_MMA(0, 1, At, B1); PG8_BAR;
;             PG8_LDA(At, 1, 1); PG8_STAGE(PG8_SA(1, 0), a3, voffA);
;             PG8_BAR; PG8_WAIT_L(0); PG8_MMA(1, 0, At, B0); PG8_BAR; PG8_SCHED;
;             PG8_STAGE(PG8_SB(1, 1), b3, voffB1);
	v_mfma_f32_16x16x32_bf16 v[52:55], v[212:215], v[176:179], v[52:55]
	v_mfma_f32_16x16x32_bf16 v[48:51], v[220:223], v[176:179], v[48:51]
	v_mfma_f32_16x16x32_bf16 v[36:39], v[212:215], v[184:187], v[36:39]
	v_mfma_f32_16x16x32_bf16 v[32:35], v[220:223], v[184:187], v[32:35]
	v_mfma_f32_16x16x32_bf16 v[20:23], v[212:215], v[192:195], v[20:23]
	v_mfma_f32_16x16x32_bf16 v[16:19], v[220:223], v[192:195], v[16:19]
	v_mfma_f32_16x16x32_bf16 v[4:7], v[212:215], v[204:207], v[4:7]
	v_mfma_f32_16x16x32_bf16 v[0:3], v[220:223], v[204:207], v[0:3]
	v_mfma_f32_16x16x32_bf16 v[52:55], v[216:219], v[180:183], v[52:55]
	v_mfma_f32_16x16x32_bf16 v[48:51], v[224:227], v[180:183], v[48:51]
	v_mfma_f32_16x16x32_bf16 v[36:39], v[216:219], v[188:191], v[36:39]
	v_mfma_f32_16x16x32_bf16 v[32:35], v[224:227], v[188:191], v[32:35]
	v_mfma_f32_16x16x32_bf16 v[20:23], v[216:219], v[196:199], v[20:23]
	v_mfma_f32_16x16x32_bf16 v[16:19], v[224:227], v[196:199], v[16:19]
	v_mfma_f32_16x16x32_bf16 v[4:7], v[216:219], v[208:211], v[4:7]
	v_mfma_f32_16x16x32_bf16 v[0:3], v[224:227], v[208:211], v[0:3]
	s_add_i32 s33, 0, 0x18000
	v_add_u32_e32 v172, s33, v147
	s_barrier
	ds_read_b128 v[160:163], v172
	ds_read_b128 v[164:167], v172 offset:1024
	ds_read_b128 v[168:171], v172 offset:2048
	ds_read_b128 v[172:175], v172 offset:3072
	s_add_u32 s40, s40, 0x20000
	s_addc_u32 s41, s41, 0
	s_mov_b32 m0, s52
	v_lshl_add_u64 v[212:213], s[40:41], 0, v[138:139]
	ds_read_b128 v[176:179], v158 offset:32768
	ds_read_b128 v[180:183], v158 offset:33792
	ds_read_b128 v[184:187], v158 offset:34816
	ds_read_b128 v[188:191], v158 offset:35840
	ds_read_b128 v[192:195], v158 offset:36864
	ds_read_b128 v[196:199], v158 offset:37888
	ds_read_b128 v[204:207], v158 offset:38912
	ds_read_b128 v[208:211], v158 offset:39936
	global_load_lds_dwordx4 v[212:213], off
	v_lshl_add_u64 v[212:213], s[40:41], 0, v[132:133]
	s_mov_b32 m0, s53
	s_nop 0
	global_load_lds_dwordx4 v[212:213], off
	s_waitcnt lgkmcnt(8)
	s_barrier
	s_waitcnt lgkmcnt(0)
	v_mfma_f32_16x16x32_bf16 v[124:127], v[160:163], v[176:179], v[124:127]
	v_mfma_f32_16x16x32_bf16 v[120:123], v[168:171], v[176:179], v[120:123]
	v_mfma_f32_16x16x32_bf16 v[108:111], v[160:163], v[184:187], v[108:111]
	v_mfma_f32_16x16x32_bf16 v[104:107], v[168:171], v[184:187], v[104:107]
	v_mfma_f32_16x16x32_bf16 v[92:95], v[160:163], v[192:195], v[92:95]
	v_mfma_f32_16x16x32_bf16 v[88:91], v[168:171], v[192:195], v[88:91]
	v_mfma_f32_16x16x32_bf16 v[76:79], v[160:163], v[204:207], v[76:79]
	v_mfma_f32_16x16x32_bf16 v[72:75], v[168:171], v[204:207], v[72:75]
	v_mfma_f32_16x16x32_bf16 v[124:127], v[164:167], v[180:183], v[124:127]
	v_mfma_f32_16x16x32_bf16 v[120:123], v[172:175], v[180:183], v[120:123]
	v_mfma_f32_16x16x32_bf16 v[108:111], v[164:167], v[188:191], v[108:111]
	v_mfma_f32_16x16x32_bf16 v[104:107], v[172:175], v[188:191], v[104:107]
	v_mfma_f32_16x16x32_bf16 v[92:95], v[164:167], v[196:199], v[92:95]
	v_mfma_f32_16x16x32_bf16 v[88:91], v[172:175], v[196:199], v[88:91]
	v_mfma_f32_16x16x32_bf16 v[76:79], v[164:167], v[208:211], v[76:79]
	v_mfma_f32_16x16x32_bf16 v[72:75], v[172:175], v[208:211], v[72:75]
	s_barrier
	s_add_i32 s40, 0, 0x1c000
	s_add_i32 s33, s33, s49
	v_add_u32_e32 v224, s40, v147
	v_lshl_add_u64 v[200:201], v[200:201], 0, s[8:9]
	s_mov_b32 m0, s33
	ds_read_b128 v[212:215], v224
	ds_read_b128 v[216:219], v224 offset:1024
	ds_read_b128 v[220:223], v224 offset:2048
	ds_read_b128 v[224:227], v224 offset:3072
	global_load_lds_dwordx4 v[200:201], off
	v_lshl_add_u64 v[200:201], v[228:229], 0, s[8:9]
	s_add_i32 m0, s33, 0x2000
	s_nop 0
	global_load_lds_dwordx4 v[200:201], off
	s_barrier
	s_waitcnt lgkmcnt(0)
	v_mfma_f32_16x16x32_bf16 v[116:119], v[212:215], v[176:179], v[116:119]
	v_mfma_f32_16x16x32_bf16 v[112:115], v[220:223], v[176:179], v[112:115]
	v_mfma_f32_16x16x32_bf16 v[100:103], v[212:215], v[184:187], v[100:103]
	v_mfma_f32_16x16x32_bf16 v[96:99], v[220:223], v[184:187], v[96:99]
	v_mfma_f32_16x16x32_bf16 v[84:87], v[212:215], v[192:195], v[84:87]
	v_mfma_f32_16x16x32_bf16 v[80:83], v[220:223], v[192:195], v[80:83]
	v_mfma_f32_16x16x32_bf16 v[68:71], v[212:215], v[204:207], v[68:71]
	v_mfma_f32_16x16x32_bf16 v[64:67], v[220:223], v[204:207], v[64:67]
	v_mfma_f32_16x16x32_bf16 v[116:119], v[216:219], v[180:183], v[116:119]
	v_mfma_f32_16x16x32_bf16 v[112:115], v[224:227], v[180:183], v[112:115]
	v_mfma_f32_16x16x32_bf16 v[100:103], v[216:219], v[188:191], v[100:103]
	v_mfma_f32_16x16x32_bf16 v[96:99], v[224:227], v[188:191], v[96:99]
	v_mfma_f32_16x16x32_bf16 v[84:87], v[216:219], v[196:199], v[84:87]
	v_mfma_f32_16x16x32_bf16 v[80:83], v[224:227], v[196:199], v[80:83]
	v_mfma_f32_16x16x32_bf16 v[68:71], v[216:219], v[208:211], v[68:71]
	v_mfma_f32_16x16x32_bf16 v[64:67], v[224:227], v[208:211], v[64:67]
	s_mov_b32 m0, s55
	v_lshl_add_u64 v[200:201], v[230:231], 0, s[8:9]
	s_barrier
	ds_read_b128 v[176:179], v158 offset:49152
	ds_read_b128 v[180:183], v158 offset:50176
	ds_read_b128 v[184:187], v158 offset:51200
	ds_read_b128 v[188:191], v158 offset:52224
	ds_read_b128 v[192:195], v158 offset:53248
	ds_read_b128 v[196:199], v158 offset:54272
	ds_read_b128 v[204:207], v158 offset:55296
	ds_read_b128 v[208:211], v158 offset:56320
	global_load_lds_dwordx4 v[200:201], off
	v_lshl_add_u64 v[200:201], v[232:233], 0, s[8:9]
	s_mov_b32 m0, s56
	s_nop 0
	global_load_lds_dwordx4 v[200:201], off
	s_barrier
; #define PG8_BAR __builtin_amdgcn_s_barrier()
; __device__ __forceinline__ unsigned dpp_ror8(unsigned x) { return (unsigned)__builtin_amdgcn_update_dpp(0, (int)x, 0x128, 0xf, 0xf, false); }
; __device__ __forceinline__ void store_pair_lines(bf16_t* O, int ldc, int row, int fr, int col0, u32x4 wA, u32x4 wB) {
;     const u32x4 sA = {dpp_ror8(wA.x), dpp_ror8(wA.y), dpp_ror8(wA.z), dpp_ror8(wA.w)}, sB = {dpp_ror8(wB.x), dpp_ror8(wB.y), dpp_ror8(wB.z), dpp_ror8(wB.w)};
;     const bool lo = fr < 8;
;     const u32x4 o1 = lo ? wA : sB, o2 = lo ? sA : wB;
;     const int r1 = row - fr + (fr & 7), cb = col0 + (lo ? 0 : 8);
;     *(u32x4*)(O + (size_t)r1 * ldc + cb) = o1;
;     *(u32x4*)(O + (size_t)(r1 + 8) * ldc + cb) = o2;
; }
;     const bool lo = fr < 8;
;     const int r1 = row - fr + (fr & 7), cb = col0 + (lo ? 0 : boff);
;     const u32x4 l1 = *(const u32x4*)(P + (size_t)r1 * ld + cb), l2 = *(const u32x4*)(P + (size_t)(r1 + 8) * ld + cb);
;     const u32x4 s1 = {dpp_ror8(l1.x), dpp_ror8(l1.y), dpp_ror8(l1.z), dpp_ror8(l1.w)}, s2 = {dpp_ror8(l2.x), dpp_ror8(l2.y), dpp_ror8(l2.z), dpp_ror8(l2.w)};
;     wA = lo ? l1 : s2; wB = lo ? s1 : l2;
; }
;     __device__ __forceinline__ void operator()(const f32x4 (&acc)[2][2][4][2], const Unit& u, int wr, int wc, int fr, int fq) const {
;         const int row0 = u.pm * BM + wr * 64 + fr; const int col0 = u.pn * BM + wc * 64 + 16 * fq;
; #pragma unroll
;         for (int ai = 0; ai < 2; ++ai)
; #pragma unroll
;             for (int m = 0; m < 4; ++m) { const int row = row0 + ai * HALF + m * 16;
;                 const float rs = ssin ? __builtin_amdgcn_rsqf(ssin[row] * (1.f / D) + EPS) : 1.0f; float sq = 0.f; u32x4 w[2];
; #pragma unroll
;                 for (int bj = 0; bj < 2; ++bj) { f32x4 v0 = acc[ai][bj][m][0] * rs, v1 = acc[ai][bj][m][1] * rs;
;                     if (ACT == 1) {
; #pragma unroll
; template <class Epi>
; __device__ __forceinline__ void gemm_phase(LAS unsigned char* lds, const Gemm g, const StaticOrder& S, const Epi& E) {
;     ...
;             PG8_BAR; PG8_WAIT_L(0); PG8_MMA(0, 1, At, B1); PG8_BAR;
;             PG8_LDA(At, 1, 1); PG8_STAGE(PG8_SA(1, 0), a3, voffA);
;             PG8_BAR; PG8_WAIT_L(0); PG8_MMA(1, 0, At, B0); PG8_BAR; PG8_SCHED;
;             PG8_STAGE(PG8_SB(1, 1), b3, voffB1);
;             PG8_WAIT_V(6); PG8_BAR; PG8_MMA(1, 1, At, B1); PG8_BAR;
;         }
	s_waitcnt lgkmcnt(0)
	v_mfma_f32_16x16x32_bf16 v[60:63], v[160:163], v[176:179], v[60:63]
	v_mfma_f32_16x16x32_bf16 v[56:59], v[168:171], v[176:179], v[56:59]
	v_mfma_f32_16x16x32_bf16 v[44:47], v[160:163], v[184:187], v[44:47]
	v_mfma_f32_16x16x32_bf16 v[40:43], v[168:171], v[184:187], v[40:43]
	v_mfma_f32_16x16x32_bf16 v[28:31], v[160:163], v[192:195], v[28:31]
	v_mfma_f32_16x16x32_bf16 v[24:27], v[168:171], v[192:195], v[24:27]
	v_mfma_f32_16x16x32_bf16 v[12:15], v[160:163], v[204:207], v[12:15]
	v_mfma_f32_16x16x32_bf16 v[8:11], v[168:171], v[204:207], v[8:11]
	v_mfma_f32_16x16x32_bf16 v[60:63], v[164:167], v[180:183], v[60:63]
	v_mfma_f32_16x16x32_bf16 v[56:59], v[172:175], v[180:183], v[56:59]
	v_mfma_f32_16x16x32_bf16 v[44:47], v[164:167], v[188:191], v[44:47]
	v_mfma_f32_16x16x32_bf16 v[40:43], v[172:175], v[188:191], v[40:43]
	v_mfma_f32_16x16x32_bf16 v[28:31], v[164:167], v[196:199], v[28:31]
	v_mfma_f32_16x16x32_bf16 v[24:27], v[172:175], v[196:199], v[24:27]
	v_mfma_f32_16x16x32_bf16 v[12:15], v[164:167], v[208:211], v[12:15]
	v_mfma_f32_16x16x32_bf16 v[8:11], v[172:175], v[208:211], v[8:11]
	s_barrier
	s_add_i32 s33, s40, s49
	v_lshl_add_u64 v[160:161], v[234:235], 0, s[8:9]
	s_mov_b32 m0, s33
	s_nop 0
	global_load_lds_dwordx4 v[160:161], off
	v_lshl_add_u64 v[160:161], v[236:237], 0, s[8:9]
	s_add_i32 m0, s33, 0x2000
	s_nop 0
	global_load_lds_dwordx4 v[160:161], off
	s_waitcnt vmcnt(6)
	s_barrier
	v_mfma_f32_16x16x32_bf16 v[52:55], v[212:215], v[176:179], v[52:55]
	v_mfma_f32_16x16x32_bf16 v[48:51], v[220:223], v[176:179], v[48:51]
	v_mfma_f32_16x16x32_bf16 v[36:39], v[212:215], v[184:187], v[36:39]
	v_mfma_f32_16x16x32_bf16 v[32:35], v[220:223], v[184:187], v[32:35]
	v_mfma_f32_16x16x32_bf16 v[20:23], v[212:215], v[192:195], v[20:23]
	v_mfma_f32_16x16x32_bf16 v[16:19], v[220:223], v[192:195], v[16:19]
	v_mfma_f32_16x16x32_bf16 v[4:7], v[212:215], v[204:207], v[4:7]
	v_mfma_f32_16x16x32_bf16 v[0:3], v[220:223], v[204:207], v[0:3]
	v_mfma_f32_16x16x32_bf16 v[52:55], v[216:219], v[180:183], v[52:55]
	v_mfma_f32_16x16x32_bf16 v[48:51], v[224:227], v[180:183], v[48:51]
	v_mfma_f32_16x16x32_bf16 v[36:39], v[216:219], v[188:191], v[36:39]
	v_mfma_f32_16x16x32_bf16 v[32:35], v[224:227], v[188:191], v[32:35]
	v_mfma_f32_16x16x32_bf16 v[20:23], v[216:219], v[196:199], v[20:23]
	v_mfma_f32_16x16x32_bf16 v[16:19], v[224:227], v[196:199], v[16:19]
	v_mfma_f32_16x16x32_bf16 v[4:7], v[216:219], v[208:211], v[4:7]
	v_mfma_f32_16x16x32_bf16 v[0:3], v[224:227], v[208:211], v[0:3]
	s_add_i32 s68, s68, 2
	s_add_u32 s38, s38, 0x100
	s_addc_u32 s39, s39, 0
	s_add_u32 s66, s66, 0x100
	s_addc_u32 s67, s67, 0
	s_cmp_gt_u32 s68, 5
	s_barrier
	s_cbranch_scc0 .LBB0_234
	s_lshl_b32 s11, s36, 8
	v_cvt_pk_bf16_f32 v124, v124, v125
	v_cvt_pk_bf16_f32 v125, v126, v127
	v_cvt_pk_bf16_f32 v120, v120, v121
	v_cvt_pk_bf16_f32 v121, v122, v123
	v_cvt_pk_bf16_f32 v122, v116, v117
	v_cvt_pk_bf16_f32 v123, v118, v119
	v_cvt_pk_bf16_f32 v112, v112, v113
	v_cvt_pk_bf16_f32 v113, v114, v115
	s_add_i32 s11, s11, s57
	v_lshl_or_b32 v162, s63, 8, v156
	v_mov_b32_dpp v114, v124 row_ror:8 row_mask:0xf bank_mask:0xf
	v_mov_b32_dpp v115, v125 row_ror:8 row_mask:0xf bank_mask:0xf
	v_mov_b32_dpp v126, v120 row_ror:8 row_mask:0xf bank_mask:0xf
	v_mov_b32_dpp v127, v121 row_ror:8 row_mask:0xf bank_mask:0xf
	v_mov_b32_dpp v118, v112 row_ror:8 row_mask:0xf bank_mask:0xf
	v_mov_b32_dpp v119, v113 row_ror:8 row_mask:0xf bank_mask:0xf
	v_ashrrev_i32_e32 v163, 31, v162
	v_mov_b32_dpp v116, v122 row_ror:8 row_mask:0xf bank_mask:0xf
	v_mov_b32_dpp v117, v123 row_ror:8 row_mask:0xf bank_mask:0xf
	v_cndmask_b32_e64 v118, v118, v120, s[4:5]
	v_cndmask_b32_e64 v119, v119, v121, s[4:5]
	v_cndmask_b32_e64 v120, v122, v114, s[4:5]
	v_cndmask_b32_e64 v121, v123, v115, s[4:5]
	v_cndmask_b32_e64 v122, v112, v126, s[4:5]
	v_cndmask_b32_e64 v123, v113, v127, s[4:5]
	v_or_b32_e32 v126, s11, v148
	v_mov_b64_e32 v[112:113], s[6:7]
	v_cndmask_b32_e64 v116, v116, v124, s[4:5]
	v_cndmask_b32_e64 v117, v117, v125, s[4:5]
	v_mad_i64_i32 v[124:125], s[38:39], v126, s62, v[112:113]
	v_lshlrev_b64 v[114:115], 1, v[162:163]
	v_lshl_add_u64 v[124:125], v[124:125], 0, v[114:115]
	global_store_dwordx4 v[124:125], v[116:119], off
	v_or_b32_e32 v160, s11, v146
	s_and_b64 vcc, exec, s[30:31]
	v_or_b32_e32 v116, 8, v126
	v_mad_i64_i32 v[116:117], s[38:39], v116, s62, v[112:113]
	v_lshl_add_u64 v[116:117], v[116:117], 0, v[114:115]
	global_store_dwordx4 v[116:117], v[120:123], off
	v_cvt_pk_bf16_f32 v108, v108, v109
	v_cvt_pk_bf16_f32 v109, v110, v111
	v_cvt_pk_bf16_f32 v104, v104, v105
	v_cvt_pk_bf16_f32 v105, v106, v107
	v_cvt_pk_bf16_f32 v100, v100, v101
	v_cvt_pk_bf16_f32 v101, v102, v103
	v_cvt_pk_bf16_f32 v102, v96, v97
	v_cvt_pk_bf16_f32 v103, v98, v99
	s_nop 0
	v_mov_b32_dpp v106, v108 row_ror:8 row_mask:0xf bank_mask:0xf
	v_mov_b32_dpp v96, v100 row_ror:8 row_mask:0xf bank_mask:0xf
	v_mov_b32_dpp v98, v102 row_ror:8 row_mask:0xf bank_mask:0xf
	v_mov_b32_dpp v99, v103 row_ror:8 row_mask:0xf bank_mask:0xf
	v_cndmask_b32_e64 v100, v100, v106, s[4:5]
	v_add_u32_e32 v106, v149, v160
	v_mov_b32_dpp v110, v104 row_ror:8 row_mask:0xf bank_mask:0xf
	v_mov_b32_dpp v111, v105 row_ror:8 row_mask:0xf bank_mask:0xf
	v_mov_b32_dpp v97, v101 row_ror:8 row_mask:0xf bank_mask:0xf
	v_cndmask_b32_e64 v98, v98, v104, s[4:5]
	v_cndmask_b32_e64 v99, v99, v105, s[4:5]
	v_mad_i64_i32 v[104:105], s[38:39], v106, s62, v[112:113]
	v_cndmask_b32_e64 v96, v96, v108, s[4:5]
	v_cndmask_b32_e64 v97, v97, v109, s[4:5]
	v_lshl_add_u64 v[104:105], v[104:105], 0, v[114:115]
	global_store_dwordx4 v[104:105], v[96:99], off
; __device__ __forceinline__ unsigned cvt_pk_bf16(float lo, float hi) { unsigned r; asm volatile("v_cvt_pk_bf16_f32 %0, %1, %2" : "=v"(r) : "v"(lo), "v"(hi)); return r; }
; __device__ __forceinline__ unsigned dpp_ror8(unsigned x) { return (unsigned)__builtin_amdgcn_update_dpp(0, (int)x, 0x128, 0xf, 0xf, false); }
; __device__ __forceinline__ void store_pair_lines(bf16_t* O, int ldc, int row, int fr, int col0, u32x4 wA, u32x4 wB) {
;     const u32x4 sA = {dpp_ror8(wA.x), dpp_ror8(wA.y), dpp_ror8(wA.z), dpp_ror8(wA.w)}, sB = {dpp_ror8(wB.x), dpp_ror8(wB.y), dpp_ror8(wB.z), dpp_ror8(wB.w)};
;     const bool lo = fr < 8;
;     const u32x4 o1 = lo ? wA : sB, o2 = lo ? sA : wB;
;     const int r1 = row - fr + (fr & 7), cb = col0 + (lo ? 0 : 8);
;     *(u32x4*)(O + (size_t)r1 * ldc + cb) = o1;
;     *(u32x4*)(O + (size_t)(r1 + 8) * ldc + cb) = o2;
; }
;     __device__ __forceinline__ void operator()(const f32x4 (&acc)[2][2][4][2], const Unit& u, int wr, int wc, int fr, int fq) const {
;     ...
;             for (int m = 0; m < 4; ++m) { const int row = row0 + ai * HALF + m * 16;
;                 const float rs = ssin ? __builtin_amdgcn_rsqf(ssin[row] * (1.f / D) + EPS) : 1.0f; float sq = 0.f; u32x4 w[2];
; #pragma unroll
;                 for (int bj = 0; bj < 2; ++bj) { f32x4 v0 = acc[ai][bj][m][0] * rs, v1 = acc[ai][bj][m][1] * rs;
;                     if (ACT == 1) {
; #pragma unroll
;                         for (int j = 0; j < 4; ++j) { const float a = fmaxf(v0[j], 0.f), b = fmaxf(v1[j], 0.f); v0[j] = a * a; v1[j] = b * b; } }
;                     sq += (v0[0] * v0[0] + v0[1] * v0[1]) + (v0[2] * v0[2] + v0[3] * v0[3]) + (v1[0] * v1[0] + v1[1] * v1[1]) + (v1[2] * v1[2] + v1[3] * v1[3]);
;                     w[bj].x = cvt_pk_bf16(v0[0], v0[1]); w[bj].y = cvt_pk_bf16(v0[2], v0[3]); w[bj].z = cvt_pk_bf16(v1[0], v1[1]); w[bj].w = cvt_pk_bf16(v1[2], v1[3]); }
;                 store_pair_lines(O, ldc, row, fr, col0, w[0], w[1]);
;                 if (ssout) { sq += __shfl_xor(sq, 16); sq += __shfl_xor(sq, 32); if (fq == 0) unsafeAtomicAdd(ssout + row, sq); } }
	v_cndmask_b32_e64 v102, v102, v110, s[4:5]
	v_mov_b32_dpp v107, v109 row_ror:8 row_mask:0xf bank_mask:0xf
	v_add_u32_e32 v96, 8, v106
	v_mad_i64_i32 v[96:97], s[38:39], v96, s62, v[112:113]
	v_cndmask_b32_e64 v101, v101, v107, s[4:5]
	v_cndmask_b32_e64 v103, v103, v111, s[4:5]
	v_lshl_add_u64 v[96:97], v[96:97], 0, v[114:115]
	global_store_dwordx4 v[96:97], v[100:103], off
	v_cvt_pk_bf16_f32 v92, v92, v93
	v_cvt_pk_bf16_f32 v93, v94, v95
	v_cvt_pk_bf16_f32 v88, v88, v89
	v_cvt_pk_bf16_f32 v89, v90, v91
	v_cvt_pk_bf16_f32 v84, v84, v85
	v_cvt_pk_bf16_f32 v85, v86, v87
	v_cvt_pk_bf16_f32 v86, v80, v81
	v_cvt_pk_bf16_f32 v87, v82, v83
	s_nop 0
	v_mov_b32_dpp v90, v92 row_ror:8 row_mask:0xf bank_mask:0xf
	v_mov_b32_dpp v80, v84 row_ror:8 row_mask:0xf bank_mask:0xf
	v_mov_b32_dpp v82, v86 row_ror:8 row_mask:0xf bank_mask:0xf
	v_mov_b32_dpp v83, v87 row_ror:8 row_mask:0xf bank_mask:0xf
	v_cndmask_b32_e64 v84, v84, v90, s[4:5]
	v_add_u32_e32 v90, v150, v160
	v_mov_b32_dpp v94, v88 row_ror:8 row_mask:0xf bank_mask:0xf
	v_mov_b32_dpp v95, v89 row_ror:8 row_mask:0xf bank_mask:0xf
	v_mov_b32_dpp v81, v85 row_ror:8 row_mask:0xf bank_mask:0xf
	v_cndmask_b32_e64 v82, v82, v88, s[4:5]
	v_cndmask_b32_e64 v83, v83, v89, s[4:5]
	v_mad_i64_i32 v[88:89], s[38:39], v90, s62, v[112:113]
	v_cndmask_b32_e64 v80, v80, v92, s[4:5]
	v_cndmask_b32_e64 v81, v81, v93, s[4:5]
	v_lshl_add_u64 v[88:89], v[88:89], 0, v[114:115]
	global_store_dwordx4 v[88:89], v[80:83], off
	v_cndmask_b32_e64 v86, v86, v94, s[4:5]
	v_mov_b32_dpp v91, v93 row_ror:8 row_mask:0xf bank_mask:0xf
	v_add_u32_e32 v80, 8, v90
	v_mad_i64_i32 v[80:81], s[38:39], v80, s62, v[112:113]
	v_cndmask_b32_e64 v85, v85, v91, s[4:5]
	v_cndmask_b32_e64 v87, v87, v95, s[4:5]
	v_lshl_add_u64 v[80:81], v[80:81], 0, v[114:115]
	global_store_dwordx4 v[80:81], v[84:87], off
	v_cvt_pk_bf16_f32 v76, v76, v77
	v_cvt_pk_bf16_f32 v77, v78, v79
	v_cvt_pk_bf16_f32 v72, v72, v73
	v_cvt_pk_bf16_f32 v73, v74, v75
	v_cvt_pk_bf16_f32 v68, v68, v69
	v_cvt_pk_bf16_f32 v69, v70, v71
	v_cvt_pk_bf16_f32 v70, v64, v65
	v_cvt_pk_bf16_f32 v71, v66, v67
	s_nop 0
	v_mov_b32_dpp v74, v76 row_ror:8 row_mask:0xf bank_mask:0xf
	v_mov_b32_dpp v64, v68 row_ror:8 row_mask:0xf bank_mask:0xf
	v_mov_b32_dpp v66, v70 row_ror:8 row_mask:0xf bank_mask:0xf
	v_mov_b32_dpp v67, v71 row_ror:8 row_mask:0xf bank_mask:0xf
	v_cndmask_b32_e64 v68, v68, v74, s[4:5]
	v_add_u32_e32 v74, v151, v160
	v_mov_b32_dpp v78, v72 row_ror:8 row_mask:0xf bank_mask:0xf
	v_mov_b32_dpp v79, v73 row_ror:8 row_mask:0xf bank_mask:0xf
	v_mov_b32_dpp v65, v69 row_ror:8 row_mask:0xf bank_mask:0xf
	v_cndmask_b32_e64 v66, v66, v72, s[4:5]
	v_cndmask_b32_e64 v67, v67, v73, s[4:5]
	v_mad_i64_i32 v[72:73], s[38:39], v74, s62, v[112:113]
	v_cndmask_b32_e64 v64, v64, v76, s[4:5]
	v_cndmask_b32_e64 v65, v65, v77, s[4:5]
	v_lshl_add_u64 v[72:73], v[72:73], 0, v[114:115]
	global_store_dwordx4 v[72:73], v[64:67], off
	v_cndmask_b32_e64 v70, v70, v78, s[4:5]
	v_mov_b32_dpp v75, v77 row_ror:8 row_mask:0xf bank_mask:0xf
	v_add_u32_e32 v64, 8, v74
	v_mad_i64_i32 v[64:65], s[38:39], v64, s62, v[112:113]
	v_cndmask_b32_e64 v69, v69, v75, s[4:5]
	v_cndmask_b32_e64 v71, v71, v79, s[4:5]
	v_lshl_add_u64 v[64:65], v[64:65], 0, v[114:115]
	global_store_dwordx4 v[64:65], v[68:71], off
	v_cvt_pk_bf16_f32 v60, v60, v61
	v_cvt_pk_bf16_f32 v61, v62, v63
	v_cvt_pk_bf16_f32 v56, v56, v57
	v_cvt_pk_bf16_f32 v57, v58, v59
	v_cvt_pk_bf16_f32 v52, v52, v53
	v_cvt_pk_bf16_f32 v53, v54, v55
	v_cvt_pk_bf16_f32 v54, v48, v49
	v_cvt_pk_bf16_f32 v55, v50, v51
	s_nop 0
	v_mov_b32_dpp v58, v60 row_ror:8 row_mask:0xf bank_mask:0xf
	v_mov_b32_dpp v48, v52 row_ror:8 row_mask:0xf bank_mask:0xf
	v_mov_b32_dpp v50, v54 row_ror:8 row_mask:0xf bank_mask:0xf
	v_mov_b32_dpp v51, v55 row_ror:8 row_mask:0xf bank_mask:0xf
	v_cndmask_b32_e64 v52, v52, v58, s[4:5]
	v_add_u32_e32 v58, v152, v160
	v_mov_b32_dpp v62, v56 row_ror:8 row_mask:0xf bank_mask:0xf
	v_mov_b32_dpp v63, v57 row_ror:8 row_mask:0xf bank_mask:0xf
	v_mov_b32_dpp v49, v53 row_ror:8 row_mask:0xf bank_mask:0xf
	v_cndmask_b32_e64 v50, v50, v56, s[4:5]
	v_cndmask_b32_e64 v51, v51, v57, s[4:5]
	v_mad_i64_i32 v[56:57], s[38:39], v58, s62, v[112:113]
	v_cndmask_b32_e64 v48, v48, v60, s[4:5]
	v_cndmask_b32_e64 v49, v49, v61, s[4:5]
	v_lshl_add_u64 v[56:57], v[56:57], 0, v[114:115]
	global_store_dwordx4 v[56:57], v[48:51], off
	v_cndmask_b32_e64 v54, v54, v62, s[4:5]
	v_mov_b32_dpp v59, v61 row_ror:8 row_mask:0xf bank_mask:0xf
	v_add_u32_e32 v48, 8, v58
	v_mad_i64_i32 v[48:49], s[38:39], v48, s62, v[112:113]
	v_cndmask_b32_e64 v53, v53, v59, s[4:5]
; __device__ __forceinline__ unsigned cvt_pk_bf16(float lo, float hi) { unsigned r; asm volatile("v_cvt_pk_bf16_f32 %0, %1, %2" : "=v"(r) : "v"(lo), "v"(hi)); return r; }
; #define PG8_WAIT_V(n) asm volatile("s_waitcnt vmcnt(" #n ")" ::: "memory")
; #define PG8_BAR __builtin_amdgcn_s_barrier()
;     __device__ __forceinline__ void operator()(const f32x4 (&acc)[2][2][4][2], const Unit& u, int wr, int wc, int fr, int fq) const {
;     ...
;             for (int m = 0; m < 4; ++m) { const int row = row0 + ai * HALF + m * 16;
;                 const float rs = ssin ? __builtin_amdgcn_rsqf(ssin[row] * (1.f / D) + EPS) : 1.0f; float sq = 0.f; u32x4 w[2];
; #pragma unroll
;                 for (int bj = 0; bj < 2; ++bj) { f32x4 v0 = acc[ai][bj][m][0] * rs, v1 = acc[ai][bj][m][1] * rs;
;                     if (ACT == 1) {
; #pragma unroll
;                         for (int j = 0; j < 4; ++j) { const float a = fmaxf(v0[j], 0.f), b = fmaxf(v1[j], 0.f); v0[j] = a * a; v1[j] = b * b; } }
;                     sq += (v0[0] * v0[0] + v0[1] * v0[1]) + (v0[2] * v0[2] + v0[3] * v0[3]) + (v1[0] * v1[0] + v1[1] * v1[1]) + (v1[2] * v1[2] + v1[3] * v1[3]);
;                     w[bj].x = cvt_pk_bf16(v0[0], v0[1]); w[bj].y = cvt_pk_bf16(v0[2], v0[3]); w[bj].z = cvt_pk_bf16(v1[0], v1[1]); w[bj].w = cvt_pk_bf16(v1[2], v1[3]); }
;                 store_pair_lines(O, ldc, row, fr, col0, w[0], w[1]);
;                 if (ssout) { sq += __shfl_xor(sq, 16); sq += __shfl_xor(sq, 32); if (fq == 0) unsafeAtomicAdd(ssout + row, sq); } }
; template <class Epi>
; __device__ __forceinline__ void gemm_phase(LAS unsigned char* lds, const Gemm g, const StaticOrder& S, const Epi& E) {
;     ...
;         if (!has_next) break;
; #pragma unroll
;         for (int a = 0; a < 2; ++a)
; #pragma unroll
;             for (int b = 0; b < 2; ++b)
; #pragma unroll
;                 for (int m = 0; m < 4; ++m)
; #pragma unroll
;                     for (int n = 0; n < 2; ++n) acc[a][b][m][n] = (f32x4){0.f, 0.f, 0.f, 0.f};
;         cur = nxt; cA = nA; cB = nB; ++ui;
;     }
;     PG8_WAIT_V(0);
;     if (wr == 0) PG8_BAR;
;     PG8_BAR;
	v_cndmask_b32_e64 v55, v55, v63, s[4:5]
	v_lshl_add_u64 v[48:49], v[48:49], 0, v[114:115]
	global_store_dwordx4 v[48:49], v[52:55], off
	v_cvt_pk_bf16_f32 v44, v44, v45
	v_cvt_pk_bf16_f32 v45, v46, v47
	v_cvt_pk_bf16_f32 v40, v40, v41
	v_cvt_pk_bf16_f32 v41, v42, v43
	v_cvt_pk_bf16_f32 v36, v36, v37
	v_cvt_pk_bf16_f32 v37, v38, v39
	v_cvt_pk_bf16_f32 v38, v32, v33
	v_cvt_pk_bf16_f32 v39, v34, v35
	s_nop 0
	v_mov_b32_dpp v42, v44 row_ror:8 row_mask:0xf bank_mask:0xf
	v_mov_b32_dpp v32, v36 row_ror:8 row_mask:0xf bank_mask:0xf
	v_mov_b32_dpp v34, v38 row_ror:8 row_mask:0xf bank_mask:0xf
	v_mov_b32_dpp v35, v39 row_ror:8 row_mask:0xf bank_mask:0xf
	v_cndmask_b32_e64 v36, v36, v42, s[4:5]
	v_add_u32_e32 v42, v153, v160
	v_mov_b32_dpp v46, v40 row_ror:8 row_mask:0xf bank_mask:0xf
	v_mov_b32_dpp v47, v41 row_ror:8 row_mask:0xf bank_mask:0xf
	v_mov_b32_dpp v33, v37 row_ror:8 row_mask:0xf bank_mask:0xf
	v_cndmask_b32_e64 v34, v34, v40, s[4:5]
	v_cndmask_b32_e64 v35, v35, v41, s[4:5]
	v_mad_i64_i32 v[40:41], s[38:39], v42, s62, v[112:113]
	v_cndmask_b32_e64 v32, v32, v44, s[4:5]
	v_cndmask_b32_e64 v33, v33, v45, s[4:5]
	v_lshl_add_u64 v[40:41], v[40:41], 0, v[114:115]
	global_store_dwordx4 v[40:41], v[32:35], off
	v_cndmask_b32_e64 v38, v38, v46, s[4:5]
	v_mov_b32_dpp v43, v45 row_ror:8 row_mask:0xf bank_mask:0xf
	v_add_u32_e32 v32, 8, v42
	v_mad_i64_i32 v[32:33], s[38:39], v32, s62, v[112:113]
	v_cndmask_b32_e64 v37, v37, v43, s[4:5]
	v_cndmask_b32_e64 v39, v39, v47, s[4:5]
	v_lshl_add_u64 v[32:33], v[32:33], 0, v[114:115]
	global_store_dwordx4 v[32:33], v[36:39], off
	v_cvt_pk_bf16_f32 v28, v28, v29
	v_cvt_pk_bf16_f32 v29, v30, v31
	v_cvt_pk_bf16_f32 v24, v24, v25
	v_cvt_pk_bf16_f32 v25, v26, v27
	v_cvt_pk_bf16_f32 v20, v20, v21
	v_cvt_pk_bf16_f32 v21, v22, v23
	v_cvt_pk_bf16_f32 v22, v16, v17
	v_cvt_pk_bf16_f32 v23, v18, v19
	s_nop 0
	v_mov_b32_dpp v26, v28 row_ror:8 row_mask:0xf bank_mask:0xf
	v_mov_b32_dpp v16, v20 row_ror:8 row_mask:0xf bank_mask:0xf
	v_mov_b32_dpp v18, v22 row_ror:8 row_mask:0xf bank_mask:0xf
	v_mov_b32_dpp v19, v23 row_ror:8 row_mask:0xf bank_mask:0xf
	v_cndmask_b32_e64 v20, v20, v26, s[4:5]
	v_add_u32_e32 v26, v154, v160
	v_mov_b32_dpp v30, v24 row_ror:8 row_mask:0xf bank_mask:0xf
	v_mov_b32_dpp v31, v25 row_ror:8 row_mask:0xf bank_mask:0xf
	v_mov_b32_dpp v17, v21 row_ror:8 row_mask:0xf bank_mask:0xf
	v_cndmask_b32_e64 v18, v18, v24, s[4:5]
	v_cndmask_b32_e64 v19, v19, v25, s[4:5]
	v_mad_i64_i32 v[24:25], s[38:39], v26, s62, v[112:113]
	v_cndmask_b32_e64 v16, v16, v28, s[4:5]
	v_cndmask_b32_e64 v17, v17, v29, s[4:5]
	v_lshl_add_u64 v[24:25], v[24:25], 0, v[114:115]
	global_store_dwordx4 v[24:25], v[16:19], off
	v_cndmask_b32_e64 v22, v22, v30, s[4:5]
	v_mov_b32_dpp v27, v29 row_ror:8 row_mask:0xf bank_mask:0xf
	v_add_u32_e32 v16, 8, v26
	v_mad_i64_i32 v[16:17], s[38:39], v16, s62, v[112:113]
	v_cndmask_b32_e64 v21, v21, v27, s[4:5]
	v_cndmask_b32_e64 v23, v23, v31, s[4:5]
	v_lshl_add_u64 v[16:17], v[16:17], 0, v[114:115]
	global_store_dwordx4 v[16:17], v[20:23], off
	v_cvt_pk_bf16_f32 v12, v12, v13
	v_cvt_pk_bf16_f32 v13, v14, v15
	v_cvt_pk_bf16_f32 v8, v8, v9
	v_cvt_pk_bf16_f32 v9, v10, v11
	v_cvt_pk_bf16_f32 v4, v4, v5
	v_cvt_pk_bf16_f32 v5, v6, v7
	v_cvt_pk_bf16_f32 v6, v0, v1
	v_cvt_pk_bf16_f32 v7, v2, v3
	s_nop 0
	v_mov_b32_dpp v10, v12 row_ror:8 row_mask:0xf bank_mask:0xf
	v_mov_b32_dpp v0, v4 row_ror:8 row_mask:0xf bank_mask:0xf
	v_mov_b32_dpp v2, v6 row_ror:8 row_mask:0xf bank_mask:0xf
	v_mov_b32_dpp v3, v7 row_ror:8 row_mask:0xf bank_mask:0xf
	v_cndmask_b32_e64 v4, v4, v10, s[4:5]
	v_add_u32_e32 v10, v155, v160
	v_mov_b32_dpp v14, v8 row_ror:8 row_mask:0xf bank_mask:0xf
	v_mov_b32_dpp v15, v9 row_ror:8 row_mask:0xf bank_mask:0xf
	v_mov_b32_dpp v1, v5 row_ror:8 row_mask:0xf bank_mask:0xf
	v_cndmask_b32_e64 v2, v2, v8, s[4:5]
	v_cndmask_b32_e64 v3, v3, v9, s[4:5]
	v_mad_i64_i32 v[8:9], s[38:39], v10, s62, v[112:113]
	v_cndmask_b32_e64 v0, v0, v12, s[4:5]
	v_cndmask_b32_e64 v1, v1, v13, s[4:5]
	v_lshl_add_u64 v[8:9], v[8:9], 0, v[114:115]
	global_store_dwordx4 v[8:9], v[0:3], off
	v_cndmask_b32_e64 v6, v6, v14, s[4:5]
	v_mov_b32_dpp v11, v13 row_ror:8 row_mask:0xf bank_mask:0xf
	v_add_u32_e32 v0, 8, v10
	v_mad_i64_i32 v[0:1], s[38:39], v0, s62, v[112:113]
	v_cndmask_b32_e64 v5, v5, v11, s[4:5]
	v_cndmask_b32_e64 v7, v7, v15, s[4:5]
	v_lshl_add_u64 v[0:1], v[0:1], 0, v[114:115]
	s_mov_b32 s63, s10
	s_mov_b32 s36, s16
	s_mov_b64 s[40:41], s[34:35]
	s_mov_b64 s[38:39], s[18:19]
	global_store_dwordx4 v[0:1], v[4:7], off
	s_cbranch_vccz .LBB0_230
	s_waitcnt vmcnt(0)
	s_cmpk_gt_u32 s44, 0xff
	s_cbranch_scc1 .LBB0_238
	s_barrier

; #define PG8_STAGE(bufoff, gbase, voff) do { _Pragma("unroll") for (int _i = 0; _i < 2; ++_i) \
;         __builtin_amdgcn_global_load_lds((const unsigned*)((const char*)(gbase) + (voff)[_i]), (LAS unsigned*)(lds + (bufoff) + ldsw + _i * 8192), 16, 0, 0); } while (0)
; #define PG8_LDA(dst, b, h) do { _Pragma("unroll") for (int m = 0; m < 4; ++m) _Pragma("unroll") for (int k = 0; k < 2; ++k) dst[m][k] = *(const LAS bf16x8*)(lds + PG8_SA(b, h) + aoff + m * 2048 + k * 1024); } while (0)
; #define PG8_LDB(dst, b, h) do { _Pragma("unroll") for (int n = 0; n < 2; ++n) _Pragma("unroll") for (int k = 0; k < 2; ++k) dst[n][k] = *(const LAS bf16x8*)(lds + PG8_SB(b, h) + boff + n * 2048 + k * 1024); } while (0)
; #define PG8_MMA(ai, bj, At, Bt) do { __builtin_amdgcn_s_setprio(1); _Pragma("unroll") for (int m = 0; m < 4; ++m) _Pragma("unroll") for (int n = 0; n < 2; ++n) _Pragma("unroll") for (int k = 0; k < 2; ++k) \
;         acc[ai][bj][m][n] = __builtin_amdgcn_mfma_f32_16x16x32_bf16(Bt[n][k], At[m][k], acc[ai][bj][m][n], 0, 0, 0); __builtin_amdgcn_s_setprio(0); } while (0)
; #define PG8_WAIT_L(n) asm volatile("s_waitcnt lgkmcnt(" #n ")" ::: "memory")
; #define PG8_BAR __builtin_amdgcn_s_barrier()
; #define PG8_SCHED __builtin_amdgcn_sched_barrier(0)
; template <class Epi>
; __device__ __forceinline__ void gemm_phase(LAS unsigned char* lds, const Gemm g, const StaticOrder& S, const Epi& E) {
;     ...
;             PG8_LDB(B0, 0, 0); PG8_SCHED; PG8_LDA(At, 0, 0); PG8_STAGE(PG8_SA(1, 1), a1 + hstep, voffA);
;             PG8_WAIT_L(8); PG8_BAR; PG8_WAIT_L(0); PG8_MMA(0, 0, At, B0); PG8_BAR; PG8_SCHED;
;             PG8_LDB(B1, 0, 1); PG8_STAGE(PG8_SB(0, 0), b2, voffB0);
;             PG8_BAR; PG8_WAIT_L(0); PG8_MMA(0, 1, At, B1); PG8_BAR;
;             PG8_LDA(At, 0, 1); PG8_STAGE(PG8_SA(0, 0), a2, voffA);
;             PG8_BAR; PG8_WAIT_L(0); PG8_MMA(1, 0, At, B0); PG8_BAR; PG8_SCHED;
.LBB0_248:
	s_add_u32 s16, s42, s50
	s_addc_u32 s17, s43, 0
	s_add_u32 s33, s16, 0x100
	s_addc_u32 s48, s17, 0
	v_cndmask_b32_e64 v172, 0, 1, s[46:47]
	s_and_b64 s[46:47], s[44:45], exec
	s_cselect_b32 s49, s19, s48
	s_cselect_b32 s48, s72, s33
	s_add_u32 s33, s40, s50
	s_addc_u32 s46, s41, 0
	s_add_u32 s33, s33, 0x100
	s_addc_u32 s47, s46, 0
	s_and_b64 s[44:45], s[44:45], exec
	ds_read_b128 v[156:159], v153
	ds_read_b128 v[160:163], v153 offset:1024
	ds_read_b128 v[164:167], v153 offset:2048
	ds_read_b128 v[168:171], v153 offset:3072
	s_cselect_b32 s46, s73, s33
	s_cselect_b32 s47, s11, s47
	s_add_u32 s50, s16, 0x10080
	s_addc_u32 s51, s17, 0
	s_add_i32 s17, s69, s57
	s_add_i32 s79, s70, s57
	s_add_i32 m0, s39, 0xc000
	s_add_i32 s16, s39, 0xe000
	s_add_i32 s82, s17, 0x2000
	s_add_i32 s78, s79, 0x2000
	s_add_i32 s77, 0, 0x18000
	s_add_u32 s44, s48, 0x10000
	s_addc_u32 s45, s49, 0
	s_add_i32 s74, 0, 0x1c000
	s_add_i32 s75, s77, s57
	s_add_i32 s81, s74, s57
	s_add_i32 s33, s75, 0x2000
	s_add_i32 s80, s81, 0x2000
	v_cmp_ne_u32_e32 vcc, 1, v172
	v_lshl_add_u64 v[200:201], s[50:51], 0, v[138:139]
	ds_read_b128 v[172:175], v154
	ds_read_b128 v[176:179], v154 offset:1024
	ds_read_b128 v[180:183], v154 offset:2048
	ds_read_b128 v[184:187], v154 offset:3072
	ds_read_b128 v[188:191], v154 offset:4096
	ds_read_b128 v[192:195], v154 offset:5120
	ds_read_b128 v[196:199], v154 offset:6144
	ds_read_b128 v[204:207], v154 offset:7168
	global_load_lds_dwordx4 v[200:201], off
	v_lshl_add_u64 v[200:201], s[50:51], 0, v[132:133]
	s_mov_b32 m0, s16
	s_nop 0
	global_load_lds_dwordx4 v[200:201], off
	s_waitcnt lgkmcnt(8)
	s_barrier
	s_waitcnt lgkmcnt(0)
	v_mfma_f32_16x16x32_bf16 v[124:127], v[156:159], v[172:175], v[124:127]
	v_mfma_f32_16x16x32_bf16 v[120:123], v[164:167], v[172:175], v[120:123]
	v_mfma_f32_16x16x32_bf16 v[108:111], v[156:159], v[180:183], v[108:111]
	v_mfma_f32_16x16x32_bf16 v[104:107], v[164:167], v[180:183], v[104:107]
	v_mfma_f32_16x16x32_bf16 v[92:95], v[156:159], v[188:191], v[92:95]
	v_mfma_f32_16x16x32_bf16 v[88:91], v[164:167], v[188:191], v[88:91]
	v_mfma_f32_16x16x32_bf16 v[76:79], v[156:159], v[196:199], v[76:79]
	v_mfma_f32_16x16x32_bf16 v[72:75], v[164:167], v[196:199], v[72:75]
	v_mfma_f32_16x16x32_bf16 v[124:127], v[160:163], v[176:179], v[124:127]
	v_mfma_f32_16x16x32_bf16 v[120:123], v[168:171], v[176:179], v[120:123]
	v_mfma_f32_16x16x32_bf16 v[108:111], v[160:163], v[184:187], v[108:111]
	v_mfma_f32_16x16x32_bf16 v[104:107], v[168:171], v[184:187], v[104:107]
	v_mfma_f32_16x16x32_bf16 v[92:95], v[160:163], v[192:195], v[92:95]
	v_mfma_f32_16x16x32_bf16 v[88:91], v[168:171], v[192:195], v[88:91]
	v_mfma_f32_16x16x32_bf16 v[76:79], v[160:163], v[204:207], v[76:79]
	v_mfma_f32_16x16x32_bf16 v[72:75], v[168:171], v[204:207], v[72:75]
	s_barrier
	s_mov_b32 m0, s17
	v_lshl_add_u64 v[200:201], s[46:47], 0, v[134:135]
	ds_read_b128 v[208:211], v155
	ds_read_b128 v[212:215], v155 offset:1024
	ds_read_b128 v[216:219], v155 offset:2048
	ds_read_b128 v[220:223], v155 offset:3072
	global_load_lds_dwordx4 v[200:201], off
	v_lshl_add_u64 v[224:225], s[46:47], 0, v[128:129]
	s_mov_b32 m0, s82
	s_nop 0
	global_load_lds_dwordx4 v[224:225], off
	s_barrier
	s_waitcnt lgkmcnt(0)
	v_mfma_f32_16x16x32_bf16 v[116:119], v[208:211], v[172:175], v[116:119]
	v_mfma_f32_16x16x32_bf16 v[112:115], v[216:219], v[172:175], v[112:115]
	v_mfma_f32_16x16x32_bf16 v[100:103], v[208:211], v[180:183], v[100:103]
	v_mfma_f32_16x16x32_bf16 v[96:99], v[216:219], v[180:183], v[96:99]
	v_mfma_f32_16x16x32_bf16 v[84:87], v[208:211], v[188:191], v[84:87]
	v_mfma_f32_16x16x32_bf16 v[80:83], v[216:219], v[188:191], v[80:83]
	v_mfma_f32_16x16x32_bf16 v[68:71], v[208:211], v[196:199], v[68:71]
	v_mfma_f32_16x16x32_bf16 v[64:67], v[216:219], v[196:199], v[64:67]
	v_mfma_f32_16x16x32_bf16 v[116:119], v[212:215], v[176:179], v[116:119]
	v_mfma_f32_16x16x32_bf16 v[112:115], v[220:223], v[176:179], v[112:115]
	v_mfma_f32_16x16x32_bf16 v[100:103], v[212:215], v[184:187], v[100:103]
	v_mfma_f32_16x16x32_bf16 v[96:99], v[220:223], v[184:187], v[96:99]
	v_mfma_f32_16x16x32_bf16 v[84:87], v[212:215], v[192:195], v[84:87]
	v_mfma_f32_16x16x32_bf16 v[80:83], v[220:223], v[192:195], v[80:83]
	v_mfma_f32_16x16x32_bf16 v[68:71], v[212:215], v[204:207], v[68:71]
	v_mfma_f32_16x16x32_bf16 v[64:67], v[220:223], v[204:207], v[64:67]
	s_mov_b32 m0, s39
	v_lshl_add_u64 v[226:227], s[48:49], 0, v[138:139]
	s_barrier
	ds_read_b128 v[172:175], v154 offset:16384
	ds_read_b128 v[176:179], v154 offset:17408
	ds_read_b128 v[180:183], v154 offset:18432
	ds_read_b128 v[184:187], v154 offset:19456
	ds_read_b128 v[188:191], v154 offset:20480
	ds_read_b128 v[192:195], v154 offset:21504
	ds_read_b128 v[196:199], v154 offset:22528
	ds_read_b128 v[204:207], v154 offset:23552
	global_load_lds_dwordx4 v[226:227], off
	v_lshl_add_u64 v[228:229], s[48:49], 0, v[132:133]
	s_mov_b32 m0, s59
	s_nop 0
	global_load_lds_dwordx4 v[228:229], off
	s_barrier
	s_waitcnt lgkmcnt(0)
	v_mfma_f32_16x16x32_bf16 v[60:63], v[156:159], v[172:175], v[60:63]
	v_mfma_f32_16x16x32_bf16 v[56:59], v[164:167], v[172:175], v[56:59]
	v_mfma_f32_16x16x32_bf16 v[44:47], v[156:159], v[180:183], v[44:47]
	v_mfma_f32_16x16x32_bf16 v[40:43], v[164:167], v[180:183], v[40:43]
	v_mfma_f32_16x16x32_bf16 v[28:31], v[156:159], v[188:191], v[28:31]
	v_mfma_f32_16x16x32_bf16 v[24:27], v[164:167], v[188:191], v[24:27]
	v_mfma_f32_16x16x32_bf16 v[12:15], v[156:159], v[196:199], v[12:15]
	v_mfma_f32_16x16x32_bf16 v[8:11], v[164:167], v[196:199], v[8:11]
	v_mfma_f32_16x16x32_bf16 v[60:63], v[160:163], v[176:179], v[60:63]
	v_mfma_f32_16x16x32_bf16 v[56:59], v[168:171], v[176:179], v[56:59]
	v_mfma_f32_16x16x32_bf16 v[44:47], v[160:163], v[184:187], v[44:47]
	v_mfma_f32_16x16x32_bf16 v[40:43], v[168:171], v[184:187], v[40:43]
	v_mfma_f32_16x16x32_bf16 v[28:31], v[160:163], v[192:195], v[28:31]
	v_mfma_f32_16x16x32_bf16 v[24:27], v[168:171], v[192:195], v[24:27]
	v_mfma_f32_16x16x32_bf16 v[12:15], v[160:163], v[204:207], v[12:15]
	v_mfma_f32_16x16x32_bf16 v[8:11], v[168:171], v[204:207], v[8:11]
	s_barrier
; #define PG8_STAGE(bufoff, gbase, voff) do { _Pragma("unroll") for (int _i = 0; _i < 2; ++_i) \
;         __builtin_amdgcn_global_load_lds((const unsigned*)((const char*)(gbase) + (voff)[_i]), (LAS unsigned*)(lds + (bufoff) + ldsw + _i * 8192), 16, 0, 0); } while (0)
; #define PG8_LDA(dst, b, h) do { _Pragma("unroll") for (int m = 0; m < 4; ++m) _Pragma("unroll") for (int k = 0; k < 2; ++k) dst[m][k] = *(const LAS bf16x8*)(lds + PG8_SA(b, h) + aoff + m * 2048 + k * 1024); } while (0)
; #define PG8_LDB(dst, b, h) do { _Pragma("unroll") for (int n = 0; n < 2; ++n) _Pragma("unroll") for (int k = 0; k < 2; ++k) dst[n][k] = *(const LAS bf16x8*)(lds + PG8_SB(b, h) + boff + n * 2048 + k * 1024); } while (0)
; #define PG8_MMA(ai, bj, At, Bt) do { __builtin_amdgcn_s_setprio(1); _Pragma("unroll") for (int m = 0; m < 4; ++m) _Pragma("unroll") for (int n = 0; n < 2; ++n) _Pragma("unroll") for (int k = 0; k < 2; ++k) \
;         acc[ai][bj][m][n] = __builtin_amdgcn_mfma_f32_16x16x32_bf16(Bt[n][k], At[m][k], acc[ai][bj][m][n], 0, 0, 0); __builtin_amdgcn_s_setprio(0); } while (0)
; #define PG8_WAIT_V(n) asm volatile("s_waitcnt vmcnt(" #n ")" ::: "memory")
; #define PG8_WAIT_L(n) asm volatile("s_waitcnt lgkmcnt(" #n ")" ::: "memory")
; #define PG8_BAR __builtin_amdgcn_s_barrier()
; #define PG8_SCHED __builtin_amdgcn_sched_barrier(0)
; template <class Epi>
; __device__ __forceinline__ void gemm_phase(LAS unsigned char* lds, const Gemm g, const StaticOrder& S, const Epi& E) {
;     ...
;             PG8_STAGE(PG8_SB(0, 1), b2, voffB1);
;             PG8_WAIT_V(6); PG8_BAR; PG8_MMA(1, 1, At, B1); PG8_BAR;
;             PG8_LDB(B0, 1, 0); PG8_SCHED; PG8_LDA(At, 1, 0); PG8_STAGE(PG8_SA(0, 1), a2 + hstep, voffA);
;             PG8_WAIT_L(8); PG8_BAR; PG8_WAIT_L(0); PG8_MMA(0, 0, At, B0); PG8_BAR; PG8_SCHED;
;             PG8_LDB(B1, 1, 1); PG8_STAGE(PG8_SB(1, 0), b3, voffB0);
;             PG8_BAR; PG8_WAIT_L(0); PG8_MMA(0, 1, At, B1); PG8_BAR;
;             PG8_LDA(At, 1, 1); PG8_STAGE(PG8_SA(1, 0), a3, voffA);
;             PG8_BAR; PG8_WAIT_L(0); PG8_MMA(1, 0, At, B0); PG8_BAR; PG8_SCHED;
	s_mov_b32 m0, s79
	v_lshl_add_u64 v[230:231], s[46:47], 0, v[136:137]
	global_load_lds_dwordx4 v[230:231], off
	v_lshl_add_u64 v[232:233], s[46:47], 0, v[130:131]
	s_mov_b32 m0, s78
	s_nop 0
	global_load_lds_dwordx4 v[232:233], off
	s_waitcnt vmcnt(6)
	s_barrier
	v_mfma_f32_16x16x32_bf16 v[52:55], v[208:211], v[172:175], v[52:55]
	v_mfma_f32_16x16x32_bf16 v[48:51], v[216:219], v[172:175], v[48:51]
	v_mfma_f32_16x16x32_bf16 v[36:39], v[208:211], v[180:183], v[36:39]
	v_mfma_f32_16x16x32_bf16 v[32:35], v[216:219], v[180:183], v[32:35]
	v_mfma_f32_16x16x32_bf16 v[20:23], v[208:211], v[188:191], v[20:23]
	v_mfma_f32_16x16x32_bf16 v[16:19], v[216:219], v[188:191], v[16:19]
	v_mfma_f32_16x16x32_bf16 v[4:7], v[208:211], v[196:199], v[4:7]
	v_mfma_f32_16x16x32_bf16 v[0:3], v[216:219], v[196:199], v[0:3]
	v_mfma_f32_16x16x32_bf16 v[52:55], v[212:215], v[176:179], v[52:55]
	v_mfma_f32_16x16x32_bf16 v[48:51], v[220:223], v[176:179], v[48:51]
	v_mfma_f32_16x16x32_bf16 v[36:39], v[212:215], v[184:187], v[36:39]
	v_mfma_f32_16x16x32_bf16 v[32:35], v[220:223], v[184:187], v[32:35]
	v_mfma_f32_16x16x32_bf16 v[20:23], v[212:215], v[192:195], v[20:23]
	v_mfma_f32_16x16x32_bf16 v[16:19], v[220:223], v[192:195], v[16:19]
	v_mfma_f32_16x16x32_bf16 v[4:7], v[212:215], v[204:207], v[4:7]
	v_mfma_f32_16x16x32_bf16 v[0:3], v[220:223], v[204:207], v[0:3]
	v_add_u32_e32 v168, s77, v143
	s_barrier
	ds_read_b128 v[156:159], v168
	ds_read_b128 v[160:163], v168 offset:1024
	ds_read_b128 v[164:167], v168 offset:2048
	ds_read_b128 v[168:171], v168 offset:3072
	s_mov_b32 m0, s60
	v_lshl_add_u64 v[208:209], s[44:45], 0, v[138:139]
	ds_read_b128 v[172:175], v154 offset:32768
	ds_read_b128 v[176:179], v154 offset:33792
	ds_read_b128 v[180:183], v154 offset:34816
	ds_read_b128 v[184:187], v154 offset:35840
	ds_read_b128 v[188:191], v154 offset:36864
	ds_read_b128 v[192:195], v154 offset:37888
	ds_read_b128 v[196:199], v154 offset:38912
	ds_read_b128 v[204:207], v154 offset:39936
	global_load_lds_dwordx4 v[208:209], off
	v_lshl_add_u64 v[208:209], s[44:45], 0, v[132:133]
	s_mov_b32 m0, s61
	s_nop 0
	global_load_lds_dwordx4 v[208:209], off
	s_waitcnt lgkmcnt(8)
	s_barrier
	s_waitcnt lgkmcnt(0)
	v_mfma_f32_16x16x32_bf16 v[124:127], v[156:159], v[172:175], v[124:127]
	v_mfma_f32_16x16x32_bf16 v[120:123], v[164:167], v[172:175], v[120:123]
	v_mfma_f32_16x16x32_bf16 v[108:111], v[156:159], v[180:183], v[108:111]
	v_mfma_f32_16x16x32_bf16 v[104:107], v[164:167], v[180:183], v[104:107]
	v_mfma_f32_16x16x32_bf16 v[92:95], v[156:159], v[188:191], v[92:95]
	v_mfma_f32_16x16x32_bf16 v[88:91], v[164:167], v[188:191], v[88:91]
	v_mfma_f32_16x16x32_bf16 v[76:79], v[156:159], v[196:199], v[76:79]
	v_mfma_f32_16x16x32_bf16 v[72:75], v[164:167], v[196:199], v[72:75]
	v_mfma_f32_16x16x32_bf16 v[124:127], v[160:163], v[176:179], v[124:127]
	v_mfma_f32_16x16x32_bf16 v[120:123], v[168:171], v[176:179], v[120:123]
	v_mfma_f32_16x16x32_bf16 v[108:111], v[160:163], v[184:187], v[108:111]
	v_mfma_f32_16x16x32_bf16 v[104:107], v[168:171], v[184:187], v[104:107]
	v_mfma_f32_16x16x32_bf16 v[92:95], v[160:163], v[192:195], v[92:95]
	v_mfma_f32_16x16x32_bf16 v[88:91], v[168:171], v[192:195], v[88:91]
	v_mfma_f32_16x16x32_bf16 v[76:79], v[160:163], v[204:207], v[76:79]
	v_mfma_f32_16x16x32_bf16 v[72:75], v[168:171], v[204:207], v[72:75]
	s_barrier
	s_mov_b32 m0, s75
	v_add_u32_e32 v220, s74, v143
	v_lshl_add_u64 v[200:201], v[200:201], 0, s[8:9]
	ds_read_b128 v[208:211], v220
	ds_read_b128 v[212:215], v220 offset:1024
	ds_read_b128 v[216:219], v220 offset:2048
	ds_read_b128 v[220:223], v220 offset:3072
	global_load_lds_dwordx4 v[200:201], off
	v_lshl_add_u64 v[200:201], v[224:225], 0, s[8:9]
	s_mov_b32 m0, s33
	s_nop 0
	global_load_lds_dwordx4 v[200:201], off
	s_barrier
	s_waitcnt lgkmcnt(0)
	v_mfma_f32_16x16x32_bf16 v[116:119], v[208:211], v[172:175], v[116:119]
	v_mfma_f32_16x16x32_bf16 v[112:115], v[216:219], v[172:175], v[112:115]
	v_mfma_f32_16x16x32_bf16 v[100:103], v[208:211], v[180:183], v[100:103]
	v_mfma_f32_16x16x32_bf16 v[96:99], v[216:219], v[180:183], v[96:99]
	v_mfma_f32_16x16x32_bf16 v[84:87], v[208:211], v[188:191], v[84:87]
	v_mfma_f32_16x16x32_bf16 v[80:83], v[216:219], v[188:191], v[80:83]
	v_mfma_f32_16x16x32_bf16 v[68:71], v[208:211], v[196:199], v[68:71]
	v_mfma_f32_16x16x32_bf16 v[64:67], v[216:219], v[196:199], v[64:67]
	v_mfma_f32_16x16x32_bf16 v[116:119], v[212:215], v[176:179], v[116:119]
	v_mfma_f32_16x16x32_bf16 v[112:115], v[220:223], v[176:179], v[112:115]
	v_mfma_f32_16x16x32_bf16 v[100:103], v[212:215], v[184:187], v[100:103]
	v_mfma_f32_16x16x32_bf16 v[96:99], v[220:223], v[184:187], v[96:99]
	v_mfma_f32_16x16x32_bf16 v[84:87], v[212:215], v[192:195], v[84:87]
	v_mfma_f32_16x16x32_bf16 v[80:83], v[220:223], v[192:195], v[80:83]
	v_mfma_f32_16x16x32_bf16 v[68:71], v[212:215], v[204:207], v[68:71]
	v_mfma_f32_16x16x32_bf16 v[64:67], v[220:223], v[204:207], v[64:67]
	s_mov_b32 m0, s63
	v_lshl_add_u64 v[200:201], v[226:227], 0, s[8:9]
	s_barrier
	ds_read_b128 v[172:175], v154 offset:49152
	ds_read_b128 v[176:179], v154 offset:50176
	ds_read_b128 v[180:183], v154 offset:51200
	ds_read_b128 v[184:187], v154 offset:52224
	ds_read_b128 v[188:191], v154 offset:53248
	ds_read_b128 v[192:195], v154 offset:54272
	ds_read_b128 v[196:199], v154 offset:55296
	ds_read_b128 v[204:207], v154 offset:56320
	global_load_lds_dwordx4 v[200:201], off
	v_lshl_add_u64 v[200:201], v[228:229], 0, s[8:9]
	s_mov_b32 m0, s64
	s_nop 0
	global_load_lds_dwordx4 v[200:201], off
	s_barrier
; __device__ __forceinline__ unsigned cvt_pk_bf16(float lo, float hi) { unsigned r; asm volatile("v_cvt_pk_bf16_f32 %0, %1, %2" : "=v"(r) : "v"(lo), "v"(hi)); return r; }
; __device__ __forceinline__ unsigned dpp_ror8(unsigned x) { return (unsigned)__builtin_amdgcn_update_dpp(0, (int)x, 0x128, 0xf, 0xf, false); }
; #define PG8_WAIT_V(n) asm volatile("s_waitcnt vmcnt(" #n ")" ::: "memory")
; __device__ __forceinline__ void store_pair_lines(bf16_t* O, int ldc, int row, int fr, int col0, u32x4 wA, u32x4 wB) {
;     const u32x4 sA = {dpp_ror8(wA.x), dpp_ror8(wA.y), dpp_ror8(wA.z), dpp_ror8(wA.w)}, sB = {dpp_ror8(wB.x), dpp_ror8(wB.y), dpp_ror8(wB.z), dpp_ror8(wB.w)};
;     const bool lo = fr < 8;
;     const u32x4 o1 = lo ? wA : sB, o2 = lo ? sA : wB;
;     const int r1 = row - fr + (fr & 7), cb = col0 + (lo ? 0 : 8);
;     *(u32x4*)(O + (size_t)r1 * ldc + cb) = o1;
;     *(u32x4*)(O + (size_t)(r1 + 8) * ldc + cb) = o2;
;     __device__ __forceinline__ void operator()(const f32x4 (&acc)[2][2][4][2], const Unit& u, int wr, int wc, int fr, int fq) const {
;     ...
;             for (int m = 0; m < 4; ++m) { const int row = row0 + ai * HALF + m * 16;
;                 const float rs = ssin ? __builtin_amdgcn_rsqf(ssin[row] * (1.f / D) + EPS) : 1.0f; float sq = 0.f; u32x4 w[2];
; #pragma unroll
;                 for (int bj = 0; bj < 2; ++bj) { f32x4 v0 = acc[ai][bj][m][0] * rs, v1 = acc[ai][bj][m][1] * rs;
;                     if (ACT == 1) {
; #pragma unroll
;                         for (int j = 0; j < 4; ++j) { const float a = fmaxf(v0[j], 0.f), b = fmaxf(v1[j], 0.f); v0[j] = a * a; v1[j] = b * b; } }
;                     sq += (v0[0] * v0[0] + v0[1] * v0[1]) + (v0[2] * v0[2] + v0[3] * v0[3]) + (v1[0] * v1[0] + v1[1] * v1[1]) + (v1[2] * v1[2] + v1[3] * v1[3]);
;                     w[bj].x = cvt_pk_bf16(v0[0], v0[1]); w[bj].y = cvt_pk_bf16(v0[2], v0[3]); w[bj].z = cvt_pk_bf16(v1[0], v1[1]); w[bj].w = cvt_pk_bf16(v1[2], v1[3]); }
;                 store_pair_lines(O, ldc, row, fr, col0, w[0], w[1]);
; template <class Epi>
; __device__ __forceinline__ void gemm_phase(LAS unsigned char* lds, const Gemm g, const StaticOrder& S, const Epi& E) {
;     ...
;             PG8_BAR; PG8_WAIT_L(0); PG8_MMA(1, 0, At, B0); PG8_BAR; PG8_SCHED;
;             PG8_STAGE(PG8_SB(1, 1), b3, voffB1);
;             PG8_WAIT_V(6); PG8_BAR; PG8_MMA(1, 1, At, B1); PG8_BAR;
	s_waitcnt lgkmcnt(0)
	v_mfma_f32_16x16x32_bf16 v[60:63], v[156:159], v[172:175], v[60:63]
	v_mfma_f32_16x16x32_bf16 v[56:59], v[164:167], v[172:175], v[56:59]
	v_mfma_f32_16x16x32_bf16 v[44:47], v[156:159], v[180:183], v[44:47]
	v_mfma_f32_16x16x32_bf16 v[40:43], v[164:167], v[180:183], v[40:43]
	v_mfma_f32_16x16x32_bf16 v[28:31], v[156:159], v[188:191], v[28:31]
	v_mfma_f32_16x16x32_bf16 v[24:27], v[164:167], v[188:191], v[24:27]
	v_mfma_f32_16x16x32_bf16 v[12:15], v[156:159], v[196:199], v[12:15]
	v_mfma_f32_16x16x32_bf16 v[8:11], v[164:167], v[196:199], v[8:11]
	v_mfma_f32_16x16x32_bf16 v[60:63], v[160:163], v[176:179], v[60:63]
	v_mfma_f32_16x16x32_bf16 v[56:59], v[168:171], v[176:179], v[56:59]
	v_mfma_f32_16x16x32_bf16 v[44:47], v[160:163], v[184:187], v[44:47]
	v_mfma_f32_16x16x32_bf16 v[40:43], v[168:171], v[184:187], v[40:43]
	v_mfma_f32_16x16x32_bf16 v[28:31], v[160:163], v[192:195], v[28:31]
	v_mfma_f32_16x16x32_bf16 v[24:27], v[168:171], v[192:195], v[24:27]
	v_mfma_f32_16x16x32_bf16 v[12:15], v[160:163], v[204:207], v[12:15]
	v_mfma_f32_16x16x32_bf16 v[8:11], v[168:171], v[204:207], v[8:11]
	s_barrier
	s_mov_b32 m0, s81
	v_lshl_add_u64 v[156:157], v[230:231], 0, s[8:9]
	global_load_lds_dwordx4 v[156:157], off
	v_lshl_add_u64 v[156:157], v[232:233], 0, s[8:9]
	s_mov_b32 m0, s80
	s_nop 0
	global_load_lds_dwordx4 v[156:157], off
	s_waitcnt vmcnt(6)
	s_barrier
	v_mfma_f32_16x16x32_bf16 v[52:55], v[208:211], v[172:175], v[52:55]
	v_mfma_f32_16x16x32_bf16 v[48:51], v[216:219], v[172:175], v[48:51]
	v_mfma_f32_16x16x32_bf16 v[36:39], v[208:211], v[180:183], v[36:39]
	v_mfma_f32_16x16x32_bf16 v[32:35], v[216:219], v[180:183], v[32:35]
	v_mfma_f32_16x16x32_bf16 v[20:23], v[208:211], v[188:191], v[20:23]
	v_mfma_f32_16x16x32_bf16 v[16:19], v[216:219], v[188:191], v[16:19]
	v_mfma_f32_16x16x32_bf16 v[4:7], v[208:211], v[196:199], v[4:7]
	v_mfma_f32_16x16x32_bf16 v[0:3], v[216:219], v[196:199], v[0:3]
	v_mfma_f32_16x16x32_bf16 v[52:55], v[212:215], v[176:179], v[52:55]
	v_mfma_f32_16x16x32_bf16 v[48:51], v[220:223], v[176:179], v[48:51]
	v_mfma_f32_16x16x32_bf16 v[36:39], v[212:215], v[184:187], v[36:39]
	v_mfma_f32_16x16x32_bf16 v[32:35], v[220:223], v[184:187], v[32:35]
	v_mfma_f32_16x16x32_bf16 v[20:23], v[212:215], v[192:195], v[20:23]
	v_mfma_f32_16x16x32_bf16 v[16:19], v[220:223], v[192:195], v[16:19]
	v_mfma_f32_16x16x32_bf16 v[4:7], v[212:215], v[204:207], v[4:7]
	v_mfma_f32_16x16x32_bf16 v[0:3], v[220:223], v[204:207], v[0:3]
	s_movk_i32 s50, 0x100
	s_mov_b64 s[46:47], 0
	s_mov_b64 s[44:45], -1
	s_barrier
	s_cbranch_vccz .LBB0_248
	s_lshl_b32 s11, s38, 8
	v_cvt_pk_bf16_f32 v124, v124, v125
	v_cvt_pk_bf16_f32 v125, v126, v127
	v_cvt_pk_bf16_f32 v120, v120, v121
	v_cvt_pk_bf16_f32 v121, v122, v123
	v_cvt_pk_bf16_f32 v122, v116, v117
	v_cvt_pk_bf16_f32 v119, v118, v119
	s_add_i32 s11, s11, s65
	v_cvt_pk_bf16_f32 v112, v112, v113
	v_cvt_pk_bf16_f32 v113, v114, v115
	v_mov_b32_dpp v118, v124 row_ror:8 row_mask:0xf bank_mask:0xf
	v_mov_b32_dpp v123, v125 row_ror:8 row_mask:0xf bank_mask:0xf
	v_mov_b32_dpp v114, v122 row_ror:8 row_mask:0xf bank_mask:0xf
	v_cndmask_b32_e64 v118, v122, v118, s[4:5]
	v_or_b32_e32 v122, s11, v144
	v_lshl_or_b32 v158, s71, 8, v152
	v_mov_b32_dpp v126, v120 row_ror:8 row_mask:0xf bank_mask:0xf
	v_mov_b32_dpp v127, v121 row_ror:8 row_mask:0xf bank_mask:0xf
	v_mov_b32_dpp v115, v119 row_ror:8 row_mask:0xf bank_mask:0xf
	v_mov_b32_dpp v116, v112 row_ror:8 row_mask:0xf bank_mask:0xf
	v_mov_b32_dpp v117, v113 row_ror:8 row_mask:0xf bank_mask:0xf
	v_cndmask_b32_e64 v119, v119, v123, s[4:5]
	v_ashrrev_i32_e32 v123, 31, v122
	v_ashrrev_i32_e32 v159, 31, v158
	v_cndmask_b32_e64 v116, v116, v120, s[4:5]
	v_cndmask_b32_e64 v117, v117, v121, s[4:5]
	v_cndmask_b32_e64 v120, v112, v126, s[4:5]
	v_cndmask_b32_e64 v121, v113, v127, s[4:5]
	v_lshlrev_b64 v[112:113], 12, v[122:123]
	v_cndmask_b32_e64 v114, v114, v124, s[4:5]
	v_cndmask_b32_e64 v115, v115, v125, s[4:5]
	v_lshl_add_u64 v[124:125], s[6:7], 0, v[112:113]
	v_lshlrev_b64 v[112:113], 1, v[158:159]
	v_lshl_add_u64 v[124:125], v[124:125], 0, v[112:113]
	global_store_dwordx4 v[124:125], v[114:117], off
	v_or_b32_e32 v156, s11, v142
	s_mov_b32 s71, s10
	v_or_b32_e32 v114, 8, v122
	v_ashrrev_i32_e32 v115, 31, v114
	v_lshlrev_b64 v[114:115], 12, v[114:115]
	v_lshl_add_u64 v[114:115], s[6:7], 0, v[114:115]
	v_lshl_add_u64 v[114:115], v[114:115], 0, v[112:113]
	global_store_dwordx4 v[114:115], v[118:121], off
	v_cvt_pk_bf16_f32 v108, v108, v109
	v_cvt_pk_bf16_f32 v109, v110, v111
	v_cvt_pk_bf16_f32 v104, v104, v105
	v_cvt_pk_bf16_f32 v105, v106, v107
	v_cvt_pk_bf16_f32 v100, v100, v101
	v_cvt_pk_bf16_f32 v101, v102, v103
	v_cvt_pk_bf16_f32 v102, v96, v97
	v_cvt_pk_bf16_f32 v103, v98, v99
	v_mov_b32_e32 v98, 0
	v_mov_b32_dpp v98, v102 row_ror:8 row_mask:0xf bank_mask:0xf
	v_mov_b32_dpp v110, v104 row_ror:8 row_mask:0xf bank_mask:0xf
	v_mov_b32_dpp v99, v103 row_ror:8 row_mask:0xf bank_mask:0xf
	v_cndmask_b32_e64 v98, v98, v104, s[4:5]
	v_add_u32_e32 v104, v145, v156
	v_mov_b32_dpp v111, v105 row_ror:8 row_mask:0xf bank_mask:0xf
	v_cndmask_b32_e64 v99, v99, v105, s[4:5]
	v_ashrrev_i32_e32 v105, 31, v104
	v_lshlrev_b64 v[104:105], 12, v[104:105]
	v_mov_b32_dpp v96, v100 row_ror:8 row_mask:0xf bank_mask:0xf
	v_mov_b32_dpp v97, v101 row_ror:8 row_mask:0xf bank_mask:0xf
	v_lshl_add_u64 v[104:105], s[6:7], 0, v[104:105]
	v_cndmask_b32_e64 v96, v96, v108, s[4:5]
	v_cndmask_b32_e64 v97, v97, v109, s[4:5]
	v_lshl_add_u64 v[104:105], v[104:105], 0, v[112:113]
	v_mov_b32_dpp v106, v108 row_ror:8 row_mask:0xf bank_mask:0xf
	v_mov_b32_dpp v107, v109 row_ror:8 row_mask:0xf bank_mask:0xf
; __device__ __forceinline__ unsigned cvt_pk_bf16(float lo, float hi) { unsigned r; asm volatile("v_cvt_pk_bf16_f32 %0, %1, %2" : "=v"(r) : "v"(lo), "v"(hi)); return r; }
; __device__ __forceinline__ unsigned dpp_ror8(unsigned x) { return (unsigned)__builtin_amdgcn_update_dpp(0, (int)x, 0x128, 0xf, 0xf, false); }
; __device__ __forceinline__ void store_pair_lines(bf16_t* O, int ldc, int row, int fr, int col0, u32x4 wA, u32x4 wB) {
;     const u32x4 sA = {dpp_ror8(wA.x), dpp_ror8(wA.y), dpp_ror8(wA.z), dpp_ror8(wA.w)}, sB = {dpp_ror8(wB.x), dpp_ror8(wB.y), dpp_ror8(wB.z), dpp_ror8(wB.w)};
;     const bool lo = fr < 8;
;     const u32x4 o1 = lo ? wA : sB, o2 = lo ? sA : wB;
;     const int r1 = row - fr + (fr & 7), cb = col0 + (lo ? 0 : 8);
;     *(u32x4*)(O + (size_t)r1 * ldc + cb) = o1;
;     *(u32x4*)(O + (size_t)(r1 + 8) * ldc + cb) = o2;
;     __device__ __forceinline__ void operator()(const f32x4 (&acc)[2][2][4][2], const Unit& u, int wr, int wc, int fr, int fq) const {
;     ...
;             for (int m = 0; m < 4; ++m) { const int row = row0 + ai * HALF + m * 16;
;                 const float rs = ssin ? __builtin_amdgcn_rsqf(ssin[row] * (1.f / D) + EPS) : 1.0f; float sq = 0.f; u32x4 w[2];
; #pragma unroll
;                 for (int bj = 0; bj < 2; ++bj) { f32x4 v0 = acc[ai][bj][m][0] * rs, v1 = acc[ai][bj][m][1] * rs;
;                     if (ACT == 1) {
; #pragma unroll
;                         for (int j = 0; j < 4; ++j) { const float a = fmaxf(v0[j], 0.f), b = fmaxf(v1[j], 0.f); v0[j] = a * a; v1[j] = b * b; } }
;                     sq += (v0[0] * v0[0] + v0[1] * v0[1]) + (v0[2] * v0[2] + v0[3] * v0[3]) + (v1[0] * v1[0] + v1[1] * v1[1]) + (v1[2] * v1[2] + v1[3] * v1[3]);
;                     w[bj].x = cvt_pk_bf16(v0[0], v0[1]); w[bj].y = cvt_pk_bf16(v0[2], v0[3]); w[bj].z = cvt_pk_bf16(v1[0], v1[1]); w[bj].w = cvt_pk_bf16(v1[2], v1[3]); }
;                 store_pair_lines(O, ldc, row, fr, col0, w[0], w[1]);
	global_store_dwordx4 v[104:105], v[96:99], off
	v_cndmask_b32_e64 v100, v100, v106, s[4:5]
	v_cndmask_b32_e64 v101, v101, v107, s[4:5]
	v_add_co_u32_e32 v96, vcc, s66, v104
	v_cndmask_b32_e64 v102, v102, v110, s[4:5]
	v_cndmask_b32_e64 v103, v103, v111, s[4:5]
	v_addc_co_u32_e32 v97, vcc, 0, v105, vcc
	global_store_dwordx4 v[96:97], v[100:103], off
	v_cvt_pk_bf16_f32 v92, v92, v93
	v_cvt_pk_bf16_f32 v93, v94, v95
	v_cvt_pk_bf16_f32 v88, v88, v89
	v_cvt_pk_bf16_f32 v89, v90, v91
	v_cvt_pk_bf16_f32 v84, v84, v85
	v_cvt_pk_bf16_f32 v85, v86, v87
	v_cvt_pk_bf16_f32 v86, v80, v81
	v_cvt_pk_bf16_f32 v87, v82, v83
	v_mov_b32_e32 v82, 0
	v_mov_b32_dpp v82, v86 row_ror:8 row_mask:0xf bank_mask:0xf
	v_mov_b32_dpp v94, v88 row_ror:8 row_mask:0xf bank_mask:0xf
	v_mov_b32_dpp v83, v87 row_ror:8 row_mask:0xf bank_mask:0xf
	v_cndmask_b32_e64 v82, v82, v88, s[4:5]
	v_add_u32_e32 v88, v146, v156
	v_mov_b32_dpp v95, v89 row_ror:8 row_mask:0xf bank_mask:0xf
	v_cndmask_b32_e64 v83, v83, v89, s[4:5]
	v_ashrrev_i32_e32 v89, 31, v88
	v_lshlrev_b64 v[88:89], 12, v[88:89]
	v_mov_b32_dpp v80, v84 row_ror:8 row_mask:0xf bank_mask:0xf
	v_mov_b32_dpp v81, v85 row_ror:8 row_mask:0xf bank_mask:0xf
	v_lshl_add_u64 v[88:89], s[6:7], 0, v[88:89]
	v_cndmask_b32_e64 v80, v80, v92, s[4:5]
	v_cndmask_b32_e64 v81, v81, v93, s[4:5]
	v_lshl_add_u64 v[88:89], v[88:89], 0, v[112:113]
	v_mov_b32_dpp v90, v92 row_ror:8 row_mask:0xf bank_mask:0xf
	v_mov_b32_dpp v91, v93 row_ror:8 row_mask:0xf bank_mask:0xf
	global_store_dwordx4 v[88:89], v[80:83], off
	v_cndmask_b32_e64 v84, v84, v90, s[4:5]
	v_cndmask_b32_e64 v85, v85, v91, s[4:5]
	v_add_co_u32_e32 v80, vcc, s66, v88
	v_cndmask_b32_e64 v86, v86, v94, s[4:5]
	v_cndmask_b32_e64 v87, v87, v95, s[4:5]
	v_addc_co_u32_e32 v81, vcc, 0, v89, vcc
	global_store_dwordx4 v[80:81], v[84:87], off
	v_cvt_pk_bf16_f32 v76, v76, v77
	v_cvt_pk_bf16_f32 v77, v78, v79
	v_cvt_pk_bf16_f32 v72, v72, v73
	v_cvt_pk_bf16_f32 v73, v74, v75
	v_cvt_pk_bf16_f32 v68, v68, v69
	v_cvt_pk_bf16_f32 v69, v70, v71
	v_cvt_pk_bf16_f32 v70, v64, v65
	v_cvt_pk_bf16_f32 v71, v66, v67
	v_mov_b32_e32 v66, 0
	v_mov_b32_dpp v66, v70 row_ror:8 row_mask:0xf bank_mask:0xf
	v_mov_b32_dpp v78, v72 row_ror:8 row_mask:0xf bank_mask:0xf
	v_mov_b32_dpp v67, v71 row_ror:8 row_mask:0xf bank_mask:0xf
	v_cndmask_b32_e64 v66, v66, v72, s[4:5]
	v_add_u32_e32 v72, v147, v156
	v_mov_b32_dpp v79, v73 row_ror:8 row_mask:0xf bank_mask:0xf
	v_cndmask_b32_e64 v67, v67, v73, s[4:5]
	v_ashrrev_i32_e32 v73, 31, v72
	v_lshlrev_b64 v[72:73], 12, v[72:73]
	v_mov_b32_dpp v64, v68 row_ror:8 row_mask:0xf bank_mask:0xf
	v_mov_b32_dpp v65, v69 row_ror:8 row_mask:0xf bank_mask:0xf
	v_lshl_add_u64 v[72:73], s[6:7], 0, v[72:73]
	v_cndmask_b32_e64 v64, v64, v76, s[4:5]
	v_cndmask_b32_e64 v65, v65, v77, s[4:5]
	v_lshl_add_u64 v[72:73], v[72:73], 0, v[112:113]
	v_mov_b32_dpp v74, v76 row_ror:8 row_mask:0xf bank_mask:0xf
	v_mov_b32_dpp v75, v77 row_ror:8 row_mask:0xf bank_mask:0xf
	global_store_dwordx4 v[72:73], v[64:67], off
	v_cndmask_b32_e64 v68, v68, v74, s[4:5]
	v_cndmask_b32_e64 v69, v69, v75, s[4:5]
	v_add_co_u32_e32 v64, vcc, s66, v72
	v_cndmask_b32_e64 v70, v70, v78, s[4:5]
	v_cndmask_b32_e64 v71, v71, v79, s[4:5]
	v_addc_co_u32_e32 v65, vcc, 0, v73, vcc
	global_store_dwordx4 v[64:65], v[68:71], off
	v_cvt_pk_bf16_f32 v60, v60, v61
	v_cvt_pk_bf16_f32 v61, v62, v63
	v_cvt_pk_bf16_f32 v56, v56, v57
	v_cvt_pk_bf16_f32 v57, v58, v59
	v_cvt_pk_bf16_f32 v52, v52, v53
	v_cvt_pk_bf16_f32 v53, v54, v55
	v_cvt_pk_bf16_f32 v54, v48, v49
	v_cvt_pk_bf16_f32 v55, v50, v51
	v_mov_b32_e32 v50, 0
	v_mov_b32_dpp v50, v54 row_ror:8 row_mask:0xf bank_mask:0xf
	v_mov_b32_dpp v62, v56 row_ror:8 row_mask:0xf bank_mask:0xf
	v_mov_b32_dpp v51, v55 row_ror:8 row_mask:0xf bank_mask:0xf
	v_cndmask_b32_e64 v50, v50, v56, s[4:5]
	v_add_u32_e32 v56, v148, v156
	v_mov_b32_dpp v63, v57 row_ror:8 row_mask:0xf bank_mask:0xf
	v_cndmask_b32_e64 v51, v51, v57, s[4:5]
	v_ashrrev_i32_e32 v57, 31, v56
	v_lshlrev_b64 v[56:57], 12, v[56:57]
	v_mov_b32_dpp v48, v52 row_ror:8 row_mask:0xf bank_mask:0xf
	v_mov_b32_dpp v49, v53 row_ror:8 row_mask:0xf bank_mask:0xf
	v_lshl_add_u64 v[56:57], s[6:7], 0, v[56:57]
	v_cndmask_b32_e64 v48, v48, v60, s[4:5]
	v_cndmask_b32_e64 v49, v49, v61, s[4:5]
	v_lshl_add_u64 v[56:57], v[56:57], 0, v[112:113]
	v_mov_b32_dpp v58, v60 row_ror:8 row_mask:0xf bank_mask:0xf
	v_mov_b32_dpp v59, v61 row_ror:8 row_mask:0xf bank_mask:0xf
	global_store_dwordx4 v[56:57], v[48:51], off
	v_cndmask_b32_e64 v52, v52, v58, s[4:5]
	v_cndmask_b32_e64 v53, v53, v59, s[4:5]
	v_add_co_u32_e32 v48, vcc, s66, v56
	v_cndmask_b32_e64 v54, v54, v62, s[4:5]
	v_cndmask_b32_e64 v55, v55, v63, s[4:5]
; __device__ __forceinline__ unsigned dpp_ror8(unsigned x) { return (unsigned)__builtin_amdgcn_update_dpp(0, (int)x, 0x128, 0xf, 0xf, false); }
; __device__ __forceinline__ void store_pair_lines(bf16_t* O, int ldc, int row, int fr, int col0, u32x4 wA, u32x4 wB) {
;     const u32x4 sA = {dpp_ror8(wA.x), dpp_ror8(wA.y), dpp_ror8(wA.z), dpp_ror8(wA.w)}, sB = {dpp_ror8(wB.x), dpp_ror8(wB.y), dpp_ror8(wB.z), dpp_ror8(wB.w)};
;     const bool lo = fr < 8;
;     const u32x4 o1 = lo ? wA : sB, o2 = lo ? sA : wB;
;     const int r1 = row - fr + (fr & 7), cb = col0 + (lo ? 0 : 8);
;     *(u32x4*)(O + (size_t)r1 * ldc + cb) = o1;
;     *(u32x4*)(O + (size_t)(r1 + 8) * ldc + cb) = o2;
;     __device__ __forceinline__ void operator()(const f32x4 (&acc)[2][2][4][2], const Unit& u, int wr, int wc, int fr, int fq) const {
;     ...
;             for (int m = 0; m < 4; ++m) { const int row = row0 + ai * HALF + m * 16;
;                 const float rs = ssin ? __builtin_amdgcn_rsqf(ssin[row] * (1.f / D) + EPS) : 1.0f; float sq = 0.f; u32x4 w[2];
; #pragma unroll
;                 for (int bj = 0; bj < 2; ++bj) { f32x4 v0 = acc[ai][bj][m][0] * rs, v1 = acc[ai][bj][m][1] * rs;
;                     if (ACT == 1) {
; #pragma unroll
;                         for (int j = 0; j < 4; ++j) { const float a = fmaxf(v0[j], 0.f), b = fmaxf(v1[j], 0.f); v0[j] = a * a; v1[j] = b * b; } }
;                     sq += (v0[0] * v0[0] + v0[1] * v0[1]) + (v0[2] * v0[2] + v0[3] * v0[3]) + (v1[0] * v1[0] + v1[1] * v1[1]) + (v1[2] * v1[2] + v1[3] * v1[3]);
;                     w[bj].x = cvt_pk_bf16(v0[0], v0[1]); w[bj].y = cvt_pk_bf16(v0[2], v0[3]); w[bj].z = cvt_pk_bf16(v1[0], v1[1]); w[bj].w = cvt_pk_bf16(v1[2], v1[3]); }
;                 store_pair_lines(O, ldc, row, fr, col0, w[0], w[1]);
; template <class Epi>
; __device__ __forceinline__ void gemm_phase(LAS unsigned char* lds, const Gemm g, const StaticOrder& S, const Epi& E) {
;     ...
;         E(acc, cur, wr, wc, fr, fq);
;         if (!has_next) break;
; #pragma unroll
;         for (int a = 0; a < 2; ++a)
; #pragma unroll
;             for (int b = 0; b < 2; ++b)
; #pragma unroll
;                 for (int m = 0; m < 4; ++m)
; #pragma unroll
;                     for (int n = 0; n < 2; ++n) acc[a][b][m][n] = (f32x4){0.f, 0.f, 0.f, 0.f};
;         cur = nxt; cA = nA; cB = nB; ++ui;
;     }
;     PG8_WAIT_V(0);
;     if (wr == 0) PG8_BAR;
;     PG8_BAR;
	v_addc_co_u32_e32 v49, vcc, 0, v57, vcc
	global_store_dwordx4 v[48:49], v[52:55], off
	v_cvt_pk_bf16_f32 v44, v44, v45
	v_cvt_pk_bf16_f32 v45, v46, v47
	v_cvt_pk_bf16_f32 v40, v40, v41
	v_cvt_pk_bf16_f32 v41, v42, v43
	v_cvt_pk_bf16_f32 v36, v36, v37
	v_cvt_pk_bf16_f32 v37, v38, v39
	v_cvt_pk_bf16_f32 v38, v32, v33
	v_cvt_pk_bf16_f32 v39, v34, v35
	v_mov_b32_e32 v34, 0
	v_mov_b32_dpp v34, v38 row_ror:8 row_mask:0xf bank_mask:0xf
	v_mov_b32_dpp v46, v40 row_ror:8 row_mask:0xf bank_mask:0xf
	v_mov_b32_dpp v35, v39 row_ror:8 row_mask:0xf bank_mask:0xf
	v_cndmask_b32_e64 v34, v34, v40, s[4:5]
	v_add_u32_e32 v40, v149, v156
	v_mov_b32_dpp v47, v41 row_ror:8 row_mask:0xf bank_mask:0xf
	v_cndmask_b32_e64 v35, v35, v41, s[4:5]
	v_ashrrev_i32_e32 v41, 31, v40
	v_lshlrev_b64 v[40:41], 12, v[40:41]
	v_mov_b32_dpp v32, v36 row_ror:8 row_mask:0xf bank_mask:0xf
	v_mov_b32_dpp v33, v37 row_ror:8 row_mask:0xf bank_mask:0xf
	v_lshl_add_u64 v[40:41], s[6:7], 0, v[40:41]
	v_cndmask_b32_e64 v32, v32, v44, s[4:5]
	v_cndmask_b32_e64 v33, v33, v45, s[4:5]
	v_lshl_add_u64 v[40:41], v[40:41], 0, v[112:113]
	v_mov_b32_dpp v42, v44 row_ror:8 row_mask:0xf bank_mask:0xf
	v_mov_b32_dpp v43, v45 row_ror:8 row_mask:0xf bank_mask:0xf
	global_store_dwordx4 v[40:41], v[32:35], off
	v_cndmask_b32_e64 v36, v36, v42, s[4:5]
	v_cndmask_b32_e64 v37, v37, v43, s[4:5]
	v_add_co_u32_e32 v32, vcc, s66, v40
	v_cndmask_b32_e64 v38, v38, v46, s[4:5]
	v_cndmask_b32_e64 v39, v39, v47, s[4:5]
	v_addc_co_u32_e32 v33, vcc, 0, v41, vcc
	global_store_dwordx4 v[32:33], v[36:39], off
	v_cvt_pk_bf16_f32 v28, v28, v29
	v_cvt_pk_bf16_f32 v29, v30, v31
	v_cvt_pk_bf16_f32 v24, v24, v25
	v_cvt_pk_bf16_f32 v25, v26, v27
	v_cvt_pk_bf16_f32 v20, v20, v21
	v_cvt_pk_bf16_f32 v21, v22, v23
	v_cvt_pk_bf16_f32 v22, v16, v17
	v_cvt_pk_bf16_f32 v23, v18, v19
	v_mov_b32_e32 v18, 0
	v_mov_b32_dpp v18, v22 row_ror:8 row_mask:0xf bank_mask:0xf
	v_mov_b32_dpp v30, v24 row_ror:8 row_mask:0xf bank_mask:0xf
	v_mov_b32_dpp v19, v23 row_ror:8 row_mask:0xf bank_mask:0xf
	v_cndmask_b32_e64 v18, v18, v24, s[4:5]
	v_add_u32_e32 v24, v150, v156
	v_mov_b32_dpp v31, v25 row_ror:8 row_mask:0xf bank_mask:0xf
	v_cndmask_b32_e64 v19, v19, v25, s[4:5]
	v_ashrrev_i32_e32 v25, 31, v24
	v_lshlrev_b64 v[24:25], 12, v[24:25]
	v_mov_b32_dpp v16, v20 row_ror:8 row_mask:0xf bank_mask:0xf
	v_mov_b32_dpp v17, v21 row_ror:8 row_mask:0xf bank_mask:0xf
	v_lshl_add_u64 v[24:25], s[6:7], 0, v[24:25]
	v_cndmask_b32_e64 v16, v16, v28, s[4:5]
	v_cndmask_b32_e64 v17, v17, v29, s[4:5]
	v_lshl_add_u64 v[24:25], v[24:25], 0, v[112:113]
	v_mov_b32_dpp v26, v28 row_ror:8 row_mask:0xf bank_mask:0xf
	v_mov_b32_dpp v27, v29 row_ror:8 row_mask:0xf bank_mask:0xf
	global_store_dwordx4 v[24:25], v[16:19], off
	v_cndmask_b32_e64 v20, v20, v26, s[4:5]
	v_cndmask_b32_e64 v21, v21, v27, s[4:5]
	v_add_co_u32_e32 v16, vcc, s66, v24
	v_cndmask_b32_e64 v22, v22, v30, s[4:5]
	v_cndmask_b32_e64 v23, v23, v31, s[4:5]
	v_addc_co_u32_e32 v17, vcc, 0, v25, vcc
	global_store_dwordx4 v[16:17], v[20:23], off
	v_cvt_pk_bf16_f32 v12, v12, v13
	v_cvt_pk_bf16_f32 v13, v14, v15
	v_cvt_pk_bf16_f32 v8, v8, v9
	v_cvt_pk_bf16_f32 v9, v10, v11
	v_cvt_pk_bf16_f32 v4, v4, v5
	v_cvt_pk_bf16_f32 v5, v6, v7
	v_cvt_pk_bf16_f32 v6, v0, v1
	v_cvt_pk_bf16_f32 v7, v2, v3
	v_mov_b32_e32 v2, 0
	v_mov_b32_dpp v2, v6 row_ror:8 row_mask:0xf bank_mask:0xf
	v_mov_b32_dpp v14, v8 row_ror:8 row_mask:0xf bank_mask:0xf
	v_mov_b32_dpp v3, v7 row_ror:8 row_mask:0xf bank_mask:0xf
	v_cndmask_b32_e64 v2, v2, v8, s[4:5]
	v_add_u32_e32 v8, v151, v156
	v_mov_b32_dpp v15, v9 row_ror:8 row_mask:0xf bank_mask:0xf
	v_cndmask_b32_e64 v3, v3, v9, s[4:5]
	v_ashrrev_i32_e32 v9, 31, v8
	v_lshlrev_b64 v[8:9], 12, v[8:9]
	v_mov_b32_dpp v0, v4 row_ror:8 row_mask:0xf bank_mask:0xf
	v_mov_b32_dpp v1, v5 row_ror:8 row_mask:0xf bank_mask:0xf
	v_lshl_add_u64 v[8:9], s[6:7], 0, v[8:9]
	v_cndmask_b32_e64 v0, v0, v12, s[4:5]
	v_cndmask_b32_e64 v1, v1, v13, s[4:5]
	v_lshl_add_u64 v[8:9], v[8:9], 0, v[112:113]
	global_store_dwordx4 v[8:9], v[0:3], off
	v_mov_b32_dpp v10, v12 row_ror:8 row_mask:0xf bank_mask:0xf
	v_mov_b32_dpp v11, v13 row_ror:8 row_mask:0xf bank_mask:0xf
	v_add_co_u32_e32 v0, vcc, 0x8000, v8
	v_cndmask_b32_e64 v4, v4, v10, s[4:5]
	s_nop 0
	v_addc_co_u32_e32 v1, vcc, 0, v9, vcc
	v_cndmask_b32_e64 v5, v5, v11, s[4:5]
	v_cndmask_b32_e64 v6, v6, v14, s[4:5]
	v_cndmask_b32_e64 v7, v7, v15, s[4:5]
	s_and_b64 vcc, exec, s[34:35]
	s_mov_b32 s38, s18
	s_mov_b64 s[40:41], s[36:37]
	s_mov_b64 s[42:43], s[30:31]
	global_store_dwordx4 v[0:1], v[4:7], off
	s_cbranch_vccz .LBB0_243
	s_waitcnt vmcnt(0)
	s_cmpk_gt_u32 s52, 0xff
	s_cbranch_scc1 .LBB0_252
	s_barrier

; #define PG8_STAGE(bufoff, gbase, voff) do { _Pragma("unroll") for (int _i = 0; _i < 2; ++_i) \
;         __builtin_amdgcn_global_load_lds((const unsigned*)((const char*)(gbase) + (voff)[_i]), (LAS unsigned*)(lds + (bufoff) + ldsw + _i * 8192), 16, 0, 0); } while (0)
; #define PG8_LDA(dst, b, h) do { _Pragma("unroll") for (int m = 0; m < 4; ++m) _Pragma("unroll") for (int k = 0; k < 2; ++k) dst[m][k] = *(const LAS bf16x8*)(lds + PG8_SA(b, h) + aoff + m * 2048 + k * 1024); } while (0)
; #define PG8_LDB(dst, b, h) do { _Pragma("unroll") for (int n = 0; n < 2; ++n) _Pragma("unroll") for (int k = 0; k < 2; ++k) dst[n][k] = *(const LAS bf16x8*)(lds + PG8_SB(b, h) + boff + n * 2048 + k * 1024); } while (0)
; #define PG8_MMA(ai, bj, At, Bt) do { __builtin_amdgcn_s_setprio(1); _Pragma("unroll") for (int m = 0; m < 4; ++m) _Pragma("unroll") for (int n = 0; n < 2; ++n) _Pragma("unroll") for (int k = 0; k < 2; ++k) \
;         acc[ai][bj][m][n] = __builtin_amdgcn_mfma_f32_16x16x32_bf16(Bt[n][k], At[m][k], acc[ai][bj][m][n], 0, 0, 0); __builtin_amdgcn_s_setprio(0); } while (0)
; #define PG8_WAIT_V(n) asm volatile("s_waitcnt vmcnt(" #n ")" ::: "memory")
; #define PG8_WAIT_L(n) asm volatile("s_waitcnt lgkmcnt(" #n ")" ::: "memory")
; #define PG8_BAR __builtin_amdgcn_s_barrier()
; #define PG8_SCHED __builtin_amdgcn_sched_barrier(0)
; template <class Epi>
; __device__ __forceinline__ void gemm_phase(LAS unsigned char* lds, const Gemm g, const StaticOrder& S, const Epi& E) {
;     ...
;             PG8_LDB(B0, 0, 0); PG8_SCHED; PG8_LDA(At, 0, 0); PG8_STAGE(PG8_SA(1, 1), a1 + hstep, voffA);
;             PG8_WAIT_L(8); PG8_BAR; PG8_WAIT_L(0); PG8_MMA(0, 0, At, B0); PG8_BAR; PG8_SCHED;
;             PG8_LDB(B1, 0, 1); PG8_STAGE(PG8_SB(0, 0), b2, voffB0);
;             PG8_BAR; PG8_WAIT_L(0); PG8_MMA(0, 1, At, B1); PG8_BAR;
;             PG8_LDA(At, 0, 1); PG8_STAGE(PG8_SA(0, 0), a2, voffA);
;             PG8_BAR; PG8_WAIT_L(0); PG8_MMA(1, 0, At, B0); PG8_BAR; PG8_SCHED;
;             PG8_STAGE(PG8_SB(0, 1), b2, voffB1);
;             PG8_WAIT_V(6); PG8_BAR; PG8_MMA(1, 1, At, B1); PG8_BAR;
.LBB0_613:
	ds_read_b128 v[146:149], v155
	ds_read_b128 v[158:161], v155 offset:1024
	ds_read_b128 v[162:165], v155 offset:2048
	ds_read_b128 v[166:169], v155 offset:3072
	s_add_u32 s33, s54, 0xfff80080
	s_addc_u32 s56, s55, -1
	s_cmp_eq_u32 s88, 28
	s_cselect_b32 s57, s43, s56
	s_cselect_b32 s56, s51, s33
	s_cselect_b32 s59, s41, s87
	s_cselect_b32 s58, s85, s86
	v_lshl_add_u64 v[204:205], s[54:55], 0, v[140:141]
	s_add_i32 m0, s53, 0xc000
	ds_read_b128 v[170:173], v156
	ds_read_b128 v[174:177], v156 offset:1024
	ds_read_b128 v[178:181], v156 offset:2048
	ds_read_b128 v[182:185], v156 offset:3072
	ds_read_b128 v[186:189], v156 offset:4096
	ds_read_b128 v[190:193], v156 offset:5120
	ds_read_b128 v[194:197], v156 offset:6144
	ds_read_b128 v[198:201], v156 offset:7168
	global_load_lds_dwordx4 v[204:205], off
	v_lshl_add_u64 v[204:205], s[54:55], 0, v[142:143]
	s_add_i32 m0, s53, 0xe000
	s_nop 0
	global_load_lds_dwordx4 v[204:205], off
	s_waitcnt lgkmcnt(8)
	s_barrier
	s_waitcnt lgkmcnt(0)
	v_mfma_f32_16x16x32_bf16 v[124:127], v[146:149], v[170:173], v[124:127]
	v_mfma_f32_16x16x32_bf16 v[120:123], v[162:165], v[170:173], v[120:123]
	v_mfma_f32_16x16x32_bf16 v[108:111], v[146:149], v[178:181], v[108:111]
	v_mfma_f32_16x16x32_bf16 v[104:107], v[162:165], v[178:181], v[104:107]
	v_mfma_f32_16x16x32_bf16 v[92:95], v[146:149], v[186:189], v[92:95]
	v_mfma_f32_16x16x32_bf16 v[88:91], v[162:165], v[186:189], v[88:91]
	v_mfma_f32_16x16x32_bf16 v[76:79], v[146:149], v[194:197], v[76:79]
	v_mfma_f32_16x16x32_bf16 v[72:75], v[162:165], v[194:197], v[72:75]
	v_mfma_f32_16x16x32_bf16 v[124:127], v[158:161], v[174:177], v[124:127]
	v_mfma_f32_16x16x32_bf16 v[120:123], v[166:169], v[174:177], v[120:123]
	v_mfma_f32_16x16x32_bf16 v[108:111], v[158:161], v[182:185], v[108:111]
	v_mfma_f32_16x16x32_bf16 v[104:107], v[166:169], v[182:185], v[104:107]
	v_mfma_f32_16x16x32_bf16 v[92:95], v[158:161], v[190:193], v[92:95]
	v_mfma_f32_16x16x32_bf16 v[88:91], v[166:169], v[190:193], v[88:91]
	v_mfma_f32_16x16x32_bf16 v[76:79], v[158:161], v[198:201], v[76:79]
	v_mfma_f32_16x16x32_bf16 v[72:75], v[166:169], v[198:201], v[72:75]
	s_barrier
	s_add_i32 s33, s79, s65
	v_lshl_add_u64 v[220:221], s[58:59], 0, v[130:131]
	s_mov_b32 m0, s33
	ds_read_b128 v[204:207], v157
	ds_read_b128 v[208:211], v157 offset:1024
	ds_read_b128 v[212:215], v157 offset:2048
	ds_read_b128 v[216:219], v157 offset:3072
	global_load_lds_dwordx4 v[220:221], off
	v_lshl_add_u64 v[222:223], s[58:59], 0, v[136:137]
	s_add_i32 m0, s33, 0x2000
	s_nop 0
	global_load_lds_dwordx4 v[222:223], off
	s_barrier
	s_waitcnt lgkmcnt(0)
	v_mfma_f32_16x16x32_bf16 v[116:119], v[204:207], v[170:173], v[116:119]
	v_mfma_f32_16x16x32_bf16 v[112:115], v[212:215], v[170:173], v[112:115]
	v_mfma_f32_16x16x32_bf16 v[100:103], v[204:207], v[178:181], v[100:103]
	v_mfma_f32_16x16x32_bf16 v[96:99], v[212:215], v[178:181], v[96:99]
	v_mfma_f32_16x16x32_bf16 v[84:87], v[204:207], v[186:189], v[84:87]
	v_mfma_f32_16x16x32_bf16 v[80:83], v[212:215], v[186:189], v[80:83]
	v_mfma_f32_16x16x32_bf16 v[68:71], v[204:207], v[194:197], v[68:71]
	v_mfma_f32_16x16x32_bf16 v[64:67], v[212:215], v[194:197], v[64:67]
	v_mfma_f32_16x16x32_bf16 v[116:119], v[208:211], v[174:177], v[116:119]
	v_mfma_f32_16x16x32_bf16 v[112:115], v[216:219], v[174:177], v[112:115]
	v_mfma_f32_16x16x32_bf16 v[100:103], v[208:211], v[182:185], v[100:103]
	v_mfma_f32_16x16x32_bf16 v[96:99], v[216:219], v[182:185], v[96:99]
	v_mfma_f32_16x16x32_bf16 v[84:87], v[208:211], v[190:193], v[84:87]
	v_mfma_f32_16x16x32_bf16 v[80:83], v[216:219], v[190:193], v[80:83]
	v_mfma_f32_16x16x32_bf16 v[68:71], v[208:211], v[198:201], v[68:71]
	v_mfma_f32_16x16x32_bf16 v[64:67], v[216:219], v[198:201], v[64:67]
	s_mov_b32 m0, s53
	v_lshl_add_u64 v[224:225], s[56:57], 0, v[128:129]
	s_barrier
	ds_read_b128 v[170:173], v156 offset:16384
	ds_read_b128 v[174:177], v156 offset:17408
	ds_read_b128 v[178:181], v156 offset:18432
	ds_read_b128 v[182:185], v156 offset:19456
	ds_read_b128 v[186:189], v156 offset:20480
	ds_read_b128 v[190:193], v156 offset:21504
	ds_read_b128 v[194:197], v156 offset:22528
	ds_read_b128 v[198:201], v156 offset:23552
	global_load_lds_dwordx4 v[224:225], off
	v_lshl_add_u64 v[226:227], s[56:57], 0, v[134:135]
	s_mov_b32 m0, s66
	s_nop 0
	global_load_lds_dwordx4 v[226:227], off
	s_barrier
	s_waitcnt lgkmcnt(0)
	v_mfma_f32_16x16x32_bf16 v[60:63], v[146:149], v[170:173], v[60:63]
	v_mfma_f32_16x16x32_bf16 v[56:59], v[162:165], v[170:173], v[56:59]
	v_mfma_f32_16x16x32_bf16 v[44:47], v[146:149], v[178:181], v[44:47]
	v_mfma_f32_16x16x32_bf16 v[40:43], v[162:165], v[178:181], v[40:43]
	v_mfma_f32_16x16x32_bf16 v[28:31], v[146:149], v[186:189], v[28:31]
	v_mfma_f32_16x16x32_bf16 v[24:27], v[162:165], v[186:189], v[24:27]
	v_mfma_f32_16x16x32_bf16 v[12:15], v[146:149], v[194:197], v[12:15]
	v_mfma_f32_16x16x32_bf16 v[8:11], v[162:165], v[194:197], v[8:11]
	v_mfma_f32_16x16x32_bf16 v[60:63], v[158:161], v[174:177], v[60:63]
	v_mfma_f32_16x16x32_bf16 v[56:59], v[166:169], v[174:177], v[56:59]
	v_mfma_f32_16x16x32_bf16 v[44:47], v[158:161], v[182:185], v[44:47]
	v_mfma_f32_16x16x32_bf16 v[40:43], v[166:169], v[182:185], v[40:43]
	v_mfma_f32_16x16x32_bf16 v[28:31], v[158:161], v[190:193], v[28:31]
	v_mfma_f32_16x16x32_bf16 v[24:27], v[166:169], v[190:193], v[24:27]
	v_mfma_f32_16x16x32_bf16 v[12:15], v[158:161], v[198:201], v[12:15]
	v_mfma_f32_16x16x32_bf16 v[8:11], v[166:169], v[198:201], v[8:11]
	s_barrier
	s_add_i32 s33, s80, s65
	v_lshl_add_u64 v[228:229], s[58:59], 0, v[132:133]
	s_mov_b32 m0, s33
	v_lshl_add_u64 v[230:231], s[58:59], 0, v[138:139]
	global_load_lds_dwordx4 v[228:229], off
	s_add_i32 m0, s33, 0x2000
	s_nop 0
	global_load_lds_dwordx4 v[230:231], off
	s_waitcnt vmcnt(6)
	s_barrier
; #define PG8_STAGE(bufoff, gbase, voff) do { _Pragma("unroll") for (int _i = 0; _i < 2; ++_i) \
;         __builtin_amdgcn_global_load_lds((const unsigned*)((const char*)(gbase) + (voff)[_i]), (LAS unsigned*)(lds + (bufoff) + ldsw + _i * 8192), 16, 0, 0); } while (0)
; #define PG8_LDA(dst, b, h) do { _Pragma("unroll") for (int m = 0; m < 4; ++m) _Pragma("unroll") for (int k = 0; k < 2; ++k) dst[m][k] = *(const LAS bf16x8*)(lds + PG8_SA(b, h) + aoff + m * 2048 + k * 1024); } while (0)
; #define PG8_LDB(dst, b, h) do { _Pragma("unroll") for (int n = 0; n < 2; ++n) _Pragma("unroll") for (int k = 0; k < 2; ++k) dst[n][k] = *(const LAS bf16x8*)(lds + PG8_SB(b, h) + boff + n * 2048 + k * 1024); } while (0)
; #define PG8_MMA(ai, bj, At, Bt) do { __builtin_amdgcn_s_setprio(1); _Pragma("unroll") for (int m = 0; m < 4; ++m) _Pragma("unroll") for (int n = 0; n < 2; ++n) _Pragma("unroll") for (int k = 0; k < 2; ++k) \
;         acc[ai][bj][m][n] = __builtin_amdgcn_mfma_f32_16x16x32_bf16(Bt[n][k], At[m][k], acc[ai][bj][m][n], 0, 0, 0); __builtin_amdgcn_s_setprio(0); } while (0)
; #define PG8_WAIT_V(n) asm volatile("s_waitcnt vmcnt(" #n ")" ::: "memory")
; #define PG8_WAIT_L(n) asm volatile("s_waitcnt lgkmcnt(" #n ")" ::: "memory")
; #define PG8_BAR __builtin_amdgcn_s_barrier()
; #define PG8_SCHED __builtin_amdgcn_sched_barrier(0)
; template <class Epi>
; __device__ __forceinline__ void gemm_phase(LAS unsigned char* lds, const Gemm g, const StaticOrder& S, const Epi& E) {
;     ...
;             PG8_WAIT_V(6); PG8_BAR; PG8_MMA(1, 1, At, B1); PG8_BAR;
;             PG8_LDB(B0, 1, 0); PG8_SCHED; PG8_LDA(At, 1, 0); PG8_STAGE(PG8_SA(0, 1), a2 + hstep, voffA);
;             PG8_WAIT_L(8); PG8_BAR; PG8_WAIT_L(0); PG8_MMA(0, 0, At, B0); PG8_BAR; PG8_SCHED;
;             PG8_LDB(B1, 1, 1); PG8_STAGE(PG8_SB(1, 0), b3, voffB0);
;             PG8_BAR; PG8_WAIT_L(0); PG8_MMA(0, 1, At, B1); PG8_BAR;
;             PG8_LDA(At, 1, 1); PG8_STAGE(PG8_SA(1, 0), a3, voffA);
;             PG8_BAR; PG8_WAIT_L(0); PG8_MMA(1, 0, At, B0); PG8_BAR; PG8_SCHED;
	v_mfma_f32_16x16x32_bf16 v[52:55], v[204:207], v[170:173], v[52:55]
	v_mfma_f32_16x16x32_bf16 v[48:51], v[212:215], v[170:173], v[48:51]
	v_mfma_f32_16x16x32_bf16 v[36:39], v[204:207], v[178:181], v[36:39]
	v_mfma_f32_16x16x32_bf16 v[32:35], v[212:215], v[178:181], v[32:35]
	v_mfma_f32_16x16x32_bf16 v[20:23], v[204:207], v[186:189], v[20:23]
	v_mfma_f32_16x16x32_bf16 v[16:19], v[212:215], v[186:189], v[16:19]
	v_mfma_f32_16x16x32_bf16 v[4:7], v[204:207], v[194:197], v[4:7]
	v_mfma_f32_16x16x32_bf16 v[0:3], v[212:215], v[194:197], v[0:3]
	v_mfma_f32_16x16x32_bf16 v[52:55], v[208:211], v[174:177], v[52:55]
	v_mfma_f32_16x16x32_bf16 v[48:51], v[216:219], v[174:177], v[48:51]
	v_mfma_f32_16x16x32_bf16 v[36:39], v[208:211], v[182:185], v[36:39]
	v_mfma_f32_16x16x32_bf16 v[32:35], v[216:219], v[182:185], v[32:35]
	v_mfma_f32_16x16x32_bf16 v[20:23], v[208:211], v[190:193], v[20:23]
	v_mfma_f32_16x16x32_bf16 v[16:19], v[216:219], v[190:193], v[16:19]
	v_mfma_f32_16x16x32_bf16 v[4:7], v[208:211], v[198:201], v[4:7]
	v_mfma_f32_16x16x32_bf16 v[0:3], v[216:219], v[198:201], v[0:3]
	s_add_i32 s33, 0, 0x18000
	v_add_u32_e32 v166, s33, v151
	s_barrier
	ds_read_b128 v[146:149], v166
	ds_read_b128 v[158:161], v166 offset:1024
	ds_read_b128 v[162:165], v166 offset:2048
	ds_read_b128 v[166:169], v166 offset:3072
	s_add_u32 s56, s56, 0x80000
	s_addc_u32 s57, s57, 0
	s_mov_b32 m0, s67
	v_lshl_add_u64 v[204:205], s[56:57], 0, v[128:129]
	ds_read_b128 v[170:173], v156 offset:32768
	ds_read_b128 v[174:177], v156 offset:33792
	ds_read_b128 v[178:181], v156 offset:34816
	ds_read_b128 v[182:185], v156 offset:35840
	ds_read_b128 v[186:189], v156 offset:36864
	ds_read_b128 v[190:193], v156 offset:37888
	ds_read_b128 v[194:197], v156 offset:38912
	ds_read_b128 v[198:201], v156 offset:39936
	global_load_lds_dwordx4 v[204:205], off
	v_lshl_add_u64 v[204:205], s[56:57], 0, v[134:135]
	s_mov_b32 m0, s68
	s_nop 0
	global_load_lds_dwordx4 v[204:205], off
	s_waitcnt lgkmcnt(8)
	s_barrier
	s_waitcnt lgkmcnt(0)
	v_mfma_f32_16x16x32_bf16 v[124:127], v[146:149], v[170:173], v[124:127]
	v_mfma_f32_16x16x32_bf16 v[120:123], v[162:165], v[170:173], v[120:123]
	v_mfma_f32_16x16x32_bf16 v[108:111], v[146:149], v[178:181], v[108:111]
	v_mfma_f32_16x16x32_bf16 v[104:107], v[162:165], v[178:181], v[104:107]
	v_mfma_f32_16x16x32_bf16 v[92:95], v[146:149], v[186:189], v[92:95]
	v_mfma_f32_16x16x32_bf16 v[88:91], v[162:165], v[186:189], v[88:91]
	v_mfma_f32_16x16x32_bf16 v[76:79], v[146:149], v[194:197], v[76:79]
	v_mfma_f32_16x16x32_bf16 v[72:75], v[162:165], v[194:197], v[72:75]
	v_mfma_f32_16x16x32_bf16 v[124:127], v[158:161], v[174:177], v[124:127]
	v_mfma_f32_16x16x32_bf16 v[120:123], v[166:169], v[174:177], v[120:123]
	v_mfma_f32_16x16x32_bf16 v[108:111], v[158:161], v[182:185], v[108:111]
	v_mfma_f32_16x16x32_bf16 v[104:107], v[166:169], v[182:185], v[104:107]
	v_mfma_f32_16x16x32_bf16 v[92:95], v[158:161], v[190:193], v[92:95]
	v_mfma_f32_16x16x32_bf16 v[88:91], v[166:169], v[190:193], v[88:91]
	v_mfma_f32_16x16x32_bf16 v[76:79], v[158:161], v[198:201], v[76:79]
	v_mfma_f32_16x16x32_bf16 v[72:75], v[166:169], v[198:201], v[72:75]
	s_barrier
	s_add_i32 s56, 0, 0x1c000
	s_add_i32 s33, s33, s65
	v_add_u32_e32 v216, s56, v151
	v_lshl_add_u64 v[220:221], v[220:221], 0, s[36:37]
	s_mov_b32 m0, s33
	ds_read_b128 v[204:207], v216
	ds_read_b128 v[208:211], v216 offset:1024
	ds_read_b128 v[212:215], v216 offset:2048
	ds_read_b128 v[216:219], v216 offset:3072
	global_load_lds_dwordx4 v[220:221], off
	v_lshl_add_u64 v[220:221], v[222:223], 0, s[36:37]
	s_add_i32 m0, s33, 0x2000
	s_nop 0
	global_load_lds_dwordx4 v[220:221], off
	s_barrier
	s_waitcnt lgkmcnt(0)
	v_mfma_f32_16x16x32_bf16 v[116:119], v[204:207], v[170:173], v[116:119]
	v_mfma_f32_16x16x32_bf16 v[112:115], v[212:215], v[170:173], v[112:115]
	v_mfma_f32_16x16x32_bf16 v[100:103], v[204:207], v[178:181], v[100:103]
	v_mfma_f32_16x16x32_bf16 v[96:99], v[212:215], v[178:181], v[96:99]
	v_mfma_f32_16x16x32_bf16 v[84:87], v[204:207], v[186:189], v[84:87]
	v_mfma_f32_16x16x32_bf16 v[80:83], v[212:215], v[186:189], v[80:83]
	v_mfma_f32_16x16x32_bf16 v[68:71], v[204:207], v[194:197], v[68:71]
	v_mfma_f32_16x16x32_bf16 v[64:67], v[212:215], v[194:197], v[64:67]
	v_mfma_f32_16x16x32_bf16 v[116:119], v[208:211], v[174:177], v[116:119]
	v_mfma_f32_16x16x32_bf16 v[112:115], v[216:219], v[174:177], v[112:115]
	v_mfma_f32_16x16x32_bf16 v[100:103], v[208:211], v[182:185], v[100:103]
	v_mfma_f32_16x16x32_bf16 v[96:99], v[216:219], v[182:185], v[96:99]
	v_mfma_f32_16x16x32_bf16 v[84:87], v[208:211], v[190:193], v[84:87]
	v_mfma_f32_16x16x32_bf16 v[80:83], v[216:219], v[190:193], v[80:83]
	v_mfma_f32_16x16x32_bf16 v[68:71], v[208:211], v[198:201], v[68:71]
	v_mfma_f32_16x16x32_bf16 v[64:67], v[216:219], v[198:201], v[64:67]
	s_mov_b32 m0, s72
	v_lshl_add_u64 v[220:221], v[224:225], 0, s[36:37]
	s_barrier
	ds_read_b128 v[170:173], v156 offset:49152
	ds_read_b128 v[174:177], v156 offset:50176
	ds_read_b128 v[178:181], v156 offset:51200
	ds_read_b128 v[182:185], v156 offset:52224
	ds_read_b128 v[186:189], v156 offset:53248
	ds_read_b128 v[190:193], v156 offset:54272
	ds_read_b128 v[194:197], v156 offset:55296
	ds_read_b128 v[198:201], v156 offset:56320
	global_load_lds_dwordx4 v[220:221], off
	v_lshl_add_u64 v[220:221], v[226:227], 0, s[36:37]
	s_mov_b32 m0, s73
	s_nop 0
	global_load_lds_dwordx4 v[220:221], off
	s_barrier
; __device__ __forceinline__ unsigned cvt_pk_bf16(float lo, float hi) { unsigned r; asm volatile("v_cvt_pk_bf16_f32 %0, %1, %2" : "=v"(r) : "v"(lo), "v"(hi)); return r; }
; __device__ __forceinline__ float bflo(unsigned w) { return __uint_as_float(w << 16); }
; __device__ __forceinline__ float bfhi(unsigned w) { return __uint_as_float(w & 0xffff0000u); }
; #define PG8_WAIT_V(n) asm volatile("s_waitcnt vmcnt(" #n ")" ::: "memory")
; #define PG8_WAIT_L(n) asm volatile("s_waitcnt lgkmcnt(" #n ")" ::: "memory")
; #define PG8_BAR __builtin_amdgcn_s_barrier()
; #define PG8_SCHED __builtin_amdgcn_sched_barrier(0)
;     __device__ __forceinline__ void operator()(const f32x4 (&acc)[2][2][4][2], const Unit& u, int wr, int wc, int fr, int fq) const {
;     ...
;             for (int m = 0; m < 4; ++m) { const int row = row0 + ai * HALF + m * 16; const size_t off = (size_t)row * D + col0; float sq = 0.f; u32x4 w[2];
;                 const float sc = rsin ? __builtin_amdgcn_rcpf(rsin[row] * (1.f / D) + EPS) : 1.0f;
;                 u32x4 rr[2]; if (R) load_pair_lines(R, D, row, fr, col0, rr[0], rr[1]);
; #pragma unroll
;                 for (int bj = 0; bj < 2; ++bj) { f32x4 r0, r1;
;                     if (R) { const u32x4 rw = rr[bj]; r0 = (f32x4){bflo(rw.x), bfhi(rw.x), bflo(rw.y), bfhi(rw.y)}; r1 = (f32x4){bflo(rw.z), bfhi(rw.z), bflo(rw.w), bfhi(rw.w)}; }
;                     else { const float* rp = (row < 8192 ? src_p + off : src_s + (off - (size_t)8192 * D)) + 8 * bj; r0 = *(const f32x4*)rp; r1 = *(const f32x4*)(rp + 4); }
;                     const f32x4 o0 = r0 + acc[ai][bj][m][0] * sc, o1 = r1 + acc[ai][bj][m][1] * sc;
;                     sq += (o0[0] * o0[0] + o0[1] * o0[1]) + (o0[2] * o0[2] + o0[3] * o0[3]) + (o1[0] * o1[0] + o1[1] * o1[1]) + (o1[2] * o1[2] + o1[3] * o1[3]);
;                     w[bj].x = cvt_pk_bf16(o0[0], o0[1]); w[bj].y = cvt_pk_bf16(o0[2], o0[3]); w[bj].z = cvt_pk_bf16(o1[0], o1[1]); w[bj].w = cvt_pk_bf16(o1[2], o1[3]); }
;                 store_pair_lines(O, D, row, fr, col0, w[0], w[1]);
; template <class Epi>
; __device__ __forceinline__ void gemm_phase(LAS unsigned char* lds, const Gemm g, const StaticOrder& S, const Epi& E) {
;     ...
;             PG8_BAR; PG8_WAIT_L(0); PG8_MMA(1, 0, At, B0); PG8_BAR; PG8_SCHED;
;             PG8_STAGE(PG8_SB(1, 1), b3, voffB1);
;             PG8_WAIT_V(6); PG8_BAR; PG8_MMA(1, 1, At, B1); PG8_BAR;
	s_waitcnt lgkmcnt(0)
	v_mfma_f32_16x16x32_bf16 v[60:63], v[146:149], v[170:173], v[60:63]
	v_mfma_f32_16x16x32_bf16 v[56:59], v[162:165], v[170:173], v[56:59]
	v_mfma_f32_16x16x32_bf16 v[44:47], v[146:149], v[178:181], v[44:47]
	v_mfma_f32_16x16x32_bf16 v[40:43], v[162:165], v[178:181], v[40:43]
	v_mfma_f32_16x16x32_bf16 v[28:31], v[146:149], v[186:189], v[28:31]
	v_mfma_f32_16x16x32_bf16 v[24:27], v[162:165], v[186:189], v[24:27]
	v_mfma_f32_16x16x32_bf16 v[12:15], v[146:149], v[194:197], v[12:15]
	v_mfma_f32_16x16x32_bf16 v[8:11], v[162:165], v[194:197], v[8:11]
	v_mfma_f32_16x16x32_bf16 v[60:63], v[158:161], v[174:177], v[60:63]
	v_mfma_f32_16x16x32_bf16 v[56:59], v[166:169], v[174:177], v[56:59]
	v_mfma_f32_16x16x32_bf16 v[44:47], v[158:161], v[182:185], v[44:47]
	v_mfma_f32_16x16x32_bf16 v[40:43], v[166:169], v[182:185], v[40:43]
	v_mfma_f32_16x16x32_bf16 v[28:31], v[158:161], v[190:193], v[28:31]
	v_mfma_f32_16x16x32_bf16 v[24:27], v[166:169], v[190:193], v[24:27]
	v_mfma_f32_16x16x32_bf16 v[12:15], v[158:161], v[198:201], v[12:15]
	v_mfma_f32_16x16x32_bf16 v[8:11], v[166:169], v[198:201], v[8:11]
	s_barrier
	s_add_i32 s33, s56, s65
	v_lshl_add_u64 v[146:147], v[228:229], 0, s[36:37]
	s_mov_b32 m0, s33
	s_nop 0
	global_load_lds_dwordx4 v[146:147], off
	v_lshl_add_u64 v[146:147], v[230:231], 0, s[36:37]
	s_add_i32 m0, s33, 0x2000
	s_nop 0
	global_load_lds_dwordx4 v[146:147], off
	s_waitcnt vmcnt(6)
	s_barrier
	v_mfma_f32_16x16x32_bf16 v[52:55], v[204:207], v[170:173], v[52:55]
	v_mfma_f32_16x16x32_bf16 v[48:51], v[212:215], v[170:173], v[48:51]
	v_mfma_f32_16x16x32_bf16 v[36:39], v[204:207], v[178:181], v[36:39]
	v_mfma_f32_16x16x32_bf16 v[32:35], v[212:215], v[178:181], v[32:35]
	v_mfma_f32_16x16x32_bf16 v[20:23], v[204:207], v[186:189], v[20:23]
	v_mfma_f32_16x16x32_bf16 v[16:19], v[212:215], v[186:189], v[16:19]
	v_mfma_f32_16x16x32_bf16 v[4:7], v[204:207], v[194:197], v[4:7]
	v_mfma_f32_16x16x32_bf16 v[0:3], v[212:215], v[194:197], v[0:3]
	v_mfma_f32_16x16x32_bf16 v[52:55], v[208:211], v[174:177], v[52:55]
	v_mfma_f32_16x16x32_bf16 v[48:51], v[216:219], v[174:177], v[48:51]
	v_mfma_f32_16x16x32_bf16 v[36:39], v[208:211], v[182:185], v[36:39]
	v_mfma_f32_16x16x32_bf16 v[32:35], v[216:219], v[182:185], v[32:35]
	v_mfma_f32_16x16x32_bf16 v[20:23], v[208:211], v[190:193], v[20:23]
	v_mfma_f32_16x16x32_bf16 v[16:19], v[216:219], v[190:193], v[16:19]
	v_mfma_f32_16x16x32_bf16 v[4:7], v[208:211], v[198:201], v[4:7]
	v_mfma_f32_16x16x32_bf16 v[0:3], v[216:219], v[198:201], v[0:3]
	s_add_i32 s88, s88, 2
	s_add_u32 s54, s54, 0x100
	s_addc_u32 s55, s55, 0
	s_add_u32 s86, s86, 0x100
	s_addc_u32 s87, s87, 0
	s_cmp_gt_u32 s88, 29
	s_barrier
	s_cbranch_scc0 .LBB0_613
	s_lshl_b32 s33, s52, 8
	s_add_i32 s33, s33, s74
	v_or_b32_e32 v146, s33, v150
	v_lshl_or_b32 v148, s50, 8, v154
	v_ashrrev_i32_e32 v147, 31, v146
	v_ashrrev_i32_e32 v149, 31, v148
	v_lshlrev_b64 v[158:159], 11, v[146:147]
	v_lshl_add_u64 v[158:159], v[158:159], 0, v[148:149]
	v_lshlrev_b64 v[158:159], 2, v[158:159]
	v_lshl_add_u64 v[160:161], s[16:17], 0, v[158:159]
	v_lshl_add_u64 v[158:159], s[18:19], 0, v[158:159]
	v_lshl_add_u64 v[158:159], v[158:159], 0, s[38:39]
	v_cmp_gt_i32_e32 vcc, s70, v146
	v_mov_b32_e32 v183, 0
	v_mov_b32_e32 v184, 0
	v_cndmask_b32_e32 v167, v159, v161, vcc
	v_cndmask_b32_e32 v166, v158, v160, vcc
	global_load_dwordx4 v[158:161], v[166:167], off
	global_load_dwordx4 v[162:165], v[166:167], off offset:16
	v_or_b32_e32 v188, 16, v146
	v_ashrrev_i32_e32 v189, 31, v188
	v_lshlrev_b64 v[190:191], 11, v[188:189]
	v_lshl_add_u64 v[190:191], v[190:191], 0, v[148:149]
	v_lshlrev_b64 v[190:191], 2, v[190:191]
	v_lshl_add_u64 v[192:193], s[16:17], 0, v[190:191]
	v_lshl_add_u64 v[190:191], s[18:19], 0, v[190:191]
	v_lshl_add_u64 v[190:191], v[190:191], 0, s[38:39]
	v_cmp_gt_i32_e32 vcc, s70, v188
	s_nop 1
	v_cndmask_b32_e32 v195, v191, v193, vcc
	v_cndmask_b32_e32 v194, v190, v192, vcc
	global_load_dwordx4 v[196:199], v[194:195], off
	global_load_dwordx4 v[204:207], v[194:195], off offset:16
	global_load_dwordx4 v[208:211], v[194:195], off offset:32
	global_load_dwordx4 v[212:215], v[194:195], off offset:48
	v_or_b32_e32 v188, 32, v146
	v_ashrrev_i32_e32 v189, 31, v188
	v_lshlrev_b64 v[190:191], 11, v[188:189]
	v_lshl_add_u64 v[190:191], v[190:191], 0, v[148:149]
	v_lshlrev_b64 v[190:191], 2, v[190:191]
	v_lshl_add_u64 v[192:193], s[16:17], 0, v[190:191]
	v_lshl_add_u64 v[190:191], s[18:19], 0, v[190:191]
	v_lshl_add_u64 v[190:191], v[190:191], 0, s[38:39]
	v_cmp_gt_i32_e32 vcc, s70, v188
	s_nop 1
	v_cndmask_b32_e32 v195, v191, v193, vcc
	v_cndmask_b32_e32 v194, v190, v192, vcc
	global_load_dwordx4 v[216:219], v[194:195], off
	global_load_dwordx4 v[220:223], v[194:195], off offset:16
	global_load_dwordx4 v[224:227], v[194:195], off offset:32
	global_load_dwordx4 v[228:231], v[194:195], off offset:48
	v_or_b32_e32 v188, 48, v146
	v_ashrrev_i32_e32 v189, 31, v188
	v_lshlrev_b64 v[190:191], 11, v[188:189]
	v_lshl_add_u64 v[190:191], v[190:191], 0, v[148:149]
	v_lshlrev_b64 v[190:191], 2, v[190:191]
	v_lshl_add_u64 v[192:193], s[16:17], 0, v[190:191]
	v_lshl_add_u64 v[190:191], s[18:19], 0, v[190:191]
	v_lshl_add_u64 v[190:191], v[190:191], 0, s[38:39]
	v_cmp_gt_i32_e32 vcc, s70, v188
	s_nop 1
	v_cndmask_b32_e32 v195, v191, v193, vcc
	v_cndmask_b32_e32 v194, v190, v192, vcc
	global_load_dwordx4 v[232:235], v[194:195], off
	global_load_dwordx4 v[236:239], v[194:195], off offset:16
	global_load_dwordx4 v[240:243], v[194:195], off offset:32
	global_load_dwordx4 v[244:247], v[194:195], off offset:48
	s_waitcnt vmcnt(12)
; __device__ __forceinline__ unsigned cvt_pk_bf16(float lo, float hi) { unsigned r; asm volatile("v_cvt_pk_bf16_f32 %0, %1, %2" : "=v"(r) : "v"(lo), "v"(hi)); return r; }
; __device__ __forceinline__ float bflo(unsigned w) { return __uint_as_float(w << 16); }
; __device__ __forceinline__ void store_pair_lines(bf16_t* O, int ldc, int row, int fr, int col0, u32x4 wA, u32x4 wB) {
;     const u32x4 sA = {dpp_ror8(wA.x), dpp_ror8(wA.y), dpp_ror8(wA.z), dpp_ror8(wA.w)}, sB = {dpp_ror8(wB.x), dpp_ror8(wB.y), dpp_ror8(wB.z), dpp_ror8(wB.w)};
;     const bool lo = fr < 8;
;     const u32x4 o1 = lo ? wA : sB, o2 = lo ? sA : wB;
;     const int r1 = row - fr + (fr & 7), cb = col0 + (lo ? 0 : 8);
;     *(u32x4*)(O + (size_t)r1 * ldc + cb) = o1;
;     *(u32x4*)(O + (size_t)(r1 + 8) * ldc + cb) = o2;
;     __device__ __forceinline__ void operator()(const f32x4 (&acc)[2][2][4][2], const Unit& u, int wr, int wc, int fr, int fq) const {
;     ...
;             for (int m = 0; m < 4; ++m) { const int row = row0 + ai * HALF + m * 16; const size_t off = (size_t)row * D + col0; float sq = 0.f; u32x4 w[2];
;                 const float sc = rsin ? __builtin_amdgcn_rcpf(rsin[row] * (1.f / D) + EPS) : 1.0f;
;                 u32x4 rr[2]; if (R) load_pair_lines(R, D, row, fr, col0, rr[0], rr[1]);
; #pragma unroll
;                 for (int bj = 0; bj < 2; ++bj) { f32x4 r0, r1;
;                     if (R) { const u32x4 rw = rr[bj]; r0 = (f32x4){bflo(rw.x), bfhi(rw.x), bflo(rw.y), bfhi(rw.y)}; r1 = (f32x4){bflo(rw.z), bfhi(rw.z), bflo(rw.w), bfhi(rw.w)}; }
;                     else { const float* rp = (row < 8192 ? src_p + off : src_s + (off - (size_t)8192 * D)) + 8 * bj; r0 = *(const f32x4*)rp; r1 = *(const f32x4*)(rp + 4); }
;                     const f32x4 o0 = r0 + acc[ai][bj][m][0] * sc, o1 = r1 + acc[ai][bj][m][1] * sc;
;                     sq += (o0[0] * o0[0] + o0[1] * o0[1]) + (o0[2] * o0[2] + o0[3] * o0[3]) + (o1[0] * o1[0] + o1[1] * o1[1]) + (o1[2] * o1[2] + o1[3] * o1[3]);
;                     w[bj].x = cvt_pk_bf16(o0[0], o0[1]); w[bj].y = cvt_pk_bf16(o0[2], o0[3]); w[bj].z = cvt_pk_bf16(o1[0], o1[1]); w[bj].w = cvt_pk_bf16(o1[2], o1[3]); }
;                 store_pair_lines(O, D, row, fr, col0, w[0], w[1]);
;                 if (ssout) { sq += __shfl_xor(sq, 16); sq += __shfl_xor(sq, 32); if (fq == 0) unsafeAtomicAdd(ssout + row, sq); } }
	v_pk_add_f32 v[168:169], v[126:127], v[160:161]
	v_pk_add_f32 v[170:171], v[124:125], v[158:159]
	v_pk_add_f32 v[164:165], v[122:123], v[164:165]
	v_pk_add_f32 v[162:163], v[120:121], v[162:163]
	v_cvt_pk_bf16_f32 v123, v170, v171
	v_cvt_pk_bf16_f32 v176, v168, v169
	v_mul_f32_e32 v171, v171, v171
	v_cvt_pk_bf16_f32 v177, v162, v163
	v_cvt_pk_bf16_f32 v178, v164, v165
	global_load_dwordx4 v[124:127], v[166:167], off offset:32
	global_load_dwordx4 v[158:161], v[166:167], off offset:48
	v_mul_f32_e32 v169, v169, v169
	v_and_b32_e32 v121, 64, v203
	v_mul_f32_e32 v163, v163, v163
	v_fmac_f32_e32 v171, v170, v170
	v_fmac_f32_e32 v169, v168, v168
	v_xor_b32_e32 v122, 16, v203
	v_add_u32_e32 v172, 64, v121
	v_mul_f32_e32 v165, v165, v165
	v_fmac_f32_e32 v163, v162, v162
	v_add_f32_e32 v162, v171, v169
	v_cmp_lt_i32_e32 vcc, v122, v172
	v_fmac_f32_e32 v165, v164, v164
	v_add_f32_e32 v162, v163, v162
	v_cndmask_b32_e32 v122, v203, v122, vcc
	v_add_f32_e32 v162, v165, v162
	v_xor_b32_e32 v167, 32, v203
	v_lshlrev_b32_e32 v122, 2, v122
	v_or_b32_e32 v166, s33, v152
	v_cmp_lt_i32_e32 vcc, v167, v172
	v_or_b32_e32 v120, v148, v153
	v_ashrrev_i32_e32 v121, 31, v120
	v_cndmask_b32_e32 v187, v203, v167, vcc
	v_ashrrev_i32_e32 v167, 31, v166
	v_or_b32_e32 v174, 8, v166
	v_lshlrev_b64 v[166:167], 12, v[166:167]
	v_lshlrev_b64 v[172:173], 1, v[120:121]
	v_lshl_add_u64 v[166:167], s[10:11], 0, v[166:167]
	v_lshl_add_u64 v[166:167], v[166:167], 0, v[172:173]
	v_ashrrev_i32_e32 v175, 31, v174
	v_mov_b32_dpp v179, v123 row_ror:8 row_mask:0xf bank_mask:0xf
	v_mov_b32_dpp v180, v176 row_ror:8 row_mask:0xf bank_mask:0xf
	v_mov_b32_dpp v181, v177 row_ror:8 row_mask:0xf bank_mask:0xf
	v_mov_b32_dpp v182, v178 row_ror:8 row_mask:0xf bank_mask:0xf
	s_waitcnt vmcnt(0)
	v_pk_add_f32 v[126:127], v[118:119], v[126:127]
	v_pk_add_f32 v[124:125], v[116:117], v[124:125]
	v_pk_add_f32 v[112:113], v[112:113], v[158:159]
	v_cvt_pk_bf16_f32 v116, v124, v125
	v_cvt_pk_bf16_f32 v117, v126, v127
	v_mul_f32_e32 v125, v125, v125
	v_mul_f32_e32 v127, v127, v127
	v_pk_add_f32 v[114:115], v[114:115], v[160:161]
	v_mul_f32_e32 v158, v113, v113
	v_fmac_f32_e32 v125, v124, v124
	v_fmac_f32_e32 v127, v126, v126
	v_cvt_pk_bf16_f32 v118, v112, v113
	v_cvt_pk_bf16_f32 v119, v114, v115
	v_mul_f32_e32 v115, v115, v115
	v_fmac_f32_e32 v158, v112, v112
	v_add_f32_e32 v112, v125, v127
	v_fmac_f32_e32 v115, v114, v114
	v_add_f32_e32 v112, v158, v112
	v_add_f32_e32 v112, v115, v112
	v_add_f32_e32 v124, v162, v112
	ds_bpermute_b32 v125, v122, v124
	v_mov_b32_dpp v183, v116 row_ror:8 row_mask:0xf bank_mask:0xf
	v_mov_b32_dpp v184, v117 row_ror:8 row_mask:0xf bank_mask:0xf
	v_mov_b32_dpp v185, v118 row_ror:8 row_mask:0xf bank_mask:0xf
	v_mov_b32_dpp v186, v119 row_ror:8 row_mask:0xf bank_mask:0xf
	v_cndmask_b32_e64 v113, v184, v176, s[6:7]
	v_cndmask_b32_e64 v115, v186, v178, s[6:7]
	v_cndmask_b32_e64 v112, v183, v123, s[6:7]
	v_cndmask_b32_e64 v114, v185, v177, s[6:7]
	global_store_dwordx4 v[166:167], v[112:115], off
	v_cndmask_b32_e64 v117, v117, v180, s[6:7]
	v_cndmask_b32_e64 v119, v119, v182, s[6:7]
	s_waitcnt lgkmcnt(0)
	v_add_f32_e32 v112, v124, v125
	v_lshlrev_b32_e32 v114, 2, v187
	ds_bpermute_b32 v113, v114, v112
	v_lshlrev_b64 v[124:125], 12, v[174:175]
	v_lshl_add_u64 v[124:125], s[10:11], 0, v[124:125]
	v_cndmask_b32_e64 v116, v116, v179, s[6:7]
	v_cndmask_b32_e64 v118, v118, v181, s[6:7]
	v_lshl_add_u64 v[124:125], v[124:125], 0, v[172:173]
	global_store_dwordx4 v[124:125], v[116:119], off
	s_and_saveexec_b64 s[50:51], s[8:9]
	s_cbranch_execz .LBB0_616
	s_waitcnt lgkmcnt(0)
	v_add_f32_e32 v115, v112, v113
	v_lshl_add_u64 v[112:113], v[146:147], 2, s[12:13]
	global_atomic_add_f32 v[112:113], v115, off
.LBB0_616:
	s_or_b64 exec, exec, s[50:51]
	v_or_b32_e32 v112, 16, v146
	s_waitcnt lgkmcnt(0)
	v_ashrrev_i32_e32 v113, 31, v112
	v_lshlrev_b64 v[116:117], 11, v[112:113]
	v_lshl_add_u64 v[116:117], v[116:117], 0, v[148:149]
	v_lshlrev_b64 v[116:117], 2, v[116:117]
	v_lshl_add_u64 v[118:119], s[16:17], 0, v[116:117]
	v_lshl_add_u64 v[116:117], s[18:19], 0, v[116:117]
	v_lshl_add_u64 v[116:117], v[116:117], 0, s[38:39]
	v_cmp_gt_i32_e32 vcc, s70, v112
	v_mov_b32_e32 v165, 0
	v_mov_b32_e32 v166, 0
	v_cndmask_b32_e32 v159, v117, v119, vcc
	v_cndmask_b32_e32 v158, v116, v118, vcc
	s_waitcnt vmcnt(12)
; __device__ __forceinline__ unsigned cvt_pk_bf16(float lo, float hi) { unsigned r; asm volatile("v_cvt_pk_bf16_f32 %0, %1, %2" : "=v"(r) : "v"(lo), "v"(hi)); return r; }
; __device__ __forceinline__ float bflo(unsigned w) { return __uint_as_float(w << 16); }
; __device__ __forceinline__ void store_pair_lines(bf16_t* O, int ldc, int row, int fr, int col0, u32x4 wA, u32x4 wB) {
;     const u32x4 sA = {dpp_ror8(wA.x), dpp_ror8(wA.y), dpp_ror8(wA.z), dpp_ror8(wA.w)}, sB = {dpp_ror8(wB.x), dpp_ror8(wB.y), dpp_ror8(wB.z), dpp_ror8(wB.w)};
;     const bool lo = fr < 8;
;     const u32x4 o1 = lo ? wA : sB, o2 = lo ? sA : wB;
;     const int r1 = row - fr + (fr & 7), cb = col0 + (lo ? 0 : 8);
;     *(u32x4*)(O + (size_t)r1 * ldc + cb) = o1;
;     *(u32x4*)(O + (size_t)(r1 + 8) * ldc + cb) = o2;
;     __device__ __forceinline__ void operator()(const f32x4 (&acc)[2][2][4][2], const Unit& u, int wr, int wc, int fr, int fq) const {
;     ...
;             for (int m = 0; m < 4; ++m) { const int row = row0 + ai * HALF + m * 16; const size_t off = (size_t)row * D + col0; float sq = 0.f; u32x4 w[2];
;                 const float sc = rsin ? __builtin_amdgcn_rcpf(rsin[row] * (1.f / D) + EPS) : 1.0f;
;                 u32x4 rr[2]; if (R) load_pair_lines(R, D, row, fr, col0, rr[0], rr[1]);
; #pragma unroll
;                 for (int bj = 0; bj < 2; ++bj) { f32x4 r0, r1;
;                     if (R) { const u32x4 rw = rr[bj]; r0 = (f32x4){bflo(rw.x), bfhi(rw.x), bflo(rw.y), bfhi(rw.y)}; r1 = (f32x4){bflo(rw.z), bfhi(rw.z), bflo(rw.w), bfhi(rw.w)}; }
;                     else { const float* rp = (row < 8192 ? src_p + off : src_s + (off - (size_t)8192 * D)) + 8 * bj; r0 = *(const f32x4*)rp; r1 = *(const f32x4*)(rp + 4); }
;                     const f32x4 o0 = r0 + acc[ai][bj][m][0] * sc, o1 = r1 + acc[ai][bj][m][1] * sc;
;                     sq += (o0[0] * o0[0] + o0[1] * o0[1]) + (o0[2] * o0[2] + o0[3] * o0[3]) + (o1[0] * o1[0] + o1[1] * o1[1]) + (o1[2] * o1[2] + o1[3] * o1[3]);
;                     w[bj].x = cvt_pk_bf16(o0[0], o0[1]); w[bj].y = cvt_pk_bf16(o0[2], o0[3]); w[bj].z = cvt_pk_bf16(o1[0], o1[1]); w[bj].w = cvt_pk_bf16(o1[2], o1[3]); }
;                 store_pair_lines(O, D, row, fr, col0, w[0], w[1]);
;                 if (ssout) { sq += __shfl_xor(sq, 16); sq += __shfl_xor(sq, 32); if (fq == 0) unsafeAtomicAdd(ssout + row, sq); } }
	s_nop 0
	v_mov_b64_e32 v[116:117], v[196:197]
	v_mov_b64_e32 v[118:119], v[198:199]
	v_mov_b64_e32 v[124:125], v[204:205]
	v_mov_b64_e32 v[126:127], v[206:207]
	v_pk_add_f32 v[118:119], v[110:111], v[118:119]
	v_pk_add_f32 v[116:117], v[108:109], v[116:117]
	v_pk_add_f32 v[126:127], v[106:107], v[126:127]
	v_pk_add_f32 v[124:125], v[104:105], v[124:125]
	v_cvt_pk_bf16_f32 v115, v116, v117
	v_cvt_pk_bf16_f32 v123, v118, v119
	v_mul_f32_e32 v117, v117, v117
	v_cvt_pk_bf16_f32 v147, v124, v125
	v_cvt_pk_bf16_f32 v160, v126, v127
	v_mov_b64_e32 v[104:105], v[208:209]
	v_mov_b64_e32 v[106:107], v[210:211]
	v_mov_b64_e32 v[108:109], v[212:213]
	v_mov_b64_e32 v[110:111], v[214:215]
	s_nop 1
	v_add_u32_e32 v188, 0x80, v146
	v_ashrrev_i32_e32 v189, 31, v188
	v_lshlrev_b64 v[190:191], 11, v[188:189]
	v_lshl_add_u64 v[190:191], v[190:191], 0, v[148:149]
	v_lshlrev_b64 v[190:191], 2, v[190:191]
	v_lshl_add_u64 v[192:193], s[16:17], 0, v[190:191]
	v_lshl_add_u64 v[190:191], s[18:19], 0, v[190:191]
	v_lshl_add_u64 v[190:191], v[190:191], 0, s[38:39]
	v_cmp_gt_i32_e32 vcc, s81, v146
	s_nop 1
	v_cndmask_b32_e32 v195, v191, v193, vcc
	v_cndmask_b32_e32 v194, v190, v192, vcc
	global_load_dwordx4 v[196:199], v[194:195], off
	global_load_dwordx4 v[204:207], v[194:195], off offset:16
	global_load_dwordx4 v[208:211], v[194:195], off offset:32
	global_load_dwordx4 v[212:215], v[194:195], off offset:48
	v_mul_f32_e32 v119, v119, v119
	v_mul_f32_e32 v125, v125, v125
	v_fmac_f32_e32 v117, v116, v116
	v_fmac_f32_e32 v119, v118, v118
	v_mul_f32_e32 v127, v127, v127
	v_fmac_f32_e32 v125, v124, v124
	v_add_f32_e32 v116, v117, v119
	v_fmac_f32_e32 v127, v126, v126
	v_add_f32_e32 v116, v125, v116
	v_add_f32_e32 v116, v127, v116
	v_sub_u32_e32 v158, v112, v150
	v_add_u32_e32 v158, v158, v152
	v_ashrrev_i32_e32 v159, 31, v158
	v_lshlrev_b64 v[158:159], 12, v[158:159]
	v_lshl_add_u64 v[158:159], s[10:11], 0, v[158:159]
	v_lshl_add_u64 v[158:159], v[120:121], 1, v[158:159]
	v_mov_b32_dpp v161, v115 row_ror:8 row_mask:0xf bank_mask:0xf
	v_mov_b32_dpp v162, v123 row_ror:8 row_mask:0xf bank_mask:0xf
	v_mov_b32_dpp v163, v147 row_ror:8 row_mask:0xf bank_mask:0xf
	v_mov_b32_dpp v164, v160 row_ror:8 row_mask:0xf bank_mask:0xf
	v_pk_add_f32 v[102:103], v[102:103], v[106:107]
	v_pk_add_f32 v[104:105], v[100:101], v[104:105]
	v_pk_add_f32 v[106:107], v[98:99], v[110:111]
	v_pk_add_f32 v[96:97], v[96:97], v[108:109]
	v_cvt_pk_bf16_f32 v98, v104, v105
	v_mul_f32_e32 v105, v105, v105
	v_mul_f32_e32 v108, v103, v103
	v_cvt_pk_bf16_f32 v99, v102, v103
	v_cvt_pk_bf16_f32 v100, v96, v97
	v_mul_f32_e32 v97, v97, v97
	v_fmac_f32_e32 v105, v104, v104
	v_fmac_f32_e32 v108, v102, v102
	v_cvt_pk_bf16_f32 v101, v106, v107
	v_mul_f32_e32 v107, v107, v107
	v_fmac_f32_e32 v97, v96, v96
	v_add_f32_e32 v96, v105, v108
	v_fmac_f32_e32 v107, v106, v106
	v_add_f32_e32 v96, v97, v96
	v_add_f32_e32 v96, v107, v96
	v_add_f32_e32 v96, v116, v96
	ds_bpermute_b32 v97, v122, v96
	v_mov_b32_dpp v165, v98 row_ror:8 row_mask:0xf bank_mask:0xf
	v_mov_b32_dpp v166, v99 row_ror:8 row_mask:0xf bank_mask:0xf
	v_mov_b32_dpp v167, v100 row_ror:8 row_mask:0xf bank_mask:0xf
	v_mov_b32_dpp v168, v101 row_ror:8 row_mask:0xf bank_mask:0xf
	s_waitcnt lgkmcnt(0)
	v_add_f32_e32 v96, v96, v97
	ds_bpermute_b32 v97, v114, v96
	v_cndmask_b32_e64 v103, v166, v123, s[6:7]
	v_cndmask_b32_e64 v105, v168, v160, s[6:7]
	v_cndmask_b32_e64 v102, v165, v115, s[6:7]
	v_cndmask_b32_e64 v104, v167, v147, s[6:7]
	global_store_dwordx4 v[158:159], v[102:105], off
	v_cndmask_b32_e64 v99, v99, v162, s[6:7]
	v_cndmask_b32_e64 v101, v101, v164, s[6:7]
	v_add_co_u32_e32 v102, vcc, s69, v158
	v_cndmask_b32_e64 v98, v98, v161, s[6:7]
	v_cndmask_b32_e64 v100, v100, v163, s[6:7]
	v_addc_co_u32_e32 v103, vcc, 0, v159, vcc
	global_store_dwordx4 v[102:103], v[98:101], off
	s_and_saveexec_b64 s[50:51], s[8:9]
	s_cbranch_execz .LBB0_618
	s_waitcnt lgkmcnt(0)
	v_add_f32_e32 v98, v96, v97
	v_lshl_add_u64 v[96:97], v[112:113], 2, s[12:13]
	global_atomic_add_f32 v[96:97], v98, off
.LBB0_618:
	s_or_b64 exec, exec, s[50:51]
	v_or_b32_e32 v96, 32, v146
	s_waitcnt lgkmcnt(0)
	v_ashrrev_i32_e32 v97, 31, v96
	v_lshlrev_b64 v[98:99], 11, v[96:97]
	v_lshl_add_u64 v[98:99], v[98:99], 0, v[148:149]
	v_lshlrev_b64 v[98:99], 2, v[98:99]
	v_lshl_add_u64 v[100:101], s[16:17], 0, v[98:99]
	v_lshl_add_u64 v[98:99], s[18:19], 0, v[98:99]
	v_lshl_add_u64 v[98:99], v[98:99], 0, s[38:39]
	v_cmp_gt_i32_e32 vcc, s70, v96
	v_mov_b32_e32 v117, 0
	v_mov_b32_e32 v118, 0
	v_cndmask_b32_e32 v107, v99, v101, vcc
	v_cndmask_b32_e32 v106, v98, v100, vcc
	s_waitcnt vmcnt(14)
; __device__ __forceinline__ unsigned cvt_pk_bf16(float lo, float hi) { unsigned r; asm volatile("v_cvt_pk_bf16_f32 %0, %1, %2" : "=v"(r) : "v"(lo), "v"(hi)); return r; }
; __device__ __forceinline__ float bflo(unsigned w) { return __uint_as_float(w << 16); }
; __device__ __forceinline__ void store_pair_lines(bf16_t* O, int ldc, int row, int fr, int col0, u32x4 wA, u32x4 wB) {
;     const u32x4 sA = {dpp_ror8(wA.x), dpp_ror8(wA.y), dpp_ror8(wA.z), dpp_ror8(wA.w)}, sB = {dpp_ror8(wB.x), dpp_ror8(wB.y), dpp_ror8(wB.z), dpp_ror8(wB.w)};
;     const bool lo = fr < 8;
;     const u32x4 o1 = lo ? wA : sB, o2 = lo ? sA : wB;
;     const int r1 = row - fr + (fr & 7), cb = col0 + (lo ? 0 : 8);
;     *(u32x4*)(O + (size_t)r1 * ldc + cb) = o1;
;     *(u32x4*)(O + (size_t)(r1 + 8) * ldc + cb) = o2;
;     __device__ __forceinline__ void operator()(const f32x4 (&acc)[2][2][4][2], const Unit& u, int wr, int wc, int fr, int fq) const {
;     ...
;             for (int m = 0; m < 4; ++m) { const int row = row0 + ai * HALF + m * 16; const size_t off = (size_t)row * D + col0; float sq = 0.f; u32x4 w[2];
;                 const float sc = rsin ? __builtin_amdgcn_rcpf(rsin[row] * (1.f / D) + EPS) : 1.0f;
;                 u32x4 rr[2]; if (R) load_pair_lines(R, D, row, fr, col0, rr[0], rr[1]);
; #pragma unroll
;                 for (int bj = 0; bj < 2; ++bj) { f32x4 r0, r1;
;                     if (R) { const u32x4 rw = rr[bj]; r0 = (f32x4){bflo(rw.x), bfhi(rw.x), bflo(rw.y), bfhi(rw.y)}; r1 = (f32x4){bflo(rw.z), bfhi(rw.z), bflo(rw.w), bfhi(rw.w)}; }
;                     else { const float* rp = (row < 8192 ? src_p + off : src_s + (off - (size_t)8192 * D)) + 8 * bj; r0 = *(const f32x4*)rp; r1 = *(const f32x4*)(rp + 4); }
;                     const f32x4 o0 = r0 + acc[ai][bj][m][0] * sc, o1 = r1 + acc[ai][bj][m][1] * sc;
;                     sq += (o0[0] * o0[0] + o0[1] * o0[1]) + (o0[2] * o0[2] + o0[3] * o0[3]) + (o1[0] * o1[0] + o1[1] * o1[1]) + (o1[2] * o1[2] + o1[3] * o1[3]);
;                     w[bj].x = cvt_pk_bf16(o0[0], o0[1]); w[bj].y = cvt_pk_bf16(o0[2], o0[3]); w[bj].z = cvt_pk_bf16(o1[0], o1[1]); w[bj].w = cvt_pk_bf16(o1[2], o1[3]); }
;                 store_pair_lines(O, D, row, fr, col0, w[0], w[1]);
;                 if (ssout) { sq += __shfl_xor(sq, 16); sq += __shfl_xor(sq, 32); if (fq == 0) unsafeAtomicAdd(ssout + row, sq); } }
	s_nop 0
	v_mov_b64_e32 v[98:99], v[216:217]
	v_mov_b64_e32 v[100:101], v[218:219]
	v_mov_b64_e32 v[102:103], v[220:221]
	v_mov_b64_e32 v[104:105], v[222:223]
	v_pk_add_f32 v[100:101], v[94:95], v[100:101]
	v_pk_add_f32 v[98:99], v[92:93], v[98:99]
	v_pk_add_f32 v[104:105], v[90:91], v[104:105]
	v_pk_add_f32 v[102:103], v[88:89], v[102:103]
	v_cvt_pk_bf16_f32 v108, v98, v99
	v_cvt_pk_bf16_f32 v109, v100, v101
	v_mul_f32_e32 v99, v99, v99
	v_cvt_pk_bf16_f32 v110, v102, v103
	v_cvt_pk_bf16_f32 v111, v104, v105
	v_mov_b64_e32 v[88:89], v[224:225]
	v_mov_b64_e32 v[90:91], v[226:227]
	v_mov_b64_e32 v[92:93], v[228:229]
	v_mov_b64_e32 v[94:95], v[230:231]
	s_nop 1
	v_add_u32_e32 v188, 0x90, v146
	v_ashrrev_i32_e32 v189, 31, v188
	v_lshlrev_b64 v[190:191], 11, v[188:189]
	v_lshl_add_u64 v[190:191], v[190:191], 0, v[148:149]
	v_lshlrev_b64 v[190:191], 2, v[190:191]
	v_lshl_add_u64 v[192:193], s[16:17], 0, v[190:191]
	v_lshl_add_u64 v[190:191], s[18:19], 0, v[190:191]
	v_lshl_add_u64 v[190:191], v[190:191], 0, s[38:39]
	v_cmp_gt_i32_e32 vcc, s82, v146
	s_nop 1
	v_cndmask_b32_e32 v195, v191, v193, vcc
	v_cndmask_b32_e32 v194, v190, v192, vcc
	global_load_dwordx4 v[216:219], v[194:195], off
	global_load_dwordx4 v[220:223], v[194:195], off offset:16
	global_load_dwordx4 v[224:227], v[194:195], off offset:32
	global_load_dwordx4 v[228:231], v[194:195], off offset:48
	v_mul_f32_e32 v101, v101, v101
	v_mul_f32_e32 v103, v103, v103
	v_fmac_f32_e32 v99, v98, v98
	v_fmac_f32_e32 v101, v100, v100
	v_mul_f32_e32 v105, v105, v105
	v_fmac_f32_e32 v103, v102, v102
	v_add_f32_e32 v98, v99, v101
	v_fmac_f32_e32 v105, v104, v104
	v_add_f32_e32 v98, v103, v98
	v_add_f32_e32 v98, v105, v98
	v_sub_u32_e32 v106, v96, v150
	v_add_u32_e32 v106, v106, v152
	v_ashrrev_i32_e32 v107, 31, v106
	v_lshlrev_b64 v[106:107], 12, v[106:107]
	v_lshl_add_u64 v[106:107], s[10:11], 0, v[106:107]
	v_lshl_add_u64 v[106:107], v[120:121], 1, v[106:107]
	v_mov_b32_dpp v112, v108 row_ror:8 row_mask:0xf bank_mask:0xf
	v_mov_b32_dpp v113, v109 row_ror:8 row_mask:0xf bank_mask:0xf
	v_mov_b32_dpp v115, v110 row_ror:8 row_mask:0xf bank_mask:0xf
	v_mov_b32_dpp v116, v111 row_ror:8 row_mask:0xf bank_mask:0xf
	v_pk_add_f32 v[86:87], v[86:87], v[90:91]
	v_pk_add_f32 v[88:89], v[84:85], v[88:89]
	v_pk_add_f32 v[90:91], v[82:83], v[94:95]
	v_pk_add_f32 v[80:81], v[80:81], v[92:93]
	v_cvt_pk_bf16_f32 v82, v88, v89
	v_mul_f32_e32 v89, v89, v89
	v_mul_f32_e32 v92, v87, v87
	v_cvt_pk_bf16_f32 v83, v86, v87
	v_cvt_pk_bf16_f32 v84, v80, v81
	v_mul_f32_e32 v81, v81, v81
	v_fmac_f32_e32 v89, v88, v88
	v_fmac_f32_e32 v92, v86, v86
	v_cvt_pk_bf16_f32 v85, v90, v91
	v_mul_f32_e32 v91, v91, v91
	v_fmac_f32_e32 v81, v80, v80
	v_add_f32_e32 v80, v89, v92
	v_fmac_f32_e32 v91, v90, v90
	v_add_f32_e32 v80, v81, v80
	v_add_f32_e32 v80, v91, v80
	v_add_f32_e32 v80, v98, v80
	ds_bpermute_b32 v81, v122, v80
	v_mov_b32_dpp v117, v82 row_ror:8 row_mask:0xf bank_mask:0xf
	v_mov_b32_dpp v118, v83 row_ror:8 row_mask:0xf bank_mask:0xf
	v_mov_b32_dpp v119, v84 row_ror:8 row_mask:0xf bank_mask:0xf
	v_mov_b32_dpp v123, v85 row_ror:8 row_mask:0xf bank_mask:0xf
	s_waitcnt lgkmcnt(0)
	v_add_f32_e32 v80, v80, v81
	ds_bpermute_b32 v81, v114, v80
	v_cndmask_b32_e64 v87, v118, v109, s[6:7]
	v_cndmask_b32_e64 v89, v123, v111, s[6:7]
	v_cndmask_b32_e64 v86, v117, v108, s[6:7]
	v_cndmask_b32_e64 v88, v119, v110, s[6:7]
	global_store_dwordx4 v[106:107], v[86:89], off
	v_cndmask_b32_e64 v83, v83, v113, s[6:7]
	v_cndmask_b32_e64 v85, v85, v116, s[6:7]
	v_add_co_u32_e32 v86, vcc, s69, v106
	v_cndmask_b32_e64 v82, v82, v112, s[6:7]
	v_cndmask_b32_e64 v84, v84, v115, s[6:7]
	v_addc_co_u32_e32 v87, vcc, 0, v107, vcc
	global_store_dwordx4 v[86:87], v[82:85], off
	s_and_saveexec_b64 s[50:51], s[8:9]
	s_cbranch_execz .LBB0_620
	s_waitcnt lgkmcnt(0)
	v_add_f32_e32 v82, v80, v81
	v_lshl_add_u64 v[80:81], v[96:97], 2, s[12:13]
	global_atomic_add_f32 v[80:81], v82, off
.LBB0_620:
	s_or_b64 exec, exec, s[50:51]
	v_or_b32_e32 v80, 48, v146
	s_waitcnt lgkmcnt(0)
	v_ashrrev_i32_e32 v81, 31, v80
	v_lshlrev_b64 v[82:83], 11, v[80:81]
	v_lshl_add_u64 v[82:83], v[82:83], 0, v[148:149]
	v_lshlrev_b64 v[82:83], 2, v[82:83]
	v_lshl_add_u64 v[84:85], s[16:17], 0, v[82:83]
	v_lshl_add_u64 v[82:83], s[18:19], 0, v[82:83]
	v_lshl_add_u64 v[82:83], v[82:83], 0, s[38:39]
	v_cmp_gt_i32_e32 vcc, s70, v80
	v_mov_b32_e32 v100, 0
	v_mov_b32_e32 v101, 0
	v_cndmask_b32_e32 v91, v83, v85, vcc
	v_cndmask_b32_e32 v90, v82, v84, vcc
	s_waitcnt vmcnt(16)
; __device__ __forceinline__ unsigned cvt_pk_bf16(float lo, float hi) { unsigned r; asm volatile("v_cvt_pk_bf16_f32 %0, %1, %2" : "=v"(r) : "v"(lo), "v"(hi)); return r; }
; __device__ __forceinline__ float bflo(unsigned w) { return __uint_as_float(w << 16); }
; __device__ __forceinline__ void store_pair_lines(bf16_t* O, int ldc, int row, int fr, int col0, u32x4 wA, u32x4 wB) {
;     const u32x4 sA = {dpp_ror8(wA.x), dpp_ror8(wA.y), dpp_ror8(wA.z), dpp_ror8(wA.w)}, sB = {dpp_ror8(wB.x), dpp_ror8(wB.y), dpp_ror8(wB.z), dpp_ror8(wB.w)};
;     const bool lo = fr < 8;
;     const u32x4 o1 = lo ? wA : sB, o2 = lo ? sA : wB;
;     const int r1 = row - fr + (fr & 7), cb = col0 + (lo ? 0 : 8);
;     *(u32x4*)(O + (size_t)r1 * ldc + cb) = o1;
;     *(u32x4*)(O + (size_t)(r1 + 8) * ldc + cb) = o2;
;     __device__ __forceinline__ void operator()(const f32x4 (&acc)[2][2][4][2], const Unit& u, int wr, int wc, int fr, int fq) const {
;     ...
;             for (int m = 0; m < 4; ++m) { const int row = row0 + ai * HALF + m * 16; const size_t off = (size_t)row * D + col0; float sq = 0.f; u32x4 w[2];
;                 const float sc = rsin ? __builtin_amdgcn_rcpf(rsin[row] * (1.f / D) + EPS) : 1.0f;
;                 u32x4 rr[2]; if (R) load_pair_lines(R, D, row, fr, col0, rr[0], rr[1]);
; #pragma unroll
;                 for (int bj = 0; bj < 2; ++bj) { f32x4 r0, r1;
;                     if (R) { const u32x4 rw = rr[bj]; r0 = (f32x4){bflo(rw.x), bfhi(rw.x), bflo(rw.y), bfhi(rw.y)}; r1 = (f32x4){bflo(rw.z), bfhi(rw.z), bflo(rw.w), bfhi(rw.w)}; }
;                     else { const float* rp = (row < 8192 ? src_p + off : src_s + (off - (size_t)8192 * D)) + 8 * bj; r0 = *(const f32x4*)rp; r1 = *(const f32x4*)(rp + 4); }
;                     const f32x4 o0 = r0 + acc[ai][bj][m][0] * sc, o1 = r1 + acc[ai][bj][m][1] * sc;
;                     sq += (o0[0] * o0[0] + o0[1] * o0[1]) + (o0[2] * o0[2] + o0[3] * o0[3]) + (o1[0] * o1[0] + o1[1] * o1[1]) + (o1[2] * o1[2] + o1[3] * o1[3]);
;                     w[bj].x = cvt_pk_bf16(o0[0], o0[1]); w[bj].y = cvt_pk_bf16(o0[2], o0[3]); w[bj].z = cvt_pk_bf16(o1[0], o1[1]); w[bj].w = cvt_pk_bf16(o1[2], o1[3]); }
;                 store_pair_lines(O, D, row, fr, col0, w[0], w[1]);
;                 if (ssout) { sq += __shfl_xor(sq, 16); sq += __shfl_xor(sq, 32); if (fq == 0) unsafeAtomicAdd(ssout + row, sq); } }
	s_nop 0
	v_mov_b64_e32 v[82:83], v[232:233]
	v_mov_b64_e32 v[84:85], v[234:235]
	v_mov_b64_e32 v[86:87], v[236:237]
	v_mov_b64_e32 v[88:89], v[238:239]
	v_pk_add_f32 v[84:85], v[78:79], v[84:85]
	v_pk_add_f32 v[82:83], v[76:77], v[82:83]
	v_pk_add_f32 v[88:89], v[74:75], v[88:89]
	v_pk_add_f32 v[86:87], v[72:73], v[86:87]
	v_cvt_pk_bf16_f32 v92, v82, v83
	v_cvt_pk_bf16_f32 v93, v84, v85
	v_mul_f32_e32 v83, v83, v83
	v_cvt_pk_bf16_f32 v94, v86, v87
	v_cvt_pk_bf16_f32 v95, v88, v89
	v_mov_b64_e32 v[72:73], v[240:241]
	v_mov_b64_e32 v[74:75], v[242:243]
	v_mov_b64_e32 v[76:77], v[244:245]
	v_mov_b64_e32 v[78:79], v[246:247]
	s_nop 1
	v_add_u32_e32 v188, 0xa0, v146
	v_ashrrev_i32_e32 v189, 31, v188
	v_lshlrev_b64 v[190:191], 11, v[188:189]
	v_lshl_add_u64 v[190:191], v[190:191], 0, v[148:149]
	v_lshlrev_b64 v[190:191], 2, v[190:191]
	v_lshl_add_u64 v[192:193], s[16:17], 0, v[190:191]
	v_lshl_add_u64 v[190:191], s[18:19], 0, v[190:191]
	v_lshl_add_u64 v[190:191], v[190:191], 0, s[38:39]
	v_cmp_gt_i32_e32 vcc, s83, v146
	s_nop 1
	v_cndmask_b32_e32 v195, v191, v193, vcc
	v_cndmask_b32_e32 v194, v190, v192, vcc
	global_load_dwordx4 v[232:235], v[194:195], off
	global_load_dwordx4 v[236:239], v[194:195], off offset:16
	global_load_dwordx4 v[240:243], v[194:195], off offset:32
	global_load_dwordx4 v[244:247], v[194:195], off offset:48
	v_mul_f32_e32 v85, v85, v85
	v_mul_f32_e32 v87, v87, v87
	v_fmac_f32_e32 v83, v82, v82
	v_fmac_f32_e32 v85, v84, v84
	v_mul_f32_e32 v89, v89, v89
	v_fmac_f32_e32 v87, v86, v86
	v_add_f32_e32 v82, v83, v85
	v_fmac_f32_e32 v89, v88, v88
	v_add_f32_e32 v82, v87, v82
	v_add_f32_e32 v82, v89, v82
	v_sub_u32_e32 v90, v80, v150
	v_add_u32_e32 v90, v90, v152
	v_ashrrev_i32_e32 v91, 31, v90
	v_lshlrev_b64 v[90:91], 12, v[90:91]
	v_lshl_add_u64 v[90:91], s[10:11], 0, v[90:91]
	v_lshl_add_u64 v[90:91], v[120:121], 1, v[90:91]
	v_mov_b32_dpp v96, v92 row_ror:8 row_mask:0xf bank_mask:0xf
	v_mov_b32_dpp v97, v93 row_ror:8 row_mask:0xf bank_mask:0xf
	v_mov_b32_dpp v98, v94 row_ror:8 row_mask:0xf bank_mask:0xf
	v_mov_b32_dpp v99, v95 row_ror:8 row_mask:0xf bank_mask:0xf
	v_pk_add_f32 v[70:71], v[70:71], v[74:75]
	v_pk_add_f32 v[72:73], v[68:69], v[72:73]
	v_pk_add_f32 v[74:75], v[66:67], v[78:79]
	v_pk_add_f32 v[64:65], v[64:65], v[76:77]
	v_cvt_pk_bf16_f32 v66, v72, v73
	v_mul_f32_e32 v73, v73, v73
	v_mul_f32_e32 v76, v71, v71
	v_cvt_pk_bf16_f32 v67, v70, v71
	v_cvt_pk_bf16_f32 v68, v64, v65
	v_mul_f32_e32 v65, v65, v65
	v_fmac_f32_e32 v73, v72, v72
	v_fmac_f32_e32 v76, v70, v70
	v_cvt_pk_bf16_f32 v69, v74, v75
	v_mul_f32_e32 v75, v75, v75
	v_fmac_f32_e32 v65, v64, v64
	v_add_f32_e32 v64, v73, v76
	v_fmac_f32_e32 v75, v74, v74
	v_add_f32_e32 v64, v65, v64
	v_add_f32_e32 v64, v75, v64
	v_add_f32_e32 v64, v82, v64
	ds_bpermute_b32 v65, v122, v64
	v_mov_b32_dpp v100, v66 row_ror:8 row_mask:0xf bank_mask:0xf
	v_mov_b32_dpp v101, v67 row_ror:8 row_mask:0xf bank_mask:0xf
	v_mov_b32_dpp v102, v68 row_ror:8 row_mask:0xf bank_mask:0xf
	v_mov_b32_dpp v103, v69 row_ror:8 row_mask:0xf bank_mask:0xf
	s_waitcnt lgkmcnt(0)
	v_add_f32_e32 v64, v64, v65
	ds_bpermute_b32 v65, v114, v64
	v_cndmask_b32_e64 v71, v101, v93, s[6:7]
	v_cndmask_b32_e64 v73, v103, v95, s[6:7]
	v_cndmask_b32_e64 v70, v100, v92, s[6:7]
	v_cndmask_b32_e64 v72, v102, v94, s[6:7]
	global_store_dwordx4 v[90:91], v[70:73], off
	v_cndmask_b32_e64 v67, v67, v97, s[6:7]
	v_cndmask_b32_e64 v69, v69, v99, s[6:7]
	v_add_co_u32_e32 v70, vcc, s69, v90
	v_cndmask_b32_e64 v66, v66, v96, s[6:7]
	v_cndmask_b32_e64 v68, v68, v98, s[6:7]
	v_addc_co_u32_e32 v71, vcc, 0, v91, vcc
	global_store_dwordx4 v[70:71], v[66:69], off
	s_and_saveexec_b64 s[50:51], s[8:9]
	s_cbranch_execz .LBB0_622
	s_waitcnt lgkmcnt(0)
	v_add_f32_e32 v66, v64, v65
	v_lshl_add_u64 v[64:65], v[80:81], 2, s[12:13]
	global_atomic_add_f32 v[64:65], v66, off
.LBB0_622:
	s_or_b64 exec, exec, s[50:51]
	v_add_u32_e32 v64, 0x80, v146
	s_waitcnt lgkmcnt(0)
	v_ashrrev_i32_e32 v65, 31, v64
	v_lshlrev_b64 v[66:67], 11, v[64:65]
	v_lshl_add_u64 v[66:67], v[66:67], 0, v[148:149]
	v_lshlrev_b64 v[66:67], 2, v[66:67]
	v_lshl_add_u64 v[68:69], s[16:17], 0, v[66:67]
	v_lshl_add_u64 v[66:67], s[18:19], 0, v[66:67]
	v_lshl_add_u64 v[66:67], v[66:67], 0, s[38:39]
	v_cmp_gt_i32_e32 vcc, s81, v146
	v_mov_b32_e32 v84, 0
	v_mov_b32_e32 v85, 0
	v_cndmask_b32_e32 v75, v67, v69, vcc
	v_cndmask_b32_e32 v74, v66, v68, vcc
	s_waitcnt vmcnt(14)
; __device__ __forceinline__ unsigned cvt_pk_bf16(float lo, float hi) { unsigned r; asm volatile("v_cvt_pk_bf16_f32 %0, %1, %2" : "=v"(r) : "v"(lo), "v"(hi)); return r; }
; __device__ __forceinline__ float bflo(unsigned w) { return __uint_as_float(w << 16); }
; __device__ __forceinline__ void store_pair_lines(bf16_t* O, int ldc, int row, int fr, int col0, u32x4 wA, u32x4 wB) {
;     const u32x4 sA = {dpp_ror8(wA.x), dpp_ror8(wA.y), dpp_ror8(wA.z), dpp_ror8(wA.w)}, sB = {dpp_ror8(wB.x), dpp_ror8(wB.y), dpp_ror8(wB.z), dpp_ror8(wB.w)};
;     const bool lo = fr < 8;
;     const u32x4 o1 = lo ? wA : sB, o2 = lo ? sA : wB;
;     const int r1 = row - fr + (fr & 7), cb = col0 + (lo ? 0 : 8);
;     *(u32x4*)(O + (size_t)r1 * ldc + cb) = o1;
;     *(u32x4*)(O + (size_t)(r1 + 8) * ldc + cb) = o2;
;     __device__ __forceinline__ void operator()(const f32x4 (&acc)[2][2][4][2], const Unit& u, int wr, int wc, int fr, int fq) const {
;     ...
;             for (int m = 0; m < 4; ++m) { const int row = row0 + ai * HALF + m * 16; const size_t off = (size_t)row * D + col0; float sq = 0.f; u32x4 w[2];
;                 const float sc = rsin ? __builtin_amdgcn_rcpf(rsin[row] * (1.f / D) + EPS) : 1.0f;
;                 u32x4 rr[2]; if (R) load_pair_lines(R, D, row, fr, col0, rr[0], rr[1]);
; #pragma unroll
;                 for (int bj = 0; bj < 2; ++bj) { f32x4 r0, r1;
;                     if (R) { const u32x4 rw = rr[bj]; r0 = (f32x4){bflo(rw.x), bfhi(rw.x), bflo(rw.y), bfhi(rw.y)}; r1 = (f32x4){bflo(rw.z), bfhi(rw.z), bflo(rw.w), bfhi(rw.w)}; }
;                     else { const float* rp = (row < 8192 ? src_p + off : src_s + (off - (size_t)8192 * D)) + 8 * bj; r0 = *(const f32x4*)rp; r1 = *(const f32x4*)(rp + 4); }
;                     const f32x4 o0 = r0 + acc[ai][bj][m][0] * sc, o1 = r1 + acc[ai][bj][m][1] * sc;
;                     sq += (o0[0] * o0[0] + o0[1] * o0[1]) + (o0[2] * o0[2] + o0[3] * o0[3]) + (o1[0] * o1[0] + o1[1] * o1[1]) + (o1[2] * o1[2] + o1[3] * o1[3]);
;                     w[bj].x = cvt_pk_bf16(o0[0], o0[1]); w[bj].y = cvt_pk_bf16(o0[2], o0[3]); w[bj].z = cvt_pk_bf16(o1[0], o1[1]); w[bj].w = cvt_pk_bf16(o1[2], o1[3]); }
;                 store_pair_lines(O, D, row, fr, col0, w[0], w[1]);
;                 if (ssout) { sq += __shfl_xor(sq, 16); sq += __shfl_xor(sq, 32); if (fq == 0) unsafeAtomicAdd(ssout + row, sq); } }
	s_nop 0
	v_mov_b64_e32 v[66:67], v[196:197]
	v_mov_b64_e32 v[68:69], v[198:199]
	v_mov_b64_e32 v[70:71], v[204:205]
	v_mov_b64_e32 v[72:73], v[206:207]
	v_pk_add_f32 v[68:69], v[62:63], v[68:69]
	v_pk_add_f32 v[66:67], v[60:61], v[66:67]
	v_pk_add_f32 v[72:73], v[58:59], v[72:73]
	v_pk_add_f32 v[70:71], v[56:57], v[70:71]
	v_cvt_pk_bf16_f32 v76, v66, v67
	v_cvt_pk_bf16_f32 v77, v68, v69
	v_mul_f32_e32 v67, v67, v67
	v_cvt_pk_bf16_f32 v78, v70, v71
	v_cvt_pk_bf16_f32 v79, v72, v73
	v_mov_b64_e32 v[56:57], v[208:209]
	v_mov_b64_e32 v[58:59], v[210:211]
	v_mov_b64_e32 v[60:61], v[212:213]
	v_mov_b64_e32 v[62:63], v[214:215]
	s_nop 1
	v_add_u32_e32 v188, 0xb0, v146
	v_ashrrev_i32_e32 v189, 31, v188
	v_lshlrev_b64 v[190:191], 11, v[188:189]
	v_lshl_add_u64 v[190:191], v[190:191], 0, v[148:149]
	v_lshlrev_b64 v[190:191], 2, v[190:191]
	v_lshl_add_u64 v[192:193], s[16:17], 0, v[190:191]
	v_lshl_add_u64 v[190:191], s[18:19], 0, v[190:191]
	v_lshl_add_u64 v[190:191], v[190:191], 0, s[38:39]
	v_cmp_gt_i32_e32 vcc, s84, v146
	s_nop 1
	v_cndmask_b32_e32 v195, v191, v193, vcc
	v_cndmask_b32_e32 v194, v190, v192, vcc
	global_load_dwordx4 v[196:199], v[194:195], off
	global_load_dwordx4 v[204:207], v[194:195], off offset:16
	global_load_dwordx4 v[208:211], v[194:195], off offset:32
	global_load_dwordx4 v[212:215], v[194:195], off offset:48
	v_mul_f32_e32 v69, v69, v69
	v_mul_f32_e32 v71, v71, v71
	v_fmac_f32_e32 v67, v66, v66
	v_fmac_f32_e32 v69, v68, v68
	v_mul_f32_e32 v73, v73, v73
	v_fmac_f32_e32 v71, v70, v70
	v_add_f32_e32 v66, v67, v69
	v_fmac_f32_e32 v73, v72, v72
	v_add_f32_e32 v66, v71, v66
	v_add_f32_e32 v66, v73, v66
	v_sub_u32_e32 v74, v64, v150
	v_add_u32_e32 v74, v74, v152
	v_ashrrev_i32_e32 v75, 31, v74
	v_lshlrev_b64 v[74:75], 12, v[74:75]
	v_lshl_add_u64 v[74:75], s[10:11], 0, v[74:75]
	v_lshl_add_u64 v[74:75], v[120:121], 1, v[74:75]
	v_mov_b32_dpp v80, v76 row_ror:8 row_mask:0xf bank_mask:0xf
	v_mov_b32_dpp v81, v77 row_ror:8 row_mask:0xf bank_mask:0xf
	v_mov_b32_dpp v82, v78 row_ror:8 row_mask:0xf bank_mask:0xf
	v_mov_b32_dpp v83, v79 row_ror:8 row_mask:0xf bank_mask:0xf
	v_pk_add_f32 v[54:55], v[54:55], v[58:59]
	v_pk_add_f32 v[56:57], v[52:53], v[56:57]
	v_pk_add_f32 v[58:59], v[50:51], v[62:63]
	v_pk_add_f32 v[48:49], v[48:49], v[60:61]
	v_cvt_pk_bf16_f32 v50, v56, v57
	v_mul_f32_e32 v57, v57, v57
	v_mul_f32_e32 v60, v55, v55
	v_cvt_pk_bf16_f32 v51, v54, v55
	v_cvt_pk_bf16_f32 v52, v48, v49
	v_mul_f32_e32 v49, v49, v49
	v_fmac_f32_e32 v57, v56, v56
	v_fmac_f32_e32 v60, v54, v54
	v_cvt_pk_bf16_f32 v53, v58, v59
	v_mul_f32_e32 v59, v59, v59
	v_fmac_f32_e32 v49, v48, v48
	v_add_f32_e32 v48, v57, v60
	v_fmac_f32_e32 v59, v58, v58
	v_add_f32_e32 v48, v49, v48
	v_add_f32_e32 v48, v59, v48
	v_add_f32_e32 v48, v66, v48
	ds_bpermute_b32 v49, v122, v48
	v_mov_b32_dpp v84, v50 row_ror:8 row_mask:0xf bank_mask:0xf
	v_mov_b32_dpp v85, v51 row_ror:8 row_mask:0xf bank_mask:0xf
	v_mov_b32_dpp v86, v52 row_ror:8 row_mask:0xf bank_mask:0xf
	v_mov_b32_dpp v87, v53 row_ror:8 row_mask:0xf bank_mask:0xf
	s_waitcnt lgkmcnt(0)
	v_add_f32_e32 v48, v48, v49
	ds_bpermute_b32 v49, v114, v48
	v_cndmask_b32_e64 v55, v85, v77, s[6:7]
	v_cndmask_b32_e64 v57, v87, v79, s[6:7]
	v_cndmask_b32_e64 v54, v84, v76, s[6:7]
	v_cndmask_b32_e64 v56, v86, v78, s[6:7]
	global_store_dwordx4 v[74:75], v[54:57], off
	v_cndmask_b32_e64 v51, v51, v81, s[6:7]
	v_cndmask_b32_e64 v53, v53, v83, s[6:7]
	v_add_co_u32_e32 v54, vcc, s69, v74
	v_cndmask_b32_e64 v50, v50, v80, s[6:7]
	v_cndmask_b32_e64 v52, v52, v82, s[6:7]
	v_addc_co_u32_e32 v55, vcc, 0, v75, vcc
	global_store_dwordx4 v[54:55], v[50:53], off
	s_and_saveexec_b64 s[50:51], s[8:9]
	s_cbranch_execz .LBB0_624
	s_waitcnt lgkmcnt(0)
	v_add_f32_e32 v50, v48, v49
	v_lshl_add_u64 v[48:49], v[64:65], 2, s[12:13]
	global_atomic_add_f32 v[48:49], v50, off
.LBB0_624:
	s_or_b64 exec, exec, s[50:51]
	v_add_u32_e32 v48, 0x90, v146
	s_waitcnt lgkmcnt(0)
	v_ashrrev_i32_e32 v49, 31, v48
	v_lshlrev_b64 v[50:51], 11, v[48:49]
	v_lshl_add_u64 v[50:51], v[50:51], 0, v[148:149]
	v_lshlrev_b64 v[50:51], 2, v[50:51]
	v_lshl_add_u64 v[52:53], s[16:17], 0, v[50:51]
	v_lshl_add_u64 v[50:51], s[18:19], 0, v[50:51]
	v_lshl_add_u64 v[50:51], v[50:51], 0, s[38:39]
	v_cmp_gt_i32_e32 vcc, s82, v146
	v_mov_b32_e32 v68, 0
	v_mov_b32_e32 v69, 0
	v_cndmask_b32_e32 v59, v51, v53, vcc
	v_cndmask_b32_e32 v58, v50, v52, vcc
	s_waitcnt vmcnt(14)
	s_nop 0
	v_mov_b64_e32 v[50:51], v[216:217]
	v_mov_b64_e32 v[52:53], v[218:219]
	v_mov_b64_e32 v[54:55], v[220:221]
	v_mov_b64_e32 v[56:57], v[222:223]
	v_pk_add_f32 v[52:53], v[46:47], v[52:53]
	v_pk_add_f32 v[50:51], v[44:45], v[50:51]
	v_pk_add_f32 v[56:57], v[42:43], v[56:57]
	v_pk_add_f32 v[54:55], v[40:41], v[54:55]
	v_cvt_pk_bf16_f32 v60, v50, v51
	v_cvt_pk_bf16_f32 v61, v52, v53
	v_mul_f32_e32 v51, v51, v51
	v_cvt_pk_bf16_f32 v62, v54, v55
	v_cvt_pk_bf16_f32 v63, v56, v57
	v_mov_b64_e32 v[40:41], v[224:225]
	v_mov_b64_e32 v[42:43], v[226:227]
	v_mov_b64_e32 v[44:45], v[228:229]
	v_mov_b64_e32 v[46:47], v[230:231]
	s_nop 1
	v_mul_f32_e32 v53, v53, v53
	v_mul_f32_e32 v55, v55, v55
	v_fmac_f32_e32 v51, v50, v50
	v_fmac_f32_e32 v53, v52, v52
	v_mul_f32_e32 v57, v57, v57
	v_fmac_f32_e32 v55, v54, v54
	v_add_f32_e32 v50, v51, v53
	v_fmac_f32_e32 v57, v56, v56
	v_add_f32_e32 v50, v55, v50
	v_add_f32_e32 v50, v57, v50
	v_sub_u32_e32 v58, v48, v150
	v_add_u32_e32 v58, v58, v152
	v_ashrrev_i32_e32 v59, 31, v58
	v_lshlrev_b64 v[58:59], 12, v[58:59]
	v_lshl_add_u64 v[58:59], s[10:11], 0, v[58:59]
	v_lshl_add_u64 v[58:59], v[120:121], 1, v[58:59]
	v_mov_b32_dpp v64, v60 row_ror:8 row_mask:0xf bank_mask:0xf
	v_mov_b32_dpp v65, v61 row_ror:8 row_mask:0xf bank_mask:0xf
	v_mov_b32_dpp v66, v62 row_ror:8 row_mask:0xf bank_mask:0xf
	v_mov_b32_dpp v67, v63 row_ror:8 row_mask:0xf bank_mask:0xf
	v_pk_add_f32 v[38:39], v[38:39], v[42:43]
	v_pk_add_f32 v[40:41], v[36:37], v[40:41]
	v_pk_add_f32 v[42:43], v[34:35], v[46:47]
	v_pk_add_f32 v[32:33], v[32:33], v[44:45]
	v_cvt_pk_bf16_f32 v34, v40, v41
	v_mul_f32_e32 v41, v41, v41
	v_mul_f32_e32 v44, v39, v39
	v_cvt_pk_bf16_f32 v35, v38, v39
	v_cvt_pk_bf16_f32 v36, v32, v33
	v_mul_f32_e32 v33, v33, v33
	v_fmac_f32_e32 v41, v40, v40
	v_fmac_f32_e32 v44, v38, v38
	v_cvt_pk_bf16_f32 v37, v42, v43
	v_mul_f32_e32 v43, v43, v43
	v_fmac_f32_e32 v33, v32, v32
	v_add_f32_e32 v32, v41, v44
	v_fmac_f32_e32 v43, v42, v42
	v_add_f32_e32 v32, v33, v32
	v_add_f32_e32 v32, v43, v32
	v_add_f32_e32 v32, v50, v32
	ds_bpermute_b32 v33, v122, v32
	v_mov_b32_dpp v68, v34 row_ror:8 row_mask:0xf bank_mask:0xf
	v_mov_b32_dpp v69, v35 row_ror:8 row_mask:0xf bank_mask:0xf
	v_mov_b32_dpp v70, v36 row_ror:8 row_mask:0xf bank_mask:0xf
	v_mov_b32_dpp v71, v37 row_ror:8 row_mask:0xf bank_mask:0xf
	s_waitcnt lgkmcnt(0)
; __device__ __forceinline__ unsigned cvt_pk_bf16(float lo, float hi) { unsigned r; asm volatile("v_cvt_pk_bf16_f32 %0, %1, %2" : "=v"(r) : "v"(lo), "v"(hi)); return r; }
; __device__ __forceinline__ float bflo(unsigned w) { return __uint_as_float(w << 16); }
; __device__ __forceinline__ void store_pair_lines(bf16_t* O, int ldc, int row, int fr, int col0, u32x4 wA, u32x4 wB) {
;     const u32x4 sA = {dpp_ror8(wA.x), dpp_ror8(wA.y), dpp_ror8(wA.z), dpp_ror8(wA.w)}, sB = {dpp_ror8(wB.x), dpp_ror8(wB.y), dpp_ror8(wB.z), dpp_ror8(wB.w)};
;     const bool lo = fr < 8;
;     const u32x4 o1 = lo ? wA : sB, o2 = lo ? sA : wB;
;     const int r1 = row - fr + (fr & 7), cb = col0 + (lo ? 0 : 8);
;     *(u32x4*)(O + (size_t)r1 * ldc + cb) = o1;
;     *(u32x4*)(O + (size_t)(r1 + 8) * ldc + cb) = o2;
;     __device__ __forceinline__ void operator()(const f32x4 (&acc)[2][2][4][2], const Unit& u, int wr, int wc, int fr, int fq) const {
;     ...
;             for (int m = 0; m < 4; ++m) { const int row = row0 + ai * HALF + m * 16; const size_t off = (size_t)row * D + col0; float sq = 0.f; u32x4 w[2];
;                 const float sc = rsin ? __builtin_amdgcn_rcpf(rsin[row] * (1.f / D) + EPS) : 1.0f;
;                 u32x4 rr[2]; if (R) load_pair_lines(R, D, row, fr, col0, rr[0], rr[1]);
; #pragma unroll
;                 for (int bj = 0; bj < 2; ++bj) { f32x4 r0, r1;
;                     if (R) { const u32x4 rw = rr[bj]; r0 = (f32x4){bflo(rw.x), bfhi(rw.x), bflo(rw.y), bfhi(rw.y)}; r1 = (f32x4){bflo(rw.z), bfhi(rw.z), bflo(rw.w), bfhi(rw.w)}; }
;                     else { const float* rp = (row < 8192 ? src_p + off : src_s + (off - (size_t)8192 * D)) + 8 * bj; r0 = *(const f32x4*)rp; r1 = *(const f32x4*)(rp + 4); }
;                     const f32x4 o0 = r0 + acc[ai][bj][m][0] * sc, o1 = r1 + acc[ai][bj][m][1] * sc;
;                     sq += (o0[0] * o0[0] + o0[1] * o0[1]) + (o0[2] * o0[2] + o0[3] * o0[3]) + (o1[0] * o1[0] + o1[1] * o1[1]) + (o1[2] * o1[2] + o1[3] * o1[3]);
;                     w[bj].x = cvt_pk_bf16(o0[0], o0[1]); w[bj].y = cvt_pk_bf16(o0[2], o0[3]); w[bj].z = cvt_pk_bf16(o1[0], o1[1]); w[bj].w = cvt_pk_bf16(o1[2], o1[3]); }
;                 store_pair_lines(O, D, row, fr, col0, w[0], w[1]);
;                 if (ssout) { sq += __shfl_xor(sq, 16); sq += __shfl_xor(sq, 32); if (fq == 0) unsafeAtomicAdd(ssout + row, sq); } }
	v_add_f32_e32 v32, v32, v33
	ds_bpermute_b32 v33, v114, v32
	v_cndmask_b32_e64 v39, v69, v61, s[6:7]
	v_cndmask_b32_e64 v41, v71, v63, s[6:7]
	v_cndmask_b32_e64 v38, v68, v60, s[6:7]
	v_cndmask_b32_e64 v40, v70, v62, s[6:7]
	global_store_dwordx4 v[58:59], v[38:41], off
	v_cndmask_b32_e64 v35, v35, v65, s[6:7]
	v_cndmask_b32_e64 v37, v37, v67, s[6:7]
	v_add_co_u32_e32 v38, vcc, s69, v58
	v_cndmask_b32_e64 v34, v34, v64, s[6:7]
	v_cndmask_b32_e64 v36, v36, v66, s[6:7]
	v_addc_co_u32_e32 v39, vcc, 0, v59, vcc
	global_store_dwordx4 v[38:39], v[34:37], off
	s_and_saveexec_b64 s[50:51], s[8:9]
	s_cbranch_execz .LBB0_626
	s_waitcnt lgkmcnt(0)
	v_add_f32_e32 v34, v32, v33
	v_lshl_add_u64 v[32:33], v[48:49], 2, s[12:13]
	global_atomic_add_f32 v[32:33], v34, off
.LBB0_626:
	s_or_b64 exec, exec, s[50:51]
	v_add_u32_e32 v32, 0xa0, v146
	s_waitcnt lgkmcnt(0)
	v_ashrrev_i32_e32 v33, 31, v32
	v_lshlrev_b64 v[34:35], 11, v[32:33]
	v_lshl_add_u64 v[34:35], v[34:35], 0, v[148:149]
	v_lshlrev_b64 v[34:35], 2, v[34:35]
	v_lshl_add_u64 v[36:37], s[16:17], 0, v[34:35]
	v_lshl_add_u64 v[34:35], s[18:19], 0, v[34:35]
	v_lshl_add_u64 v[34:35], v[34:35], 0, s[38:39]
	v_cmp_gt_i32_e32 vcc, s83, v146
	v_mov_b32_e32 v52, 0
	v_mov_b32_e32 v53, 0
	v_cndmask_b32_e32 v43, v35, v37, vcc
	v_cndmask_b32_e32 v42, v34, v36, vcc
	s_waitcnt vmcnt(10)
	s_nop 0
	v_mov_b64_e32 v[34:35], v[232:233]
	v_mov_b64_e32 v[36:37], v[234:235]
	v_mov_b64_e32 v[38:39], v[236:237]
	v_mov_b64_e32 v[40:41], v[238:239]
	v_pk_add_f32 v[36:37], v[30:31], v[36:37]
	v_pk_add_f32 v[34:35], v[28:29], v[34:35]
	v_pk_add_f32 v[40:41], v[26:27], v[40:41]
	v_pk_add_f32 v[38:39], v[24:25], v[38:39]
	v_cvt_pk_bf16_f32 v44, v34, v35
	v_cvt_pk_bf16_f32 v45, v36, v37
	v_mul_f32_e32 v35, v35, v35
	v_cvt_pk_bf16_f32 v46, v38, v39
	v_cvt_pk_bf16_f32 v47, v40, v41
	v_mov_b64_e32 v[24:25], v[240:241]
	v_mov_b64_e32 v[26:27], v[242:243]
	v_mov_b64_e32 v[28:29], v[244:245]
	v_mov_b64_e32 v[30:31], v[246:247]
	s_nop 1
	v_mul_f32_e32 v37, v37, v37
	v_mul_f32_e32 v39, v39, v39
	v_fmac_f32_e32 v35, v34, v34
	v_fmac_f32_e32 v37, v36, v36
	v_mul_f32_e32 v41, v41, v41
	v_fmac_f32_e32 v39, v38, v38
	v_add_f32_e32 v34, v35, v37
	v_fmac_f32_e32 v41, v40, v40
	v_add_f32_e32 v34, v39, v34
	v_add_f32_e32 v34, v41, v34
	v_sub_u32_e32 v42, v32, v150
	v_add_u32_e32 v42, v42, v152
	v_ashrrev_i32_e32 v43, 31, v42
	v_lshlrev_b64 v[42:43], 12, v[42:43]
	v_lshl_add_u64 v[42:43], s[10:11], 0, v[42:43]
	v_lshl_add_u64 v[42:43], v[120:121], 1, v[42:43]
	v_mov_b32_dpp v48, v44 row_ror:8 row_mask:0xf bank_mask:0xf
	v_mov_b32_dpp v49, v45 row_ror:8 row_mask:0xf bank_mask:0xf
	v_mov_b32_dpp v50, v46 row_ror:8 row_mask:0xf bank_mask:0xf
	v_mov_b32_dpp v51, v47 row_ror:8 row_mask:0xf bank_mask:0xf
	v_pk_add_f32 v[22:23], v[22:23], v[26:27]
	v_pk_add_f32 v[24:25], v[20:21], v[24:25]
	v_pk_add_f32 v[26:27], v[18:19], v[30:31]
	v_pk_add_f32 v[16:17], v[16:17], v[28:29]
	v_cvt_pk_bf16_f32 v18, v24, v25
	v_mul_f32_e32 v25, v25, v25
	v_mul_f32_e32 v28, v23, v23
	v_cvt_pk_bf16_f32 v19, v22, v23
	v_cvt_pk_bf16_f32 v20, v16, v17
	v_mul_f32_e32 v17, v17, v17
	v_fmac_f32_e32 v25, v24, v24
	v_fmac_f32_e32 v28, v22, v22
	v_cvt_pk_bf16_f32 v21, v26, v27
	v_mul_f32_e32 v27, v27, v27
	v_fmac_f32_e32 v17, v16, v16
	v_add_f32_e32 v16, v25, v28
	v_fmac_f32_e32 v27, v26, v26
	v_add_f32_e32 v16, v17, v16
	v_add_f32_e32 v16, v27, v16
	v_add_f32_e32 v16, v34, v16
	ds_bpermute_b32 v17, v122, v16
	v_mov_b32_dpp v52, v18 row_ror:8 row_mask:0xf bank_mask:0xf
	v_mov_b32_dpp v53, v19 row_ror:8 row_mask:0xf bank_mask:0xf
	v_mov_b32_dpp v54, v20 row_ror:8 row_mask:0xf bank_mask:0xf
	v_mov_b32_dpp v55, v21 row_ror:8 row_mask:0xf bank_mask:0xf
	s_waitcnt lgkmcnt(0)
	v_add_f32_e32 v16, v16, v17
	ds_bpermute_b32 v17, v114, v16
	v_cndmask_b32_e64 v23, v53, v45, s[6:7]
	v_cndmask_b32_e64 v25, v55, v47, s[6:7]
	v_cndmask_b32_e64 v22, v52, v44, s[6:7]
	v_cndmask_b32_e64 v24, v54, v46, s[6:7]
	global_store_dwordx4 v[42:43], v[22:25], off
	v_cndmask_b32_e64 v19, v19, v49, s[6:7]
	v_cndmask_b32_e64 v21, v21, v51, s[6:7]
	v_add_co_u32_e32 v22, vcc, s69, v42
	v_cndmask_b32_e64 v18, v18, v48, s[6:7]
	v_cndmask_b32_e64 v20, v20, v50, s[6:7]
	v_addc_co_u32_e32 v23, vcc, 0, v43, vcc
	global_store_dwordx4 v[22:23], v[18:21], off
	s_and_saveexec_b64 s[50:51], s[8:9]
	s_cbranch_execz .LBB0_628
	s_waitcnt lgkmcnt(0)
	v_add_f32_e32 v18, v16, v17
	v_lshl_add_u64 v[16:17], v[32:33], 2, s[12:13]
	global_atomic_add_f32 v[16:17], v18, off
; __device__ __forceinline__ unsigned cvt_pk_bf16(float lo, float hi) { unsigned r; asm volatile("v_cvt_pk_bf16_f32 %0, %1, %2" : "=v"(r) : "v"(lo), "v"(hi)); return r; }
; __device__ __forceinline__ float bflo(unsigned w) { return __uint_as_float(w << 16); }
; __device__ __forceinline__ void store_pair_lines(bf16_t* O, int ldc, int row, int fr, int col0, u32x4 wA, u32x4 wB) {
;     const u32x4 sA = {dpp_ror8(wA.x), dpp_ror8(wA.y), dpp_ror8(wA.z), dpp_ror8(wA.w)}, sB = {dpp_ror8(wB.x), dpp_ror8(wB.y), dpp_ror8(wB.z), dpp_ror8(wB.w)};
;     const bool lo = fr < 8;
;     const u32x4 o1 = lo ? wA : sB, o2 = lo ? sA : wB;
;     const int r1 = row - fr + (fr & 7), cb = col0 + (lo ? 0 : 8);
;     *(u32x4*)(O + (size_t)r1 * ldc + cb) = o1;
;     *(u32x4*)(O + (size_t)(r1 + 8) * ldc + cb) = o2;
;     __device__ __forceinline__ void operator()(const f32x4 (&acc)[2][2][4][2], const Unit& u, int wr, int wc, int fr, int fq) const {
;     ...
;             for (int m = 0; m < 4; ++m) { const int row = row0 + ai * HALF + m * 16; const size_t off = (size_t)row * D + col0; float sq = 0.f; u32x4 w[2];
;                 const float sc = rsin ? __builtin_amdgcn_rcpf(rsin[row] * (1.f / D) + EPS) : 1.0f;
;                 u32x4 rr[2]; if (R) load_pair_lines(R, D, row, fr, col0, rr[0], rr[1]);
; #pragma unroll
;                 for (int bj = 0; bj < 2; ++bj) { f32x4 r0, r1;
;                     if (R) { const u32x4 rw = rr[bj]; r0 = (f32x4){bflo(rw.x), bfhi(rw.x), bflo(rw.y), bfhi(rw.y)}; r1 = (f32x4){bflo(rw.z), bfhi(rw.z), bflo(rw.w), bfhi(rw.w)}; }
;                     else { const float* rp = (row < 8192 ? src_p + off : src_s + (off - (size_t)8192 * D)) + 8 * bj; r0 = *(const f32x4*)rp; r1 = *(const f32x4*)(rp + 4); }
;                     const f32x4 o0 = r0 + acc[ai][bj][m][0] * sc, o1 = r1 + acc[ai][bj][m][1] * sc;
;                     sq += (o0[0] * o0[0] + o0[1] * o0[1]) + (o0[2] * o0[2] + o0[3] * o0[3]) + (o1[0] * o1[0] + o1[1] * o1[1]) + (o1[2] * o1[2] + o1[3] * o1[3]);
;                     w[bj].x = cvt_pk_bf16(o0[0], o0[1]); w[bj].y = cvt_pk_bf16(o0[2], o0[3]); w[bj].z = cvt_pk_bf16(o1[0], o1[1]); w[bj].w = cvt_pk_bf16(o1[2], o1[3]); }
;                 store_pair_lines(O, D, row, fr, col0, w[0], w[1]);
;                 if (ssout) { sq += __shfl_xor(sq, 16); sq += __shfl_xor(sq, 32); if (fq == 0) unsafeAtomicAdd(ssout + row, sq); } }
.LBB0_628:
	s_or_b64 exec, exec, s[50:51]
	v_add_u32_e32 v16, 0xb0, v146
	s_waitcnt lgkmcnt(0)
	v_ashrrev_i32_e32 v17, 31, v16
	v_lshlrev_b64 v[18:19], 11, v[16:17]
	v_lshl_add_u64 v[18:19], v[18:19], 0, v[148:149]
	v_lshlrev_b64 v[18:19], 2, v[18:19]
	v_lshl_add_u64 v[20:21], s[16:17], 0, v[18:19]
	v_lshl_add_u64 v[18:19], s[18:19], 0, v[18:19]
	v_lshl_add_u64 v[18:19], v[18:19], 0, s[38:39]
	v_cmp_gt_i32_e32 vcc, s84, v146
	v_mov_b32_e32 v36, 0
	v_mov_b32_e32 v37, 0
	v_cndmask_b32_e32 v27, v19, v21, vcc
	v_cndmask_b32_e32 v26, v18, v20, vcc
	s_waitcnt vmcnt(6)
	s_nop 0
	v_mov_b64_e32 v[18:19], v[196:197]
	v_mov_b64_e32 v[20:21], v[198:199]
	v_mov_b64_e32 v[22:23], v[204:205]
	v_mov_b64_e32 v[24:25], v[206:207]
	v_pk_add_f32 v[20:21], v[14:15], v[20:21]
	v_pk_add_f32 v[18:19], v[12:13], v[18:19]
	v_pk_add_f32 v[24:25], v[10:11], v[24:25]
	v_pk_add_f32 v[22:23], v[8:9], v[22:23]
	v_cvt_pk_bf16_f32 v28, v18, v19
	v_cvt_pk_bf16_f32 v29, v20, v21
	v_mul_f32_e32 v19, v19, v19
	v_cvt_pk_bf16_f32 v30, v22, v23
	v_cvt_pk_bf16_f32 v31, v24, v25
	v_mov_b64_e32 v[8:9], v[208:209]
	v_mov_b64_e32 v[10:11], v[210:211]
	v_mov_b64_e32 v[12:13], v[212:213]
	v_mov_b64_e32 v[14:15], v[214:215]
	s_nop 1
	v_mul_f32_e32 v21, v21, v21
	v_mul_f32_e32 v23, v23, v23
	v_fmac_f32_e32 v19, v18, v18
	v_fmac_f32_e32 v21, v20, v20
	v_mul_f32_e32 v25, v25, v25
	v_fmac_f32_e32 v23, v22, v22
	v_add_f32_e32 v18, v19, v21
	v_fmac_f32_e32 v25, v24, v24
	v_add_f32_e32 v18, v23, v18
	v_add_f32_e32 v18, v25, v18
	v_sub_u32_e32 v26, v16, v150
	v_add_u32_e32 v26, v26, v152
	v_ashrrev_i32_e32 v27, 31, v26
	v_lshlrev_b64 v[26:27], 12, v[26:27]
	v_lshl_add_u64 v[26:27], s[10:11], 0, v[26:27]
	v_lshl_add_u64 v[26:27], v[120:121], 1, v[26:27]
	v_mov_b32_dpp v32, v28 row_ror:8 row_mask:0xf bank_mask:0xf
	v_mov_b32_dpp v33, v29 row_ror:8 row_mask:0xf bank_mask:0xf
	v_mov_b32_dpp v34, v30 row_ror:8 row_mask:0xf bank_mask:0xf
	v_mov_b32_dpp v35, v31 row_ror:8 row_mask:0xf bank_mask:0xf
	v_pk_add_f32 v[6:7], v[6:7], v[10:11]
	v_pk_add_f32 v[8:9], v[4:5], v[8:9]
	v_pk_add_f32 v[10:11], v[2:3], v[14:15]
	v_pk_add_f32 v[0:1], v[0:1], v[12:13]
	v_cvt_pk_bf16_f32 v2, v8, v9
	v_mul_f32_e32 v9, v9, v9
	v_mul_f32_e32 v12, v7, v7
	v_cvt_pk_bf16_f32 v3, v6, v7
	v_cvt_pk_bf16_f32 v4, v0, v1
	v_mul_f32_e32 v1, v1, v1
	v_fmac_f32_e32 v9, v8, v8
	v_fmac_f32_e32 v12, v6, v6
	v_cvt_pk_bf16_f32 v5, v10, v11
	v_mul_f32_e32 v11, v11, v11
	v_fmac_f32_e32 v1, v0, v0
	v_add_f32_e32 v0, v9, v12
	v_fmac_f32_e32 v11, v10, v10
	v_add_f32_e32 v0, v1, v0
	v_add_f32_e32 v0, v11, v0
	v_add_f32_e32 v0, v18, v0
	ds_bpermute_b32 v1, v122, v0
	v_mov_b32_dpp v36, v2 row_ror:8 row_mask:0xf bank_mask:0xf
	v_mov_b32_dpp v37, v3 row_ror:8 row_mask:0xf bank_mask:0xf
	v_mov_b32_dpp v38, v4 row_ror:8 row_mask:0xf bank_mask:0xf
	v_mov_b32_dpp v39, v5 row_ror:8 row_mask:0xf bank_mask:0xf
	s_waitcnt lgkmcnt(0)
	v_add_f32_e32 v0, v0, v1
	ds_bpermute_b32 v1, v114, v0
	v_cndmask_b32_e64 v7, v37, v29, s[6:7]
	v_cndmask_b32_e64 v9, v39, v31, s[6:7]
	v_cndmask_b32_e64 v6, v36, v28, s[6:7]
	v_cndmask_b32_e64 v8, v38, v30, s[6:7]
	global_store_dwordx4 v[26:27], v[6:9], off
	v_cndmask_b32_e64 v3, v3, v33, s[6:7]
	v_cndmask_b32_e64 v5, v5, v35, s[6:7]
	v_add_co_u32_e32 v6, vcc, s69, v26
	v_cndmask_b32_e64 v2, v2, v32, s[6:7]
	v_cndmask_b32_e64 v4, v4, v34, s[6:7]
	v_addc_co_u32_e32 v7, vcc, 0, v27, vcc
	global_store_dwordx4 v[6:7], v[2:5], off
	s_and_saveexec_b64 s[50:51], s[8:9]
	s_cbranch_execz .LBB0_604
	s_waitcnt lgkmcnt(0)
	v_add_f32_e32 v2, v0, v1
	v_lshl_add_u64 v[0:1], v[16:17], 2, s[12:13]
	global_atomic_add_f32 v[0:1], v2, off
	s_branch .LBB0_604

; #define PG8_STAGE(bufoff, gbase, voff) do { _Pragma("unroll") for (int _i = 0; _i < 2; ++_i) \
;         __builtin_amdgcn_global_load_lds((const unsigned*)((const char*)(gbase) + (voff)[_i]), (LAS unsigned*)(lds + (bufoff) + ldsw + _i * 8192), 16, 0, 0); } while (0)
; #define PG8_LDA(dst, b, h) do { _Pragma("unroll") for (int m = 0; m < 4; ++m) _Pragma("unroll") for (int k = 0; k < 2; ++k) dst[m][k] = *(const LAS bf16x8*)(lds + PG8_SA(b, h) + aoff + m * 2048 + k * 1024); } while (0)
; #define PG8_LDB(dst, b, h) do { _Pragma("unroll") for (int n = 0; n < 2; ++n) _Pragma("unroll") for (int k = 0; k < 2; ++k) dst[n][k] = *(const LAS bf16x8*)(lds + PG8_SB(b, h) + boff + n * 2048 + k * 1024); } while (0)
; #define PG8_MMA(ai, bj, At, Bt) do { __builtin_amdgcn_s_setprio(1); _Pragma("unroll") for (int m = 0; m < 4; ++m) _Pragma("unroll") for (int n = 0; n < 2; ++n) _Pragma("unroll") for (int k = 0; k < 2; ++k) \
;         acc[ai][bj][m][n] = __builtin_amdgcn_mfma_f32_16x16x32_bf16(Bt[n][k], At[m][k], acc[ai][bj][m][n], 0, 0, 0); __builtin_amdgcn_s_setprio(0); } while (0)
; #define PG8_WAIT_L(n) asm volatile("s_waitcnt lgkmcnt(" #n ")" ::: "memory")
; #define PG8_BAR __builtin_amdgcn_s_barrier()
; #define PG8_SCHED __builtin_amdgcn_sched_barrier(0)
; template <class Epi>
; __device__ __forceinline__ void gemm_phase(LAS unsigned char* lds, const Gemm g, const StaticOrder& S, const Epi& E) {
;     ...
;             PG8_LDB(B0, 0, 0); PG8_SCHED; PG8_LDA(At, 0, 0); PG8_STAGE(PG8_SA(1, 1), a1 + hstep, voffA);
;             PG8_WAIT_L(8); PG8_BAR; PG8_WAIT_L(0); PG8_MMA(0, 0, At, B0); PG8_BAR; PG8_SCHED;
;             PG8_LDB(B1, 0, 1); PG8_STAGE(PG8_SB(0, 0), b2, voffB0);
;             PG8_BAR; PG8_WAIT_L(0); PG8_MMA(0, 1, At, B1); PG8_BAR;
;             PG8_LDA(At, 0, 1); PG8_STAGE(PG8_SA(0, 0), a2, voffA);
;             PG8_BAR; PG8_WAIT_L(0); PG8_MMA(1, 0, At, B0); PG8_BAR; PG8_SCHED;
.LBB0_645:
	s_add_u32 s33, s50, s58
	s_addc_u32 s59, s51, 0
	s_add_u32 s56, s33, 0x100
	s_addc_u32 s57, s59, 0
	v_cndmask_b32_e64 v153, 0, 1, s[54:55]
	s_and_b64 s[54:55], s[52:53], exec
	s_cselect_b32 s57, s37, s57
	s_cselect_b32 s56, s45, s56
	s_add_u32 s54, s48, s58
	s_addc_u32 s55, s49, 0
	s_add_u32 s54, s54, 0x100
	s_addc_u32 s55, s55, 0
	s_and_b64 s[52:53], s[52:53], exec
	ds_read_b128 v[142:145], v150
	ds_read_b128 v[154:157], v150 offset:1024
	ds_read_b128 v[158:161], v150 offset:2048
	ds_read_b128 v[162:165], v150 offset:3072
	s_cselect_b32 s54, s80, s54
	s_cselect_b32 s55, s19, s55
	s_add_u32 s58, s33, 0x10080
	s_addc_u32 s59, s59, 0
	s_add_i32 s89, s78, s65
	s_add_i32 s85, s79, s65
	s_add_i32 m0, s47, 0xc000
	s_add_i32 s33, s47, 0xe000
	s_add_i32 s88, s89, 0x2000
	s_add_i32 s84, s85, 0x2000
	s_add_i32 s83, 0, 0x18000
	s_add_u32 s52, s56, 0x10000
	s_addc_u32 s53, s57, 0
	s_add_i32 s81, 0, 0x1c000
	s_add_i32 s82, s83, s65
	s_add_i32 s87, s81, s65
	s_add_i32 s90, s82, 0x2000
	s_add_i32 s86, s87, 0x2000
	v_cmp_ne_u32_e32 vcc, 1, v153
	v_lshl_add_u64 v[198:199], s[58:59], 0, v[128:129]
	ds_read_b128 v[166:169], v151
	ds_read_b128 v[170:173], v151 offset:1024
	ds_read_b128 v[174:177], v151 offset:2048
	ds_read_b128 v[178:181], v151 offset:3072
	ds_read_b128 v[182:185], v151 offset:4096
	ds_read_b128 v[186:189], v151 offset:5120
	ds_read_b128 v[190:193], v151 offset:6144
	ds_read_b128 v[194:197], v151 offset:7168
	global_load_lds_dwordx4 v[198:199], off
	v_lshl_add_u64 v[198:199], s[58:59], 0, v[134:135]
	s_mov_b32 m0, s33
	s_nop 0
	global_load_lds_dwordx4 v[198:199], off
	s_waitcnt lgkmcnt(8)
	s_barrier
	s_waitcnt lgkmcnt(0)
	v_mfma_f32_16x16x32_bf16 v[124:127], v[142:145], v[166:169], v[124:127]
	v_mfma_f32_16x16x32_bf16 v[120:123], v[158:161], v[166:169], v[120:123]
	v_mfma_f32_16x16x32_bf16 v[108:111], v[142:145], v[174:177], v[108:111]
	v_mfma_f32_16x16x32_bf16 v[104:107], v[158:161], v[174:177], v[104:107]
	v_mfma_f32_16x16x32_bf16 v[92:95], v[142:145], v[182:185], v[92:95]
	v_mfma_f32_16x16x32_bf16 v[88:91], v[158:161], v[182:185], v[88:91]
	v_mfma_f32_16x16x32_bf16 v[76:79], v[142:145], v[190:193], v[76:79]
	v_mfma_f32_16x16x32_bf16 v[72:75], v[158:161], v[190:193], v[72:75]
	v_mfma_f32_16x16x32_bf16 v[124:127], v[154:157], v[170:173], v[124:127]
	v_mfma_f32_16x16x32_bf16 v[120:123], v[162:165], v[170:173], v[120:123]
	v_mfma_f32_16x16x32_bf16 v[108:111], v[154:157], v[178:181], v[108:111]
	v_mfma_f32_16x16x32_bf16 v[104:107], v[162:165], v[178:181], v[104:107]
	v_mfma_f32_16x16x32_bf16 v[92:95], v[154:157], v[186:189], v[92:95]
	v_mfma_f32_16x16x32_bf16 v[88:91], v[162:165], v[186:189], v[88:91]
	v_mfma_f32_16x16x32_bf16 v[76:79], v[154:157], v[194:197], v[76:79]
	v_mfma_f32_16x16x32_bf16 v[72:75], v[162:165], v[194:197], v[72:75]
	s_barrier
	s_mov_b32 m0, s89
	v_lshl_add_u64 v[216:217], s[54:55], 0, v[130:131]
	ds_read_b128 v[198:201], v152
	ds_read_b128 v[204:207], v152 offset:1024
	ds_read_b128 v[208:211], v152 offset:2048
	ds_read_b128 v[212:215], v152 offset:3072
	global_load_lds_dwordx4 v[216:217], off
	v_lshl_add_u64 v[218:219], s[54:55], 0, v[136:137]
	s_mov_b32 m0, s88
	s_nop 0
	global_load_lds_dwordx4 v[218:219], off
	s_barrier
	s_waitcnt lgkmcnt(0)
	v_mfma_f32_16x16x32_bf16 v[116:119], v[198:201], v[166:169], v[116:119]
	v_mfma_f32_16x16x32_bf16 v[112:115], v[208:211], v[166:169], v[112:115]
	v_mfma_f32_16x16x32_bf16 v[100:103], v[198:201], v[174:177], v[100:103]
	v_mfma_f32_16x16x32_bf16 v[96:99], v[208:211], v[174:177], v[96:99]
	v_mfma_f32_16x16x32_bf16 v[84:87], v[198:201], v[182:185], v[84:87]
	v_mfma_f32_16x16x32_bf16 v[80:83], v[208:211], v[182:185], v[80:83]
	v_mfma_f32_16x16x32_bf16 v[68:71], v[198:201], v[190:193], v[68:71]
	v_mfma_f32_16x16x32_bf16 v[64:67], v[208:211], v[190:193], v[64:67]
	v_mfma_f32_16x16x32_bf16 v[116:119], v[204:207], v[170:173], v[116:119]
	v_mfma_f32_16x16x32_bf16 v[112:115], v[212:215], v[170:173], v[112:115]
	v_mfma_f32_16x16x32_bf16 v[100:103], v[204:207], v[178:181], v[100:103]
	v_mfma_f32_16x16x32_bf16 v[96:99], v[212:215], v[178:181], v[96:99]
	v_mfma_f32_16x16x32_bf16 v[84:87], v[204:207], v[186:189], v[84:87]
	v_mfma_f32_16x16x32_bf16 v[80:83], v[212:215], v[186:189], v[80:83]
	v_mfma_f32_16x16x32_bf16 v[68:71], v[204:207], v[194:197], v[68:71]
	v_mfma_f32_16x16x32_bf16 v[64:67], v[212:215], v[194:197], v[64:67]
	s_mov_b32 m0, s47
	v_lshl_add_u64 v[220:221], s[56:57], 0, v[128:129]
	s_barrier
	ds_read_b128 v[166:169], v151 offset:16384
	ds_read_b128 v[170:173], v151 offset:17408
	ds_read_b128 v[174:177], v151 offset:18432
	ds_read_b128 v[178:181], v151 offset:19456
	ds_read_b128 v[182:185], v151 offset:20480
	ds_read_b128 v[186:189], v151 offset:21504
	ds_read_b128 v[190:193], v151 offset:22528
	ds_read_b128 v[194:197], v151 offset:23552
	global_load_lds_dwordx4 v[220:221], off
	v_lshl_add_u64 v[222:223], s[56:57], 0, v[134:135]
	s_mov_b32 m0, s66
	s_nop 0
	global_load_lds_dwordx4 v[222:223], off
	s_barrier
	s_waitcnt lgkmcnt(0)
	v_mfma_f32_16x16x32_bf16 v[60:63], v[142:145], v[166:169], v[60:63]
	v_mfma_f32_16x16x32_bf16 v[56:59], v[158:161], v[166:169], v[56:59]
	v_mfma_f32_16x16x32_bf16 v[44:47], v[142:145], v[174:177], v[44:47]
	v_mfma_f32_16x16x32_bf16 v[40:43], v[158:161], v[174:177], v[40:43]
	v_mfma_f32_16x16x32_bf16 v[28:31], v[142:145], v[182:185], v[28:31]
	v_mfma_f32_16x16x32_bf16 v[24:27], v[158:161], v[182:185], v[24:27]
	v_mfma_f32_16x16x32_bf16 v[12:15], v[142:145], v[190:193], v[12:15]
	v_mfma_f32_16x16x32_bf16 v[8:11], v[158:161], v[190:193], v[8:11]
	v_mfma_f32_16x16x32_bf16 v[60:63], v[154:157], v[170:173], v[60:63]
	v_mfma_f32_16x16x32_bf16 v[56:59], v[162:165], v[170:173], v[56:59]
	v_mfma_f32_16x16x32_bf16 v[44:47], v[154:157], v[178:181], v[44:47]
	v_mfma_f32_16x16x32_bf16 v[40:43], v[162:165], v[178:181], v[40:43]
	v_mfma_f32_16x16x32_bf16 v[28:31], v[154:157], v[186:189], v[28:31]
	v_mfma_f32_16x16x32_bf16 v[24:27], v[162:165], v[186:189], v[24:27]
	v_mfma_f32_16x16x32_bf16 v[12:15], v[154:157], v[194:197], v[12:15]
	v_mfma_f32_16x16x32_bf16 v[8:11], v[162:165], v[194:197], v[8:11]
	s_barrier
; #define PG8_STAGE(bufoff, gbase, voff) do { _Pragma("unroll") for (int _i = 0; _i < 2; ++_i) \
;         __builtin_amdgcn_global_load_lds((const unsigned*)((const char*)(gbase) + (voff)[_i]), (LAS unsigned*)(lds + (bufoff) + ldsw + _i * 8192), 16, 0, 0); } while (0)
; #define PG8_LDA(dst, b, h) do { _Pragma("unroll") for (int m = 0; m < 4; ++m) _Pragma("unroll") for (int k = 0; k < 2; ++k) dst[m][k] = *(const LAS bf16x8*)(lds + PG8_SA(b, h) + aoff + m * 2048 + k * 1024); } while (0)
; #define PG8_LDB(dst, b, h) do { _Pragma("unroll") for (int n = 0; n < 2; ++n) _Pragma("unroll") for (int k = 0; k < 2; ++k) dst[n][k] = *(const LAS bf16x8*)(lds + PG8_SB(b, h) + boff + n * 2048 + k * 1024); } while (0)
; #define PG8_MMA(ai, bj, At, Bt) do { __builtin_amdgcn_s_setprio(1); _Pragma("unroll") for (int m = 0; m < 4; ++m) _Pragma("unroll") for (int n = 0; n < 2; ++n) _Pragma("unroll") for (int k = 0; k < 2; ++k) \
;         acc[ai][bj][m][n] = __builtin_amdgcn_mfma_f32_16x16x32_bf16(Bt[n][k], At[m][k], acc[ai][bj][m][n], 0, 0, 0); __builtin_amdgcn_s_setprio(0); } while (0)
; #define PG8_WAIT_V(n) asm volatile("s_waitcnt vmcnt(" #n ")" ::: "memory")
; #define PG8_WAIT_L(n) asm volatile("s_waitcnt lgkmcnt(" #n ")" ::: "memory")
; #define PG8_BAR __builtin_amdgcn_s_barrier()
; #define PG8_SCHED __builtin_amdgcn_sched_barrier(0)
; template <class Epi>
; __device__ __forceinline__ void gemm_phase(LAS unsigned char* lds, const Gemm g, const StaticOrder& S, const Epi& E) {
;     ...
;             PG8_STAGE(PG8_SB(0, 1), b2, voffB1);
;             PG8_WAIT_V(6); PG8_BAR; PG8_MMA(1, 1, At, B1); PG8_BAR;
;             PG8_LDB(B0, 1, 0); PG8_SCHED; PG8_LDA(At, 1, 0); PG8_STAGE(PG8_SA(0, 1), a2 + hstep, voffA);
;             PG8_WAIT_L(8); PG8_BAR; PG8_WAIT_L(0); PG8_MMA(0, 0, At, B0); PG8_BAR; PG8_SCHED;
;             PG8_LDB(B1, 1, 1); PG8_STAGE(PG8_SB(1, 0), b3, voffB0);
;             PG8_BAR; PG8_WAIT_L(0); PG8_MMA(0, 1, At, B1); PG8_BAR;
;             PG8_LDA(At, 1, 1); PG8_STAGE(PG8_SA(1, 0), a3, voffA);
;             PG8_BAR; PG8_WAIT_L(0); PG8_MMA(1, 0, At, B0); PG8_BAR; PG8_SCHED;
	s_mov_b32 m0, s85
	v_lshl_add_u64 v[224:225], s[54:55], 0, v[132:133]
	global_load_lds_dwordx4 v[224:225], off
	v_lshl_add_u64 v[226:227], s[54:55], 0, v[138:139]
	s_mov_b32 m0, s84
	s_nop 0
	global_load_lds_dwordx4 v[226:227], off
	s_waitcnt vmcnt(6)
	s_barrier
	v_mfma_f32_16x16x32_bf16 v[52:55], v[198:201], v[166:169], v[52:55]
	v_mfma_f32_16x16x32_bf16 v[48:51], v[208:211], v[166:169], v[48:51]
	v_mfma_f32_16x16x32_bf16 v[36:39], v[198:201], v[174:177], v[36:39]
	v_mfma_f32_16x16x32_bf16 v[32:35], v[208:211], v[174:177], v[32:35]
	v_mfma_f32_16x16x32_bf16 v[20:23], v[198:201], v[182:185], v[20:23]
	v_mfma_f32_16x16x32_bf16 v[16:19], v[208:211], v[182:185], v[16:19]
	v_mfma_f32_16x16x32_bf16 v[4:7], v[198:201], v[190:193], v[4:7]
	v_mfma_f32_16x16x32_bf16 v[0:3], v[208:211], v[190:193], v[0:3]
	v_mfma_f32_16x16x32_bf16 v[52:55], v[204:207], v[170:173], v[52:55]
	v_mfma_f32_16x16x32_bf16 v[48:51], v[212:215], v[170:173], v[48:51]
	v_mfma_f32_16x16x32_bf16 v[36:39], v[204:207], v[178:181], v[36:39]
	v_mfma_f32_16x16x32_bf16 v[32:35], v[212:215], v[178:181], v[32:35]
	v_mfma_f32_16x16x32_bf16 v[20:23], v[204:207], v[186:189], v[20:23]
	v_mfma_f32_16x16x32_bf16 v[16:19], v[212:215], v[186:189], v[16:19]
	v_mfma_f32_16x16x32_bf16 v[4:7], v[204:207], v[194:197], v[4:7]
	v_mfma_f32_16x16x32_bf16 v[0:3], v[212:215], v[194:197], v[0:3]
	v_add_u32_e32 v153, s83, v147
	s_barrier
	ds_read_b128 v[142:145], v153
	ds_read_b128 v[154:157], v153 offset:1024
	ds_read_b128 v[158:161], v153 offset:2048
	ds_read_b128 v[162:165], v153 offset:3072
	s_mov_b32 m0, s67
	v_lshl_add_u64 v[198:199], s[52:53], 0, v[128:129]
	ds_read_b128 v[166:169], v151 offset:32768
	ds_read_b128 v[170:173], v151 offset:33792
	ds_read_b128 v[174:177], v151 offset:34816
	ds_read_b128 v[178:181], v151 offset:35840
	ds_read_b128 v[182:185], v151 offset:36864
	ds_read_b128 v[186:189], v151 offset:37888
	ds_read_b128 v[190:193], v151 offset:38912
	ds_read_b128 v[194:197], v151 offset:39936
	global_load_lds_dwordx4 v[198:199], off
	v_lshl_add_u64 v[198:199], s[52:53], 0, v[134:135]
	s_mov_b32 m0, s68
	s_nop 0
	global_load_lds_dwordx4 v[198:199], off
	s_waitcnt lgkmcnt(8)
	s_barrier
	s_waitcnt lgkmcnt(0)
	v_mfma_f32_16x16x32_bf16 v[124:127], v[142:145], v[166:169], v[124:127]
	v_mfma_f32_16x16x32_bf16 v[120:123], v[158:161], v[166:169], v[120:123]
	v_mfma_f32_16x16x32_bf16 v[108:111], v[142:145], v[174:177], v[108:111]
	v_mfma_f32_16x16x32_bf16 v[104:107], v[158:161], v[174:177], v[104:107]
	v_mfma_f32_16x16x32_bf16 v[92:95], v[142:145], v[182:185], v[92:95]
	v_mfma_f32_16x16x32_bf16 v[88:91], v[158:161], v[182:185], v[88:91]
	v_mfma_f32_16x16x32_bf16 v[76:79], v[142:145], v[190:193], v[76:79]
	v_mfma_f32_16x16x32_bf16 v[72:75], v[158:161], v[190:193], v[72:75]
	v_mfma_f32_16x16x32_bf16 v[124:127], v[154:157], v[170:173], v[124:127]
	v_mfma_f32_16x16x32_bf16 v[120:123], v[162:165], v[170:173], v[120:123]
	v_mfma_f32_16x16x32_bf16 v[108:111], v[154:157], v[178:181], v[108:111]
	v_mfma_f32_16x16x32_bf16 v[104:107], v[162:165], v[178:181], v[104:107]
	v_mfma_f32_16x16x32_bf16 v[92:95], v[154:157], v[186:189], v[92:95]
	v_mfma_f32_16x16x32_bf16 v[88:91], v[162:165], v[186:189], v[88:91]
	v_mfma_f32_16x16x32_bf16 v[76:79], v[154:157], v[194:197], v[76:79]
	v_mfma_f32_16x16x32_bf16 v[72:75], v[162:165], v[194:197], v[72:75]
	s_barrier
	s_mov_b32 m0, s82
	v_add_u32_e32 v153, s81, v147
	v_lshl_add_u64 v[216:217], v[216:217], 0, s[16:17]
	ds_read_b128 v[198:201], v153
	ds_read_b128 v[204:207], v153 offset:1024
	ds_read_b128 v[208:211], v153 offset:2048
	ds_read_b128 v[212:215], v153 offset:3072
	global_load_lds_dwordx4 v[216:217], off
	v_lshl_add_u64 v[216:217], v[218:219], 0, s[16:17]
	s_mov_b32 m0, s90
	s_nop 0
	global_load_lds_dwordx4 v[216:217], off
	s_barrier
	s_waitcnt lgkmcnt(0)
	v_mfma_f32_16x16x32_bf16 v[116:119], v[198:201], v[166:169], v[116:119]
	v_mfma_f32_16x16x32_bf16 v[112:115], v[208:211], v[166:169], v[112:115]
	v_mfma_f32_16x16x32_bf16 v[100:103], v[198:201], v[174:177], v[100:103]
	v_mfma_f32_16x16x32_bf16 v[96:99], v[208:211], v[174:177], v[96:99]
	v_mfma_f32_16x16x32_bf16 v[84:87], v[198:201], v[182:185], v[84:87]
	v_mfma_f32_16x16x32_bf16 v[80:83], v[208:211], v[182:185], v[80:83]
	v_mfma_f32_16x16x32_bf16 v[68:71], v[198:201], v[190:193], v[68:71]
	v_mfma_f32_16x16x32_bf16 v[64:67], v[208:211], v[190:193], v[64:67]
	v_mfma_f32_16x16x32_bf16 v[116:119], v[204:207], v[170:173], v[116:119]
	v_mfma_f32_16x16x32_bf16 v[112:115], v[212:215], v[170:173], v[112:115]
	v_mfma_f32_16x16x32_bf16 v[100:103], v[204:207], v[178:181], v[100:103]
	v_mfma_f32_16x16x32_bf16 v[96:99], v[212:215], v[178:181], v[96:99]
	v_mfma_f32_16x16x32_bf16 v[84:87], v[204:207], v[186:189], v[84:87]
	v_mfma_f32_16x16x32_bf16 v[80:83], v[212:215], v[186:189], v[80:83]
	v_mfma_f32_16x16x32_bf16 v[68:71], v[204:207], v[194:197], v[68:71]
	v_mfma_f32_16x16x32_bf16 v[64:67], v[212:215], v[194:197], v[64:67]
	s_mov_b32 m0, s70
	v_lshl_add_u64 v[216:217], v[220:221], 0, s[16:17]
	s_barrier
	ds_read_b128 v[166:169], v151 offset:49152
	ds_read_b128 v[170:173], v151 offset:50176
	ds_read_b128 v[174:177], v151 offset:51200
	ds_read_b128 v[178:181], v151 offset:52224
	ds_read_b128 v[182:185], v151 offset:53248
	ds_read_b128 v[186:189], v151 offset:54272
	ds_read_b128 v[190:193], v151 offset:55296
	ds_read_b128 v[194:197], v151 offset:56320
	global_load_lds_dwordx4 v[216:217], off
	v_lshl_add_u64 v[216:217], v[222:223], 0, s[16:17]
	s_mov_b32 m0, s71
	s_nop 0
	global_load_lds_dwordx4 v[216:217], off
	s_barrier
; __device__ __forceinline__ unsigned cvt_pk_bf16(float lo, float hi) { unsigned r; asm volatile("v_cvt_pk_bf16_f32 %0, %1, %2" : "=v"(r) : "v"(lo), "v"(hi)); return r; }
; #define PG8_WAIT_V(n) asm volatile("s_waitcnt vmcnt(" #n ")" ::: "memory")
; __device__ __forceinline__ void store_pair_lines(bf16_t* O, int ldc, int row, int fr, int col0, u32x4 wA, u32x4 wB) {
;     const u32x4 sA = {dpp_ror8(wA.x), dpp_ror8(wA.y), dpp_ror8(wA.z), dpp_ror8(wA.w)}, sB = {dpp_ror8(wB.x), dpp_ror8(wB.y), dpp_ror8(wB.z), dpp_ror8(wB.w)};
;     const bool lo = fr < 8;
;     const u32x4 o1 = lo ? wA : sB, o2 = lo ? sA : wB;
;     const int r1 = row - fr + (fr & 7), cb = col0 + (lo ? 0 : 8);
;     *(u32x4*)(O + (size_t)r1 * ldc + cb) = o1;
;     *(u32x4*)(O + (size_t)(r1 + 8) * ldc + cb) = o2;
;     __device__ __forceinline__ void operator()(const f32x4 (&acc)[2][2][4][2], const Unit& u, int wr, int wc, int fr, int fq) const {
;     ...
;             for (int m = 0; m < 4; ++m) { const int row = row0 + ai * HALF + m * 16;
;                 const float rs = ssin ? __builtin_amdgcn_rsqf(ssin[row] * (1.f / D) + EPS) : 1.0f; float sq = 0.f; u32x4 w[2];
; #pragma unroll
;                 for (int bj = 0; bj < 2; ++bj) { f32x4 v0 = acc[ai][bj][m][0] * rs, v1 = acc[ai][bj][m][1] * rs;
;                     if (ACT == 1) {
; #pragma unroll
;                         for (int j = 0; j < 4; ++j) { const float a = fmaxf(v0[j], 0.f), b = fmaxf(v1[j], 0.f); v0[j] = a * a; v1[j] = b * b; } }
;                     sq += (v0[0] * v0[0] + v0[1] * v0[1]) + (v0[2] * v0[2] + v0[3] * v0[3]) + (v1[0] * v1[0] + v1[1] * v1[1]) + (v1[2] * v1[2] + v1[3] * v1[3]);
;                     w[bj].x = cvt_pk_bf16(v0[0], v0[1]); w[bj].y = cvt_pk_bf16(v0[2], v0[3]); w[bj].z = cvt_pk_bf16(v1[0], v1[1]); w[bj].w = cvt_pk_bf16(v1[2], v1[3]); }
;                 store_pair_lines(O, ldc, row, fr, col0, w[0], w[1]);
;                 if (ssout) { sq += __shfl_xor(sq, 16); sq += __shfl_xor(sq, 32); if (fq == 0) unsafeAtomicAdd(ssout + row, sq); } }
; template <class Epi>
; __device__ __forceinline__ void gemm_phase(LAS unsigned char* lds, const Gemm g, const StaticOrder& S, const Epi& E) {
;     ...
;             PG8_BAR; PG8_WAIT_L(0); PG8_MMA(1, 0, At, B0); PG8_BAR; PG8_SCHED;
;             PG8_STAGE(PG8_SB(1, 1), b3, voffB1);
;             PG8_WAIT_V(6); PG8_BAR; PG8_MMA(1, 1, At, B1); PG8_BAR;
	s_waitcnt lgkmcnt(0)
	v_mfma_f32_16x16x32_bf16 v[60:63], v[142:145], v[166:169], v[60:63]
	v_mfma_f32_16x16x32_bf16 v[56:59], v[158:161], v[166:169], v[56:59]
	v_mfma_f32_16x16x32_bf16 v[44:47], v[142:145], v[174:177], v[44:47]
	v_mfma_f32_16x16x32_bf16 v[40:43], v[158:161], v[174:177], v[40:43]
	v_mfma_f32_16x16x32_bf16 v[28:31], v[142:145], v[182:185], v[28:31]
	v_mfma_f32_16x16x32_bf16 v[24:27], v[158:161], v[182:185], v[24:27]
	v_mfma_f32_16x16x32_bf16 v[12:15], v[142:145], v[190:193], v[12:15]
	v_mfma_f32_16x16x32_bf16 v[8:11], v[158:161], v[190:193], v[8:11]
	v_mfma_f32_16x16x32_bf16 v[60:63], v[154:157], v[170:173], v[60:63]
	v_mfma_f32_16x16x32_bf16 v[56:59], v[162:165], v[170:173], v[56:59]
	v_mfma_f32_16x16x32_bf16 v[44:47], v[154:157], v[178:181], v[44:47]
	v_mfma_f32_16x16x32_bf16 v[40:43], v[162:165], v[178:181], v[40:43]
	v_mfma_f32_16x16x32_bf16 v[28:31], v[154:157], v[186:189], v[28:31]
	v_mfma_f32_16x16x32_bf16 v[24:27], v[162:165], v[186:189], v[24:27]
	v_mfma_f32_16x16x32_bf16 v[12:15], v[154:157], v[194:197], v[12:15]
	v_mfma_f32_16x16x32_bf16 v[8:11], v[162:165], v[194:197], v[8:11]
	s_barrier
	s_mov_b32 m0, s87
	v_lshl_add_u64 v[142:143], v[224:225], 0, s[16:17]
	global_load_lds_dwordx4 v[142:143], off
	v_lshl_add_u64 v[142:143], v[226:227], 0, s[16:17]
	s_mov_b32 m0, s86
	s_nop 0
	global_load_lds_dwordx4 v[142:143], off
	s_waitcnt vmcnt(6)
	s_barrier
	v_mfma_f32_16x16x32_bf16 v[52:55], v[198:201], v[166:169], v[52:55]
	v_mfma_f32_16x16x32_bf16 v[48:51], v[208:211], v[166:169], v[48:51]
	v_mfma_f32_16x16x32_bf16 v[36:39], v[198:201], v[174:177], v[36:39]
	v_mfma_f32_16x16x32_bf16 v[32:35], v[208:211], v[174:177], v[32:35]
	v_mfma_f32_16x16x32_bf16 v[20:23], v[198:201], v[182:185], v[20:23]
	v_mfma_f32_16x16x32_bf16 v[16:19], v[208:211], v[182:185], v[16:19]
	v_mfma_f32_16x16x32_bf16 v[4:7], v[198:201], v[190:193], v[4:7]
	v_mfma_f32_16x16x32_bf16 v[0:3], v[208:211], v[190:193], v[0:3]
	v_mfma_f32_16x16x32_bf16 v[52:55], v[204:207], v[170:173], v[52:55]
	v_mfma_f32_16x16x32_bf16 v[48:51], v[212:215], v[170:173], v[48:51]
	v_mfma_f32_16x16x32_bf16 v[36:39], v[204:207], v[178:181], v[36:39]
	v_mfma_f32_16x16x32_bf16 v[32:35], v[212:215], v[178:181], v[32:35]
	v_mfma_f32_16x16x32_bf16 v[20:23], v[204:207], v[186:189], v[20:23]
	v_mfma_f32_16x16x32_bf16 v[16:19], v[212:215], v[186:189], v[16:19]
	v_mfma_f32_16x16x32_bf16 v[4:7], v[204:207], v[194:197], v[4:7]
	v_mfma_f32_16x16x32_bf16 v[0:3], v[212:215], v[194:197], v[0:3]
	s_movk_i32 s58, 0x100
	s_mov_b64 s[54:55], 0
	s_mov_b64 s[52:53], -1
	s_barrier
	s_cbranch_vccz .LBB0_645
	v_cvt_pk_bf16_f32 v145, v124, v125
	v_cvt_pk_bf16_f32 v153, v126, v127
	v_cvt_pk_bf16_f32 v156, v120, v121
	v_cvt_pk_bf16_f32 v157, v122, v123
	v_cvt_pk_bf16_f32 v158, v116, v117
	v_cvt_pk_bf16_f32 v159, v118, v119
	v_cvt_pk_bf16_f32 v160, v112, v113
	v_cvt_pk_bf16_f32 v161, v114, v115
	v_mul_f32_e32 v123, v123, v123
	v_mul_f32_e32 v115, v115, v115
	v_fmac_f32_e32 v123, v122, v122
	v_mul_f32_e32 v122, v125, v125
	v_fmac_f32_e32 v115, v114, v114
	v_mul_f32_e32 v114, v117, v117
	v_fmac_f32_e32 v122, v124, v124
	v_mul_f32_e32 v124, v127, v127
	v_fmac_f32_e32 v114, v116, v116
	v_mul_f32_e32 v116, v119, v119
	v_fmac_f32_e32 v124, v126, v126
	v_mul_f32_e32 v121, v121, v121
	v_fmac_f32_e32 v116, v118, v118
	v_mul_f32_e32 v113, v113, v113
	v_add_f32_e32 v122, v122, v124
	v_fmac_f32_e32 v121, v120, v120
	v_add_f32_e32 v114, v114, v116
	v_fmac_f32_e32 v113, v112, v112
	v_add_f32_e32 v120, v122, v121
	v_add_f32_e32 v112, v114, v113
	s_lshl_b32 s19, s46, 8
	v_add_f32_e32 v120, v123, v120
	v_add_f32_e32 v112, v115, v112
	v_and_b32_e32 v113, 64, v203
	s_add_i32 s19, s19, s72
	v_mov_b32_dpp v162, v145 row_ror:8 row_mask:0xf bank_mask:0xf
	v_add_f32_e32 v115, v120, v112
	v_xor_b32_e32 v112, 16, v203
	v_add_u32_e32 v118, 64, v113
	v_mov_b32_dpp v163, v153 row_ror:8 row_mask:0xf bank_mask:0xf
	v_mov_b32_dpp v154, v158 row_ror:8 row_mask:0xf bank_mask:0xf
	v_cndmask_b32_e64 v158, v158, v162, s[6:7]
	v_or_b32_e32 v162, s19, v148
	v_cmp_lt_i32_e32 vcc, v112, v118
	v_lshl_or_b32 v142, s44, 8, v149
	v_mov_b32_dpp v164, v156 row_ror:8 row_mask:0xf bank_mask:0xf
	v_mov_b32_dpp v165, v157 row_ror:8 row_mask:0xf bank_mask:0xf
	v_mov_b32_dpp v155, v159 row_ror:8 row_mask:0xf bank_mask:0xf
	v_cndmask_b32_e64 v159, v159, v163, s[6:7]
	v_ashrrev_i32_e32 v163, 31, v162
	v_cndmask_b32_e32 v112, v203, v112, vcc
	v_ashrrev_i32_e32 v143, 31, v142
	v_mov_b32_dpp v166, v160 row_ror:8 row_mask:0xf bank_mask:0xf
	v_mov_b32_dpp v167, v161 row_ror:8 row_mask:0xf bank_mask:0xf
	v_cndmask_b32_e64 v160, v160, v164, s[6:7]
	v_cndmask_b32_e64 v161, v161, v165, s[6:7]
	v_lshlrev_b64 v[164:165], 12, v[162:163]
	v_lshlrev_b32_e32 v114, 2, v112
	v_cndmask_b32_e64 v156, v166, v156, s[6:7]
	v_cndmask_b32_e64 v157, v167, v157, s[6:7]
	v_lshl_add_u64 v[164:165], s[10:11], 0, v[164:165]
	v_lshlrev_b64 v[166:167], 1, v[142:143]
	ds_bpermute_b32 v119, v114, v115
	v_cndmask_b32_e64 v154, v154, v145, s[6:7]
	v_cndmask_b32_e64 v155, v155, v153, s[6:7]
	v_lshl_add_u64 v[112:113], v[164:165], 0, v[166:167]
	global_store_dwordx4 v[112:113], v[154:157], off
	v_xor_b32_e32 v113, 32, v203
	v_cmp_lt_i32_e32 vcc, v113, v118
	s_waitcnt lgkmcnt(0)
	v_add_f32_e32 v112, v115, v119
	v_or_b32_e32 v116, 8, v162
	v_cndmask_b32_e32 v113, v203, v113, vcc
	v_lshlrev_b32_e32 v115, 2, v113
	ds_bpermute_b32 v113, v115, v112
	v_ashrrev_i32_e32 v117, 31, v116
	v_lshlrev_b64 v[116:117], 12, v[116:117]
	v_lshl_add_u64 v[116:117], s[10:11], 0, v[116:117]
	v_or_b32_e32 v144, s19, v146
	v_lshl_add_u64 v[116:117], v[116:117], 0, v[166:167]
	global_store_dwordx4 v[116:117], v[158:161], off
	s_and_saveexec_b64 s[44:45], s[8:9]
	s_cbranch_execz .LBB0_648
	v_ashrrev_i32_e32 v145, 31, v144
	s_waitcnt lgkmcnt(0)
	v_add_f32_e32 v116, v112, v113
	v_lshl_add_u64 v[112:113], v[144:145], 2, s[12:13]
	global_atomic_add_f32 v[112:113], v116, off
; __device__ __forceinline__ unsigned cvt_pk_bf16(float lo, float hi) { unsigned r; asm volatile("v_cvt_pk_bf16_f32 %0, %1, %2" : "=v"(r) : "v"(lo), "v"(hi)); return r; }
; __device__ __forceinline__ unsigned dpp_ror8(unsigned x) { return (unsigned)__builtin_amdgcn_update_dpp(0, (int)x, 0x128, 0xf, 0xf, false); }
; __device__ __forceinline__ void store_pair_lines(bf16_t* O, int ldc, int row, int fr, int col0, u32x4 wA, u32x4 wB) {
;     const u32x4 sA = {dpp_ror8(wA.x), dpp_ror8(wA.y), dpp_ror8(wA.z), dpp_ror8(wA.w)}, sB = {dpp_ror8(wB.x), dpp_ror8(wB.y), dpp_ror8(wB.z), dpp_ror8(wB.w)};
;     const bool lo = fr < 8;
;     const u32x4 o1 = lo ? wA : sB, o2 = lo ? sA : wB;
;     const int r1 = row - fr + (fr & 7), cb = col0 + (lo ? 0 : 8);
;     *(u32x4*)(O + (size_t)r1 * ldc + cb) = o1;
;     *(u32x4*)(O + (size_t)(r1 + 8) * ldc + cb) = o2;
;     __device__ __forceinline__ void operator()(const f32x4 (&acc)[2][2][4][2], const Unit& u, int wr, int wc, int fr, int fq) const {
;     ...
;             for (int m = 0; m < 4; ++m) { const int row = row0 + ai * HALF + m * 16;
;                 const float rs = ssin ? __builtin_amdgcn_rsqf(ssin[row] * (1.f / D) + EPS) : 1.0f; float sq = 0.f; u32x4 w[2];
; #pragma unroll
;                 for (int bj = 0; bj < 2; ++bj) { f32x4 v0 = acc[ai][bj][m][0] * rs, v1 = acc[ai][bj][m][1] * rs;
;                     if (ACT == 1) {
; #pragma unroll
;                         for (int j = 0; j < 4; ++j) { const float a = fmaxf(v0[j], 0.f), b = fmaxf(v1[j], 0.f); v0[j] = a * a; v1[j] = b * b; } }
;                     sq += (v0[0] * v0[0] + v0[1] * v0[1]) + (v0[2] * v0[2] + v0[3] * v0[3]) + (v1[0] * v1[0] + v1[1] * v1[1]) + (v1[2] * v1[2] + v1[3] * v1[3]);
;                     w[bj].x = cvt_pk_bf16(v0[0], v0[1]); w[bj].y = cvt_pk_bf16(v0[2], v0[3]); w[bj].z = cvt_pk_bf16(v1[0], v1[1]); w[bj].w = cvt_pk_bf16(v1[2], v1[3]); }
;                 store_pair_lines(O, ldc, row, fr, col0, w[0], w[1]);
;                 if (ssout) { sq += __shfl_xor(sq, 16); sq += __shfl_xor(sq, 32); if (fq == 0) unsafeAtomicAdd(ssout + row, sq); } }
.LBB0_648:
	s_or_b64 exec, exec, s[44:45]
	s_waitcnt lgkmcnt(0)
	v_cvt_pk_bf16_f32 v113, v108, v109
	v_cvt_pk_bf16_f32 v117, v110, v111
	v_cvt_pk_bf16_f32 v118, v104, v105
	v_cvt_pk_bf16_f32 v119, v106, v107
	v_cvt_pk_bf16_f32 v120, v100, v101
	v_cvt_pk_bf16_f32 v121, v102, v103
	v_cvt_pk_bf16_f32 v122, v96, v97
	v_cvt_pk_bf16_f32 v123, v98, v99
	v_mul_f32_e32 v107, v107, v107
	v_mul_f32_e32 v99, v99, v99
	v_fmac_f32_e32 v107, v106, v106
	v_mul_f32_e32 v106, v109, v109
	v_fmac_f32_e32 v99, v98, v98
	v_mul_f32_e32 v98, v101, v101
	v_fmac_f32_e32 v106, v108, v108
	v_mul_f32_e32 v108, v111, v111
	v_fmac_f32_e32 v98, v100, v100
	v_mul_f32_e32 v100, v103, v103
	v_fmac_f32_e32 v108, v110, v110
	v_mul_f32_e32 v105, v105, v105
	v_fmac_f32_e32 v100, v102, v102
	v_mul_f32_e32 v97, v97, v97
	v_add_f32_e32 v106, v106, v108
	v_fmac_f32_e32 v105, v104, v104
	v_add_f32_e32 v98, v98, v100
	v_fmac_f32_e32 v97, v96, v96
	v_add_f32_e32 v104, v106, v105
	v_add_f32_e32 v96, v98, v97
	v_add_f32_e32 v104, v107, v104
	v_add_f32_e32 v96, v99, v96
	v_or_b32_e32 v112, 16, v144
	v_mov_b32_dpp v116, v120 row_ror:8 row_mask:0xf bank_mask:0xf
	v_add_f32_e32 v100, v104, v96
	v_mov_b32_dpp v124, v113 row_ror:8 row_mask:0xf bank_mask:0xf
	v_cndmask_b32_e64 v116, v116, v113, s[6:7]
	v_sub_u32_e32 v113, v112, v146
	ds_bpermute_b32 v101, v114, v100
	v_mov_b32_dpp v125, v117 row_ror:8 row_mask:0xf bank_mask:0xf
	v_cndmask_b32_e64 v120, v120, v124, s[6:7]
	v_add_u32_e32 v124, v113, v148
	v_mov_b32_dpp v145, v121 row_ror:8 row_mask:0xf bank_mask:0xf
	v_cndmask_b32_e64 v121, v121, v125, s[6:7]
	v_ashrrev_i32_e32 v125, 31, v124
	v_lshlrev_b64 v[96:97], 12, v[124:125]
	v_lshl_add_u64 v[96:97], s[10:11], 0, v[96:97]
	v_lshl_add_u64 v[98:99], v[142:143], 1, v[96:97]
	s_waitcnt lgkmcnt(0)
	v_add_f32_e32 v96, v100, v101
	ds_bpermute_b32 v97, v115, v96
	v_mov_b32_dpp v153, v122 row_ror:8 row_mask:0xf bank_mask:0xf
	v_mov_b32_dpp v154, v123 row_ror:8 row_mask:0xf bank_mask:0xf
	v_mov_b32_dpp v126, v118 row_ror:8 row_mask:0xf bank_mask:0xf
	v_mov_b32_dpp v127, v119 row_ror:8 row_mask:0xf bank_mask:0xf
	v_cndmask_b32_e64 v117, v145, v117, s[6:7]
	v_cndmask_b32_e64 v118, v153, v118, s[6:7]
	v_cndmask_b32_e64 v119, v154, v119, s[6:7]
	global_store_dwordx4 v[98:99], v[116:119], off
	v_add_co_u32_e32 v98, vcc, s73, v98
	v_cndmask_b32_e64 v122, v122, v126, s[6:7]
	v_cndmask_b32_e64 v123, v123, v127, s[6:7]
	v_addc_co_u32_e32 v99, vcc, 0, v99, vcc
	global_store_dwordx4 v[98:99], v[120:123], off
	s_and_saveexec_b64 s[44:45], s[8:9]
	s_cbranch_execz .LBB0_650
	v_ashrrev_i32_e32 v113, 31, v112
	s_waitcnt lgkmcnt(0)
	v_add_f32_e32 v98, v96, v97
	v_lshl_add_u64 v[96:97], v[112:113], 2, s[12:13]
	global_atomic_add_f32 v[96:97], v98, off
.LBB0_650:
	s_or_b64 exec, exec, s[44:45]
	s_waitcnt lgkmcnt(0)
	v_cvt_pk_bf16_f32 v97, v92, v93
	v_cvt_pk_bf16_f32 v99, v94, v95
	v_cvt_pk_bf16_f32 v100, v88, v89
	v_cvt_pk_bf16_f32 v101, v90, v91
	v_cvt_pk_bf16_f32 v102, v84, v85
	v_cvt_pk_bf16_f32 v103, v86, v87
	v_cvt_pk_bf16_f32 v104, v80, v81
	v_cvt_pk_bf16_f32 v105, v82, v83
	v_mul_f32_e32 v91, v91, v91
	v_mul_f32_e32 v83, v83, v83
	v_fmac_f32_e32 v91, v90, v90
	v_mul_f32_e32 v90, v93, v93
	v_fmac_f32_e32 v83, v82, v82
	v_mul_f32_e32 v82, v85, v85
	v_fmac_f32_e32 v90, v92, v92
	v_mul_f32_e32 v92, v95, v95
	v_fmac_f32_e32 v82, v84, v84
	v_mul_f32_e32 v84, v87, v87
	v_fmac_f32_e32 v92, v94, v94
	v_mul_f32_e32 v89, v89, v89
	v_fmac_f32_e32 v84, v86, v86
	v_mul_f32_e32 v81, v81, v81
	v_add_f32_e32 v90, v90, v92
	v_fmac_f32_e32 v89, v88, v88
	v_add_f32_e32 v82, v82, v84
	v_fmac_f32_e32 v81, v80, v80
	v_add_f32_e32 v88, v90, v89
	v_add_f32_e32 v80, v82, v81
	v_add_f32_e32 v88, v91, v88
	v_add_f32_e32 v80, v83, v80
	v_or_b32_e32 v96, 32, v144
	v_mov_b32_dpp v98, v102 row_ror:8 row_mask:0xf bank_mask:0xf
	v_add_f32_e32 v84, v88, v80
	v_mov_b32_dpp v106, v97 row_ror:8 row_mask:0xf bank_mask:0xf
	v_cndmask_b32_e64 v98, v98, v97, s[6:7]
	v_sub_u32_e32 v97, v96, v146
	ds_bpermute_b32 v85, v114, v84
	v_mov_b32_dpp v107, v99 row_ror:8 row_mask:0xf bank_mask:0xf
	v_cndmask_b32_e64 v102, v102, v106, s[6:7]
	v_add_u32_e32 v106, v97, v148
	v_mov_b32_dpp v110, v103 row_ror:8 row_mask:0xf bank_mask:0xf
	v_cndmask_b32_e64 v103, v103, v107, s[6:7]
	v_ashrrev_i32_e32 v107, 31, v106
	v_lshlrev_b64 v[80:81], 12, v[106:107]
	v_lshl_add_u64 v[80:81], s[10:11], 0, v[80:81]
	v_lshl_add_u64 v[82:83], v[142:143], 1, v[80:81]
	s_waitcnt lgkmcnt(0)
	v_add_f32_e32 v80, v84, v85
	ds_bpermute_b32 v81, v115, v80
	v_mov_b32_dpp v111, v104 row_ror:8 row_mask:0xf bank_mask:0xf
	v_mov_b32_dpp v112, v105 row_ror:8 row_mask:0xf bank_mask:0xf
	v_mov_b32_dpp v108, v100 row_ror:8 row_mask:0xf bank_mask:0xf
	v_mov_b32_dpp v109, v101 row_ror:8 row_mask:0xf bank_mask:0xf
	v_cndmask_b32_e64 v99, v110, v99, s[6:7]
	v_cndmask_b32_e64 v100, v111, v100, s[6:7]
	v_cndmask_b32_e64 v101, v112, v101, s[6:7]
	global_store_dwordx4 v[82:83], v[98:101], off
	v_add_co_u32_e32 v82, vcc, s73, v82
	v_cndmask_b32_e64 v104, v104, v108, s[6:7]
	v_cndmask_b32_e64 v105, v105, v109, s[6:7]
	v_addc_co_u32_e32 v83, vcc, 0, v83, vcc
	global_store_dwordx4 v[82:83], v[102:105], off
	s_and_saveexec_b64 s[44:45], s[8:9]
	s_cbranch_execz .LBB0_652
	v_ashrrev_i32_e32 v97, 31, v96
	s_waitcnt lgkmcnt(0)
	v_add_f32_e32 v82, v80, v81
	v_lshl_add_u64 v[80:81], v[96:97], 2, s[12:13]
	global_atomic_add_f32 v[80:81], v82, off
; __device__ __forceinline__ unsigned cvt_pk_bf16(float lo, float hi) { unsigned r; asm volatile("v_cvt_pk_bf16_f32 %0, %1, %2" : "=v"(r) : "v"(lo), "v"(hi)); return r; }
; __device__ __forceinline__ unsigned dpp_ror8(unsigned x) { return (unsigned)__builtin_amdgcn_update_dpp(0, (int)x, 0x128, 0xf, 0xf, false); }
; __device__ __forceinline__ void store_pair_lines(bf16_t* O, int ldc, int row, int fr, int col0, u32x4 wA, u32x4 wB) {
;     const u32x4 sA = {dpp_ror8(wA.x), dpp_ror8(wA.y), dpp_ror8(wA.z), dpp_ror8(wA.w)}, sB = {dpp_ror8(wB.x), dpp_ror8(wB.y), dpp_ror8(wB.z), dpp_ror8(wB.w)};
;     const bool lo = fr < 8;
;     const u32x4 o1 = lo ? wA : sB, o2 = lo ? sA : wB;
;     const int r1 = row - fr + (fr & 7), cb = col0 + (lo ? 0 : 8);
;     *(u32x4*)(O + (size_t)r1 * ldc + cb) = o1;
;     *(u32x4*)(O + (size_t)(r1 + 8) * ldc + cb) = o2;
;     __device__ __forceinline__ void operator()(const f32x4 (&acc)[2][2][4][2], const Unit& u, int wr, int wc, int fr, int fq) const {
;     ...
;             for (int m = 0; m < 4; ++m) { const int row = row0 + ai * HALF + m * 16;
;                 const float rs = ssin ? __builtin_amdgcn_rsqf(ssin[row] * (1.f / D) + EPS) : 1.0f; float sq = 0.f; u32x4 w[2];
; #pragma unroll
;                 for (int bj = 0; bj < 2; ++bj) { f32x4 v0 = acc[ai][bj][m][0] * rs, v1 = acc[ai][bj][m][1] * rs;
;                     if (ACT == 1) {
; #pragma unroll
;                         for (int j = 0; j < 4; ++j) { const float a = fmaxf(v0[j], 0.f), b = fmaxf(v1[j], 0.f); v0[j] = a * a; v1[j] = b * b; } }
;                     sq += (v0[0] * v0[0] + v0[1] * v0[1]) + (v0[2] * v0[2] + v0[3] * v0[3]) + (v1[0] * v1[0] + v1[1] * v1[1]) + (v1[2] * v1[2] + v1[3] * v1[3]);
;                     w[bj].x = cvt_pk_bf16(v0[0], v0[1]); w[bj].y = cvt_pk_bf16(v0[2], v0[3]); w[bj].z = cvt_pk_bf16(v1[0], v1[1]); w[bj].w = cvt_pk_bf16(v1[2], v1[3]); }
;                 store_pair_lines(O, ldc, row, fr, col0, w[0], w[1]);
;                 if (ssout) { sq += __shfl_xor(sq, 16); sq += __shfl_xor(sq, 32); if (fq == 0) unsafeAtomicAdd(ssout + row, sq); } }
.LBB0_652:
	s_or_b64 exec, exec, s[44:45]
	s_waitcnt lgkmcnt(0)
	v_cvt_pk_bf16_f32 v81, v76, v77
	v_cvt_pk_bf16_f32 v83, v78, v79
	v_cvt_pk_bf16_f32 v84, v72, v73
	v_cvt_pk_bf16_f32 v85, v74, v75
	v_cvt_pk_bf16_f32 v86, v68, v69
	v_cvt_pk_bf16_f32 v87, v70, v71
	v_cvt_pk_bf16_f32 v88, v64, v65
	v_cvt_pk_bf16_f32 v89, v66, v67
	v_mul_f32_e32 v75, v75, v75
	v_mul_f32_e32 v67, v67, v67
	v_fmac_f32_e32 v75, v74, v74
	v_mul_f32_e32 v74, v77, v77
	v_fmac_f32_e32 v67, v66, v66
	v_mul_f32_e32 v66, v69, v69
	v_fmac_f32_e32 v74, v76, v76
	v_mul_f32_e32 v76, v79, v79
	v_fmac_f32_e32 v66, v68, v68
	v_mul_f32_e32 v68, v71, v71
	v_fmac_f32_e32 v76, v78, v78
	v_mul_f32_e32 v73, v73, v73
	v_fmac_f32_e32 v68, v70, v70
	v_mul_f32_e32 v65, v65, v65
	v_add_f32_e32 v74, v74, v76
	v_fmac_f32_e32 v73, v72, v72
	v_add_f32_e32 v66, v66, v68
	v_fmac_f32_e32 v65, v64, v64
	v_add_f32_e32 v72, v74, v73
	v_add_f32_e32 v64, v66, v65
	v_add_f32_e32 v72, v75, v72
	v_add_f32_e32 v64, v67, v64
	v_or_b32_e32 v80, 48, v144
	v_mov_b32_dpp v82, v86 row_ror:8 row_mask:0xf bank_mask:0xf
	v_add_f32_e32 v68, v72, v64
	v_mov_b32_dpp v90, v81 row_ror:8 row_mask:0xf bank_mask:0xf
	v_cndmask_b32_e64 v82, v82, v81, s[6:7]
	v_sub_u32_e32 v81, v80, v146
	ds_bpermute_b32 v69, v114, v68
	v_mov_b32_dpp v91, v83 row_ror:8 row_mask:0xf bank_mask:0xf
	v_cndmask_b32_e64 v86, v86, v90, s[6:7]
	v_add_u32_e32 v90, v81, v148
	v_mov_b32_dpp v94, v87 row_ror:8 row_mask:0xf bank_mask:0xf
	v_cndmask_b32_e64 v87, v87, v91, s[6:7]
	v_ashrrev_i32_e32 v91, 31, v90
	v_lshlrev_b64 v[64:65], 12, v[90:91]
	v_lshl_add_u64 v[64:65], s[10:11], 0, v[64:65]
	v_lshl_add_u64 v[66:67], v[142:143], 1, v[64:65]
	s_waitcnt lgkmcnt(0)
	v_add_f32_e32 v64, v68, v69
	ds_bpermute_b32 v65, v115, v64
	v_mov_b32_dpp v95, v88 row_ror:8 row_mask:0xf bank_mask:0xf
	v_mov_b32_dpp v96, v89 row_ror:8 row_mask:0xf bank_mask:0xf
	v_mov_b32_dpp v92, v84 row_ror:8 row_mask:0xf bank_mask:0xf
	v_mov_b32_dpp v93, v85 row_ror:8 row_mask:0xf bank_mask:0xf
	v_cndmask_b32_e64 v83, v94, v83, s[6:7]
	v_cndmask_b32_e64 v84, v95, v84, s[6:7]
	v_cndmask_b32_e64 v85, v96, v85, s[6:7]
	global_store_dwordx4 v[66:67], v[82:85], off
	v_add_co_u32_e32 v66, vcc, s73, v66
	v_cndmask_b32_e64 v88, v88, v92, s[6:7]
	v_cndmask_b32_e64 v89, v89, v93, s[6:7]
	v_addc_co_u32_e32 v67, vcc, 0, v67, vcc
	global_store_dwordx4 v[66:67], v[86:89], off
	s_and_saveexec_b64 s[44:45], s[8:9]
	s_cbranch_execz .LBB0_654
	v_ashrrev_i32_e32 v81, 31, v80
	s_waitcnt lgkmcnt(0)
	v_add_f32_e32 v66, v64, v65
	v_lshl_add_u64 v[64:65], v[80:81], 2, s[12:13]
	global_atomic_add_f32 v[64:65], v66, off
.LBB0_654:
	s_or_b64 exec, exec, s[44:45]
	s_waitcnt lgkmcnt(0)
	v_cvt_pk_bf16_f32 v65, v60, v61
	v_cvt_pk_bf16_f32 v67, v62, v63
	v_cvt_pk_bf16_f32 v68, v56, v57
	v_cvt_pk_bf16_f32 v69, v58, v59
	v_cvt_pk_bf16_f32 v70, v52, v53
	v_cvt_pk_bf16_f32 v71, v54, v55
	v_cvt_pk_bf16_f32 v72, v48, v49
	v_cvt_pk_bf16_f32 v73, v50, v51
	v_mul_f32_e32 v59, v59, v59
	v_mul_f32_e32 v51, v51, v51
	v_fmac_f32_e32 v59, v58, v58
	v_mul_f32_e32 v58, v61, v61
	v_fmac_f32_e32 v51, v50, v50
	v_mul_f32_e32 v50, v53, v53
	v_fmac_f32_e32 v58, v60, v60
	v_mul_f32_e32 v60, v63, v63
	v_fmac_f32_e32 v50, v52, v52
	v_mul_f32_e32 v52, v55, v55
	v_fmac_f32_e32 v60, v62, v62
	v_mul_f32_e32 v57, v57, v57
	v_fmac_f32_e32 v52, v54, v54
	v_mul_f32_e32 v49, v49, v49
	v_add_f32_e32 v58, v58, v60
	v_fmac_f32_e32 v57, v56, v56
	v_add_f32_e32 v50, v50, v52
	v_fmac_f32_e32 v49, v48, v48
	v_add_f32_e32 v56, v58, v57
	v_add_f32_e32 v48, v50, v49
	v_add_f32_e32 v56, v59, v56
	v_add_f32_e32 v48, v51, v48
	v_add_u32_e32 v64, 0x80, v144
	v_mov_b32_dpp v66, v70 row_ror:8 row_mask:0xf bank_mask:0xf
	v_add_f32_e32 v52, v56, v48
	v_mov_b32_dpp v74, v65 row_ror:8 row_mask:0xf bank_mask:0xf
	v_cndmask_b32_e64 v66, v66, v65, s[6:7]
	v_sub_u32_e32 v65, v64, v146
	ds_bpermute_b32 v53, v114, v52
	v_mov_b32_dpp v75, v67 row_ror:8 row_mask:0xf bank_mask:0xf
	v_cndmask_b32_e64 v70, v70, v74, s[6:7]
	v_add_u32_e32 v74, v65, v148
	v_mov_b32_dpp v78, v71 row_ror:8 row_mask:0xf bank_mask:0xf
	v_cndmask_b32_e64 v71, v71, v75, s[6:7]
	v_ashrrev_i32_e32 v75, 31, v74
	v_lshlrev_b64 v[48:49], 12, v[74:75]
	v_lshl_add_u64 v[48:49], s[10:11], 0, v[48:49]
	v_lshl_add_u64 v[50:51], v[142:143], 1, v[48:49]
	s_waitcnt lgkmcnt(0)
	v_add_f32_e32 v48, v52, v53
	ds_bpermute_b32 v49, v115, v48
	v_mov_b32_dpp v79, v72 row_ror:8 row_mask:0xf bank_mask:0xf
	v_mov_b32_dpp v80, v73 row_ror:8 row_mask:0xf bank_mask:0xf
	v_mov_b32_dpp v76, v68 row_ror:8 row_mask:0xf bank_mask:0xf
	v_mov_b32_dpp v77, v69 row_ror:8 row_mask:0xf bank_mask:0xf
	v_cndmask_b32_e64 v67, v78, v67, s[6:7]
	v_cndmask_b32_e64 v68, v79, v68, s[6:7]
	v_cndmask_b32_e64 v69, v80, v69, s[6:7]
	global_store_dwordx4 v[50:51], v[66:69], off
	v_add_co_u32_e32 v50, vcc, s73, v50
	v_cndmask_b32_e64 v72, v72, v76, s[6:7]
	v_cndmask_b32_e64 v73, v73, v77, s[6:7]
	v_addc_co_u32_e32 v51, vcc, 0, v51, vcc
	global_store_dwordx4 v[50:51], v[70:73], off
	s_and_saveexec_b64 s[44:45], s[8:9]
	s_cbranch_execz .LBB0_656
	v_ashrrev_i32_e32 v65, 31, v64
	s_waitcnt lgkmcnt(0)
	v_add_f32_e32 v50, v48, v49
	v_lshl_add_u64 v[48:49], v[64:65], 2, s[12:13]
	global_atomic_add_f32 v[48:49], v50, off
; __device__ __forceinline__ unsigned cvt_pk_bf16(float lo, float hi) { unsigned r; asm volatile("v_cvt_pk_bf16_f32 %0, %1, %2" : "=v"(r) : "v"(lo), "v"(hi)); return r; }
; __device__ __forceinline__ unsigned dpp_ror8(unsigned x) { return (unsigned)__builtin_amdgcn_update_dpp(0, (int)x, 0x128, 0xf, 0xf, false); }
; __device__ __forceinline__ void store_pair_lines(bf16_t* O, int ldc, int row, int fr, int col0, u32x4 wA, u32x4 wB) {
;     const u32x4 sA = {dpp_ror8(wA.x), dpp_ror8(wA.y), dpp_ror8(wA.z), dpp_ror8(wA.w)}, sB = {dpp_ror8(wB.x), dpp_ror8(wB.y), dpp_ror8(wB.z), dpp_ror8(wB.w)};
;     const bool lo = fr < 8;
;     const u32x4 o1 = lo ? wA : sB, o2 = lo ? sA : wB;
;     const int r1 = row - fr + (fr & 7), cb = col0 + (lo ? 0 : 8);
;     *(u32x4*)(O + (size_t)r1 * ldc + cb) = o1;
;     *(u32x4*)(O + (size_t)(r1 + 8) * ldc + cb) = o2;
;     __device__ __forceinline__ void operator()(const f32x4 (&acc)[2][2][4][2], const Unit& u, int wr, int wc, int fr, int fq) const {
;     ...
;             for (int m = 0; m < 4; ++m) { const int row = row0 + ai * HALF + m * 16;
;                 const float rs = ssin ? __builtin_amdgcn_rsqf(ssin[row] * (1.f / D) + EPS) : 1.0f; float sq = 0.f; u32x4 w[2];
; #pragma unroll
;                 for (int bj = 0; bj < 2; ++bj) { f32x4 v0 = acc[ai][bj][m][0] * rs, v1 = acc[ai][bj][m][1] * rs;
;                     if (ACT == 1) {
; #pragma unroll
;                         for (int j = 0; j < 4; ++j) { const float a = fmaxf(v0[j], 0.f), b = fmaxf(v1[j], 0.f); v0[j] = a * a; v1[j] = b * b; } }
;                     sq += (v0[0] * v0[0] + v0[1] * v0[1]) + (v0[2] * v0[2] + v0[3] * v0[3]) + (v1[0] * v1[0] + v1[1] * v1[1]) + (v1[2] * v1[2] + v1[3] * v1[3]);
;                     w[bj].x = cvt_pk_bf16(v0[0], v0[1]); w[bj].y = cvt_pk_bf16(v0[2], v0[3]); w[bj].z = cvt_pk_bf16(v1[0], v1[1]); w[bj].w = cvt_pk_bf16(v1[2], v1[3]); }
;                 store_pair_lines(O, ldc, row, fr, col0, w[0], w[1]);
;                 if (ssout) { sq += __shfl_xor(sq, 16); sq += __shfl_xor(sq, 32); if (fq == 0) unsafeAtomicAdd(ssout + row, sq); } }
.LBB0_656:
	s_or_b64 exec, exec, s[44:45]
	s_waitcnt lgkmcnt(0)
	v_cvt_pk_bf16_f32 v49, v44, v45
	v_cvt_pk_bf16_f32 v51, v46, v47
	v_cvt_pk_bf16_f32 v52, v40, v41
	v_cvt_pk_bf16_f32 v53, v42, v43
	v_cvt_pk_bf16_f32 v54, v36, v37
	v_cvt_pk_bf16_f32 v55, v38, v39
	v_cvt_pk_bf16_f32 v56, v32, v33
	v_cvt_pk_bf16_f32 v57, v34, v35
	v_mul_f32_e32 v43, v43, v43
	v_mul_f32_e32 v35, v35, v35
	v_fmac_f32_e32 v43, v42, v42
	v_mul_f32_e32 v42, v45, v45
	v_fmac_f32_e32 v35, v34, v34
	v_mul_f32_e32 v34, v37, v37
	v_fmac_f32_e32 v42, v44, v44
	v_mul_f32_e32 v44, v47, v47
	v_fmac_f32_e32 v34, v36, v36
	v_mul_f32_e32 v36, v39, v39
	v_fmac_f32_e32 v44, v46, v46
	v_mul_f32_e32 v41, v41, v41
	v_fmac_f32_e32 v36, v38, v38
	v_mul_f32_e32 v33, v33, v33
	v_add_f32_e32 v42, v42, v44
	v_fmac_f32_e32 v41, v40, v40
	v_add_f32_e32 v34, v34, v36
	v_fmac_f32_e32 v33, v32, v32
	v_add_f32_e32 v40, v42, v41
	v_add_f32_e32 v32, v34, v33
	v_add_f32_e32 v40, v43, v40
	v_add_f32_e32 v32, v35, v32
	v_add_u32_e32 v48, 0x90, v144
	v_mov_b32_dpp v50, v54 row_ror:8 row_mask:0xf bank_mask:0xf
	v_add_f32_e32 v36, v40, v32
	v_mov_b32_dpp v58, v49 row_ror:8 row_mask:0xf bank_mask:0xf
	v_cndmask_b32_e64 v50, v50, v49, s[6:7]
	v_sub_u32_e32 v49, v48, v146
	ds_bpermute_b32 v37, v114, v36
	v_mov_b32_dpp v59, v51 row_ror:8 row_mask:0xf bank_mask:0xf
	v_cndmask_b32_e64 v54, v54, v58, s[6:7]
	v_add_u32_e32 v58, v49, v148
	v_mov_b32_dpp v62, v55 row_ror:8 row_mask:0xf bank_mask:0xf
	v_cndmask_b32_e64 v55, v55, v59, s[6:7]
	v_ashrrev_i32_e32 v59, 31, v58
	v_lshlrev_b64 v[32:33], 12, v[58:59]
	v_lshl_add_u64 v[32:33], s[10:11], 0, v[32:33]
	v_lshl_add_u64 v[34:35], v[142:143], 1, v[32:33]
	s_waitcnt lgkmcnt(0)
	v_add_f32_e32 v32, v36, v37
	ds_bpermute_b32 v33, v115, v32
	v_mov_b32_dpp v63, v56 row_ror:8 row_mask:0xf bank_mask:0xf
	v_mov_b32_dpp v64, v57 row_ror:8 row_mask:0xf bank_mask:0xf
	v_mov_b32_dpp v60, v52 row_ror:8 row_mask:0xf bank_mask:0xf
	v_mov_b32_dpp v61, v53 row_ror:8 row_mask:0xf bank_mask:0xf
	v_cndmask_b32_e64 v51, v62, v51, s[6:7]
	v_cndmask_b32_e64 v52, v63, v52, s[6:7]
	v_cndmask_b32_e64 v53, v64, v53, s[6:7]
	global_store_dwordx4 v[34:35], v[50:53], off
	v_add_co_u32_e32 v34, vcc, s73, v34
	v_cndmask_b32_e64 v56, v56, v60, s[6:7]
	v_cndmask_b32_e64 v57, v57, v61, s[6:7]
	v_addc_co_u32_e32 v35, vcc, 0, v35, vcc
	global_store_dwordx4 v[34:35], v[54:57], off
	s_and_saveexec_b64 s[44:45], s[8:9]
	s_cbranch_execz .LBB0_658
	v_ashrrev_i32_e32 v49, 31, v48
	s_waitcnt lgkmcnt(0)
	v_add_f32_e32 v34, v32, v33
	v_lshl_add_u64 v[32:33], v[48:49], 2, s[12:13]
	global_atomic_add_f32 v[32:33], v34, off
; __device__ __forceinline__ unsigned cvt_pk_bf16(float lo, float hi) { unsigned r; asm volatile("v_cvt_pk_bf16_f32 %0, %1, %2" : "=v"(r) : "v"(lo), "v"(hi)); return r; }
; __device__ __forceinline__ unsigned dpp_ror8(unsigned x) { return (unsigned)__builtin_amdgcn_update_dpp(0, (int)x, 0x128, 0xf, 0xf, false); }
; __device__ __forceinline__ void store_pair_lines(bf16_t* O, int ldc, int row, int fr, int col0, u32x4 wA, u32x4 wB) {
;     const u32x4 sA = {dpp_ror8(wA.x), dpp_ror8(wA.y), dpp_ror8(wA.z), dpp_ror8(wA.w)}, sB = {dpp_ror8(wB.x), dpp_ror8(wB.y), dpp_ror8(wB.z), dpp_ror8(wB.w)};
;     const bool lo = fr < 8;
;     const u32x4 o1 = lo ? wA : sB, o2 = lo ? sA : wB;
;     const int r1 = row - fr + (fr & 7), cb = col0 + (lo ? 0 : 8);
;     *(u32x4*)(O + (size_t)r1 * ldc + cb) = o1;
;     *(u32x4*)(O + (size_t)(r1 + 8) * ldc + cb) = o2;
;     __device__ __forceinline__ void operator()(const f32x4 (&acc)[2][2][4][2], const Unit& u, int wr, int wc, int fr, int fq) const {
;     ...
;             for (int m = 0; m < 4; ++m) { const int row = row0 + ai * HALF + m * 16;
;                 const float rs = ssin ? __builtin_amdgcn_rsqf(ssin[row] * (1.f / D) + EPS) : 1.0f; float sq = 0.f; u32x4 w[2];
; #pragma unroll
;                 for (int bj = 0; bj < 2; ++bj) { f32x4 v0 = acc[ai][bj][m][0] * rs, v1 = acc[ai][bj][m][1] * rs;
;                     if (ACT == 1) {
; #pragma unroll
;                         for (int j = 0; j < 4; ++j) { const float a = fmaxf(v0[j], 0.f), b = fmaxf(v1[j], 0.f); v0[j] = a * a; v1[j] = b * b; } }
;                     sq += (v0[0] * v0[0] + v0[1] * v0[1]) + (v0[2] * v0[2] + v0[3] * v0[3]) + (v1[0] * v1[0] + v1[1] * v1[1]) + (v1[2] * v1[2] + v1[3] * v1[3]);
;                     w[bj].x = cvt_pk_bf16(v0[0], v0[1]); w[bj].y = cvt_pk_bf16(v0[2], v0[3]); w[bj].z = cvt_pk_bf16(v1[0], v1[1]); w[bj].w = cvt_pk_bf16(v1[2], v1[3]); }
;                 store_pair_lines(O, ldc, row, fr, col0, w[0], w[1]);
;                 if (ssout) { sq += __shfl_xor(sq, 16); sq += __shfl_xor(sq, 32); if (fq == 0) unsafeAtomicAdd(ssout + row, sq); } }
.LBB0_658:
	s_or_b64 exec, exec, s[44:45]
	s_waitcnt lgkmcnt(0)
	v_cvt_pk_bf16_f32 v33, v28, v29
	v_cvt_pk_bf16_f32 v35, v30, v31
	v_cvt_pk_bf16_f32 v36, v24, v25
	v_cvt_pk_bf16_f32 v37, v26, v27
	v_cvt_pk_bf16_f32 v38, v20, v21
	v_cvt_pk_bf16_f32 v39, v22, v23
	v_cvt_pk_bf16_f32 v40, v16, v17
	v_cvt_pk_bf16_f32 v41, v18, v19
	v_mul_f32_e32 v27, v27, v27
	v_mul_f32_e32 v19, v19, v19
	v_fmac_f32_e32 v27, v26, v26
	v_mul_f32_e32 v26, v29, v29
	v_fmac_f32_e32 v19, v18, v18
	v_mul_f32_e32 v18, v21, v21
	v_fmac_f32_e32 v26, v28, v28
	v_mul_f32_e32 v28, v31, v31
	v_fmac_f32_e32 v18, v20, v20
	v_mul_f32_e32 v20, v23, v23
	v_fmac_f32_e32 v28, v30, v30
	v_mul_f32_e32 v25, v25, v25
	v_fmac_f32_e32 v20, v22, v22
	v_mul_f32_e32 v17, v17, v17
	v_add_f32_e32 v26, v26, v28
	v_fmac_f32_e32 v25, v24, v24
	v_add_f32_e32 v18, v18, v20
	v_fmac_f32_e32 v17, v16, v16
	v_add_f32_e32 v24, v26, v25
	v_add_f32_e32 v16, v18, v17
	v_add_f32_e32 v24, v27, v24
	v_add_f32_e32 v16, v19, v16
	v_add_u32_e32 v32, 0xa0, v144
	v_mov_b32_dpp v34, v38 row_ror:8 row_mask:0xf bank_mask:0xf
	v_add_f32_e32 v20, v24, v16
	v_mov_b32_dpp v42, v33 row_ror:8 row_mask:0xf bank_mask:0xf
	v_cndmask_b32_e64 v34, v34, v33, s[6:7]
	v_sub_u32_e32 v33, v32, v146
	ds_bpermute_b32 v21, v114, v20
	v_mov_b32_dpp v43, v35 row_ror:8 row_mask:0xf bank_mask:0xf
	v_cndmask_b32_e64 v38, v38, v42, s[6:7]
	v_add_u32_e32 v42, v33, v148
	v_mov_b32_dpp v46, v39 row_ror:8 row_mask:0xf bank_mask:0xf
	v_cndmask_b32_e64 v39, v39, v43, s[6:7]
	v_ashrrev_i32_e32 v43, 31, v42
	v_lshlrev_b64 v[16:17], 12, v[42:43]
	v_lshl_add_u64 v[16:17], s[10:11], 0, v[16:17]
	v_lshl_add_u64 v[18:19], v[142:143], 1, v[16:17]
	s_waitcnt lgkmcnt(0)
	v_add_f32_e32 v16, v20, v21
	ds_bpermute_b32 v17, v115, v16
	v_mov_b32_dpp v47, v40 row_ror:8 row_mask:0xf bank_mask:0xf
	v_mov_b32_dpp v48, v41 row_ror:8 row_mask:0xf bank_mask:0xf
	v_mov_b32_dpp v44, v36 row_ror:8 row_mask:0xf bank_mask:0xf
	v_mov_b32_dpp v45, v37 row_ror:8 row_mask:0xf bank_mask:0xf
	v_cndmask_b32_e64 v35, v46, v35, s[6:7]
	v_cndmask_b32_e64 v36, v47, v36, s[6:7]
	v_cndmask_b32_e64 v37, v48, v37, s[6:7]
	global_store_dwordx4 v[18:19], v[34:37], off
	v_add_co_u32_e32 v18, vcc, s73, v18
	v_cndmask_b32_e64 v40, v40, v44, s[6:7]
	v_cndmask_b32_e64 v41, v41, v45, s[6:7]
	v_addc_co_u32_e32 v19, vcc, 0, v19, vcc
	global_store_dwordx4 v[18:19], v[38:41], off
	s_and_saveexec_b64 s[44:45], s[8:9]
	s_cbranch_execz .LBB0_660
	v_ashrrev_i32_e32 v33, 31, v32
	s_waitcnt lgkmcnt(0)
	v_add_f32_e32 v18, v16, v17
	v_lshl_add_u64 v[16:17], v[32:33], 2, s[12:13]
	global_atomic_add_f32 v[16:17], v18, off
.LBB0_660:
	s_or_b64 exec, exec, s[44:45]
	s_waitcnt lgkmcnt(0)
	v_cvt_pk_bf16_f32 v17, v12, v13
	v_cvt_pk_bf16_f32 v19, v14, v15
	v_cvt_pk_bf16_f32 v20, v8, v9
	v_cvt_pk_bf16_f32 v21, v10, v11
	v_cvt_pk_bf16_f32 v22, v4, v5
	v_cvt_pk_bf16_f32 v23, v6, v7
	v_cvt_pk_bf16_f32 v24, v0, v1
	v_cvt_pk_bf16_f32 v25, v2, v3
	v_mul_f32_e32 v11, v11, v11
	v_mul_f32_e32 v3, v3, v3
	v_fmac_f32_e32 v11, v10, v10
	v_mul_f32_e32 v10, v13, v13
	v_fmac_f32_e32 v3, v2, v2
	v_mul_f32_e32 v2, v5, v5
	v_fmac_f32_e32 v10, v12, v12
	v_mul_f32_e32 v12, v15, v15
	v_fmac_f32_e32 v2, v4, v4
	v_mul_f32_e32 v4, v7, v7
	v_fmac_f32_e32 v12, v14, v14
	v_mul_f32_e32 v9, v9, v9
	v_fmac_f32_e32 v4, v6, v6
	v_mul_f32_e32 v1, v1, v1
	v_add_f32_e32 v10, v10, v12
	v_fmac_f32_e32 v9, v8, v8
	v_add_f32_e32 v2, v2, v4
	v_fmac_f32_e32 v1, v0, v0
	v_add_f32_e32 v8, v10, v9
	v_add_f32_e32 v0, v2, v1
	v_add_f32_e32 v8, v11, v8
	v_add_f32_e32 v0, v3, v0
	v_add_u32_e32 v16, 0xb0, v144
	v_mov_b32_dpp v18, v22 row_ror:8 row_mask:0xf bank_mask:0xf
	v_add_f32_e32 v4, v8, v0
	v_mov_b32_dpp v26, v17 row_ror:8 row_mask:0xf bank_mask:0xf
	v_cndmask_b32_e64 v18, v18, v17, s[6:7]
	v_sub_u32_e32 v17, v16, v146
	ds_bpermute_b32 v5, v114, v4
	v_mov_b32_dpp v27, v19 row_ror:8 row_mask:0xf bank_mask:0xf
	v_cndmask_b32_e64 v22, v22, v26, s[6:7]
	v_add_u32_e32 v26, v17, v148
	v_mov_b32_dpp v30, v23 row_ror:8 row_mask:0xf bank_mask:0xf
	v_cndmask_b32_e64 v23, v23, v27, s[6:7]
	v_ashrrev_i32_e32 v27, 31, v26
	v_lshlrev_b64 v[0:1], 12, v[26:27]
	v_lshl_add_u64 v[0:1], s[10:11], 0, v[0:1]
	v_lshl_add_u64 v[2:3], v[142:143], 1, v[0:1]
	s_waitcnt lgkmcnt(0)
	v_add_f32_e32 v0, v4, v5
	ds_bpermute_b32 v1, v115, v0
	v_mov_b32_dpp v31, v24 row_ror:8 row_mask:0xf bank_mask:0xf
	v_mov_b32_dpp v32, v25 row_ror:8 row_mask:0xf bank_mask:0xf
	v_mov_b32_dpp v28, v20 row_ror:8 row_mask:0xf bank_mask:0xf
	v_mov_b32_dpp v29, v21 row_ror:8 row_mask:0xf bank_mask:0xf
	v_cndmask_b32_e64 v19, v30, v19, s[6:7]
	v_cndmask_b32_e64 v20, v31, v20, s[6:7]
	v_cndmask_b32_e64 v21, v32, v21, s[6:7]
	global_store_dwordx4 v[2:3], v[18:21], off
	v_add_co_u32_e32 v2, vcc, s73, v2
	v_cndmask_b32_e64 v24, v24, v28, s[6:7]
	v_cndmask_b32_e64 v25, v25, v29, s[6:7]
	v_addc_co_u32_e32 v3, vcc, 0, v3, vcc
	global_store_dwordx4 v[2:3], v[22:25], off
	s_and_saveexec_b64 s[44:45], s[8:9]
	s_cbranch_execz .LBB0_639
	v_ashrrev_i32_e32 v17, 31, v16
	s_waitcnt lgkmcnt(0)
	v_add_f32_e32 v2, v0, v1
	v_lshl_add_u64 v[0:1], v[16:17], 2, s[12:13]
	global_atomic_add_f32 v[0:1], v2, off
	s_branch .LBB0_639

; #define PG8_STAGE(bufoff, gbase, voff) do { _Pragma("unroll") for (int _i = 0; _i < 2; ++_i) \
;         __builtin_amdgcn_global_load_lds((const unsigned*)((const char*)(gbase) + (voff)[_i]), (LAS unsigned*)(lds + (bufoff) + ldsw + _i * 8192), 16, 0, 0); } while (0)
; #define PG8_LDA(dst, b, h) do { _Pragma("unroll") for (int m = 0; m < 4; ++m) _Pragma("unroll") for (int k = 0; k < 2; ++k) dst[m][k] = *(const LAS bf16x8*)(lds + PG8_SA(b, h) + aoff + m * 2048 + k * 1024); } while (0)
; #define PG8_LDB(dst, b, h) do { _Pragma("unroll") for (int n = 0; n < 2; ++n) _Pragma("unroll") for (int k = 0; k < 2; ++k) dst[n][k] = *(const LAS bf16x8*)(lds + PG8_SB(b, h) + boff + n * 2048 + k * 1024); } while (0)
; #define PG8_MMA(ai, bj, At, Bt) do { __builtin_amdgcn_s_setprio(1); _Pragma("unroll") for (int m = 0; m < 4; ++m) _Pragma("unroll") for (int n = 0; n < 2; ++n) _Pragma("unroll") for (int k = 0; k < 2; ++k) \
;         acc[ai][bj][m][n] = __builtin_amdgcn_mfma_f32_16x16x32_bf16(Bt[n][k], At[m][k], acc[ai][bj][m][n], 0, 0, 0); __builtin_amdgcn_s_setprio(0); } while (0)
; #define PG8_WAIT_V(n) asm volatile("s_waitcnt vmcnt(" #n ")" ::: "memory")
; #define PG8_WAIT_L(n) asm volatile("s_waitcnt lgkmcnt(" #n ")" ::: "memory")
; #define PG8_BAR __builtin_amdgcn_s_barrier()
; #define PG8_SCHED __builtin_amdgcn_sched_barrier(0)
; template <class Epi>
; __device__ __forceinline__ void gemm_phase(LAS unsigned char* lds, const Gemm g, const StaticOrder& S, const Epi& E) {
;     ...
;             PG8_LDB(B0, 0, 0); PG8_SCHED; PG8_LDA(At, 0, 0); PG8_STAGE(PG8_SA(1, 1), a1 + hstep, voffA);
;             PG8_WAIT_L(8); PG8_BAR; PG8_WAIT_L(0); PG8_MMA(0, 0, At, B0); PG8_BAR; PG8_SCHED;
;             PG8_LDB(B1, 0, 1); PG8_STAGE(PG8_SB(0, 0), b2, voffB0);
;             PG8_BAR; PG8_WAIT_L(0); PG8_MMA(0, 1, At, B1); PG8_BAR;
;             PG8_LDA(At, 0, 1); PG8_STAGE(PG8_SA(0, 0), a2, voffA);
;             PG8_BAR; PG8_WAIT_L(0); PG8_MMA(1, 0, At, B0); PG8_BAR; PG8_SCHED;
;             PG8_STAGE(PG8_SB(0, 1), b2, voffB1);
;             PG8_WAIT_V(6); PG8_BAR; PG8_MMA(1, 1, At, B1); PG8_BAR;
.LBB0_733:
	ds_read_b128 v[160:163], v157
	ds_read_b128 v[164:167], v157 offset:1024
	ds_read_b128 v[168:171], v157 offset:2048
	ds_read_b128 v[172:175], v157 offset:3072
	s_add_u32 s33, s46, 0xfff80080
	s_addc_u32 s48, s47, -1
	s_cmp_eq_u32 s74, 28
	s_cselect_b32 s49, s37, s48
	s_cselect_b32 s48, s70, s33
	s_cselect_b32 s51, s19, s73
	s_cselect_b32 s50, s71, s72
	v_lshl_add_u64 v[200:201], s[46:47], 0, v[140:141]
	s_add_i32 m0, s45, 0xc000
	ds_read_b128 v[176:179], v158
	ds_read_b128 v[180:183], v158 offset:1024
	ds_read_b128 v[184:187], v158 offset:2048
	ds_read_b128 v[188:191], v158 offset:3072
	ds_read_b128 v[192:195], v158 offset:4096
	ds_read_b128 v[196:199], v158 offset:5120
	ds_read_b128 v[204:207], v158 offset:6144
	ds_read_b128 v[208:211], v158 offset:7168
	global_load_lds_dwordx4 v[200:201], off
	v_lshl_add_u64 v[200:201], s[46:47], 0, v[142:143]
	s_add_i32 m0, s45, 0xe000
	s_nop 0
	global_load_lds_dwordx4 v[200:201], off
	s_waitcnt lgkmcnt(8)
	s_barrier
	s_waitcnt lgkmcnt(0)
	v_mfma_f32_16x16x32_bf16 v[124:127], v[160:163], v[176:179], v[124:127]
	v_mfma_f32_16x16x32_bf16 v[120:123], v[168:171], v[176:179], v[120:123]
	v_mfma_f32_16x16x32_bf16 v[108:111], v[160:163], v[184:187], v[108:111]
	v_mfma_f32_16x16x32_bf16 v[104:107], v[168:171], v[184:187], v[104:107]
	v_mfma_f32_16x16x32_bf16 v[92:95], v[160:163], v[192:195], v[92:95]
	v_mfma_f32_16x16x32_bf16 v[88:91], v[168:171], v[192:195], v[88:91]
	v_mfma_f32_16x16x32_bf16 v[76:79], v[160:163], v[204:207], v[76:79]
	v_mfma_f32_16x16x32_bf16 v[72:75], v[168:171], v[204:207], v[72:75]
	v_mfma_f32_16x16x32_bf16 v[124:127], v[164:167], v[180:183], v[124:127]
	v_mfma_f32_16x16x32_bf16 v[120:123], v[172:175], v[180:183], v[120:123]
	v_mfma_f32_16x16x32_bf16 v[108:111], v[164:167], v[188:191], v[108:111]
	v_mfma_f32_16x16x32_bf16 v[104:107], v[172:175], v[188:191], v[104:107]
	v_mfma_f32_16x16x32_bf16 v[92:95], v[164:167], v[196:199], v[92:95]
	v_mfma_f32_16x16x32_bf16 v[88:91], v[172:175], v[196:199], v[88:91]
	v_mfma_f32_16x16x32_bf16 v[76:79], v[164:167], v[208:211], v[76:79]
	v_mfma_f32_16x16x32_bf16 v[72:75], v[172:175], v[208:211], v[72:75]
	s_barrier
	s_add_i32 s33, s66, s56
	v_lshl_add_u64 v[200:201], s[50:51], 0, v[130:131]
	s_mov_b32 m0, s33
	ds_read_b128 v[212:215], v159
	ds_read_b128 v[216:219], v159 offset:1024
	ds_read_b128 v[220:223], v159 offset:2048
	ds_read_b128 v[224:227], v159 offset:3072
	global_load_lds_dwordx4 v[200:201], off
	v_lshl_add_u64 v[228:229], s[50:51], 0, v[136:137]
	s_add_i32 m0, s33, 0x2000
	s_nop 0
	global_load_lds_dwordx4 v[228:229], off
	s_barrier
	s_waitcnt lgkmcnt(0)
	v_mfma_f32_16x16x32_bf16 v[116:119], v[212:215], v[176:179], v[116:119]
	v_mfma_f32_16x16x32_bf16 v[112:115], v[220:223], v[176:179], v[112:115]
	v_mfma_f32_16x16x32_bf16 v[100:103], v[212:215], v[184:187], v[100:103]
	v_mfma_f32_16x16x32_bf16 v[96:99], v[220:223], v[184:187], v[96:99]
	v_mfma_f32_16x16x32_bf16 v[84:87], v[212:215], v[192:195], v[84:87]
	v_mfma_f32_16x16x32_bf16 v[80:83], v[220:223], v[192:195], v[80:83]
	v_mfma_f32_16x16x32_bf16 v[68:71], v[212:215], v[204:207], v[68:71]
	v_mfma_f32_16x16x32_bf16 v[64:67], v[220:223], v[204:207], v[64:67]
	v_mfma_f32_16x16x32_bf16 v[116:119], v[216:219], v[180:183], v[116:119]
	v_mfma_f32_16x16x32_bf16 v[112:115], v[224:227], v[180:183], v[112:115]
	v_mfma_f32_16x16x32_bf16 v[100:103], v[216:219], v[188:191], v[100:103]
	v_mfma_f32_16x16x32_bf16 v[96:99], v[224:227], v[188:191], v[96:99]
	v_mfma_f32_16x16x32_bf16 v[84:87], v[216:219], v[196:199], v[84:87]
	v_mfma_f32_16x16x32_bf16 v[80:83], v[224:227], v[196:199], v[80:83]
	v_mfma_f32_16x16x32_bf16 v[68:71], v[216:219], v[208:211], v[68:71]
	v_mfma_f32_16x16x32_bf16 v[64:67], v[224:227], v[208:211], v[64:67]
	s_mov_b32 m0, s45
	v_lshl_add_u64 v[230:231], s[48:49], 0, v[128:129]
	s_barrier
	ds_read_b128 v[176:179], v158 offset:16384
	ds_read_b128 v[180:183], v158 offset:17408
	ds_read_b128 v[184:187], v158 offset:18432
	ds_read_b128 v[188:191], v158 offset:19456
	ds_read_b128 v[192:195], v158 offset:20480
	ds_read_b128 v[196:199], v158 offset:21504
	ds_read_b128 v[204:207], v158 offset:22528
	ds_read_b128 v[208:211], v158 offset:23552
	global_load_lds_dwordx4 v[230:231], off
	v_lshl_add_u64 v[232:233], s[48:49], 0, v[134:135]
	s_mov_b32 m0, s57
	s_nop 0
	global_load_lds_dwordx4 v[232:233], off
	s_barrier
	s_waitcnt lgkmcnt(0)
	v_mfma_f32_16x16x32_bf16 v[60:63], v[160:163], v[176:179], v[60:63]
	v_mfma_f32_16x16x32_bf16 v[56:59], v[168:171], v[176:179], v[56:59]
	v_mfma_f32_16x16x32_bf16 v[44:47], v[160:163], v[184:187], v[44:47]
	v_mfma_f32_16x16x32_bf16 v[40:43], v[168:171], v[184:187], v[40:43]
	v_mfma_f32_16x16x32_bf16 v[28:31], v[160:163], v[192:195], v[28:31]
	v_mfma_f32_16x16x32_bf16 v[24:27], v[168:171], v[192:195], v[24:27]
	v_mfma_f32_16x16x32_bf16 v[12:15], v[160:163], v[204:207], v[12:15]
	v_mfma_f32_16x16x32_bf16 v[8:11], v[168:171], v[204:207], v[8:11]
	v_mfma_f32_16x16x32_bf16 v[60:63], v[164:167], v[180:183], v[60:63]
	v_mfma_f32_16x16x32_bf16 v[56:59], v[172:175], v[180:183], v[56:59]
	v_mfma_f32_16x16x32_bf16 v[44:47], v[164:167], v[188:191], v[44:47]
	v_mfma_f32_16x16x32_bf16 v[40:43], v[172:175], v[188:191], v[40:43]
	v_mfma_f32_16x16x32_bf16 v[28:31], v[164:167], v[196:199], v[28:31]
	v_mfma_f32_16x16x32_bf16 v[24:27], v[172:175], v[196:199], v[24:27]
	v_mfma_f32_16x16x32_bf16 v[12:15], v[164:167], v[208:211], v[12:15]
	v_mfma_f32_16x16x32_bf16 v[8:11], v[172:175], v[208:211], v[8:11]
	s_barrier
	s_add_i32 s33, s67, s56
	v_lshl_add_u64 v[234:235], s[50:51], 0, v[132:133]
	s_mov_b32 m0, s33
	v_lshl_add_u64 v[236:237], s[50:51], 0, v[138:139]
	global_load_lds_dwordx4 v[234:235], off
	s_add_i32 m0, s33, 0x2000
	s_nop 0
	global_load_lds_dwordx4 v[236:237], off
	s_waitcnt vmcnt(6)
	s_barrier
; #define PG8_STAGE(bufoff, gbase, voff) do { _Pragma("unroll") for (int _i = 0; _i < 2; ++_i) \
;         __builtin_amdgcn_global_load_lds((const unsigned*)((const char*)(gbase) + (voff)[_i]), (LAS unsigned*)(lds + (bufoff) + ldsw + _i * 8192), 16, 0, 0); } while (0)
; #define PG8_LDA(dst, b, h) do { _Pragma("unroll") for (int m = 0; m < 4; ++m) _Pragma("unroll") for (int k = 0; k < 2; ++k) dst[m][k] = *(const LAS bf16x8*)(lds + PG8_SA(b, h) + aoff + m * 2048 + k * 1024); } while (0)
; #define PG8_LDB(dst, b, h) do { _Pragma("unroll") for (int n = 0; n < 2; ++n) _Pragma("unroll") for (int k = 0; k < 2; ++k) dst[n][k] = *(const LAS bf16x8*)(lds + PG8_SB(b, h) + boff + n * 2048 + k * 1024); } while (0)
; #define PG8_WAIT_V(n) asm volatile("s_waitcnt vmcnt(" #n ")" ::: "memory")
; #define PG8_WAIT_L(n) asm volatile("s_waitcnt lgkmcnt(" #n ")" ::: "memory")
; #define PG8_BAR __builtin_amdgcn_s_barrier()
; #define PG8_SCHED __builtin_amdgcn_sched_barrier(0)
; template <class Epi>
; __device__ __forceinline__ void gemm_phase(LAS unsigned char* lds, const Gemm g, const StaticOrder& S, const Epi& E) {
;     ...
;             PG8_LDB(B0, 0, 0); PG8_SCHED; PG8_LDA(At, 0, 0); PG8_STAGE(PG8_SA(1, 1), a1 + hstep, voffA);
;             PG8_WAIT_L(8); PG8_BAR; PG8_WAIT_L(0); PG8_MMA(0, 0, At, B0); PG8_BAR; PG8_SCHED;
;             PG8_LDB(B1, 0, 1); PG8_STAGE(PG8_SB(0, 0), b2, voffB0);
;             PG8_BAR; PG8_WAIT_L(0); PG8_MMA(0, 1, At, B1); PG8_BAR;
;             PG8_LDA(At, 0, 1); PG8_STAGE(PG8_SA(0, 0), a2, voffA);
;             PG8_BAR; PG8_WAIT_L(0); PG8_MMA(1, 0, At, B0); PG8_BAR; PG8_SCHED;
;             PG8_STAGE(PG8_SB(0, 1), b2, voffB1);
;             PG8_WAIT_V(6); PG8_BAR; PG8_MMA(1, 1, At, B1); PG8_BAR;
;             PG8_LDB(B0, 1, 0); PG8_SCHED; PG8_LDA(At, 1, 0); PG8_STAGE(PG8_SA(0, 1), a2 + hstep, voffA);
;             PG8_WAIT_L(8); PG8_BAR; PG8_WAIT_L(0); PG8_MMA(0, 0, At, B0); PG8_BAR; PG8_SCHED;
;             PG8_LDB(B1, 1, 1); PG8_STAGE(PG8_SB(1, 0), b3, voffB0);
;             PG8_BAR; PG8_WAIT_L(0); PG8_MMA(0, 1, At, B1); PG8_BAR;
;             PG8_LDA(At, 1, 1); PG8_STAGE(PG8_SA(1, 0), a3, voffA);
;             PG8_BAR; PG8_WAIT_L(0); PG8_MMA(1, 0, At, B0); PG8_BAR; PG8_SCHED;
;             PG8_STAGE(PG8_SB(1, 1), b3, voffB1);
;             PG8_WAIT_V(6); PG8_BAR; PG8_MMA(1, 1, At, B1); PG8_BAR;
	v_mfma_f32_16x16x32_bf16 v[52:55], v[212:215], v[176:179], v[52:55]
	v_mfma_f32_16x16x32_bf16 v[48:51], v[220:223], v[176:179], v[48:51]
	v_mfma_f32_16x16x32_bf16 v[36:39], v[212:215], v[184:187], v[36:39]
	v_mfma_f32_16x16x32_bf16 v[32:35], v[220:223], v[184:187], v[32:35]
	v_mfma_f32_16x16x32_bf16 v[20:23], v[212:215], v[192:195], v[20:23]
	v_mfma_f32_16x16x32_bf16 v[16:19], v[220:223], v[192:195], v[16:19]
	v_mfma_f32_16x16x32_bf16 v[4:7], v[212:215], v[204:207], v[4:7]
	v_mfma_f32_16x16x32_bf16 v[0:3], v[220:223], v[204:207], v[0:3]
	v_mfma_f32_16x16x32_bf16 v[52:55], v[216:219], v[180:183], v[52:55]
	v_mfma_f32_16x16x32_bf16 v[48:51], v[224:227], v[180:183], v[48:51]
	v_mfma_f32_16x16x32_bf16 v[36:39], v[216:219], v[188:191], v[36:39]
	v_mfma_f32_16x16x32_bf16 v[32:35], v[224:227], v[188:191], v[32:35]
	v_mfma_f32_16x16x32_bf16 v[20:23], v[216:219], v[196:199], v[20:23]
	v_mfma_f32_16x16x32_bf16 v[16:19], v[224:227], v[196:199], v[16:19]
	v_mfma_f32_16x16x32_bf16 v[4:7], v[216:219], v[208:211], v[4:7]
	v_mfma_f32_16x16x32_bf16 v[0:3], v[224:227], v[208:211], v[0:3]
	s_add_i32 s33, 0, 0x18000
	v_add_u32_e32 v172, s33, v147
	s_barrier
	ds_read_b128 v[160:163], v172
	ds_read_b128 v[164:167], v172 offset:1024
	ds_read_b128 v[168:171], v172 offset:2048
	ds_read_b128 v[172:175], v172 offset:3072
	s_add_u32 s48, s48, 0x80000
	s_addc_u32 s49, s49, 0
	s_mov_b32 m0, s58
	v_lshl_add_u64 v[212:213], s[48:49], 0, v[128:129]
	ds_read_b128 v[176:179], v158 offset:32768
	ds_read_b128 v[180:183], v158 offset:33792
	ds_read_b128 v[184:187], v158 offset:34816
	ds_read_b128 v[188:191], v158 offset:35840
	ds_read_b128 v[192:195], v158 offset:36864
	ds_read_b128 v[196:199], v158 offset:37888
	ds_read_b128 v[204:207], v158 offset:38912
	ds_read_b128 v[208:211], v158 offset:39936
	global_load_lds_dwordx4 v[212:213], off
	v_lshl_add_u64 v[212:213], s[48:49], 0, v[134:135]
	s_mov_b32 m0, s59
	s_nop 0
	global_load_lds_dwordx4 v[212:213], off
	s_waitcnt lgkmcnt(8)
	s_barrier
	s_waitcnt lgkmcnt(0)
	v_mfma_f32_16x16x32_bf16 v[124:127], v[160:163], v[176:179], v[124:127]
	v_mfma_f32_16x16x32_bf16 v[120:123], v[168:171], v[176:179], v[120:123]
	v_mfma_f32_16x16x32_bf16 v[108:111], v[160:163], v[184:187], v[108:111]
	v_mfma_f32_16x16x32_bf16 v[104:107], v[168:171], v[184:187], v[104:107]
	v_mfma_f32_16x16x32_bf16 v[92:95], v[160:163], v[192:195], v[92:95]
	v_mfma_f32_16x16x32_bf16 v[88:91], v[168:171], v[192:195], v[88:91]
	v_mfma_f32_16x16x32_bf16 v[76:79], v[160:163], v[204:207], v[76:79]
	v_mfma_f32_16x16x32_bf16 v[72:75], v[168:171], v[204:207], v[72:75]
	v_mfma_f32_16x16x32_bf16 v[124:127], v[164:167], v[180:183], v[124:127]
	v_mfma_f32_16x16x32_bf16 v[120:123], v[172:175], v[180:183], v[120:123]
	v_mfma_f32_16x16x32_bf16 v[108:111], v[164:167], v[188:191], v[108:111]
	v_mfma_f32_16x16x32_bf16 v[104:107], v[172:175], v[188:191], v[104:107]
	v_mfma_f32_16x16x32_bf16 v[92:95], v[164:167], v[196:199], v[92:95]
	v_mfma_f32_16x16x32_bf16 v[88:91], v[172:175], v[196:199], v[88:91]
	v_mfma_f32_16x16x32_bf16 v[76:79], v[164:167], v[208:211], v[76:79]
	v_mfma_f32_16x16x32_bf16 v[72:75], v[172:175], v[208:211], v[72:75]
	s_barrier
	s_add_i32 s48, 0, 0x1c000
	s_add_i32 s33, s33, s56
	v_add_u32_e32 v224, s48, v147
	v_lshl_add_u64 v[200:201], v[200:201], 0, s[16:17]
	s_mov_b32 m0, s33
	ds_read_b128 v[212:215], v224
	ds_read_b128 v[216:219], v224 offset:1024
	ds_read_b128 v[220:223], v224 offset:2048
	ds_read_b128 v[224:227], v224 offset:3072
	global_load_lds_dwordx4 v[200:201], off
	v_lshl_add_u64 v[200:201], v[228:229], 0, s[16:17]
	s_add_i32 m0, s33, 0x2000
	s_nop 0
	global_load_lds_dwordx4 v[200:201], off
	s_barrier
	s_waitcnt lgkmcnt(0)
	v_mfma_f32_16x16x32_bf16 v[116:119], v[212:215], v[176:179], v[116:119]
	v_mfma_f32_16x16x32_bf16 v[112:115], v[220:223], v[176:179], v[112:115]
	v_mfma_f32_16x16x32_bf16 v[100:103], v[212:215], v[184:187], v[100:103]
	v_mfma_f32_16x16x32_bf16 v[96:99], v[220:223], v[184:187], v[96:99]
	v_mfma_f32_16x16x32_bf16 v[84:87], v[212:215], v[192:195], v[84:87]
	v_mfma_f32_16x16x32_bf16 v[80:83], v[220:223], v[192:195], v[80:83]
	v_mfma_f32_16x16x32_bf16 v[68:71], v[212:215], v[204:207], v[68:71]
	v_mfma_f32_16x16x32_bf16 v[64:67], v[220:223], v[204:207], v[64:67]
	v_mfma_f32_16x16x32_bf16 v[116:119], v[216:219], v[180:183], v[116:119]
	v_mfma_f32_16x16x32_bf16 v[112:115], v[224:227], v[180:183], v[112:115]
	v_mfma_f32_16x16x32_bf16 v[100:103], v[216:219], v[188:191], v[100:103]
	v_mfma_f32_16x16x32_bf16 v[96:99], v[224:227], v[188:191], v[96:99]
	v_mfma_f32_16x16x32_bf16 v[84:87], v[216:219], v[196:199], v[84:87]
	v_mfma_f32_16x16x32_bf16 v[80:83], v[224:227], v[196:199], v[80:83]
	v_mfma_f32_16x16x32_bf16 v[68:71], v[216:219], v[208:211], v[68:71]
	v_mfma_f32_16x16x32_bf16 v[64:67], v[224:227], v[208:211], v[64:67]
	s_mov_b32 m0, s61
	v_lshl_add_u64 v[200:201], v[230:231], 0, s[16:17]
	s_barrier
	ds_read_b128 v[176:179], v158 offset:49152
	ds_read_b128 v[180:183], v158 offset:50176
	ds_read_b128 v[184:187], v158 offset:51200
	ds_read_b128 v[188:191], v158 offset:52224
	ds_read_b128 v[192:195], v158 offset:53248
	ds_read_b128 v[196:199], v158 offset:54272
	ds_read_b128 v[204:207], v158 offset:55296
	ds_read_b128 v[208:211], v158 offset:56320
	global_load_lds_dwordx4 v[200:201], off
	v_lshl_add_u64 v[200:201], v[232:233], 0, s[16:17]
	s_mov_b32 m0, s62
	s_nop 0
	global_load_lds_dwordx4 v[200:201], off
	s_barrier
;     __device__ __forceinline__ void operator()(const f32x4 (&acc)[2][2][4][2], const Unit& u, int wr, int wc, int fr, int fq) const {
;     ...
;             for (int m = 0; m < 4; ++m) { const int row = row0 + ai * HALF + m * 16;
;                 const float rs = ssin ? __builtin_amdgcn_rsqf(ssin[row] * (1.f / D) + EPS) : 1.0f; float sq = 0.f; u32x4 w[2];
; #pragma unroll
;                 for (int bj = 0; bj < 2; ++bj) { f32x4 v0 = acc[ai][bj][m][0] * rs, v1 = acc[ai][bj][m][1] * rs;
;                     if (ACT == 1) {
; #pragma unroll
;                         for (int j = 0; j < 4; ++j) { const float a = fmaxf(v0[j], 0.f), b = fmaxf(v1[j], 0.f); v0[j] = a * a; v1[j] = b * b; } }
;                     sq += (v0[0] * v0[0] + v0[1] * v0[1]) + (v0[2] * v0[2] + v0[3] * v0[3]) + (v1[0] * v1[0] + v1[1] * v1[1]) + (v1[2] * v1[2] + v1[3] * v1[3]);
;                     w[bj].x = cvt_pk_bf16(v0[0], v0[1]); w[bj].y = cvt_pk_bf16(v0[2], v0[3]); w[bj].z = cvt_pk_bf16(v1[0], v1[1]); w[bj].w = cvt_pk_bf16(v1[2], v1[3]); }
; template <class Epi>
; __device__ __forceinline__ void gemm_phase(LAS unsigned char* lds, const Gemm g, const StaticOrder& S, const Epi& E) {
;     ...
;             PG8_LDB(B0, 0, 0); PG8_SCHED; PG8_LDA(At, 0, 0); PG8_STAGE(PG8_SA(1, 1), a1 + hstep, voffA);
;             PG8_WAIT_L(8); PG8_BAR; PG8_WAIT_L(0); PG8_MMA(0, 0, At, B0); PG8_BAR; PG8_SCHED;
;             PG8_LDB(B1, 0, 1); PG8_STAGE(PG8_SB(0, 0), b2, voffB0);
;             PG8_BAR; PG8_WAIT_L(0); PG8_MMA(0, 1, At, B1); PG8_BAR;
;             PG8_LDA(At, 0, 1); PG8_STAGE(PG8_SA(0, 0), a2, voffA);
;             PG8_BAR; PG8_WAIT_L(0); PG8_MMA(1, 0, At, B0); PG8_BAR; PG8_SCHED;
;             PG8_STAGE(PG8_SB(0, 1), b2, voffB1);
;             PG8_WAIT_V(6); PG8_BAR; PG8_MMA(1, 1, At, B1); PG8_BAR;
;             PG8_LDB(B0, 1, 0); PG8_SCHED; PG8_LDA(At, 1, 0); PG8_STAGE(PG8_SA(0, 1), a2 + hstep, voffA);
;             PG8_WAIT_L(8); PG8_BAR; PG8_WAIT_L(0); PG8_MMA(0, 0, At, B0); PG8_BAR; PG8_SCHED;
;             PG8_LDB(B1, 1, 1); PG8_STAGE(PG8_SB(1, 0), b3, voffB0);
;             PG8_BAR; PG8_WAIT_L(0); PG8_MMA(0, 1, At, B1); PG8_BAR;
;             PG8_LDA(At, 1, 1); PG8_STAGE(PG8_SA(1, 0), a3, voffA);
;             PG8_BAR; PG8_WAIT_L(0); PG8_MMA(1, 0, At, B0); PG8_BAR; PG8_SCHED;
;             PG8_STAGE(PG8_SB(1, 1), b3, voffB1);
;             PG8_WAIT_V(6); PG8_BAR; PG8_MMA(1, 1, At, B1); PG8_BAR;
	s_waitcnt lgkmcnt(0)
	v_mfma_f32_16x16x32_bf16 v[60:63], v[160:163], v[176:179], v[60:63]
	v_mfma_f32_16x16x32_bf16 v[56:59], v[168:171], v[176:179], v[56:59]
	v_mfma_f32_16x16x32_bf16 v[44:47], v[160:163], v[184:187], v[44:47]
	v_mfma_f32_16x16x32_bf16 v[40:43], v[168:171], v[184:187], v[40:43]
	v_mfma_f32_16x16x32_bf16 v[28:31], v[160:163], v[192:195], v[28:31]
	v_mfma_f32_16x16x32_bf16 v[24:27], v[168:171], v[192:195], v[24:27]
	v_mfma_f32_16x16x32_bf16 v[12:15], v[160:163], v[204:207], v[12:15]
	v_mfma_f32_16x16x32_bf16 v[8:11], v[168:171], v[204:207], v[8:11]
	v_mfma_f32_16x16x32_bf16 v[60:63], v[164:167], v[180:183], v[60:63]
	v_mfma_f32_16x16x32_bf16 v[56:59], v[172:175], v[180:183], v[56:59]
	v_mfma_f32_16x16x32_bf16 v[44:47], v[164:167], v[188:191], v[44:47]
	v_mfma_f32_16x16x32_bf16 v[40:43], v[172:175], v[188:191], v[40:43]
	v_mfma_f32_16x16x32_bf16 v[28:31], v[164:167], v[196:199], v[28:31]
	v_mfma_f32_16x16x32_bf16 v[24:27], v[172:175], v[196:199], v[24:27]
	v_mfma_f32_16x16x32_bf16 v[12:15], v[164:167], v[208:211], v[12:15]
	v_mfma_f32_16x16x32_bf16 v[8:11], v[172:175], v[208:211], v[8:11]
	s_barrier
	s_add_i32 s33, s48, s56
	v_lshl_add_u64 v[160:161], v[234:235], 0, s[16:17]
	s_mov_b32 m0, s33
	s_nop 0
	global_load_lds_dwordx4 v[160:161], off
	v_lshl_add_u64 v[160:161], v[236:237], 0, s[16:17]
	s_add_i32 m0, s33, 0x2000
	s_nop 0
	global_load_lds_dwordx4 v[160:161], off
	s_waitcnt vmcnt(6)
	s_barrier
	v_mfma_f32_16x16x32_bf16 v[52:55], v[212:215], v[176:179], v[52:55]
	v_mfma_f32_16x16x32_bf16 v[48:51], v[220:223], v[176:179], v[48:51]
	v_mfma_f32_16x16x32_bf16 v[36:39], v[212:215], v[184:187], v[36:39]
	v_mfma_f32_16x16x32_bf16 v[32:35], v[220:223], v[184:187], v[32:35]
	v_mfma_f32_16x16x32_bf16 v[20:23], v[212:215], v[192:195], v[20:23]
	v_mfma_f32_16x16x32_bf16 v[16:19], v[220:223], v[192:195], v[16:19]
	v_mfma_f32_16x16x32_bf16 v[4:7], v[212:215], v[204:207], v[4:7]
	v_mfma_f32_16x16x32_bf16 v[0:3], v[220:223], v[204:207], v[0:3]
	v_mfma_f32_16x16x32_bf16 v[52:55], v[216:219], v[180:183], v[52:55]
	v_mfma_f32_16x16x32_bf16 v[48:51], v[224:227], v[180:183], v[48:51]
	v_mfma_f32_16x16x32_bf16 v[36:39], v[216:219], v[188:191], v[36:39]
	v_mfma_f32_16x16x32_bf16 v[32:35], v[224:227], v[188:191], v[32:35]
	v_mfma_f32_16x16x32_bf16 v[20:23], v[216:219], v[196:199], v[20:23]
	v_mfma_f32_16x16x32_bf16 v[16:19], v[224:227], v[196:199], v[16:19]
	v_mfma_f32_16x16x32_bf16 v[4:7], v[216:219], v[208:211], v[4:7]
	v_mfma_f32_16x16x32_bf16 v[0:3], v[224:227], v[208:211], v[0:3]
	s_add_i32 s74, s74, 2
	s_add_u32 s46, s46, 0x100
	s_addc_u32 s47, s47, 0
	s_add_u32 s72, s72, 0x100
	s_addc_u32 s73, s73, 0
	s_cmp_gt_u32 s74, 29
	s_barrier
	s_cbranch_scc0 .LBB0_733
	v_max_f32_e32 v124, 0, v124
	v_max_f32_e32 v120, 0, v120
	v_max_f32_e32 v125, 0, v125
	v_max_f32_e32 v121, 0, v121
	v_max_f32_e32 v122, 0, v122
	v_max_f32_e32 v118, 0, v118
	v_max_f32_e32 v119, 0, v119
	v_mul_f32_e32 v124, v124, v124
	v_mul_f32_e32 v120, v120, v120
	v_mul_f32_e32 v125, v125, v125
	v_mul_f32_e32 v121, v121, v121
	v_max_f32_e32 v126, 0, v126
	v_mul_f32_e32 v122, v122, v122
	v_max_f32_e32 v127, 0, v127
	v_max_f32_e32 v123, 0, v123
	v_max_f32_e32 v116, 0, v116
	v_max_f32_e32 v112, 0, v112
	v_max_f32_e32 v117, 0, v117
	v_max_f32_e32 v113, 0, v113
	v_max_f32_e32 v114, 0, v114
	v_mul_f32_e32 v118, v118, v118
	v_mul_f32_e32 v119, v119, v119
	s_lshl_b32 s19, s44, 8
	v_mul_f32_e32 v126, v126, v126
	v_mul_f32_e32 v127, v127, v127
	v_mul_f32_e32 v123, v123, v123
	v_cvt_pk_bf16_f32 v124, v124, v125
	v_cvt_pk_bf16_f32 v125, v126, v127
	v_cvt_pk_bf16_f32 v120, v120, v121
	v_cvt_pk_bf16_f32 v121, v122, v123
	v_mul_f32_e32 v116, v116, v116
	v_mul_f32_e32 v112, v112, v112
	v_mul_f32_e32 v117, v117, v117
	v_mul_f32_e32 v113, v113, v113
	v_mul_f32_e32 v114, v114, v114
	v_max_f32_e32 v115, 0, v115
	v_cvt_pk_bf16_f32 v122, v116, v117
	v_cvt_pk_bf16_f32 v119, v118, v119
	s_add_i32 s19, s19, s63
	v_mul_f32_e32 v115, v115, v115
	v_cvt_pk_bf16_f32 v112, v112, v113
	v_cvt_pk_bf16_f32 v113, v114, v115
	v_mov_b32_dpp v118, v124 row_ror:8 row_mask:0xf bank_mask:0xf
	v_mov_b32_dpp v123, v125 row_ror:8 row_mask:0xf bank_mask:0xf
	v_mov_b32_dpp v114, v122 row_ror:8 row_mask:0xf bank_mask:0xf
	v_cndmask_b32_e64 v118, v122, v118, s[6:7]
	v_or_b32_e32 v122, s19, v148
	v_lshl_or_b32 v162, s69, 8, v156
	v_mov_b32_dpp v126, v120 row_ror:8 row_mask:0xf bank_mask:0xf
	v_mov_b32_dpp v127, v121 row_ror:8 row_mask:0xf bank_mask:0xf
	v_mov_b32_dpp v115, v119 row_ror:8 row_mask:0xf bank_mask:0xf
	v_mov_b32_dpp v116, v112 row_ror:8 row_mask:0xf bank_mask:0xf
	v_mov_b32_dpp v117, v113 row_ror:8 row_mask:0xf bank_mask:0xf
	v_cndmask_b32_e64 v119, v119, v123, s[6:7]
	v_ashrrev_i32_e32 v123, 31, v122
	v_ashrrev_i32_e32 v163, 31, v162
	v_cndmask_b32_e64 v116, v116, v120, s[6:7]
	v_cndmask_b32_e64 v117, v117, v121, s[6:7]
	v_cndmask_b32_e64 v120, v112, v126, s[6:7]
	v_cndmask_b32_e64 v121, v113, v127, s[6:7]
	v_lshlrev_b64 v[112:113], 14, v[122:123]
	v_cndmask_b32_e64 v114, v114, v124, s[6:7]
	v_cndmask_b32_e64 v115, v115, v125, s[6:7]
	v_lshl_add_u64 v[124:125], s[10:11], 0, v[112:113]
	v_lshlrev_b64 v[112:113], 1, v[162:163]
	v_lshl_add_u64 v[124:125], v[124:125], 0, v[112:113]
	global_store_dwordx4 v[124:125], v[114:117], off
	v_max_f32_e32 v108, v108, v108
	v_max_f32_e32 v104, v104, v104
	v_or_b32_e32 v114, 8, v122
	v_ashrrev_i32_e32 v115, 31, v114
	v_lshlrev_b64 v[114:115], 14, v[114:115]
	v_lshl_add_u64 v[114:115], s[10:11], 0, v[114:115]
	v_max_f32_e32 v108, 0, v108
	v_max_f32_e32 v104, 0, v104
	v_max_f32_e32 v109, 0, v109
	v_max_f32_e32 v105, 0, v105
	v_max_f32_e32 v100, 0, v100
	v_max_f32_e32 v101, 0, v101
; __device__ __forceinline__ unsigned cvt_pk_bf16(float lo, float hi) { unsigned r; asm volatile("v_cvt_pk_bf16_f32 %0, %1, %2" : "=v"(r) : "v"(lo), "v"(hi)); return r; }
; __device__ __forceinline__ unsigned dpp_ror8(unsigned x) { return (unsigned)__builtin_amdgcn_update_dpp(0, (int)x, 0x128, 0xf, 0xf, false); }
; __device__ __forceinline__ void store_pair_lines(bf16_t* O, int ldc, int row, int fr, int col0, u32x4 wA, u32x4 wB) {
;     const u32x4 sA = {dpp_ror8(wA.x), dpp_ror8(wA.y), dpp_ror8(wA.z), dpp_ror8(wA.w)}, sB = {dpp_ror8(wB.x), dpp_ror8(wB.y), dpp_ror8(wB.z), dpp_ror8(wB.w)};
;     const bool lo = fr < 8;
;     const u32x4 o1 = lo ? wA : sB, o2 = lo ? sA : wB;
;     const int r1 = row - fr + (fr & 7), cb = col0 + (lo ? 0 : 8);
;     *(u32x4*)(O + (size_t)r1 * ldc + cb) = o1;
;     *(u32x4*)(O + (size_t)(r1 + 8) * ldc + cb) = o2;
; }
;     __device__ __forceinline__ void operator()(const f32x4 (&acc)[2][2][4][2], const Unit& u, int wr, int wc, int fr, int fq) const {
;     ...
;             for (int m = 0; m < 4; ++m) { const int row = row0 + ai * HALF + m * 16;
;                 const float rs = ssin ? __builtin_amdgcn_rsqf(ssin[row] * (1.f / D) + EPS) : 1.0f; float sq = 0.f; u32x4 w[2];
; #pragma unroll
;                 for (int bj = 0; bj < 2; ++bj) { f32x4 v0 = acc[ai][bj][m][0] * rs, v1 = acc[ai][bj][m][1] * rs;
;                     if (ACT == 1) {
; #pragma unroll
;                         for (int j = 0; j < 4; ++j) { const float a = fmaxf(v0[j], 0.f), b = fmaxf(v1[j], 0.f); v0[j] = a * a; v1[j] = b * b; } }
;                     sq += (v0[0] * v0[0] + v0[1] * v0[1]) + (v0[2] * v0[2] + v0[3] * v0[3]) + (v1[0] * v1[0] + v1[1] * v1[1]) + (v1[2] * v1[2] + v1[3] * v1[3]);
;                     w[bj].x = cvt_pk_bf16(v0[0], v0[1]); w[bj].y = cvt_pk_bf16(v0[2], v0[3]); w[bj].z = cvt_pk_bf16(v1[0], v1[1]); w[bj].w = cvt_pk_bf16(v1[2], v1[3]); }
;                 store_pair_lines(O, ldc, row, fr, col0, w[0], w[1]);
	v_max_f32_e32 v102, 0, v102
	v_max_f32_e32 v98, 0, v98
	v_max_f32_e32 v103, 0, v103
	v_lshl_add_u64 v[114:115], v[114:115], 0, v[112:113]
	v_mul_f32_e32 v108, v108, v108
	v_mul_f32_e32 v104, v104, v104
	v_mul_f32_e32 v109, v109, v109
	v_mul_f32_e32 v105, v105, v105
	v_max_f32_e32 v110, 0, v110
	v_max_f32_e32 v106, 0, v106
	v_max_f32_e32 v111, 0, v111
	v_max_f32_e32 v107, 0, v107
	v_max_f32_e32 v96, 0, v96
	v_mul_f32_e32 v100, v100, v100
	v_max_f32_e32 v97, 0, v97
	v_mul_f32_e32 v101, v101, v101
	v_mul_f32_e32 v102, v102, v102
	v_mul_f32_e32 v98, v98, v98
	v_max_f32_e32 v99, 0, v99
	v_mul_f32_e32 v103, v103, v103
	global_store_dwordx4 v[114:115], v[118:121], off
	v_mul_f32_e32 v110, v110, v110
	v_mul_f32_e32 v106, v106, v106
	v_mul_f32_e32 v111, v111, v111
	v_mul_f32_e32 v107, v107, v107
	v_cvt_pk_bf16_f32 v108, v108, v109
	v_cvt_pk_bf16_f32 v109, v110, v111
	v_cvt_pk_bf16_f32 v104, v104, v105
	v_cvt_pk_bf16_f32 v105, v106, v107
	v_mul_f32_e32 v96, v96, v96
	v_mul_f32_e32 v97, v97, v97
	v_mul_f32_e32 v99, v99, v99
	v_cvt_pk_bf16_f32 v100, v100, v101
	v_cvt_pk_bf16_f32 v101, v102, v103
	v_cvt_pk_bf16_f32 v102, v96, v97
	v_cvt_pk_bf16_f32 v103, v98, v99
	v_or_b32_e32 v160, s19, v146
	v_mov_b32_dpp v98, v102 row_ror:8 row_mask:0xf bank_mask:0xf
	v_mov_b32_dpp v110, v104 row_ror:8 row_mask:0xf bank_mask:0xf
	v_mov_b32_dpp v99, v103 row_ror:8 row_mask:0xf bank_mask:0xf
	v_cndmask_b32_e64 v98, v98, v104, s[6:7]
	v_add_u32_e32 v104, v149, v160
	v_mov_b32_dpp v111, v105 row_ror:8 row_mask:0xf bank_mask:0xf
	v_cndmask_b32_e64 v99, v99, v105, s[6:7]
	v_ashrrev_i32_e32 v105, 31, v104
	v_lshlrev_b64 v[104:105], 14, v[104:105]
	v_mov_b32_dpp v96, v100 row_ror:8 row_mask:0xf bank_mask:0xf
	v_mov_b32_dpp v97, v101 row_ror:8 row_mask:0xf bank_mask:0xf
	v_lshl_add_u64 v[104:105], s[10:11], 0, v[104:105]
	v_cndmask_b32_e64 v96, v96, v108, s[6:7]
	v_cndmask_b32_e64 v97, v97, v109, s[6:7]
	v_lshl_add_u64 v[104:105], v[104:105], 0, v[112:113]
	v_mov_b32_dpp v106, v108 row_ror:8 row_mask:0xf bank_mask:0xf
	v_mov_b32_dpp v107, v109 row_ror:8 row_mask:0xf bank_mask:0xf
	global_store_dwordx4 v[104:105], v[96:99], off
	v_max_f32_e32 v92, 0, v92
	v_max_f32_e32 v88, 0, v88
	v_add_co_u32_e32 v96, vcc, s68, v104
	v_max_f32_e32 v93, 0, v93
	v_max_f32_e32 v89, 0, v89
	v_max_f32_e32 v84, 0, v84
	v_max_f32_e32 v85, 0, v85
	v_max_f32_e32 v86, 0, v86
	v_max_f32_e32 v82, 0, v82
	v_max_f32_e32 v87, 0, v87
	v_cndmask_b32_e64 v100, v100, v106, s[6:7]
	v_cndmask_b32_e64 v101, v101, v107, s[6:7]
	v_cndmask_b32_e64 v102, v102, v110, s[6:7]
	v_cndmask_b32_e64 v103, v103, v111, s[6:7]
	v_addc_co_u32_e32 v97, vcc, 0, v105, vcc
	v_mul_f32_e32 v92, v92, v92
	v_mul_f32_e32 v88, v88, v88
	v_mul_f32_e32 v93, v93, v93
	v_mul_f32_e32 v89, v89, v89
	v_max_f32_e32 v94, 0, v94
	v_max_f32_e32 v90, 0, v90
	v_max_f32_e32 v95, 0, v95
	v_max_f32_e32 v91, 0, v91
	v_max_f32_e32 v80, 0, v80
	v_mul_f32_e32 v84, v84, v84
	v_max_f32_e32 v81, 0, v81
	v_mul_f32_e32 v85, v85, v85
	v_mul_f32_e32 v86, v86, v86
	v_mul_f32_e32 v82, v82, v82
	v_max_f32_e32 v83, 0, v83
	v_mul_f32_e32 v87, v87, v87
	global_store_dwordx4 v[96:97], v[100:103], off
	v_mul_f32_e32 v94, v94, v94
	v_mul_f32_e32 v90, v90, v90
	v_mul_f32_e32 v95, v95, v95
	v_mul_f32_e32 v91, v91, v91
	v_cvt_pk_bf16_f32 v92, v92, v93
	v_cvt_pk_bf16_f32 v93, v94, v95
	v_cvt_pk_bf16_f32 v88, v88, v89
	v_cvt_pk_bf16_f32 v89, v90, v91
	v_mul_f32_e32 v80, v80, v80
	v_mul_f32_e32 v81, v81, v81
	v_mul_f32_e32 v83, v83, v83
	v_cvt_pk_bf16_f32 v84, v84, v85
	v_cvt_pk_bf16_f32 v85, v86, v87
	v_cvt_pk_bf16_f32 v86, v80, v81
	v_cvt_pk_bf16_f32 v87, v82, v83
	v_mov_b32_e32 v82, 0
	v_mov_b32_dpp v82, v86 row_ror:8 row_mask:0xf bank_mask:0xf
	v_mov_b32_dpp v94, v88 row_ror:8 row_mask:0xf bank_mask:0xf
	v_mov_b32_dpp v83, v87 row_ror:8 row_mask:0xf bank_mask:0xf
	v_cndmask_b32_e64 v82, v82, v88, s[6:7]
	v_add_u32_e32 v88, v150, v160
	v_mov_b32_dpp v95, v89 row_ror:8 row_mask:0xf bank_mask:0xf
	v_cndmask_b32_e64 v83, v83, v89, s[6:7]
	v_ashrrev_i32_e32 v89, 31, v88
	v_lshlrev_b64 v[88:89], 14, v[88:89]
	v_mov_b32_dpp v80, v84 row_ror:8 row_mask:0xf bank_mask:0xf
	v_mov_b32_dpp v81, v85 row_ror:8 row_mask:0xf bank_mask:0xf
	v_lshl_add_u64 v[88:89], s[10:11], 0, v[88:89]
	v_cndmask_b32_e64 v80, v80, v92, s[6:7]
	v_cndmask_b32_e64 v81, v81, v93, s[6:7]
	v_lshl_add_u64 v[88:89], v[88:89], 0, v[112:113]
	v_mov_b32_dpp v90, v92 row_ror:8 row_mask:0xf bank_mask:0xf
	v_mov_b32_dpp v91, v93 row_ror:8 row_mask:0xf bank_mask:0xf
	global_store_dwordx4 v[88:89], v[80:83], off
	v_max_f32_e32 v76, 0, v76
	v_max_f32_e32 v72, 0, v72
	v_add_co_u32_e32 v80, vcc, s68, v88
	v_max_f32_e32 v77, 0, v77
	v_max_f32_e32 v73, 0, v73
	v_max_f32_e32 v68, 0, v68
	v_max_f32_e32 v69, 0, v69
	v_max_f32_e32 v70, 0, v70
	v_max_f32_e32 v66, 0, v66
	v_max_f32_e32 v71, 0, v71
	v_cndmask_b32_e64 v84, v84, v90, s[6:7]
	v_cndmask_b32_e64 v85, v85, v91, s[6:7]
	v_cndmask_b32_e64 v86, v86, v94, s[6:7]
	v_cndmask_b32_e64 v87, v87, v95, s[6:7]
	v_addc_co_u32_e32 v81, vcc, 0, v89, vcc
	v_mul_f32_e32 v76, v76, v76
	v_mul_f32_e32 v72, v72, v72
	v_mul_f32_e32 v77, v77, v77
	v_mul_f32_e32 v73, v73, v73
	v_max_f32_e32 v78, 0, v78
	v_max_f32_e32 v74, 0, v74
	v_max_f32_e32 v79, 0, v79
	v_max_f32_e32 v75, 0, v75
	v_max_f32_e32 v64, 0, v64
	v_mul_f32_e32 v68, v68, v68
	v_max_f32_e32 v65, 0, v65
	v_mul_f32_e32 v69, v69, v69
	v_mul_f32_e32 v70, v70, v70
	v_mul_f32_e32 v66, v66, v66
	v_max_f32_e32 v67, 0, v67
	v_mul_f32_e32 v71, v71, v71
	global_store_dwordx4 v[80:81], v[84:87], off
	v_mul_f32_e32 v78, v78, v78
	v_mul_f32_e32 v74, v74, v74
	v_mul_f32_e32 v79, v79, v79
	v_mul_f32_e32 v75, v75, v75
	v_cvt_pk_bf16_f32 v76, v76, v77
; __device__ __forceinline__ unsigned cvt_pk_bf16(float lo, float hi) { unsigned r; asm volatile("v_cvt_pk_bf16_f32 %0, %1, %2" : "=v"(r) : "v"(lo), "v"(hi)); return r; }
; __device__ __forceinline__ unsigned dpp_ror8(unsigned x) { return (unsigned)__builtin_amdgcn_update_dpp(0, (int)x, 0x128, 0xf, 0xf, false); }
; __device__ __forceinline__ void store_pair_lines(bf16_t* O, int ldc, int row, int fr, int col0, u32x4 wA, u32x4 wB) {
;     const u32x4 sA = {dpp_ror8(wA.x), dpp_ror8(wA.y), dpp_ror8(wA.z), dpp_ror8(wA.w)}, sB = {dpp_ror8(wB.x), dpp_ror8(wB.y), dpp_ror8(wB.z), dpp_ror8(wB.w)};
;     const bool lo = fr < 8;
;     const u32x4 o1 = lo ? wA : sB, o2 = lo ? sA : wB;
;     const int r1 = row - fr + (fr & 7), cb = col0 + (lo ? 0 : 8);
;     *(u32x4*)(O + (size_t)r1 * ldc + cb) = o1;
;     *(u32x4*)(O + (size_t)(r1 + 8) * ldc + cb) = o2;
; }
;     __device__ __forceinline__ void operator()(const f32x4 (&acc)[2][2][4][2], const Unit& u, int wr, int wc, int fr, int fq) const {
;     ...
;             for (int m = 0; m < 4; ++m) { const int row = row0 + ai * HALF + m * 16;
;                 const float rs = ssin ? __builtin_amdgcn_rsqf(ssin[row] * (1.f / D) + EPS) : 1.0f; float sq = 0.f; u32x4 w[2];
; #pragma unroll
;                 for (int bj = 0; bj < 2; ++bj) { f32x4 v0 = acc[ai][bj][m][0] * rs, v1 = acc[ai][bj][m][1] * rs;
;                     if (ACT == 1) {
; #pragma unroll
;                         for (int j = 0; j < 4; ++j) { const float a = fmaxf(v0[j], 0.f), b = fmaxf(v1[j], 0.f); v0[j] = a * a; v1[j] = b * b; } }
;                     sq += (v0[0] * v0[0] + v0[1] * v0[1]) + (v0[2] * v0[2] + v0[3] * v0[3]) + (v1[0] * v1[0] + v1[1] * v1[1]) + (v1[2] * v1[2] + v1[3] * v1[3]);
;                     w[bj].x = cvt_pk_bf16(v0[0], v0[1]); w[bj].y = cvt_pk_bf16(v0[2], v0[3]); w[bj].z = cvt_pk_bf16(v1[0], v1[1]); w[bj].w = cvt_pk_bf16(v1[2], v1[3]); }
;                 store_pair_lines(O, ldc, row, fr, col0, w[0], w[1]);
	v_cvt_pk_bf16_f32 v77, v78, v79
	v_cvt_pk_bf16_f32 v72, v72, v73
	v_cvt_pk_bf16_f32 v73, v74, v75
	v_mul_f32_e32 v64, v64, v64
	v_mul_f32_e32 v65, v65, v65
	v_mul_f32_e32 v67, v67, v67
	v_cvt_pk_bf16_f32 v68, v68, v69
	v_cvt_pk_bf16_f32 v69, v70, v71
	v_cvt_pk_bf16_f32 v70, v64, v65
	v_cvt_pk_bf16_f32 v71, v66, v67
	v_mov_b32_e32 v66, 0
	v_mov_b32_dpp v66, v70 row_ror:8 row_mask:0xf bank_mask:0xf
	v_mov_b32_dpp v78, v72 row_ror:8 row_mask:0xf bank_mask:0xf
	v_mov_b32_dpp v67, v71 row_ror:8 row_mask:0xf bank_mask:0xf
	v_cndmask_b32_e64 v66, v66, v72, s[6:7]
	v_add_u32_e32 v72, v151, v160
	v_mov_b32_dpp v79, v73 row_ror:8 row_mask:0xf bank_mask:0xf
	v_cndmask_b32_e64 v67, v67, v73, s[6:7]
	v_ashrrev_i32_e32 v73, 31, v72
	v_lshlrev_b64 v[72:73], 14, v[72:73]
	v_mov_b32_dpp v64, v68 row_ror:8 row_mask:0xf bank_mask:0xf
	v_mov_b32_dpp v65, v69 row_ror:8 row_mask:0xf bank_mask:0xf
	v_lshl_add_u64 v[72:73], s[10:11], 0, v[72:73]
	v_cndmask_b32_e64 v64, v64, v76, s[6:7]
	v_cndmask_b32_e64 v65, v65, v77, s[6:7]
	v_lshl_add_u64 v[72:73], v[72:73], 0, v[112:113]
	v_mov_b32_dpp v74, v76 row_ror:8 row_mask:0xf bank_mask:0xf
	v_mov_b32_dpp v75, v77 row_ror:8 row_mask:0xf bank_mask:0xf
	global_store_dwordx4 v[72:73], v[64:67], off
	v_max_f32_e32 v60, 0, v60
	v_max_f32_e32 v56, 0, v56
	v_add_co_u32_e32 v64, vcc, s68, v72
	v_max_f32_e32 v61, 0, v61
	v_max_f32_e32 v57, 0, v57
	v_max_f32_e32 v52, 0, v52
	v_max_f32_e32 v53, 0, v53
	v_max_f32_e32 v54, 0, v54
	v_max_f32_e32 v50, 0, v50
	v_max_f32_e32 v55, 0, v55
	v_cndmask_b32_e64 v68, v68, v74, s[6:7]
	v_cndmask_b32_e64 v69, v69, v75, s[6:7]
	v_cndmask_b32_e64 v70, v70, v78, s[6:7]
	v_cndmask_b32_e64 v71, v71, v79, s[6:7]
	v_addc_co_u32_e32 v65, vcc, 0, v73, vcc
	v_mul_f32_e32 v60, v60, v60
	v_mul_f32_e32 v56, v56, v56
	v_mul_f32_e32 v61, v61, v61
	v_mul_f32_e32 v57, v57, v57
	v_max_f32_e32 v62, 0, v62
	v_max_f32_e32 v58, 0, v58
	v_max_f32_e32 v63, 0, v63
	v_max_f32_e32 v59, 0, v59
	v_max_f32_e32 v48, 0, v48
	v_mul_f32_e32 v52, v52, v52
	v_max_f32_e32 v49, 0, v49
	v_mul_f32_e32 v53, v53, v53
	v_mul_f32_e32 v54, v54, v54
	v_mul_f32_e32 v50, v50, v50
	v_max_f32_e32 v51, 0, v51
	v_mul_f32_e32 v55, v55, v55
	global_store_dwordx4 v[64:65], v[68:71], off
	v_mul_f32_e32 v62, v62, v62
	v_mul_f32_e32 v58, v58, v58
	v_mul_f32_e32 v63, v63, v63
	v_mul_f32_e32 v59, v59, v59
	v_cvt_pk_bf16_f32 v60, v60, v61
	v_cvt_pk_bf16_f32 v61, v62, v63
	v_cvt_pk_bf16_f32 v56, v56, v57
	v_cvt_pk_bf16_f32 v57, v58, v59
	v_mul_f32_e32 v48, v48, v48
	v_mul_f32_e32 v49, v49, v49
	v_mul_f32_e32 v51, v51, v51
	v_cvt_pk_bf16_f32 v52, v52, v53
	v_cvt_pk_bf16_f32 v53, v54, v55
	v_cvt_pk_bf16_f32 v54, v48, v49
	v_cvt_pk_bf16_f32 v55, v50, v51
	v_mov_b32_e32 v50, 0
	v_mov_b32_dpp v50, v54 row_ror:8 row_mask:0xf bank_mask:0xf
	v_mov_b32_dpp v62, v56 row_ror:8 row_mask:0xf bank_mask:0xf
	v_mov_b32_dpp v51, v55 row_ror:8 row_mask:0xf bank_mask:0xf
	v_cndmask_b32_e64 v50, v50, v56, s[6:7]
	v_add_u32_e32 v56, v152, v160
	v_mov_b32_dpp v63, v57 row_ror:8 row_mask:0xf bank_mask:0xf
	v_cndmask_b32_e64 v51, v51, v57, s[6:7]
	v_ashrrev_i32_e32 v57, 31, v56
	v_lshlrev_b64 v[56:57], 14, v[56:57]
	v_mov_b32_dpp v48, v52 row_ror:8 row_mask:0xf bank_mask:0xf
	v_mov_b32_dpp v49, v53 row_ror:8 row_mask:0xf bank_mask:0xf
	v_lshl_add_u64 v[56:57], s[10:11], 0, v[56:57]
	v_cndmask_b32_e64 v48, v48, v60, s[6:7]
	v_cndmask_b32_e64 v49, v49, v61, s[6:7]
	v_lshl_add_u64 v[56:57], v[56:57], 0, v[112:113]
	v_mov_b32_dpp v58, v60 row_ror:8 row_mask:0xf bank_mask:0xf
	v_mov_b32_dpp v59, v61 row_ror:8 row_mask:0xf bank_mask:0xf
	global_store_dwordx4 v[56:57], v[48:51], off
	v_max_f32_e32 v44, 0, v44
	v_max_f32_e32 v40, 0, v40
	v_add_co_u32_e32 v48, vcc, s68, v56
	v_max_f32_e32 v45, 0, v45
	v_max_f32_e32 v41, 0, v41
	v_max_f32_e32 v36, 0, v36
	v_max_f32_e32 v37, 0, v37
	v_max_f32_e32 v38, 0, v38
	v_max_f32_e32 v34, 0, v34
	v_max_f32_e32 v39, 0, v39
	v_cndmask_b32_e64 v52, v52, v58, s[6:7]
	v_cndmask_b32_e64 v53, v53, v59, s[6:7]
	v_cndmask_b32_e64 v54, v54, v62, s[6:7]
	v_cndmask_b32_e64 v55, v55, v63, s[6:7]
	v_addc_co_u32_e32 v49, vcc, 0, v57, vcc
	v_mul_f32_e32 v44, v44, v44
	v_mul_f32_e32 v40, v40, v40
	v_mul_f32_e32 v45, v45, v45
	v_mul_f32_e32 v41, v41, v41
	v_max_f32_e32 v46, 0, v46
	v_max_f32_e32 v42, 0, v42
	v_max_f32_e32 v47, 0, v47
	v_max_f32_e32 v43, 0, v43
	v_max_f32_e32 v32, 0, v32
	v_mul_f32_e32 v36, v36, v36
	v_max_f32_e32 v33, 0, v33
	v_mul_f32_e32 v37, v37, v37
	v_mul_f32_e32 v38, v38, v38
	v_mul_f32_e32 v34, v34, v34
	v_max_f32_e32 v35, 0, v35
	v_mul_f32_e32 v39, v39, v39
	global_store_dwordx4 v[48:49], v[52:55], off
	v_mul_f32_e32 v46, v46, v46
	v_mul_f32_e32 v42, v42, v42
	v_mul_f32_e32 v47, v47, v47
	v_mul_f32_e32 v43, v43, v43
	v_cvt_pk_bf16_f32 v44, v44, v45
	v_cvt_pk_bf16_f32 v45, v46, v47
	v_cvt_pk_bf16_f32 v40, v40, v41
	v_cvt_pk_bf16_f32 v41, v42, v43
	v_mul_f32_e32 v32, v32, v32
	v_mul_f32_e32 v33, v33, v33
	v_mul_f32_e32 v35, v35, v35
	v_cvt_pk_bf16_f32 v36, v36, v37
	v_cvt_pk_bf16_f32 v37, v38, v39
	v_cvt_pk_bf16_f32 v38, v32, v33
	v_cvt_pk_bf16_f32 v39, v34, v35
	v_mov_b32_e32 v34, 0
	v_mov_b32_dpp v34, v38 row_ror:8 row_mask:0xf bank_mask:0xf
	v_mov_b32_dpp v46, v40 row_ror:8 row_mask:0xf bank_mask:0xf
	v_mov_b32_dpp v35, v39 row_ror:8 row_mask:0xf bank_mask:0xf
	v_cndmask_b32_e64 v34, v34, v40, s[6:7]
	v_add_u32_e32 v40, v153, v160
	v_mov_b32_dpp v47, v41 row_ror:8 row_mask:0xf bank_mask:0xf
	v_cndmask_b32_e64 v35, v35, v41, s[6:7]
	v_ashrrev_i32_e32 v41, 31, v40
	v_lshlrev_b64 v[40:41], 14, v[40:41]
	v_mov_b32_dpp v32, v36 row_ror:8 row_mask:0xf bank_mask:0xf
; __device__ __forceinline__ unsigned cvt_pk_bf16(float lo, float hi) { unsigned r; asm volatile("v_cvt_pk_bf16_f32 %0, %1, %2" : "=v"(r) : "v"(lo), "v"(hi)); return r; }
; __device__ __forceinline__ unsigned dpp_ror8(unsigned x) { return (unsigned)__builtin_amdgcn_update_dpp(0, (int)x, 0x128, 0xf, 0xf, false); }
; __device__ __forceinline__ void store_pair_lines(bf16_t* O, int ldc, int row, int fr, int col0, u32x4 wA, u32x4 wB) {
;     const u32x4 sA = {dpp_ror8(wA.x), dpp_ror8(wA.y), dpp_ror8(wA.z), dpp_ror8(wA.w)}, sB = {dpp_ror8(wB.x), dpp_ror8(wB.y), dpp_ror8(wB.z), dpp_ror8(wB.w)};
;     const bool lo = fr < 8;
;     const u32x4 o1 = lo ? wA : sB, o2 = lo ? sA : wB;
;     const int r1 = row - fr + (fr & 7), cb = col0 + (lo ? 0 : 8);
;     *(u32x4*)(O + (size_t)r1 * ldc + cb) = o1;
;     *(u32x4*)(O + (size_t)(r1 + 8) * ldc + cb) = o2;
; }
;     __device__ __forceinline__ void operator()(const f32x4 (&acc)[2][2][4][2], const Unit& u, int wr, int wc, int fr, int fq) const {
;     ...
;             for (int m = 0; m < 4; ++m) { const int row = row0 + ai * HALF + m * 16;
;                 const float rs = ssin ? __builtin_amdgcn_rsqf(ssin[row] * (1.f / D) + EPS) : 1.0f; float sq = 0.f; u32x4 w[2];
; #pragma unroll
;                 for (int bj = 0; bj < 2; ++bj) { f32x4 v0 = acc[ai][bj][m][0] * rs, v1 = acc[ai][bj][m][1] * rs;
;                     if (ACT == 1) {
; #pragma unroll
;                         for (int j = 0; j < 4; ++j) { const float a = fmaxf(v0[j], 0.f), b = fmaxf(v1[j], 0.f); v0[j] = a * a; v1[j] = b * b; } }
;                     sq += (v0[0] * v0[0] + v0[1] * v0[1]) + (v0[2] * v0[2] + v0[3] * v0[3]) + (v1[0] * v1[0] + v1[1] * v1[1]) + (v1[2] * v1[2] + v1[3] * v1[3]);
;                     w[bj].x = cvt_pk_bf16(v0[0], v0[1]); w[bj].y = cvt_pk_bf16(v0[2], v0[3]); w[bj].z = cvt_pk_bf16(v1[0], v1[1]); w[bj].w = cvt_pk_bf16(v1[2], v1[3]); }
;                 store_pair_lines(O, ldc, row, fr, col0, w[0], w[1]);
	v_mov_b32_dpp v33, v37 row_ror:8 row_mask:0xf bank_mask:0xf
	v_lshl_add_u64 v[40:41], s[10:11], 0, v[40:41]
	v_cndmask_b32_e64 v32, v32, v44, s[6:7]
	v_cndmask_b32_e64 v33, v33, v45, s[6:7]
	v_lshl_add_u64 v[40:41], v[40:41], 0, v[112:113]
	v_mov_b32_dpp v42, v44 row_ror:8 row_mask:0xf bank_mask:0xf
	v_mov_b32_dpp v43, v45 row_ror:8 row_mask:0xf bank_mask:0xf
	global_store_dwordx4 v[40:41], v[32:35], off
	v_max_f32_e32 v28, 0, v28
	v_max_f32_e32 v24, 0, v24
	v_add_co_u32_e32 v32, vcc, s68, v40
	v_max_f32_e32 v29, 0, v29
	v_max_f32_e32 v25, 0, v25
	v_max_f32_e32 v20, 0, v20
	v_max_f32_e32 v21, 0, v21
	v_max_f32_e32 v22, 0, v22
	v_max_f32_e32 v18, 0, v18
	v_max_f32_e32 v23, 0, v23
	v_cndmask_b32_e64 v36, v36, v42, s[6:7]
	v_cndmask_b32_e64 v37, v37, v43, s[6:7]
	v_cndmask_b32_e64 v38, v38, v46, s[6:7]
	v_cndmask_b32_e64 v39, v39, v47, s[6:7]
	v_addc_co_u32_e32 v33, vcc, 0, v41, vcc
	v_mul_f32_e32 v28, v28, v28
	v_mul_f32_e32 v24, v24, v24
	v_mul_f32_e32 v29, v29, v29
	v_mul_f32_e32 v25, v25, v25
	v_max_f32_e32 v30, 0, v30
	v_max_f32_e32 v26, 0, v26
	v_max_f32_e32 v31, 0, v31
	v_max_f32_e32 v27, 0, v27
	v_max_f32_e32 v16, 0, v16
	v_mul_f32_e32 v20, v20, v20
	v_max_f32_e32 v17, 0, v17
	v_mul_f32_e32 v21, v21, v21
	v_mul_f32_e32 v22, v22, v22
	v_mul_f32_e32 v18, v18, v18
	v_max_f32_e32 v19, 0, v19
	v_mul_f32_e32 v23, v23, v23
	global_store_dwordx4 v[32:33], v[36:39], off
	v_mul_f32_e32 v30, v30, v30
	v_mul_f32_e32 v26, v26, v26
	v_mul_f32_e32 v31, v31, v31
	v_mul_f32_e32 v27, v27, v27
	v_cvt_pk_bf16_f32 v28, v28, v29
	v_cvt_pk_bf16_f32 v29, v30, v31
	v_cvt_pk_bf16_f32 v24, v24, v25
	v_cvt_pk_bf16_f32 v25, v26, v27
	v_mul_f32_e32 v16, v16, v16
	v_mul_f32_e32 v17, v17, v17
	v_mul_f32_e32 v19, v19, v19
	v_cvt_pk_bf16_f32 v20, v20, v21
	v_cvt_pk_bf16_f32 v21, v22, v23
	v_cvt_pk_bf16_f32 v22, v16, v17
	v_cvt_pk_bf16_f32 v23, v18, v19
	v_mov_b32_e32 v18, 0
	v_mov_b32_dpp v18, v22 row_ror:8 row_mask:0xf bank_mask:0xf
	v_mov_b32_dpp v30, v24 row_ror:8 row_mask:0xf bank_mask:0xf
	v_mov_b32_dpp v19, v23 row_ror:8 row_mask:0xf bank_mask:0xf
	v_cndmask_b32_e64 v18, v18, v24, s[6:7]
	v_add_u32_e32 v24, v154, v160
	v_mov_b32_dpp v31, v25 row_ror:8 row_mask:0xf bank_mask:0xf
	v_cndmask_b32_e64 v19, v19, v25, s[6:7]
	v_ashrrev_i32_e32 v25, 31, v24
	v_lshlrev_b64 v[24:25], 14, v[24:25]
	v_mov_b32_dpp v16, v20 row_ror:8 row_mask:0xf bank_mask:0xf
	v_mov_b32_dpp v17, v21 row_ror:8 row_mask:0xf bank_mask:0xf
	v_lshl_add_u64 v[24:25], s[10:11], 0, v[24:25]
	v_cndmask_b32_e64 v16, v16, v28, s[6:7]
	v_cndmask_b32_e64 v17, v17, v29, s[6:7]
	v_lshl_add_u64 v[24:25], v[24:25], 0, v[112:113]
	v_mov_b32_dpp v26, v28 row_ror:8 row_mask:0xf bank_mask:0xf
	v_mov_b32_dpp v27, v29 row_ror:8 row_mask:0xf bank_mask:0xf
	global_store_dwordx4 v[24:25], v[16:19], off
	v_max_f32_e32 v12, 0, v12
	v_max_f32_e32 v8, 0, v8
	v_add_co_u32_e32 v16, vcc, s68, v24
	v_max_f32_e32 v13, 0, v13
	v_max_f32_e32 v9, 0, v9
	v_max_f32_e32 v4, 0, v4
	v_max_f32_e32 v5, 0, v5
	v_max_f32_e32 v6, 0, v6
	v_max_f32_e32 v2, 0, v2
	v_max_f32_e32 v7, 0, v7
	v_cndmask_b32_e64 v20, v20, v26, s[6:7]
	v_cndmask_b32_e64 v21, v21, v27, s[6:7]
	v_cndmask_b32_e64 v22, v22, v30, s[6:7]
	v_cndmask_b32_e64 v23, v23, v31, s[6:7]
	v_addc_co_u32_e32 v17, vcc, 0, v25, vcc
	v_mul_f32_e32 v12, v12, v12
	v_mul_f32_e32 v8, v8, v8
	v_mul_f32_e32 v13, v13, v13
	v_mul_f32_e32 v9, v9, v9
	v_max_f32_e32 v14, 0, v14
	v_max_f32_e32 v10, 0, v10
	v_max_f32_e32 v15, 0, v15
	v_max_f32_e32 v11, 0, v11
	v_max_f32_e32 v0, 0, v0
	v_mul_f32_e32 v4, v4, v4
	v_max_f32_e32 v1, 0, v1
	v_mul_f32_e32 v5, v5, v5
	v_mul_f32_e32 v6, v6, v6
	v_mul_f32_e32 v2, v2, v2
	v_max_f32_e32 v3, 0, v3
	v_mul_f32_e32 v7, v7, v7
	global_store_dwordx4 v[16:17], v[20:23], off
	v_mul_f32_e32 v14, v14, v14
	v_mul_f32_e32 v10, v10, v10
	v_mul_f32_e32 v15, v15, v15
	v_mul_f32_e32 v11, v11, v11
	v_cvt_pk_bf16_f32 v12, v12, v13
	v_cvt_pk_bf16_f32 v13, v14, v15
	v_cvt_pk_bf16_f32 v8, v8, v9
	v_cvt_pk_bf16_f32 v9, v10, v11
	v_mul_f32_e32 v0, v0, v0
	v_mul_f32_e32 v1, v1, v1
	v_mul_f32_e32 v3, v3, v3
	v_cvt_pk_bf16_f32 v4, v4, v5
	v_cvt_pk_bf16_f32 v5, v6, v7
	v_cvt_pk_bf16_f32 v6, v0, v1
	v_cvt_pk_bf16_f32 v7, v2, v3
	v_mov_b32_e32 v2, 0
	v_mov_b32_dpp v2, v6 row_ror:8 row_mask:0xf bank_mask:0xf
	v_mov_b32_dpp v14, v8 row_ror:8 row_mask:0xf bank_mask:0xf
	v_mov_b32_dpp v3, v7 row_ror:8 row_mask:0xf bank_mask:0xf
	v_cndmask_b32_e64 v2, v2, v8, s[6:7]
	v_add_u32_e32 v8, v155, v160
	v_mov_b32_dpp v15, v9 row_ror:8 row_mask:0xf bank_mask:0xf
	v_cndmask_b32_e64 v3, v3, v9, s[6:7]
	v_ashrrev_i32_e32 v9, 31, v8
	v_lshlrev_b64 v[8:9], 14, v[8:9]
	v_mov_b32_dpp v0, v4 row_ror:8 row_mask:0xf bank_mask:0xf
	v_mov_b32_dpp v1, v5 row_ror:8 row_mask:0xf bank_mask:0xf
	v_lshl_add_u64 v[8:9], s[10:11], 0, v[8:9]
	v_cndmask_b32_e64 v0, v0, v12, s[6:7]
	v_cndmask_b32_e64 v1, v1, v13, s[6:7]
	v_lshl_add_u64 v[8:9], v[8:9], 0, v[112:113]
	global_store_dwordx4 v[8:9], v[0:3], off
	v_mov_b32_dpp v10, v12 row_ror:8 row_mask:0xf bank_mask:0xf
	v_mov_b32_dpp v11, v13 row_ror:8 row_mask:0xf bank_mask:0xf
	v_add_co_u32_e32 v0, vcc, 0x20000, v8
	v_cndmask_b32_e64 v4, v4, v10, s[6:7]
	s_nop 0
	v_addc_co_u32_e32 v1, vcc, 0, v9, vcc
	v_cndmask_b32_e64 v5, v5, v11, s[6:7]
	v_cndmask_b32_e64 v6, v6, v14, s[6:7]
	v_cndmask_b32_e64 v7, v7, v15, s[6:7]
	s_and_b64 vcc, exec, s[40:41]
	s_mov_b32 s69, s18
	s_mov_b32 s44, s36
	s_mov_b64 s[48:49], s[42:43]
	s_mov_b64 s[46:47], s[38:39]
	global_store_dwordx4 v[0:1], v[4:7], off
	s_cbranch_vccz .LBB0_725
	s_waitcnt vmcnt(0)
	s_cmpk_gt_u32 s52, 0xff
	s_cbranch_scc1 .LBB0_737
	s_barrier

; #define PG8_STAGE(bufoff, gbase, voff) do { _Pragma("unroll") for (int _i = 0; _i < 2; ++_i) \
;         __builtin_amdgcn_global_load_lds((const unsigned*)((const char*)(gbase) + (voff)[_i]), (LAS unsigned*)(lds + (bufoff) + ldsw + _i * 8192), 16, 0, 0); } while (0)
; #define PG8_LDA(dst, b, h) do { _Pragma("unroll") for (int m = 0; m < 4; ++m) _Pragma("unroll") for (int k = 0; k < 2; ++k) dst[m][k] = *(const LAS bf16x8*)(lds + PG8_SA(b, h) + aoff + m * 2048 + k * 1024); } while (0)
; #define PG8_LDB(dst, b, h) do { _Pragma("unroll") for (int n = 0; n < 2; ++n) _Pragma("unroll") for (int k = 0; k < 2; ++k) dst[n][k] = *(const LAS bf16x8*)(lds + PG8_SB(b, h) + boff + n * 2048 + k * 1024); } while (0)
; #define PG8_WAIT_V(n) asm volatile("s_waitcnt vmcnt(" #n ")" ::: "memory")
; #define PG8_BAR __builtin_amdgcn_s_barrier()
; template <class Epi>
; __device__ __forceinline__ void gemm_phase(LAS unsigned char* lds, const Gemm g, const StaticOrder& S, const Epi& E) {
;     ...
;         const char* nA = has_next ? (const char*)g.A + (size_t)nxt.pm * tstep : cA; const char* nB = has_next ? (const char*)g.Bt + (size_t)nxt.pn * tstep : cB;
;         for (int t = 0; t < nt; t += 2) {
;             const bool last = (t == nt - 2);
;             const char* a1 = cA + (size_t)(t + 1) * kstep;
;             const char* a2 = last ? nA : cA + (size_t)(t + 2) * kstep; const char* b2 = last ? nB : cB + (size_t)(t + 2) * kstep;
;             const char* a3 = a2 + kstep; const char* b3 = b2 + kstep;
;             PG8_LDB(B0, 0, 0); PG8_SCHED; PG8_LDA(At, 0, 0); PG8_STAGE(PG8_SA(1, 1), a1 + hstep, voffA);
;             PG8_WAIT_L(8); PG8_BAR; PG8_WAIT_L(0); PG8_MMA(0, 0, At, B0); PG8_BAR; PG8_SCHED;
;             PG8_LDB(B1, 0, 1); PG8_STAGE(PG8_SB(0, 0), b2, voffB0);
;             PG8_BAR; PG8_WAIT_L(0); PG8_MMA(0, 1, At, B1); PG8_BAR;
;             PG8_LDA(At, 0, 1); PG8_STAGE(PG8_SA(0, 0), a2, voffA);
;             PG8_BAR; PG8_WAIT_L(0); PG8_MMA(1, 0, At, B0); PG8_BAR; PG8_SCHED;
;             PG8_STAGE(PG8_SB(0, 1), b2, voffB1);
;             PG8_WAIT_V(6); PG8_BAR; PG8_MMA(1, 1, At, B1); PG8_BAR;
;             PG8_LDB(B0, 1, 0); PG8_SCHED; PG8_LDA(At, 1, 0); PG8_STAGE(PG8_SA(0, 1), a2 + hstep, voffA);
;             PG8_WAIT_L(8); PG8_BAR; PG8_WAIT_L(0); PG8_MMA(0, 0, At, B0); PG8_BAR; PG8_SCHED;
;             PG8_LDB(B1, 1, 1); PG8_STAGE(PG8_SB(1, 0), b3, voffB0);
.LBB0_806:
	ds_read_b128 v[146:149], v156
	ds_read_b128 v[160:163], v156 offset:1024
	ds_read_b128 v[164:167], v156 offset:2048
	ds_read_b128 v[168:171], v156 offset:3072
	s_add_u32 s33, s50, 0xffe00080
	s_addc_u32 s52, s51, -1
	s_cmpk_eq_i32 s80, 0x7c
	s_cselect_b32 s53, s41, s52
	s_cselect_b32 s52, s75, s33
	s_cselect_b32 s55, s39, s79
	s_cselect_b32 s54, s77, s78
	v_lshl_add_u64 v[150:151], s[50:51], 0, v[140:141]
	s_add_i32 m0, s49, 0xc000
	ds_read_b128 v[172:175], v157
	ds_read_b128 v[176:179], v157 offset:1024
	ds_read_b128 v[180:183], v157 offset:2048
	ds_read_b128 v[184:187], v157 offset:3072
	ds_read_b128 v[188:191], v157 offset:4096
	ds_read_b128 v[192:195], v157 offset:5120
	ds_read_b128 v[196:199], v157 offset:6144
	ds_read_b128 v[204:207], v157 offset:7168
	global_load_lds_dwordx4 v[150:151], off
	v_lshl_add_u64 v[150:151], s[50:51], 0, v[142:143]
	s_add_i32 m0, s49, 0xe000
	s_nop 0
	global_load_lds_dwordx4 v[150:151], off
	s_waitcnt lgkmcnt(8)
	s_barrier
	s_waitcnt lgkmcnt(0)
	v_mfma_f32_16x16x32_bf16 v[124:127], v[146:149], v[172:175], v[124:127]
	v_mfma_f32_16x16x32_bf16 v[120:123], v[164:167], v[172:175], v[120:123]
	v_mfma_f32_16x16x32_bf16 v[108:111], v[146:149], v[180:183], v[108:111]
	v_mfma_f32_16x16x32_bf16 v[104:107], v[164:167], v[180:183], v[104:107]
	v_mfma_f32_16x16x32_bf16 v[92:95], v[146:149], v[188:191], v[92:95]
	v_mfma_f32_16x16x32_bf16 v[88:91], v[164:167], v[188:191], v[88:91]
	v_mfma_f32_16x16x32_bf16 v[76:79], v[146:149], v[196:199], v[76:79]
	v_mfma_f32_16x16x32_bf16 v[72:75], v[164:167], v[196:199], v[72:75]
	v_mfma_f32_16x16x32_bf16 v[124:127], v[160:163], v[176:179], v[124:127]
	v_mfma_f32_16x16x32_bf16 v[120:123], v[168:171], v[176:179], v[120:123]
	v_mfma_f32_16x16x32_bf16 v[108:111], v[160:163], v[184:187], v[108:111]
	v_mfma_f32_16x16x32_bf16 v[104:107], v[168:171], v[184:187], v[104:107]
	v_mfma_f32_16x16x32_bf16 v[92:95], v[160:163], v[192:195], v[92:95]
	v_mfma_f32_16x16x32_bf16 v[88:91], v[168:171], v[192:195], v[88:91]
	v_mfma_f32_16x16x32_bf16 v[76:79], v[160:163], v[204:207], v[76:79]
	v_mfma_f32_16x16x32_bf16 v[72:75], v[168:171], v[204:207], v[72:75]
	s_barrier
	s_add_i32 s33, s72, s62
	v_lshl_add_u64 v[150:151], s[54:55], 0, v[130:131]
	s_mov_b32 m0, s33
	ds_read_b128 v[208:211], v158
	ds_read_b128 v[212:215], v158 offset:1024
	ds_read_b128 v[216:219], v158 offset:2048
	ds_read_b128 v[220:223], v158 offset:3072
	global_load_lds_dwordx4 v[150:151], off
	v_lshl_add_u64 v[200:201], s[54:55], 0, v[136:137]
	s_add_i32 m0, s33, 0x2000
	s_nop 0
	global_load_lds_dwordx4 v[200:201], off
	s_barrier
	s_waitcnt lgkmcnt(0)
	v_mfma_f32_16x16x32_bf16 v[116:119], v[208:211], v[172:175], v[116:119]
	v_mfma_f32_16x16x32_bf16 v[112:115], v[216:219], v[172:175], v[112:115]
	v_mfma_f32_16x16x32_bf16 v[100:103], v[208:211], v[180:183], v[100:103]
	v_mfma_f32_16x16x32_bf16 v[96:99], v[216:219], v[180:183], v[96:99]
	v_mfma_f32_16x16x32_bf16 v[84:87], v[208:211], v[188:191], v[84:87]
	v_mfma_f32_16x16x32_bf16 v[80:83], v[216:219], v[188:191], v[80:83]
	v_mfma_f32_16x16x32_bf16 v[68:71], v[208:211], v[196:199], v[68:71]
	v_mfma_f32_16x16x32_bf16 v[64:67], v[216:219], v[196:199], v[64:67]
	v_mfma_f32_16x16x32_bf16 v[116:119], v[212:215], v[176:179], v[116:119]
	v_mfma_f32_16x16x32_bf16 v[112:115], v[220:223], v[176:179], v[112:115]
	v_mfma_f32_16x16x32_bf16 v[100:103], v[212:215], v[184:187], v[100:103]
	v_mfma_f32_16x16x32_bf16 v[96:99], v[220:223], v[184:187], v[96:99]
	v_mfma_f32_16x16x32_bf16 v[84:87], v[212:215], v[192:195], v[84:87]
	v_mfma_f32_16x16x32_bf16 v[80:83], v[220:223], v[192:195], v[80:83]
	v_mfma_f32_16x16x32_bf16 v[68:71], v[212:215], v[204:207], v[68:71]
	v_mfma_f32_16x16x32_bf16 v[64:67], v[220:223], v[204:207], v[64:67]
	s_mov_b32 m0, s49
	v_lshl_add_u64 v[224:225], s[52:53], 0, v[128:129]
	s_barrier
	ds_read_b128 v[172:175], v157 offset:16384
	ds_read_b128 v[176:179], v157 offset:17408
	ds_read_b128 v[180:183], v157 offset:18432
	ds_read_b128 v[184:187], v157 offset:19456
	ds_read_b128 v[188:191], v157 offset:20480
	ds_read_b128 v[192:195], v157 offset:21504
	ds_read_b128 v[196:199], v157 offset:22528
	ds_read_b128 v[204:207], v157 offset:23552
	global_load_lds_dwordx4 v[224:225], off
	v_lshl_add_u64 v[226:227], s[52:53], 0, v[134:135]
	s_mov_b32 m0, s63
	s_nop 0
	global_load_lds_dwordx4 v[226:227], off
	s_barrier
	s_waitcnt lgkmcnt(0)
	v_mfma_f32_16x16x32_bf16 v[60:63], v[146:149], v[172:175], v[60:63]
	v_mfma_f32_16x16x32_bf16 v[56:59], v[164:167], v[172:175], v[56:59]
	v_mfma_f32_16x16x32_bf16 v[44:47], v[146:149], v[180:183], v[44:47]
	v_mfma_f32_16x16x32_bf16 v[40:43], v[164:167], v[180:183], v[40:43]
	v_mfma_f32_16x16x32_bf16 v[28:31], v[146:149], v[188:191], v[28:31]
	v_mfma_f32_16x16x32_bf16 v[24:27], v[164:167], v[188:191], v[24:27]
	v_mfma_f32_16x16x32_bf16 v[12:15], v[146:149], v[196:199], v[12:15]
	v_mfma_f32_16x16x32_bf16 v[8:11], v[164:167], v[196:199], v[8:11]
	v_mfma_f32_16x16x32_bf16 v[60:63], v[160:163], v[176:179], v[60:63]
	v_mfma_f32_16x16x32_bf16 v[56:59], v[168:171], v[176:179], v[56:59]
	v_mfma_f32_16x16x32_bf16 v[44:47], v[160:163], v[184:187], v[44:47]
	v_mfma_f32_16x16x32_bf16 v[40:43], v[168:171], v[184:187], v[40:43]
	v_mfma_f32_16x16x32_bf16 v[28:31], v[160:163], v[192:195], v[28:31]
	v_mfma_f32_16x16x32_bf16 v[24:27], v[168:171], v[192:195], v[24:27]
	v_mfma_f32_16x16x32_bf16 v[12:15], v[160:163], v[204:207], v[12:15]
	v_mfma_f32_16x16x32_bf16 v[8:11], v[168:171], v[204:207], v[8:11]
	s_barrier
	s_add_i32 s33, s73, s62
	v_lshl_add_u64 v[228:229], s[54:55], 0, v[132:133]
	s_mov_b32 m0, s33
	v_lshl_add_u64 v[230:231], s[54:55], 0, v[138:139]
	global_load_lds_dwordx4 v[228:229], off
	s_add_i32 m0, s33, 0x2000
	s_nop 0
	global_load_lds_dwordx4 v[230:231], off
	s_waitcnt vmcnt(6)
	s_barrier
; #define PG8_STAGE(bufoff, gbase, voff) do { _Pragma("unroll") for (int _i = 0; _i < 2; ++_i) \
;         __builtin_amdgcn_global_load_lds((const unsigned*)((const char*)(gbase) + (voff)[_i]), (LAS unsigned*)(lds + (bufoff) + ldsw + _i * 8192), 16, 0, 0); } while (0)
; #define PG8_LDA(dst, b, h) do { _Pragma("unroll") for (int m = 0; m < 4; ++m) _Pragma("unroll") for (int k = 0; k < 2; ++k) dst[m][k] = *(const LAS bf16x8*)(lds + PG8_SA(b, h) + aoff + m * 2048 + k * 1024); } while (0)
; #define PG8_LDB(dst, b, h) do { _Pragma("unroll") for (int n = 0; n < 2; ++n) _Pragma("unroll") for (int k = 0; k < 2; ++k) dst[n][k] = *(const LAS bf16x8*)(lds + PG8_SB(b, h) + boff + n * 2048 + k * 1024); } while (0)
; #define PG8_MMA(ai, bj, At, Bt) do { __builtin_amdgcn_s_setprio(1); _Pragma("unroll") for (int m = 0; m < 4; ++m) _Pragma("unroll") for (int n = 0; n < 2; ++n) _Pragma("unroll") for (int k = 0; k < 2; ++k) \
;         acc[ai][bj][m][n] = __builtin_amdgcn_mfma_f32_16x16x32_bf16(Bt[n][k], At[m][k], acc[ai][bj][m][n], 0, 0, 0); __builtin_amdgcn_s_setprio(0); } while (0)
; #define PG8_WAIT_V(n) asm volatile("s_waitcnt vmcnt(" #n ")" ::: "memory")
; #define PG8_WAIT_L(n) asm volatile("s_waitcnt lgkmcnt(" #n ")" ::: "memory")
; #define PG8_BAR __builtin_amdgcn_s_barrier()
; #define PG8_SCHED __builtin_amdgcn_sched_barrier(0)
; template <class Epi>
; __device__ __forceinline__ void gemm_phase(LAS unsigned char* lds, const Gemm g, const StaticOrder& S, const Epi& E) {
;     ...
;             PG8_LDB(B0, 1, 0); PG8_SCHED; PG8_LDA(At, 1, 0); PG8_STAGE(PG8_SA(0, 1), a2 + hstep, voffA);
;             PG8_WAIT_L(8); PG8_BAR; PG8_WAIT_L(0); PG8_MMA(0, 0, At, B0); PG8_BAR; PG8_SCHED;
;             PG8_LDB(B1, 1, 1); PG8_STAGE(PG8_SB(1, 0), b3, voffB0);
;             PG8_BAR; PG8_WAIT_L(0); PG8_MMA(0, 1, At, B1); PG8_BAR;
;             PG8_LDA(At, 1, 1); PG8_STAGE(PG8_SA(1, 0), a3, voffA);
;             PG8_BAR; PG8_WAIT_L(0); PG8_MMA(1, 0, At, B0); PG8_BAR; PG8_SCHED;
;             PG8_STAGE(PG8_SB(1, 1), b3, voffB1);
;             PG8_WAIT_V(6); PG8_BAR; PG8_MMA(1, 1, At, B1); PG8_BAR;
	v_mfma_f32_16x16x32_bf16 v[52:55], v[208:211], v[172:175], v[52:55]
	v_mfma_f32_16x16x32_bf16 v[48:51], v[216:219], v[172:175], v[48:51]
	v_mfma_f32_16x16x32_bf16 v[36:39], v[208:211], v[180:183], v[36:39]
	v_mfma_f32_16x16x32_bf16 v[32:35], v[216:219], v[180:183], v[32:35]
	v_mfma_f32_16x16x32_bf16 v[20:23], v[208:211], v[188:191], v[20:23]
	v_mfma_f32_16x16x32_bf16 v[16:19], v[216:219], v[188:191], v[16:19]
	v_mfma_f32_16x16x32_bf16 v[4:7], v[208:211], v[196:199], v[4:7]
	v_mfma_f32_16x16x32_bf16 v[0:3], v[216:219], v[196:199], v[0:3]
	v_mfma_f32_16x16x32_bf16 v[52:55], v[212:215], v[176:179], v[52:55]
	v_mfma_f32_16x16x32_bf16 v[48:51], v[220:223], v[176:179], v[48:51]
	v_mfma_f32_16x16x32_bf16 v[36:39], v[212:215], v[184:187], v[36:39]
	v_mfma_f32_16x16x32_bf16 v[32:35], v[220:223], v[184:187], v[32:35]
	v_mfma_f32_16x16x32_bf16 v[20:23], v[212:215], v[192:195], v[20:23]
	v_mfma_f32_16x16x32_bf16 v[16:19], v[220:223], v[192:195], v[16:19]
	v_mfma_f32_16x16x32_bf16 v[4:7], v[212:215], v[204:207], v[4:7]
	v_mfma_f32_16x16x32_bf16 v[0:3], v[220:223], v[204:207], v[0:3]
	s_add_i32 s33, 0, 0x18000
	v_add_u32_e32 v168, s33, v153
	s_barrier
	ds_read_b128 v[146:149], v168
	ds_read_b128 v[160:163], v168 offset:1024
	ds_read_b128 v[164:167], v168 offset:2048
	ds_read_b128 v[168:171], v168 offset:3072
	s_add_u32 s52, s52, 0x200000
	s_addc_u32 s53, s53, 0
	s_mov_b32 m0, s64
	v_lshl_add_u64 v[208:209], s[52:53], 0, v[128:129]
	ds_read_b128 v[172:175], v157 offset:32768
	ds_read_b128 v[176:179], v157 offset:33792
	ds_read_b128 v[180:183], v157 offset:34816
	ds_read_b128 v[184:187], v157 offset:35840
	ds_read_b128 v[188:191], v157 offset:36864
	ds_read_b128 v[192:195], v157 offset:37888
	ds_read_b128 v[196:199], v157 offset:38912
	ds_read_b128 v[204:207], v157 offset:39936
	global_load_lds_dwordx4 v[208:209], off
	v_lshl_add_u64 v[208:209], s[52:53], 0, v[134:135]
	s_mov_b32 m0, s65
	s_nop 0
	global_load_lds_dwordx4 v[208:209], off
	s_waitcnt lgkmcnt(8)
	s_barrier
	s_waitcnt lgkmcnt(0)
	v_mfma_f32_16x16x32_bf16 v[124:127], v[146:149], v[172:175], v[124:127]
	v_mfma_f32_16x16x32_bf16 v[120:123], v[164:167], v[172:175], v[120:123]
	v_mfma_f32_16x16x32_bf16 v[108:111], v[146:149], v[180:183], v[108:111]
	v_mfma_f32_16x16x32_bf16 v[104:107], v[164:167], v[180:183], v[104:107]
	v_mfma_f32_16x16x32_bf16 v[92:95], v[146:149], v[188:191], v[92:95]
	v_mfma_f32_16x16x32_bf16 v[88:91], v[164:167], v[188:191], v[88:91]
	v_mfma_f32_16x16x32_bf16 v[76:79], v[146:149], v[196:199], v[76:79]
	v_mfma_f32_16x16x32_bf16 v[72:75], v[164:167], v[196:199], v[72:75]
	v_mfma_f32_16x16x32_bf16 v[124:127], v[160:163], v[176:179], v[124:127]
	v_mfma_f32_16x16x32_bf16 v[120:123], v[168:171], v[176:179], v[120:123]
	v_mfma_f32_16x16x32_bf16 v[108:111], v[160:163], v[184:187], v[108:111]
	v_mfma_f32_16x16x32_bf16 v[104:107], v[168:171], v[184:187], v[104:107]
	v_mfma_f32_16x16x32_bf16 v[92:95], v[160:163], v[192:195], v[92:95]
	v_mfma_f32_16x16x32_bf16 v[88:91], v[168:171], v[192:195], v[88:91]
	v_mfma_f32_16x16x32_bf16 v[76:79], v[160:163], v[204:207], v[76:79]
	v_mfma_f32_16x16x32_bf16 v[72:75], v[168:171], v[204:207], v[72:75]
	s_barrier
	s_add_i32 s52, 0, 0x1c000
	s_add_i32 s33, s33, s62
	v_add_u32_e32 v220, s52, v153
	v_lshl_add_u64 v[150:151], v[150:151], 0, s[18:19]
	s_mov_b32 m0, s33
	ds_read_b128 v[208:211], v220
	ds_read_b128 v[212:215], v220 offset:1024
	ds_read_b128 v[216:219], v220 offset:2048
	ds_read_b128 v[220:223], v220 offset:3072
	global_load_lds_dwordx4 v[150:151], off
	v_lshl_add_u64 v[150:151], v[200:201], 0, s[18:19]
	s_add_i32 m0, s33, 0x2000
	s_nop 0
	global_load_lds_dwordx4 v[150:151], off
	s_barrier
	s_waitcnt lgkmcnt(0)
	v_mfma_f32_16x16x32_bf16 v[116:119], v[208:211], v[172:175], v[116:119]
	v_mfma_f32_16x16x32_bf16 v[112:115], v[216:219], v[172:175], v[112:115]
	v_mfma_f32_16x16x32_bf16 v[100:103], v[208:211], v[180:183], v[100:103]
	v_mfma_f32_16x16x32_bf16 v[96:99], v[216:219], v[180:183], v[96:99]
	v_mfma_f32_16x16x32_bf16 v[84:87], v[208:211], v[188:191], v[84:87]
	v_mfma_f32_16x16x32_bf16 v[80:83], v[216:219], v[188:191], v[80:83]
	v_mfma_f32_16x16x32_bf16 v[68:71], v[208:211], v[196:199], v[68:71]
	v_mfma_f32_16x16x32_bf16 v[64:67], v[216:219], v[196:199], v[64:67]
	v_mfma_f32_16x16x32_bf16 v[116:119], v[212:215], v[176:179], v[116:119]
	v_mfma_f32_16x16x32_bf16 v[112:115], v[220:223], v[176:179], v[112:115]
	v_mfma_f32_16x16x32_bf16 v[100:103], v[212:215], v[184:187], v[100:103]
	v_mfma_f32_16x16x32_bf16 v[96:99], v[220:223], v[184:187], v[96:99]
	v_mfma_f32_16x16x32_bf16 v[84:87], v[212:215], v[192:195], v[84:87]
	v_mfma_f32_16x16x32_bf16 v[80:83], v[220:223], v[192:195], v[80:83]
	v_mfma_f32_16x16x32_bf16 v[68:71], v[212:215], v[204:207], v[68:71]
	v_mfma_f32_16x16x32_bf16 v[64:67], v[220:223], v[204:207], v[64:67]
	s_mov_b32 m0, s67
	v_lshl_add_u64 v[150:151], v[224:225], 0, s[18:19]
	s_barrier
	ds_read_b128 v[172:175], v157 offset:49152
	ds_read_b128 v[176:179], v157 offset:50176
	ds_read_b128 v[180:183], v157 offset:51200
	ds_read_b128 v[184:187], v157 offset:52224
	ds_read_b128 v[188:191], v157 offset:53248
	ds_read_b128 v[192:195], v157 offset:54272
	ds_read_b128 v[196:199], v157 offset:55296
	ds_read_b128 v[204:207], v157 offset:56320
	global_load_lds_dwordx4 v[150:151], off
	v_lshl_add_u64 v[150:151], v[226:227], 0, s[18:19]
	s_mov_b32 m0, s68
	s_nop 0
	global_load_lds_dwordx4 v[150:151], off
	s_barrier
; #define PG8_STAGE(bufoff, gbase, voff) do { _Pragma("unroll") for (int _i = 0; _i < 2; ++_i) \
;         __builtin_amdgcn_global_load_lds((const unsigned*)((const char*)(gbase) + (voff)[_i]), (LAS unsigned*)(lds + (bufoff) + ldsw + _i * 8192), 16, 0, 0); } while (0)
; #define PG8_LDA(dst, b, h) do { _Pragma("unroll") for (int m = 0; m < 4; ++m) _Pragma("unroll") for (int k = 0; k < 2; ++k) dst[m][k] = *(const LAS bf16x8*)(lds + PG8_SA(b, h) + aoff + m * 2048 + k * 1024); } while (0)
; #define PG8_LDB(dst, b, h) do { _Pragma("unroll") for (int n = 0; n < 2; ++n) _Pragma("unroll") for (int k = 0; k < 2; ++k) dst[n][k] = *(const LAS bf16x8*)(lds + PG8_SB(b, h) + boff + n * 2048 + k * 1024); } while (0)
; #define PG8_WAIT_V(n) asm volatile("s_waitcnt vmcnt(" #n ")" ::: "memory")
; #define PG8_WAIT_L(n) asm volatile("s_waitcnt lgkmcnt(" #n ")" ::: "memory")
; #define PG8_BAR __builtin_amdgcn_s_barrier()
; #define PG8_SCHED __builtin_amdgcn_sched_barrier(0)
;     __device__ __forceinline__ void operator()(const f32x4 (&acc)[2][2][4][2], const Unit& u, int wr, int wc, int fr, int fq) const {
;     ...
;             for (int m = 0; m < 4; ++m) { const int row = row0 + ai * HALF + m * 16; const size_t off = (size_t)row * D + col0; float sq = 0.f; u32x4 w[2];
;                 const float sc = rsin ? __builtin_amdgcn_rcpf(rsin[row] * (1.f / D) + EPS) : 1.0f;
;                 u32x4 rr[2]; if (R) load_pair_lines(R, D, row, fr, col0, rr[0], rr[1]);
; template <class Epi>
; __device__ __forceinline__ void gemm_phase(LAS unsigned char* lds, const Gemm g, const StaticOrder& S, const Epi& E) {
;     ...
;             PG8_WAIT_V(6); PG8_BAR; PG8_MMA(1, 1, At, B1); PG8_BAR;
;             PG8_LDB(B0, 1, 0); PG8_SCHED; PG8_LDA(At, 1, 0); PG8_STAGE(PG8_SA(0, 1), a2 + hstep, voffA);
;             PG8_WAIT_L(8); PG8_BAR; PG8_WAIT_L(0); PG8_MMA(0, 0, At, B0); PG8_BAR; PG8_SCHED;
;             PG8_LDB(B1, 1, 1); PG8_STAGE(PG8_SB(1, 0), b3, voffB0);
;             PG8_BAR; PG8_WAIT_L(0); PG8_MMA(0, 1, At, B1); PG8_BAR;
;             PG8_LDA(At, 1, 1); PG8_STAGE(PG8_SA(1, 0), a3, voffA);
;             PG8_BAR; PG8_WAIT_L(0); PG8_MMA(1, 0, At, B0); PG8_BAR; PG8_SCHED;
;             PG8_STAGE(PG8_SB(1, 1), b3, voffB1);
;             PG8_WAIT_V(6); PG8_BAR; PG8_MMA(1, 1, At, B1); PG8_BAR;
;         }
;         E(acc, cur, wr, wc, fr, fq);
;         if (!has_next) break;
	s_waitcnt lgkmcnt(0)
	v_mfma_f32_16x16x32_bf16 v[60:63], v[146:149], v[172:175], v[60:63]
	v_mfma_f32_16x16x32_bf16 v[56:59], v[164:167], v[172:175], v[56:59]
	v_mfma_f32_16x16x32_bf16 v[44:47], v[146:149], v[180:183], v[44:47]
	v_mfma_f32_16x16x32_bf16 v[40:43], v[164:167], v[180:183], v[40:43]
	v_mfma_f32_16x16x32_bf16 v[28:31], v[146:149], v[188:191], v[28:31]
	v_mfma_f32_16x16x32_bf16 v[24:27], v[164:167], v[188:191], v[24:27]
	v_mfma_f32_16x16x32_bf16 v[12:15], v[146:149], v[196:199], v[12:15]
	v_mfma_f32_16x16x32_bf16 v[8:11], v[164:167], v[196:199], v[8:11]
	v_mfma_f32_16x16x32_bf16 v[60:63], v[160:163], v[176:179], v[60:63]
	v_mfma_f32_16x16x32_bf16 v[56:59], v[168:171], v[176:179], v[56:59]
	v_mfma_f32_16x16x32_bf16 v[44:47], v[160:163], v[184:187], v[44:47]
	v_mfma_f32_16x16x32_bf16 v[40:43], v[168:171], v[184:187], v[40:43]
	v_mfma_f32_16x16x32_bf16 v[28:31], v[160:163], v[192:195], v[28:31]
	v_mfma_f32_16x16x32_bf16 v[24:27], v[168:171], v[192:195], v[24:27]
	v_mfma_f32_16x16x32_bf16 v[12:15], v[160:163], v[204:207], v[12:15]
	v_mfma_f32_16x16x32_bf16 v[8:11], v[168:171], v[204:207], v[8:11]
	s_barrier
	s_add_i32 s33, s52, s62
	v_lshl_add_u64 v[146:147], v[228:229], 0, s[18:19]
	s_mov_b32 m0, s33
	s_nop 0
	global_load_lds_dwordx4 v[146:147], off
	v_lshl_add_u64 v[146:147], v[230:231], 0, s[18:19]
	s_add_i32 m0, s33, 0x2000
	s_nop 0
	global_load_lds_dwordx4 v[146:147], off
	s_waitcnt vmcnt(6)
	s_barrier
	v_mfma_f32_16x16x32_bf16 v[52:55], v[208:211], v[172:175], v[52:55]
	v_mfma_f32_16x16x32_bf16 v[48:51], v[216:219], v[172:175], v[48:51]
	v_mfma_f32_16x16x32_bf16 v[36:39], v[208:211], v[180:183], v[36:39]
	v_mfma_f32_16x16x32_bf16 v[32:35], v[216:219], v[180:183], v[32:35]
	v_mfma_f32_16x16x32_bf16 v[20:23], v[208:211], v[188:191], v[20:23]
	v_mfma_f32_16x16x32_bf16 v[16:19], v[216:219], v[188:191], v[16:19]
	v_mfma_f32_16x16x32_bf16 v[4:7], v[208:211], v[196:199], v[4:7]
	v_mfma_f32_16x16x32_bf16 v[0:3], v[216:219], v[196:199], v[0:3]
	v_mfma_f32_16x16x32_bf16 v[52:55], v[212:215], v[176:179], v[52:55]
	v_mfma_f32_16x16x32_bf16 v[48:51], v[220:223], v[176:179], v[48:51]
	v_mfma_f32_16x16x32_bf16 v[36:39], v[212:215], v[184:187], v[36:39]
	v_mfma_f32_16x16x32_bf16 v[32:35], v[220:223], v[184:187], v[32:35]
	v_mfma_f32_16x16x32_bf16 v[20:23], v[212:215], v[192:195], v[20:23]
	v_mfma_f32_16x16x32_bf16 v[16:19], v[220:223], v[192:195], v[16:19]
	v_mfma_f32_16x16x32_bf16 v[4:7], v[212:215], v[204:207], v[4:7]
	v_mfma_f32_16x16x32_bf16 v[0:3], v[220:223], v[204:207], v[0:3]
	s_add_i32 s80, s80, 2
	s_add_u32 s50, s50, 0x100
	s_addc_u32 s51, s51, 0
	s_add_u32 s78, s78, 0x100
	s_addc_u32 s79, s79, 0
	s_cmpk_gt_u32 s80, 0x7d
	s_barrier
	s_cbranch_scc0 .LBB0_806
	s_lshl_b32 s33, s48, 8
	s_add_i32 s33, s33, s69
	v_or_b32_e32 v164, s33, v154
	v_ashrrev_i32_e32 v165, 31, v164
	v_lshl_or_b32 v146, s74, 8, v155
	v_lshlrev_b64 v[168:169], 12, v[164:165]
	v_or_b32_e32 v164, 8, v164
	v_or_b32_e32 v150, s33, v152
	v_ashrrev_i32_e32 v147, 31, v146
	v_ashrrev_i32_e32 v165, 31, v164
	v_ashrrev_i32_e32 v151, 31, v150
	v_lshl_add_u64 v[160:161], s[16:17], 0, v[168:169]
	v_lshlrev_b64 v[146:147], 1, v[146:147]
	v_lshlrev_b64 v[170:171], 12, v[164:165]
	v_lshl_add_u64 v[148:149], v[150:151], 2, s[10:11]
	v_lshl_add_u64 v[160:161], v[160:161], 0, v[146:147]
	v_lshl_add_u64 v[164:165], s[16:17], 0, v[170:171]
	global_load_dword v151, v[148:149], off
	s_nop 0
	global_load_dwordx4 v[160:163], v[160:161], off
	v_lshl_add_u64 v[164:165], v[164:165], 0, v[146:147]
	global_load_dwordx4 v[164:167], v[164:165], off
	v_or_b32_e32 v190, 16, v150
	v_ashrrev_i32_e32 v191, 31, v190
	v_lshl_add_u64 v[192:193], v[190:191], 2, s[10:11]
	v_sub_u32_e32 v190, v190, v152
	v_add_u32_e32 v190, v190, v154
	v_ashrrev_i32_e32 v191, 31, v190
	v_lshlrev_b64 v[196:197], 12, v[190:191]
	v_lshl_add_u64 v[190:191], s[16:17], 0, v[196:197]
	v_lshl_add_u64 v[198:199], v[196:197], 0, s[36:37]
	v_lshl_add_u64 v[190:191], v[190:191], 0, v[146:147]
	v_lshl_add_u64 v[194:195], s[16:17], 0, v[198:199]
	global_load_dword v204, v[192:193], off
	global_load_dwordx4 v[208:211], v[190:191], off
	v_lshl_add_u64 v[194:195], v[194:195], 0, v[146:147]
	global_load_dwordx4 v[212:215], v[194:195], off
	v_or_b32_e32 v190, 32, v150
	v_ashrrev_i32_e32 v191, 31, v190
	v_lshl_add_u64 v[192:193], v[190:191], 2, s[10:11]
	v_sub_u32_e32 v190, v190, v152
	v_add_u32_e32 v190, v190, v154
	v_ashrrev_i32_e32 v191, 31, v190
	v_lshlrev_b64 v[196:197], 12, v[190:191]
	v_lshl_add_u64 v[190:191], s[16:17], 0, v[196:197]
	v_lshl_add_u64 v[198:199], v[196:197], 0, s[36:37]
	v_lshl_add_u64 v[190:191], v[190:191], 0, v[146:147]
	v_lshl_add_u64 v[194:195], s[16:17], 0, v[198:199]
	global_load_dword v205, v[192:193], off
	global_load_dwordx4 v[216:219], v[190:191], off
	v_lshl_add_u64 v[194:195], v[194:195], 0, v[146:147]
	global_load_dwordx4 v[220:223], v[194:195], off
	v_or_b32_e32 v190, 48, v150
	v_ashrrev_i32_e32 v191, 31, v190
	v_lshl_add_u64 v[192:193], v[190:191], 2, s[10:11]
	v_sub_u32_e32 v190, v190, v152
	v_add_u32_e32 v190, v190, v154
	v_ashrrev_i32_e32 v191, 31, v190
	v_lshlrev_b64 v[196:197], 12, v[190:191]
	v_lshl_add_u64 v[190:191], s[16:17], 0, v[196:197]
	v_lshl_add_u64 v[198:199], v[196:197], 0, s[36:37]
	v_lshl_add_u64 v[190:191], v[190:191], 0, v[146:147]
	v_lshl_add_u64 v[194:195], s[16:17], 0, v[198:199]
	global_load_dword v206, v[192:193], off
	global_load_dwordx4 v[224:227], v[190:191], off
	v_lshl_add_u64 v[194:195], v[194:195], 0, v[146:147]
	global_load_dwordx4 v[228:231], v[194:195], off
	v_sub_u32_e32 v190, v150, v152
	v_add_u32_e32 v199, v190, v154
	v_add_u32_e32 v190, 0x80, v199
	v_ashrrev_i32_e32 v191, 31, v190
	v_lshlrev_b64 v[194:195], 12, v[190:191]
	v_lshl_add_u64 v[190:191], s[16:17], 0, v[194:195]
	v_lshl_add_u64 v[196:197], v[194:195], 0, s[36:37]
	v_lshl_add_u64 v[190:191], v[190:191], 0, v[146:147]
	v_lshl_add_u64 v[192:193], s[16:17], 0, v[196:197]
	global_load_dword v207, v[148:149], off offset:512
	global_load_dwordx4 v[232:235], v[190:191], off
	v_lshl_add_u64 v[192:193], v[192:193], 0, v[146:147]
	global_load_dwordx4 v[236:239], v[192:193], off
	v_sub_u32_e32 v198, v150, v152
	v_add_u32_e32 v201, v198, v154
	v_add_u32_e32 v190, 0x90, v201
	v_ashrrev_i32_e32 v191, 31, v190
	v_lshlrev_b64 v[194:195], 12, v[190:191]
	v_lshl_add_u64 v[190:191], s[16:17], 0, v[194:195]
	v_lshl_add_u64 v[196:197], v[194:195], 0, s[36:37]
	v_lshl_add_u64 v[190:191], v[190:191], 0, v[146:147]
	v_lshl_add_u64 v[192:193], s[16:17], 0, v[196:197]
	global_load_dword v240, v[148:149], off offset:576
	global_load_dwordx4 v[244:247], v[190:191], off
	v_lshl_add_u64 v[192:193], v[192:193], 0, v[146:147]
	global_load_dwordx4 v[248:251], v[192:193], off
	s_and_b64 vcc, exec, s[44:45]
	s_mov_b32 s74, s38
	s_mov_b32 s48, s40
	s_mov_b64 s[52:53], s[46:47]
	s_mov_b64 s[50:51], s[42:43]
	s_waitcnt vmcnt(15)
; __device__ __forceinline__ void store_pair_lines(bf16_t* O, int ldc, int row, int fr, int col0, u32x4 wA, u32x4 wB) {
;     const u32x4 sA = {dpp_ror8(wA.x), dpp_ror8(wA.y), dpp_ror8(wA.z), dpp_ror8(wA.w)}, sB = {dpp_ror8(wB.x), dpp_ror8(wB.y), dpp_ror8(wB.z), dpp_ror8(wB.w)};
;     const bool lo = fr < 8;
;     const u32x4 o1 = lo ? wA : sB, o2 = lo ? sA : wB;
;     const int r1 = row - fr + (fr & 7), cb = col0 + (lo ? 0 : 8);
;     *(u32x4*)(O + (size_t)r1 * ldc + cb) = o1;
;     *(u32x4*)(O + (size_t)(r1 + 8) * ldc + cb) = o2;
; }
;     const bool lo = fr < 8;
;     const int r1 = row - fr + (fr & 7), cb = col0 + (lo ? 0 : boff);
;     const u32x4 l1 = *(const u32x4*)(P + (size_t)r1 * ld + cb), l2 = *(const u32x4*)(P + (size_t)(r1 + 8) * ld + cb);
;     const u32x4 s1 = {dpp_ror8(l1.x), dpp_ror8(l1.y), dpp_ror8(l1.z), dpp_ror8(l1.w)}, s2 = {dpp_ror8(l2.x), dpp_ror8(l2.y), dpp_ror8(l2.z), dpp_ror8(l2.w)};
;     wA = lo ? l1 : s2; wB = lo ? s1 : l2;
;     __device__ __forceinline__ void operator()(const f32x4 (&acc)[2][2][4][2], const Unit& u, int wr, int wc, int fr, int fq) const {
;     ...
;             for (int m = 0; m < 4; ++m) { const int row = row0 + ai * HALF + m * 16; const size_t off = (size_t)row * D + col0; float sq = 0.f; u32x4 w[2];
;                 const float sc = rsin ? __builtin_amdgcn_rcpf(rsin[row] * (1.f / D) + EPS) : 1.0f;
;                 u32x4 rr[2]; if (R) load_pair_lines(R, D, row, fr, col0, rr[0], rr[1]);
; #pragma unroll
;                 for (int bj = 0; bj < 2; ++bj) { f32x4 r0, r1;
;                     if (R) { const u32x4 rw = rr[bj]; r0 = (f32x4){bflo(rw.x), bfhi(rw.x), bflo(rw.y), bfhi(rw.y)}; r1 = (f32x4){bflo(rw.z), bfhi(rw.z), bflo(rw.w), bfhi(rw.w)}; }
;                     else { const float* rp = (row < 8192 ? src_p + off : src_s + (off - (size_t)8192 * D)) + 8 * bj; r0 = *(const f32x4*)rp; r1 = *(const f32x4*)(rp + 4); }
;                     const f32x4 o0 = r0 + acc[ai][bj][m][0] * sc, o1 = r1 + acc[ai][bj][m][1] * sc;
;                     sq += (o0[0] * o0[0] + o0[1] * o0[1]) + (o0[2] * o0[2] + o0[3] * o0[3]) + (o1[0] * o1[0] + o1[1] * o1[1]) + (o1[2] * o1[2] + o1[3] * o1[3]);
;                     w[bj].x = cvt_pk_bf16(o0[0], o0[1]); w[bj].y = cvt_pk_bf16(o0[2], o0[3]); w[bj].z = cvt_pk_bf16(o1[0], o1[1]); w[bj].w = cvt_pk_bf16(o1[2], o1[3]); }
;                 store_pair_lines(O, D, row, fr, col0, w[0], w[1]);
	v_fmamk_f32 v151, v151, 0x3a000000, v159
	v_rcp_f32_e32 v172, v151
	v_mov_b32_dpp v173, v160 row_ror:8 row_mask:0xf bank_mask:0xf
	v_mov_b32_dpp v174, v161 row_ror:8 row_mask:0xf bank_mask:0xf
	v_mov_b32_dpp v175, v162 row_ror:8 row_mask:0xf bank_mask:0xf
	v_mov_b32_dpp v177, v164 row_ror:8 row_mask:0xf bank_mask:0xf
	v_mov_b32_dpp v178, v165 row_ror:8 row_mask:0xf bank_mask:0xf
	v_mov_b32_dpp v179, v166 row_ror:8 row_mask:0xf bank_mask:0xf
	v_mov_b32_dpp v176, v163 row_ror:8 row_mask:0xf bank_mask:0xf
	v_mov_b32_dpp v180, v167 row_ror:8 row_mask:0xf bank_mask:0xf
	v_cndmask_b32_e64 v166, v166, v175, s[6:7]
	v_cndmask_b32_e64 v165, v165, v174, s[6:7]
	v_cndmask_b32_e64 v164, v164, v173, s[6:7]
	v_cndmask_b32_e64 v179, v179, v162, s[6:7]
	v_cndmask_b32_e64 v178, v178, v161, s[6:7]
	v_cndmask_b32_e64 v175, v177, v160, s[6:7]
	v_cndmask_b32_e64 v151, v167, v176, s[6:7]
	v_cndmask_b32_e64 v173, v180, v163, s[6:7]
	v_lshlrev_b32_e32 v160, 16, v164
	v_and_b32_e32 v161, 0xffff0000, v164
	v_lshlrev_b32_e32 v162, 16, v165
	v_and_b32_e32 v163, 0xffff0000, v165
	v_lshlrev_b32_e32 v174, 16, v175
	v_and_b32_e32 v175, 0xffff0000, v175
	v_lshlrev_b32_e32 v176, 16, v178
	v_and_b32_e32 v177, 0xffff0000, v178
	v_lshlrev_b32_e32 v178, 16, v179
	v_and_b32_e32 v179, 0xffff0000, v179
	v_lshlrev_b32_e32 v164, 16, v166
	v_and_b32_e32 v165, 0xffff0000, v166
	v_lshlrev_b32_e32 v166, 16, v151
	v_and_b32_e32 v167, 0xffff0000, v151
	v_lshlrev_b32_e32 v180, 16, v173
	v_and_b32_e32 v181, 0xffff0000, v173
	v_pk_fma_f32 v[118:119], v[118:119], v[172:173], v[162:163] op_sel_hi:[1,0,1]
	v_pk_fma_f32 v[116:117], v[116:117], v[172:173], v[160:161] op_sel_hi:[1,0,1]
	v_pk_fma_f32 v[124:125], v[124:125], v[172:173], v[174:175] op_sel_hi:[1,0,1]
	v_pk_fma_f32 v[120:121], v[120:121], v[172:173], v[178:179] op_sel_hi:[1,0,1]
	v_pk_fma_f32 v[114:115], v[114:115], v[172:173], v[166:167] op_sel_hi:[1,0,1]
	v_pk_fma_f32 v[112:113], v[112:113], v[172:173], v[164:165] op_sel_hi:[1,0,1]
	v_pk_fma_f32 v[126:127], v[126:127], v[172:173], v[176:177] op_sel_hi:[1,0,1]
	v_pk_fma_f32 v[122:123], v[122:123], v[172:173], v[180:181] op_sel_hi:[1,0,1]
	v_cvt_pk_bf16_f32 v124, v124, v125
	v_cvt_pk_bf16_f32 v125, v126, v127
	v_cvt_pk_bf16_f32 v120, v120, v121
	v_cvt_pk_bf16_f32 v121, v122, v123
	v_cvt_pk_bf16_f32 v116, v116, v117
	v_cvt_pk_bf16_f32 v117, v118, v119
	v_cvt_pk_bf16_f32 v118, v112, v113
	v_cvt_pk_bf16_f32 v119, v114, v115
	s_nop 0
	v_mov_b32_dpp v184, v120 row_ror:8 row_mask:0xf bank_mask:0xf
	v_mov_b32_dpp v185, v121 row_ror:8 row_mask:0xf bank_mask:0xf
	v_mov_b32_dpp v188, v118 row_ror:8 row_mask:0xf bank_mask:0xf
	v_mov_b32_dpp v189, v119 row_ror:8 row_mask:0xf bank_mask:0xf
	v_mov_b32_dpp v186, v116 row_ror:8 row_mask:0xf bank_mask:0xf
	v_mov_b32_dpp v187, v117 row_ror:8 row_mask:0xf bank_mask:0xf
	v_cndmask_b32_e64 v114, v188, v120, s[6:7]
	v_cndmask_b32_e64 v115, v189, v121, s[6:7]
	v_lshl_add_u64 v[120:121], s[8:9], 0, v[168:169]
	v_cndmask_b32_e64 v112, v186, v124, s[6:7]
	v_cndmask_b32_e64 v113, v187, v125, s[6:7]
	v_lshl_add_u64 v[120:121], v[120:121], 0, v[146:147]
	v_mov_b32_dpp v182, v124 row_ror:8 row_mask:0xf bank_mask:0xf
	v_mov_b32_dpp v183, v125 row_ror:8 row_mask:0xf bank_mask:0xf
	global_store_dwordx4 v[120:121], v[112:115], off
	v_cndmask_b32_e64 v116, v116, v182, s[6:7]
	v_cndmask_b32_e64 v117, v117, v183, s[6:7]
	v_lshl_add_u64 v[112:113], s[8:9], 0, v[170:171]
	v_cndmask_b32_e64 v118, v118, v184, s[6:7]
	v_cndmask_b32_e64 v119, v119, v185, s[6:7]
	v_lshl_add_u64 v[112:113], v[112:113], 0, v[146:147]
	global_store_dwordx4 v[112:113], v[116:119], off
	v_or_b32_e32 v112, 16, v150
	v_ashrrev_i32_e32 v113, 31, v112
	v_lshl_add_u64 v[114:115], v[112:113], 2, s[10:11]
	v_sub_u32_e32 v112, v112, v152
	v_add_u32_e32 v112, v112, v154
	v_ashrrev_i32_e32 v113, 31, v112
	v_lshlrev_b64 v[120:121], 12, v[112:113]
	v_lshl_add_u64 v[112:113], s[16:17], 0, v[120:121]
	v_lshl_add_u64 v[122:123], v[120:121], 0, s[36:37]
	v_lshl_add_u64 v[112:113], v[112:113], 0, v[146:147]
	v_lshl_add_u64 v[116:117], s[16:17], 0, v[122:123]
	s_waitcnt vmcnt(14)
	s_nop 0
	v_mov_b32_e32 v124, v204
	s_nop 0
	v_mov_b64_e32 v[112:113], v[208:209]
	v_mov_b64_e32 v[114:115], v[210:211]
	v_lshl_add_u64 v[116:117], v[116:117], 0, v[146:147]
	v_mov_b64_e32 v[116:117], v[212:213]
	v_mov_b64_e32 v[118:119], v[214:215]
	s_nop 1
	v_sub_u32_e32 v198, v150, v152
	v_add_u32_e32 v201, v198, v154
	v_add_u32_e32 v190, 0xa0, v201
	v_ashrrev_i32_e32 v191, 31, v190
	v_lshlrev_b64 v[194:195], 12, v[190:191]
	v_lshl_add_u64 v[196:197], v[194:195], 0, s[36:37]
	global_load_dword v204, v[148:149], off offset:640
	v_lshl_add_u64 v[190:191], s[16:17], 0, v[194:195]
	v_lshl_add_u64 v[192:193], s[16:17], 0, v[196:197]
	v_lshl_add_u64 v[190:191], v[190:191], 0, v[146:147]
	v_lshl_add_u64 v[192:193], v[192:193], 0, v[146:147]
	global_load_dwordx4 v[208:211], v[190:191], off
	global_load_dwordx4 v[212:215], v[192:193], off
	v_fmamk_f32 v124, v124, 0x3a000000, v159
	v_rcp_f32_e32 v124, v124
	v_mov_b32_dpp v125, v112 row_ror:8 row_mask:0xf bank_mask:0xf
	v_mov_b32_dpp v126, v113 row_ror:8 row_mask:0xf bank_mask:0xf
	v_mov_b32_dpp v127, v114 row_ror:8 row_mask:0xf bank_mask:0xf
	v_mov_b32_dpp v151, v115 row_ror:8 row_mask:0xf bank_mask:0xf
	v_mov_b32_dpp v160, v116 row_ror:8 row_mask:0xf bank_mask:0xf
	v_mov_b32_dpp v161, v117 row_ror:8 row_mask:0xf bank_mask:0xf
	v_mov_b32_dpp v162, v118 row_ror:8 row_mask:0xf bank_mask:0xf
	v_mov_b32_dpp v163, v119 row_ror:8 row_mask:0xf bank_mask:0xf
	v_cndmask_b32_e64 v163, v163, v115, s[6:7]
	v_cndmask_b32_e64 v162, v162, v114, s[6:7]
	v_cndmask_b32_e64 v115, v161, v113, s[6:7]
; __device__ __forceinline__ void store_pair_lines(bf16_t* O, int ldc, int row, int fr, int col0, u32x4 wA, u32x4 wB) {
;     const u32x4 sA = {dpp_ror8(wA.x), dpp_ror8(wA.y), dpp_ror8(wA.z), dpp_ror8(wA.w)}, sB = {dpp_ror8(wB.x), dpp_ror8(wB.y), dpp_ror8(wB.z), dpp_ror8(wB.w)};
;     const bool lo = fr < 8;
;     const u32x4 o1 = lo ? wA : sB, o2 = lo ? sA : wB;
;     const int r1 = row - fr + (fr & 7), cb = col0 + (lo ? 0 : 8);
;     *(u32x4*)(O + (size_t)r1 * ldc + cb) = o1;
;     *(u32x4*)(O + (size_t)(r1 + 8) * ldc + cb) = o2;
; }
;     const bool lo = fr < 8;
;     const int r1 = row - fr + (fr & 7), cb = col0 + (lo ? 0 : boff);
;     const u32x4 l1 = *(const u32x4*)(P + (size_t)r1 * ld + cb), l2 = *(const u32x4*)(P + (size_t)(r1 + 8) * ld + cb);
;     const u32x4 s1 = {dpp_ror8(l1.x), dpp_ror8(l1.y), dpp_ror8(l1.z), dpp_ror8(l1.w)}, s2 = {dpp_ror8(l2.x), dpp_ror8(l2.y), dpp_ror8(l2.z), dpp_ror8(l2.w)};
;     wA = lo ? l1 : s2; wB = lo ? s1 : l2;
;     __device__ __forceinline__ void operator()(const f32x4 (&acc)[2][2][4][2], const Unit& u, int wr, int wc, int fr, int fq) const {
;     ...
;             for (int m = 0; m < 4; ++m) { const int row = row0 + ai * HALF + m * 16; const size_t off = (size_t)row * D + col0; float sq = 0.f; u32x4 w[2];
;                 const float sc = rsin ? __builtin_amdgcn_rcpf(rsin[row] * (1.f / D) + EPS) : 1.0f;
;                 u32x4 rr[2]; if (R) load_pair_lines(R, D, row, fr, col0, rr[0], rr[1]);
; #pragma unroll
;                 for (int bj = 0; bj < 2; ++bj) { f32x4 r0, r1;
;                     if (R) { const u32x4 rw = rr[bj]; r0 = (f32x4){bflo(rw.x), bfhi(rw.x), bflo(rw.y), bfhi(rw.y)}; r1 = (f32x4){bflo(rw.z), bfhi(rw.z), bflo(rw.w), bfhi(rw.w)}; }
;                     else { const float* rp = (row < 8192 ? src_p + off : src_s + (off - (size_t)8192 * D)) + 8 * bj; r0 = *(const f32x4*)rp; r1 = *(const f32x4*)(rp + 4); }
;                     const f32x4 o0 = r0 + acc[ai][bj][m][0] * sc, o1 = r1 + acc[ai][bj][m][1] * sc;
;                     sq += (o0[0] * o0[0] + o0[1] * o0[1]) + (o0[2] * o0[2] + o0[3] * o0[3]) + (o1[0] * o1[0] + o1[1] * o1[1]) + (o1[2] * o1[2] + o1[3] * o1[3]);
;                     w[bj].x = cvt_pk_bf16(o0[0], o0[1]); w[bj].y = cvt_pk_bf16(o0[2], o0[3]); w[bj].z = cvt_pk_bf16(o1[0], o1[1]); w[bj].w = cvt_pk_bf16(o1[2], o1[3]); }
;                 store_pair_lines(O, D, row, fr, col0, w[0], w[1]);
	v_cndmask_b32_e64 v113, v160, v112, s[6:7]
	v_cndmask_b32_e64 v151, v119, v151, s[6:7]
	v_cndmask_b32_e64 v164, v118, v127, s[6:7]
	v_cndmask_b32_e64 v161, v117, v126, s[6:7]
	v_cndmask_b32_e64 v125, v116, v125, s[6:7]
	v_lshlrev_b32_e32 v112, 16, v113
	v_and_b32_e32 v113, 0xffff0000, v113
	v_lshlrev_b32_e32 v116, 16, v162
	v_and_b32_e32 v117, 0xffff0000, v162
	v_lshlrev_b32_e32 v118, 16, v163
	v_and_b32_e32 v119, 0xffff0000, v163
	v_lshlrev_b32_e32 v126, 16, v125
	v_and_b32_e32 v127, 0xffff0000, v125
	v_lshlrev_b32_e32 v160, 16, v161
	v_and_b32_e32 v161, 0xffff0000, v161
	v_lshlrev_b32_e32 v162, 16, v164
	v_and_b32_e32 v163, 0xffff0000, v164
	v_lshlrev_b32_e32 v164, 16, v151
	v_and_b32_e32 v165, 0xffff0000, v151
	v_lshlrev_b32_e32 v114, 16, v115
	v_and_b32_e32 v115, 0xffff0000, v115
	v_pk_fma_f32 v[108:109], v[108:109], v[124:125], v[112:113] op_sel_hi:[1,0,1]
	v_pk_fma_f32 v[104:105], v[104:105], v[124:125], v[116:117] op_sel_hi:[1,0,1]
	v_pk_fma_f32 v[102:103], v[102:103], v[124:125], v[160:161] op_sel_hi:[1,0,1]
	v_pk_fma_f32 v[100:101], v[100:101], v[124:125], v[126:127] op_sel_hi:[1,0,1]
	v_pk_fma_f32 v[98:99], v[98:99], v[124:125], v[164:165] op_sel_hi:[1,0,1]
	v_pk_fma_f32 v[110:111], v[110:111], v[124:125], v[114:115] op_sel_hi:[1,0,1]
	v_pk_fma_f32 v[106:107], v[106:107], v[124:125], v[118:119] op_sel_hi:[1,0,1]
	v_pk_fma_f32 v[96:97], v[96:97], v[124:125], v[162:163] op_sel_hi:[1,0,1]
	v_cvt_pk_bf16_f32 v108, v108, v109
	v_cvt_pk_bf16_f32 v109, v110, v111
	v_cvt_pk_bf16_f32 v104, v104, v105
	v_cvt_pk_bf16_f32 v105, v106, v107
	v_cvt_pk_bf16_f32 v100, v100, v101
	v_cvt_pk_bf16_f32 v101, v102, v103
	s_nop 0
	v_cvt_pk_bf16_f32 v102, v96, v97
	v_cvt_pk_bf16_f32 v103, v98, v99
	v_mov_b32_e32 v98, 0
	v_mov_b32_dpp v98, v102 row_ror:8 row_mask:0xf bank_mask:0xf
	v_mov_b32_dpp v99, v103 row_ror:8 row_mask:0xf bank_mask:0xf
	v_mov_b32_dpp v107, v104 row_ror:8 row_mask:0xf bank_mask:0xf
	v_mov_b32_dpp v110, v105 row_ror:8 row_mask:0xf bank_mask:0xf
	v_mov_b32_dpp v96, v100 row_ror:8 row_mask:0xf bank_mask:0xf
	v_mov_b32_dpp v97, v101 row_ror:8 row_mask:0xf bank_mask:0xf
	v_cndmask_b32_e64 v98, v98, v104, s[6:7]
	v_cndmask_b32_e64 v99, v99, v105, s[6:7]
	v_lshl_add_u64 v[104:105], s[8:9], 0, v[120:121]
	v_cndmask_b32_e64 v96, v96, v108, s[6:7]
	v_cndmask_b32_e64 v97, v97, v109, s[6:7]
	v_lshl_add_u64 v[104:105], v[104:105], 0, v[146:147]
	v_mov_b32_dpp v166, v108 row_ror:8 row_mask:0xf bank_mask:0xf
	v_mov_b32_dpp v106, v109 row_ror:8 row_mask:0xf bank_mask:0xf
	global_store_dwordx4 v[104:105], v[96:99], off
	v_cndmask_b32_e64 v100, v100, v166, s[6:7]
	v_cndmask_b32_e64 v101, v101, v106, s[6:7]
	v_lshl_add_u64 v[96:97], s[8:9], 0, v[122:123]
	v_cndmask_b32_e64 v102, v102, v107, s[6:7]
	v_cndmask_b32_e64 v103, v103, v110, s[6:7]
	v_lshl_add_u64 v[96:97], v[96:97], 0, v[146:147]
	global_store_dwordx4 v[96:97], v[100:103], off
	v_or_b32_e32 v96, 32, v150
	v_ashrrev_i32_e32 v97, 31, v96
	v_lshl_add_u64 v[98:99], v[96:97], 2, s[10:11]
	v_sub_u32_e32 v96, v96, v152
	v_add_u32_e32 v96, v96, v154
	v_ashrrev_i32_e32 v97, 31, v96
	v_lshlrev_b64 v[104:105], 12, v[96:97]
	v_lshl_add_u64 v[96:97], s[16:17], 0, v[104:105]
	v_lshl_add_u64 v[106:107], v[104:105], 0, s[36:37]
	v_lshl_add_u64 v[96:97], v[96:97], 0, v[146:147]
	v_lshl_add_u64 v[100:101], s[16:17], 0, v[106:107]
	s_waitcnt vmcnt(16)
	s_nop 0
	v_mov_b32_e32 v108, v205
	s_nop 0
	v_mov_b64_e32 v[96:97], v[216:217]
	v_mov_b64_e32 v[98:99], v[218:219]
	v_lshl_add_u64 v[100:101], v[100:101], 0, v[146:147]
	v_mov_b64_e32 v[100:101], v[220:221]
	v_mov_b64_e32 v[102:103], v[222:223]
	s_nop 1
	v_sub_u32_e32 v198, v150, v152
	v_add_u32_e32 v201, v198, v154
	v_add_u32_e32 v190, 0xb0, v201
	v_ashrrev_i32_e32 v191, 31, v190
	v_lshlrev_b64 v[194:195], 12, v[190:191]
	v_lshl_add_u64 v[196:197], v[194:195], 0, s[36:37]
	global_load_dword v205, v[148:149], off offset:704
	v_lshl_add_u64 v[190:191], s[16:17], 0, v[194:195]
	v_lshl_add_u64 v[192:193], s[16:17], 0, v[196:197]
	v_lshl_add_u64 v[190:191], v[190:191], 0, v[146:147]
	v_lshl_add_u64 v[192:193], v[192:193], 0, v[146:147]
	global_load_dwordx4 v[216:219], v[190:191], off
	global_load_dwordx4 v[220:223], v[192:193], off
	v_fmamk_f32 v108, v108, 0x3a000000, v159
	v_rcp_f32_e32 v108, v108
	v_mov_b32_dpp v109, v96 row_ror:8 row_mask:0xf bank_mask:0xf
	v_mov_b32_dpp v113, v100 row_ror:8 row_mask:0xf bank_mask:0xf
	v_mov_b32_dpp v114, v101 row_ror:8 row_mask:0xf bank_mask:0xf
	v_mov_b32_dpp v115, v102 row_ror:8 row_mask:0xf bank_mask:0xf
	v_mov_b32_dpp v116, v103 row_ror:8 row_mask:0xf bank_mask:0xf
	v_mov_b32_dpp v110, v97 row_ror:8 row_mask:0xf bank_mask:0xf
	v_mov_b32_dpp v111, v98 row_ror:8 row_mask:0xf bank_mask:0xf
	v_mov_b32_dpp v112, v99 row_ror:8 row_mask:0xf bank_mask:0xf
	v_cndmask_b32_e64 v116, v116, v99, s[6:7]
	v_cndmask_b32_e64 v115, v115, v98, s[6:7]
	v_cndmask_b32_e64 v99, v114, v97, s[6:7]
	v_cndmask_b32_e64 v97, v113, v96, s[6:7]
	v_cndmask_b32_e64 v114, v103, v112, s[6:7]
	v_cndmask_b32_e64 v117, v102, v111, s[6:7]
	v_cndmask_b32_e64 v113, v101, v110, s[6:7]
	v_cndmask_b32_e64 v109, v100, v109, s[6:7]
	v_lshlrev_b32_e32 v96, 16, v97
	v_and_b32_e32 v97, 0xffff0000, v97
	v_lshlrev_b32_e32 v98, 16, v99
	v_and_b32_e32 v99, 0xffff0000, v99
	v_lshlrev_b32_e32 v100, 16, v115
	v_and_b32_e32 v101, 0xffff0000, v115
	v_lshlrev_b32_e32 v102, 16, v116
	v_and_b32_e32 v103, 0xffff0000, v116
	v_pk_fma_f32 v[94:95], v[94:95], v[108:109], v[98:99] op_sel_hi:[1,0,1]
	v_pk_fma_f32 v[92:93], v[92:93], v[108:109], v[96:97] op_sel_hi:[1,0,1]
	v_pk_fma_f32 v[90:91], v[90:91], v[108:109], v[102:103] op_sel_hi:[1,0,1]
	v_pk_fma_f32 v[88:89], v[88:89], v[108:109], v[100:101] op_sel_hi:[1,0,1]
; __device__ __forceinline__ void store_pair_lines(bf16_t* O, int ldc, int row, int fr, int col0, u32x4 wA, u32x4 wB) {
;     const u32x4 sA = {dpp_ror8(wA.x), dpp_ror8(wA.y), dpp_ror8(wA.z), dpp_ror8(wA.w)}, sB = {dpp_ror8(wB.x), dpp_ror8(wB.y), dpp_ror8(wB.z), dpp_ror8(wB.w)};
;     const bool lo = fr < 8;
;     const u32x4 o1 = lo ? wA : sB, o2 = lo ? sA : wB;
;     const int r1 = row - fr + (fr & 7), cb = col0 + (lo ? 0 : 8);
;     *(u32x4*)(O + (size_t)r1 * ldc + cb) = o1;
;     *(u32x4*)(O + (size_t)(r1 + 8) * ldc + cb) = o2;
; }
;     const bool lo = fr < 8;
;     const int r1 = row - fr + (fr & 7), cb = col0 + (lo ? 0 : boff);
;     const u32x4 l1 = *(const u32x4*)(P + (size_t)r1 * ld + cb), l2 = *(const u32x4*)(P + (size_t)(r1 + 8) * ld + cb);
;     const u32x4 s1 = {dpp_ror8(l1.x), dpp_ror8(l1.y), dpp_ror8(l1.z), dpp_ror8(l1.w)}, s2 = {dpp_ror8(l2.x), dpp_ror8(l2.y), dpp_ror8(l2.z), dpp_ror8(l2.w)};
;     wA = lo ? l1 : s2; wB = lo ? s1 : l2;
;     __device__ __forceinline__ void operator()(const f32x4 (&acc)[2][2][4][2], const Unit& u, int wr, int wc, int fr, int fq) const {
;     ...
;             for (int m = 0; m < 4; ++m) { const int row = row0 + ai * HALF + m * 16; const size_t off = (size_t)row * D + col0; float sq = 0.f; u32x4 w[2];
;                 const float sc = rsin ? __builtin_amdgcn_rcpf(rsin[row] * (1.f / D) + EPS) : 1.0f;
;                 u32x4 rr[2]; if (R) load_pair_lines(R, D, row, fr, col0, rr[0], rr[1]);
; #pragma unroll
;                 for (int bj = 0; bj < 2; ++bj) { f32x4 r0, r1;
;                     if (R) { const u32x4 rw = rr[bj]; r0 = (f32x4){bflo(rw.x), bfhi(rw.x), bflo(rw.y), bfhi(rw.y)}; r1 = (f32x4){bflo(rw.z), bfhi(rw.z), bflo(rw.w), bfhi(rw.w)}; }
;                     else { const float* rp = (row < 8192 ? src_p + off : src_s + (off - (size_t)8192 * D)) + 8 * bj; r0 = *(const f32x4*)rp; r1 = *(const f32x4*)(rp + 4); }
;                     const f32x4 o0 = r0 + acc[ai][bj][m][0] * sc, o1 = r1 + acc[ai][bj][m][1] * sc;
;                     sq += (o0[0] * o0[0] + o0[1] * o0[1]) + (o0[2] * o0[2] + o0[3] * o0[3]) + (o1[0] * o1[0] + o1[1] * o1[1]) + (o1[2] * o1[2] + o1[3] * o1[3]);
;                     w[bj].x = cvt_pk_bf16(o0[0], o0[1]); w[bj].y = cvt_pk_bf16(o0[2], o0[3]); w[bj].z = cvt_pk_bf16(o1[0], o1[1]); w[bj].w = cvt_pk_bf16(o1[2], o1[3]); }
;                 store_pair_lines(O, D, row, fr, col0, w[0], w[1]);
	v_lshlrev_b32_e32 v110, 16, v109
	v_and_b32_e32 v111, 0xffff0000, v109
	v_lshlrev_b32_e32 v112, 16, v113
	v_and_b32_e32 v113, 0xffff0000, v113
	v_cvt_pk_bf16_f32 v92, v92, v93
	v_cvt_pk_bf16_f32 v93, v94, v95
	v_cvt_pk_bf16_f32 v94, v88, v89
	v_cvt_pk_bf16_f32 v95, v90, v91
	v_lshlrev_b32_e32 v88, 16, v117
	v_and_b32_e32 v89, 0xffff0000, v117
	v_lshlrev_b32_e32 v90, 16, v114
	v_and_b32_e32 v91, 0xffff0000, v114
	v_pk_fma_f32 v[86:87], v[86:87], v[108:109], v[112:113] op_sel_hi:[1,0,1]
	v_pk_fma_f32 v[84:85], v[84:85], v[108:109], v[110:111] op_sel_hi:[1,0,1]
	v_pk_fma_f32 v[82:83], v[82:83], v[108:109], v[90:91] op_sel_hi:[1,0,1]
	v_pk_fma_f32 v[80:81], v[80:81], v[108:109], v[88:89] op_sel_hi:[1,0,1]
	v_cvt_pk_bf16_f32 v84, v84, v85
	v_cvt_pk_bf16_f32 v85, v86, v87
	v_cvt_pk_bf16_f32 v86, v80, v81
	v_cvt_pk_bf16_f32 v87, v82, v83
	s_nop 0
	v_mov_b32_dpp v88, v92 row_ror:8 row_mask:0xf bank_mask:0xf
	v_mov_b32_dpp v89, v93 row_ror:8 row_mask:0xf bank_mask:0xf
	v_mov_b32_dpp v80, v84 row_ror:8 row_mask:0xf bank_mask:0xf
	v_mov_b32_dpp v81, v85 row_ror:8 row_mask:0xf bank_mask:0xf
	v_mov_b32_dpp v82, v86 row_ror:8 row_mask:0xf bank_mask:0xf
	v_mov_b32_dpp v83, v87 row_ror:8 row_mask:0xf bank_mask:0xf
	v_cndmask_b32_e64 v84, v84, v88, s[6:7]
	v_cndmask_b32_e64 v85, v85, v89, s[6:7]
	v_lshl_add_u64 v[88:89], s[8:9], 0, v[104:105]
	v_cndmask_b32_e64 v80, v80, v92, s[6:7]
	v_cndmask_b32_e64 v81, v81, v93, s[6:7]
	v_cndmask_b32_e64 v82, v82, v94, s[6:7]
	v_cndmask_b32_e64 v83, v83, v95, s[6:7]
	v_lshl_add_u64 v[88:89], v[88:89], 0, v[146:147]
	v_mov_b32_dpp v90, v94 row_ror:8 row_mask:0xf bank_mask:0xf
	v_mov_b32_dpp v91, v95 row_ror:8 row_mask:0xf bank_mask:0xf
	global_store_dwordx4 v[88:89], v[80:83], off
	v_cndmask_b32_e64 v86, v86, v90, s[6:7]
	v_cndmask_b32_e64 v87, v87, v91, s[6:7]
	v_lshl_add_u64 v[80:81], s[8:9], 0, v[106:107]
	v_lshl_add_u64 v[80:81], v[80:81], 0, v[146:147]
	global_store_dwordx4 v[80:81], v[84:87], off
	v_or_b32_e32 v80, 48, v150
	v_ashrrev_i32_e32 v81, 31, v80
	v_lshl_add_u64 v[82:83], v[80:81], 2, s[10:11]
	v_sub_u32_e32 v80, v80, v152
	v_add_u32_e32 v80, v80, v154
	v_ashrrev_i32_e32 v81, 31, v80
	v_lshlrev_b64 v[88:89], 12, v[80:81]
	v_lshl_add_u64 v[80:81], s[16:17], 0, v[88:89]
	v_lshl_add_u64 v[90:91], v[88:89], 0, s[36:37]
	v_lshl_add_u64 v[80:81], v[80:81], 0, v[146:147]
	v_lshl_add_u64 v[84:85], s[16:17], 0, v[90:91]
	s_waitcnt vmcnt(18)
	s_nop 0
	v_mov_b32_e32 v92, v206
	s_nop 0
	v_mov_b64_e32 v[80:81], v[224:225]
	v_mov_b64_e32 v[82:83], v[226:227]
	v_lshl_add_u64 v[84:85], v[84:85], 0, v[146:147]
	v_mov_b64_e32 v[84:85], v[228:229]
	v_mov_b64_e32 v[86:87], v[230:231]
	s_nop 1
	v_fmamk_f32 v92, v92, 0x3a000000, v159
	v_rcp_f32_e32 v92, v92
	v_mov_b32_dpp v93, v80 row_ror:8 row_mask:0xf bank_mask:0xf
	v_mov_b32_dpp v97, v84 row_ror:8 row_mask:0xf bank_mask:0xf
	v_mov_b32_dpp v98, v85 row_ror:8 row_mask:0xf bank_mask:0xf
	v_mov_b32_dpp v99, v86 row_ror:8 row_mask:0xf bank_mask:0xf
	v_mov_b32_dpp v100, v87 row_ror:8 row_mask:0xf bank_mask:0xf
	v_mov_b32_dpp v94, v81 row_ror:8 row_mask:0xf bank_mask:0xf
	v_mov_b32_dpp v95, v82 row_ror:8 row_mask:0xf bank_mask:0xf
	v_mov_b32_dpp v96, v83 row_ror:8 row_mask:0xf bank_mask:0xf
	v_cndmask_b32_e64 v100, v100, v83, s[6:7]
	v_cndmask_b32_e64 v99, v99, v82, s[6:7]
	v_cndmask_b32_e64 v83, v98, v81, s[6:7]
	v_cndmask_b32_e64 v81, v97, v80, s[6:7]
	v_cndmask_b32_e64 v96, v87, v96, s[6:7]
	v_cndmask_b32_e64 v95, v86, v95, s[6:7]
	v_cndmask_b32_e64 v94, v85, v94, s[6:7]
	v_cndmask_b32_e64 v93, v84, v93, s[6:7]
	v_lshlrev_b32_e32 v80, 16, v81
	v_and_b32_e32 v81, 0xffff0000, v81
	v_lshlrev_b32_e32 v82, 16, v83
	v_and_b32_e32 v83, 0xffff0000, v83
	v_lshlrev_b32_e32 v84, 16, v99
	v_and_b32_e32 v85, 0xffff0000, v99
	v_lshlrev_b32_e32 v86, 16, v100
	v_and_b32_e32 v87, 0xffff0000, v100
	v_pk_fma_f32 v[78:79], v[78:79], v[92:93], v[82:83] op_sel_hi:[1,0,1]
	v_pk_fma_f32 v[76:77], v[76:77], v[92:93], v[80:81] op_sel_hi:[1,0,1]
	v_pk_fma_f32 v[74:75], v[74:75], v[92:93], v[86:87] op_sel_hi:[1,0,1]
	v_pk_fma_f32 v[72:73], v[72:73], v[92:93], v[84:85] op_sel_hi:[1,0,1]
	v_cvt_pk_bf16_f32 v80, v76, v77
	v_cvt_pk_bf16_f32 v81, v78, v79
	v_lshlrev_b32_e32 v76, 16, v95
	v_cvt_pk_bf16_f32 v82, v72, v73
	v_cvt_pk_bf16_f32 v83, v74, v75
	v_lshlrev_b32_e32 v72, 16, v93
	v_and_b32_e32 v73, 0xffff0000, v93
	v_lshlrev_b32_e32 v74, 16, v94
	v_and_b32_e32 v75, 0xffff0000, v94
	v_and_b32_e32 v77, 0xffff0000, v95
	v_lshlrev_b32_e32 v78, 16, v96
	v_and_b32_e32 v79, 0xffff0000, v96
	v_pk_fma_f32 v[70:71], v[70:71], v[92:93], v[74:75] op_sel_hi:[1,0,1]
	v_pk_fma_f32 v[68:69], v[68:69], v[92:93], v[72:73] op_sel_hi:[1,0,1]
	v_pk_fma_f32 v[66:67], v[66:67], v[92:93], v[78:79] op_sel_hi:[1,0,1]
	v_pk_fma_f32 v[64:65], v[64:65], v[92:93], v[76:77] op_sel_hi:[1,0,1]
	v_cvt_pk_bf16_f32 v68, v68, v69
	v_cvt_pk_bf16_f32 v69, v70, v71
	v_cvt_pk_bf16_f32 v70, v64, v65
	v_cvt_pk_bf16_f32 v71, v66, v67
	s_nop 0
	v_mov_b32_dpp v72, v80 row_ror:8 row_mask:0xf bank_mask:0xf
	v_mov_b32_dpp v73, v81 row_ror:8 row_mask:0xf bank_mask:0xf
	v_mov_b32_dpp v64, v68 row_ror:8 row_mask:0xf bank_mask:0xf
	v_mov_b32_dpp v65, v69 row_ror:8 row_mask:0xf bank_mask:0xf
	v_mov_b32_dpp v66, v70 row_ror:8 row_mask:0xf bank_mask:0xf
	v_mov_b32_dpp v67, v71 row_ror:8 row_mask:0xf bank_mask:0xf
	v_cndmask_b32_e64 v68, v68, v72, s[6:7]
	v_cndmask_b32_e64 v69, v69, v73, s[6:7]
	v_lshl_add_u64 v[72:73], s[8:9], 0, v[88:89]
	v_cndmask_b32_e64 v64, v64, v80, s[6:7]
	v_cndmask_b32_e64 v65, v65, v81, s[6:7]
	v_cndmask_b32_e64 v66, v66, v82, s[6:7]
	v_cndmask_b32_e64 v67, v67, v83, s[6:7]
	v_lshl_add_u64 v[72:73], v[72:73], 0, v[146:147]
	v_mov_b32_dpp v74, v82 row_ror:8 row_mask:0xf bank_mask:0xf
	v_mov_b32_dpp v75, v83 row_ror:8 row_mask:0xf bank_mask:0xf
	global_store_dwordx4 v[72:73], v[64:67], off
	v_cndmask_b32_e64 v70, v70, v74, s[6:7]
	v_cndmask_b32_e64 v71, v71, v75, s[6:7]
	v_lshl_add_u64 v[64:65], s[8:9], 0, v[90:91]
	v_lshl_add_u64 v[64:65], v[64:65], 0, v[146:147]
	global_store_dwordx4 v[64:65], v[68:71], off
	v_sub_u32_e32 v64, v150, v152
	v_add_u32_e32 v77, v64, v154
	v_add_u32_e32 v64, 0x80, v77
	v_ashrrev_i32_e32 v65, 31, v64
	v_lshlrev_b64 v[72:73], 12, v[64:65]
	v_lshl_add_u64 v[64:65], s[16:17], 0, v[72:73]
	v_lshl_add_u64 v[74:75], v[72:73], 0, s[36:37]
	v_lshl_add_u64 v[64:65], v[64:65], 0, v[146:147]
	v_lshl_add_u64 v[68:69], s[16:17], 0, v[74:75]
	s_waitcnt vmcnt(17)
; __device__ __forceinline__ void store_pair_lines(bf16_t* O, int ldc, int row, int fr, int col0, u32x4 wA, u32x4 wB) {
;     const u32x4 sA = {dpp_ror8(wA.x), dpp_ror8(wA.y), dpp_ror8(wA.z), dpp_ror8(wA.w)}, sB = {dpp_ror8(wB.x), dpp_ror8(wB.y), dpp_ror8(wB.z), dpp_ror8(wB.w)};
;     const bool lo = fr < 8;
;     const u32x4 o1 = lo ? wA : sB, o2 = lo ? sA : wB;
;     const int r1 = row - fr + (fr & 7), cb = col0 + (lo ? 0 : 8);
;     *(u32x4*)(O + (size_t)r1 * ldc + cb) = o1;
;     *(u32x4*)(O + (size_t)(r1 + 8) * ldc + cb) = o2;
; }
;     const bool lo = fr < 8;
;     const int r1 = row - fr + (fr & 7), cb = col0 + (lo ? 0 : boff);
;     const u32x4 l1 = *(const u32x4*)(P + (size_t)r1 * ld + cb), l2 = *(const u32x4*)(P + (size_t)(r1 + 8) * ld + cb);
;     const u32x4 s1 = {dpp_ror8(l1.x), dpp_ror8(l1.y), dpp_ror8(l1.z), dpp_ror8(l1.w)}, s2 = {dpp_ror8(l2.x), dpp_ror8(l2.y), dpp_ror8(l2.z), dpp_ror8(l2.w)};
;     wA = lo ? l1 : s2; wB = lo ? s1 : l2;
;     __device__ __forceinline__ void operator()(const f32x4 (&acc)[2][2][4][2], const Unit& u, int wr, int wc, int fr, int fq) const {
;     ...
;             for (int m = 0; m < 4; ++m) { const int row = row0 + ai * HALF + m * 16; const size_t off = (size_t)row * D + col0; float sq = 0.f; u32x4 w[2];
;                 const float sc = rsin ? __builtin_amdgcn_rcpf(rsin[row] * (1.f / D) + EPS) : 1.0f;
;                 u32x4 rr[2]; if (R) load_pair_lines(R, D, row, fr, col0, rr[0], rr[1]);
; #pragma unroll
;                 for (int bj = 0; bj < 2; ++bj) { f32x4 r0, r1;
;                     if (R) { const u32x4 rw = rr[bj]; r0 = (f32x4){bflo(rw.x), bfhi(rw.x), bflo(rw.y), bfhi(rw.y)}; r1 = (f32x4){bflo(rw.z), bfhi(rw.z), bflo(rw.w), bfhi(rw.w)}; }
;                     else { const float* rp = (row < 8192 ? src_p + off : src_s + (off - (size_t)8192 * D)) + 8 * bj; r0 = *(const f32x4*)rp; r1 = *(const f32x4*)(rp + 4); }
;                     const f32x4 o0 = r0 + acc[ai][bj][m][0] * sc, o1 = r1 + acc[ai][bj][m][1] * sc;
;                     sq += (o0[0] * o0[0] + o0[1] * o0[1]) + (o0[2] * o0[2] + o0[3] * o0[3]) + (o1[0] * o1[0] + o1[1] * o1[1]) + (o1[2] * o1[2] + o1[3] * o1[3]);
;                     w[bj].x = cvt_pk_bf16(o0[0], o0[1]); w[bj].y = cvt_pk_bf16(o0[2], o0[3]); w[bj].z = cvt_pk_bf16(o1[0], o1[1]); w[bj].w = cvt_pk_bf16(o1[2], o1[3]); }
;                 store_pair_lines(O, D, row, fr, col0, w[0], w[1]);
	s_nop 0
	v_mov_b32_e32 v76, v207
	s_nop 0
	v_mov_b64_e32 v[64:65], v[232:233]
	v_mov_b64_e32 v[66:67], v[234:235]
	v_lshl_add_u64 v[68:69], v[68:69], 0, v[146:147]
	v_mov_b64_e32 v[68:69], v[236:237]
	v_mov_b64_e32 v[70:71], v[238:239]
	s_nop 1
	v_fmamk_f32 v76, v76, 0x3a000000, v159
	v_rcp_f32_e32 v76, v76
	v_mov_b32_dpp v78, v64 row_ror:8 row_mask:0xf bank_mask:0xf
	v_mov_b32_dpp v82, v68 row_ror:8 row_mask:0xf bank_mask:0xf
	v_mov_b32_dpp v83, v69 row_ror:8 row_mask:0xf bank_mask:0xf
	v_mov_b32_dpp v84, v70 row_ror:8 row_mask:0xf bank_mask:0xf
	v_mov_b32_dpp v85, v71 row_ror:8 row_mask:0xf bank_mask:0xf
	v_mov_b32_dpp v79, v65 row_ror:8 row_mask:0xf bank_mask:0xf
	v_mov_b32_dpp v80, v66 row_ror:8 row_mask:0xf bank_mask:0xf
	v_mov_b32_dpp v81, v67 row_ror:8 row_mask:0xf bank_mask:0xf
	v_cndmask_b32_e64 v85, v85, v67, s[6:7]
	v_cndmask_b32_e64 v84, v84, v66, s[6:7]
	v_cndmask_b32_e64 v67, v83, v65, s[6:7]
	v_cndmask_b32_e64 v65, v82, v64, s[6:7]
	v_cndmask_b32_e64 v81, v71, v81, s[6:7]
	v_cndmask_b32_e64 v80, v70, v80, s[6:7]
	v_cndmask_b32_e64 v79, v69, v79, s[6:7]
	v_cndmask_b32_e64 v78, v68, v78, s[6:7]
	v_lshlrev_b32_e32 v64, 16, v65
	v_and_b32_e32 v65, 0xffff0000, v65
	v_lshlrev_b32_e32 v66, 16, v67
	v_and_b32_e32 v67, 0xffff0000, v67
	v_lshlrev_b32_e32 v68, 16, v84
	v_and_b32_e32 v69, 0xffff0000, v84
	v_lshlrev_b32_e32 v70, 16, v85
	v_and_b32_e32 v71, 0xffff0000, v85
	v_pk_fma_f32 v[62:63], v[62:63], v[76:77], v[66:67] op_sel_hi:[1,0,1]
	v_pk_fma_f32 v[60:61], v[60:61], v[76:77], v[64:65] op_sel_hi:[1,0,1]
	v_pk_fma_f32 v[58:59], v[58:59], v[76:77], v[70:71] op_sel_hi:[1,0,1]
	v_pk_fma_f32 v[56:57], v[56:57], v[76:77], v[68:69] op_sel_hi:[1,0,1]
	v_cvt_pk_bf16_f32 v64, v60, v61
	v_cvt_pk_bf16_f32 v65, v62, v63
	v_lshlrev_b32_e32 v60, 16, v80
	v_cvt_pk_bf16_f32 v66, v56, v57
	v_cvt_pk_bf16_f32 v67, v58, v59
	v_lshlrev_b32_e32 v56, 16, v78
	v_and_b32_e32 v57, 0xffff0000, v78
	v_lshlrev_b32_e32 v58, 16, v79
	v_and_b32_e32 v59, 0xffff0000, v79
	v_and_b32_e32 v61, 0xffff0000, v80
	v_lshlrev_b32_e32 v62, 16, v81
	v_and_b32_e32 v63, 0xffff0000, v81
	v_pk_fma_f32 v[54:55], v[54:55], v[76:77], v[58:59] op_sel_hi:[1,0,1]
	v_pk_fma_f32 v[52:53], v[52:53], v[76:77], v[56:57] op_sel_hi:[1,0,1]
	v_pk_fma_f32 v[50:51], v[50:51], v[76:77], v[62:63] op_sel_hi:[1,0,1]
	v_pk_fma_f32 v[48:49], v[48:49], v[76:77], v[60:61] op_sel_hi:[1,0,1]
	v_cvt_pk_bf16_f32 v52, v52, v53
	v_cvt_pk_bf16_f32 v53, v54, v55
	v_cvt_pk_bf16_f32 v54, v48, v49
	v_cvt_pk_bf16_f32 v55, v50, v51
	s_nop 0
	v_mov_b32_dpp v56, v64 row_ror:8 row_mask:0xf bank_mask:0xf
	v_mov_b32_dpp v57, v65 row_ror:8 row_mask:0xf bank_mask:0xf
	v_mov_b32_dpp v48, v52 row_ror:8 row_mask:0xf bank_mask:0xf
	v_mov_b32_dpp v49, v53 row_ror:8 row_mask:0xf bank_mask:0xf
	v_mov_b32_dpp v50, v54 row_ror:8 row_mask:0xf bank_mask:0xf
	v_mov_b32_dpp v51, v55 row_ror:8 row_mask:0xf bank_mask:0xf
	v_cndmask_b32_e64 v52, v52, v56, s[6:7]
	v_cndmask_b32_e64 v53, v53, v57, s[6:7]
	v_lshl_add_u64 v[56:57], s[8:9], 0, v[72:73]
	v_cndmask_b32_e64 v48, v48, v64, s[6:7]
	v_cndmask_b32_e64 v49, v49, v65, s[6:7]
	v_cndmask_b32_e64 v50, v50, v66, s[6:7]
	v_cndmask_b32_e64 v51, v51, v67, s[6:7]
	v_lshl_add_u64 v[56:57], v[56:57], 0, v[146:147]
	v_mov_b32_dpp v58, v66 row_ror:8 row_mask:0xf bank_mask:0xf
	v_mov_b32_dpp v59, v67 row_ror:8 row_mask:0xf bank_mask:0xf
	global_store_dwordx4 v[56:57], v[48:51], off
	v_cndmask_b32_e64 v54, v54, v58, s[6:7]
	v_cndmask_b32_e64 v55, v55, v59, s[6:7]
	v_lshl_add_u64 v[48:49], s[8:9], 0, v[74:75]
	v_lshl_add_u64 v[48:49], v[48:49], 0, v[146:147]
	global_store_dwordx4 v[48:49], v[52:55], off
	v_add_u32_e32 v48, 0x90, v77
	v_ashrrev_i32_e32 v49, 31, v48
	v_lshlrev_b64 v[56:57], 12, v[48:49]
	v_lshl_add_u64 v[48:49], s[16:17], 0, v[56:57]
	v_lshl_add_u64 v[58:59], v[56:57], 0, s[36:37]
	v_lshl_add_u64 v[48:49], v[48:49], 0, v[146:147]
	v_lshl_add_u64 v[52:53], s[16:17], 0, v[58:59]
	s_waitcnt vmcnt(16)
	s_nop 0
	v_mov_b32_e32 v60, v240
	s_nop 0
	v_mov_b64_e32 v[48:49], v[244:245]
	v_mov_b64_e32 v[50:51], v[246:247]
	v_lshl_add_u64 v[52:53], v[52:53], 0, v[146:147]
	v_mov_b64_e32 v[52:53], v[248:249]
	v_mov_b64_e32 v[54:55], v[250:251]
	s_nop 1
	v_fmamk_f32 v60, v60, 0x3a000000, v159
	v_rcp_f32_e32 v60, v60
	v_mov_b32_dpp v61, v48 row_ror:8 row_mask:0xf bank_mask:0xf
	v_mov_b32_dpp v65, v52 row_ror:8 row_mask:0xf bank_mask:0xf
	v_mov_b32_dpp v66, v53 row_ror:8 row_mask:0xf bank_mask:0xf
	v_mov_b32_dpp v67, v54 row_ror:8 row_mask:0xf bank_mask:0xf
	v_mov_b32_dpp v68, v55 row_ror:8 row_mask:0xf bank_mask:0xf
	v_mov_b32_dpp v62, v49 row_ror:8 row_mask:0xf bank_mask:0xf
	v_mov_b32_dpp v63, v50 row_ror:8 row_mask:0xf bank_mask:0xf
	v_mov_b32_dpp v64, v51 row_ror:8 row_mask:0xf bank_mask:0xf
	v_cndmask_b32_e64 v68, v68, v51, s[6:7]
	v_cndmask_b32_e64 v67, v67, v50, s[6:7]
	v_cndmask_b32_e64 v51, v66, v49, s[6:7]
	v_cndmask_b32_e64 v49, v65, v48, s[6:7]
	v_cndmask_b32_e64 v64, v55, v64, s[6:7]
	v_cndmask_b32_e64 v63, v54, v63, s[6:7]
	v_cndmask_b32_e64 v62, v53, v62, s[6:7]
	v_cndmask_b32_e64 v61, v52, v61, s[6:7]
	v_lshlrev_b32_e32 v48, 16, v49
	v_and_b32_e32 v49, 0xffff0000, v49
	v_lshlrev_b32_e32 v50, 16, v51
	v_and_b32_e32 v51, 0xffff0000, v51
	v_lshlrev_b32_e32 v52, 16, v67
	v_and_b32_e32 v53, 0xffff0000, v67
	v_lshlrev_b32_e32 v54, 16, v68
	v_and_b32_e32 v55, 0xffff0000, v68
	v_pk_fma_f32 v[46:47], v[46:47], v[60:61], v[50:51] op_sel_hi:[1,0,1]
	v_pk_fma_f32 v[44:45], v[44:45], v[60:61], v[48:49] op_sel_hi:[1,0,1]
	v_pk_fma_f32 v[42:43], v[42:43], v[60:61], v[54:55] op_sel_hi:[1,0,1]
	v_pk_fma_f32 v[40:41], v[40:41], v[60:61], v[52:53] op_sel_hi:[1,0,1]
	v_cvt_pk_bf16_f32 v48, v44, v45
; __device__ __forceinline__ void store_pair_lines(bf16_t* O, int ldc, int row, int fr, int col0, u32x4 wA, u32x4 wB) {
;     const u32x4 sA = {dpp_ror8(wA.x), dpp_ror8(wA.y), dpp_ror8(wA.z), dpp_ror8(wA.w)}, sB = {dpp_ror8(wB.x), dpp_ror8(wB.y), dpp_ror8(wB.z), dpp_ror8(wB.w)};
;     const bool lo = fr < 8;
;     const u32x4 o1 = lo ? wA : sB, o2 = lo ? sA : wB;
;     const int r1 = row - fr + (fr & 7), cb = col0 + (lo ? 0 : 8);
;     *(u32x4*)(O + (size_t)r1 * ldc + cb) = o1;
;     *(u32x4*)(O + (size_t)(r1 + 8) * ldc + cb) = o2;
; }
;     const bool lo = fr < 8;
;     const int r1 = row - fr + (fr & 7), cb = col0 + (lo ? 0 : boff);
;     const u32x4 l1 = *(const u32x4*)(P + (size_t)r1 * ld + cb), l2 = *(const u32x4*)(P + (size_t)(r1 + 8) * ld + cb);
;     const u32x4 s1 = {dpp_ror8(l1.x), dpp_ror8(l1.y), dpp_ror8(l1.z), dpp_ror8(l1.w)}, s2 = {dpp_ror8(l2.x), dpp_ror8(l2.y), dpp_ror8(l2.z), dpp_ror8(l2.w)};
;     wA = lo ? l1 : s2; wB = lo ? s1 : l2;
;     __device__ __forceinline__ void operator()(const f32x4 (&acc)[2][2][4][2], const Unit& u, int wr, int wc, int fr, int fq) const {
;     ...
;             for (int m = 0; m < 4; ++m) { const int row = row0 + ai * HALF + m * 16; const size_t off = (size_t)row * D + col0; float sq = 0.f; u32x4 w[2];
;                 const float sc = rsin ? __builtin_amdgcn_rcpf(rsin[row] * (1.f / D) + EPS) : 1.0f;
;                 u32x4 rr[2]; if (R) load_pair_lines(R, D, row, fr, col0, rr[0], rr[1]);
; #pragma unroll
;                 for (int bj = 0; bj < 2; ++bj) { f32x4 r0, r1;
;                     if (R) { const u32x4 rw = rr[bj]; r0 = (f32x4){bflo(rw.x), bfhi(rw.x), bflo(rw.y), bfhi(rw.y)}; r1 = (f32x4){bflo(rw.z), bfhi(rw.z), bflo(rw.w), bfhi(rw.w)}; }
;                     else { const float* rp = (row < 8192 ? src_p + off : src_s + (off - (size_t)8192 * D)) + 8 * bj; r0 = *(const f32x4*)rp; r1 = *(const f32x4*)(rp + 4); }
;                     const f32x4 o0 = r0 + acc[ai][bj][m][0] * sc, o1 = r1 + acc[ai][bj][m][1] * sc;
;                     sq += (o0[0] * o0[0] + o0[1] * o0[1]) + (o0[2] * o0[2] + o0[3] * o0[3]) + (o1[0] * o1[0] + o1[1] * o1[1]) + (o1[2] * o1[2] + o1[3] * o1[3]);
;                     w[bj].x = cvt_pk_bf16(o0[0], o0[1]); w[bj].y = cvt_pk_bf16(o0[2], o0[3]); w[bj].z = cvt_pk_bf16(o1[0], o1[1]); w[bj].w = cvt_pk_bf16(o1[2], o1[3]); }
;                 store_pair_lines(O, D, row, fr, col0, w[0], w[1]);
	v_cvt_pk_bf16_f32 v49, v46, v47
	v_lshlrev_b32_e32 v44, 16, v63
	v_cvt_pk_bf16_f32 v50, v40, v41
	v_cvt_pk_bf16_f32 v51, v42, v43
	v_lshlrev_b32_e32 v40, 16, v61
	v_and_b32_e32 v41, 0xffff0000, v61
	v_lshlrev_b32_e32 v42, 16, v62
	v_and_b32_e32 v43, 0xffff0000, v62
	v_and_b32_e32 v45, 0xffff0000, v63
	v_lshlrev_b32_e32 v46, 16, v64
	v_and_b32_e32 v47, 0xffff0000, v64
	v_pk_fma_f32 v[38:39], v[38:39], v[60:61], v[42:43] op_sel_hi:[1,0,1]
	v_pk_fma_f32 v[36:37], v[36:37], v[60:61], v[40:41] op_sel_hi:[1,0,1]
	v_pk_fma_f32 v[34:35], v[34:35], v[60:61], v[46:47] op_sel_hi:[1,0,1]
	v_pk_fma_f32 v[32:33], v[32:33], v[60:61], v[44:45] op_sel_hi:[1,0,1]
	v_cvt_pk_bf16_f32 v36, v36, v37
	v_cvt_pk_bf16_f32 v37, v38, v39
	v_cvt_pk_bf16_f32 v38, v32, v33
	v_cvt_pk_bf16_f32 v39, v34, v35
	s_nop 0
	v_mov_b32_dpp v40, v48 row_ror:8 row_mask:0xf bank_mask:0xf
	v_mov_b32_dpp v41, v49 row_ror:8 row_mask:0xf bank_mask:0xf
	v_mov_b32_dpp v32, v36 row_ror:8 row_mask:0xf bank_mask:0xf
	v_mov_b32_dpp v33, v37 row_ror:8 row_mask:0xf bank_mask:0xf
	v_mov_b32_dpp v34, v38 row_ror:8 row_mask:0xf bank_mask:0xf
	v_mov_b32_dpp v35, v39 row_ror:8 row_mask:0xf bank_mask:0xf
	v_cndmask_b32_e64 v36, v36, v40, s[6:7]
	v_cndmask_b32_e64 v37, v37, v41, s[6:7]
	v_lshl_add_u64 v[40:41], s[8:9], 0, v[56:57]
	v_cndmask_b32_e64 v32, v32, v48, s[6:7]
	v_cndmask_b32_e64 v33, v33, v49, s[6:7]
	v_cndmask_b32_e64 v34, v34, v50, s[6:7]
	v_cndmask_b32_e64 v35, v35, v51, s[6:7]
	v_lshl_add_u64 v[40:41], v[40:41], 0, v[146:147]
	v_mov_b32_dpp v42, v50 row_ror:8 row_mask:0xf bank_mask:0xf
	v_mov_b32_dpp v43, v51 row_ror:8 row_mask:0xf bank_mask:0xf
	global_store_dwordx4 v[40:41], v[32:35], off
	v_cndmask_b32_e64 v38, v38, v42, s[6:7]
	v_cndmask_b32_e64 v39, v39, v43, s[6:7]
	v_lshl_add_u64 v[32:33], s[8:9], 0, v[58:59]
	v_lshl_add_u64 v[32:33], v[32:33], 0, v[146:147]
	global_store_dwordx4 v[32:33], v[36:39], off
	v_add_u32_e32 v32, 0xa0, v77
	v_ashrrev_i32_e32 v33, 31, v32
	v_lshlrev_b64 v[40:41], 12, v[32:33]
	v_lshl_add_u64 v[42:43], v[40:41], 0, s[36:37]
	s_waitcnt vmcnt(13)
	s_nop 0
	v_mov_b32_e32 v44, v204
	v_lshl_add_u64 v[32:33], s[16:17], 0, v[40:41]
	v_lshl_add_u64 v[36:37], s[16:17], 0, v[42:43]
	v_lshl_add_u64 v[32:33], v[32:33], 0, v[146:147]
	v_lshl_add_u64 v[36:37], v[36:37], 0, v[146:147]
	v_mov_b64_e32 v[32:33], v[208:209]
	v_mov_b64_e32 v[34:35], v[210:211]
	v_mov_b64_e32 v[36:37], v[212:213]
	v_mov_b64_e32 v[38:39], v[214:215]
	s_nop 1
	v_fmamk_f32 v44, v44, 0x3a000000, v159
	v_rcp_f32_e32 v44, v44
	v_mov_b32_dpp v45, v32 row_ror:8 row_mask:0xf bank_mask:0xf
	v_mov_b32_dpp v46, v33 row_ror:8 row_mask:0xf bank_mask:0xf
	v_mov_b32_dpp v49, v36 row_ror:8 row_mask:0xf bank_mask:0xf
	v_mov_b32_dpp v50, v37 row_ror:8 row_mask:0xf bank_mask:0xf
	v_mov_b32_dpp v51, v38 row_ror:8 row_mask:0xf bank_mask:0xf
	v_mov_b32_dpp v52, v39 row_ror:8 row_mask:0xf bank_mask:0xf
	v_mov_b32_dpp v47, v34 row_ror:8 row_mask:0xf bank_mask:0xf
	v_mov_b32_dpp v48, v35 row_ror:8 row_mask:0xf bank_mask:0xf
	v_cndmask_b32_e64 v52, v52, v35, s[6:7]
	v_cndmask_b32_e64 v51, v51, v34, s[6:7]
	v_cndmask_b32_e64 v35, v50, v33, s[6:7]
	v_cndmask_b32_e64 v33, v49, v32, s[6:7]
	v_cndmask_b32_e64 v48, v39, v48, s[6:7]
	v_cndmask_b32_e64 v47, v38, v47, s[6:7]
	v_cndmask_b32_e64 v46, v37, v46, s[6:7]
	v_cndmask_b32_e64 v45, v36, v45, s[6:7]
	v_lshlrev_b32_e32 v32, 16, v33
	v_and_b32_e32 v33, 0xffff0000, v33
	v_lshlrev_b32_e32 v34, 16, v35
	v_and_b32_e32 v35, 0xffff0000, v35
	v_lshlrev_b32_e32 v36, 16, v51
	v_and_b32_e32 v37, 0xffff0000, v51
	v_lshlrev_b32_e32 v38, 16, v52
	v_and_b32_e32 v39, 0xffff0000, v52
	v_pk_fma_f32 v[30:31], v[30:31], v[44:45], v[34:35] op_sel_hi:[1,0,1]
	v_pk_fma_f32 v[28:29], v[28:29], v[44:45], v[32:33] op_sel_hi:[1,0,1]
	v_pk_fma_f32 v[26:27], v[26:27], v[44:45], v[38:39] op_sel_hi:[1,0,1]
	v_pk_fma_f32 v[24:25], v[24:25], v[44:45], v[36:37] op_sel_hi:[1,0,1]
	v_cvt_pk_bf16_f32 v32, v28, v29
	v_cvt_pk_bf16_f32 v33, v30, v31
	v_lshlrev_b32_e32 v28, 16, v47
	v_cvt_pk_bf16_f32 v34, v24, v25
	v_cvt_pk_bf16_f32 v35, v26, v27
	v_lshlrev_b32_e32 v24, 16, v45
	v_and_b32_e32 v25, 0xffff0000, v45
	v_lshlrev_b32_e32 v26, 16, v46
	v_and_b32_e32 v27, 0xffff0000, v46
	v_and_b32_e32 v29, 0xffff0000, v47
	v_lshlrev_b32_e32 v30, 16, v48
	v_and_b32_e32 v31, 0xffff0000, v48
	v_pk_fma_f32 v[22:23], v[22:23], v[44:45], v[26:27] op_sel_hi:[1,0,1]
	v_pk_fma_f32 v[20:21], v[20:21], v[44:45], v[24:25] op_sel_hi:[1,0,1]
	v_pk_fma_f32 v[18:19], v[18:19], v[44:45], v[30:31] op_sel_hi:[1,0,1]
	v_pk_fma_f32 v[16:17], v[16:17], v[44:45], v[28:29] op_sel_hi:[1,0,1]
	v_cvt_pk_bf16_f32 v20, v20, v21
	v_cvt_pk_bf16_f32 v21, v22, v23
	v_cvt_pk_bf16_f32 v22, v16, v17
	v_cvt_pk_bf16_f32 v23, v18, v19
	s_nop 0
	v_mov_b32_dpp v24, v32 row_ror:8 row_mask:0xf bank_mask:0xf
	v_mov_b32_dpp v25, v33 row_ror:8 row_mask:0xf bank_mask:0xf
	v_mov_b32_dpp v16, v20 row_ror:8 row_mask:0xf bank_mask:0xf
	v_mov_b32_dpp v17, v21 row_ror:8 row_mask:0xf bank_mask:0xf
	v_mov_b32_dpp v18, v22 row_ror:8 row_mask:0xf bank_mask:0xf
	v_mov_b32_dpp v19, v23 row_ror:8 row_mask:0xf bank_mask:0xf
	v_cndmask_b32_e64 v20, v20, v24, s[6:7]
	v_cndmask_b32_e64 v21, v21, v25, s[6:7]
	v_lshl_add_u64 v[24:25], s[8:9], 0, v[40:41]
	v_cndmask_b32_e64 v16, v16, v32, s[6:7]
	v_cndmask_b32_e64 v17, v17, v33, s[6:7]
	v_cndmask_b32_e64 v18, v18, v34, s[6:7]
	v_cndmask_b32_e64 v19, v19, v35, s[6:7]
	v_lshl_add_u64 v[24:25], v[24:25], 0, v[146:147]
	v_mov_b32_dpp v26, v34 row_ror:8 row_mask:0xf bank_mask:0xf
	v_mov_b32_dpp v27, v35 row_ror:8 row_mask:0xf bank_mask:0xf
	global_store_dwordx4 v[24:25], v[16:19], off
	v_cndmask_b32_e64 v22, v22, v26, s[6:7]
	v_cndmask_b32_e64 v23, v23, v27, s[6:7]
	v_lshl_add_u64 v[16:17], s[8:9], 0, v[42:43]
	v_lshl_add_u64 v[16:17], v[16:17], 0, v[146:147]
	global_store_dwordx4 v[16:17], v[20:23], off
	v_add_u32_e32 v16, 0xb0, v77
	v_ashrrev_i32_e32 v17, 31, v16
	v_lshlrev_b64 v[24:25], 12, v[16:17]
	v_lshl_add_u64 v[26:27], v[24:25], 0, s[36:37]
	s_waitcnt vmcnt(10)
; __device__ __forceinline__ void store_pair_lines(bf16_t* O, int ldc, int row, int fr, int col0, u32x4 wA, u32x4 wB) {
;     const u32x4 sA = {dpp_ror8(wA.x), dpp_ror8(wA.y), dpp_ror8(wA.z), dpp_ror8(wA.w)}, sB = {dpp_ror8(wB.x), dpp_ror8(wB.y), dpp_ror8(wB.z), dpp_ror8(wB.w)};
;     const bool lo = fr < 8;
;     const u32x4 o1 = lo ? wA : sB, o2 = lo ? sA : wB;
;     const int r1 = row - fr + (fr & 7), cb = col0 + (lo ? 0 : 8);
;     *(u32x4*)(O + (size_t)r1 * ldc + cb) = o1;
;     *(u32x4*)(O + (size_t)(r1 + 8) * ldc + cb) = o2;
; }
;     const bool lo = fr < 8;
;     const int r1 = row - fr + (fr & 7), cb = col0 + (lo ? 0 : boff);
;     const u32x4 l1 = *(const u32x4*)(P + (size_t)r1 * ld + cb), l2 = *(const u32x4*)(P + (size_t)(r1 + 8) * ld + cb);
;     const u32x4 s1 = {dpp_ror8(l1.x), dpp_ror8(l1.y), dpp_ror8(l1.z), dpp_ror8(l1.w)}, s2 = {dpp_ror8(l2.x), dpp_ror8(l2.y), dpp_ror8(l2.z), dpp_ror8(l2.w)};
;     wA = lo ? l1 : s2; wB = lo ? s1 : l2;
;     __device__ __forceinline__ void operator()(const f32x4 (&acc)[2][2][4][2], const Unit& u, int wr, int wc, int fr, int fq) const {
;     ...
;             for (int m = 0; m < 4; ++m) { const int row = row0 + ai * HALF + m * 16; const size_t off = (size_t)row * D + col0; float sq = 0.f; u32x4 w[2];
;                 const float sc = rsin ? __builtin_amdgcn_rcpf(rsin[row] * (1.f / D) + EPS) : 1.0f;
;                 u32x4 rr[2]; if (R) load_pair_lines(R, D, row, fr, col0, rr[0], rr[1]);
; #pragma unroll
;                 for (int bj = 0; bj < 2; ++bj) { f32x4 r0, r1;
;                     if (R) { const u32x4 rw = rr[bj]; r0 = (f32x4){bflo(rw.x), bfhi(rw.x), bflo(rw.y), bfhi(rw.y)}; r1 = (f32x4){bflo(rw.z), bfhi(rw.z), bflo(rw.w), bfhi(rw.w)}; }
;                     else { const float* rp = (row < 8192 ? src_p + off : src_s + (off - (size_t)8192 * D)) + 8 * bj; r0 = *(const f32x4*)rp; r1 = *(const f32x4*)(rp + 4); }
;                     const f32x4 o0 = r0 + acc[ai][bj][m][0] * sc, o1 = r1 + acc[ai][bj][m][1] * sc;
;                     sq += (o0[0] * o0[0] + o0[1] * o0[1]) + (o0[2] * o0[2] + o0[3] * o0[3]) + (o1[0] * o1[0] + o1[1] * o1[1]) + (o1[2] * o1[2] + o1[3] * o1[3]);
;                     w[bj].x = cvt_pk_bf16(o0[0], o0[1]); w[bj].y = cvt_pk_bf16(o0[2], o0[3]); w[bj].z = cvt_pk_bf16(o1[0], o1[1]); w[bj].w = cvt_pk_bf16(o1[2], o1[3]); }
;                 store_pair_lines(O, D, row, fr, col0, w[0], w[1]);
	s_nop 0
	v_mov_b32_e32 v28, v205
	v_lshl_add_u64 v[16:17], s[16:17], 0, v[24:25]
	v_lshl_add_u64 v[20:21], s[16:17], 0, v[26:27]
	v_lshl_add_u64 v[16:17], v[16:17], 0, v[146:147]
	v_lshl_add_u64 v[20:21], v[20:21], 0, v[146:147]
	v_mov_b64_e32 v[16:17], v[216:217]
	v_mov_b64_e32 v[18:19], v[218:219]
	v_mov_b64_e32 v[20:21], v[220:221]
	v_mov_b64_e32 v[22:23], v[222:223]
	s_nop 1
	v_fmamk_f32 v28, v28, 0x3a000000, v159
	v_rcp_f32_e32 v28, v28
	v_mov_b32_dpp v29, v16 row_ror:8 row_mask:0xf bank_mask:0xf
	v_mov_b32_dpp v30, v17 row_ror:8 row_mask:0xf bank_mask:0xf
	v_mov_b32_dpp v33, v20 row_ror:8 row_mask:0xf bank_mask:0xf
	v_mov_b32_dpp v34, v21 row_ror:8 row_mask:0xf bank_mask:0xf
	v_mov_b32_dpp v35, v22 row_ror:8 row_mask:0xf bank_mask:0xf
	v_mov_b32_dpp v36, v23 row_ror:8 row_mask:0xf bank_mask:0xf
	v_mov_b32_dpp v31, v18 row_ror:8 row_mask:0xf bank_mask:0xf
	v_mov_b32_dpp v32, v19 row_ror:8 row_mask:0xf bank_mask:0xf
	v_cndmask_b32_e64 v36, v36, v19, s[6:7]
	v_cndmask_b32_e64 v35, v35, v18, s[6:7]
	v_cndmask_b32_e64 v19, v34, v17, s[6:7]
	v_cndmask_b32_e64 v17, v33, v16, s[6:7]
	v_cndmask_b32_e64 v32, v23, v32, s[6:7]
	v_cndmask_b32_e64 v31, v22, v31, s[6:7]
	v_cndmask_b32_e64 v30, v21, v30, s[6:7]
	v_cndmask_b32_e64 v29, v20, v29, s[6:7]
	v_lshlrev_b32_e32 v16, 16, v17
	v_and_b32_e32 v17, 0xffff0000, v17
	v_lshlrev_b32_e32 v18, 16, v19
	v_and_b32_e32 v19, 0xffff0000, v19
	v_lshlrev_b32_e32 v20, 16, v35
	v_and_b32_e32 v21, 0xffff0000, v35
	v_lshlrev_b32_e32 v22, 16, v36
	v_and_b32_e32 v23, 0xffff0000, v36
	v_pk_fma_f32 v[14:15], v[14:15], v[28:29], v[18:19] op_sel_hi:[1,0,1]
	v_pk_fma_f32 v[12:13], v[12:13], v[28:29], v[16:17] op_sel_hi:[1,0,1]
	v_pk_fma_f32 v[10:11], v[10:11], v[28:29], v[22:23] op_sel_hi:[1,0,1]
	v_pk_fma_f32 v[8:9], v[8:9], v[28:29], v[20:21] op_sel_hi:[1,0,1]
	v_cvt_pk_bf16_f32 v16, v12, v13
	v_cvt_pk_bf16_f32 v17, v14, v15
	v_lshlrev_b32_e32 v12, 16, v31
	v_cvt_pk_bf16_f32 v18, v8, v9
	v_cvt_pk_bf16_f32 v19, v10, v11
	v_lshlrev_b32_e32 v8, 16, v29
	v_and_b32_e32 v9, 0xffff0000, v29
	v_lshlrev_b32_e32 v10, 16, v30
	v_and_b32_e32 v11, 0xffff0000, v30
	v_and_b32_e32 v13, 0xffff0000, v31
	v_lshlrev_b32_e32 v14, 16, v32
	v_and_b32_e32 v15, 0xffff0000, v32
	v_pk_fma_f32 v[6:7], v[6:7], v[28:29], v[10:11] op_sel_hi:[1,0,1]
	v_pk_fma_f32 v[4:5], v[4:5], v[28:29], v[8:9] op_sel_hi:[1,0,1]
	v_pk_fma_f32 v[2:3], v[2:3], v[28:29], v[14:15] op_sel_hi:[1,0,1]
	v_pk_fma_f32 v[0:1], v[0:1], v[28:29], v[12:13] op_sel_hi:[1,0,1]
	v_cvt_pk_bf16_f32 v4, v4, v5
	v_cvt_pk_bf16_f32 v5, v6, v7
	v_cvt_pk_bf16_f32 v6, v0, v1
	v_cvt_pk_bf16_f32 v7, v2, v3
	s_nop 0
	v_mov_b32_dpp v8, v16 row_ror:8 row_mask:0xf bank_mask:0xf
	v_mov_b32_dpp v9, v17 row_ror:8 row_mask:0xf bank_mask:0xf
	v_mov_b32_dpp v0, v4 row_ror:8 row_mask:0xf bank_mask:0xf
	v_mov_b32_dpp v1, v5 row_ror:8 row_mask:0xf bank_mask:0xf
	v_mov_b32_dpp v2, v6 row_ror:8 row_mask:0xf bank_mask:0xf
	v_mov_b32_dpp v3, v7 row_ror:8 row_mask:0xf bank_mask:0xf
	v_cndmask_b32_e64 v4, v4, v8, s[6:7]
	v_cndmask_b32_e64 v5, v5, v9, s[6:7]
	v_lshl_add_u64 v[8:9], s[8:9], 0, v[24:25]
	v_cndmask_b32_e64 v0, v0, v16, s[6:7]
	v_cndmask_b32_e64 v1, v1, v17, s[6:7]
	v_cndmask_b32_e64 v2, v2, v18, s[6:7]
	v_cndmask_b32_e64 v3, v3, v19, s[6:7]
	v_lshl_add_u64 v[8:9], v[8:9], 0, v[146:147]
	v_mov_b32_dpp v10, v18 row_ror:8 row_mask:0xf bank_mask:0xf
	v_mov_b32_dpp v11, v19 row_ror:8 row_mask:0xf bank_mask:0xf
	global_store_dwordx4 v[8:9], v[0:3], off
	v_cndmask_b32_e64 v6, v6, v10, s[6:7]
	v_cndmask_b32_e64 v7, v7, v11, s[6:7]
	v_lshl_add_u64 v[0:1], s[8:9], 0, v[26:27]
	v_lshl_add_u64 v[0:1], v[0:1], 0, v[146:147]
	global_store_dwordx4 v[0:1], v[4:7], off
	s_cbranch_vccz .LBB0_798
	s_waitcnt vmcnt(0)
	s_cmpk_gt_u32 s56, 0xff
	s_cbranch_scc1 .LBB0_810
	s_barrier

; #define PG8_STAGE(bufoff, gbase, voff) do { _Pragma("unroll") for (int _i = 0; _i < 2; ++_i) \
;         __builtin_amdgcn_global_load_lds((const unsigned*)((const char*)(gbase) + (voff)[_i]), (LAS unsigned*)(lds + (bufoff) + ldsw + _i * 8192), 16, 0, 0); } while (0)
; #define PG8_LDA(dst, b, h) do { _Pragma("unroll") for (int m = 0; m < 4; ++m) _Pragma("unroll") for (int k = 0; k < 2; ++k) dst[m][k] = *(const LAS bf16x8*)(lds + PG8_SA(b, h) + aoff + m * 2048 + k * 1024); } while (0)
; #define PG8_LDB(dst, b, h) do { _Pragma("unroll") for (int n = 0; n < 2; ++n) _Pragma("unroll") for (int k = 0; k < 2; ++k) dst[n][k] = *(const LAS bf16x8*)(lds + PG8_SB(b, h) + boff + n * 2048 + k * 1024); } while (0)
; #define PG8_WAIT_V(n) asm volatile("s_waitcnt vmcnt(" #n ")" ::: "memory")
; #define PG8_BAR __builtin_amdgcn_s_barrier()
; template <class Epi>
; __device__ __forceinline__ void gemm_phase(LAS unsigned char* lds, const Gemm g, const StaticOrder& S, const Epi& E) {
;     ...
;         const char* nA = has_next ? (const char*)g.A + (size_t)nxt.pm * tstep : cA; const char* nB = has_next ? (const char*)g.Bt + (size_t)nxt.pn * tstep : cB;
;         for (int t = 0; t < nt; t += 2) {
;             const bool last = (t == nt - 2);
;             const char* a1 = cA + (size_t)(t + 1) * kstep;
;             const char* a2 = last ? nA : cA + (size_t)(t + 2) * kstep; const char* b2 = last ? nB : cB + (size_t)(t + 2) * kstep;
;             const char* a3 = a2 + kstep; const char* b3 = b2 + kstep;
;             PG8_LDB(B0, 0, 0); PG8_SCHED; PG8_LDA(At, 0, 0); PG8_STAGE(PG8_SA(1, 1), a1 + hstep, voffA);
;             PG8_WAIT_L(8); PG8_BAR; PG8_WAIT_L(0); PG8_MMA(0, 0, At, B0); PG8_BAR; PG8_SCHED;
;             PG8_LDB(B1, 0, 1); PG8_STAGE(PG8_SB(0, 0), b2, voffB0);
;             PG8_BAR; PG8_WAIT_L(0); PG8_MMA(0, 1, At, B1); PG8_BAR;
;             PG8_LDA(At, 0, 1); PG8_STAGE(PG8_SA(0, 0), a2, voffA);
;             PG8_BAR; PG8_WAIT_L(0); PG8_MMA(1, 0, At, B0); PG8_BAR; PG8_SCHED;
;             PG8_STAGE(PG8_SB(0, 1), b2, voffB1);
;             PG8_WAIT_V(6); PG8_BAR; PG8_MMA(1, 1, At, B1); PG8_BAR;
;             PG8_LDB(B0, 1, 0); PG8_SCHED; PG8_LDA(At, 1, 0); PG8_STAGE(PG8_SA(0, 1), a2 + hstep, voffA);
;             PG8_WAIT_L(8); PG8_BAR; PG8_WAIT_L(0); PG8_MMA(0, 0, At, B0); PG8_BAR; PG8_SCHED;
;             PG8_LDB(B1, 1, 1); PG8_STAGE(PG8_SB(1, 0), b3, voffB0);
.LBB0_882:
	ds_read_b128 v[32:35], v177
	ds_read_b128 v[40:43], v177 offset:1024
	ds_read_b128 v[48:51], v177 offset:2048
	ds_read_b128 v[52:55], v177 offset:3072
	s_add_u32 s33, s60, 0xfff80080
	s_addc_u32 s62, s61, -1
	s_cmp_eq_u32 s86, 28
	s_cselect_b32 s63, s49, s62
	s_cselect_b32 s62, s57, s33
	s_cselect_b32 s65, s47, s85
	s_cselect_b32 s64, s83, s84
	v_lshl_add_u64 v[170:171], s[60:61], 0, v[156:157]
	s_add_i32 m0, s59, 0xc000
	ds_read_b128 v[162:165], v178
	ds_read_b128 v[166:169], v178 offset:1024
	ds_read_b128 v[182:185], v178 offset:2048
	ds_read_b128 v[186:189], v178 offset:3072
	ds_read_b128 v[190:193], v178 offset:4096
	ds_read_b128 v[194:197], v178 offset:5120
	ds_read_b128 v[198:201], v178 offset:6144
	ds_read_b128 v[204:207], v178 offset:7168
	global_load_lds_dwordx4 v[170:171], off
	v_lshl_add_u64 v[170:171], s[60:61], 0, v[158:159]
	s_add_i32 m0, s59, 0xe000
	s_nop 0
	global_load_lds_dwordx4 v[170:171], off
	s_waitcnt lgkmcnt(8)
	s_barrier
	s_waitcnt lgkmcnt(0)
	v_mfma_f32_16x16x32_bf16 v[140:143], v[32:35], v[162:165], v[140:143]
	v_mfma_f32_16x16x32_bf16 v[136:139], v[48:51], v[162:165], v[136:139]
	v_mfma_f32_16x16x32_bf16 v[124:127], v[32:35], v[182:185], v[124:127]
	v_mfma_f32_16x16x32_bf16 v[120:123], v[48:51], v[182:185], v[120:123]
	v_mfma_f32_16x16x32_bf16 v[108:111], v[32:35], v[190:193], v[108:111]
	v_mfma_f32_16x16x32_bf16 v[104:107], v[48:51], v[190:193], v[104:107]
	v_mfma_f32_16x16x32_bf16 v[92:95], v[32:35], v[198:201], v[92:95]
	v_mfma_f32_16x16x32_bf16 v[88:91], v[48:51], v[198:201], v[88:91]
	v_mfma_f32_16x16x32_bf16 v[140:143], v[40:43], v[166:169], v[140:143]
	v_mfma_f32_16x16x32_bf16 v[136:139], v[52:55], v[166:169], v[136:139]
	v_mfma_f32_16x16x32_bf16 v[124:127], v[40:43], v[186:189], v[124:127]
	v_mfma_f32_16x16x32_bf16 v[120:123], v[52:55], v[186:189], v[120:123]
	v_mfma_f32_16x16x32_bf16 v[108:111], v[40:43], v[194:197], v[108:111]
	v_mfma_f32_16x16x32_bf16 v[104:107], v[52:55], v[194:197], v[104:107]
	v_mfma_f32_16x16x32_bf16 v[92:95], v[40:43], v[204:207], v[92:95]
	v_mfma_f32_16x16x32_bf16 v[88:91], v[52:55], v[204:207], v[88:91]
	s_barrier
	s_add_i32 s33, s81, s69
	v_lshl_add_u64 v[170:171], s[64:65], 0, v[146:147]
	s_mov_b32 m0, s33
	ds_read_b128 v[208:211], v179
	ds_read_b128 v[212:215], v179 offset:1024
	ds_read_b128 v[216:219], v179 offset:2048
	ds_read_b128 v[220:223], v179 offset:3072
	global_load_lds_dwordx4 v[170:171], off
	v_lshl_add_u64 v[224:225], s[64:65], 0, v[152:153]
	s_add_i32 m0, s33, 0x2000
	s_nop 0
	global_load_lds_dwordx4 v[224:225], off
	s_barrier
	s_waitcnt lgkmcnt(0)
	v_mfma_f32_16x16x32_bf16 v[132:135], v[208:211], v[162:165], v[132:135]
	v_mfma_f32_16x16x32_bf16 v[128:131], v[216:219], v[162:165], v[128:131]
	v_mfma_f32_16x16x32_bf16 v[116:119], v[208:211], v[182:185], v[116:119]
	v_mfma_f32_16x16x32_bf16 v[112:115], v[216:219], v[182:185], v[112:115]
	v_mfma_f32_16x16x32_bf16 v[100:103], v[208:211], v[190:193], v[100:103]
	v_mfma_f32_16x16x32_bf16 v[96:99], v[216:219], v[190:193], v[96:99]
	v_mfma_f32_16x16x32_bf16 v[84:87], v[208:211], v[198:201], v[84:87]
	v_mfma_f32_16x16x32_bf16 v[80:83], v[216:219], v[198:201], v[80:83]
	v_mfma_f32_16x16x32_bf16 v[132:135], v[212:215], v[166:169], v[132:135]
	v_mfma_f32_16x16x32_bf16 v[128:131], v[220:223], v[166:169], v[128:131]
	v_mfma_f32_16x16x32_bf16 v[116:119], v[212:215], v[186:189], v[116:119]
	v_mfma_f32_16x16x32_bf16 v[112:115], v[220:223], v[186:189], v[112:115]
	v_mfma_f32_16x16x32_bf16 v[100:103], v[212:215], v[194:197], v[100:103]
	v_mfma_f32_16x16x32_bf16 v[96:99], v[220:223], v[194:197], v[96:99]
	v_mfma_f32_16x16x32_bf16 v[84:87], v[212:215], v[204:207], v[84:87]
	v_mfma_f32_16x16x32_bf16 v[80:83], v[220:223], v[204:207], v[80:83]
	s_mov_b32 m0, s59
	v_lshl_add_u64 v[226:227], s[62:63], 0, v[144:145]
	s_barrier
	ds_read_b128 v[162:165], v178 offset:16384
	ds_read_b128 v[166:169], v178 offset:17408
	ds_read_b128 v[182:185], v178 offset:18432
	ds_read_b128 v[186:189], v178 offset:19456
	ds_read_b128 v[190:193], v178 offset:20480
	ds_read_b128 v[194:197], v178 offset:21504
	ds_read_b128 v[198:201], v178 offset:22528
	ds_read_b128 v[204:207], v178 offset:23552
	global_load_lds_dwordx4 v[226:227], off
	v_lshl_add_u64 v[228:229], s[62:63], 0, v[150:151]
	s_mov_b32 m0, s70
	s_nop 0
	global_load_lds_dwordx4 v[228:229], off
	s_barrier
	s_waitcnt lgkmcnt(0)
	v_mfma_f32_16x16x32_bf16 v[76:79], v[32:35], v[162:165], v[76:79]
	v_mfma_f32_16x16x32_bf16 v[72:75], v[48:51], v[162:165], v[72:75]
	v_mfma_f32_16x16x32_bf16 v[60:63], v[32:35], v[182:185], v[60:63]
	v_mfma_f32_16x16x32_bf16 v[56:59], v[48:51], v[182:185], v[56:59]
	v_mfma_f32_16x16x32_bf16 v[28:31], v[32:35], v[190:193], v[28:31]
	v_mfma_f32_16x16x32_bf16 v[24:27], v[48:51], v[190:193], v[24:27]
	v_mfma_f32_16x16x32_bf16 v[12:15], v[32:35], v[198:201], v[12:15]
	v_mfma_f32_16x16x32_bf16 v[8:11], v[48:51], v[198:201], v[8:11]
	v_mfma_f32_16x16x32_bf16 v[76:79], v[40:43], v[166:169], v[76:79]
	v_mfma_f32_16x16x32_bf16 v[72:75], v[52:55], v[166:169], v[72:75]
	v_mfma_f32_16x16x32_bf16 v[60:63], v[40:43], v[186:189], v[60:63]
	v_mfma_f32_16x16x32_bf16 v[56:59], v[52:55], v[186:189], v[56:59]
	v_mfma_f32_16x16x32_bf16 v[28:31], v[40:43], v[194:197], v[28:31]
	v_mfma_f32_16x16x32_bf16 v[24:27], v[52:55], v[194:197], v[24:27]
	v_mfma_f32_16x16x32_bf16 v[12:15], v[40:43], v[204:207], v[12:15]
	v_mfma_f32_16x16x32_bf16 v[8:11], v[52:55], v[204:207], v[8:11]
	s_barrier
	s_add_i32 s33, s82, s69
	v_lshl_add_u64 v[230:231], s[64:65], 0, v[148:149]
	s_mov_b32 m0, s33
	v_lshl_add_u64 v[232:233], s[64:65], 0, v[154:155]
	global_load_lds_dwordx4 v[230:231], off
	s_add_i32 m0, s33, 0x2000
	s_nop 0
	global_load_lds_dwordx4 v[232:233], off
	s_waitcnt vmcnt(6)
	s_barrier
; #define PG8_STAGE(bufoff, gbase, voff) do { _Pragma("unroll") for (int _i = 0; _i < 2; ++_i) \
;         __builtin_amdgcn_global_load_lds((const unsigned*)((const char*)(gbase) + (voff)[_i]), (LAS unsigned*)(lds + (bufoff) + ldsw + _i * 8192), 16, 0, 0); } while (0)
; #define PG8_LDA(dst, b, h) do { _Pragma("unroll") for (int m = 0; m < 4; ++m) _Pragma("unroll") for (int k = 0; k < 2; ++k) dst[m][k] = *(const LAS bf16x8*)(lds + PG8_SA(b, h) + aoff + m * 2048 + k * 1024); } while (0)
; #define PG8_LDB(dst, b, h) do { _Pragma("unroll") for (int n = 0; n < 2; ++n) _Pragma("unroll") for (int k = 0; k < 2; ++k) dst[n][k] = *(const LAS bf16x8*)(lds + PG8_SB(b, h) + boff + n * 2048 + k * 1024); } while (0)
; #define PG8_MMA(ai, bj, At, Bt) do { __builtin_amdgcn_s_setprio(1); _Pragma("unroll") for (int m = 0; m < 4; ++m) _Pragma("unroll") for (int n = 0; n < 2; ++n) _Pragma("unroll") for (int k = 0; k < 2; ++k) \
;         acc[ai][bj][m][n] = __builtin_amdgcn_mfma_f32_16x16x32_bf16(Bt[n][k], At[m][k], acc[ai][bj][m][n], 0, 0, 0); __builtin_amdgcn_s_setprio(0); } while (0)
; #define PG8_WAIT_V(n) asm volatile("s_waitcnt vmcnt(" #n ")" ::: "memory")
; #define PG8_WAIT_L(n) asm volatile("s_waitcnt lgkmcnt(" #n ")" ::: "memory")
; #define PG8_BAR __builtin_amdgcn_s_barrier()
; #define PG8_SCHED __builtin_amdgcn_sched_barrier(0)
; template <class Epi>
; __device__ __forceinline__ void gemm_phase(LAS unsigned char* lds, const Gemm g, const StaticOrder& S, const Epi& E) {
;     ...
;             PG8_LDB(B0, 1, 0); PG8_SCHED; PG8_LDA(At, 1, 0); PG8_STAGE(PG8_SA(0, 1), a2 + hstep, voffA);
;             PG8_WAIT_L(8); PG8_BAR; PG8_WAIT_L(0); PG8_MMA(0, 0, At, B0); PG8_BAR; PG8_SCHED;
;             PG8_LDB(B1, 1, 1); PG8_STAGE(PG8_SB(1, 0), b3, voffB0);
;             PG8_BAR; PG8_WAIT_L(0); PG8_MMA(0, 1, At, B1); PG8_BAR;
;             PG8_LDA(At, 1, 1); PG8_STAGE(PG8_SA(1, 0), a3, voffA);
;             PG8_BAR; PG8_WAIT_L(0); PG8_MMA(1, 0, At, B0); PG8_BAR; PG8_SCHED;
;             PG8_STAGE(PG8_SB(1, 1), b3, voffB1);
;             PG8_WAIT_V(6); PG8_BAR; PG8_MMA(1, 1, At, B1); PG8_BAR;
	v_mfma_f32_16x16x32_bf16 v[44:47], v[208:211], v[182:185], v[44:47]
	v_mfma_f32_16x16x32_bf16 v[36:39], v[216:219], v[182:185], v[36:39]
	v_mfma_f32_16x16x32_bf16 v[20:23], v[208:211], v[190:193], v[20:23]
	v_mfma_f32_16x16x32_bf16 v[16:19], v[216:219], v[190:193], v[16:19]
	v_mfma_f32_16x16x32_bf16 v[4:7], v[208:211], v[198:201], v[4:7]
	v_mfma_f32_16x16x32_bf16 v[0:3], v[216:219], v[198:201], v[0:3]
	v_mfma_f32_16x16x32_bf16 v[32:35], v[208:211], v[162:165], v[68:71]
	v_mfma_f32_16x16x32_bf16 v[40:43], v[216:219], v[162:165], v[64:67]
	v_mfma_f32_16x16x32_bf16 v[44:47], v[212:215], v[186:189], v[44:47]
	v_mfma_f32_16x16x32_bf16 v[36:39], v[220:223], v[186:189], v[36:39]
	v_mfma_f32_16x16x32_bf16 v[20:23], v[212:215], v[194:197], v[20:23]
	v_mfma_f32_16x16x32_bf16 v[16:19], v[220:223], v[194:197], v[16:19]
	v_mfma_f32_16x16x32_bf16 v[4:7], v[212:215], v[204:207], v[4:7]
	v_mfma_f32_16x16x32_bf16 v[0:3], v[220:223], v[204:207], v[0:3]
	v_mfma_f32_16x16x32_bf16 v[32:35], v[212:215], v[166:169], v[32:35]
	v_mfma_f32_16x16x32_bf16 v[40:43], v[220:223], v[166:169], v[40:43]
	s_add_i32 s33, 0, 0x18000
	v_add_u32_e32 v68, s33, v173
	s_barrier
	ds_read_b128 v[48:51], v68
	ds_read_b128 v[52:55], v68 offset:1024
	ds_read_b128 v[64:67], v68 offset:2048
	ds_read_b128 v[68:71], v68 offset:3072
	s_add_u32 s62, s62, 0x80000
	s_addc_u32 s63, s63, 0
	s_mov_b32 m0, s71
	v_lshl_add_u64 v[208:209], s[62:63], 0, v[144:145]
	ds_read_b128 v[162:165], v178 offset:32768
	ds_read_b128 v[166:169], v178 offset:33792
	ds_read_b128 v[182:185], v178 offset:34816
	ds_read_b128 v[186:189], v178 offset:35840
	ds_read_b128 v[190:193], v178 offset:36864
	ds_read_b128 v[194:197], v178 offset:37888
	ds_read_b128 v[198:201], v178 offset:38912
	ds_read_b128 v[204:207], v178 offset:39936
	global_load_lds_dwordx4 v[208:209], off
	v_lshl_add_u64 v[208:209], s[62:63], 0, v[150:151]
	s_mov_b32 m0, s72
	s_nop 0
	global_load_lds_dwordx4 v[208:209], off
	s_waitcnt lgkmcnt(8)
	s_barrier
	s_waitcnt lgkmcnt(0)
	v_mfma_f32_16x16x32_bf16 v[140:143], v[48:51], v[162:165], v[140:143]
	v_mfma_f32_16x16x32_bf16 v[136:139], v[64:67], v[162:165], v[136:139]
	v_mfma_f32_16x16x32_bf16 v[124:127], v[48:51], v[182:185], v[124:127]
	v_mfma_f32_16x16x32_bf16 v[120:123], v[64:67], v[182:185], v[120:123]
	v_mfma_f32_16x16x32_bf16 v[108:111], v[48:51], v[190:193], v[108:111]
	v_mfma_f32_16x16x32_bf16 v[104:107], v[64:67], v[190:193], v[104:107]
	v_mfma_f32_16x16x32_bf16 v[92:95], v[48:51], v[198:201], v[92:95]
	v_mfma_f32_16x16x32_bf16 v[88:91], v[64:67], v[198:201], v[88:91]
	v_mfma_f32_16x16x32_bf16 v[140:143], v[52:55], v[166:169], v[140:143]
	v_mfma_f32_16x16x32_bf16 v[136:139], v[68:71], v[166:169], v[136:139]
	v_mfma_f32_16x16x32_bf16 v[124:127], v[52:55], v[186:189], v[124:127]
	v_mfma_f32_16x16x32_bf16 v[120:123], v[68:71], v[186:189], v[120:123]
	v_mfma_f32_16x16x32_bf16 v[108:111], v[52:55], v[194:197], v[108:111]
	v_mfma_f32_16x16x32_bf16 v[104:107], v[68:71], v[194:197], v[104:107]
	v_mfma_f32_16x16x32_bf16 v[92:95], v[52:55], v[204:207], v[92:95]
	v_mfma_f32_16x16x32_bf16 v[88:91], v[68:71], v[204:207], v[88:91]
	s_barrier
	s_add_i32 s62, 0, 0x1c000
	s_add_i32 s33, s33, s69
	v_add_u32_e32 v181, s62, v173
	v_lshl_add_u64 v[170:171], v[170:171], 0, s[42:43]
	s_mov_b32 m0, s33
	ds_read_b128 v[208:211], v181
	ds_read_b128 v[212:215], v181 offset:1024
	ds_read_b128 v[216:219], v181 offset:2048
	ds_read_b128 v[220:223], v181 offset:3072
	global_load_lds_dwordx4 v[170:171], off
	v_lshl_add_u64 v[170:171], v[224:225], 0, s[42:43]
	s_add_i32 m0, s33, 0x2000
	s_nop 0
	global_load_lds_dwordx4 v[170:171], off
	s_barrier
	s_waitcnt lgkmcnt(0)
	v_mfma_f32_16x16x32_bf16 v[132:135], v[208:211], v[162:165], v[132:135]
	v_mfma_f32_16x16x32_bf16 v[128:131], v[216:219], v[162:165], v[128:131]
	v_mfma_f32_16x16x32_bf16 v[116:119], v[208:211], v[182:185], v[116:119]
	v_mfma_f32_16x16x32_bf16 v[112:115], v[216:219], v[182:185], v[112:115]
	v_mfma_f32_16x16x32_bf16 v[100:103], v[208:211], v[190:193], v[100:103]
	v_mfma_f32_16x16x32_bf16 v[96:99], v[216:219], v[190:193], v[96:99]
	v_mfma_f32_16x16x32_bf16 v[84:87], v[208:211], v[198:201], v[84:87]
	v_mfma_f32_16x16x32_bf16 v[80:83], v[216:219], v[198:201], v[80:83]
	v_mfma_f32_16x16x32_bf16 v[132:135], v[212:215], v[166:169], v[132:135]
	v_mfma_f32_16x16x32_bf16 v[128:131], v[220:223], v[166:169], v[128:131]
	v_mfma_f32_16x16x32_bf16 v[116:119], v[212:215], v[186:189], v[116:119]
	v_mfma_f32_16x16x32_bf16 v[112:115], v[220:223], v[186:189], v[112:115]
	v_mfma_f32_16x16x32_bf16 v[100:103], v[212:215], v[194:197], v[100:103]
	v_mfma_f32_16x16x32_bf16 v[96:99], v[220:223], v[194:197], v[96:99]
	v_mfma_f32_16x16x32_bf16 v[84:87], v[212:215], v[204:207], v[84:87]
	v_mfma_f32_16x16x32_bf16 v[80:83], v[220:223], v[204:207], v[80:83]
	s_mov_b32 m0, s74
	v_lshl_add_u64 v[170:171], v[226:227], 0, s[42:43]
	s_barrier
	ds_read_b128 v[162:165], v178 offset:49152
	ds_read_b128 v[166:169], v178 offset:50176
	ds_read_b128 v[182:185], v178 offset:51200
	ds_read_b128 v[186:189], v178 offset:52224
	ds_read_b128 v[190:193], v178 offset:53248
	ds_read_b128 v[194:197], v178 offset:54272
	ds_read_b128 v[198:201], v178 offset:55296
	ds_read_b128 v[204:207], v178 offset:56320
	global_load_lds_dwordx4 v[170:171], off
	v_lshl_add_u64 v[170:171], v[228:229], 0, s[42:43]
	s_mov_b32 m0, s75
	s_nop 0
	global_load_lds_dwordx4 v[170:171], off
	s_barrier
; __device__ __forceinline__ float bflo(unsigned w) { return __uint_as_float(w << 16); }
; __device__ __forceinline__ float bfhi(unsigned w) { return __uint_as_float(w & 0xffff0000u); }
; #define PG8_WAIT_V(n) asm volatile("s_waitcnt vmcnt(" #n ")" ::: "memory")
; #define PG8_BAR __builtin_amdgcn_s_barrier()
;     __device__ __forceinline__ void operator()(const f32x4 (&acc)[2][2][4][2], const Unit& u, int wr, int wc, int fr, int fq) const {
;     ...
;             for (int m = 0; m < 4; ++m) { const int row = row0 + ai * HALF + m * 16; const size_t off = (size_t)row * D + col0; const float ri = __builtin_amdgcn_rsqf(sse[row] * (1.f / D) + EPS); float sq = 0.f; u32x4 w[2];
;                 u32x4 rr[2], ee[2]; load_pair_lines(R, D, row, fr, col0, rr[0], rr[1]); load_pair_lines(E, D, row, fr, col0, ee[0], ee[1]);
; #pragma unroll
;                 for (int bj = 0; bj < 2; ++bj) { const u32x4 rw = rr[bj], ew = ee[bj];
;                     const float r[8] = {bflo(rw.x), bfhi(rw.x), bflo(rw.y), bfhi(rw.y), bflo(rw.z), bfhi(rw.z), bflo(rw.w), bfhi(rw.w)};
;                     const float e[8] = {bflo(ew.x), bfhi(ew.x), bflo(ew.y), bfhi(ew.y), bflo(ew.z), bfhi(ew.z), bflo(ew.w), bfhi(ew.w)};
;                     float o[8];
; #pragma unroll
;                     for (int j = 0; j < 8; ++j) { const float a = acc[ai][bj][m][j >> 2][j & 3]; const float gg = gv[bj][j >> 2][j & 3];
;                         o[j] = r[j] + e[j] * ri * gg * __builtin_amdgcn_rcpf(1.f + __builtin_amdgcn_exp2f(-a * LOG2E)); }
; template <class Epi>
; __device__ __forceinline__ void gemm_phase(LAS unsigned char* lds, const Gemm g, const StaticOrder& S, const Epi& E) {
;     ...
;             PG8_WAIT_V(6); PG8_BAR; PG8_MMA(1, 1, At, B1); PG8_BAR;
;             PG8_LDB(B0, 1, 0); PG8_SCHED; PG8_LDA(At, 1, 0); PG8_STAGE(PG8_SA(0, 1), a2 + hstep, voffA);
;             PG8_WAIT_L(8); PG8_BAR; PG8_WAIT_L(0); PG8_MMA(0, 0, At, B0); PG8_BAR; PG8_SCHED;
;             PG8_LDB(B1, 1, 1); PG8_STAGE(PG8_SB(1, 0), b3, voffB0);
;             PG8_BAR; PG8_WAIT_L(0); PG8_MMA(0, 1, At, B1); PG8_BAR;
;             PG8_LDA(At, 1, 1); PG8_STAGE(PG8_SA(1, 0), a3, voffA);
;             PG8_BAR; PG8_WAIT_L(0); PG8_MMA(1, 0, At, B0); PG8_BAR; PG8_SCHED;
;             PG8_STAGE(PG8_SB(1, 1), b3, voffB1);
;             PG8_WAIT_V(6); PG8_BAR; PG8_MMA(1, 1, At, B1); PG8_BAR;
;         }
;         E(acc, cur, wr, wc, fr, fq);
	s_waitcnt lgkmcnt(0)
	v_mfma_f32_16x16x32_bf16 v[76:79], v[48:51], v[162:165], v[76:79]
	v_mfma_f32_16x16x32_bf16 v[72:75], v[64:67], v[162:165], v[72:75]
	v_mfma_f32_16x16x32_bf16 v[60:63], v[48:51], v[182:185], v[60:63]
	v_mfma_f32_16x16x32_bf16 v[56:59], v[64:67], v[182:185], v[56:59]
	v_mfma_f32_16x16x32_bf16 v[28:31], v[48:51], v[190:193], v[28:31]
	v_mfma_f32_16x16x32_bf16 v[24:27], v[64:67], v[190:193], v[24:27]
	v_mfma_f32_16x16x32_bf16 v[12:15], v[48:51], v[198:201], v[12:15]
	v_mfma_f32_16x16x32_bf16 v[8:11], v[64:67], v[198:201], v[8:11]
	v_mfma_f32_16x16x32_bf16 v[76:79], v[52:55], v[166:169], v[76:79]
	v_mfma_f32_16x16x32_bf16 v[72:75], v[68:71], v[166:169], v[72:75]
	v_mfma_f32_16x16x32_bf16 v[60:63], v[52:55], v[186:189], v[60:63]
	v_mfma_f32_16x16x32_bf16 v[56:59], v[68:71], v[186:189], v[56:59]
	v_mfma_f32_16x16x32_bf16 v[28:31], v[52:55], v[194:197], v[28:31]
	v_mfma_f32_16x16x32_bf16 v[24:27], v[68:71], v[194:197], v[24:27]
	v_mfma_f32_16x16x32_bf16 v[12:15], v[52:55], v[204:207], v[12:15]
	v_mfma_f32_16x16x32_bf16 v[8:11], v[68:71], v[204:207], v[8:11]
	s_barrier
	s_add_i32 s33, s62, s69
	v_lshl_add_u64 v[48:49], v[230:231], 0, s[42:43]
	s_mov_b32 m0, s33
	s_nop 0
	global_load_lds_dwordx4 v[48:49], off
	v_lshl_add_u64 v[48:49], v[232:233], 0, s[42:43]
	s_add_i32 m0, s33, 0x2000
	s_nop 0
	global_load_lds_dwordx4 v[48:49], off
	s_waitcnt vmcnt(6)
	s_barrier
	v_mfma_f32_16x16x32_bf16 v[32:35], v[208:211], v[162:165], v[32:35]
	v_mfma_f32_16x16x32_bf16 v[68:71], v[212:215], v[166:169], v[32:35]
	v_mfma_f32_16x16x32_bf16 v[32:35], v[216:219], v[162:165], v[40:43]
	v_mfma_f32_16x16x32_bf16 v[64:67], v[220:223], v[166:169], v[32:35]
	v_mfma_f32_16x16x32_bf16 v[32:35], v[208:211], v[182:185], v[44:47]
	v_mfma_f32_16x16x32_bf16 v[44:47], v[212:215], v[186:189], v[32:35]
	v_mfma_f32_16x16x32_bf16 v[32:35], v[216:219], v[182:185], v[36:39]
	v_mfma_f32_16x16x32_bf16 v[20:23], v[208:211], v[190:193], v[20:23]
	v_mfma_f32_16x16x32_bf16 v[16:19], v[216:219], v[190:193], v[16:19]
	v_mfma_f32_16x16x32_bf16 v[4:7], v[208:211], v[198:201], v[4:7]
	v_mfma_f32_16x16x32_bf16 v[0:3], v[216:219], v[198:201], v[0:3]
	v_mfma_f32_16x16x32_bf16 v[36:39], v[220:223], v[186:189], v[32:35]
	v_mfma_f32_16x16x32_bf16 v[20:23], v[212:215], v[194:197], v[20:23]
	v_mfma_f32_16x16x32_bf16 v[16:19], v[220:223], v[194:197], v[16:19]
	v_mfma_f32_16x16x32_bf16 v[4:7], v[212:215], v[204:207], v[4:7]
	v_mfma_f32_16x16x32_bf16 v[0:3], v[220:223], v[204:207], v[0:3]
	s_add_i32 s86, s86, 2
	s_add_u32 s60, s60, 0x100
	s_addc_u32 s61, s61, 0
	s_add_u32 s84, s84, 0x100
	s_addc_u32 s85, s85, 0
	s_cmp_gt_u32 s86, 29
	s_barrier
	s_cbranch_scc0 .LBB0_882
	s_lshl_b32 s33, s58, 8
	s_add_i32 s33, s33, s77
	v_lshl_or_b32 v32, s56, 8, v176
	v_or_b32_e32 v40, s33, v174
	v_or_b32_e32 v34, v32, v175
	v_ashrrev_i32_e32 v41, 31, v40
	v_ashrrev_i32_e32 v35, 31, v34
	v_lshlrev_b64 v[168:169], 12, v[40:41]
	v_lshl_add_u64 v[42:43], s[16:17], 0, v[168:169]
	v_lshlrev_b64 v[162:163], 1, v[34:35]
	v_lshl_add_u64 v[34:35], v[42:43], 0, v[162:163]
	global_load_dwordx4 v[182:185], v[34:35], off
	v_or_b32_e32 v34, 8, v40
	v_ashrrev_i32_e32 v35, 31, v34
	v_or_b32_e32 v164, s33, v172
	v_lshlrev_b64 v[170:171], 12, v[34:35]
	v_ashrrev_i32_e32 v165, 31, v164
	v_lshl_add_u64 v[34:35], s[16:17], 0, v[170:171]
	v_lshl_add_u64 v[166:167], v[164:165], 2, s[40:41]
	v_lshl_add_u64 v[34:35], v[34:35], 0, v[162:163]
	global_load_dword v181, v[166:167], off
	v_lshl_add_u64 v[40:41], s[38:39], 0, v[168:169]
	global_load_dwordx4 v[190:193], v[34:35], off
	v_lshl_add_u64 v[34:35], s[38:39], 0, v[170:171]
	v_lshl_add_u64 v[40:41], v[40:41], 0, v[162:163]
	v_lshl_add_u64 v[34:35], v[34:35], 0, v[162:163]
	global_load_dwordx4 v[186:189], v[40:41], off
	global_load_dwordx4 v[194:197], v[34:35], off
	v_ashrrev_i32_e32 v33, 31, v32
	v_lshl_add_u64 v[40:41], v[32:33], 2, s[10:11]
	global_load_dwordx4 v[52:55], v[40:41], off
	global_load_dwordx4 v[48:51], v[40:41], off offset:16
	global_load_dwordx4 v[32:35], v[40:41], off offset:48
	s_nop 0
	global_load_dwordx4 v[40:43], v[40:41], off offset:32
	v_or_b32_e32 v216, 16, v164
	v_ashrrev_i32_e32 v217, 31, v216
	v_lshl_add_u64 v[218:219], v[216:217], 2, s[40:41]
	global_load_dword v226, v[218:219], off
	v_sub_u32_e32 v218, v216, v172
	v_add_u32_e32 v218, v218, v174
	v_ashrrev_i32_e32 v219, 31, v218
	v_lshlrev_b64 v[218:219], 12, v[218:219]
	v_lshl_add_u64 v[220:221], s[16:17], 0, v[218:219]
	v_lshl_add_u64 v[220:221], v[220:221], 0, v[162:163]
	global_load_dwordx4 v[228:231], v[220:221], off
	v_lshl_add_u64 v[220:221], s[38:39], 0, v[218:219]
	v_lshl_add_u64 v[220:221], v[220:221], 0, v[162:163]
	global_load_dwordx4 v[232:235], v[220:221], off
	v_lshl_add_u64 v[220:221], v[218:219], 0, s[44:45]
	v_lshl_add_u64 v[224:225], s[38:39], 0, v[220:221]
	v_lshl_add_u64 v[222:223], s[16:17], 0, v[220:221]
	v_lshl_add_u64 v[224:225], v[224:225], 0, v[162:163]
	v_lshl_add_u64 v[222:223], v[222:223], 0, v[162:163]
	global_load_dwordx4 v[236:239], v[224:225], off
	global_load_dwordx4 v[240:243], v[222:223], off
	v_mul_f32_e32 v140, 0xbfb8aa3b, v140
	v_exp_f32_e32 v140, v140
	v_mul_f32_e32 v141, 0xbfb8aa3b, v141
	v_exp_f32_e32 v141, v141
	v_add_f32_e32 v140, 1.0, v140
	v_rcp_f32_e32 v140, v140
	v_add_f32_e32 v141, 1.0, v141
	v_rcp_f32_e32 v141, v141
	v_mul_f32_e32 v136, 0xbfb8aa3b, v136
	v_exp_f32_e32 v136, v136
	v_mul_f32_e32 v137, 0xbfb8aa3b, v137
	v_exp_f32_e32 v137, v137
	v_add_f32_e32 v136, 1.0, v136
	v_rcp_f32_e32 v136, v136
	v_add_f32_e32 v137, 1.0, v137
	v_mul_f32_e32 v132, 0xbfb8aa3b, v132
	v_rcp_f32_e32 v137, v137
	v_exp_f32_e32 v132, v132
	v_mul_f32_e32 v133, 0xbfb8aa3b, v133
	v_exp_f32_e32 v133, v133
	v_add_f32_e32 v132, 1.0, v132
	v_rcp_f32_e32 v132, v132
	v_add_f32_e32 v133, 1.0, v133
	v_rcp_f32_e32 v133, v133
	v_mul_f32_e32 v128, 0xbfb8aa3b, v128
	v_exp_f32_e32 v128, v128
	v_mul_f32_e32 v129, 0xbfb8aa3b, v129
	v_exp_f32_e32 v129, v129
	v_add_f32_e32 v128, 1.0, v128
	v_rcp_f32_e32 v128, v128
	v_add_f32_e32 v129, 1.0, v129
	v_rcp_f32_e32 v129, v129
	s_waitcnt vmcnt(5)
; __device__ __forceinline__ unsigned cvt_pk_bf16(float lo, float hi) { unsigned r; asm volatile("v_cvt_pk_bf16_f32 %0, %1, %2" : "=v"(r) : "v"(lo), "v"(hi)); return r; }
; __device__ __forceinline__ float bflo(unsigned w) { return __uint_as_float(w << 16); }
;     const bool lo = fr < 8;
;     const int r1 = row - fr + (fr & 7), cb = col0 + (lo ? 0 : boff);
;     const u32x4 l1 = *(const u32x4*)(P + (size_t)r1 * ld + cb), l2 = *(const u32x4*)(P + (size_t)(r1 + 8) * ld + cb);
;     const u32x4 s1 = {dpp_ror8(l1.x), dpp_ror8(l1.y), dpp_ror8(l1.z), dpp_ror8(l1.w)}, s2 = {dpp_ror8(l2.x), dpp_ror8(l2.y), dpp_ror8(l2.z), dpp_ror8(l2.w)};
;     wA = lo ? l1 : s2; wB = lo ? s1 : l2;
; }
;     __device__ __forceinline__ void operator()(const f32x4 (&acc)[2][2][4][2], const Unit& u, int wr, int wc, int fr, int fq) const {
;     ...
;             for (int m = 0; m < 4; ++m) { const int row = row0 + ai * HALF + m * 16; const size_t off = (size_t)row * D + col0; const float ri = __builtin_amdgcn_rsqf(sse[row] * (1.f / D) + EPS); float sq = 0.f; u32x4 w[2];
;                 u32x4 rr[2], ee[2]; load_pair_lines(R, D, row, fr, col0, rr[0], rr[1]); load_pair_lines(E, D, row, fr, col0, ee[0], ee[1]);
; #pragma unroll
;                 for (int bj = 0; bj < 2; ++bj) { const u32x4 rw = rr[bj], ew = ee[bj];
;                     const float r[8] = {bflo(rw.x), bfhi(rw.x), bflo(rw.y), bfhi(rw.y), bflo(rw.z), bfhi(rw.z), bflo(rw.w), bfhi(rw.w)};
;                     const float e[8] = {bflo(ew.x), bfhi(ew.x), bflo(ew.y), bfhi(ew.y), bflo(ew.z), bfhi(ew.z), bflo(ew.w), bfhi(ew.w)};
;                     float o[8];
; #pragma unroll
;                     for (int j = 0; j < 8; ++j) { const float a = acc[ai][bj][m][j >> 2][j & 3]; const float gg = gv[bj][j >> 2][j & 3];
;                         o[j] = r[j] + e[j] * ri * gg * __builtin_amdgcn_rcpf(1.f + __builtin_amdgcn_exp2f(-a * LOG2E)); }
;                     if (OUT) { *(f32x4*)(OUT + off + 8 * bj) = (f32x4){o[0], o[1], o[2], o[3]}; *(f32x4*)(OUT + off + 8 * bj + 4) = (f32x4){o[4], o[5], o[6], o[7]}; }
;                     else { sq += (o[0] * o[0] + o[1] * o[1]) + (o[2] * o[2] + o[3] * o[3]) + (o[4] * o[4] + o[5] * o[5]) + (o[6] * o[6] + o[7] * o[7]);
;                         w[bj].x = cvt_pk_bf16(o[0], o[1]); w[bj].y = cvt_pk_bf16(o[2], o[3]); w[bj].z = cvt_pk_bf16(o[4], o[5]); w[bj].w = cvt_pk_bf16(o[6], o[7]); } }
	v_mov_b32_dpp v198, v182 row_ror:8 row_mask:0xf bank_mask:0xf
	v_mov_b32_dpp v199, v183 row_ror:8 row_mask:0xf bank_mask:0xf
	v_mov_b32_dpp v200, v184 row_ror:8 row_mask:0xf bank_mask:0xf
	v_mov_b32_dpp v201, v185 row_ror:8 row_mask:0xf bank_mask:0xf
	v_fmamk_f32 v181, v181, 0x3a000000, v180
	v_rsq_f32_e32 v181, v181
	v_mov_b32_dpp v204, v190 row_ror:8 row_mask:0xf bank_mask:0xf
	v_cndmask_b32_e64 v182, v204, v182, s[6:7]
	v_cndmask_b32_e64 v190, v190, v198, s[6:7]
	v_lshlrev_b32_e32 v198, 16, v182
	v_mov_b32_dpp v208, v186 row_ror:8 row_mask:0xf bank_mask:0xf
	v_mov_b32_dpp v212, v194 row_ror:8 row_mask:0xf bank_mask:0xf
	v_cndmask_b32_e64 v186, v212, v186, s[6:7]
	v_lshlrev_b32_e32 v204, 16, v186
	v_mul_f32_e32 v204, v181, v204
	v_and_b32_e32 v186, 0xffff0000, v186
	v_mul_f32_e32 v204, v52, v204
	v_fmac_f32_e32 v198, v140, v204
	v_mul_f32_e32 v140, v181, v186
	v_and_b32_e32 v182, 0xffff0000, v182
	v_mul_f32_e32 v140, v53, v140
	v_fmac_f32_e32 v182, v141, v140
	v_mul_f32_e32 v140, 0xbfb8aa3b, v142
	v_exp_f32_e32 v140, v140
	v_mul_f32_e32 v142, 0xbfb8aa3b, v143
	v_exp_f32_e32 v142, v142
	v_mov_b32_dpp v213, v195 row_ror:8 row_mask:0xf bank_mask:0xf
	v_add_f32_e32 v140, 1.0, v140
	v_mov_b32_dpp v209, v187 row_ror:8 row_mask:0xf bank_mask:0xf
	v_mov_b32_dpp v205, v191 row_ror:8 row_mask:0xf bank_mask:0xf
	v_cndmask_b32_e64 v187, v213, v187, s[6:7]
	v_rcp_f32_e32 v140, v140
	v_cndmask_b32_e64 v183, v205, v183, s[6:7]
	v_lshlrev_b32_e32 v205, 16, v187
	v_add_f32_e32 v142, 1.0, v142
	v_mul_f32_e32 v141, v181, v205
	v_rcp_f32_e32 v142, v142
	v_cndmask_b32_e64 v191, v191, v199, s[6:7]
	v_mov_b32_dpp v214, v196 row_ror:8 row_mask:0xf bank_mask:0xf
	v_lshlrev_b32_e32 v199, 16, v183
	v_and_b32_e32 v187, 0xffff0000, v187
	v_mul_f32_e32 v141, v54, v141
	v_mov_b32_dpp v210, v188 row_ror:8 row_mask:0xf bank_mask:0xf
	v_mov_b32_dpp v206, v192 row_ror:8 row_mask:0xf bank_mask:0xf
	v_cndmask_b32_e64 v188, v214, v188, s[6:7]
	v_fmac_f32_e32 v199, v140, v141
	v_mul_f32_e32 v140, v181, v187
	v_cndmask_b32_e64 v184, v206, v184, s[6:7]
	v_and_b32_e32 v183, 0xffff0000, v183
	v_lshlrev_b32_e32 v206, 16, v188
	v_mul_f32_e32 v140, v55, v140
	v_fmac_f32_e32 v183, v142, v140
	v_mul_f32_e32 v140, v181, v206
	v_cndmask_b32_e64 v192, v192, v200, s[6:7]
	v_lshlrev_b32_e32 v200, 16, v184
	v_and_b32_e32 v188, 0xffff0000, v188
	v_mul_f32_e32 v140, v48, v140
	v_fmac_f32_e32 v200, v136, v140
	v_mul_f32_e32 v136, v181, v188
	v_and_b32_e32 v184, 0xffff0000, v184
	v_mul_f32_e32 v136, v49, v136
	v_fmac_f32_e32 v184, v137, v136
	v_mul_f32_e32 v136, 0xbfb8aa3b, v138
	v_cndmask_b32_e64 v194, v194, v208, s[6:7]
	v_exp_f32_e32 v136, v136
	v_mul_f32_e32 v138, 0xbfb8aa3b, v139
	v_lshlrev_b32_e32 v187, 16, v194
	v_exp_f32_e32 v138, v138
	v_mul_f32_e32 v187, v181, v187
	v_lshlrev_b32_e32 v141, 16, v190
	v_and_b32_e32 v188, 0xffff0000, v194
	v_mul_f32_e32 v187, v40, v187
	v_mov_b32_dpp v215, v197 row_ror:8 row_mask:0xf bank_mask:0xf
	v_add_f32_e32 v136, 1.0, v136
	v_fmac_f32_e32 v141, v132, v187
	v_mul_f32_e32 v132, v181, v188
	v_mov_b32_dpp v211, v189 row_ror:8 row_mask:0xf bank_mask:0xf
	v_mov_b32_dpp v207, v193 row_ror:8 row_mask:0xf bank_mask:0xf
	v_cndmask_b32_e64 v189, v215, v189, s[6:7]
	v_rcp_f32_e32 v136, v136
	v_and_b32_e32 v142, 0xffff0000, v190
	v_mul_f32_e32 v132, v41, v132
	v_cndmask_b32_e64 v185, v207, v185, s[6:7]
	v_lshlrev_b32_e32 v207, 16, v189
	v_add_f32_e32 v138, 1.0, v138
	v_fmac_f32_e32 v142, v133, v132
	v_mul_f32_e32 v132, 0xbfb8aa3b, v134
	v_mul_f32_e32 v137, v181, v207
	v_rcp_f32_e32 v138, v138
	v_exp_f32_e32 v132, v132
	v_cndmask_b32_e64 v193, v193, v201, s[6:7]
	v_lshlrev_b32_e32 v201, 16, v185
	v_and_b32_e32 v189, 0xffff0000, v189
	v_mul_f32_e32 v137, v50, v137
	v_mul_f32_e32 v134, 0xbfb8aa3b, v135
	v_fmac_f32_e32 v201, v136, v137
	v_mul_f32_e32 v136, v181, v189
	v_exp_f32_e32 v134, v134
	v_and_b32_e32 v185, 0xffff0000, v185
	v_mul_f32_e32 v136, v51, v136
	v_fmac_f32_e32 v185, v138, v136
	v_mul_f32_e32 v136, v182, v182
	v_mul_f32_e32 v137, v183, v183
	v_add_f32_e32 v132, 1.0, v132
	v_cndmask_b32_e64 v195, v195, v209, s[6:7]
	v_fmac_f32_e32 v136, v198, v198
	v_fmac_f32_e32 v137, v199, v199
	v_rcp_f32_e32 v132, v132
	v_add_f32_e32 v136, v136, v137
	v_mul_f32_e32 v137, v184, v184
	v_lshlrev_b32_e32 v189, 16, v195
	v_add_f32_e32 v134, 1.0, v134
	v_fmac_f32_e32 v137, v200, v200
	v_mul_f32_e32 v133, v181, v189
	v_rcp_f32_e32 v134, v134
	v_add_f32_e32 v136, v137, v136
	v_mul_f32_e32 v137, v185, v185
	v_lshlrev_b32_e32 v143, 16, v191
	v_and_b32_e32 v190, 0xffff0000, v195
	v_mul_f32_e32 v133, v42, v133
	v_cndmask_b32_e64 v196, v196, v210, s[6:7]
	v_fmac_f32_e32 v137, v201, v201
	v_fmac_f32_e32 v143, v132, v133
	v_mul_f32_e32 v132, v181, v190
	v_add_f32_e32 v136, v137, v136
	v_cvt_pk_bf16_f32 v137, v198, v182
	v_and_b32_e32 v182, 0xffff0000, v191
	v_lshlrev_b32_e32 v191, 16, v196
	v_mul_f32_e32 v132, v43, v132
	v_fmac_f32_e32 v182, v134, v132
	v_mul_f32_e32 v132, v181, v191
	v_cvt_pk_bf16_f32 v138, v199, v183
	v_cvt_pk_bf16_f32 v139, v200, v184
	v_lshlrev_b32_e32 v183, 16, v192
	v_and_b32_e32 v184, 0xffff0000, v192
	v_and_b32_e32 v192, 0xffff0000, v196
	v_mul_f32_e32 v132, v32, v132
	v_fmac_f32_e32 v183, v128, v132
	v_mul_f32_e32 v128, v181, v192
	v_mul_f32_e32 v128, v33, v128
	v_fmac_f32_e32 v184, v129, v128
	v_mul_f32_e32 v128, 0xbfb8aa3b, v130
	v_exp_f32_e32 v128, v128
	v_mul_f32_e32 v130, 0xbfb8aa3b, v131
	v_exp_f32_e32 v130, v130
	v_cndmask_b32_e64 v197, v197, v211, s[6:7]
	v_add_f32_e32 v128, 1.0, v128
	v_rcp_f32_e32 v128, v128
	v_cvt_pk_bf16_f32 v140, v201, v185
	v_lshlrev_b32_e32 v185, 16, v193
	v_and_b32_e32 v186, 0xffff0000, v193
	v_lshlrev_b32_e32 v193, 16, v197
; __device__ __forceinline__ unsigned cvt_pk_bf16(float lo, float hi) { unsigned r; asm volatile("v_cvt_pk_bf16_f32 %0, %1, %2" : "=v"(r) : "v"(lo), "v"(hi)); return r; }
; __device__ __forceinline__ unsigned dpp_ror8(unsigned x) { return (unsigned)__builtin_amdgcn_update_dpp(0, (int)x, 0x128, 0xf, 0xf, false); }
; __device__ __forceinline__ void store_pair_lines(bf16_t* O, int ldc, int row, int fr, int col0, u32x4 wA, u32x4 wB) {
;     const u32x4 sA = {dpp_ror8(wA.x), dpp_ror8(wA.y), dpp_ror8(wA.z), dpp_ror8(wA.w)}, sB = {dpp_ror8(wB.x), dpp_ror8(wB.y), dpp_ror8(wB.z), dpp_ror8(wB.w)};
;     const bool lo = fr < 8;
;     const u32x4 o1 = lo ? wA : sB, o2 = lo ? sA : wB;
;     const int r1 = row - fr + (fr & 7), cb = col0 + (lo ? 0 : 8);
;     *(u32x4*)(O + (size_t)r1 * ldc + cb) = o1;
;     *(u32x4*)(O + (size_t)(r1 + 8) * ldc + cb) = o2;
; }
;     __device__ __forceinline__ void operator()(const f32x4 (&acc)[2][2][4][2], const Unit& u, int wr, int wc, int fr, int fq) const {
;     ...
;                     for (int j = 0; j < 8; ++j) { const float a = acc[ai][bj][m][j >> 2][j & 3]; const float gg = gv[bj][j >> 2][j & 3];
;                         o[j] = r[j] + e[j] * ri * gg * __builtin_amdgcn_rcpf(1.f + __builtin_amdgcn_exp2f(-a * LOG2E)); }
;                     if (OUT) { *(f32x4*)(OUT + off + 8 * bj) = (f32x4){o[0], o[1], o[2], o[3]}; *(f32x4*)(OUT + off + 8 * bj + 4) = (f32x4){o[4], o[5], o[6], o[7]}; }
;                     else { sq += (o[0] * o[0] + o[1] * o[1]) + (o[2] * o[2] + o[3] * o[3]) + (o[4] * o[4] + o[5] * o[5]) + (o[6] * o[6] + o[7] * o[7]);
;                         w[bj].x = cvt_pk_bf16(o[0], o[1]); w[bj].y = cvt_pk_bf16(o[2], o[3]); w[bj].z = cvt_pk_bf16(o[4], o[5]); w[bj].w = cvt_pk_bf16(o[6], o[7]); } }
;                 if (!OUT) { store_pair_lines(O, D, row, fr, col0, w[0], w[1]);
;                     sq += __shfl_xor(sq, 16); sq += __shfl_xor(sq, 32); if (fq == 0) unsafeAtomicAdd(ssout + row, sq); } }
	v_add_f32_e32 v130, 1.0, v130
	v_mul_f32_e32 v129, v181, v193
	v_rcp_f32_e32 v130, v130
	v_and_b32_e32 v194, 0xffff0000, v197
	v_mul_f32_e32 v129, v34, v129
	v_fmac_f32_e32 v185, v128, v129
	v_mul_f32_e32 v128, v181, v194
	v_mul_f32_e32 v128, v35, v128
	v_fmac_f32_e32 v186, v130, v128
	v_mul_f32_e32 v128, v142, v142
	v_mul_f32_e32 v129, v182, v182
	v_fmac_f32_e32 v128, v141, v141
	v_fmac_f32_e32 v129, v143, v143
	v_add_f32_e32 v128, v128, v129
	v_mul_f32_e32 v129, v184, v184
	v_fmac_f32_e32 v129, v183, v183
	v_add_f32_e32 v128, v129, v128
	v_mul_f32_e32 v129, v186, v186
	v_fmac_f32_e32 v129, v185, v185
	v_add_f32_e32 v128, v129, v128
	v_add_f32_e32 v135, v128, v136
	v_cvt_pk_bf16_f32 v128, v141, v142
	v_cvt_pk_bf16_f32 v129, v143, v182
	v_mov_b32_dpp v143, v138 row_ror:8 row_mask:0xf bank_mask:0xf
	v_mov_b32_dpp v130, v128 row_ror:8 row_mask:0xf bank_mask:0xf
	v_mov_b32_dpp v134, v137 row_ror:8 row_mask:0xf bank_mask:0xf
	v_cndmask_b32_e64 v130, v130, v137, s[6:7]
	v_mov_b32_dpp v131, v129 row_ror:8 row_mask:0xf bank_mask:0xf
	v_cndmask_b32_e64 v137, v129, v143, s[6:7]
	v_and_b32_e32 v129, 64, v203
	v_cndmask_b32_e64 v136, v128, v134, s[6:7]
	v_xor_b32_e32 v128, 16, v203
	v_add_u32_e32 v143, 64, v129
	v_cmp_lt_i32_e32 vcc, v128, v143
	v_cvt_pk_bf16_f32 v141, v183, v184
	v_mov_b32_e32 v181, 0
	v_mov_b32_e32 v133, 0
	v_cndmask_b32_e32 v128, v203, v128, vcc
	v_lshlrev_b32_e32 v134, 2, v128
	ds_bpermute_b32 v183, v134, v135
	v_cvt_pk_bf16_f32 v142, v185, v186
	v_mov_b32_dpp v181, v139 row_ror:8 row_mask:0xf bank_mask:0xf
	v_mov_b32_e32 v182, 0
	v_mov_b32_dpp v133, v142 row_ror:8 row_mask:0xf bank_mask:0xf
	v_lshl_add_u64 v[128:129], s[36:37], 0, v[168:169]
	v_mov_b32_dpp v182, v140 row_ror:8 row_mask:0xf bank_mask:0xf
	v_mov_b32_dpp v132, v141 row_ror:8 row_mask:0xf bank_mask:0xf
	v_cndmask_b32_e64 v131, v131, v138, s[6:7]
	v_cndmask_b32_e64 v133, v133, v140, s[6:7]
	v_cndmask_b32_e64 v138, v141, v181, s[6:7]
	v_lshl_add_u64 v[140:141], v[128:129], 0, v[162:163]
	v_xor_b32_e32 v129, 32, v203
	v_cmp_lt_i32_e32 vcc, v129, v143
	s_waitcnt lgkmcnt(0)
	v_add_f32_e32 v128, v135, v183
	v_cndmask_b32_e64 v132, v132, v139, s[6:7]
	v_cndmask_b32_e32 v129, v203, v129, vcc
	v_lshlrev_b32_e32 v135, 2, v129
	ds_bpermute_b32 v129, v135, v128
	global_store_dwordx4 v[140:141], v[130:133], off
	v_cndmask_b32_e64 v139, v142, v182, s[6:7]
	s_nop 0
	v_lshl_add_u64 v[130:131], s[36:37], 0, v[170:171]
	v_lshl_add_u64 v[130:131], v[130:131], 0, v[162:163]
	global_store_dwordx4 v[130:131], v[136:139], off
	s_and_saveexec_b64 s[56:57], s[8:9]
	s_cbranch_execz .LBB0_885
	v_lshl_add_u64 v[130:131], v[164:165], 2, s[18:19]
	s_waitcnt lgkmcnt(0)
	v_add_f32_e32 v128, v128, v129
	global_atomic_add_f32 v[130:131], v128, off
.LBB0_885:
	s_or_b64 exec, exec, s[56:57]
	v_or_b32_e32 v128, 16, v164
	s_waitcnt lgkmcnt(0)
	v_ashrrev_i32_e32 v129, 31, v128
	v_lshl_add_u64 v[130:131], v[128:129], 2, s[40:41]
	s_waitcnt vmcnt(2)
	s_nop 0
	v_mov_b32_e32 v165, v226
	v_sub_u32_e32 v130, v128, v172
	v_add_u32_e32 v130, v130, v174
	v_ashrrev_i32_e32 v131, 31, v130
	v_lshlrev_b64 v[130:131], 12, v[130:131]
	v_lshl_add_u64 v[132:133], s[16:17], 0, v[130:131]
	v_lshl_add_u64 v[132:133], v[132:133], 0, v[162:163]
	v_mov_b64_e32 v[136:137], v[228:229]
	v_mov_b64_e32 v[138:139], v[230:231]
	v_lshl_add_u64 v[132:133], s[38:39], 0, v[130:131]
	v_lshl_add_u64 v[132:133], v[132:133], 0, v[162:163]
	v_mov_b64_e32 v[140:141], v[232:233]
	v_mov_b64_e32 v[142:143], v[234:235]
	v_lshl_add_u64 v[132:133], v[130:131], 0, s[44:45]
	v_lshl_add_u64 v[182:183], s[38:39], 0, v[132:133]
	v_lshl_add_u64 v[168:169], s[16:17], 0, v[132:133]
	v_lshl_add_u64 v[182:183], v[182:183], 0, v[162:163]
	v_lshl_add_u64 v[168:169], v[168:169], 0, v[162:163]
	v_mov_b64_e32 v[182:183], v[236:237]
	v_mov_b64_e32 v[184:185], v[238:239]
	v_mul_f32_e32 v124, 0xbfb8aa3b, v124
	v_mov_b64_e32 v[168:169], v[240:241]
	v_mov_b64_e32 v[170:171], v[242:243]
	s_nop 1
	v_or_b32_e32 v216, 32, v164
	v_ashrrev_i32_e32 v217, 31, v216
	v_lshl_add_u64 v[218:219], v[216:217], 2, s[40:41]
	global_load_dword v226, v[218:219], off
	v_sub_u32_e32 v218, v216, v172
	v_add_u32_e32 v218, v218, v174
	v_ashrrev_i32_e32 v219, 31, v218
	v_lshlrev_b64 v[218:219], 12, v[218:219]
	v_lshl_add_u64 v[220:221], s[16:17], 0, v[218:219]
	v_lshl_add_u64 v[220:221], v[220:221], 0, v[162:163]
	global_load_dwordx4 v[228:231], v[220:221], off
	v_lshl_add_u64 v[220:221], s[38:39], 0, v[218:219]
	v_lshl_add_u64 v[220:221], v[220:221], 0, v[162:163]
	global_load_dwordx4 v[232:235], v[220:221], off
	v_lshl_add_u64 v[220:221], v[218:219], 0, s[44:45]
	v_lshl_add_u64 v[224:225], s[38:39], 0, v[220:221]
	v_lshl_add_u64 v[222:223], s[16:17], 0, v[220:221]
	v_lshl_add_u64 v[224:225], v[224:225], 0, v[162:163]
	v_lshl_add_u64 v[222:223], v[222:223], 0, v[162:163]
	global_load_dwordx4 v[236:239], v[224:225], off
	global_load_dwordx4 v[240:243], v[222:223], off
	v_exp_f32_e32 v124, v124
	v_mul_f32_e32 v125, 0xbfb8aa3b, v125
	v_exp_f32_e32 v125, v125
	v_add_f32_e32 v124, 1.0, v124
	v_rcp_f32_e32 v124, v124
	v_add_f32_e32 v125, 1.0, v125
	v_rcp_f32_e32 v125, v125
	v_mul_f32_e32 v120, 0xbfb8aa3b, v120
	v_exp_f32_e32 v120, v120
	v_mul_f32_e32 v121, 0xbfb8aa3b, v121
	v_exp_f32_e32 v121, v121
	v_add_f32_e32 v120, 1.0, v120
	v_rcp_f32_e32 v120, v120
	v_add_f32_e32 v121, 1.0, v121
	v_mul_f32_e32 v116, 0xbfb8aa3b, v116
	v_rcp_f32_e32 v121, v121
	v_exp_f32_e32 v116, v116
	v_mul_f32_e32 v117, 0xbfb8aa3b, v117
	v_exp_f32_e32 v117, v117
	v_add_f32_e32 v116, 1.0, v116
	v_rcp_f32_e32 v116, v116
	v_add_f32_e32 v117, 1.0, v117
	v_rcp_f32_e32 v117, v117
	v_mul_f32_e32 v112, 0xbfb8aa3b, v112
; __device__ __forceinline__ float bflo(unsigned w) { return __uint_as_float(w << 16); }
; __device__ __forceinline__ float bfhi(unsigned w) { return __uint_as_float(w & 0xffff0000u); }
; __device__ __forceinline__ unsigned dpp_ror8(unsigned x) { return (unsigned)__builtin_amdgcn_update_dpp(0, (int)x, 0x128, 0xf, 0xf, false); }
;     const bool lo = fr < 8;
;     const int r1 = row - fr + (fr & 7), cb = col0 + (lo ? 0 : boff);
;     const u32x4 l1 = *(const u32x4*)(P + (size_t)r1 * ld + cb), l2 = *(const u32x4*)(P + (size_t)(r1 + 8) * ld + cb);
;     const u32x4 s1 = {dpp_ror8(l1.x), dpp_ror8(l1.y), dpp_ror8(l1.z), dpp_ror8(l1.w)}, s2 = {dpp_ror8(l2.x), dpp_ror8(l2.y), dpp_ror8(l2.z), dpp_ror8(l2.w)};
;     wA = lo ? l1 : s2; wB = lo ? s1 : l2;
; }
;     __device__ __forceinline__ void operator()(const f32x4 (&acc)[2][2][4][2], const Unit& u, int wr, int wc, int fr, int fq) const {
;     ...
;             for (int m = 0; m < 4; ++m) { const int row = row0 + ai * HALF + m * 16; const size_t off = (size_t)row * D + col0; const float ri = __builtin_amdgcn_rsqf(sse[row] * (1.f / D) + EPS); float sq = 0.f; u32x4 w[2];
;                 u32x4 rr[2], ee[2]; load_pair_lines(R, D, row, fr, col0, rr[0], rr[1]); load_pair_lines(E, D, row, fr, col0, ee[0], ee[1]);
; #pragma unroll
;                 for (int bj = 0; bj < 2; ++bj) { const u32x4 rw = rr[bj], ew = ee[bj];
;                     const float r[8] = {bflo(rw.x), bfhi(rw.x), bflo(rw.y), bfhi(rw.y), bflo(rw.z), bfhi(rw.z), bflo(rw.w), bfhi(rw.w)};
;                     const float e[8] = {bflo(ew.x), bfhi(ew.x), bflo(ew.y), bfhi(ew.y), bflo(ew.z), bfhi(ew.z), bflo(ew.w), bfhi(ew.w)};
;                     float o[8];
; #pragma unroll
;                     for (int j = 0; j < 8; ++j) { const float a = acc[ai][bj][m][j >> 2][j & 3]; const float gg = gv[bj][j >> 2][j & 3];
;                         o[j] = r[j] + e[j] * ri * gg * __builtin_amdgcn_rcpf(1.f + __builtin_amdgcn_exp2f(-a * LOG2E)); }
	v_exp_f32_e32 v112, v112
	v_mul_f32_e32 v113, 0xbfb8aa3b, v113
	v_exp_f32_e32 v113, v113
	v_add_f32_e32 v112, 1.0, v112
	v_rcp_f32_e32 v112, v112
	v_add_f32_e32 v113, 1.0, v113
	v_rcp_f32_e32 v113, v113
	v_fmamk_f32 v165, v165, 0x3a000000, v180
	v_rsq_f32_e32 v165, v165
	v_mov_b32_dpp v181, v136 row_ror:8 row_mask:0xf bank_mask:0xf
	v_mov_b32_dpp v186, v137 row_ror:8 row_mask:0xf bank_mask:0xf
	v_mov_b32_dpp v187, v138 row_ror:8 row_mask:0xf bank_mask:0xf
	v_mov_b32_dpp v193, v140 row_ror:8 row_mask:0xf bank_mask:0xf
	v_mov_b32_dpp v196, v143 row_ror:8 row_mask:0xf bank_mask:0xf
	v_mov_b32_dpp v194, v141 row_ror:8 row_mask:0xf bank_mask:0xf
	v_mov_b32_dpp v195, v142 row_ror:8 row_mask:0xf bank_mask:0xf
	v_mov_b32_dpp v188, v139 row_ror:8 row_mask:0xf bank_mask:0xf
	v_mov_b32_dpp v197, v182 row_ror:8 row_mask:0xf bank_mask:0xf
	v_cndmask_b32_e64 v140, v197, v140, s[6:7]
	v_mov_b32_dpp v189, v168 row_ror:8 row_mask:0xf bank_mask:0xf
	v_cndmask_b32_e64 v136, v189, v136, s[6:7]
	v_lshlrev_b32_e32 v189, 16, v140
	v_mul_f32_e32 v189, v165, v189
	v_cndmask_b32_e64 v168, v168, v181, s[6:7]
	v_mov_b32_dpp v200, v185 row_ror:8 row_mask:0xf bank_mask:0xf
	v_cndmask_b32_e64 v181, v185, v196, s[6:7]
	v_lshlrev_b32_e32 v185, 16, v136
	v_and_b32_e32 v140, 0xffff0000, v140
	v_mul_f32_e32 v189, v52, v189
	v_fmac_f32_e32 v185, v124, v189
	v_mul_f32_e32 v124, v165, v140
	v_and_b32_e32 v136, 0xffff0000, v136
	v_mul_f32_e32 v124, v53, v124
	v_fmac_f32_e32 v136, v125, v124
	v_mul_f32_e32 v124, 0xbfb8aa3b, v126
	v_exp_f32_e32 v124, v124
	v_mul_f32_e32 v126, 0xbfb8aa3b, v127
	v_exp_f32_e32 v126, v126
	v_mov_b32_dpp v198, v183 row_ror:8 row_mask:0xf bank_mask:0xf
	v_add_f32_e32 v124, 1.0, v124
	v_mov_b32_dpp v190, v169 row_ror:8 row_mask:0xf bank_mask:0xf
	v_cndmask_b32_e64 v141, v198, v141, s[6:7]
	v_rcp_f32_e32 v124, v124
	v_cndmask_b32_e64 v137, v190, v137, s[6:7]
	v_lshlrev_b32_e32 v190, 16, v141
	v_add_f32_e32 v126, 1.0, v126
	v_mul_f32_e32 v125, v165, v190
	v_rcp_f32_e32 v126, v126
	v_cndmask_b32_e64 v169, v169, v186, s[6:7]
	v_mov_b32_dpp v199, v184 row_ror:8 row_mask:0xf bank_mask:0xf
	v_lshlrev_b32_e32 v186, 16, v137
	v_and_b32_e32 v141, 0xffff0000, v141
	v_mul_f32_e32 v125, v54, v125
	v_mov_b32_dpp v191, v170 row_ror:8 row_mask:0xf bank_mask:0xf
	v_cndmask_b32_e64 v142, v199, v142, s[6:7]
	v_fmac_f32_e32 v186, v124, v125
	v_mul_f32_e32 v124, v165, v141
	v_cndmask_b32_e64 v138, v191, v138, s[6:7]
	v_and_b32_e32 v137, 0xffff0000, v137
	v_lshlrev_b32_e32 v191, 16, v142
	v_mul_f32_e32 v124, v55, v124
	v_fmac_f32_e32 v137, v126, v124
	v_mul_f32_e32 v124, v165, v191
	v_cndmask_b32_e64 v170, v170, v187, s[6:7]
	v_lshlrev_b32_e32 v187, 16, v138
	v_and_b32_e32 v142, 0xffff0000, v142
	v_mul_f32_e32 v124, v48, v124
	v_fmac_f32_e32 v187, v120, v124
	v_mul_f32_e32 v120, v165, v142
	v_and_b32_e32 v138, 0xffff0000, v138
	v_mul_f32_e32 v120, v49, v120
	v_fmac_f32_e32 v138, v121, v120
	v_mul_f32_e32 v120, 0xbfb8aa3b, v122
	v_cndmask_b32_e64 v182, v182, v193, s[6:7]
	v_exp_f32_e32 v120, v120
	v_mul_f32_e32 v122, 0xbfb8aa3b, v123
	v_lshlrev_b32_e32 v141, 16, v182
	v_exp_f32_e32 v122, v122
	v_mul_f32_e32 v141, v165, v141
	v_lshlrev_b32_e32 v125, 16, v168
	v_and_b32_e32 v142, 0xffff0000, v182
	v_mul_f32_e32 v141, v40, v141
	v_add_f32_e32 v120, 1.0, v120
	v_fmac_f32_e32 v125, v116, v141
	v_mul_f32_e32 v116, v165, v142
	v_mov_b32_dpp v192, v171 row_ror:8 row_mask:0xf bank_mask:0xf
	v_cndmask_b32_e64 v143, v200, v143, s[6:7]
	v_rcp_f32_e32 v120, v120
	v_and_b32_e32 v126, 0xffff0000, v168
	v_mul_f32_e32 v116, v41, v116
	v_cndmask_b32_e64 v139, v192, v139, s[6:7]
	v_lshlrev_b32_e32 v192, 16, v143
	v_add_f32_e32 v122, 1.0, v122
	v_fmac_f32_e32 v126, v117, v116
	v_mul_f32_e32 v116, 0xbfb8aa3b, v118
	v_mul_f32_e32 v121, v165, v192
	v_rcp_f32_e32 v122, v122
	v_exp_f32_e32 v116, v116
	v_cndmask_b32_e64 v171, v171, v188, s[6:7]
	v_lshlrev_b32_e32 v188, 16, v139
	v_and_b32_e32 v143, 0xffff0000, v143
	v_mul_f32_e32 v121, v50, v121
	v_mul_f32_e32 v118, 0xbfb8aa3b, v119
	v_fmac_f32_e32 v188, v120, v121
	v_mul_f32_e32 v120, v165, v143
	v_exp_f32_e32 v118, v118
	v_and_b32_e32 v139, 0xffff0000, v139
	v_mul_f32_e32 v120, v51, v120
	v_fmac_f32_e32 v139, v122, v120
	v_mul_f32_e32 v120, v136, v136
	v_mul_f32_e32 v121, v137, v137
	v_add_f32_e32 v116, 1.0, v116
	v_cndmask_b32_e64 v183, v183, v194, s[6:7]
	v_fmac_f32_e32 v120, v185, v185
	v_fmac_f32_e32 v121, v186, v186
	v_rcp_f32_e32 v116, v116
	v_add_f32_e32 v120, v120, v121
	v_mul_f32_e32 v121, v138, v138
	v_lshlrev_b32_e32 v143, 16, v183
	v_add_f32_e32 v118, 1.0, v118
	v_fmac_f32_e32 v121, v187, v187
	v_mul_f32_e32 v117, v165, v143
	v_rcp_f32_e32 v118, v118
	v_add_f32_e32 v120, v121, v120
	v_mul_f32_e32 v121, v139, v139
	v_lshlrev_b32_e32 v127, 16, v169
	v_and_b32_e32 v168, 0xffff0000, v183
	v_mul_f32_e32 v117, v42, v117
	v_cndmask_b32_e64 v184, v184, v195, s[6:7]
	v_fmac_f32_e32 v121, v188, v188
	v_fmac_f32_e32 v127, v116, v117
	v_mul_f32_e32 v116, v165, v168
	v_add_f32_e32 v120, v121, v120
	v_cvt_pk_bf16_f32 v121, v185, v136
	v_and_b32_e32 v136, 0xffff0000, v169
	v_lshlrev_b32_e32 v169, 16, v184
	v_mul_f32_e32 v116, v43, v116
	v_fmac_f32_e32 v136, v118, v116
	v_mul_f32_e32 v116, v165, v169
	v_cvt_pk_bf16_f32 v122, v186, v137
	v_cvt_pk_bf16_f32 v123, v187, v138
	v_lshlrev_b32_e32 v137, 16, v170
	v_and_b32_e32 v138, 0xffff0000, v170
	v_and_b32_e32 v170, 0xffff0000, v184
	v_mul_f32_e32 v116, v32, v116
	v_fmac_f32_e32 v137, v112, v116
	v_mul_f32_e32 v112, v165, v170
	v_mul_f32_e32 v112, v33, v112
	v_fmac_f32_e32 v138, v113, v112
	v_mul_f32_e32 v112, 0xbfb8aa3b, v114
	v_exp_f32_e32 v112, v112
	v_mul_f32_e32 v114, 0xbfb8aa3b, v115
; __device__ __forceinline__ void store_pair_lines(bf16_t* O, int ldc, int row, int fr, int col0, u32x4 wA, u32x4 wB) {
;     const u32x4 sA = {dpp_ror8(wA.x), dpp_ror8(wA.y), dpp_ror8(wA.z), dpp_ror8(wA.w)}, sB = {dpp_ror8(wB.x), dpp_ror8(wB.y), dpp_ror8(wB.z), dpp_ror8(wB.w)};
;     const bool lo = fr < 8;
;     const u32x4 o1 = lo ? wA : sB, o2 = lo ? sA : wB;
;     const int r1 = row - fr + (fr & 7), cb = col0 + (lo ? 0 : 8);
;     *(u32x4*)(O + (size_t)r1 * ldc + cb) = o1;
;     __device__ __forceinline__ void operator()(const f32x4 (&acc)[2][2][4][2], const Unit& u, int wr, int wc, int fr, int fq) const {
;     ...
;             for (int m = 0; m < 4; ++m) { const int row = row0 + ai * HALF + m * 16; const size_t off = (size_t)row * D + col0; const float ri = __builtin_amdgcn_rsqf(sse[row] * (1.f / D) + EPS); float sq = 0.f; u32x4 w[2];
;                 u32x4 rr[2], ee[2]; load_pair_lines(R, D, row, fr, col0, rr[0], rr[1]); load_pair_lines(E, D, row, fr, col0, ee[0], ee[1]);
; #pragma unroll
;                 for (int bj = 0; bj < 2; ++bj) { const u32x4 rw = rr[bj], ew = ee[bj];
;                     const float r[8] = {bflo(rw.x), bfhi(rw.x), bflo(rw.y), bfhi(rw.y), bflo(rw.z), bfhi(rw.z), bflo(rw.w), bfhi(rw.w)};
;                     const float e[8] = {bflo(ew.x), bfhi(ew.x), bflo(ew.y), bfhi(ew.y), bflo(ew.z), bfhi(ew.z), bflo(ew.w), bfhi(ew.w)};
;                     float o[8];
; #pragma unroll
;                     for (int j = 0; j < 8; ++j) { const float a = acc[ai][bj][m][j >> 2][j & 3]; const float gg = gv[bj][j >> 2][j & 3];
;                         o[j] = r[j] + e[j] * ri * gg * __builtin_amdgcn_rcpf(1.f + __builtin_amdgcn_exp2f(-a * LOG2E)); }
;                     if (OUT) { *(f32x4*)(OUT + off + 8 * bj) = (f32x4){o[0], o[1], o[2], o[3]}; *(f32x4*)(OUT + off + 8 * bj + 4) = (f32x4){o[4], o[5], o[6], o[7]}; }
;                     else { sq += (o[0] * o[0] + o[1] * o[1]) + (o[2] * o[2] + o[3] * o[3]) + (o[4] * o[4] + o[5] * o[5]) + (o[6] * o[6] + o[7] * o[7]);
;                         w[bj].x = cvt_pk_bf16(o[0], o[1]); w[bj].y = cvt_pk_bf16(o[2], o[3]); w[bj].z = cvt_pk_bf16(o[4], o[5]); w[bj].w = cvt_pk_bf16(o[6], o[7]); } }
;                 if (!OUT) { store_pair_lines(O, D, row, fr, col0, w[0], w[1]);
;                     sq += __shfl_xor(sq, 16); sq += __shfl_xor(sq, 32); if (fq == 0) unsafeAtomicAdd(ssout + row, sq); } }
	v_exp_f32_e32 v114, v114
	v_cvt_pk_bf16_f32 v124, v188, v139
	v_add_f32_e32 v112, 1.0, v112
	v_rcp_f32_e32 v112, v112
	v_lshlrev_b32_e32 v139, 16, v171
	v_and_b32_e32 v140, 0xffff0000, v171
	v_lshlrev_b32_e32 v171, 16, v181
	v_add_f32_e32 v114, 1.0, v114
	v_mul_f32_e32 v113, v165, v171
	v_rcp_f32_e32 v114, v114
	v_and_b32_e32 v181, 0xffff0000, v181
	v_mul_f32_e32 v113, v34, v113
	v_fmac_f32_e32 v139, v112, v113
	v_mul_f32_e32 v112, v165, v181
	v_mul_f32_e32 v112, v35, v112
	v_fmac_f32_e32 v140, v114, v112
	v_mul_f32_e32 v112, v126, v126
	v_mul_f32_e32 v113, v136, v136
	v_fmac_f32_e32 v112, v125, v125
	v_fmac_f32_e32 v113, v127, v127
	v_add_f32_e32 v112, v112, v113
	v_mul_f32_e32 v113, v138, v138
	v_fmac_f32_e32 v113, v137, v137
	v_add_f32_e32 v112, v113, v112
	v_mul_f32_e32 v113, v140, v140
	v_fmac_f32_e32 v113, v139, v139
	v_add_f32_e32 v112, v113, v112
	v_add_f32_e32 v141, v112, v120
	v_cvt_pk_bf16_f32 v112, v125, v126
	v_cvt_pk_bf16_f32 v113, v127, v136
	v_cvt_pk_bf16_f32 v120, v137, v138
	v_cvt_pk_bf16_f32 v125, v139, v140
	v_mov_b32_e32 v127, 0
	v_mov_b32_e32 v118, 0
	v_mov_b32_dpp v117, v125 row_ror:8 row_mask:0xf bank_mask:0xf
	v_mov_b32_dpp v127, v124 row_ror:8 row_mask:0xf bank_mask:0xf
	v_cndmask_b32_e64 v117, v117, v124, s[6:7]
	ds_bpermute_b32 v124, v134, v141
	v_mov_b32_dpp v118, v121 row_ror:8 row_mask:0xf bank_mask:0xf
	v_mov_b32_dpp v119, v122 row_ror:8 row_mask:0xf bank_mask:0xf
	v_mov_b32_dpp v114, v112 row_ror:8 row_mask:0xf bank_mask:0xf
	v_mov_b32_dpp v115, v113 row_ror:8 row_mask:0xf bank_mask:0xf
	v_mov_b32_dpp v116, v120 row_ror:8 row_mask:0xf bank_mask:0xf
	v_cndmask_b32_e64 v118, v112, v118, s[6:7]
	v_cndmask_b32_e64 v119, v113, v119, s[6:7]
	v_lshl_add_u64 v[112:113], s[36:37], 0, v[130:131]
	v_mov_b32_dpp v126, v123 row_ror:8 row_mask:0xf bank_mask:0xf
	v_cndmask_b32_e64 v115, v115, v122, s[6:7]
	v_cndmask_b32_e64 v116, v116, v123, s[6:7]
	v_lshl_add_u64 v[122:123], v[112:113], 0, v[162:163]
	s_waitcnt lgkmcnt(0)
	v_add_f32_e32 v112, v141, v124
	ds_bpermute_b32 v113, v135, v112
	v_cndmask_b32_e64 v114, v114, v121, s[6:7]
	global_store_dwordx4 v[122:123], v[114:117], off
	v_cndmask_b32_e64 v120, v120, v126, s[6:7]
	v_cndmask_b32_e64 v121, v125, v127, s[6:7]
	v_lshl_add_u64 v[114:115], s[36:37], 0, v[132:133]
	v_lshl_add_u64 v[114:115], v[114:115], 0, v[162:163]
	global_store_dwordx4 v[114:115], v[118:121], off
	s_and_saveexec_b64 s[56:57], s[8:9]
	s_cbranch_execz .LBB0_887
	v_lshl_add_u64 v[114:115], v[128:129], 2, s[18:19]
	s_waitcnt lgkmcnt(0)
	v_add_f32_e32 v112, v112, v113
	global_atomic_add_f32 v[114:115], v112, off
.LBB0_887:
	s_or_b64 exec, exec, s[56:57]
	v_or_b32_e32 v112, 32, v164
	s_waitcnt lgkmcnt(0)
	v_ashrrev_i32_e32 v113, 31, v112
	v_lshl_add_u64 v[114:115], v[112:113], 2, s[40:41]
	s_waitcnt vmcnt(2)
	s_nop 0
	v_mov_b32_e32 v136, v226
	v_sub_u32_e32 v114, v112, v172
	v_add_u32_e32 v114, v114, v174
	v_ashrrev_i32_e32 v115, 31, v114
	v_lshlrev_b64 v[114:115], 12, v[114:115]
	v_lshl_add_u64 v[116:117], s[16:17], 0, v[114:115]
	v_lshl_add_u64 v[116:117], v[116:117], 0, v[162:163]
	v_mov_b64_e32 v[118:119], v[228:229]
	v_mov_b64_e32 v[120:121], v[230:231]
	v_lshl_add_u64 v[116:117], s[38:39], 0, v[114:115]
	v_lshl_add_u64 v[116:117], v[116:117], 0, v[162:163]
	v_mov_b64_e32 v[122:123], v[232:233]
	v_mov_b64_e32 v[124:125], v[234:235]
	v_lshl_add_u64 v[116:117], v[114:115], 0, s[44:45]
	v_lshl_add_u64 v[130:131], s[38:39], 0, v[116:117]
	v_lshl_add_u64 v[126:127], s[16:17], 0, v[116:117]
	v_lshl_add_u64 v[130:131], v[130:131], 0, v[162:163]
	v_lshl_add_u64 v[126:127], v[126:127], 0, v[162:163]
	v_mov_b64_e32 v[130:131], v[236:237]
	v_mov_b64_e32 v[132:133], v[238:239]
	v_mul_f32_e32 v108, 0xbfb8aa3b, v108
	v_mov_b64_e32 v[126:127], v[240:241]
	v_mov_b64_e32 v[128:129], v[242:243]
	s_nop 1
	v_or_b32_e32 v216, 48, v164
	v_ashrrev_i32_e32 v217, 31, v216
	v_lshl_add_u64 v[218:219], v[216:217], 2, s[40:41]
	global_load_dword v226, v[218:219], off
	v_sub_u32_e32 v218, v216, v172
	v_add_u32_e32 v218, v218, v174
	v_ashrrev_i32_e32 v219, 31, v218
	v_lshlrev_b64 v[218:219], 12, v[218:219]
	v_lshl_add_u64 v[220:221], s[16:17], 0, v[218:219]
	v_lshl_add_u64 v[220:221], v[220:221], 0, v[162:163]
	global_load_dwordx4 v[228:231], v[220:221], off
	v_lshl_add_u64 v[220:221], s[38:39], 0, v[218:219]
	v_lshl_add_u64 v[220:221], v[220:221], 0, v[162:163]
	global_load_dwordx4 v[232:235], v[220:221], off
	v_lshl_add_u64 v[220:221], v[218:219], 0, s[44:45]
	v_lshl_add_u64 v[224:225], s[38:39], 0, v[220:221]
	v_lshl_add_u64 v[222:223], s[16:17], 0, v[220:221]
	v_lshl_add_u64 v[224:225], v[224:225], 0, v[162:163]
	v_lshl_add_u64 v[222:223], v[222:223], 0, v[162:163]
	global_load_dwordx4 v[236:239], v[224:225], off
	global_load_dwordx4 v[240:243], v[222:223], off
	v_exp_f32_e32 v108, v108
	v_mul_f32_e32 v109, 0xbfb8aa3b, v109
	v_exp_f32_e32 v109, v109
	v_add_f32_e32 v108, 1.0, v108
	v_rcp_f32_e32 v108, v108
	v_add_f32_e32 v109, 1.0, v109
	v_rcp_f32_e32 v109, v109
	v_mul_f32_e32 v104, 0xbfb8aa3b, v104
	v_exp_f32_e32 v104, v104
	v_mul_f32_e32 v105, 0xbfb8aa3b, v105
	v_exp_f32_e32 v105, v105
	v_add_f32_e32 v104, 1.0, v104
	v_rcp_f32_e32 v104, v104
	v_add_f32_e32 v105, 1.0, v105
	v_mul_f32_e32 v100, 0xbfb8aa3b, v100
	v_rcp_f32_e32 v105, v105
	v_exp_f32_e32 v100, v100
	v_mul_f32_e32 v101, 0xbfb8aa3b, v101
	v_exp_f32_e32 v101, v101
	v_add_f32_e32 v100, 1.0, v100
	v_rcp_f32_e32 v100, v100
	v_add_f32_e32 v101, 1.0, v101
	v_rcp_f32_e32 v101, v101
	v_mul_f32_e32 v96, 0xbfb8aa3b, v96
	v_exp_f32_e32 v96, v96
	v_mul_f32_e32 v97, 0xbfb8aa3b, v97
	v_exp_f32_e32 v97, v97
	v_add_f32_e32 v96, 1.0, v96
	v_rcp_f32_e32 v96, v96
	v_add_f32_e32 v97, 1.0, v97
; __device__ __forceinline__ void store_pair_lines(bf16_t* O, int ldc, int row, int fr, int col0, u32x4 wA, u32x4 wB) {
;     const u32x4 sA = {dpp_ror8(wA.x), dpp_ror8(wA.y), dpp_ror8(wA.z), dpp_ror8(wA.w)}, sB = {dpp_ror8(wB.x), dpp_ror8(wB.y), dpp_ror8(wB.z), dpp_ror8(wB.w)};
;     const bool lo = fr < 8;
;     const u32x4 o1 = lo ? wA : sB, o2 = lo ? sA : wB;
;     const int r1 = row - fr + (fr & 7), cb = col0 + (lo ? 0 : 8);
;     *(u32x4*)(O + (size_t)r1 * ldc + cb) = o1;
;     __device__ __forceinline__ void operator()(const f32x4 (&acc)[2][2][4][2], const Unit& u, int wr, int wc, int fr, int fq) const {
;     ...
;             for (int m = 0; m < 4; ++m) { const int row = row0 + ai * HALF + m * 16; const size_t off = (size_t)row * D + col0; const float ri = __builtin_amdgcn_rsqf(sse[row] * (1.f / D) + EPS); float sq = 0.f; u32x4 w[2];
;                 u32x4 rr[2], ee[2]; load_pair_lines(R, D, row, fr, col0, rr[0], rr[1]); load_pair_lines(E, D, row, fr, col0, ee[0], ee[1]);
; #pragma unroll
;                 for (int bj = 0; bj < 2; ++bj) { const u32x4 rw = rr[bj], ew = ee[bj];
;                     const float r[8] = {bflo(rw.x), bfhi(rw.x), bflo(rw.y), bfhi(rw.y), bflo(rw.z), bfhi(rw.z), bflo(rw.w), bfhi(rw.w)};
;                     const float e[8] = {bflo(ew.x), bfhi(ew.x), bflo(ew.y), bfhi(ew.y), bflo(ew.z), bfhi(ew.z), bflo(ew.w), bfhi(ew.w)};
;                     float o[8];
; #pragma unroll
;                     for (int j = 0; j < 8; ++j) { const float a = acc[ai][bj][m][j >> 2][j & 3]; const float gg = gv[bj][j >> 2][j & 3];
;                         o[j] = r[j] + e[j] * ri * gg * __builtin_amdgcn_rcpf(1.f + __builtin_amdgcn_exp2f(-a * LOG2E)); }
;                     if (OUT) { *(f32x4*)(OUT + off + 8 * bj) = (f32x4){o[0], o[1], o[2], o[3]}; *(f32x4*)(OUT + off + 8 * bj + 4) = (f32x4){o[4], o[5], o[6], o[7]}; }
;                     else { sq += (o[0] * o[0] + o[1] * o[1]) + (o[2] * o[2] + o[3] * o[3]) + (o[4] * o[4] + o[5] * o[5]) + (o[6] * o[6] + o[7] * o[7]);
;                         w[bj].x = cvt_pk_bf16(o[0], o[1]); w[bj].y = cvt_pk_bf16(o[2], o[3]); w[bj].z = cvt_pk_bf16(o[4], o[5]); w[bj].w = cvt_pk_bf16(o[6], o[7]); } }
;                 if (!OUT) { store_pair_lines(O, D, row, fr, col0, w[0], w[1]);
;                     sq += __shfl_xor(sq, 16); sq += __shfl_xor(sq, 32); if (fq == 0) unsafeAtomicAdd(ssout + row, sq); } }
	v_rcp_f32_e32 v97, v97
	v_fmamk_f32 v136, v136, 0x3a000000, v180
	v_rsq_f32_e32 v136, v136
	v_mov_b32_dpp v137, v118 row_ror:8 row_mask:0xf bank_mask:0xf
	v_mov_b32_dpp v138, v119 row_ror:8 row_mask:0xf bank_mask:0xf
	v_mov_b32_dpp v139, v120 row_ror:8 row_mask:0xf bank_mask:0xf
	v_mov_b32_dpp v168, v122 row_ror:8 row_mask:0xf bank_mask:0xf
	v_mov_b32_dpp v169, v123 row_ror:8 row_mask:0xf bank_mask:0xf
	v_mov_b32_dpp v170, v124 row_ror:8 row_mask:0xf bank_mask:0xf
	v_mov_b32_dpp v171, v125 row_ror:8 row_mask:0xf bank_mask:0xf
	v_mov_b32_dpp v140, v121 row_ror:8 row_mask:0xf bank_mask:0xf
	v_mov_b32_dpp v181, v130 row_ror:8 row_mask:0xf bank_mask:0xf
	v_cndmask_b32_e64 v122, v181, v122, s[6:7]
	v_mov_b32_dpp v141, v126 row_ror:8 row_mask:0xf bank_mask:0xf
	v_cndmask_b32_e64 v118, v141, v118, s[6:7]
	v_lshlrev_b32_e32 v141, 16, v122
	v_mul_f32_e32 v141, v136, v141
	v_cndmask_b32_e64 v126, v126, v137, s[6:7]
	v_lshlrev_b32_e32 v137, 16, v118
	v_and_b32_e32 v122, 0xffff0000, v122
	v_mul_f32_e32 v141, v52, v141
	v_fmac_f32_e32 v137, v108, v141
	v_mul_f32_e32 v108, v136, v122
	v_and_b32_e32 v118, 0xffff0000, v118
	v_mul_f32_e32 v108, v53, v108
	v_fmac_f32_e32 v118, v109, v108
	v_mul_f32_e32 v108, 0xbfb8aa3b, v110
	v_exp_f32_e32 v108, v108
	v_mul_f32_e32 v110, 0xbfb8aa3b, v111
	v_exp_f32_e32 v110, v110
	v_mov_b32_dpp v182, v131 row_ror:8 row_mask:0xf bank_mask:0xf
	v_add_f32_e32 v108, 1.0, v108
	v_mov_b32_dpp v142, v127 row_ror:8 row_mask:0xf bank_mask:0xf
	v_cndmask_b32_e64 v123, v182, v123, s[6:7]
	v_rcp_f32_e32 v108, v108
	v_cndmask_b32_e64 v119, v142, v119, s[6:7]
	v_lshlrev_b32_e32 v142, 16, v123
	v_add_f32_e32 v110, 1.0, v110
	v_mul_f32_e32 v109, v136, v142
	v_rcp_f32_e32 v110, v110
	v_cndmask_b32_e64 v127, v127, v138, s[6:7]
	v_mov_b32_dpp v183, v132 row_ror:8 row_mask:0xf bank_mask:0xf
	v_lshlrev_b32_e32 v138, 16, v119
	v_and_b32_e32 v123, 0xffff0000, v123
	v_mul_f32_e32 v109, v54, v109
	v_mov_b32_dpp v143, v128 row_ror:8 row_mask:0xf bank_mask:0xf
	v_cndmask_b32_e64 v124, v183, v124, s[6:7]
	v_fmac_f32_e32 v138, v108, v109
	v_mul_f32_e32 v108, v136, v123
	v_cndmask_b32_e64 v120, v143, v120, s[6:7]
	v_and_b32_e32 v119, 0xffff0000, v119
	v_lshlrev_b32_e32 v143, 16, v124
	v_mul_f32_e32 v108, v55, v108
	v_fmac_f32_e32 v119, v110, v108
	v_mul_f32_e32 v108, v136, v143
	v_cndmask_b32_e64 v128, v128, v139, s[6:7]
	v_lshlrev_b32_e32 v139, 16, v120
	v_and_b32_e32 v124, 0xffff0000, v124
	v_mul_f32_e32 v108, v48, v108
	v_fmac_f32_e32 v139, v104, v108
	v_mul_f32_e32 v104, v136, v124
	v_and_b32_e32 v120, 0xffff0000, v120
	v_mul_f32_e32 v104, v49, v104
	v_fmac_f32_e32 v120, v105, v104
	v_mul_f32_e32 v104, 0xbfb8aa3b, v106
	v_cndmask_b32_e64 v130, v130, v168, s[6:7]
	v_exp_f32_e32 v104, v104
	v_mul_f32_e32 v106, 0xbfb8aa3b, v107
	v_lshlrev_b32_e32 v123, 16, v130
	v_exp_f32_e32 v106, v106
	v_mul_f32_e32 v123, v136, v123
	v_lshlrev_b32_e32 v109, 16, v126
	v_and_b32_e32 v124, 0xffff0000, v130
	v_mul_f32_e32 v123, v40, v123
	v_mov_b32_dpp v184, v133 row_ror:8 row_mask:0xf bank_mask:0xf
	v_add_f32_e32 v104, 1.0, v104
	v_fmac_f32_e32 v109, v100, v123
	v_mul_f32_e32 v100, v136, v124
	v_mov_b32_dpp v165, v129 row_ror:8 row_mask:0xf bank_mask:0xf
	v_cndmask_b32_e64 v125, v184, v125, s[6:7]
	v_rcp_f32_e32 v104, v104
	v_and_b32_e32 v110, 0xffff0000, v126
	v_mul_f32_e32 v100, v41, v100
	v_cndmask_b32_e64 v121, v165, v121, s[6:7]
	v_lshlrev_b32_e32 v165, 16, v125
	v_add_f32_e32 v106, 1.0, v106
	v_fmac_f32_e32 v110, v101, v100
	v_mul_f32_e32 v100, 0xbfb8aa3b, v102
	v_mul_f32_e32 v105, v136, v165
	v_rcp_f32_e32 v106, v106
	v_exp_f32_e32 v100, v100
	v_cndmask_b32_e64 v129, v129, v140, s[6:7]
	v_lshlrev_b32_e32 v140, 16, v121
	v_and_b32_e32 v125, 0xffff0000, v125
	v_mul_f32_e32 v105, v50, v105
	v_mul_f32_e32 v102, 0xbfb8aa3b, v103
	v_fmac_f32_e32 v140, v104, v105
	v_mul_f32_e32 v104, v136, v125
	v_exp_f32_e32 v102, v102
	v_and_b32_e32 v121, 0xffff0000, v121
	v_mul_f32_e32 v104, v51, v104
	v_fmac_f32_e32 v121, v106, v104
	v_mul_f32_e32 v104, v118, v118
	v_mul_f32_e32 v105, v119, v119
	v_add_f32_e32 v100, 1.0, v100
	v_cndmask_b32_e64 v131, v131, v169, s[6:7]
	v_fmac_f32_e32 v104, v137, v137
	v_fmac_f32_e32 v105, v138, v138
	v_rcp_f32_e32 v100, v100
	v_add_f32_e32 v104, v104, v105
	v_mul_f32_e32 v105, v120, v120
	v_lshlrev_b32_e32 v125, 16, v131
	v_add_f32_e32 v102, 1.0, v102
	v_fmac_f32_e32 v105, v139, v139
	v_mul_f32_e32 v101, v136, v125
	v_rcp_f32_e32 v102, v102
	v_add_f32_e32 v104, v105, v104
	v_mul_f32_e32 v105, v121, v121
	v_lshlrev_b32_e32 v111, 16, v127
	v_and_b32_e32 v126, 0xffff0000, v131
	v_mul_f32_e32 v101, v42, v101
	v_cndmask_b32_e64 v132, v132, v170, s[6:7]
	v_fmac_f32_e32 v105, v140, v140
	v_fmac_f32_e32 v111, v100, v101
	v_mul_f32_e32 v100, v136, v126
	v_add_f32_e32 v104, v105, v104
	v_cvt_pk_bf16_f32 v105, v137, v118
	v_and_b32_e32 v118, 0xffff0000, v127
	v_lshlrev_b32_e32 v127, 16, v132
	v_mul_f32_e32 v100, v43, v100
	v_fmac_f32_e32 v118, v102, v100
	v_mul_f32_e32 v100, v136, v127
	v_cvt_pk_bf16_f32 v106, v138, v119
	v_cvt_pk_bf16_f32 v107, v139, v120
	v_lshlrev_b32_e32 v119, 16, v128
	v_and_b32_e32 v120, 0xffff0000, v128
	v_and_b32_e32 v128, 0xffff0000, v132
	v_mul_f32_e32 v100, v32, v100
	v_fmac_f32_e32 v119, v96, v100
	v_mul_f32_e32 v96, v136, v128
	v_mul_f32_e32 v96, v33, v96
	v_fmac_f32_e32 v120, v97, v96
	v_mul_f32_e32 v96, 0xbfb8aa3b, v98
	v_exp_f32_e32 v96, v96
	v_mul_f32_e32 v98, 0xbfb8aa3b, v99
	v_exp_f32_e32 v98, v98
	v_cndmask_b32_e64 v133, v133, v171, s[6:7]
	v_add_f32_e32 v96, 1.0, v96
	v_rcp_f32_e32 v96, v96
	v_cvt_pk_bf16_f32 v108, v140, v121
	v_lshlrev_b32_e32 v121, 16, v129
	v_and_b32_e32 v122, 0xffff0000, v129
	v_lshlrev_b32_e32 v129, 16, v133
; __device__ __forceinline__ void store_pair_lines(bf16_t* O, int ldc, int row, int fr, int col0, u32x4 wA, u32x4 wB) {
;     const u32x4 sA = {dpp_ror8(wA.x), dpp_ror8(wA.y), dpp_ror8(wA.z), dpp_ror8(wA.w)}, sB = {dpp_ror8(wB.x), dpp_ror8(wB.y), dpp_ror8(wB.z), dpp_ror8(wB.w)};
;     const bool lo = fr < 8;
;     const u32x4 o1 = lo ? wA : sB, o2 = lo ? sA : wB;
;     const int r1 = row - fr + (fr & 7), cb = col0 + (lo ? 0 : 8);
;     *(u32x4*)(O + (size_t)r1 * ldc + cb) = o1;
;     __device__ __forceinline__ void operator()(const f32x4 (&acc)[2][2][4][2], const Unit& u, int wr, int wc, int fr, int fq) const {
;     ...
;             for (int m = 0; m < 4; ++m) { const int row = row0 + ai * HALF + m * 16; const size_t off = (size_t)row * D + col0; const float ri = __builtin_amdgcn_rsqf(sse[row] * (1.f / D) + EPS); float sq = 0.f; u32x4 w[2];
;                 u32x4 rr[2], ee[2]; load_pair_lines(R, D, row, fr, col0, rr[0], rr[1]); load_pair_lines(E, D, row, fr, col0, ee[0], ee[1]);
; #pragma unroll
;                 for (int bj = 0; bj < 2; ++bj) { const u32x4 rw = rr[bj], ew = ee[bj];
;                     const float r[8] = {bflo(rw.x), bfhi(rw.x), bflo(rw.y), bfhi(rw.y), bflo(rw.z), bfhi(rw.z), bflo(rw.w), bfhi(rw.w)};
;                     const float e[8] = {bflo(ew.x), bfhi(ew.x), bflo(ew.y), bfhi(ew.y), bflo(ew.z), bfhi(ew.z), bflo(ew.w), bfhi(ew.w)};
;                     float o[8];
; #pragma unroll
;                     for (int j = 0; j < 8; ++j) { const float a = acc[ai][bj][m][j >> 2][j & 3]; const float gg = gv[bj][j >> 2][j & 3];
;                         o[j] = r[j] + e[j] * ri * gg * __builtin_amdgcn_rcpf(1.f + __builtin_amdgcn_exp2f(-a * LOG2E)); }
;                     if (OUT) { *(f32x4*)(OUT + off + 8 * bj) = (f32x4){o[0], o[1], o[2], o[3]}; *(f32x4*)(OUT + off + 8 * bj + 4) = (f32x4){o[4], o[5], o[6], o[7]}; }
;                     else { sq += (o[0] * o[0] + o[1] * o[1]) + (o[2] * o[2] + o[3] * o[3]) + (o[4] * o[4] + o[5] * o[5]) + (o[6] * o[6] + o[7] * o[7]);
;                         w[bj].x = cvt_pk_bf16(o[0], o[1]); w[bj].y = cvt_pk_bf16(o[2], o[3]); w[bj].z = cvt_pk_bf16(o[4], o[5]); w[bj].w = cvt_pk_bf16(o[6], o[7]); } }
;                 if (!OUT) { store_pair_lines(O, D, row, fr, col0, w[0], w[1]);
;                     sq += __shfl_xor(sq, 16); sq += __shfl_xor(sq, 32); if (fq == 0) unsafeAtomicAdd(ssout + row, sq); } }
	v_add_f32_e32 v98, 1.0, v98
	v_mul_f32_e32 v97, v136, v129
	v_rcp_f32_e32 v98, v98
	v_and_b32_e32 v130, 0xffff0000, v133
	v_mul_f32_e32 v97, v34, v97
	v_fmac_f32_e32 v121, v96, v97
	v_mul_f32_e32 v96, v136, v130
	v_mul_f32_e32 v96, v35, v96
	v_fmac_f32_e32 v122, v98, v96
	v_mul_f32_e32 v96, v110, v110
	v_mul_f32_e32 v97, v118, v118
	v_fmac_f32_e32 v96, v109, v109
	v_fmac_f32_e32 v97, v111, v111
	v_add_f32_e32 v96, v96, v97
	v_mul_f32_e32 v97, v120, v120
	v_fmac_f32_e32 v97, v119, v119
	v_add_f32_e32 v96, v97, v96
	v_mul_f32_e32 v97, v122, v122
	v_fmac_f32_e32 v97, v121, v121
	v_add_f32_e32 v96, v97, v96
	v_add_f32_e32 v123, v96, v104
	v_cvt_pk_bf16_f32 v96, v109, v110
	v_cvt_pk_bf16_f32 v97, v111, v118
	v_cvt_pk_bf16_f32 v104, v119, v120
	v_cvt_pk_bf16_f32 v109, v121, v122
	v_mov_b32_e32 v111, 0
	v_mov_b32_e32 v102, 0
	v_mov_b32_dpp v101, v109 row_ror:8 row_mask:0xf bank_mask:0xf
	v_mov_b32_dpp v111, v108 row_ror:8 row_mask:0xf bank_mask:0xf
	v_cndmask_b32_e64 v101, v101, v108, s[6:7]
	ds_bpermute_b32 v108, v134, v123
	v_mov_b32_dpp v102, v105 row_ror:8 row_mask:0xf bank_mask:0xf
	v_mov_b32_dpp v103, v106 row_ror:8 row_mask:0xf bank_mask:0xf
	v_mov_b32_dpp v98, v96 row_ror:8 row_mask:0xf bank_mask:0xf
	v_mov_b32_dpp v99, v97 row_ror:8 row_mask:0xf bank_mask:0xf
	v_mov_b32_dpp v100, v104 row_ror:8 row_mask:0xf bank_mask:0xf
	v_cndmask_b32_e64 v102, v96, v102, s[6:7]
	v_cndmask_b32_e64 v103, v97, v103, s[6:7]
	v_lshl_add_u64 v[96:97], s[36:37], 0, v[114:115]
	v_mov_b32_dpp v110, v107 row_ror:8 row_mask:0xf bank_mask:0xf
	v_cndmask_b32_e64 v99, v99, v106, s[6:7]
	v_cndmask_b32_e64 v100, v100, v107, s[6:7]
	v_lshl_add_u64 v[106:107], v[96:97], 0, v[162:163]
	s_waitcnt lgkmcnt(0)
	v_add_f32_e32 v96, v123, v108
	ds_bpermute_b32 v97, v135, v96
	v_cndmask_b32_e64 v98, v98, v105, s[6:7]
	global_store_dwordx4 v[106:107], v[98:101], off
	v_cndmask_b32_e64 v104, v104, v110, s[6:7]
	v_cndmask_b32_e64 v105, v109, v111, s[6:7]
	v_lshl_add_u64 v[98:99], s[36:37], 0, v[116:117]
	v_lshl_add_u64 v[98:99], v[98:99], 0, v[162:163]
	global_store_dwordx4 v[98:99], v[102:105], off
	s_and_saveexec_b64 s[56:57], s[8:9]
	s_cbranch_execz .LBB0_889
	v_lshl_add_u64 v[98:99], v[112:113], 2, s[18:19]
	s_waitcnt lgkmcnt(0)
	v_add_f32_e32 v96, v96, v97
	global_atomic_add_f32 v[98:99], v96, off
.LBB0_889:
	s_or_b64 exec, exec, s[56:57]
	v_or_b32_e32 v96, 48, v164
	s_waitcnt lgkmcnt(0)
	v_ashrrev_i32_e32 v97, 31, v96
	v_lshl_add_u64 v[98:99], v[96:97], 2, s[40:41]
	s_waitcnt vmcnt(2)
	s_nop 0
	v_mov_b32_e32 v118, v226
	v_sub_u32_e32 v98, v96, v172
	v_add_u32_e32 v98, v98, v174
	v_ashrrev_i32_e32 v99, 31, v98
	v_lshlrev_b64 v[98:99], 12, v[98:99]
	v_lshl_add_u64 v[100:101], s[16:17], 0, v[98:99]
	v_lshl_add_u64 v[100:101], v[100:101], 0, v[162:163]
	v_mov_b64_e32 v[102:103], v[228:229]
	v_mov_b64_e32 v[104:105], v[230:231]
	v_lshl_add_u64 v[100:101], s[38:39], 0, v[98:99]
	v_lshl_add_u64 v[100:101], v[100:101], 0, v[162:163]
	v_mov_b64_e32 v[106:107], v[232:233]
	v_mov_b64_e32 v[108:109], v[234:235]
	v_lshl_add_u64 v[100:101], v[98:99], 0, s[44:45]
	v_lshl_add_u64 v[114:115], s[38:39], 0, v[100:101]
	v_lshl_add_u64 v[110:111], s[16:17], 0, v[100:101]
	v_lshl_add_u64 v[114:115], v[114:115], 0, v[162:163]
	v_lshl_add_u64 v[110:111], v[110:111], 0, v[162:163]
	v_mov_b64_e32 v[114:115], v[236:237]
	v_mov_b64_e32 v[116:117], v[238:239]
	v_mul_f32_e32 v92, 0xbfb8aa3b, v92
	v_mov_b64_e32 v[110:111], v[240:241]
	v_mov_b64_e32 v[112:113], v[242:243]
	s_nop 1
	v_add_u32_e32 v216, 0x80, v164
	v_sub_u32_e32 v218, v216, v172
	v_add_u32_e32 v218, v218, v174
	v_ashrrev_i32_e32 v219, 31, v218
	v_lshlrev_b64 v[218:219], 12, v[218:219]
	v_lshl_add_u64 v[220:221], s[16:17], 0, v[218:219]
	v_lshl_add_u64 v[220:221], v[220:221], 0, v[162:163]
	global_load_dwordx4 v[228:231], v[220:221], off
	v_lshl_add_u64 v[220:221], s[38:39], 0, v[218:219]
	v_lshl_add_u64 v[220:221], v[220:221], 0, v[162:163]
	global_load_dword v226, v[166:167], off offset:512
	global_load_dwordx4 v[232:235], v[220:221], off
	v_lshl_add_u64 v[220:221], v[218:219], 0, s[44:45]
	v_lshl_add_u64 v[224:225], s[38:39], 0, v[220:221]
	v_lshl_add_u64 v[222:223], s[16:17], 0, v[220:221]
	v_lshl_add_u64 v[224:225], v[224:225], 0, v[162:163]
	v_lshl_add_u64 v[222:223], v[222:223], 0, v[162:163]
	global_load_dwordx4 v[236:239], v[224:225], off
	global_load_dwordx4 v[240:243], v[222:223], off
	v_exp_f32_e32 v92, v92
	v_mul_f32_e32 v93, 0xbfb8aa3b, v93
	v_exp_f32_e32 v93, v93
	v_add_f32_e32 v92, 1.0, v92
	v_rcp_f32_e32 v92, v92
	v_add_f32_e32 v93, 1.0, v93
	v_rcp_f32_e32 v93, v93
	v_mul_f32_e32 v88, 0xbfb8aa3b, v88
	v_exp_f32_e32 v88, v88
	v_mul_f32_e32 v89, 0xbfb8aa3b, v89
	v_exp_f32_e32 v89, v89
	v_add_f32_e32 v88, 1.0, v88
	v_rcp_f32_e32 v88, v88
	v_add_f32_e32 v89, 1.0, v89
	v_mul_f32_e32 v84, 0xbfb8aa3b, v84
	v_rcp_f32_e32 v89, v89
	v_exp_f32_e32 v84, v84
	v_mul_f32_e32 v85, 0xbfb8aa3b, v85
	v_exp_f32_e32 v85, v85
	v_add_f32_e32 v84, 1.0, v84
	v_rcp_f32_e32 v84, v84
	v_add_f32_e32 v85, 1.0, v85
	v_rcp_f32_e32 v85, v85
	v_mul_f32_e32 v80, 0xbfb8aa3b, v80
	v_exp_f32_e32 v80, v80
	v_mul_f32_e32 v81, 0xbfb8aa3b, v81
	v_exp_f32_e32 v81, v81
	v_add_f32_e32 v80, 1.0, v80
	v_rcp_f32_e32 v80, v80
	v_add_f32_e32 v81, 1.0, v81
	v_rcp_f32_e32 v81, v81
	v_fmamk_f32 v118, v118, 0x3a000000, v180
	v_rsq_f32_e32 v118, v118
	v_mov_b32_dpp v119, v102 row_ror:8 row_mask:0xf bank_mask:0xf
	v_mov_b32_dpp v120, v103 row_ror:8 row_mask:0xf bank_mask:0xf
	v_mov_b32_dpp v121, v104 row_ror:8 row_mask:0xf bank_mask:0xf
	v_mov_b32_dpp v127, v106 row_ror:8 row_mask:0xf bank_mask:0xf
	v_mov_b32_dpp v128, v107 row_ror:8 row_mask:0xf bank_mask:0xf
; __device__ __forceinline__ void store_pair_lines(bf16_t* O, int ldc, int row, int fr, int col0, u32x4 wA, u32x4 wB) {
;     const u32x4 sA = {dpp_ror8(wA.x), dpp_ror8(wA.y), dpp_ror8(wA.z), dpp_ror8(wA.w)}, sB = {dpp_ror8(wB.x), dpp_ror8(wB.y), dpp_ror8(wB.z), dpp_ror8(wB.w)};
;     const bool lo = fr < 8;
;     const u32x4 o1 = lo ? wA : sB, o2 = lo ? sA : wB;
;     const int r1 = row - fr + (fr & 7), cb = col0 + (lo ? 0 : 8);
;     *(u32x4*)(O + (size_t)r1 * ldc + cb) = o1;
;     __device__ __forceinline__ void operator()(const f32x4 (&acc)[2][2][4][2], const Unit& u, int wr, int wc, int fr, int fq) const {
;     ...
;             for (int m = 0; m < 4; ++m) { const int row = row0 + ai * HALF + m * 16; const size_t off = (size_t)row * D + col0; const float ri = __builtin_amdgcn_rsqf(sse[row] * (1.f / D) + EPS); float sq = 0.f; u32x4 w[2];
;                 u32x4 rr[2], ee[2]; load_pair_lines(R, D, row, fr, col0, rr[0], rr[1]); load_pair_lines(E, D, row, fr, col0, ee[0], ee[1]);
; #pragma unroll
;                 for (int bj = 0; bj < 2; ++bj) { const u32x4 rw = rr[bj], ew = ee[bj];
;                     const float r[8] = {bflo(rw.x), bfhi(rw.x), bflo(rw.y), bfhi(rw.y), bflo(rw.z), bfhi(rw.z), bflo(rw.w), bfhi(rw.w)};
;                     const float e[8] = {bflo(ew.x), bfhi(ew.x), bflo(ew.y), bfhi(ew.y), bflo(ew.z), bfhi(ew.z), bflo(ew.w), bfhi(ew.w)};
;                     float o[8];
; #pragma unroll
;                     for (int j = 0; j < 8; ++j) { const float a = acc[ai][bj][m][j >> 2][j & 3]; const float gg = gv[bj][j >> 2][j & 3];
;                         o[j] = r[j] + e[j] * ri * gg * __builtin_amdgcn_rcpf(1.f + __builtin_amdgcn_exp2f(-a * LOG2E)); }
;                     if (OUT) { *(f32x4*)(OUT + off + 8 * bj) = (f32x4){o[0], o[1], o[2], o[3]}; *(f32x4*)(OUT + off + 8 * bj + 4) = (f32x4){o[4], o[5], o[6], o[7]}; }
;                     else { sq += (o[0] * o[0] + o[1] * o[1]) + (o[2] * o[2] + o[3] * o[3]) + (o[4] * o[4] + o[5] * o[5]) + (o[6] * o[6] + o[7] * o[7]);
;                         w[bj].x = cvt_pk_bf16(o[0], o[1]); w[bj].y = cvt_pk_bf16(o[2], o[3]); w[bj].z = cvt_pk_bf16(o[4], o[5]); w[bj].w = cvt_pk_bf16(o[6], o[7]); } }
;                 if (!OUT) { store_pair_lines(O, D, row, fr, col0, w[0], w[1]);
;                     sq += __shfl_xor(sq, 16); sq += __shfl_xor(sq, 32); if (fq == 0) unsafeAtomicAdd(ssout + row, sq); } }
	v_mov_b32_dpp v129, v108 row_ror:8 row_mask:0xf bank_mask:0xf
	v_mov_b32_dpp v130, v109 row_ror:8 row_mask:0xf bank_mask:0xf
	v_mov_b32_dpp v122, v105 row_ror:8 row_mask:0xf bank_mask:0xf
	v_mov_b32_dpp v131, v114 row_ror:8 row_mask:0xf bank_mask:0xf
	v_cndmask_b32_e64 v106, v131, v106, s[6:7]
	v_mov_b32_dpp v123, v110 row_ror:8 row_mask:0xf bank_mask:0xf
	v_cndmask_b32_e64 v102, v123, v102, s[6:7]
	v_lshlrev_b32_e32 v123, 16, v106
	v_mul_f32_e32 v123, v118, v123
	v_cndmask_b32_e64 v110, v110, v119, s[6:7]
	v_lshlrev_b32_e32 v119, 16, v102
	v_and_b32_e32 v106, 0xffff0000, v106
	v_mul_f32_e32 v123, v52, v123
	v_fmac_f32_e32 v119, v92, v123
	v_mul_f32_e32 v92, v118, v106
	v_and_b32_e32 v102, 0xffff0000, v102
	v_mul_f32_e32 v92, v53, v92
	v_fmac_f32_e32 v102, v93, v92
	v_mul_f32_e32 v92, 0xbfb8aa3b, v94
	v_exp_f32_e32 v92, v92
	v_mul_f32_e32 v94, 0xbfb8aa3b, v95
	v_exp_f32_e32 v94, v94
	v_mov_b32_dpp v132, v115 row_ror:8 row_mask:0xf bank_mask:0xf
	v_add_f32_e32 v92, 1.0, v92
	v_mov_b32_dpp v124, v111 row_ror:8 row_mask:0xf bank_mask:0xf
	v_cndmask_b32_e64 v107, v132, v107, s[6:7]
	v_rcp_f32_e32 v92, v92
	v_cndmask_b32_e64 v103, v124, v103, s[6:7]
	v_lshlrev_b32_e32 v124, 16, v107
	v_add_f32_e32 v94, 1.0, v94
	v_mul_f32_e32 v93, v118, v124
	v_rcp_f32_e32 v94, v94
	v_cndmask_b32_e64 v111, v111, v120, s[6:7]
	v_mov_b32_dpp v133, v116 row_ror:8 row_mask:0xf bank_mask:0xf
	v_lshlrev_b32_e32 v120, 16, v103
	v_and_b32_e32 v107, 0xffff0000, v107
	v_mul_f32_e32 v93, v54, v93
	v_mov_b32_dpp v125, v112 row_ror:8 row_mask:0xf bank_mask:0xf
	v_cndmask_b32_e64 v108, v133, v108, s[6:7]
	v_fmac_f32_e32 v120, v92, v93
	v_mul_f32_e32 v92, v118, v107
	v_cndmask_b32_e64 v104, v125, v104, s[6:7]
	v_and_b32_e32 v103, 0xffff0000, v103
	v_lshlrev_b32_e32 v125, 16, v108
	v_mul_f32_e32 v92, v55, v92
	v_fmac_f32_e32 v103, v94, v92
	v_mul_f32_e32 v92, v118, v125
	v_cndmask_b32_e64 v112, v112, v121, s[6:7]
	v_lshlrev_b32_e32 v121, 16, v104
	v_and_b32_e32 v108, 0xffff0000, v108
	v_mul_f32_e32 v92, v48, v92
	v_fmac_f32_e32 v121, v88, v92
	v_mul_f32_e32 v88, v118, v108
	v_and_b32_e32 v104, 0xffff0000, v104
	v_mul_f32_e32 v88, v49, v88
	v_fmac_f32_e32 v104, v89, v88
	v_mul_f32_e32 v88, 0xbfb8aa3b, v90
	v_cndmask_b32_e64 v114, v114, v127, s[6:7]
	v_exp_f32_e32 v88, v88
	v_mul_f32_e32 v90, 0xbfb8aa3b, v91
	v_lshlrev_b32_e32 v107, 16, v114
	v_exp_f32_e32 v90, v90
	v_mul_f32_e32 v107, v118, v107
	v_lshlrev_b32_e32 v93, 16, v110
	v_and_b32_e32 v108, 0xffff0000, v114
	v_mul_f32_e32 v107, v40, v107
	v_mov_b32_dpp v136, v117 row_ror:8 row_mask:0xf bank_mask:0xf
	v_add_f32_e32 v88, 1.0, v88
	v_fmac_f32_e32 v93, v84, v107
	v_mul_f32_e32 v84, v118, v108
	v_mov_b32_dpp v126, v113 row_ror:8 row_mask:0xf bank_mask:0xf
	v_cndmask_b32_e64 v109, v136, v109, s[6:7]
	v_rcp_f32_e32 v88, v88
	v_and_b32_e32 v94, 0xffff0000, v110
	v_mul_f32_e32 v84, v41, v84
	v_cndmask_b32_e64 v105, v126, v105, s[6:7]
	v_lshlrev_b32_e32 v126, 16, v109
	v_add_f32_e32 v90, 1.0, v90
	v_fmac_f32_e32 v94, v85, v84
	v_mul_f32_e32 v84, 0xbfb8aa3b, v86
	v_mul_f32_e32 v89, v118, v126
	v_rcp_f32_e32 v90, v90
	v_exp_f32_e32 v84, v84
	v_cndmask_b32_e64 v113, v113, v122, s[6:7]
	v_lshlrev_b32_e32 v122, 16, v105
	v_and_b32_e32 v109, 0xffff0000, v109
	v_mul_f32_e32 v89, v50, v89
	v_mul_f32_e32 v86, 0xbfb8aa3b, v87
	v_fmac_f32_e32 v122, v88, v89
	v_mul_f32_e32 v88, v118, v109
	v_exp_f32_e32 v86, v86
	v_and_b32_e32 v105, 0xffff0000, v105
	v_mul_f32_e32 v88, v51, v88
	v_fmac_f32_e32 v105, v90, v88
	v_mul_f32_e32 v88, v102, v102
	v_mul_f32_e32 v89, v103, v103
	v_add_f32_e32 v84, 1.0, v84
	v_cndmask_b32_e64 v115, v115, v128, s[6:7]
	v_fmac_f32_e32 v88, v119, v119
	v_fmac_f32_e32 v89, v120, v120
	v_rcp_f32_e32 v84, v84
	v_add_f32_e32 v88, v88, v89
	v_mul_f32_e32 v89, v104, v104
	v_lshlrev_b32_e32 v109, 16, v115
	v_add_f32_e32 v86, 1.0, v86
	v_fmac_f32_e32 v89, v121, v121
	v_mul_f32_e32 v85, v118, v109
	v_rcp_f32_e32 v86, v86
	v_add_f32_e32 v88, v89, v88
	v_mul_f32_e32 v89, v105, v105
	v_lshlrev_b32_e32 v95, 16, v111
	v_and_b32_e32 v110, 0xffff0000, v115
	v_mul_f32_e32 v85, v42, v85
	v_cndmask_b32_e64 v116, v116, v129, s[6:7]
	v_fmac_f32_e32 v89, v122, v122
	v_fmac_f32_e32 v95, v84, v85
	v_mul_f32_e32 v84, v118, v110
	v_add_f32_e32 v88, v89, v88
	v_cvt_pk_bf16_f32 v89, v119, v102
	v_and_b32_e32 v102, 0xffff0000, v111
	v_lshlrev_b32_e32 v111, 16, v116
	v_mul_f32_e32 v84, v43, v84
	v_fmac_f32_e32 v102, v86, v84
	v_mul_f32_e32 v84, v118, v111
	v_cvt_pk_bf16_f32 v90, v120, v103
	v_cvt_pk_bf16_f32 v91, v121, v104
	v_lshlrev_b32_e32 v103, 16, v112
	v_and_b32_e32 v104, 0xffff0000, v112
	v_and_b32_e32 v112, 0xffff0000, v116
	v_mul_f32_e32 v84, v32, v84
	v_fmac_f32_e32 v103, v80, v84
	v_mul_f32_e32 v80, v118, v112
	v_mul_f32_e32 v80, v33, v80
	v_fmac_f32_e32 v104, v81, v80
	v_mul_f32_e32 v80, 0xbfb8aa3b, v82
	v_exp_f32_e32 v80, v80
	v_mul_f32_e32 v82, 0xbfb8aa3b, v83
	v_exp_f32_e32 v82, v82
	v_cndmask_b32_e64 v117, v117, v130, s[6:7]
	v_add_f32_e32 v80, 1.0, v80
	v_rcp_f32_e32 v80, v80
	v_cvt_pk_bf16_f32 v92, v122, v105
	v_lshlrev_b32_e32 v105, 16, v113
	v_and_b32_e32 v106, 0xffff0000, v113
	v_lshlrev_b32_e32 v113, 16, v117
	v_add_f32_e32 v82, 1.0, v82
	v_mul_f32_e32 v81, v118, v113
	v_rcp_f32_e32 v82, v82
	v_and_b32_e32 v114, 0xffff0000, v117
	v_mul_f32_e32 v81, v34, v81
	v_fmac_f32_e32 v105, v80, v81
	v_mul_f32_e32 v80, v118, v114
	v_mul_f32_e32 v80, v35, v80
	v_fmac_f32_e32 v106, v82, v80
	v_mul_f32_e32 v80, v94, v94
	v_mul_f32_e32 v81, v102, v102
	v_fmac_f32_e32 v80, v93, v93
	v_fmac_f32_e32 v81, v95, v95
	v_add_f32_e32 v80, v80, v81
	v_mul_f32_e32 v81, v104, v104
	v_fmac_f32_e32 v81, v103, v103
	v_add_f32_e32 v80, v81, v80
	v_mul_f32_e32 v81, v106, v106
	v_fmac_f32_e32 v81, v105, v105
	v_add_f32_e32 v80, v81, v80
	v_add_f32_e32 v107, v80, v88
	v_cvt_pk_bf16_f32 v80, v93, v94
	v_cvt_pk_bf16_f32 v81, v95, v102
	v_cvt_pk_bf16_f32 v88, v103, v104
	v_cvt_pk_bf16_f32 v93, v105, v106
	v_mov_b32_e32 v95, 0
	v_mov_b32_e32 v86, 0
	v_mov_b32_dpp v85, v93 row_ror:8 row_mask:0xf bank_mask:0xf
	v_mov_b32_dpp v95, v92 row_ror:8 row_mask:0xf bank_mask:0xf
	v_cndmask_b32_e64 v85, v85, v92, s[6:7]
	ds_bpermute_b32 v92, v134, v107
	v_mov_b32_dpp v86, v89 row_ror:8 row_mask:0xf bank_mask:0xf
	v_mov_b32_dpp v87, v90 row_ror:8 row_mask:0xf bank_mask:0xf
	v_mov_b32_dpp v82, v80 row_ror:8 row_mask:0xf bank_mask:0xf
	v_mov_b32_dpp v83, v81 row_ror:8 row_mask:0xf bank_mask:0xf
	v_mov_b32_dpp v84, v88 row_ror:8 row_mask:0xf bank_mask:0xf
	v_cndmask_b32_e64 v86, v80, v86, s[6:7]
	v_cndmask_b32_e64 v87, v81, v87, s[6:7]
	v_lshl_add_u64 v[80:81], s[36:37], 0, v[98:99]
	v_mov_b32_dpp v94, v91 row_ror:8 row_mask:0xf bank_mask:0xf
	v_cndmask_b32_e64 v83, v83, v90, s[6:7]
	v_cndmask_b32_e64 v84, v84, v91, s[6:7]
	v_lshl_add_u64 v[90:91], v[80:81], 0, v[162:163]
	s_waitcnt lgkmcnt(0)
; __device__ __forceinline__ void store_pair_lines(bf16_t* O, int ldc, int row, int fr, int col0, u32x4 wA, u32x4 wB) {
;     const u32x4 sA = {dpp_ror8(wA.x), dpp_ror8(wA.y), dpp_ror8(wA.z), dpp_ror8(wA.w)}, sB = {dpp_ror8(wB.x), dpp_ror8(wB.y), dpp_ror8(wB.z), dpp_ror8(wB.w)};
;     const bool lo = fr < 8;
;     const u32x4 o1 = lo ? wA : sB, o2 = lo ? sA : wB;
;     const int r1 = row - fr + (fr & 7), cb = col0 + (lo ? 0 : 8);
;     *(u32x4*)(O + (size_t)r1 * ldc + cb) = o1;
;     __device__ __forceinline__ void operator()(const f32x4 (&acc)[2][2][4][2], const Unit& u, int wr, int wc, int fr, int fq) const {
;     ...
;             for (int m = 0; m < 4; ++m) { const int row = row0 + ai * HALF + m * 16; const size_t off = (size_t)row * D + col0; const float ri = __builtin_amdgcn_rsqf(sse[row] * (1.f / D) + EPS); float sq = 0.f; u32x4 w[2];
;                 u32x4 rr[2], ee[2]; load_pair_lines(R, D, row, fr, col0, rr[0], rr[1]); load_pair_lines(E, D, row, fr, col0, ee[0], ee[1]);
; #pragma unroll
;                 for (int bj = 0; bj < 2; ++bj) { const u32x4 rw = rr[bj], ew = ee[bj];
;                     const float r[8] = {bflo(rw.x), bfhi(rw.x), bflo(rw.y), bfhi(rw.y), bflo(rw.z), bfhi(rw.z), bflo(rw.w), bfhi(rw.w)};
;                     const float e[8] = {bflo(ew.x), bfhi(ew.x), bflo(ew.y), bfhi(ew.y), bflo(ew.z), bfhi(ew.z), bflo(ew.w), bfhi(ew.w)};
;                     float o[8];
; #pragma unroll
;                     for (int j = 0; j < 8; ++j) { const float a = acc[ai][bj][m][j >> 2][j & 3]; const float gg = gv[bj][j >> 2][j & 3];
;                         o[j] = r[j] + e[j] * ri * gg * __builtin_amdgcn_rcpf(1.f + __builtin_amdgcn_exp2f(-a * LOG2E)); }
;                     if (OUT) { *(f32x4*)(OUT + off + 8 * bj) = (f32x4){o[0], o[1], o[2], o[3]}; *(f32x4*)(OUT + off + 8 * bj + 4) = (f32x4){o[4], o[5], o[6], o[7]}; }
;                     else { sq += (o[0] * o[0] + o[1] * o[1]) + (o[2] * o[2] + o[3] * o[3]) + (o[4] * o[4] + o[5] * o[5]) + (o[6] * o[6] + o[7] * o[7]);
;                         w[bj].x = cvt_pk_bf16(o[0], o[1]); w[bj].y = cvt_pk_bf16(o[2], o[3]); w[bj].z = cvt_pk_bf16(o[4], o[5]); w[bj].w = cvt_pk_bf16(o[6], o[7]); } }
;                 if (!OUT) { store_pair_lines(O, D, row, fr, col0, w[0], w[1]);
;                     sq += __shfl_xor(sq, 16); sq += __shfl_xor(sq, 32); if (fq == 0) unsafeAtomicAdd(ssout + row, sq); } }
	v_add_f32_e32 v80, v107, v92
	ds_bpermute_b32 v81, v135, v80
	v_cndmask_b32_e64 v82, v82, v89, s[6:7]
	global_store_dwordx4 v[90:91], v[82:85], off
	v_cndmask_b32_e64 v88, v88, v94, s[6:7]
	v_cndmask_b32_e64 v89, v93, v95, s[6:7]
	v_lshl_add_u64 v[82:83], s[36:37], 0, v[100:101]
	v_lshl_add_u64 v[82:83], v[82:83], 0, v[162:163]
	global_store_dwordx4 v[82:83], v[86:89], off
	s_and_saveexec_b64 s[56:57], s[8:9]
	s_cbranch_execz .LBB0_891
	v_lshl_add_u64 v[82:83], v[96:97], 2, s[18:19]
	s_waitcnt lgkmcnt(0)
	v_add_f32_e32 v80, v80, v81
	global_atomic_add_f32 v[82:83], v80, off
.LBB0_891:
	s_or_b64 exec, exec, s[56:57]
	v_add_u32_e32 v80, 0x80, v164
	v_sub_u32_e32 v82, v80, v172
	v_add_u32_e32 v82, v82, v174
	v_ashrrev_i32_e32 v83, 31, v82
	v_lshlrev_b64 v[82:83], 12, v[82:83]
	v_lshl_add_u64 v[84:85], s[16:17], 0, v[82:83]
	v_lshl_add_u64 v[84:85], v[84:85], 0, v[162:163]
	s_waitcnt vmcnt(2)
	s_nop 0
	v_mov_b64_e32 v[86:87], v[228:229]
	v_mov_b64_e32 v[88:89], v[230:231]
	v_lshl_add_u64 v[84:85], s[38:39], 0, v[82:83]
	v_lshl_add_u64 v[84:85], v[84:85], 0, v[162:163]
	s_waitcnt lgkmcnt(0)
	v_mov_b32_e32 v81, v226
	v_mov_b64_e32 v[90:91], v[232:233]
	v_mov_b64_e32 v[92:93], v[234:235]
	v_lshl_add_u64 v[84:85], v[82:83], 0, s[44:45]
	v_lshl_add_u64 v[98:99], s[38:39], 0, v[84:85]
	v_lshl_add_u64 v[94:95], s[16:17], 0, v[84:85]
	v_lshl_add_u64 v[98:99], v[98:99], 0, v[162:163]
	v_lshl_add_u64 v[94:95], v[94:95], 0, v[162:163]
	v_mov_b64_e32 v[98:99], v[236:237]
	v_mov_b64_e32 v[100:101], v[238:239]
	v_mul_f32_e32 v76, 0xbfb8aa3b, v76
	v_mov_b64_e32 v[94:95], v[240:241]
	v_mov_b64_e32 v[96:97], v[242:243]
	s_nop 1
	v_add_u32_e32 v216, 0x90, v164
	v_sub_u32_e32 v218, v216, v172
	v_add_u32_e32 v218, v218, v174
	v_ashrrev_i32_e32 v219, 31, v218
	v_lshlrev_b64 v[218:219], 12, v[218:219]
	v_lshl_add_u64 v[220:221], s[16:17], 0, v[218:219]
	v_lshl_add_u64 v[220:221], v[220:221], 0, v[162:163]
	global_load_dwordx4 v[228:231], v[220:221], off
	v_lshl_add_u64 v[220:221], s[38:39], 0, v[218:219]
	v_lshl_add_u64 v[220:221], v[220:221], 0, v[162:163]
	global_load_dword v226, v[166:167], off offset:576
	global_load_dwordx4 v[232:235], v[220:221], off
	v_lshl_add_u64 v[220:221], v[218:219], 0, s[44:45]
	v_lshl_add_u64 v[224:225], s[38:39], 0, v[220:221]
	v_lshl_add_u64 v[222:223], s[16:17], 0, v[220:221]
	v_lshl_add_u64 v[224:225], v[224:225], 0, v[162:163]
	v_lshl_add_u64 v[222:223], v[222:223], 0, v[162:163]
	global_load_dwordx4 v[236:239], v[224:225], off
	global_load_dwordx4 v[240:243], v[222:223], off
	v_exp_f32_e32 v76, v76
	v_mul_f32_e32 v77, 0xbfb8aa3b, v77
	v_exp_f32_e32 v77, v77
	v_add_f32_e32 v76, 1.0, v76
	v_rcp_f32_e32 v76, v76
	v_add_f32_e32 v77, 1.0, v77
	v_rcp_f32_e32 v77, v77
	v_mul_f32_e32 v72, 0xbfb8aa3b, v72
	v_exp_f32_e32 v72, v72
	v_mul_f32_e32 v73, 0xbfb8aa3b, v73
	v_exp_f32_e32 v73, v73
	v_add_f32_e32 v72, 1.0, v72
	v_rcp_f32_e32 v72, v72
	v_add_f32_e32 v73, 1.0, v73
	v_mul_f32_e32 v68, 0xbfb8aa3b, v68
	v_rcp_f32_e32 v73, v73
	v_exp_f32_e32 v68, v68
	v_mul_f32_e32 v69, 0xbfb8aa3b, v69
	v_exp_f32_e32 v69, v69
	v_add_f32_e32 v68, 1.0, v68
	v_rcp_f32_e32 v68, v68
	v_add_f32_e32 v69, 1.0, v69
	v_rcp_f32_e32 v69, v69
	v_mul_f32_e32 v64, 0xbfb8aa3b, v64
	v_exp_f32_e32 v64, v64
	v_mul_f32_e32 v65, 0xbfb8aa3b, v65
	v_exp_f32_e32 v65, v65
	v_add_f32_e32 v64, 1.0, v64
	v_rcp_f32_e32 v64, v64
	v_add_f32_e32 v65, 1.0, v65
	v_rcp_f32_e32 v65, v65
	v_mov_b32_dpp v102, v86 row_ror:8 row_mask:0xf bank_mask:0xf
	v_mov_b32_dpp v103, v87 row_ror:8 row_mask:0xf bank_mask:0xf
	v_mov_b32_dpp v104, v88 row_ror:8 row_mask:0xf bank_mask:0xf
	v_fmamk_f32 v81, v81, 0x3a000000, v180
	v_rsq_f32_e32 v81, v81
	v_mov_b32_dpp v110, v90 row_ror:8 row_mask:0xf bank_mask:0xf
	v_mov_b32_dpp v111, v91 row_ror:8 row_mask:0xf bank_mask:0xf
	v_mov_b32_dpp v112, v92 row_ror:8 row_mask:0xf bank_mask:0xf
	v_mov_b32_dpp v113, v93 row_ror:8 row_mask:0xf bank_mask:0xf
	v_mov_b32_dpp v105, v89 row_ror:8 row_mask:0xf bank_mask:0xf
	v_mov_b32_dpp v114, v98 row_ror:8 row_mask:0xf bank_mask:0xf
	v_cndmask_b32_e64 v90, v114, v90, s[6:7]
	v_mov_b32_dpp v106, v94 row_ror:8 row_mask:0xf bank_mask:0xf
	v_cndmask_b32_e64 v86, v106, v86, s[6:7]
	v_lshlrev_b32_e32 v106, 16, v90
	v_mul_f32_e32 v106, v81, v106
	v_cndmask_b32_e64 v94, v94, v102, s[6:7]
	v_lshlrev_b32_e32 v102, 16, v86
	v_and_b32_e32 v90, 0xffff0000, v90
	v_mul_f32_e32 v106, v52, v106
	v_fmac_f32_e32 v102, v76, v106
	v_mul_f32_e32 v76, v81, v90
	v_and_b32_e32 v86, 0xffff0000, v86
	v_mul_f32_e32 v76, v53, v76
	v_fmac_f32_e32 v86, v77, v76
	v_mul_f32_e32 v76, 0xbfb8aa3b, v78
	v_exp_f32_e32 v76, v76
	v_mul_f32_e32 v78, 0xbfb8aa3b, v79
	v_exp_f32_e32 v78, v78
	v_mov_b32_dpp v115, v99 row_ror:8 row_mask:0xf bank_mask:0xf
	v_add_f32_e32 v76, 1.0, v76
	v_mov_b32_dpp v107, v95 row_ror:8 row_mask:0xf bank_mask:0xf
	v_cndmask_b32_e64 v91, v115, v91, s[6:7]
	v_rcp_f32_e32 v76, v76
	v_cndmask_b32_e64 v87, v107, v87, s[6:7]
	v_lshlrev_b32_e32 v107, 16, v91
	v_add_f32_e32 v78, 1.0, v78
	v_mul_f32_e32 v77, v81, v107
	v_rcp_f32_e32 v78, v78
	v_cndmask_b32_e64 v95, v95, v103, s[6:7]
	v_mov_b32_dpp v116, v100 row_ror:8 row_mask:0xf bank_mask:0xf
	v_lshlrev_b32_e32 v103, 16, v87
	v_and_b32_e32 v91, 0xffff0000, v91
	v_mul_f32_e32 v77, v54, v77
	v_mov_b32_dpp v108, v96 row_ror:8 row_mask:0xf bank_mask:0xf
	v_cndmask_b32_e64 v92, v116, v92, s[6:7]
	v_fmac_f32_e32 v103, v76, v77
	v_mul_f32_e32 v76, v81, v91
	v_cndmask_b32_e64 v88, v108, v88, s[6:7]
	v_and_b32_e32 v87, 0xffff0000, v87
	v_lshlrev_b32_e32 v108, 16, v92
	v_mul_f32_e32 v76, v55, v76
	v_fmac_f32_e32 v87, v78, v76
	v_mul_f32_e32 v76, v81, v108
	v_cndmask_b32_e64 v96, v96, v104, s[6:7]
; __device__ __forceinline__ void store_pair_lines(bf16_t* O, int ldc, int row, int fr, int col0, u32x4 wA, u32x4 wB) {
;     const u32x4 sA = {dpp_ror8(wA.x), dpp_ror8(wA.y), dpp_ror8(wA.z), dpp_ror8(wA.w)}, sB = {dpp_ror8(wB.x), dpp_ror8(wB.y), dpp_ror8(wB.z), dpp_ror8(wB.w)};
;     const bool lo = fr < 8;
;     const u32x4 o1 = lo ? wA : sB, o2 = lo ? sA : wB;
;     const int r1 = row - fr + (fr & 7), cb = col0 + (lo ? 0 : 8);
;     *(u32x4*)(O + (size_t)r1 * ldc + cb) = o1;
;     __device__ __forceinline__ void operator()(const f32x4 (&acc)[2][2][4][2], const Unit& u, int wr, int wc, int fr, int fq) const {
;     ...
;             for (int m = 0; m < 4; ++m) { const int row = row0 + ai * HALF + m * 16; const size_t off = (size_t)row * D + col0; const float ri = __builtin_amdgcn_rsqf(sse[row] * (1.f / D) + EPS); float sq = 0.f; u32x4 w[2];
;                 u32x4 rr[2], ee[2]; load_pair_lines(R, D, row, fr, col0, rr[0], rr[1]); load_pair_lines(E, D, row, fr, col0, ee[0], ee[1]);
; #pragma unroll
;                 for (int bj = 0; bj < 2; ++bj) { const u32x4 rw = rr[bj], ew = ee[bj];
;                     const float r[8] = {bflo(rw.x), bfhi(rw.x), bflo(rw.y), bfhi(rw.y), bflo(rw.z), bfhi(rw.z), bflo(rw.w), bfhi(rw.w)};
;                     const float e[8] = {bflo(ew.x), bfhi(ew.x), bflo(ew.y), bfhi(ew.y), bflo(ew.z), bfhi(ew.z), bflo(ew.w), bfhi(ew.w)};
;                     float o[8];
; #pragma unroll
;                     for (int j = 0; j < 8; ++j) { const float a = acc[ai][bj][m][j >> 2][j & 3]; const float gg = gv[bj][j >> 2][j & 3];
;                         o[j] = r[j] + e[j] * ri * gg * __builtin_amdgcn_rcpf(1.f + __builtin_amdgcn_exp2f(-a * LOG2E)); }
;                     if (OUT) { *(f32x4*)(OUT + off + 8 * bj) = (f32x4){o[0], o[1], o[2], o[3]}; *(f32x4*)(OUT + off + 8 * bj + 4) = (f32x4){o[4], o[5], o[6], o[7]}; }
;                     else { sq += (o[0] * o[0] + o[1] * o[1]) + (o[2] * o[2] + o[3] * o[3]) + (o[4] * o[4] + o[5] * o[5]) + (o[6] * o[6] + o[7] * o[7]);
;                         w[bj].x = cvt_pk_bf16(o[0], o[1]); w[bj].y = cvt_pk_bf16(o[2], o[3]); w[bj].z = cvt_pk_bf16(o[4], o[5]); w[bj].w = cvt_pk_bf16(o[6], o[7]); } }
;                 if (!OUT) { store_pair_lines(O, D, row, fr, col0, w[0], w[1]);
;                     sq += __shfl_xor(sq, 16); sq += __shfl_xor(sq, 32); if (fq == 0) unsafeAtomicAdd(ssout + row, sq); } }
	v_lshlrev_b32_e32 v104, 16, v88
	v_and_b32_e32 v92, 0xffff0000, v92
	v_mul_f32_e32 v76, v48, v76
	v_fmac_f32_e32 v104, v72, v76
	v_mul_f32_e32 v72, v81, v92
	v_and_b32_e32 v88, 0xffff0000, v88
	v_mul_f32_e32 v72, v49, v72
	v_fmac_f32_e32 v88, v73, v72
	v_mul_f32_e32 v72, 0xbfb8aa3b, v74
	v_cndmask_b32_e64 v98, v98, v110, s[6:7]
	v_exp_f32_e32 v72, v72
	v_mul_f32_e32 v74, 0xbfb8aa3b, v75
	v_lshlrev_b32_e32 v91, 16, v98
	v_exp_f32_e32 v74, v74
	v_mul_f32_e32 v91, v81, v91
	v_lshlrev_b32_e32 v77, 16, v94
	v_and_b32_e32 v92, 0xffff0000, v98
	v_mul_f32_e32 v91, v40, v91
	v_mov_b32_dpp v117, v101 row_ror:8 row_mask:0xf bank_mask:0xf
	v_add_f32_e32 v72, 1.0, v72
	v_fmac_f32_e32 v77, v68, v91
	v_mul_f32_e32 v68, v81, v92
	v_mov_b32_dpp v109, v97 row_ror:8 row_mask:0xf bank_mask:0xf
	v_cndmask_b32_e64 v93, v117, v93, s[6:7]
	v_rcp_f32_e32 v72, v72
	v_and_b32_e32 v78, 0xffff0000, v94
	v_mul_f32_e32 v68, v41, v68
	v_cndmask_b32_e64 v89, v109, v89, s[6:7]
	v_lshlrev_b32_e32 v109, 16, v93
	v_add_f32_e32 v74, 1.0, v74
	v_fmac_f32_e32 v78, v69, v68
	v_mul_f32_e32 v68, 0xbfb8aa3b, v70
	v_mul_f32_e32 v73, v81, v109
	v_rcp_f32_e32 v74, v74
	v_exp_f32_e32 v68, v68
	v_cndmask_b32_e64 v97, v97, v105, s[6:7]
	v_lshlrev_b32_e32 v105, 16, v89
	v_and_b32_e32 v93, 0xffff0000, v93
	v_mul_f32_e32 v73, v50, v73
	v_mul_f32_e32 v70, 0xbfb8aa3b, v71
	v_fmac_f32_e32 v105, v72, v73
	v_mul_f32_e32 v72, v81, v93
	v_exp_f32_e32 v70, v70
	v_and_b32_e32 v89, 0xffff0000, v89
	v_mul_f32_e32 v72, v51, v72
	v_fmac_f32_e32 v89, v74, v72
	v_mul_f32_e32 v72, v86, v86
	v_mul_f32_e32 v73, v87, v87
	v_add_f32_e32 v68, 1.0, v68
	v_cndmask_b32_e64 v99, v99, v111, s[6:7]
	v_fmac_f32_e32 v72, v102, v102
	v_fmac_f32_e32 v73, v103, v103
	v_rcp_f32_e32 v68, v68
	v_add_f32_e32 v72, v72, v73
	v_mul_f32_e32 v73, v88, v88
	v_lshlrev_b32_e32 v93, 16, v99
	v_add_f32_e32 v70, 1.0, v70
	v_fmac_f32_e32 v73, v104, v104
	v_mul_f32_e32 v69, v81, v93
	v_rcp_f32_e32 v70, v70
	v_add_f32_e32 v72, v73, v72
	v_mul_f32_e32 v73, v89, v89
	v_lshlrev_b32_e32 v79, 16, v95
	v_and_b32_e32 v94, 0xffff0000, v99
	v_mul_f32_e32 v69, v42, v69
	v_cndmask_b32_e64 v100, v100, v112, s[6:7]
	v_fmac_f32_e32 v73, v105, v105
	v_fmac_f32_e32 v79, v68, v69
	v_mul_f32_e32 v68, v81, v94
	v_add_f32_e32 v72, v73, v72
	v_cvt_pk_bf16_f32 v73, v102, v86
	v_and_b32_e32 v86, 0xffff0000, v95
	v_lshlrev_b32_e32 v95, 16, v100
	v_mul_f32_e32 v68, v43, v68
	v_fmac_f32_e32 v86, v70, v68
	v_mul_f32_e32 v68, v81, v95
	v_cvt_pk_bf16_f32 v74, v103, v87
	v_cvt_pk_bf16_f32 v75, v104, v88
	v_lshlrev_b32_e32 v87, 16, v96
	v_and_b32_e32 v88, 0xffff0000, v96
	v_and_b32_e32 v96, 0xffff0000, v100
	v_mul_f32_e32 v68, v32, v68
	v_fmac_f32_e32 v87, v64, v68
	v_mul_f32_e32 v64, v81, v96
	v_mul_f32_e32 v64, v33, v64
	v_fmac_f32_e32 v88, v65, v64
	v_mul_f32_e32 v64, 0xbfb8aa3b, v66
	v_exp_f32_e32 v64, v64
	v_mul_f32_e32 v66, 0xbfb8aa3b, v67
	v_exp_f32_e32 v66, v66
	v_cndmask_b32_e64 v101, v101, v113, s[6:7]
	v_add_f32_e32 v64, 1.0, v64
	v_rcp_f32_e32 v64, v64
	v_cvt_pk_bf16_f32 v76, v105, v89
	v_lshlrev_b32_e32 v89, 16, v97
	v_and_b32_e32 v90, 0xffff0000, v97
	v_lshlrev_b32_e32 v97, 16, v101
	v_add_f32_e32 v66, 1.0, v66
	v_mul_f32_e32 v65, v81, v97
	v_rcp_f32_e32 v66, v66
	v_and_b32_e32 v98, 0xffff0000, v101
	v_mul_f32_e32 v65, v34, v65
	v_fmac_f32_e32 v89, v64, v65
	v_mul_f32_e32 v64, v81, v98
	v_mul_f32_e32 v64, v35, v64
	v_fmac_f32_e32 v90, v66, v64
	v_mul_f32_e32 v64, v78, v78
	v_mul_f32_e32 v65, v86, v86
	v_fmac_f32_e32 v64, v77, v77
	v_fmac_f32_e32 v65, v79, v79
	v_add_f32_e32 v64, v64, v65
	v_mul_f32_e32 v65, v88, v88
	v_fmac_f32_e32 v65, v87, v87
	v_add_f32_e32 v64, v65, v64
	v_mul_f32_e32 v65, v90, v90
	v_fmac_f32_e32 v65, v89, v89
	v_add_f32_e32 v64, v65, v64
	v_add_f32_e32 v81, v64, v72
	v_cvt_pk_bf16_f32 v64, v77, v78
	v_cvt_pk_bf16_f32 v65, v79, v86
	v_cvt_pk_bf16_f32 v72, v87, v88
	v_cvt_pk_bf16_f32 v77, v89, v90
	v_mov_b32_e32 v79, 0
	v_mov_b32_e32 v70, 0
	v_mov_b32_dpp v69, v77 row_ror:8 row_mask:0xf bank_mask:0xf
	v_mov_b32_dpp v79, v76 row_ror:8 row_mask:0xf bank_mask:0xf
	v_cndmask_b32_e64 v69, v69, v76, s[6:7]
	ds_bpermute_b32 v76, v134, v81
	v_mov_b32_dpp v70, v73 row_ror:8 row_mask:0xf bank_mask:0xf
	v_mov_b32_dpp v71, v74 row_ror:8 row_mask:0xf bank_mask:0xf
	v_mov_b32_dpp v66, v64 row_ror:8 row_mask:0xf bank_mask:0xf
	v_mov_b32_dpp v67, v65 row_ror:8 row_mask:0xf bank_mask:0xf
	v_mov_b32_dpp v68, v72 row_ror:8 row_mask:0xf bank_mask:0xf
	v_cndmask_b32_e64 v70, v64, v70, s[6:7]
	v_cndmask_b32_e64 v71, v65, v71, s[6:7]
	v_lshl_add_u64 v[64:65], s[36:37], 0, v[82:83]
	v_mov_b32_dpp v78, v75 row_ror:8 row_mask:0xf bank_mask:0xf
	v_cndmask_b32_e64 v67, v67, v74, s[6:7]
	v_cndmask_b32_e64 v68, v68, v75, s[6:7]
	v_lshl_add_u64 v[74:75], v[64:65], 0, v[162:163]
	s_waitcnt lgkmcnt(0)
	v_add_f32_e32 v64, v81, v76
	ds_bpermute_b32 v65, v135, v64
	v_cndmask_b32_e64 v66, v66, v73, s[6:7]
	global_store_dwordx4 v[74:75], v[66:69], off
	v_cndmask_b32_e64 v72, v72, v78, s[6:7]
	v_cndmask_b32_e64 v73, v77, v79, s[6:7]
	v_lshl_add_u64 v[66:67], s[36:37], 0, v[84:85]
	v_lshl_add_u64 v[66:67], v[66:67], 0, v[162:163]
	global_store_dwordx4 v[66:67], v[70:73], off
	s_and_saveexec_b64 s[56:57], s[8:9]
	s_cbranch_execz .LBB0_893
	v_ashrrev_i32_e32 v81, 31, v80
	v_lshl_add_u64 v[66:67], v[80:81], 2, s[18:19]
	s_waitcnt lgkmcnt(0)
	v_add_f32_e32 v64, v64, v65
	global_atomic_add_f32 v[66:67], v64, off
; __device__ __forceinline__ void store_pair_lines(bf16_t* O, int ldc, int row, int fr, int col0, u32x4 wA, u32x4 wB) {
;     const u32x4 sA = {dpp_ror8(wA.x), dpp_ror8(wA.y), dpp_ror8(wA.z), dpp_ror8(wA.w)}, sB = {dpp_ror8(wB.x), dpp_ror8(wB.y), dpp_ror8(wB.z), dpp_ror8(wB.w)};
;     const bool lo = fr < 8;
;     const u32x4 o1 = lo ? wA : sB, o2 = lo ? sA : wB;
;     const int r1 = row - fr + (fr & 7), cb = col0 + (lo ? 0 : 8);
;     *(u32x4*)(O + (size_t)r1 * ldc + cb) = o1;
;     __device__ __forceinline__ void operator()(const f32x4 (&acc)[2][2][4][2], const Unit& u, int wr, int wc, int fr, int fq) const {
;     ...
;             for (int m = 0; m < 4; ++m) { const int row = row0 + ai * HALF + m * 16; const size_t off = (size_t)row * D + col0; const float ri = __builtin_amdgcn_rsqf(sse[row] * (1.f / D) + EPS); float sq = 0.f; u32x4 w[2];
;                 u32x4 rr[2], ee[2]; load_pair_lines(R, D, row, fr, col0, rr[0], rr[1]); load_pair_lines(E, D, row, fr, col0, ee[0], ee[1]);
; #pragma unroll
;                 for (int bj = 0; bj < 2; ++bj) { const u32x4 rw = rr[bj], ew = ee[bj];
;                     const float r[8] = {bflo(rw.x), bfhi(rw.x), bflo(rw.y), bfhi(rw.y), bflo(rw.z), bfhi(rw.z), bflo(rw.w), bfhi(rw.w)};
;                     const float e[8] = {bflo(ew.x), bfhi(ew.x), bflo(ew.y), bfhi(ew.y), bflo(ew.z), bfhi(ew.z), bflo(ew.w), bfhi(ew.w)};
;                     float o[8];
; #pragma unroll
;                     for (int j = 0; j < 8; ++j) { const float a = acc[ai][bj][m][j >> 2][j & 3]; const float gg = gv[bj][j >> 2][j & 3];
;                         o[j] = r[j] + e[j] * ri * gg * __builtin_amdgcn_rcpf(1.f + __builtin_amdgcn_exp2f(-a * LOG2E)); }
;                     if (OUT) { *(f32x4*)(OUT + off + 8 * bj) = (f32x4){o[0], o[1], o[2], o[3]}; *(f32x4*)(OUT + off + 8 * bj + 4) = (f32x4){o[4], o[5], o[6], o[7]}; }
;                     else { sq += (o[0] * o[0] + o[1] * o[1]) + (o[2] * o[2] + o[3] * o[3]) + (o[4] * o[4] + o[5] * o[5]) + (o[6] * o[6] + o[7] * o[7]);
;                         w[bj].x = cvt_pk_bf16(o[0], o[1]); w[bj].y = cvt_pk_bf16(o[2], o[3]); w[bj].z = cvt_pk_bf16(o[4], o[5]); w[bj].w = cvt_pk_bf16(o[6], o[7]); } }
;                 if (!OUT) { store_pair_lines(O, D, row, fr, col0, w[0], w[1]);
;                     sq += __shfl_xor(sq, 16); sq += __shfl_xor(sq, 32); if (fq == 0) unsafeAtomicAdd(ssout + row, sq); } }
.LBB0_893:
	s_or_b64 exec, exec, s[56:57]
	v_add_u32_e32 v64, 0x90, v164
	v_sub_u32_e32 v66, v64, v172
	v_add_u32_e32 v66, v66, v174
	v_ashrrev_i32_e32 v67, 31, v66
	v_lshlrev_b64 v[66:67], 12, v[66:67]
	v_lshl_add_u64 v[68:69], s[16:17], 0, v[66:67]
	v_lshl_add_u64 v[68:69], v[68:69], 0, v[162:163]
	s_waitcnt vmcnt(2)
	s_nop 0
	v_mov_b64_e32 v[70:71], v[228:229]
	v_mov_b64_e32 v[72:73], v[230:231]
	v_lshl_add_u64 v[68:69], s[38:39], 0, v[66:67]
	v_lshl_add_u64 v[68:69], v[68:69], 0, v[162:163]
	s_waitcnt lgkmcnt(0)
	v_mov_b32_e32 v65, v226
	v_mov_b64_e32 v[74:75], v[232:233]
	v_mov_b64_e32 v[76:77], v[234:235]
	v_lshl_add_u64 v[68:69], v[66:67], 0, s[44:45]
	v_lshl_add_u64 v[82:83], s[38:39], 0, v[68:69]
	v_lshl_add_u64 v[78:79], s[16:17], 0, v[68:69]
	v_lshl_add_u64 v[82:83], v[82:83], 0, v[162:163]
	v_lshl_add_u64 v[78:79], v[78:79], 0, v[162:163]
	v_mov_b64_e32 v[82:83], v[236:237]
	v_mov_b64_e32 v[84:85], v[238:239]
	v_mul_f32_e32 v60, 0xbfb8aa3b, v60
	v_mov_b64_e32 v[78:79], v[240:241]
	v_mov_b64_e32 v[80:81], v[242:243]
	s_nop 1
	v_add_u32_e32 v216, 0xa0, v164
	v_sub_u32_e32 v218, v216, v172
	v_add_u32_e32 v218, v218, v174
	v_ashrrev_i32_e32 v219, 31, v218
	v_lshlrev_b64 v[218:219], 12, v[218:219]
	v_lshl_add_u64 v[220:221], s[16:17], 0, v[218:219]
	v_lshl_add_u64 v[220:221], v[220:221], 0, v[162:163]
	global_load_dwordx4 v[228:231], v[220:221], off
	v_lshl_add_u64 v[220:221], s[38:39], 0, v[218:219]
	v_lshl_add_u64 v[220:221], v[220:221], 0, v[162:163]
	global_load_dword v226, v[166:167], off offset:640
	global_load_dwordx4 v[232:235], v[220:221], off
	v_lshl_add_u64 v[220:221], v[218:219], 0, s[44:45]
	v_lshl_add_u64 v[222:223], s[16:17], 0, v[220:221]
	v_lshl_add_u64 v[222:223], v[222:223], 0, v[162:163]
	global_load_dwordx4 v[236:239], v[222:223], off
	v_lshl_add_u64 v[222:223], s[38:39], 0, v[220:221]
	v_lshl_add_u64 v[222:223], v[222:223], 0, v[162:163]
	global_load_dwordx4 v[240:243], v[222:223], off
	v_exp_f32_e32 v60, v60
	v_mul_f32_e32 v61, 0xbfb8aa3b, v61
	v_exp_f32_e32 v61, v61
	v_add_f32_e32 v60, 1.0, v60
	v_rcp_f32_e32 v60, v60
	v_add_f32_e32 v61, 1.0, v61
	v_rcp_f32_e32 v61, v61
	v_mul_f32_e32 v56, 0xbfb8aa3b, v56
	v_exp_f32_e32 v56, v56
	v_mul_f32_e32 v57, 0xbfb8aa3b, v57
	v_exp_f32_e32 v57, v57
	v_add_f32_e32 v56, 1.0, v56
	v_rcp_f32_e32 v56, v56
	v_add_f32_e32 v57, 1.0, v57
	v_mul_f32_e32 v44, 0xbfb8aa3b, v44
	v_rcp_f32_e32 v57, v57
	v_exp_f32_e32 v44, v44
	v_mul_f32_e32 v45, 0xbfb8aa3b, v45
	v_exp_f32_e32 v45, v45
	v_add_f32_e32 v44, 1.0, v44
	v_rcp_f32_e32 v44, v44
	v_add_f32_e32 v45, 1.0, v45
	v_rcp_f32_e32 v45, v45
	v_mul_f32_e32 v36, 0xbfb8aa3b, v36
	v_exp_f32_e32 v36, v36
	v_mul_f32_e32 v37, 0xbfb8aa3b, v37
	v_exp_f32_e32 v37, v37
	v_add_f32_e32 v36, 1.0, v36
	v_rcp_f32_e32 v36, v36
	v_add_f32_e32 v37, 1.0, v37
	v_rcp_f32_e32 v37, v37
	v_mov_b32_dpp v86, v70 row_ror:8 row_mask:0xf bank_mask:0xf
	v_mov_b32_dpp v87, v71 row_ror:8 row_mask:0xf bank_mask:0xf
	v_mov_b32_dpp v88, v72 row_ror:8 row_mask:0xf bank_mask:0xf
	v_fmamk_f32 v65, v65, 0x3a000000, v180
	v_rsq_f32_e32 v65, v65
	v_mov_b32_dpp v94, v74 row_ror:8 row_mask:0xf bank_mask:0xf
	v_mov_b32_dpp v95, v75 row_ror:8 row_mask:0xf bank_mask:0xf
	v_mov_b32_dpp v96, v76 row_ror:8 row_mask:0xf bank_mask:0xf
	v_mov_b32_dpp v97, v77 row_ror:8 row_mask:0xf bank_mask:0xf
	v_mov_b32_dpp v89, v73 row_ror:8 row_mask:0xf bank_mask:0xf
	v_mov_b32_dpp v98, v82 row_ror:8 row_mask:0xf bank_mask:0xf
	v_cndmask_b32_e64 v74, v98, v74, s[6:7]
	v_mov_b32_dpp v90, v78 row_ror:8 row_mask:0xf bank_mask:0xf
	v_cndmask_b32_e64 v70, v90, v70, s[6:7]
	v_lshlrev_b32_e32 v90, 16, v74
	v_mul_f32_e32 v90, v65, v90
	v_cndmask_b32_e64 v78, v78, v86, s[6:7]
	v_lshlrev_b32_e32 v86, 16, v70
	v_and_b32_e32 v74, 0xffff0000, v74
	v_mul_f32_e32 v90, v52, v90
	v_fmac_f32_e32 v86, v60, v90
	v_mul_f32_e32 v60, v65, v74
	v_and_b32_e32 v70, 0xffff0000, v70
	v_mul_f32_e32 v60, v53, v60
	v_fmac_f32_e32 v70, v61, v60
	v_mul_f32_e32 v60, 0xbfb8aa3b, v62
	v_exp_f32_e32 v60, v60
	v_mul_f32_e32 v62, 0xbfb8aa3b, v63
	v_exp_f32_e32 v62, v62
	v_mov_b32_dpp v99, v83 row_ror:8 row_mask:0xf bank_mask:0xf
	v_add_f32_e32 v60, 1.0, v60
	v_mov_b32_dpp v91, v79 row_ror:8 row_mask:0xf bank_mask:0xf
	v_cndmask_b32_e64 v75, v99, v75, s[6:7]
	v_rcp_f32_e32 v60, v60
	v_cndmask_b32_e64 v71, v91, v71, s[6:7]
	v_lshlrev_b32_e32 v91, 16, v75
	v_add_f32_e32 v62, 1.0, v62
	v_mul_f32_e32 v61, v65, v91
	v_rcp_f32_e32 v62, v62
	v_cndmask_b32_e64 v79, v79, v87, s[6:7]
	v_mov_b32_dpp v100, v84 row_ror:8 row_mask:0xf bank_mask:0xf
	v_lshlrev_b32_e32 v87, 16, v71
	v_and_b32_e32 v75, 0xffff0000, v75
	v_mul_f32_e32 v61, v54, v61
	v_mov_b32_dpp v92, v80 row_ror:8 row_mask:0xf bank_mask:0xf
	v_cndmask_b32_e64 v76, v100, v76, s[6:7]
	v_fmac_f32_e32 v87, v60, v61
	v_mul_f32_e32 v60, v65, v75
	v_cndmask_b32_e64 v72, v92, v72, s[6:7]
	v_and_b32_e32 v71, 0xffff0000, v71
	v_lshlrev_b32_e32 v92, 16, v76
	v_mul_f32_e32 v60, v55, v60
	v_fmac_f32_e32 v71, v62, v60
	v_mul_f32_e32 v60, v65, v92
	v_cndmask_b32_e64 v80, v80, v88, s[6:7]
	v_lshlrev_b32_e32 v88, 16, v72
	v_and_b32_e32 v76, 0xffff0000, v76
	v_mul_f32_e32 v60, v48, v60
	v_fmac_f32_e32 v88, v56, v60
	v_mul_f32_e32 v56, v65, v76
	v_and_b32_e32 v72, 0xffff0000, v72
	v_mul_f32_e32 v56, v49, v56
	v_fmac_f32_e32 v72, v57, v56
	v_mul_f32_e32 v56, 0xbfb8aa3b, v58
	v_cndmask_b32_e64 v82, v82, v94, s[6:7]
	v_exp_f32_e32 v56, v56
	v_mul_f32_e32 v58, 0xbfb8aa3b, v59
	v_lshlrev_b32_e32 v75, 16, v82
	v_exp_f32_e32 v58, v58
	v_mul_f32_e32 v75, v65, v75
	v_lshlrev_b32_e32 v61, 16, v78
	v_and_b32_e32 v76, 0xffff0000, v82
	v_mul_f32_e32 v75, v40, v75
	v_mov_b32_dpp v101, v85 row_ror:8 row_mask:0xf bank_mask:0xf
; __device__ __forceinline__ void store_pair_lines(bf16_t* O, int ldc, int row, int fr, int col0, u32x4 wA, u32x4 wB) {
;     const u32x4 sA = {dpp_ror8(wA.x), dpp_ror8(wA.y), dpp_ror8(wA.z), dpp_ror8(wA.w)}, sB = {dpp_ror8(wB.x), dpp_ror8(wB.y), dpp_ror8(wB.z), dpp_ror8(wB.w)};
;     const bool lo = fr < 8;
;     const u32x4 o1 = lo ? wA : sB, o2 = lo ? sA : wB;
;     const int r1 = row - fr + (fr & 7), cb = col0 + (lo ? 0 : 8);
;     *(u32x4*)(O + (size_t)r1 * ldc + cb) = o1;
;     __device__ __forceinline__ void operator()(const f32x4 (&acc)[2][2][4][2], const Unit& u, int wr, int wc, int fr, int fq) const {
;     ...
;             for (int m = 0; m < 4; ++m) { const int row = row0 + ai * HALF + m * 16; const size_t off = (size_t)row * D + col0; const float ri = __builtin_amdgcn_rsqf(sse[row] * (1.f / D) + EPS); float sq = 0.f; u32x4 w[2];
;                 u32x4 rr[2], ee[2]; load_pair_lines(R, D, row, fr, col0, rr[0], rr[1]); load_pair_lines(E, D, row, fr, col0, ee[0], ee[1]);
; #pragma unroll
;                 for (int bj = 0; bj < 2; ++bj) { const u32x4 rw = rr[bj], ew = ee[bj];
;                     const float r[8] = {bflo(rw.x), bfhi(rw.x), bflo(rw.y), bfhi(rw.y), bflo(rw.z), bfhi(rw.z), bflo(rw.w), bfhi(rw.w)};
;                     const float e[8] = {bflo(ew.x), bfhi(ew.x), bflo(ew.y), bfhi(ew.y), bflo(ew.z), bfhi(ew.z), bflo(ew.w), bfhi(ew.w)};
;                     float o[8];
; #pragma unroll
;                     for (int j = 0; j < 8; ++j) { const float a = acc[ai][bj][m][j >> 2][j & 3]; const float gg = gv[bj][j >> 2][j & 3];
;                         o[j] = r[j] + e[j] * ri * gg * __builtin_amdgcn_rcpf(1.f + __builtin_amdgcn_exp2f(-a * LOG2E)); }
;                     if (OUT) { *(f32x4*)(OUT + off + 8 * bj) = (f32x4){o[0], o[1], o[2], o[3]}; *(f32x4*)(OUT + off + 8 * bj + 4) = (f32x4){o[4], o[5], o[6], o[7]}; }
;                     else { sq += (o[0] * o[0] + o[1] * o[1]) + (o[2] * o[2] + o[3] * o[3]) + (o[4] * o[4] + o[5] * o[5]) + (o[6] * o[6] + o[7] * o[7]);
;                         w[bj].x = cvt_pk_bf16(o[0], o[1]); w[bj].y = cvt_pk_bf16(o[2], o[3]); w[bj].z = cvt_pk_bf16(o[4], o[5]); w[bj].w = cvt_pk_bf16(o[6], o[7]); } }
;                 if (!OUT) { store_pair_lines(O, D, row, fr, col0, w[0], w[1]);
;                     sq += __shfl_xor(sq, 16); sq += __shfl_xor(sq, 32); if (fq == 0) unsafeAtomicAdd(ssout + row, sq); } }
	v_add_f32_e32 v56, 1.0, v56
	v_fmac_f32_e32 v61, v44, v75
	v_mul_f32_e32 v44, v65, v76
	v_mov_b32_dpp v93, v81 row_ror:8 row_mask:0xf bank_mask:0xf
	v_cndmask_b32_e64 v77, v101, v77, s[6:7]
	v_rcp_f32_e32 v56, v56
	v_and_b32_e32 v62, 0xffff0000, v78
	v_mul_f32_e32 v44, v41, v44
	v_cndmask_b32_e64 v73, v93, v73, s[6:7]
	v_lshlrev_b32_e32 v93, 16, v77
	v_add_f32_e32 v58, 1.0, v58
	v_fmac_f32_e32 v62, v45, v44
	v_mul_f32_e32 v44, 0xbfb8aa3b, v46
	v_mul_f32_e32 v57, v65, v93
	v_rcp_f32_e32 v58, v58
	v_exp_f32_e32 v44, v44
	v_cndmask_b32_e64 v81, v81, v89, s[6:7]
	v_lshlrev_b32_e32 v89, 16, v73
	v_and_b32_e32 v77, 0xffff0000, v77
	v_mul_f32_e32 v57, v50, v57
	v_mul_f32_e32 v46, 0xbfb8aa3b, v47
	v_fmac_f32_e32 v89, v56, v57
	v_mul_f32_e32 v56, v65, v77
	v_exp_f32_e32 v46, v46
	v_and_b32_e32 v73, 0xffff0000, v73
	v_mul_f32_e32 v56, v51, v56
	v_fmac_f32_e32 v73, v58, v56
	v_mul_f32_e32 v56, v70, v70
	v_mul_f32_e32 v57, v71, v71
	v_add_f32_e32 v44, 1.0, v44
	v_cndmask_b32_e64 v83, v83, v95, s[6:7]
	v_fmac_f32_e32 v56, v86, v86
	v_fmac_f32_e32 v57, v87, v87
	v_rcp_f32_e32 v44, v44
	v_add_f32_e32 v56, v56, v57
	v_mul_f32_e32 v57, v72, v72
	v_lshlrev_b32_e32 v77, 16, v83
	v_add_f32_e32 v46, 1.0, v46
	v_fmac_f32_e32 v57, v88, v88
	v_mul_f32_e32 v45, v65, v77
	v_rcp_f32_e32 v46, v46
	v_add_f32_e32 v56, v57, v56
	v_mul_f32_e32 v57, v73, v73
	v_lshlrev_b32_e32 v63, 16, v79
	v_and_b32_e32 v78, 0xffff0000, v83
	v_mul_f32_e32 v45, v42, v45
	v_cndmask_b32_e64 v84, v84, v96, s[6:7]
	v_fmac_f32_e32 v57, v89, v89
	v_fmac_f32_e32 v63, v44, v45
	v_mul_f32_e32 v44, v65, v78
	v_add_f32_e32 v56, v57, v56
	v_cvt_pk_bf16_f32 v57, v86, v70
	v_and_b32_e32 v70, 0xffff0000, v79
	v_lshlrev_b32_e32 v79, 16, v84
	v_mul_f32_e32 v44, v43, v44
	v_fmac_f32_e32 v70, v46, v44
	v_mul_f32_e32 v44, v65, v79
	v_cvt_pk_bf16_f32 v58, v87, v71
	v_cvt_pk_bf16_f32 v59, v88, v72
	v_lshlrev_b32_e32 v71, 16, v80
	v_and_b32_e32 v72, 0xffff0000, v80
	v_and_b32_e32 v80, 0xffff0000, v84
	v_mul_f32_e32 v44, v32, v44
	v_fmac_f32_e32 v71, v36, v44
	v_mul_f32_e32 v36, v65, v80
	v_mul_f32_e32 v36, v33, v36
	v_fmac_f32_e32 v72, v37, v36
	v_mul_f32_e32 v36, 0xbfb8aa3b, v38
	v_exp_f32_e32 v36, v36
	v_mul_f32_e32 v38, 0xbfb8aa3b, v39
	v_exp_f32_e32 v38, v38
	v_cndmask_b32_e64 v85, v85, v97, s[6:7]
	v_add_f32_e32 v36, 1.0, v36
	v_rcp_f32_e32 v36, v36
	v_cvt_pk_bf16_f32 v60, v89, v73
	v_lshlrev_b32_e32 v73, 16, v81
	v_and_b32_e32 v74, 0xffff0000, v81
	v_lshlrev_b32_e32 v81, 16, v85
	v_add_f32_e32 v38, 1.0, v38
	v_mul_f32_e32 v37, v65, v81
	v_rcp_f32_e32 v38, v38
	v_and_b32_e32 v82, 0xffff0000, v85
	v_mul_f32_e32 v37, v34, v37
	v_fmac_f32_e32 v73, v36, v37
	v_mul_f32_e32 v36, v65, v82
	v_mul_f32_e32 v36, v35, v36
	v_fmac_f32_e32 v74, v38, v36
	v_mul_f32_e32 v36, v62, v62
	v_mul_f32_e32 v37, v70, v70
	v_fmac_f32_e32 v36, v61, v61
	v_fmac_f32_e32 v37, v63, v63
	v_add_f32_e32 v36, v36, v37
	v_mul_f32_e32 v37, v72, v72
	v_fmac_f32_e32 v37, v71, v71
	v_add_f32_e32 v36, v37, v36
	v_mul_f32_e32 v37, v74, v74
	v_fmac_f32_e32 v37, v73, v73
	v_add_f32_e32 v36, v37, v36
	v_add_f32_e32 v65, v36, v56
	v_cvt_pk_bf16_f32 v36, v61, v62
	v_cvt_pk_bf16_f32 v37, v63, v70
	v_cvt_pk_bf16_f32 v38, v71, v72
	v_cvt_pk_bf16_f32 v39, v73, v74
	v_mov_b32_e32 v63, 0
	v_mov_b32_e32 v56, 0
	v_mov_b32_dpp v47, v39 row_ror:8 row_mask:0xf bank_mask:0xf
	v_mov_b32_dpp v63, v60 row_ror:8 row_mask:0xf bank_mask:0xf
	v_cndmask_b32_e64 v47, v47, v60, s[6:7]
	ds_bpermute_b32 v60, v134, v65
	v_mov_b32_dpp v56, v57 row_ror:8 row_mask:0xf bank_mask:0xf
	v_mov_b32_dpp v61, v58 row_ror:8 row_mask:0xf bank_mask:0xf
	v_mov_b32_dpp v44, v36 row_ror:8 row_mask:0xf bank_mask:0xf
	v_mov_b32_dpp v62, v59 row_ror:8 row_mask:0xf bank_mask:0xf
	v_mov_b32_dpp v45, v37 row_ror:8 row_mask:0xf bank_mask:0xf
	v_mov_b32_dpp v46, v38 row_ror:8 row_mask:0xf bank_mask:0xf
	v_cndmask_b32_e64 v44, v44, v57, s[6:7]
	v_cndmask_b32_e64 v56, v36, v56, s[6:7]
	v_cndmask_b32_e64 v57, v37, v61, s[6:7]
	v_lshl_add_u64 v[36:37], s[36:37], 0, v[66:67]
	v_cndmask_b32_e64 v45, v45, v58, s[6:7]
	v_cndmask_b32_e64 v46, v46, v59, s[6:7]
	v_cndmask_b32_e64 v58, v38, v62, s[6:7]
	v_cndmask_b32_e64 v59, v39, v63, s[6:7]
	v_lshl_add_u64 v[38:39], v[36:37], 0, v[162:163]
	s_waitcnt lgkmcnt(0)
	v_add_f32_e32 v36, v65, v60
	ds_bpermute_b32 v37, v135, v36
	global_store_dwordx4 v[38:39], v[44:47], off
	v_lshl_add_u64 v[38:39], s[36:37], 0, v[68:69]
	v_lshl_add_u64 v[38:39], v[38:39], 0, v[162:163]
	global_store_dwordx4 v[38:39], v[56:59], off
	s_and_saveexec_b64 s[56:57], s[8:9]
	s_cbranch_execz .LBB0_895
	v_ashrrev_i32_e32 v65, 31, v64
	v_lshl_add_u64 v[38:39], v[64:65], 2, s[18:19]
	s_waitcnt lgkmcnt(0)
	v_add_f32_e32 v36, v36, v37
	global_atomic_add_f32 v[38:39], v36, off
; __device__ __forceinline__ void store_pair_lines(bf16_t* O, int ldc, int row, int fr, int col0, u32x4 wA, u32x4 wB) {
;     const u32x4 sA = {dpp_ror8(wA.x), dpp_ror8(wA.y), dpp_ror8(wA.z), dpp_ror8(wA.w)}, sB = {dpp_ror8(wB.x), dpp_ror8(wB.y), dpp_ror8(wB.z), dpp_ror8(wB.w)};
;     const bool lo = fr < 8;
;     const u32x4 o1 = lo ? wA : sB, o2 = lo ? sA : wB;
;     const int r1 = row - fr + (fr & 7), cb = col0 + (lo ? 0 : 8);
;     *(u32x4*)(O + (size_t)r1 * ldc + cb) = o1;
;     __device__ __forceinline__ void operator()(const f32x4 (&acc)[2][2][4][2], const Unit& u, int wr, int wc, int fr, int fq) const {
;     ...
;             for (int m = 0; m < 4; ++m) { const int row = row0 + ai * HALF + m * 16; const size_t off = (size_t)row * D + col0; const float ri = __builtin_amdgcn_rsqf(sse[row] * (1.f / D) + EPS); float sq = 0.f; u32x4 w[2];
;                 u32x4 rr[2], ee[2]; load_pair_lines(R, D, row, fr, col0, rr[0], rr[1]); load_pair_lines(E, D, row, fr, col0, ee[0], ee[1]);
; #pragma unroll
;                 for (int bj = 0; bj < 2; ++bj) { const u32x4 rw = rr[bj], ew = ee[bj];
;                     const float r[8] = {bflo(rw.x), bfhi(rw.x), bflo(rw.y), bfhi(rw.y), bflo(rw.z), bfhi(rw.z), bflo(rw.w), bfhi(rw.w)};
;                     const float e[8] = {bflo(ew.x), bfhi(ew.x), bflo(ew.y), bfhi(ew.y), bflo(ew.z), bfhi(ew.z), bflo(ew.w), bfhi(ew.w)};
;                     float o[8];
; #pragma unroll
;                     for (int j = 0; j < 8; ++j) { const float a = acc[ai][bj][m][j >> 2][j & 3]; const float gg = gv[bj][j >> 2][j & 3];
;                         o[j] = r[j] + e[j] * ri * gg * __builtin_amdgcn_rcpf(1.f + __builtin_amdgcn_exp2f(-a * LOG2E)); }
;                     if (OUT) { *(f32x4*)(OUT + off + 8 * bj) = (f32x4){o[0], o[1], o[2], o[3]}; *(f32x4*)(OUT + off + 8 * bj + 4) = (f32x4){o[4], o[5], o[6], o[7]}; }
;                     else { sq += (o[0] * o[0] + o[1] * o[1]) + (o[2] * o[2] + o[3] * o[3]) + (o[4] * o[4] + o[5] * o[5]) + (o[6] * o[6] + o[7] * o[7]);
;                         w[bj].x = cvt_pk_bf16(o[0], o[1]); w[bj].y = cvt_pk_bf16(o[2], o[3]); w[bj].z = cvt_pk_bf16(o[4], o[5]); w[bj].w = cvt_pk_bf16(o[6], o[7]); } }
;                 if (!OUT) { store_pair_lines(O, D, row, fr, col0, w[0], w[1]);
;                     sq += __shfl_xor(sq, 16); sq += __shfl_xor(sq, 32); if (fq == 0) unsafeAtomicAdd(ssout + row, sq); } }
.LBB0_895:
	s_or_b64 exec, exec, s[56:57]
	v_add_u32_e32 v36, 0xa0, v164
	v_sub_u32_e32 v38, v36, v172
	v_add_u32_e32 v38, v38, v174
	v_ashrrev_i32_e32 v39, 31, v38
	v_lshlrev_b64 v[38:39], 12, v[38:39]
	v_lshl_add_u64 v[44:45], s[16:17], 0, v[38:39]
	v_lshl_add_u64 v[44:45], v[44:45], 0, v[162:163]
	s_waitcnt vmcnt(2)
	s_nop 0
	v_mov_b64_e32 v[56:57], v[228:229]
	v_mov_b64_e32 v[58:59], v[230:231]
	v_lshl_add_u64 v[44:45], s[38:39], 0, v[38:39]
	v_lshl_add_u64 v[44:45], v[44:45], 0, v[162:163]
	s_waitcnt lgkmcnt(0)
	v_mov_b32_e32 v37, v226
	v_mov_b64_e32 v[60:61], v[232:233]
	v_mov_b64_e32 v[62:63], v[234:235]
	v_lshl_add_u64 v[44:45], v[38:39], 0, s[44:45]
	v_lshl_add_u64 v[46:47], s[16:17], 0, v[44:45]
	v_lshl_add_u64 v[46:47], v[46:47], 0, v[162:163]
	v_mov_b64_e32 v[64:65], v[236:237]
	v_mov_b64_e32 v[66:67], v[238:239]
	v_lshl_add_u64 v[46:47], s[38:39], 0, v[44:45]
	v_lshl_add_u64 v[46:47], v[46:47], 0, v[162:163]
	v_mov_b64_e32 v[68:69], v[240:241]
	v_mov_b64_e32 v[70:71], v[242:243]
	s_nop 1
	v_add_u32_e32 v216, 0xb0, v164
	v_sub_u32_e32 v218, v216, v172
	v_add_u32_e32 v218, v218, v174
	v_ashrrev_i32_e32 v219, 31, v218
	v_lshlrev_b64 v[218:219], 12, v[218:219]
	v_lshl_add_u64 v[220:221], s[16:17], 0, v[218:219]
	v_lshl_add_u64 v[220:221], v[220:221], 0, v[162:163]
	global_load_dwordx4 v[228:231], v[220:221], off
	v_lshl_add_u64 v[220:221], s[38:39], 0, v[218:219]
	v_lshl_add_u64 v[220:221], v[220:221], 0, v[162:163]
	global_load_dword v226, v[166:167], off offset:704
	global_load_dwordx4 v[232:235], v[220:221], off
	v_lshl_add_u64 v[220:221], v[218:219], 0, s[44:45]
	v_lshl_add_u64 v[222:223], s[16:17], 0, v[220:221]
	v_lshl_add_u64 v[222:223], v[222:223], 0, v[162:163]
	global_load_dwordx4 v[236:239], v[222:223], off
	v_lshl_add_u64 v[222:223], s[38:39], 0, v[220:221]
	v_lshl_add_u64 v[222:223], v[222:223], 0, v[162:163]
	global_load_dwordx4 v[240:243], v[222:223], off
	v_mul_f32_e32 v28, 0xbfb8aa3b, v28
	v_exp_f32_e32 v28, v28
	v_mul_f32_e32 v29, 0xbfb8aa3b, v29
	v_exp_f32_e32 v29, v29
	v_add_f32_e32 v28, 1.0, v28
	v_rcp_f32_e32 v28, v28
	v_add_f32_e32 v29, 1.0, v29
	v_rcp_f32_e32 v29, v29
	v_mul_f32_e32 v24, 0xbfb8aa3b, v24
	v_exp_f32_e32 v24, v24
	v_mul_f32_e32 v25, 0xbfb8aa3b, v25
	v_exp_f32_e32 v25, v25
	v_add_f32_e32 v24, 1.0, v24
	v_rcp_f32_e32 v24, v24
	v_add_f32_e32 v25, 1.0, v25
	v_rcp_f32_e32 v25, v25
	v_mul_f32_e32 v20, 0xbfb8aa3b, v20
	v_exp_f32_e32 v20, v20
	v_mul_f32_e32 v21, 0xbfb8aa3b, v21
	v_exp_f32_e32 v21, v21
	v_mul_f32_e32 v16, 0xbfb8aa3b, v16
	v_add_f32_e32 v20, 1.0, v20
	v_rcp_f32_e32 v20, v20
	v_add_f32_e32 v21, 1.0, v21
	v_rcp_f32_e32 v21, v21
	v_exp_f32_e32 v16, v16
	v_mul_f32_e32 v17, 0xbfb8aa3b, v17
	v_exp_f32_e32 v17, v17
	v_add_f32_e32 v16, 1.0, v16
	v_rcp_f32_e32 v16, v16
	v_add_f32_e32 v17, 1.0, v17
	v_rcp_f32_e32 v17, v17
	v_mov_b32_dpp v46, v56 row_ror:8 row_mask:0xf bank_mask:0xf
	v_mov_b32_dpp v47, v57 row_ror:8 row_mask:0xf bank_mask:0xf
	v_mov_b32_dpp v72, v58 row_ror:8 row_mask:0xf bank_mask:0xf
	v_fmamk_f32 v37, v37, 0x3a000000, v180
	v_rsq_f32_e32 v37, v37
	v_mov_b32_dpp v78, v60 row_ror:8 row_mask:0xf bank_mask:0xf
	v_mov_b32_dpp v80, v62 row_ror:8 row_mask:0xf bank_mask:0xf
	v_mov_b32_dpp v79, v61 row_ror:8 row_mask:0xf bank_mask:0xf
	v_mov_b32_dpp v74, v64 row_ror:8 row_mask:0xf bank_mask:0xf
	v_cndmask_b32_e64 v56, v74, v56, s[6:7]
	v_mov_b32_dpp v75, v65 row_ror:8 row_mask:0xf bank_mask:0xf
	v_mov_b32_dpp v82, v68 row_ror:8 row_mask:0xf bank_mask:0xf
	v_cndmask_b32_e64 v60, v82, v60, s[6:7]
	v_lshlrev_b32_e32 v74, 16, v60
	v_mul_f32_e32 v74, v37, v74
	v_cndmask_b32_e64 v47, v65, v47, s[6:7]
	v_mov_b32_dpp v84, v70 row_ror:8 row_mask:0xf bank_mask:0xf
	v_cndmask_b32_e64 v65, v70, v80, s[6:7]
	v_lshlrev_b32_e32 v70, 16, v56
	v_and_b32_e32 v60, 0xffff0000, v60
	v_mul_f32_e32 v74, v52, v74
	v_fmac_f32_e32 v70, v28, v74
	v_mul_f32_e32 v28, v37, v60
	v_and_b32_e32 v56, 0xffff0000, v56
	v_mul_f32_e32 v28, v53, v28
	v_fmac_f32_e32 v56, v29, v28
	v_mul_f32_e32 v28, 0xbfb8aa3b, v30
	v_exp_f32_e32 v28, v28
	v_mul_f32_e32 v30, 0xbfb8aa3b, v31
	v_exp_f32_e32 v30, v30
	v_mov_b32_dpp v83, v69 row_ror:8 row_mask:0xf bank_mask:0xf
	v_add_f32_e32 v28, 1.0, v28
	v_cndmask_b32_e64 v61, v83, v61, s[6:7]
	v_rcp_f32_e32 v28, v28
	v_cndmask_b32_e64 v57, v75, v57, s[6:7]
	v_lshlrev_b32_e32 v75, 16, v61
	v_add_f32_e32 v30, 1.0, v30
	v_mov_b32_dpp v81, v63 row_ror:8 row_mask:0xf bank_mask:0xf
	v_mul_f32_e32 v29, v37, v75
	v_rcp_f32_e32 v30, v30
	v_cndmask_b32_e64 v46, v64, v46, s[6:7]
	v_mov_b32_dpp v85, v71 row_ror:8 row_mask:0xf bank_mask:0xf
	v_cndmask_b32_e64 v64, v71, v81, s[6:7]
	v_lshlrev_b32_e32 v71, 16, v57
	v_and_b32_e32 v61, 0xffff0000, v61
	v_mul_f32_e32 v29, v54, v29
	v_mov_b32_dpp v76, v66 row_ror:8 row_mask:0xf bank_mask:0xf
	v_cndmask_b32_e64 v62, v84, v62, s[6:7]
	v_fmac_f32_e32 v71, v28, v29
	v_mul_f32_e32 v28, v37, v61
	v_cndmask_b32_e64 v58, v76, v58, s[6:7]
	v_and_b32_e32 v57, 0xffff0000, v57
	v_lshlrev_b32_e32 v76, 16, v62
	v_mul_f32_e32 v28, v55, v28
	v_fmac_f32_e32 v57, v30, v28
	v_mul_f32_e32 v28, v37, v76
	v_cndmask_b32_e64 v66, v66, v72, s[6:7]
	v_lshlrev_b32_e32 v72, 16, v58
	v_and_b32_e32 v62, 0xffff0000, v62
	v_mul_f32_e32 v28, v48, v28
	v_fmac_f32_e32 v72, v24, v28
	v_mul_f32_e32 v24, v37, v62
	v_and_b32_e32 v58, 0xffff0000, v58
	v_mul_f32_e32 v24, v49, v24
	v_fmac_f32_e32 v58, v25, v24
	v_mul_f32_e32 v24, 0xbfb8aa3b, v26
	v_exp_f32_e32 v24, v24
	v_mul_f32_e32 v26, 0xbfb8aa3b, v27
	v_exp_f32_e32 v26, v26
	v_mov_b32_dpp v77, v67 row_ror:8 row_mask:0xf bank_mask:0xf
	v_add_f32_e32 v24, 1.0, v24
	v_cndmask_b32_e64 v63, v85, v63, s[6:7]
	v_rcp_f32_e32 v24, v24
; __device__ __forceinline__ void store_pair_lines(bf16_t* O, int ldc, int row, int fr, int col0, u32x4 wA, u32x4 wB) {
;     const u32x4 sA = {dpp_ror8(wA.x), dpp_ror8(wA.y), dpp_ror8(wA.z), dpp_ror8(wA.w)}, sB = {dpp_ror8(wB.x), dpp_ror8(wB.y), dpp_ror8(wB.z), dpp_ror8(wB.w)};
;     const bool lo = fr < 8;
;     const u32x4 o1 = lo ? wA : sB, o2 = lo ? sA : wB;
;     const int r1 = row - fr + (fr & 7), cb = col0 + (lo ? 0 : 8);
;     *(u32x4*)(O + (size_t)r1 * ldc + cb) = o1;
;     __device__ __forceinline__ void operator()(const f32x4 (&acc)[2][2][4][2], const Unit& u, int wr, int wc, int fr, int fq) const {
;     ...
;             for (int m = 0; m < 4; ++m) { const int row = row0 + ai * HALF + m * 16; const size_t off = (size_t)row * D + col0; const float ri = __builtin_amdgcn_rsqf(sse[row] * (1.f / D) + EPS); float sq = 0.f; u32x4 w[2];
;                 u32x4 rr[2], ee[2]; load_pair_lines(R, D, row, fr, col0, rr[0], rr[1]); load_pair_lines(E, D, row, fr, col0, ee[0], ee[1]);
; #pragma unroll
;                 for (int bj = 0; bj < 2; ++bj) { const u32x4 rw = rr[bj], ew = ee[bj];
;                     const float r[8] = {bflo(rw.x), bfhi(rw.x), bflo(rw.y), bfhi(rw.y), bflo(rw.z), bfhi(rw.z), bflo(rw.w), bfhi(rw.w)};
;                     const float e[8] = {bflo(ew.x), bfhi(ew.x), bflo(ew.y), bfhi(ew.y), bflo(ew.z), bfhi(ew.z), bflo(ew.w), bfhi(ew.w)};
;                     float o[8];
; #pragma unroll
;                     for (int j = 0; j < 8; ++j) { const float a = acc[ai][bj][m][j >> 2][j & 3]; const float gg = gv[bj][j >> 2][j & 3];
;                         o[j] = r[j] + e[j] * ri * gg * __builtin_amdgcn_rcpf(1.f + __builtin_amdgcn_exp2f(-a * LOG2E)); }
;                     if (OUT) { *(f32x4*)(OUT + off + 8 * bj) = (f32x4){o[0], o[1], o[2], o[3]}; *(f32x4*)(OUT + off + 8 * bj + 4) = (f32x4){o[4], o[5], o[6], o[7]}; }
;                     else { sq += (o[0] * o[0] + o[1] * o[1]) + (o[2] * o[2] + o[3] * o[3]) + (o[4] * o[4] + o[5] * o[5]) + (o[6] * o[6] + o[7] * o[7]);
;                         w[bj].x = cvt_pk_bf16(o[0], o[1]); w[bj].y = cvt_pk_bf16(o[2], o[3]); w[bj].z = cvt_pk_bf16(o[4], o[5]); w[bj].w = cvt_pk_bf16(o[6], o[7]); } }
;                 if (!OUT) { store_pair_lines(O, D, row, fr, col0, w[0], w[1]);
;                     sq += __shfl_xor(sq, 16); sq += __shfl_xor(sq, 32); if (fq == 0) unsafeAtomicAdd(ssout + row, sq); } }
	v_mov_b32_dpp v73, v59 row_ror:8 row_mask:0xf bank_mask:0xf
	v_cndmask_b32_e64 v59, v77, v59, s[6:7]
	v_lshlrev_b32_e32 v77, 16, v63
	v_add_f32_e32 v26, 1.0, v26
	v_mul_f32_e32 v25, v37, v77
	v_rcp_f32_e32 v26, v26
	v_cndmask_b32_e64 v67, v67, v73, s[6:7]
	v_lshlrev_b32_e32 v73, 16, v59
	v_and_b32_e32 v63, 0xffff0000, v63
	v_mul_f32_e32 v25, v50, v25
	v_fmac_f32_e32 v73, v24, v25
	v_mul_f32_e32 v24, v37, v63
	v_and_b32_e32 v59, 0xffff0000, v59
	v_mul_f32_e32 v24, v51, v24
	v_fmac_f32_e32 v59, v26, v24
	v_mul_f32_e32 v24, v56, v56
	v_mul_f32_e32 v25, v57, v57
	v_fmac_f32_e32 v24, v70, v70
	v_fmac_f32_e32 v25, v71, v71
	v_add_f32_e32 v24, v24, v25
	v_mul_f32_e32 v25, v58, v58
	v_fmac_f32_e32 v25, v72, v72
	v_add_f32_e32 v24, v25, v24
	v_mul_f32_e32 v25, v59, v59
	v_cndmask_b32_e64 v68, v68, v78, s[6:7]
	v_fmac_f32_e32 v25, v73, v73
	v_add_f32_e32 v24, v25, v24
	v_cvt_pk_bf16_f32 v25, v70, v56
	v_cvt_pk_bf16_f32 v26, v71, v57
	v_cvt_pk_bf16_f32 v27, v72, v58
	v_cvt_pk_bf16_f32 v28, v73, v59
	v_lshlrev_b32_e32 v59, 16, v68
	v_mul_f32_e32 v59, v37, v59
	v_lshlrev_b32_e32 v29, 16, v46
	v_and_b32_e32 v60, 0xffff0000, v68
	v_mul_f32_e32 v59, v40, v59
	v_fmac_f32_e32 v29, v20, v59
	v_mul_f32_e32 v20, v37, v60
	v_and_b32_e32 v30, 0xffff0000, v46
	v_mul_f32_e32 v20, v41, v20
	v_fmac_f32_e32 v30, v21, v20
	v_mul_f32_e32 v20, 0xbfb8aa3b, v22
	v_exp_f32_e32 v20, v20
	v_mul_f32_e32 v22, 0xbfb8aa3b, v23
	v_exp_f32_e32 v22, v22
	v_cndmask_b32_e64 v69, v69, v79, s[6:7]
	v_add_f32_e32 v20, 1.0, v20
	v_rcp_f32_e32 v20, v20
	v_lshlrev_b32_e32 v61, 16, v69
	v_add_f32_e32 v22, 1.0, v22
	v_mul_f32_e32 v21, v37, v61
	v_rcp_f32_e32 v22, v22
	v_lshlrev_b32_e32 v31, 16, v47
	v_and_b32_e32 v62, 0xffff0000, v69
	v_mul_f32_e32 v21, v42, v21
	v_fmac_f32_e32 v31, v20, v21
	v_mul_f32_e32 v20, v37, v62
	v_and_b32_e32 v46, 0xffff0000, v47
	v_lshlrev_b32_e32 v63, 16, v65
	v_mul_f32_e32 v20, v43, v20
	v_fmac_f32_e32 v46, v22, v20
	v_mul_f32_e32 v20, v37, v63
	v_lshlrev_b32_e32 v47, 16, v66
	v_and_b32_e32 v65, 0xffff0000, v65
	v_mul_f32_e32 v20, v32, v20
	v_fmac_f32_e32 v47, v16, v20
	v_mul_f32_e32 v16, v37, v65
	v_and_b32_e32 v56, 0xffff0000, v66
	v_mul_f32_e32 v16, v33, v16
	v_fmac_f32_e32 v56, v17, v16
	v_mul_f32_e32 v16, 0xbfb8aa3b, v18
	v_exp_f32_e32 v16, v16
	v_mul_f32_e32 v18, 0xbfb8aa3b, v19
	v_exp_f32_e32 v18, v18
	v_lshlrev_b32_e32 v66, 16, v64
	v_add_f32_e32 v16, 1.0, v16
	v_rcp_f32_e32 v16, v16
	v_add_f32_e32 v18, 1.0, v18
	v_mul_f32_e32 v17, v37, v66
	v_rcp_f32_e32 v18, v18
	v_lshlrev_b32_e32 v57, 16, v67
	v_and_b32_e32 v64, 0xffff0000, v64
	v_mul_f32_e32 v17, v34, v17
	v_fmac_f32_e32 v57, v16, v17
	v_mul_f32_e32 v16, v37, v64
	v_and_b32_e32 v58, 0xffff0000, v67
	v_mul_f32_e32 v16, v35, v16
	v_fmac_f32_e32 v58, v18, v16
	v_mul_f32_e32 v16, v30, v30
	v_mul_f32_e32 v17, v46, v46
	v_fmac_f32_e32 v16, v29, v29
	v_fmac_f32_e32 v17, v31, v31
	v_add_f32_e32 v16, v16, v17
	v_mul_f32_e32 v17, v56, v56
	v_fmac_f32_e32 v17, v47, v47
	v_add_f32_e32 v16, v17, v16
	v_mul_f32_e32 v17, v58, v58
	v_fmac_f32_e32 v17, v57, v57
	v_add_f32_e32 v16, v17, v16
	v_add_f32_e32 v37, v16, v24
	v_cvt_pk_bf16_f32 v16, v29, v30
	v_cvt_pk_bf16_f32 v17, v31, v46
	v_cvt_pk_bf16_f32 v24, v47, v56
	v_cvt_pk_bf16_f32 v29, v57, v58
	v_mov_b32_e32 v31, 0
	v_mov_b32_e32 v22, 0
	v_mov_b32_dpp v21, v29 row_ror:8 row_mask:0xf bank_mask:0xf
	v_mov_b32_dpp v31, v28 row_ror:8 row_mask:0xf bank_mask:0xf
	v_cndmask_b32_e64 v21, v21, v28, s[6:7]
	ds_bpermute_b32 v28, v134, v37
	v_mov_b32_dpp v22, v25 row_ror:8 row_mask:0xf bank_mask:0xf
	v_mov_b32_dpp v23, v26 row_ror:8 row_mask:0xf bank_mask:0xf
	v_mov_b32_dpp v18, v16 row_ror:8 row_mask:0xf bank_mask:0xf
	v_mov_b32_dpp v19, v17 row_ror:8 row_mask:0xf bank_mask:0xf
	v_mov_b32_dpp v20, v24 row_ror:8 row_mask:0xf bank_mask:0xf
	v_cndmask_b32_e64 v22, v16, v22, s[6:7]
	v_cndmask_b32_e64 v23, v17, v23, s[6:7]
	v_lshl_add_u64 v[16:17], s[36:37], 0, v[38:39]
	v_mov_b32_dpp v30, v27 row_ror:8 row_mask:0xf bank_mask:0xf
	v_cndmask_b32_e64 v19, v19, v26, s[6:7]
	v_cndmask_b32_e64 v20, v20, v27, s[6:7]
	v_lshl_add_u64 v[26:27], v[16:17], 0, v[162:163]
	s_waitcnt lgkmcnt(0)
	v_add_f32_e32 v16, v37, v28
	ds_bpermute_b32 v17, v135, v16
	v_cndmask_b32_e64 v18, v18, v25, s[6:7]
	global_store_dwordx4 v[26:27], v[18:21], off
	v_cndmask_b32_e64 v24, v24, v30, s[6:7]
	v_cndmask_b32_e64 v25, v29, v31, s[6:7]
	v_lshl_add_u64 v[18:19], s[36:37], 0, v[44:45]
	v_lshl_add_u64 v[18:19], v[18:19], 0, v[162:163]
	global_store_dwordx4 v[18:19], v[22:25], off
	s_and_saveexec_b64 s[56:57], s[8:9]
	s_cbranch_execz .LBB0_897
	v_ashrrev_i32_e32 v37, 31, v36
	v_lshl_add_u64 v[18:19], v[36:37], 2, s[18:19]
	s_waitcnt lgkmcnt(0)
	v_add_f32_e32 v16, v16, v17
	global_atomic_add_f32 v[18:19], v16, off
; __device__ __forceinline__ void store_pair_lines(bf16_t* O, int ldc, int row, int fr, int col0, u32x4 wA, u32x4 wB) {
;     const u32x4 sA = {dpp_ror8(wA.x), dpp_ror8(wA.y), dpp_ror8(wA.z), dpp_ror8(wA.w)}, sB = {dpp_ror8(wB.x), dpp_ror8(wB.y), dpp_ror8(wB.z), dpp_ror8(wB.w)};
;     const bool lo = fr < 8;
;     const u32x4 o1 = lo ? wA : sB, o2 = lo ? sA : wB;
;     const int r1 = row - fr + (fr & 7), cb = col0 + (lo ? 0 : 8);
;     *(u32x4*)(O + (size_t)r1 * ldc + cb) = o1;
;     __device__ __forceinline__ void operator()(const f32x4 (&acc)[2][2][4][2], const Unit& u, int wr, int wc, int fr, int fq) const {
;     ...
;             for (int m = 0; m < 4; ++m) { const int row = row0 + ai * HALF + m * 16; const size_t off = (size_t)row * D + col0; const float ri = __builtin_amdgcn_rsqf(sse[row] * (1.f / D) + EPS); float sq = 0.f; u32x4 w[2];
;                 u32x4 rr[2], ee[2]; load_pair_lines(R, D, row, fr, col0, rr[0], rr[1]); load_pair_lines(E, D, row, fr, col0, ee[0], ee[1]);
; #pragma unroll
;                 for (int bj = 0; bj < 2; ++bj) { const u32x4 rw = rr[bj], ew = ee[bj];
;                     const float r[8] = {bflo(rw.x), bfhi(rw.x), bflo(rw.y), bfhi(rw.y), bflo(rw.z), bfhi(rw.z), bflo(rw.w), bfhi(rw.w)};
;                     const float e[8] = {bflo(ew.x), bfhi(ew.x), bflo(ew.y), bfhi(ew.y), bflo(ew.z), bfhi(ew.z), bflo(ew.w), bfhi(ew.w)};
;                     float o[8];
; #pragma unroll
;                     for (int j = 0; j < 8; ++j) { const float a = acc[ai][bj][m][j >> 2][j & 3]; const float gg = gv[bj][j >> 2][j & 3];
;                         o[j] = r[j] + e[j] * ri * gg * __builtin_amdgcn_rcpf(1.f + __builtin_amdgcn_exp2f(-a * LOG2E)); }
;                     if (OUT) { *(f32x4*)(OUT + off + 8 * bj) = (f32x4){o[0], o[1], o[2], o[3]}; *(f32x4*)(OUT + off + 8 * bj + 4) = (f32x4){o[4], o[5], o[6], o[7]}; }
;                     else { sq += (o[0] * o[0] + o[1] * o[1]) + (o[2] * o[2] + o[3] * o[3]) + (o[4] * o[4] + o[5] * o[5]) + (o[6] * o[6] + o[7] * o[7]);
;                         w[bj].x = cvt_pk_bf16(o[0], o[1]); w[bj].y = cvt_pk_bf16(o[2], o[3]); w[bj].z = cvt_pk_bf16(o[4], o[5]); w[bj].w = cvt_pk_bf16(o[6], o[7]); } }
;                 if (!OUT) { store_pair_lines(O, D, row, fr, col0, w[0], w[1]);
;                     sq += __shfl_xor(sq, 16); sq += __shfl_xor(sq, 32); if (fq == 0) unsafeAtomicAdd(ssout + row, sq); } }
.LBB0_897:
	s_or_b64 exec, exec, s[56:57]
	v_add_u32_e32 v16, 0xb0, v164
	v_sub_u32_e32 v18, v16, v172
	v_add_u32_e32 v18, v18, v174
	v_ashrrev_i32_e32 v19, 31, v18
	v_lshlrev_b64 v[18:19], 12, v[18:19]
	v_lshl_add_u64 v[20:21], s[16:17], 0, v[18:19]
	v_lshl_add_u64 v[20:21], v[20:21], 0, v[162:163]
	s_waitcnt vmcnt(2)
	s_nop 0
	v_mov_b64_e32 v[22:23], v[228:229]
	v_mov_b64_e32 v[24:25], v[230:231]
	v_lshl_add_u64 v[20:21], s[38:39], 0, v[18:19]
	v_lshl_add_u64 v[20:21], v[20:21], 0, v[162:163]
	s_waitcnt lgkmcnt(0)
	v_mov_b32_e32 v17, v226
	v_mov_b64_e32 v[26:27], v[232:233]
	v_mov_b64_e32 v[28:29], v[234:235]
	v_lshl_add_u64 v[20:21], v[18:19], 0, s[44:45]
	v_lshl_add_u64 v[30:31], s[16:17], 0, v[20:21]
	v_lshl_add_u64 v[30:31], v[30:31], 0, v[162:163]
	v_mov_b64_e32 v[36:37], v[236:237]
	v_mov_b64_e32 v[38:39], v[238:239]
	v_lshl_add_u64 v[30:31], s[38:39], 0, v[20:21]
	v_lshl_add_u64 v[30:31], v[30:31], 0, v[162:163]
	v_mov_b64_e32 v[44:45], v[240:241]
	v_mov_b64_e32 v[46:47], v[242:243]
	s_nop 1
	v_mul_f32_e32 v12, 0xbfb8aa3b, v12
	v_exp_f32_e32 v12, v12
	v_mul_f32_e32 v13, 0xbfb8aa3b, v13
	v_exp_f32_e32 v13, v13
	v_add_f32_e32 v12, 1.0, v12
	v_rcp_f32_e32 v12, v12
	v_add_f32_e32 v13, 1.0, v13
	v_rcp_f32_e32 v13, v13
	v_mul_f32_e32 v8, 0xbfb8aa3b, v8
	v_exp_f32_e32 v8, v8
	v_mul_f32_e32 v9, 0xbfb8aa3b, v9
	v_exp_f32_e32 v9, v9
	v_add_f32_e32 v8, 1.0, v8
	v_rcp_f32_e32 v8, v8
	v_add_f32_e32 v9, 1.0, v9
	v_mul_f32_e32 v4, 0xbfb8aa3b, v4
	v_rcp_f32_e32 v9, v9
	v_exp_f32_e32 v4, v4
	v_mul_f32_e32 v5, 0xbfb8aa3b, v5
	v_exp_f32_e32 v5, v5
	v_add_f32_e32 v4, 1.0, v4
	v_rcp_f32_e32 v4, v4
	v_add_f32_e32 v5, 1.0, v5
	v_rcp_f32_e32 v5, v5
	v_mul_f32_e32 v0, 0xbfb8aa3b, v0
	v_exp_f32_e32 v0, v0
	v_mul_f32_e32 v1, 0xbfb8aa3b, v1
	v_exp_f32_e32 v1, v1
	v_add_f32_e32 v0, 1.0, v0
	v_rcp_f32_e32 v0, v0
	v_add_f32_e32 v1, 1.0, v1
	v_rcp_f32_e32 v1, v1
	v_mov_b32_dpp v30, v22 row_ror:8 row_mask:0xf bank_mask:0xf
	v_mov_b32_dpp v31, v23 row_ror:8 row_mask:0xf bank_mask:0xf
	v_mov_b32_dpp v56, v24 row_ror:8 row_mask:0xf bank_mask:0xf
	v_fmamk_f32 v17, v17, 0x3a000000, v180
	v_rsq_f32_e32 v17, v17
	v_mov_b32_dpp v62, v26 row_ror:8 row_mask:0xf bank_mask:0xf
	v_mov_b32_dpp v64, v28 row_ror:8 row_mask:0xf bank_mask:0xf
	v_mov_b32_dpp v63, v27 row_ror:8 row_mask:0xf bank_mask:0xf
	v_mov_b32_dpp v58, v36 row_ror:8 row_mask:0xf bank_mask:0xf
	v_cndmask_b32_e64 v22, v58, v22, s[6:7]
	v_mov_b32_dpp v59, v37 row_ror:8 row_mask:0xf bank_mask:0xf
	v_mov_b32_dpp v66, v44 row_ror:8 row_mask:0xf bank_mask:0xf
	v_cndmask_b32_e64 v26, v66, v26, s[6:7]
	v_lshlrev_b32_e32 v58, 16, v26
	v_mul_f32_e32 v58, v17, v58
	v_cndmask_b32_e64 v31, v37, v31, s[6:7]
	v_mov_b32_dpp v68, v46 row_ror:8 row_mask:0xf bank_mask:0xf
	v_cndmask_b32_e64 v37, v46, v64, s[6:7]
	v_lshlrev_b32_e32 v46, 16, v22
	v_and_b32_e32 v26, 0xffff0000, v26
	v_mul_f32_e32 v52, v52, v58
	v_fmac_f32_e32 v46, v12, v52
	v_mul_f32_e32 v12, v17, v26
	v_and_b32_e32 v22, 0xffff0000, v22
	v_mul_f32_e32 v12, v53, v12
	v_fmac_f32_e32 v22, v13, v12
	v_mul_f32_e32 v12, 0xbfb8aa3b, v14
	v_exp_f32_e32 v12, v12
	v_mul_f32_e32 v14, 0xbfb8aa3b, v15
	v_exp_f32_e32 v14, v14
	v_mov_b32_dpp v67, v45 row_ror:8 row_mask:0xf bank_mask:0xf
	v_add_f32_e32 v12, 1.0, v12
	v_cndmask_b32_e64 v27, v67, v27, s[6:7]
	v_rcp_f32_e32 v12, v12
	v_cndmask_b32_e64 v23, v59, v23, s[6:7]
	v_lshlrev_b32_e32 v59, 16, v27
	v_add_f32_e32 v14, 1.0, v14
	v_mov_b32_dpp v65, v29 row_ror:8 row_mask:0xf bank_mask:0xf
	v_mul_f32_e32 v13, v17, v59
	v_rcp_f32_e32 v14, v14
	v_cndmask_b32_e64 v30, v36, v30, s[6:7]
	v_mov_b32_dpp v69, v47 row_ror:8 row_mask:0xf bank_mask:0xf
	v_cndmask_b32_e64 v36, v47, v65, s[6:7]
	v_lshlrev_b32_e32 v47, 16, v23
	v_and_b32_e32 v27, 0xffff0000, v27
	v_mul_f32_e32 v13, v54, v13
	v_mov_b32_dpp v60, v38 row_ror:8 row_mask:0xf bank_mask:0xf
	v_cndmask_b32_e64 v28, v68, v28, s[6:7]
	v_fmac_f32_e32 v47, v12, v13
	v_mul_f32_e32 v12, v17, v27
	v_cndmask_b32_e64 v24, v60, v24, s[6:7]
	v_and_b32_e32 v23, 0xffff0000, v23
	v_lshlrev_b32_e32 v60, 16, v28
	v_mul_f32_e32 v12, v55, v12
	v_fmac_f32_e32 v23, v14, v12
	v_mul_f32_e32 v12, v17, v60
	v_cndmask_b32_e64 v38, v38, v56, s[6:7]
	v_lshlrev_b32_e32 v56, 16, v24
	v_and_b32_e32 v28, 0xffff0000, v28
	v_mul_f32_e32 v12, v48, v12
	v_fmac_f32_e32 v56, v8, v12
	v_mul_f32_e32 v8, v17, v28
	v_and_b32_e32 v24, 0xffff0000, v24
	v_mul_f32_e32 v8, v49, v8
	v_fmac_f32_e32 v24, v9, v8
	v_mul_f32_e32 v8, 0xbfb8aa3b, v10
	v_cndmask_b32_e64 v44, v44, v62, s[6:7]
	v_exp_f32_e32 v8, v8
	v_mul_f32_e32 v10, 0xbfb8aa3b, v11
	v_lshlrev_b32_e32 v27, 16, v44
	v_exp_f32_e32 v10, v10
	v_mul_f32_e32 v27, v17, v27
; __device__ __forceinline__ void store_pair_lines(bf16_t* O, int ldc, int row, int fr, int col0, u32x4 wA, u32x4 wB) {
;     const u32x4 sA = {dpp_ror8(wA.x), dpp_ror8(wA.y), dpp_ror8(wA.z), dpp_ror8(wA.w)}, sB = {dpp_ror8(wB.x), dpp_ror8(wB.y), dpp_ror8(wB.z), dpp_ror8(wB.w)};
;     const bool lo = fr < 8;
;     const u32x4 o1 = lo ? wA : sB, o2 = lo ? sA : wB;
;     const int r1 = row - fr + (fr & 7), cb = col0 + (lo ? 0 : 8);
;     *(u32x4*)(O + (size_t)r1 * ldc + cb) = o1;
;     __device__ __forceinline__ void operator()(const f32x4 (&acc)[2][2][4][2], const Unit& u, int wr, int wc, int fr, int fq) const {
;     ...
;             for (int m = 0; m < 4; ++m) { const int row = row0 + ai * HALF + m * 16; const size_t off = (size_t)row * D + col0; const float ri = __builtin_amdgcn_rsqf(sse[row] * (1.f / D) + EPS); float sq = 0.f; u32x4 w[2];
;                 u32x4 rr[2], ee[2]; load_pair_lines(R, D, row, fr, col0, rr[0], rr[1]); load_pair_lines(E, D, row, fr, col0, ee[0], ee[1]);
; #pragma unroll
;                 for (int bj = 0; bj < 2; ++bj) { const u32x4 rw = rr[bj], ew = ee[bj];
;                     const float r[8] = {bflo(rw.x), bfhi(rw.x), bflo(rw.y), bfhi(rw.y), bflo(rw.z), bfhi(rw.z), bflo(rw.w), bfhi(rw.w)};
;                     const float e[8] = {bflo(ew.x), bfhi(ew.x), bflo(ew.y), bfhi(ew.y), bflo(ew.z), bfhi(ew.z), bflo(ew.w), bfhi(ew.w)};
;                     float o[8];
; #pragma unroll
;                     for (int j = 0; j < 8; ++j) { const float a = acc[ai][bj][m][j >> 2][j & 3]; const float gg = gv[bj][j >> 2][j & 3];
;                         o[j] = r[j] + e[j] * ri * gg * __builtin_amdgcn_rcpf(1.f + __builtin_amdgcn_exp2f(-a * LOG2E)); }
;                     if (OUT) { *(f32x4*)(OUT + off + 8 * bj) = (f32x4){o[0], o[1], o[2], o[3]}; *(f32x4*)(OUT + off + 8 * bj + 4) = (f32x4){o[4], o[5], o[6], o[7]}; }
;                     else { sq += (o[0] * o[0] + o[1] * o[1]) + (o[2] * o[2] + o[3] * o[3]) + (o[4] * o[4] + o[5] * o[5]) + (o[6] * o[6] + o[7] * o[7]);
;                         w[bj].x = cvt_pk_bf16(o[0], o[1]); w[bj].y = cvt_pk_bf16(o[2], o[3]); w[bj].z = cvt_pk_bf16(o[4], o[5]); w[bj].w = cvt_pk_bf16(o[6], o[7]); } }
;                 if (!OUT) { store_pair_lines(O, D, row, fr, col0, w[0], w[1]);
;                     sq += __shfl_xor(sq, 16); sq += __shfl_xor(sq, 32); if (fq == 0) unsafeAtomicAdd(ssout + row, sq); } }
	v_lshlrev_b32_e32 v13, 16, v30
	v_and_b32_e32 v28, 0xffff0000, v44
	v_mul_f32_e32 v27, v40, v27
	v_add_f32_e32 v8, 1.0, v8
	v_fmac_f32_e32 v13, v4, v27
	v_mul_f32_e32 v4, v17, v28
	v_mov_b32_dpp v61, v39 row_ror:8 row_mask:0xf bank_mask:0xf
	v_cndmask_b32_e64 v29, v69, v29, s[6:7]
	v_rcp_f32_e32 v8, v8
	v_and_b32_e32 v14, 0xffff0000, v30
	v_mul_f32_e32 v4, v41, v4
	v_mov_b32_dpp v57, v25 row_ror:8 row_mask:0xf bank_mask:0xf
	v_cndmask_b32_e64 v25, v61, v25, s[6:7]
	v_lshlrev_b32_e32 v61, 16, v29
	v_add_f32_e32 v10, 1.0, v10
	v_fmac_f32_e32 v14, v5, v4
	v_mul_f32_e32 v4, 0xbfb8aa3b, v6
	v_mul_f32_e32 v9, v17, v61
	v_rcp_f32_e32 v10, v10
	v_exp_f32_e32 v4, v4
	v_cndmask_b32_e64 v39, v39, v57, s[6:7]
	v_lshlrev_b32_e32 v57, 16, v25
	v_and_b32_e32 v29, 0xffff0000, v29
	v_mul_f32_e32 v9, v50, v9
	v_mul_f32_e32 v6, 0xbfb8aa3b, v7
	v_fmac_f32_e32 v57, v8, v9
	v_mul_f32_e32 v8, v17, v29
	v_exp_f32_e32 v6, v6
	v_and_b32_e32 v25, 0xffff0000, v25
	v_mul_f32_e32 v8, v51, v8
	v_fmac_f32_e32 v25, v10, v8
	v_mul_f32_e32 v8, v22, v22
	v_mul_f32_e32 v9, v23, v23
	v_add_f32_e32 v4, 1.0, v4
	v_cndmask_b32_e64 v45, v45, v63, s[6:7]
	v_fmac_f32_e32 v8, v46, v46
	v_fmac_f32_e32 v9, v47, v47
	v_rcp_f32_e32 v4, v4
	v_add_f32_e32 v8, v8, v9
	v_mul_f32_e32 v9, v24, v24
	v_lshlrev_b32_e32 v29, 16, v45
	v_add_f32_e32 v6, 1.0, v6
	v_fmac_f32_e32 v9, v56, v56
	v_mul_f32_e32 v5, v17, v29
	v_rcp_f32_e32 v6, v6
	v_add_f32_e32 v8, v9, v8
	v_mul_f32_e32 v9, v25, v25
	v_lshlrev_b32_e32 v15, 16, v31
	v_and_b32_e32 v30, 0xffff0000, v45
	v_mul_f32_e32 v5, v42, v5
	v_fmac_f32_e32 v9, v57, v57
	v_fmac_f32_e32 v15, v4, v5
	v_mul_f32_e32 v4, v17, v30
	v_add_f32_e32 v8, v9, v8
	v_cvt_pk_bf16_f32 v9, v46, v22
	v_and_b32_e32 v22, 0xffff0000, v31
	v_lshlrev_b32_e32 v31, 16, v37
	v_mul_f32_e32 v4, v43, v4
	v_fmac_f32_e32 v22, v6, v4
	v_mul_f32_e32 v4, v17, v31
	v_cvt_pk_bf16_f32 v10, v47, v23
	v_lshlrev_b32_e32 v23, 16, v38
	v_and_b32_e32 v37, 0xffff0000, v37
	v_mul_f32_e32 v4, v32, v4
	v_fmac_f32_e32 v23, v0, v4
	v_mul_f32_e32 v0, v17, v37
	v_cvt_pk_bf16_f32 v11, v56, v24
	v_and_b32_e32 v24, 0xffff0000, v38
	v_mul_f32_e32 v0, v33, v0
	v_fmac_f32_e32 v24, v1, v0
	v_mul_f32_e32 v0, 0xbfb8aa3b, v2
	v_exp_f32_e32 v0, v0
	v_mul_f32_e32 v2, 0xbfb8aa3b, v3
	v_exp_f32_e32 v2, v2
	v_lshlrev_b32_e32 v38, 16, v36
	v_add_f32_e32 v0, 1.0, v0
	v_rcp_f32_e32 v0, v0
	v_add_f32_e32 v2, 1.0, v2
	v_mul_f32_e32 v1, v17, v38
	v_rcp_f32_e32 v2, v2
	v_cvt_pk_bf16_f32 v12, v57, v25
	v_lshlrev_b32_e32 v25, 16, v39
	v_and_b32_e32 v36, 0xffff0000, v36
	v_mul_f32_e32 v1, v34, v1
	v_fmac_f32_e32 v25, v0, v1
	v_mul_f32_e32 v0, v17, v36
	v_and_b32_e32 v26, 0xffff0000, v39
	v_mul_f32_e32 v0, v35, v0
	v_fmac_f32_e32 v26, v2, v0
	v_mul_f32_e32 v0, v14, v14
	v_mul_f32_e32 v1, v22, v22
	v_fmac_f32_e32 v0, v13, v13
	v_fmac_f32_e32 v1, v15, v15
	v_add_f32_e32 v0, v0, v1
	v_mul_f32_e32 v1, v24, v24
	v_fmac_f32_e32 v1, v23, v23
	v_add_f32_e32 v0, v1, v0
	v_mul_f32_e32 v1, v26, v26
	v_fmac_f32_e32 v1, v25, v25
	v_add_f32_e32 v0, v1, v0
	v_add_f32_e32 v17, v0, v8
	v_cvt_pk_bf16_f32 v0, v13, v14
	v_cvt_pk_bf16_f32 v1, v15, v22
	v_cvt_pk_bf16_f32 v8, v23, v24
	v_cvt_pk_bf16_f32 v13, v25, v26
	v_mov_b32_e32 v15, 0
	v_mov_b32_e32 v6, 0
	v_mov_b32_dpp v5, v13 row_ror:8 row_mask:0xf bank_mask:0xf
	v_mov_b32_dpp v15, v12 row_ror:8 row_mask:0xf bank_mask:0xf
	v_cndmask_b32_e64 v5, v5, v12, s[6:7]
	ds_bpermute_b32 v12, v134, v17
	v_mov_b32_dpp v6, v9 row_ror:8 row_mask:0xf bank_mask:0xf
	v_mov_b32_dpp v7, v10 row_ror:8 row_mask:0xf bank_mask:0xf
	v_mov_b32_dpp v2, v0 row_ror:8 row_mask:0xf bank_mask:0xf
	v_mov_b32_dpp v3, v1 row_ror:8 row_mask:0xf bank_mask:0xf
	v_mov_b32_dpp v4, v8 row_ror:8 row_mask:0xf bank_mask:0xf
	v_cndmask_b32_e64 v6, v0, v6, s[6:7]
	v_cndmask_b32_e64 v7, v1, v7, s[6:7]
	v_lshl_add_u64 v[0:1], s[36:37], 0, v[18:19]
	v_mov_b32_dpp v14, v11 row_ror:8 row_mask:0xf bank_mask:0xf
	v_cndmask_b32_e64 v3, v3, v10, s[6:7]
	v_cndmask_b32_e64 v4, v4, v11, s[6:7]
	v_lshl_add_u64 v[10:11], v[0:1], 0, v[162:163]
	s_waitcnt lgkmcnt(0)
	v_add_f32_e32 v0, v17, v12
	ds_bpermute_b32 v1, v135, v0
	v_cndmask_b32_e64 v2, v2, v9, s[6:7]
	global_store_dwordx4 v[10:11], v[2:5], off
	v_cndmask_b32_e64 v8, v8, v14, s[6:7]
	v_cndmask_b32_e64 v9, v13, v15, s[6:7]
	v_lshl_add_u64 v[2:3], s[36:37], 0, v[20:21]
	v_lshl_add_u64 v[2:3], v[2:3], 0, v[162:163]
	global_store_dwordx4 v[2:3], v[6:9], off
	s_and_saveexec_b64 s[56:57], s[8:9]
	s_cbranch_execz .LBB0_873
	v_ashrrev_i32_e32 v17, 31, v16
	v_lshl_add_u64 v[2:3], v[16:17], 2, s[18:19]
	s_waitcnt lgkmcnt(0)
	v_add_f32_e32 v0, v0, v1
	global_atomic_add_f32 v[2:3], v0, off
	s_branch .LBB0_873

; #define PG8_STAGE(bufoff, gbase, voff) do { _Pragma("unroll") for (int _i = 0; _i < 2; ++_i) \
;         __builtin_amdgcn_global_load_lds((const unsigned*)((const char*)(gbase) + (voff)[_i]), (LAS unsigned*)(lds + (bufoff) + ldsw + _i * 8192), 16, 0, 0); } while (0)
; #define PG8_LDA(dst, b, h) do { _Pragma("unroll") for (int m = 0; m < 4; ++m) _Pragma("unroll") for (int k = 0; k < 2; ++k) dst[m][k] = *(const LAS bf16x8*)(lds + PG8_SA(b, h) + aoff + m * 2048 + k * 1024); } while (0)
; #define PG8_LDB(dst, b, h) do { _Pragma("unroll") for (int n = 0; n < 2; ++n) _Pragma("unroll") for (int k = 0; k < 2; ++k) dst[n][k] = *(const LAS bf16x8*)(lds + PG8_SB(b, h) + boff + n * 2048 + k * 1024); } while (0)
; #define PG8_WAIT_V(n) asm volatile("s_waitcnt vmcnt(" #n ")" ::: "memory")
; #define PG8_WAIT_L(n) asm volatile("s_waitcnt lgkmcnt(" #n ")" ::: "memory")
; #define PG8_BAR __builtin_amdgcn_s_barrier()
; #define PG8_SCHED __builtin_amdgcn_sched_barrier(0)
; template <class Epi>
; __device__ __forceinline__ void gemm_phase(LAS unsigned char* lds, const Gemm g, const StaticOrder& S, const Epi& E) {
;     ...
;             PG8_LDB(B0, 0, 0); PG8_SCHED; PG8_LDA(At, 0, 0); PG8_STAGE(PG8_SA(1, 1), a1 + hstep, voffA);
;             PG8_WAIT_L(8); PG8_BAR; PG8_WAIT_L(0); PG8_MMA(0, 0, At, B0); PG8_BAR; PG8_SCHED;
;             PG8_LDB(B1, 0, 1); PG8_STAGE(PG8_SB(0, 0), b2, voffB0);
;             PG8_BAR; PG8_WAIT_L(0); PG8_MMA(0, 1, At, B1); PG8_BAR;
;             PG8_LDA(At, 0, 1); PG8_STAGE(PG8_SA(0, 0), a2, voffA);
;             PG8_BAR; PG8_WAIT_L(0); PG8_MMA(1, 0, At, B0); PG8_BAR; PG8_SCHED;
;             PG8_STAGE(PG8_SB(0, 1), b2, voffB1);
;             PG8_WAIT_V(6); PG8_BAR; PG8_MMA(1, 1, At, B1); PG8_BAR;
;             PG8_LDB(B0, 1, 0); PG8_SCHED; PG8_LDA(At, 1, 0); PG8_STAGE(PG8_SA(0, 1), a2 + hstep, voffA);
;             PG8_WAIT_L(8); PG8_BAR; PG8_WAIT_L(0); PG8_MMA(0, 0, At, B0); PG8_BAR; PG8_SCHED;
;             PG8_LDB(B1, 1, 1); PG8_STAGE(PG8_SB(1, 0), b3, voffB0);
;             PG8_BAR; PG8_WAIT_L(0); PG8_MMA(0, 1, At, B1); PG8_BAR;
;             PG8_LDA(At, 1, 1); PG8_STAGE(PG8_SA(1, 0), a3, voffA);
;             PG8_BAR; PG8_WAIT_L(0); PG8_MMA(1, 0, At, B0); PG8_BAR; PG8_SCHED;
;             PG8_STAGE(PG8_SB(1, 1), b3, voffB1);
;             PG8_WAIT_V(6); PG8_BAR; PG8_MMA(1, 1, At, B1); PG8_BAR;
.LBB0_962:
	ds_read_b128 v[146:149], v158
	ds_read_b128 v[150:153], v158 offset:1024
	ds_read_b128 v[162:165], v158 offset:2048
	ds_read_b128 v[166:169], v158 offset:3072
	s_add_u32 s33, s46, 0xfff80080
	s_addc_u32 s48, s47, -1
	s_cmp_eq_u32 s77, 28
	s_cselect_b32 s49, s37, s48
	s_cselect_b32 s48, s72, s33
	s_cselect_b32 s51, s19, s75
	s_cselect_b32 s50, s73, s74
	v_lshl_add_u64 v[204:205], s[46:47], 0, v[140:141]
	s_add_i32 m0, s45, 0xc000
	ds_read_b128 v[170:173], v159
	ds_read_b128 v[174:177], v159 offset:1024
	ds_read_b128 v[178:181], v159 offset:2048
	ds_read_b128 v[182:185], v159 offset:3072
	ds_read_b128 v[186:189], v159 offset:4096
	ds_read_b128 v[190:193], v159 offset:5120
	ds_read_b128 v[194:197], v159 offset:6144
	ds_read_b128 v[198:201], v159 offset:7168
	global_load_lds_dwordx4 v[204:205], off
	v_lshl_add_u64 v[204:205], s[46:47], 0, v[142:143]
	s_add_i32 m0, s45, 0xe000
	s_nop 0
	global_load_lds_dwordx4 v[204:205], off
	s_waitcnt lgkmcnt(8)
	s_barrier
	s_waitcnt lgkmcnt(0)
	v_mfma_f32_16x16x32_bf16 v[124:127], v[146:149], v[170:173], v[124:127]
	v_mfma_f32_16x16x32_bf16 v[120:123], v[162:165], v[170:173], v[120:123]
	v_mfma_f32_16x16x32_bf16 v[108:111], v[146:149], v[178:181], v[108:111]
	v_mfma_f32_16x16x32_bf16 v[104:107], v[162:165], v[178:181], v[104:107]
	v_mfma_f32_16x16x32_bf16 v[92:95], v[146:149], v[186:189], v[92:95]
	v_mfma_f32_16x16x32_bf16 v[88:91], v[162:165], v[186:189], v[88:91]
	v_mfma_f32_16x16x32_bf16 v[76:79], v[146:149], v[194:197], v[76:79]
	v_mfma_f32_16x16x32_bf16 v[72:75], v[162:165], v[194:197], v[72:75]
	v_mfma_f32_16x16x32_bf16 v[124:127], v[150:153], v[174:177], v[124:127]
	v_mfma_f32_16x16x32_bf16 v[120:123], v[166:169], v[174:177], v[120:123]
	v_mfma_f32_16x16x32_bf16 v[108:111], v[150:153], v[182:185], v[108:111]
	v_mfma_f32_16x16x32_bf16 v[104:107], v[166:169], v[182:185], v[104:107]
	v_mfma_f32_16x16x32_bf16 v[92:95], v[150:153], v[190:193], v[92:95]
	v_mfma_f32_16x16x32_bf16 v[88:91], v[166:169], v[190:193], v[88:91]
	v_mfma_f32_16x16x32_bf16 v[76:79], v[150:153], v[198:201], v[76:79]
	v_mfma_f32_16x16x32_bf16 v[72:75], v[166:169], v[198:201], v[72:75]
	s_barrier
	s_add_i32 s33, s68, s57
	v_lshl_add_u64 v[220:221], s[50:51], 0, v[134:135]
	s_mov_b32 m0, s33
	ds_read_b128 v[204:207], v160
	ds_read_b128 v[208:211], v160 offset:1024
	ds_read_b128 v[212:215], v160 offset:2048
	ds_read_b128 v[216:219], v160 offset:3072
	global_load_lds_dwordx4 v[220:221], off
	v_lshl_add_u64 v[222:223], s[50:51], 0, v[128:129]
	s_add_i32 m0, s33, 0x2000
	s_nop 0
	global_load_lds_dwordx4 v[222:223], off
	s_barrier
	s_waitcnt lgkmcnt(0)
	v_mfma_f32_16x16x32_bf16 v[116:119], v[204:207], v[170:173], v[116:119]
	v_mfma_f32_16x16x32_bf16 v[112:115], v[212:215], v[170:173], v[112:115]
	v_mfma_f32_16x16x32_bf16 v[100:103], v[204:207], v[178:181], v[100:103]
	v_mfma_f32_16x16x32_bf16 v[96:99], v[212:215], v[178:181], v[96:99]
	v_mfma_f32_16x16x32_bf16 v[84:87], v[204:207], v[186:189], v[84:87]
	v_mfma_f32_16x16x32_bf16 v[80:83], v[212:215], v[186:189], v[80:83]
	v_mfma_f32_16x16x32_bf16 v[68:71], v[204:207], v[194:197], v[68:71]
	v_mfma_f32_16x16x32_bf16 v[64:67], v[212:215], v[194:197], v[64:67]
	v_mfma_f32_16x16x32_bf16 v[116:119], v[208:211], v[174:177], v[116:119]
	v_mfma_f32_16x16x32_bf16 v[112:115], v[216:219], v[174:177], v[112:115]
	v_mfma_f32_16x16x32_bf16 v[100:103], v[208:211], v[182:185], v[100:103]
	v_mfma_f32_16x16x32_bf16 v[96:99], v[216:219], v[182:185], v[96:99]
	v_mfma_f32_16x16x32_bf16 v[84:87], v[208:211], v[190:193], v[84:87]
	v_mfma_f32_16x16x32_bf16 v[80:83], v[216:219], v[190:193], v[80:83]
	v_mfma_f32_16x16x32_bf16 v[68:71], v[208:211], v[198:201], v[68:71]
	v_mfma_f32_16x16x32_bf16 v[64:67], v[216:219], v[198:201], v[64:67]
	s_mov_b32 m0, s45
	v_lshl_add_u64 v[224:225], s[48:49], 0, v[138:139]
	s_barrier
	ds_read_b128 v[170:173], v159 offset:16384
	ds_read_b128 v[174:177], v159 offset:17408
	ds_read_b128 v[178:181], v159 offset:18432
	ds_read_b128 v[182:185], v159 offset:19456
	ds_read_b128 v[186:189], v159 offset:20480
	ds_read_b128 v[190:193], v159 offset:21504
	ds_read_b128 v[194:197], v159 offset:22528
	ds_read_b128 v[198:201], v159 offset:23552
	global_load_lds_dwordx4 v[224:225], off
	v_lshl_add_u64 v[226:227], s[48:49], 0, v[132:133]
	s_mov_b32 m0, s59
	s_nop 0
	global_load_lds_dwordx4 v[226:227], off
	s_barrier
	s_waitcnt lgkmcnt(0)
	v_mfma_f32_16x16x32_bf16 v[60:63], v[146:149], v[170:173], v[60:63]
	v_mfma_f32_16x16x32_bf16 v[56:59], v[162:165], v[170:173], v[56:59]
	v_mfma_f32_16x16x32_bf16 v[44:47], v[146:149], v[178:181], v[44:47]
	v_mfma_f32_16x16x32_bf16 v[40:43], v[162:165], v[178:181], v[40:43]
	v_mfma_f32_16x16x32_bf16 v[28:31], v[146:149], v[186:189], v[28:31]
	v_mfma_f32_16x16x32_bf16 v[24:27], v[162:165], v[186:189], v[24:27]
	v_mfma_f32_16x16x32_bf16 v[12:15], v[146:149], v[194:197], v[12:15]
	v_mfma_f32_16x16x32_bf16 v[8:11], v[162:165], v[194:197], v[8:11]
	v_mfma_f32_16x16x32_bf16 v[60:63], v[150:153], v[174:177], v[60:63]
	v_mfma_f32_16x16x32_bf16 v[56:59], v[166:169], v[174:177], v[56:59]
	v_mfma_f32_16x16x32_bf16 v[44:47], v[150:153], v[182:185], v[44:47]
	v_mfma_f32_16x16x32_bf16 v[40:43], v[166:169], v[182:185], v[40:43]
	v_mfma_f32_16x16x32_bf16 v[28:31], v[150:153], v[190:193], v[28:31]
	v_mfma_f32_16x16x32_bf16 v[24:27], v[166:169], v[190:193], v[24:27]
	v_mfma_f32_16x16x32_bf16 v[12:15], v[150:153], v[198:201], v[12:15]
	v_mfma_f32_16x16x32_bf16 v[8:11], v[166:169], v[198:201], v[8:11]
	s_barrier
	s_add_i32 s33, s69, s57
	v_lshl_add_u64 v[228:229], s[50:51], 0, v[136:137]
	s_mov_b32 m0, s33
	v_lshl_add_u64 v[230:231], s[50:51], 0, v[130:131]
	global_load_lds_dwordx4 v[228:229], off
	s_add_i32 m0, s33, 0x2000
	s_nop 0
	global_load_lds_dwordx4 v[230:231], off
	s_waitcnt vmcnt(6)
	s_barrier
; #define PG8_STAGE(bufoff, gbase, voff) do { _Pragma("unroll") for (int _i = 0; _i < 2; ++_i) \
;         __builtin_amdgcn_global_load_lds((const unsigned*)((const char*)(gbase) + (voff)[_i]), (LAS unsigned*)(lds + (bufoff) + ldsw + _i * 8192), 16, 0, 0); } while (0)
; #define PG8_LDA(dst, b, h) do { _Pragma("unroll") for (int m = 0; m < 4; ++m) _Pragma("unroll") for (int k = 0; k < 2; ++k) dst[m][k] = *(const LAS bf16x8*)(lds + PG8_SA(b, h) + aoff + m * 2048 + k * 1024); } while (0)
; #define PG8_LDB(dst, b, h) do { _Pragma("unroll") for (int n = 0; n < 2; ++n) _Pragma("unroll") for (int k = 0; k < 2; ++k) dst[n][k] = *(const LAS bf16x8*)(lds + PG8_SB(b, h) + boff + n * 2048 + k * 1024); } while (0)
; #define PG8_MMA(ai, bj, At, Bt) do { __builtin_amdgcn_s_setprio(1); _Pragma("unroll") for (int m = 0; m < 4; ++m) _Pragma("unroll") for (int n = 0; n < 2; ++n) _Pragma("unroll") for (int k = 0; k < 2; ++k) \
;         acc[ai][bj][m][n] = __builtin_amdgcn_mfma_f32_16x16x32_bf16(Bt[n][k], At[m][k], acc[ai][bj][m][n], 0, 0, 0); __builtin_amdgcn_s_setprio(0); } while (0)
; #define PG8_WAIT_V(n) asm volatile("s_waitcnt vmcnt(" #n ")" ::: "memory")
; #define PG8_WAIT_L(n) asm volatile("s_waitcnt lgkmcnt(" #n ")" ::: "memory")
; #define PG8_BAR __builtin_amdgcn_s_barrier()
; #define PG8_SCHED __builtin_amdgcn_sched_barrier(0)
; template <class Epi>
; __device__ __forceinline__ void gemm_phase(LAS unsigned char* lds, const Gemm g, const StaticOrder& S, const Epi& E) {
;     ...
;             PG8_WAIT_V(6); PG8_BAR; PG8_MMA(1, 1, At, B1); PG8_BAR;
;             PG8_LDB(B0, 1, 0); PG8_SCHED; PG8_LDA(At, 1, 0); PG8_STAGE(PG8_SA(0, 1), a2 + hstep, voffA);
;             PG8_WAIT_L(8); PG8_BAR; PG8_WAIT_L(0); PG8_MMA(0, 0, At, B0); PG8_BAR; PG8_SCHED;
;             PG8_LDB(B1, 1, 1); PG8_STAGE(PG8_SB(1, 0), b3, voffB0);
;             PG8_BAR; PG8_WAIT_L(0); PG8_MMA(0, 1, At, B1); PG8_BAR;
;             PG8_LDA(At, 1, 1); PG8_STAGE(PG8_SA(1, 0), a3, voffA);
;             PG8_BAR; PG8_WAIT_L(0); PG8_MMA(1, 0, At, B0); PG8_BAR; PG8_SCHED;
;             PG8_STAGE(PG8_SB(1, 1), b3, voffB1);
;             PG8_WAIT_V(6); PG8_BAR; PG8_MMA(1, 1, At, B1); PG8_BAR;
	v_mfma_f32_16x16x32_bf16 v[52:55], v[204:207], v[170:173], v[52:55]
	v_mfma_f32_16x16x32_bf16 v[48:51], v[212:215], v[170:173], v[48:51]
	v_mfma_f32_16x16x32_bf16 v[36:39], v[204:207], v[178:181], v[36:39]
	v_mfma_f32_16x16x32_bf16 v[32:35], v[212:215], v[178:181], v[32:35]
	v_mfma_f32_16x16x32_bf16 v[20:23], v[204:207], v[186:189], v[20:23]
	v_mfma_f32_16x16x32_bf16 v[16:19], v[212:215], v[186:189], v[16:19]
	v_mfma_f32_16x16x32_bf16 v[4:7], v[204:207], v[194:197], v[4:7]
	v_mfma_f32_16x16x32_bf16 v[0:3], v[212:215], v[194:197], v[0:3]
	v_mfma_f32_16x16x32_bf16 v[52:55], v[208:211], v[174:177], v[52:55]
	v_mfma_f32_16x16x32_bf16 v[48:51], v[216:219], v[174:177], v[48:51]
	v_mfma_f32_16x16x32_bf16 v[36:39], v[208:211], v[182:185], v[36:39]
	v_mfma_f32_16x16x32_bf16 v[32:35], v[216:219], v[182:185], v[32:35]
	v_mfma_f32_16x16x32_bf16 v[20:23], v[208:211], v[190:193], v[20:23]
	v_mfma_f32_16x16x32_bf16 v[16:19], v[216:219], v[190:193], v[16:19]
	v_mfma_f32_16x16x32_bf16 v[4:7], v[208:211], v[198:201], v[4:7]
	v_mfma_f32_16x16x32_bf16 v[0:3], v[216:219], v[198:201], v[0:3]
	s_add_i32 s33, 0, 0x18000
	v_add_u32_e32 v166, s33, v155
	s_barrier
	ds_read_b128 v[146:149], v166
	ds_read_b128 v[150:153], v166 offset:1024
	ds_read_b128 v[162:165], v166 offset:2048
	ds_read_b128 v[166:169], v166 offset:3072
	s_add_u32 s48, s48, 0x80000
	s_addc_u32 s49, s49, 0
	s_mov_b32 m0, s60
	v_lshl_add_u64 v[204:205], s[48:49], 0, v[138:139]
	ds_read_b128 v[170:173], v159 offset:32768
	ds_read_b128 v[174:177], v159 offset:33792
	ds_read_b128 v[178:181], v159 offset:34816
	ds_read_b128 v[182:185], v159 offset:35840
	ds_read_b128 v[186:189], v159 offset:36864
	ds_read_b128 v[190:193], v159 offset:37888
	ds_read_b128 v[194:197], v159 offset:38912
	ds_read_b128 v[198:201], v159 offset:39936
	global_load_lds_dwordx4 v[204:205], off
	v_lshl_add_u64 v[204:205], s[48:49], 0, v[132:133]
	s_mov_b32 m0, s61
	s_nop 0
	global_load_lds_dwordx4 v[204:205], off
	s_waitcnt lgkmcnt(8)
	s_barrier
	s_waitcnt lgkmcnt(0)
	v_mfma_f32_16x16x32_bf16 v[124:127], v[146:149], v[170:173], v[124:127]
	v_mfma_f32_16x16x32_bf16 v[120:123], v[162:165], v[170:173], v[120:123]
	v_mfma_f32_16x16x32_bf16 v[108:111], v[146:149], v[178:181], v[108:111]
	v_mfma_f32_16x16x32_bf16 v[104:107], v[162:165], v[178:181], v[104:107]
	v_mfma_f32_16x16x32_bf16 v[92:95], v[146:149], v[186:189], v[92:95]
	v_mfma_f32_16x16x32_bf16 v[88:91], v[162:165], v[186:189], v[88:91]
	v_mfma_f32_16x16x32_bf16 v[76:79], v[146:149], v[194:197], v[76:79]
	v_mfma_f32_16x16x32_bf16 v[72:75], v[162:165], v[194:197], v[72:75]
	v_mfma_f32_16x16x32_bf16 v[124:127], v[150:153], v[174:177], v[124:127]
	v_mfma_f32_16x16x32_bf16 v[120:123], v[166:169], v[174:177], v[120:123]
	v_mfma_f32_16x16x32_bf16 v[108:111], v[150:153], v[182:185], v[108:111]
	v_mfma_f32_16x16x32_bf16 v[104:107], v[166:169], v[182:185], v[104:107]
	v_mfma_f32_16x16x32_bf16 v[92:95], v[150:153], v[190:193], v[92:95]
	v_mfma_f32_16x16x32_bf16 v[88:91], v[166:169], v[190:193], v[88:91]
	v_mfma_f32_16x16x32_bf16 v[76:79], v[150:153], v[198:201], v[76:79]
	v_mfma_f32_16x16x32_bf16 v[72:75], v[166:169], v[198:201], v[72:75]
	s_barrier
	s_add_i32 s48, 0, 0x1c000
	s_add_i32 s33, s33, s57
	v_add_u32_e32 v216, s48, v155
	v_lshl_add_u64 v[220:221], v[220:221], 0, s[16:17]
	s_mov_b32 m0, s33
	ds_read_b128 v[204:207], v216
	ds_read_b128 v[208:211], v216 offset:1024
	ds_read_b128 v[212:215], v216 offset:2048
	ds_read_b128 v[216:219], v216 offset:3072
	global_load_lds_dwordx4 v[220:221], off
	v_lshl_add_u64 v[220:221], v[222:223], 0, s[16:17]
	s_add_i32 m0, s33, 0x2000
	s_nop 0
	global_load_lds_dwordx4 v[220:221], off
	s_barrier
	s_waitcnt lgkmcnt(0)
	v_mfma_f32_16x16x32_bf16 v[116:119], v[204:207], v[170:173], v[116:119]
	v_mfma_f32_16x16x32_bf16 v[112:115], v[212:215], v[170:173], v[112:115]
	v_mfma_f32_16x16x32_bf16 v[100:103], v[204:207], v[178:181], v[100:103]
	v_mfma_f32_16x16x32_bf16 v[96:99], v[212:215], v[178:181], v[96:99]
	v_mfma_f32_16x16x32_bf16 v[84:87], v[204:207], v[186:189], v[84:87]
	v_mfma_f32_16x16x32_bf16 v[80:83], v[212:215], v[186:189], v[80:83]
	v_mfma_f32_16x16x32_bf16 v[68:71], v[204:207], v[194:197], v[68:71]
	v_mfma_f32_16x16x32_bf16 v[64:67], v[212:215], v[194:197], v[64:67]
	v_mfma_f32_16x16x32_bf16 v[116:119], v[208:211], v[174:177], v[116:119]
	v_mfma_f32_16x16x32_bf16 v[112:115], v[216:219], v[174:177], v[112:115]
	v_mfma_f32_16x16x32_bf16 v[100:103], v[208:211], v[182:185], v[100:103]
	v_mfma_f32_16x16x32_bf16 v[96:99], v[216:219], v[182:185], v[96:99]
	v_mfma_f32_16x16x32_bf16 v[84:87], v[208:211], v[190:193], v[84:87]
	v_mfma_f32_16x16x32_bf16 v[80:83], v[216:219], v[190:193], v[80:83]
	v_mfma_f32_16x16x32_bf16 v[68:71], v[208:211], v[198:201], v[68:71]
	v_mfma_f32_16x16x32_bf16 v[64:67], v[216:219], v[198:201], v[64:67]
	s_mov_b32 m0, s63
	v_lshl_add_u64 v[220:221], v[224:225], 0, s[16:17]
	s_barrier
	ds_read_b128 v[170:173], v159 offset:49152
	ds_read_b128 v[174:177], v159 offset:50176
	ds_read_b128 v[178:181], v159 offset:51200
	ds_read_b128 v[182:185], v159 offset:52224
	ds_read_b128 v[186:189], v159 offset:53248
	ds_read_b128 v[190:193], v159 offset:54272
	ds_read_b128 v[194:197], v159 offset:55296
	ds_read_b128 v[198:201], v159 offset:56320
	global_load_lds_dwordx4 v[220:221], off
	v_lshl_add_u64 v[220:221], v[226:227], 0, s[16:17]
	s_mov_b32 m0, s64
	s_nop 0
	global_load_lds_dwordx4 v[220:221], off
	s_barrier
; __device__ __forceinline__ unsigned cvt_pk_bf16(float lo, float hi) { unsigned r; asm volatile("v_cvt_pk_bf16_f32 %0, %1, %2" : "=v"(r) : "v"(lo), "v"(hi)); return r; }
; #define PG8_STAGE(bufoff, gbase, voff) do { _Pragma("unroll") for (int _i = 0; _i < 2; ++_i) \
;         __builtin_amdgcn_global_load_lds((const unsigned*)((const char*)(gbase) + (voff)[_i]), (LAS unsigned*)(lds + (bufoff) + ldsw + _i * 8192), 16, 0, 0); } while (0)
; #define PG8_WAIT_V(n) asm volatile("s_waitcnt vmcnt(" #n ")" ::: "memory")
; #define PG8_WAIT_L(n) asm volatile("s_waitcnt lgkmcnt(" #n ")" ::: "memory")
; #define PG8_BAR __builtin_amdgcn_s_barrier()
;     __device__ __forceinline__ void operator()(const f32x4 (&acc)[2][2][4][2], const Unit& u, int wr, int wc, int fr, int fq) const {
;     ...
;             for (int m = 0; m < 4; ++m) { const int row = row0 + ai * HALF + m * 16;
;                 const float rs = ssin ? __builtin_amdgcn_rsqf(ssin[row] * (1.f / D) + EPS) : 1.0f; float sq = 0.f; u32x4 w[2];
; #pragma unroll
;                 for (int bj = 0; bj < 2; ++bj) { f32x4 v0 = acc[ai][bj][m][0] * rs, v1 = acc[ai][bj][m][1] * rs;
;                     if (ACT == 1) {
; #pragma unroll
;                         for (int j = 0; j < 4; ++j) { const float a = fmaxf(v0[j], 0.f), b = fmaxf(v1[j], 0.f); v0[j] = a * a; v1[j] = b * b; } }
;                     sq += (v0[0] * v0[0] + v0[1] * v0[1]) + (v0[2] * v0[2] + v0[3] * v0[3]) + (v1[0] * v1[0] + v1[1] * v1[1]) + (v1[2] * v1[2] + v1[3] * v1[3]);
;                     w[bj].x = cvt_pk_bf16(v0[0], v0[1]); w[bj].y = cvt_pk_bf16(v0[2], v0[3]); w[bj].z = cvt_pk_bf16(v1[0], v1[1]); w[bj].w = cvt_pk_bf16(v1[2], v1[3]); }
;                 store_pair_lines(O, ldc, row, fr, col0, w[0], w[1]);
; template <class Epi>
; __device__ __forceinline__ void gemm_phase(LAS unsigned char* lds, const Gemm g, const StaticOrder& S, const Epi& E) {
;     ...
;             PG8_WAIT_L(8); PG8_BAR; PG8_WAIT_L(0); PG8_MMA(0, 0, At, B0); PG8_BAR; PG8_SCHED;
;             PG8_LDB(B1, 1, 1); PG8_STAGE(PG8_SB(1, 0), b3, voffB0);
;             PG8_BAR; PG8_WAIT_L(0); PG8_MMA(0, 1, At, B1); PG8_BAR;
;             PG8_LDA(At, 1, 1); PG8_STAGE(PG8_SA(1, 0), a3, voffA);
;             PG8_BAR; PG8_WAIT_L(0); PG8_MMA(1, 0, At, B0); PG8_BAR; PG8_SCHED;
;             PG8_STAGE(PG8_SB(1, 1), b3, voffB1);
;             PG8_WAIT_V(6); PG8_BAR; PG8_MMA(1, 1, At, B1); PG8_BAR;
;         }
	s_waitcnt lgkmcnt(0)
	v_mfma_f32_16x16x32_bf16 v[60:63], v[146:149], v[170:173], v[60:63]
	v_mfma_f32_16x16x32_bf16 v[56:59], v[162:165], v[170:173], v[56:59]
	v_mfma_f32_16x16x32_bf16 v[44:47], v[146:149], v[178:181], v[44:47]
	v_mfma_f32_16x16x32_bf16 v[40:43], v[162:165], v[178:181], v[40:43]
	v_mfma_f32_16x16x32_bf16 v[28:31], v[146:149], v[186:189], v[28:31]
	v_mfma_f32_16x16x32_bf16 v[24:27], v[162:165], v[186:189], v[24:27]
	v_mfma_f32_16x16x32_bf16 v[12:15], v[146:149], v[194:197], v[12:15]
	v_mfma_f32_16x16x32_bf16 v[8:11], v[162:165], v[194:197], v[8:11]
	v_mfma_f32_16x16x32_bf16 v[60:63], v[150:153], v[174:177], v[60:63]
	v_mfma_f32_16x16x32_bf16 v[56:59], v[166:169], v[174:177], v[56:59]
	v_mfma_f32_16x16x32_bf16 v[44:47], v[150:153], v[182:185], v[44:47]
	v_mfma_f32_16x16x32_bf16 v[40:43], v[166:169], v[182:185], v[40:43]
	v_mfma_f32_16x16x32_bf16 v[28:31], v[150:153], v[190:193], v[28:31]
	v_mfma_f32_16x16x32_bf16 v[24:27], v[166:169], v[190:193], v[24:27]
	v_mfma_f32_16x16x32_bf16 v[12:15], v[150:153], v[198:201], v[12:15]
	v_mfma_f32_16x16x32_bf16 v[8:11], v[166:169], v[198:201], v[8:11]
	s_barrier
	s_add_i32 s33, s48, s57
	v_lshl_add_u64 v[146:147], v[228:229], 0, s[16:17]
	s_mov_b32 m0, s33
	s_nop 0
	global_load_lds_dwordx4 v[146:147], off
	v_lshl_add_u64 v[146:147], v[230:231], 0, s[16:17]
	s_add_i32 m0, s33, 0x2000
	s_nop 0
	global_load_lds_dwordx4 v[146:147], off
	s_waitcnt vmcnt(6)
	s_barrier
	v_mfma_f32_16x16x32_bf16 v[52:55], v[204:207], v[170:173], v[52:55]
	v_mfma_f32_16x16x32_bf16 v[48:51], v[212:215], v[170:173], v[48:51]
	v_mfma_f32_16x16x32_bf16 v[36:39], v[204:207], v[178:181], v[36:39]
	v_mfma_f32_16x16x32_bf16 v[32:35], v[212:215], v[178:181], v[32:35]
	v_mfma_f32_16x16x32_bf16 v[20:23], v[204:207], v[186:189], v[20:23]
	v_mfma_f32_16x16x32_bf16 v[16:19], v[212:215], v[186:189], v[16:19]
	v_mfma_f32_16x16x32_bf16 v[4:7], v[204:207], v[194:197], v[4:7]
	v_mfma_f32_16x16x32_bf16 v[0:3], v[212:215], v[194:197], v[0:3]
	v_mfma_f32_16x16x32_bf16 v[52:55], v[208:211], v[174:177], v[52:55]
	v_mfma_f32_16x16x32_bf16 v[48:51], v[216:219], v[174:177], v[48:51]
	v_mfma_f32_16x16x32_bf16 v[36:39], v[208:211], v[182:185], v[36:39]
	v_mfma_f32_16x16x32_bf16 v[32:35], v[216:219], v[182:185], v[32:35]
	v_mfma_f32_16x16x32_bf16 v[20:23], v[208:211], v[190:193], v[20:23]
	v_mfma_f32_16x16x32_bf16 v[16:19], v[216:219], v[190:193], v[16:19]
	v_mfma_f32_16x16x32_bf16 v[4:7], v[208:211], v[198:201], v[4:7]
	v_mfma_f32_16x16x32_bf16 v[0:3], v[216:219], v[198:201], v[0:3]
	s_add_i32 s77, s77, 2
	s_add_u32 s46, s46, 0x100
	s_addc_u32 s47, s47, 0
	s_add_u32 s74, s74, 0x100
	s_addc_u32 s75, s75, 0
	s_cmp_gt_u32 s77, 29
	s_barrier
	s_cbranch_scc0 .LBB0_962
	s_lshl_b32 s19, s44, 8
	s_add_i32 s19, s19, s65
	v_or_b32_e32 v152, s19, v154
	v_ashrrev_i32_e32 v153, 31, v152
	v_lshl_add_u64 v[150:151], v[152:153], 2, s[10:11]
	global_load_dword v153, v[150:151], off
	v_or_b32_e32 v180, 16, v152
	v_ashrrev_i32_e32 v181, 31, v180
	v_lshl_add_u64 v[182:183], v[180:181], 2, s[10:11]
	global_load_dword v179, v[182:183], off
	v_or_b32_e32 v180, 32, v152
	v_ashrrev_i32_e32 v181, 31, v180
	v_lshl_add_u64 v[182:183], v[180:181], 2, s[10:11]
	global_load_dword v184, v[182:183], off
	v_or_b32_e32 v180, 48, v152
	v_ashrrev_i32_e32 v181, 31, v180
	v_lshl_add_u64 v[182:183], v[180:181], 2, s[10:11]
	global_load_dword v185, v[182:183], off
	global_load_dword v186, v[150:151], off offset:512
	global_load_dword v187, v[150:151], off offset:576
	global_load_dword v188, v[150:151], off offset:640
	global_load_dword v189, v[150:151], off offset:704
	v_lshl_or_b32 v148, s71, 8, v157
	v_mov_b32_e32 v169, 0
	v_mov_b64_e32 v[146:147], s[8:9]
	v_ashrrev_i32_e32 v149, 31, v148
	v_or_b32_e32 v164, s19, v156
	v_lshlrev_b64 v[148:149], 1, v[148:149]
	v_mad_i64_i32 v[162:163], s[46:47], v164, s70, v[146:147]
	v_or_b32_e32 v165, 8, v164
	v_or_b32_e32 v164, 16, v152
	v_lshl_add_u64 v[162:163], v[162:163], 0, v[148:149]
	v_mad_i64_i32 v[166:167], s[46:47], v165, s70, v[146:147]
	v_ashrrev_i32_e32 v165, 31, v164
	v_lshl_add_u64 v[166:167], v[166:167], 0, v[148:149]
	v_lshl_add_u64 v[170:171], v[164:165], 2, s[10:11]
	s_and_b64 vcc, exec, s[40:41]
	s_mov_b32 s71, s18
	s_mov_b32 s44, s36
	s_mov_b64 s[48:49], s[42:43]
	s_waitcnt vmcnt(7)
	v_fmamk_f32 v153, v153, 0x3a000000, v161
	v_rsq_f32_e32 v168, v153
	v_mov_b32_e32 v153, 0
	v_pk_mul_f32 v[124:125], v[124:125], v[168:169] op_sel_hi:[1,0]
	v_pk_mul_f32 v[120:121], v[120:121], v[168:169] op_sel_hi:[1,0]
	v_pk_mul_f32 v[118:119], v[118:119], v[168:169] op_sel_hi:[1,0]
	v_pk_mul_f32 v[116:117], v[116:117], v[168:169] op_sel_hi:[1,0]
	v_pk_mul_f32 v[126:127], v[126:127], v[168:169] op_sel_hi:[1,0]
	v_pk_mul_f32 v[122:123], v[122:123], v[168:169] op_sel_hi:[1,0]
	v_pk_mul_f32 v[114:115], v[114:115], v[168:169] op_sel_hi:[1,0]
	v_pk_mul_f32 v[112:113], v[112:113], v[168:169] op_sel_hi:[1,0]
	v_cvt_pk_bf16_f32 v124, v124, v125
	v_cvt_pk_bf16_f32 v125, v126, v127
	v_cvt_pk_bf16_f32 v120, v120, v121
	v_cvt_pk_bf16_f32 v121, v122, v123
	v_cvt_pk_bf16_f32 v116, v116, v117
	v_cvt_pk_bf16_f32 v117, v118, v119
	s_nop 0
	v_cvt_pk_bf16_f32 v118, v112, v113
	v_cvt_pk_bf16_f32 v119, v114, v115
	s_nop 0
	v_mov_b32_dpp v169, v124 row_ror:8 row_mask:0xf bank_mask:0xf
	v_mov_b32_dpp v172, v125 row_ror:8 row_mask:0xf bank_mask:0xf
	v_mov_b32_dpp v175, v116 row_ror:8 row_mask:0xf bank_mask:0xf
	v_mov_b32_dpp v176, v117 row_ror:8 row_mask:0xf bank_mask:0xf
	v_mov_b32_dpp v177, v118 row_ror:8 row_mask:0xf bank_mask:0xf
	v_mov_b32_dpp v178, v119 row_ror:8 row_mask:0xf bank_mask:0xf
	v_mov_b32_dpp v173, v120 row_ror:8 row_mask:0xf bank_mask:0xf
	v_mov_b32_dpp v174, v121 row_ror:8 row_mask:0xf bank_mask:0xf
	v_cndmask_b32_e64 v112, v175, v124, s[6:7]
	v_cndmask_b32_e64 v113, v176, v125, s[6:7]
	v_cndmask_b32_e64 v114, v177, v120, s[6:7]
	v_cndmask_b32_e64 v115, v178, v121, s[6:7]
	v_cndmask_b32_e64 v116, v116, v169, s[6:7]
	v_cndmask_b32_e64 v117, v117, v172, s[6:7]
	v_cndmask_b32_e64 v118, v118, v173, s[6:7]
	v_cndmask_b32_e64 v119, v119, v174, s[6:7]
	global_store_dwordx4 v[162:163], v[112:115], off
	global_store_dwordx4 v[166:167], v[116:119], off
	s_waitcnt vmcnt(8)
; __device__ __forceinline__ unsigned cvt_pk_bf16(float lo, float hi) { unsigned r; asm volatile("v_cvt_pk_bf16_f32 %0, %1, %2" : "=v"(r) : "v"(lo), "v"(hi)); return r; }
; __device__ __forceinline__ unsigned dpp_ror8(unsigned x) { return (unsigned)__builtin_amdgcn_update_dpp(0, (int)x, 0x128, 0xf, 0xf, false); }
; __device__ __forceinline__ void store_pair_lines(bf16_t* O, int ldc, int row, int fr, int col0, u32x4 wA, u32x4 wB) {
;     const u32x4 sA = {dpp_ror8(wA.x), dpp_ror8(wA.y), dpp_ror8(wA.z), dpp_ror8(wA.w)}, sB = {dpp_ror8(wB.x), dpp_ror8(wB.y), dpp_ror8(wB.z), dpp_ror8(wB.w)};
;     const bool lo = fr < 8;
;     const u32x4 o1 = lo ? wA : sB, o2 = lo ? sA : wB;
;     const int r1 = row - fr + (fr & 7), cb = col0 + (lo ? 0 : 8);
;     *(u32x4*)(O + (size_t)r1 * ldc + cb) = o1;
;     *(u32x4*)(O + (size_t)(r1 + 8) * ldc + cb) = o2;
; }
;     __device__ __forceinline__ void operator()(const f32x4 (&acc)[2][2][4][2], const Unit& u, int wr, int wc, int fr, int fq) const {
;     ...
;             for (int m = 0; m < 4; ++m) { const int row = row0 + ai * HALF + m * 16;
;                 const float rs = ssin ? __builtin_amdgcn_rsqf(ssin[row] * (1.f / D) + EPS) : 1.0f; float sq = 0.f; u32x4 w[2];
; #pragma unroll
;                 for (int bj = 0; bj < 2; ++bj) { f32x4 v0 = acc[ai][bj][m][0] * rs, v1 = acc[ai][bj][m][1] * rs;
;                     if (ACT == 1) {
; #pragma unroll
;                         for (int j = 0; j < 4; ++j) { const float a = fmaxf(v0[j], 0.f), b = fmaxf(v1[j], 0.f); v0[j] = a * a; v1[j] = b * b; } }
;                     sq += (v0[0] * v0[0] + v0[1] * v0[1]) + (v0[2] * v0[2] + v0[3] * v0[3]) + (v1[0] * v1[0] + v1[1] * v1[1]) + (v1[2] * v1[2] + v1[3] * v1[3]);
;                     w[bj].x = cvt_pk_bf16(v0[0], v0[1]); w[bj].y = cvt_pk_bf16(v0[2], v0[3]); w[bj].z = cvt_pk_bf16(v1[0], v1[1]); w[bj].w = cvt_pk_bf16(v1[2], v1[3]); }
;                 store_pair_lines(O, ldc, row, fr, col0, w[0], w[1]);
	s_nop 0
	v_mov_b32_e32 v118, v179
	s_nop 1
	v_or_b32_e32 v112, 32, v152
	v_mov_b32_e32 v119, 0
	v_sub_u32_e32 v114, v164, v154
	v_ashrrev_i32_e32 v113, 31, v112
	v_add_u32_e32 v120, v114, v156
	v_lshl_add_u64 v[114:115], v[112:113], 2, s[10:11]
	v_mad_i64_i32 v[116:117], s[46:47], v120, s70, v[146:147]
	v_add_u32_e32 v113, 8, v120
	v_lshl_add_u64 v[116:117], v[116:117], 0, v[148:149]
	v_mad_i64_i32 v[120:121], s[46:47], v113, s70, v[146:147]
	v_lshl_add_u64 v[120:121], v[120:121], 0, v[148:149]
	v_fmamk_f32 v118, v118, 0x3a000000, v161
	v_rsq_f32_e32 v118, v118
	s_nop 0
	v_pk_mul_f32 v[108:109], v[108:109], v[118:119] op_sel_hi:[1,0]
	v_pk_mul_f32 v[104:105], v[104:105], v[118:119] op_sel_hi:[1,0]
	v_pk_mul_f32 v[102:103], v[102:103], v[118:119] op_sel_hi:[1,0]
	v_pk_mul_f32 v[100:101], v[100:101], v[118:119] op_sel_hi:[1,0]
	v_pk_mul_f32 v[110:111], v[110:111], v[118:119] op_sel_hi:[1,0]
	v_pk_mul_f32 v[106:107], v[106:107], v[118:119] op_sel_hi:[1,0]
	v_pk_mul_f32 v[98:99], v[98:99], v[118:119] op_sel_hi:[1,0]
	v_pk_mul_f32 v[96:97], v[96:97], v[118:119] op_sel_hi:[1,0]
	v_cvt_pk_bf16_f32 v108, v108, v109
	v_cvt_pk_bf16_f32 v109, v110, v111
	v_cvt_pk_bf16_f32 v104, v104, v105
	v_cvt_pk_bf16_f32 v105, v106, v107
	v_cvt_pk_bf16_f32 v100, v100, v101
	v_cvt_pk_bf16_f32 v101, v102, v103
	s_nop 0
	v_cvt_pk_bf16_f32 v102, v96, v97
	v_cvt_pk_bf16_f32 v103, v98, v99
	s_nop 0
	v_mov_b32_dpp v119, v108 row_ror:8 row_mask:0xf bank_mask:0xf
	v_mov_b32_dpp v122, v109 row_ror:8 row_mask:0xf bank_mask:0xf
	v_mov_b32_dpp v125, v100 row_ror:8 row_mask:0xf bank_mask:0xf
	v_mov_b32_dpp v126, v101 row_ror:8 row_mask:0xf bank_mask:0xf
	v_mov_b32_dpp v127, v102 row_ror:8 row_mask:0xf bank_mask:0xf
	v_mov_b32_dpp v153, v103 row_ror:8 row_mask:0xf bank_mask:0xf
	v_mov_b32_dpp v123, v104 row_ror:8 row_mask:0xf bank_mask:0xf
	v_mov_b32_dpp v124, v105 row_ror:8 row_mask:0xf bank_mask:0xf
	v_cndmask_b32_e64 v96, v125, v108, s[6:7]
	v_cndmask_b32_e64 v97, v126, v109, s[6:7]
	v_cndmask_b32_e64 v98, v127, v104, s[6:7]
	v_cndmask_b32_e64 v99, v153, v105, s[6:7]
	v_cndmask_b32_e64 v100, v100, v119, s[6:7]
	v_cndmask_b32_e64 v101, v101, v122, s[6:7]
	v_cndmask_b32_e64 v102, v102, v123, s[6:7]
	v_cndmask_b32_e64 v103, v103, v124, s[6:7]
	global_store_dwordx4 v[116:117], v[96:99], off
	global_store_dwordx4 v[120:121], v[100:103], off
	s_waitcnt vmcnt(9)
	s_nop 0
	v_mov_b32_e32 v102, v184
	s_nop 1
	v_or_b32_e32 v96, 48, v152
	v_mov_b32_e32 v103, 0
	v_sub_u32_e32 v98, v112, v154
	v_ashrrev_i32_e32 v97, 31, v96
	v_add_u32_e32 v104, v98, v156
	v_lshl_add_u64 v[98:99], v[96:97], 2, s[10:11]
	v_mad_i64_i32 v[100:101], s[46:47], v104, s70, v[146:147]
	v_add_u32_e32 v97, 8, v104
	v_lshl_add_u64 v[100:101], v[100:101], 0, v[148:149]
	v_mad_i64_i32 v[104:105], s[46:47], v97, s70, v[146:147]
	v_lshl_add_u64 v[104:105], v[104:105], 0, v[148:149]
	v_fmamk_f32 v102, v102, 0x3a000000, v161
	v_rsq_f32_e32 v102, v102
	s_nop 0
	v_pk_mul_f32 v[92:93], v[92:93], v[102:103] op_sel_hi:[1,0]
	v_pk_mul_f32 v[88:89], v[88:89], v[102:103] op_sel_hi:[1,0]
	v_pk_mul_f32 v[86:87], v[86:87], v[102:103] op_sel_hi:[1,0]
	v_pk_mul_f32 v[84:85], v[84:85], v[102:103] op_sel_hi:[1,0]
	v_pk_mul_f32 v[94:95], v[94:95], v[102:103] op_sel_hi:[1,0]
	v_pk_mul_f32 v[90:91], v[90:91], v[102:103] op_sel_hi:[1,0]
	v_pk_mul_f32 v[82:83], v[82:83], v[102:103] op_sel_hi:[1,0]
	v_pk_mul_f32 v[80:81], v[80:81], v[102:103] op_sel_hi:[1,0]
	v_cvt_pk_bf16_f32 v92, v92, v93
	v_cvt_pk_bf16_f32 v93, v94, v95
	v_cvt_pk_bf16_f32 v88, v88, v89
	v_cvt_pk_bf16_f32 v89, v90, v91
	v_cvt_pk_bf16_f32 v84, v84, v85
	v_cvt_pk_bf16_f32 v85, v86, v87
	s_nop 0
	v_cvt_pk_bf16_f32 v86, v80, v81
	v_cvt_pk_bf16_f32 v87, v82, v83
	s_nop 0
	v_mov_b32_dpp v103, v92 row_ror:8 row_mask:0xf bank_mask:0xf
	v_mov_b32_dpp v106, v93 row_ror:8 row_mask:0xf bank_mask:0xf
	v_mov_b32_dpp v109, v84 row_ror:8 row_mask:0xf bank_mask:0xf
	v_mov_b32_dpp v110, v85 row_ror:8 row_mask:0xf bank_mask:0xf
	v_mov_b32_dpp v111, v86 row_ror:8 row_mask:0xf bank_mask:0xf
	v_mov_b32_dpp v113, v87 row_ror:8 row_mask:0xf bank_mask:0xf
	v_mov_b32_dpp v107, v88 row_ror:8 row_mask:0xf bank_mask:0xf
	v_mov_b32_dpp v108, v89 row_ror:8 row_mask:0xf bank_mask:0xf
	v_cndmask_b32_e64 v80, v109, v92, s[6:7]
	v_cndmask_b32_e64 v81, v110, v93, s[6:7]
	v_cndmask_b32_e64 v82, v111, v88, s[6:7]
	v_cndmask_b32_e64 v83, v113, v89, s[6:7]
	v_cndmask_b32_e64 v84, v84, v103, s[6:7]
	v_cndmask_b32_e64 v85, v85, v106, s[6:7]
	v_cndmask_b32_e64 v86, v86, v107, s[6:7]
	v_cndmask_b32_e64 v87, v87, v108, s[6:7]
	global_store_dwordx4 v[100:101], v[80:83], off
	global_store_dwordx4 v[104:105], v[84:87], off
	s_waitcnt vmcnt(10)
; __device__ __forceinline__ unsigned cvt_pk_bf16(float lo, float hi) { unsigned r; asm volatile("v_cvt_pk_bf16_f32 %0, %1, %2" : "=v"(r) : "v"(lo), "v"(hi)); return r; }
; __device__ __forceinline__ unsigned dpp_ror8(unsigned x) { return (unsigned)__builtin_amdgcn_update_dpp(0, (int)x, 0x128, 0xf, 0xf, false); }
; __device__ __forceinline__ void store_pair_lines(bf16_t* O, int ldc, int row, int fr, int col0, u32x4 wA, u32x4 wB) {
;     const u32x4 sA = {dpp_ror8(wA.x), dpp_ror8(wA.y), dpp_ror8(wA.z), dpp_ror8(wA.w)}, sB = {dpp_ror8(wB.x), dpp_ror8(wB.y), dpp_ror8(wB.z), dpp_ror8(wB.w)};
;     const bool lo = fr < 8;
;     const u32x4 o1 = lo ? wA : sB, o2 = lo ? sA : wB;
;     const int r1 = row - fr + (fr & 7), cb = col0 + (lo ? 0 : 8);
;     *(u32x4*)(O + (size_t)r1 * ldc + cb) = o1;
;     *(u32x4*)(O + (size_t)(r1 + 8) * ldc + cb) = o2;
; }
;     __device__ __forceinline__ void operator()(const f32x4 (&acc)[2][2][4][2], const Unit& u, int wr, int wc, int fr, int fq) const {
;     ...
;             for (int m = 0; m < 4; ++m) { const int row = row0 + ai * HALF + m * 16;
;                 const float rs = ssin ? __builtin_amdgcn_rsqf(ssin[row] * (1.f / D) + EPS) : 1.0f; float sq = 0.f; u32x4 w[2];
; #pragma unroll
;                 for (int bj = 0; bj < 2; ++bj) { f32x4 v0 = acc[ai][bj][m][0] * rs, v1 = acc[ai][bj][m][1] * rs;
;                     if (ACT == 1) {
; #pragma unroll
;                         for (int j = 0; j < 4; ++j) { const float a = fmaxf(v0[j], 0.f), b = fmaxf(v1[j], 0.f); v0[j] = a * a; v1[j] = b * b; } }
;                     sq += (v0[0] * v0[0] + v0[1] * v0[1]) + (v0[2] * v0[2] + v0[3] * v0[3]) + (v1[0] * v1[0] + v1[1] * v1[1]) + (v1[2] * v1[2] + v1[3] * v1[3]);
;                     w[bj].x = cvt_pk_bf16(v0[0], v0[1]); w[bj].y = cvt_pk_bf16(v0[2], v0[3]); w[bj].z = cvt_pk_bf16(v1[0], v1[1]); w[bj].w = cvt_pk_bf16(v1[2], v1[3]); }
;                 store_pair_lines(O, ldc, row, fr, col0, w[0], w[1]);
	s_nop 0
	v_mov_b32_e32 v82, v185
	s_nop 1
	v_mov_b32_e32 v83, 0
	v_sub_u32_e32 v80, v96, v154
	v_add_u32_e32 v84, v80, v156
	v_mad_i64_i32 v[80:81], s[46:47], v84, s70, v[146:147]
	v_add_u32_e32 v84, 8, v84
	v_lshl_add_u64 v[80:81], v[80:81], 0, v[148:149]
	v_mad_i64_i32 v[84:85], s[46:47], v84, s70, v[146:147]
	v_lshl_add_u64 v[84:85], v[84:85], 0, v[148:149]
	v_fmamk_f32 v82, v82, 0x3a000000, v161
	v_rsq_f32_e32 v82, v82
	s_nop 0
	v_pk_mul_f32 v[76:77], v[76:77], v[82:83] op_sel_hi:[1,0]
	v_pk_mul_f32 v[72:73], v[72:73], v[82:83] op_sel_hi:[1,0]
	v_pk_mul_f32 v[70:71], v[70:71], v[82:83] op_sel_hi:[1,0]
	v_pk_mul_f32 v[68:69], v[68:69], v[82:83] op_sel_hi:[1,0]
	v_pk_mul_f32 v[78:79], v[78:79], v[82:83] op_sel_hi:[1,0]
	v_pk_mul_f32 v[74:75], v[74:75], v[82:83] op_sel_hi:[1,0]
	v_pk_mul_f32 v[66:67], v[66:67], v[82:83] op_sel_hi:[1,0]
	v_pk_mul_f32 v[64:65], v[64:65], v[82:83] op_sel_hi:[1,0]
	v_cvt_pk_bf16_f32 v76, v76, v77
	v_cvt_pk_bf16_f32 v77, v78, v79
	v_cvt_pk_bf16_f32 v72, v72, v73
	v_cvt_pk_bf16_f32 v73, v74, v75
	v_cvt_pk_bf16_f32 v68, v68, v69
	v_cvt_pk_bf16_f32 v69, v70, v71
	s_nop 0
	v_cvt_pk_bf16_f32 v70, v64, v65
	v_cvt_pk_bf16_f32 v71, v66, v67
	s_nop 0
	v_mov_b32_dpp v83, v76 row_ror:8 row_mask:0xf bank_mask:0xf
	v_mov_b32_dpp v86, v77 row_ror:8 row_mask:0xf bank_mask:0xf
	v_mov_b32_dpp v89, v68 row_ror:8 row_mask:0xf bank_mask:0xf
	v_mov_b32_dpp v90, v69 row_ror:8 row_mask:0xf bank_mask:0xf
	v_mov_b32_dpp v91, v70 row_ror:8 row_mask:0xf bank_mask:0xf
	v_mov_b32_dpp v92, v71 row_ror:8 row_mask:0xf bank_mask:0xf
	v_mov_b32_dpp v87, v72 row_ror:8 row_mask:0xf bank_mask:0xf
	v_mov_b32_dpp v88, v73 row_ror:8 row_mask:0xf bank_mask:0xf
	v_cndmask_b32_e64 v64, v89, v76, s[6:7]
	v_cndmask_b32_e64 v65, v90, v77, s[6:7]
	v_cndmask_b32_e64 v66, v91, v72, s[6:7]
	v_cndmask_b32_e64 v67, v92, v73, s[6:7]
	v_cndmask_b32_e64 v68, v68, v83, s[6:7]
	v_cndmask_b32_e64 v69, v69, v86, s[6:7]
	v_cndmask_b32_e64 v70, v70, v87, s[6:7]
	v_cndmask_b32_e64 v71, v71, v88, s[6:7]
	global_store_dwordx4 v[80:81], v[64:67], off
	global_store_dwordx4 v[84:85], v[68:71], off
	s_waitcnt vmcnt(11)
	s_nop 0
	v_mov_b32_e32 v66, v186
	s_nop 1
	v_sub_u32_e32 v64, v152, v154
	v_mov_b32_e32 v67, 0
	v_add_u32_e32 v77, v64, v156
	v_add_u32_e32 v64, 0x80, v77
	v_add_u32_e32 v68, 0x88, v77
	v_mad_i64_i32 v[64:65], s[46:47], v64, s70, v[146:147]
	v_mad_i64_i32 v[68:69], s[46:47], v68, s70, v[146:147]
	v_lshl_add_u64 v[64:65], v[64:65], 0, v[148:149]
	v_lshl_add_u64 v[68:69], v[68:69], 0, v[148:149]
	v_fmamk_f32 v66, v66, 0x3a000000, v161
	v_rsq_f32_e32 v66, v66
	s_nop 0
	v_pk_mul_f32 v[60:61], v[60:61], v[66:67] op_sel_hi:[1,0]
	v_pk_mul_f32 v[56:57], v[56:57], v[66:67] op_sel_hi:[1,0]
	v_pk_mul_f32 v[54:55], v[54:55], v[66:67] op_sel_hi:[1,0]
	v_pk_mul_f32 v[52:53], v[52:53], v[66:67] op_sel_hi:[1,0]
	v_pk_mul_f32 v[62:63], v[62:63], v[66:67] op_sel_hi:[1,0]
	v_pk_mul_f32 v[58:59], v[58:59], v[66:67] op_sel_hi:[1,0]
	v_pk_mul_f32 v[50:51], v[50:51], v[66:67] op_sel_hi:[1,0]
	v_pk_mul_f32 v[48:49], v[48:49], v[66:67] op_sel_hi:[1,0]
	v_cvt_pk_bf16_f32 v60, v60, v61
	v_cvt_pk_bf16_f32 v61, v62, v63
	v_cvt_pk_bf16_f32 v56, v56, v57
	v_cvt_pk_bf16_f32 v57, v58, v59
	v_cvt_pk_bf16_f32 v52, v52, v53
	v_cvt_pk_bf16_f32 v53, v54, v55
	s_nop 0
	v_cvt_pk_bf16_f32 v54, v48, v49
	v_cvt_pk_bf16_f32 v55, v50, v51
	s_nop 0
	v_mov_b32_dpp v67, v60 row_ror:8 row_mask:0xf bank_mask:0xf
	v_mov_b32_dpp v70, v61 row_ror:8 row_mask:0xf bank_mask:0xf
	v_mov_b32_dpp v73, v52 row_ror:8 row_mask:0xf bank_mask:0xf
	v_mov_b32_dpp v74, v53 row_ror:8 row_mask:0xf bank_mask:0xf
	v_mov_b32_dpp v75, v54 row_ror:8 row_mask:0xf bank_mask:0xf
	v_mov_b32_dpp v76, v55 row_ror:8 row_mask:0xf bank_mask:0xf
	v_mov_b32_dpp v71, v56 row_ror:8 row_mask:0xf bank_mask:0xf
	v_mov_b32_dpp v72, v57 row_ror:8 row_mask:0xf bank_mask:0xf
	v_cndmask_b32_e64 v48, v73, v60, s[6:7]
	v_cndmask_b32_e64 v49, v74, v61, s[6:7]
	v_cndmask_b32_e64 v50, v75, v56, s[6:7]
	v_cndmask_b32_e64 v51, v76, v57, s[6:7]
	v_cndmask_b32_e64 v52, v52, v67, s[6:7]
	v_cndmask_b32_e64 v53, v53, v70, s[6:7]
	v_cndmask_b32_e64 v54, v54, v71, s[6:7]
	v_cndmask_b32_e64 v55, v55, v72, s[6:7]
	global_store_dwordx4 v[64:65], v[48:51], off
	global_store_dwordx4 v[68:69], v[52:55], off
	s_waitcnt vmcnt(12)
; __device__ __forceinline__ unsigned cvt_pk_bf16(float lo, float hi) { unsigned r; asm volatile("v_cvt_pk_bf16_f32 %0, %1, %2" : "=v"(r) : "v"(lo), "v"(hi)); return r; }
; __device__ __forceinline__ unsigned dpp_ror8(unsigned x) { return (unsigned)__builtin_amdgcn_update_dpp(0, (int)x, 0x128, 0xf, 0xf, false); }
; #define PG8_WAIT_V(n) asm volatile("s_waitcnt vmcnt(" #n ")" ::: "memory")
; #define PG8_BAR __builtin_amdgcn_s_barrier()
; __device__ __forceinline__ void store_pair_lines(bf16_t* O, int ldc, int row, int fr, int col0, u32x4 wA, u32x4 wB) {
;     const u32x4 sA = {dpp_ror8(wA.x), dpp_ror8(wA.y), dpp_ror8(wA.z), dpp_ror8(wA.w)}, sB = {dpp_ror8(wB.x), dpp_ror8(wB.y), dpp_ror8(wB.z), dpp_ror8(wB.w)};
;     const bool lo = fr < 8;
;     const u32x4 o1 = lo ? wA : sB, o2 = lo ? sA : wB;
;     const int r1 = row - fr + (fr & 7), cb = col0 + (lo ? 0 : 8);
;     *(u32x4*)(O + (size_t)r1 * ldc + cb) = o1;
;     *(u32x4*)(O + (size_t)(r1 + 8) * ldc + cb) = o2;
; }
;     __device__ __forceinline__ void operator()(const f32x4 (&acc)[2][2][4][2], const Unit& u, int wr, int wc, int fr, int fq) const {
;     ...
;             for (int m = 0; m < 4; ++m) { const int row = row0 + ai * HALF + m * 16;
;                 const float rs = ssin ? __builtin_amdgcn_rsqf(ssin[row] * (1.f / D) + EPS) : 1.0f; float sq = 0.f; u32x4 w[2];
; #pragma unroll
;                 for (int bj = 0; bj < 2; ++bj) { f32x4 v0 = acc[ai][bj][m][0] * rs, v1 = acc[ai][bj][m][1] * rs;
;                     if (ACT == 1) {
; #pragma unroll
;                         for (int j = 0; j < 4; ++j) { const float a = fmaxf(v0[j], 0.f), b = fmaxf(v1[j], 0.f); v0[j] = a * a; v1[j] = b * b; } }
;                     sq += (v0[0] * v0[0] + v0[1] * v0[1]) + (v0[2] * v0[2] + v0[3] * v0[3]) + (v1[0] * v1[0] + v1[1] * v1[1]) + (v1[2] * v1[2] + v1[3] * v1[3]);
;                     w[bj].x = cvt_pk_bf16(v0[0], v0[1]); w[bj].y = cvt_pk_bf16(v0[2], v0[3]); w[bj].z = cvt_pk_bf16(v1[0], v1[1]); w[bj].w = cvt_pk_bf16(v1[2], v1[3]); }
;                 store_pair_lines(O, ldc, row, fr, col0, w[0], w[1]);
; template <class Epi>
; __device__ __forceinline__ void gemm_phase(LAS unsigned char* lds, const Gemm g, const StaticOrder& S, const Epi& E) {
;     ...
;     PG8_WAIT_V(0);
;     if (wr == 0) PG8_BAR;
;     PG8_BAR;
	s_nop 0
	v_mov_b32_e32 v50, v187
	s_nop 1
	v_mov_b32_e32 v51, 0
	v_add_u32_e32 v48, 0x90, v77
	v_add_u32_e32 v52, 0x98, v77
	v_mad_i64_i32 v[48:49], s[46:47], v48, s70, v[146:147]
	v_mad_i64_i32 v[52:53], s[46:47], v52, s70, v[146:147]
	v_lshl_add_u64 v[48:49], v[48:49], 0, v[148:149]
	v_lshl_add_u64 v[52:53], v[52:53], 0, v[148:149]
	v_fmamk_f32 v50, v50, 0x3a000000, v161
	v_rsq_f32_e32 v50, v50
	s_nop 0
	v_pk_mul_f32 v[44:45], v[44:45], v[50:51] op_sel_hi:[1,0]
	v_pk_mul_f32 v[40:41], v[40:41], v[50:51] op_sel_hi:[1,0]
	v_pk_mul_f32 v[38:39], v[38:39], v[50:51] op_sel_hi:[1,0]
	v_pk_mul_f32 v[36:37], v[36:37], v[50:51] op_sel_hi:[1,0]
	v_pk_mul_f32 v[46:47], v[46:47], v[50:51] op_sel_hi:[1,0]
	v_pk_mul_f32 v[42:43], v[42:43], v[50:51] op_sel_hi:[1,0]
	v_pk_mul_f32 v[34:35], v[34:35], v[50:51] op_sel_hi:[1,0]
	v_pk_mul_f32 v[32:33], v[32:33], v[50:51] op_sel_hi:[1,0]
	v_cvt_pk_bf16_f32 v44, v44, v45
	v_cvt_pk_bf16_f32 v45, v46, v47
	v_cvt_pk_bf16_f32 v40, v40, v41
	v_cvt_pk_bf16_f32 v41, v42, v43
	v_cvt_pk_bf16_f32 v36, v36, v37
	v_cvt_pk_bf16_f32 v37, v38, v39
	s_nop 0
	v_cvt_pk_bf16_f32 v38, v32, v33
	v_cvt_pk_bf16_f32 v39, v34, v35
	s_nop 0
	v_mov_b32_dpp v51, v44 row_ror:8 row_mask:0xf bank_mask:0xf
	v_mov_b32_dpp v54, v45 row_ror:8 row_mask:0xf bank_mask:0xf
	v_mov_b32_dpp v57, v36 row_ror:8 row_mask:0xf bank_mask:0xf
	v_mov_b32_dpp v58, v37 row_ror:8 row_mask:0xf bank_mask:0xf
	v_mov_b32_dpp v59, v38 row_ror:8 row_mask:0xf bank_mask:0xf
	v_mov_b32_dpp v60, v39 row_ror:8 row_mask:0xf bank_mask:0xf
	v_mov_b32_dpp v55, v40 row_ror:8 row_mask:0xf bank_mask:0xf
	v_mov_b32_dpp v56, v41 row_ror:8 row_mask:0xf bank_mask:0xf
	v_cndmask_b32_e64 v32, v57, v44, s[6:7]
	v_cndmask_b32_e64 v33, v58, v45, s[6:7]
	v_cndmask_b32_e64 v34, v59, v40, s[6:7]
	v_cndmask_b32_e64 v35, v60, v41, s[6:7]
	v_cndmask_b32_e64 v36, v36, v51, s[6:7]
	v_cndmask_b32_e64 v37, v37, v54, s[6:7]
	v_cndmask_b32_e64 v38, v38, v55, s[6:7]
	v_cndmask_b32_e64 v39, v39, v56, s[6:7]
	global_store_dwordx4 v[48:49], v[32:35], off
	global_store_dwordx4 v[52:53], v[36:39], off
	s_waitcnt vmcnt(13)
	s_nop 0
	v_mov_b32_e32 v34, v188
	s_nop 1
	v_mov_b32_e32 v35, 0
	v_add_u32_e32 v32, 0xa0, v77
	v_add_u32_e32 v36, 0xa8, v77
	v_mad_i64_i32 v[32:33], s[46:47], v32, s70, v[146:147]
	v_mad_i64_i32 v[36:37], s[46:47], v36, s70, v[146:147]
	v_lshl_add_u64 v[32:33], v[32:33], 0, v[148:149]
	v_lshl_add_u64 v[36:37], v[36:37], 0, v[148:149]
	s_mov_b64 s[46:47], s[38:39]
	v_fmamk_f32 v34, v34, 0x3a000000, v161
	v_rsq_f32_e32 v34, v34
	s_nop 0
	v_pk_mul_f32 v[28:29], v[28:29], v[34:35] op_sel_hi:[1,0]
	v_pk_mul_f32 v[24:25], v[24:25], v[34:35] op_sel_hi:[1,0]
	v_pk_mul_f32 v[22:23], v[22:23], v[34:35] op_sel_hi:[1,0]
	v_pk_mul_f32 v[20:21], v[20:21], v[34:35] op_sel_hi:[1,0]
	v_pk_mul_f32 v[30:31], v[30:31], v[34:35] op_sel_hi:[1,0]
	v_pk_mul_f32 v[26:27], v[26:27], v[34:35] op_sel_hi:[1,0]
	v_pk_mul_f32 v[18:19], v[18:19], v[34:35] op_sel_hi:[1,0]
	v_pk_mul_f32 v[16:17], v[16:17], v[34:35] op_sel_hi:[1,0]
	v_cvt_pk_bf16_f32 v28, v28, v29
	v_cvt_pk_bf16_f32 v29, v30, v31
	v_cvt_pk_bf16_f32 v24, v24, v25
	v_cvt_pk_bf16_f32 v25, v26, v27
	v_cvt_pk_bf16_f32 v20, v20, v21
	v_cvt_pk_bf16_f32 v21, v22, v23
	s_nop 0
	v_cvt_pk_bf16_f32 v22, v16, v17
	v_cvt_pk_bf16_f32 v23, v18, v19
	s_nop 0
	v_mov_b32_dpp v35, v28 row_ror:8 row_mask:0xf bank_mask:0xf
	v_mov_b32_dpp v38, v29 row_ror:8 row_mask:0xf bank_mask:0xf
	v_mov_b32_dpp v41, v20 row_ror:8 row_mask:0xf bank_mask:0xf
	v_mov_b32_dpp v42, v21 row_ror:8 row_mask:0xf bank_mask:0xf
	v_mov_b32_dpp v43, v22 row_ror:8 row_mask:0xf bank_mask:0xf
	v_mov_b32_dpp v44, v23 row_ror:8 row_mask:0xf bank_mask:0xf
	v_mov_b32_dpp v39, v24 row_ror:8 row_mask:0xf bank_mask:0xf
	v_mov_b32_dpp v40, v25 row_ror:8 row_mask:0xf bank_mask:0xf
	v_cndmask_b32_e64 v16, v41, v28, s[6:7]
	v_cndmask_b32_e64 v17, v42, v29, s[6:7]
	v_cndmask_b32_e64 v18, v43, v24, s[6:7]
	v_cndmask_b32_e64 v19, v44, v25, s[6:7]
	v_cndmask_b32_e64 v20, v20, v35, s[6:7]
	v_cndmask_b32_e64 v21, v21, v38, s[6:7]
	v_cndmask_b32_e64 v22, v22, v39, s[6:7]
	v_cndmask_b32_e64 v23, v23, v40, s[6:7]
	global_store_dwordx4 v[32:33], v[16:19], off
	global_store_dwordx4 v[36:37], v[20:23], off
	s_waitcnt vmcnt(14)
	s_nop 0
	v_mov_b32_e32 v18, v189
	s_nop 1
	v_mov_b32_e32 v19, 0
	v_add_u32_e32 v16, 0xb0, v77
	v_add_u32_e32 v20, 0xb8, v77
	v_mad_i64_i32 v[16:17], s[38:39], v16, s70, v[146:147]
	v_mad_i64_i32 v[20:21], s[38:39], v20, s70, v[146:147]
	v_lshl_add_u64 v[16:17], v[16:17], 0, v[148:149]
	v_lshl_add_u64 v[20:21], v[20:21], 0, v[148:149]
	v_fmamk_f32 v18, v18, 0x3a000000, v161
	v_rsq_f32_e32 v18, v18
	s_nop 0
	v_pk_mul_f32 v[12:13], v[12:13], v[18:19] op_sel_hi:[1,0]
	v_pk_mul_f32 v[8:9], v[8:9], v[18:19] op_sel_hi:[1,0]
	v_pk_mul_f32 v[6:7], v[6:7], v[18:19] op_sel_hi:[1,0]
	v_pk_mul_f32 v[4:5], v[4:5], v[18:19] op_sel_hi:[1,0]
	v_pk_mul_f32 v[14:15], v[14:15], v[18:19] op_sel_hi:[1,0]
	v_pk_mul_f32 v[10:11], v[10:11], v[18:19] op_sel_hi:[1,0]
	v_pk_mul_f32 v[2:3], v[2:3], v[18:19] op_sel_hi:[1,0]
	v_pk_mul_f32 v[0:1], v[0:1], v[18:19] op_sel_hi:[1,0]
	v_cvt_pk_bf16_f32 v12, v12, v13
	v_cvt_pk_bf16_f32 v13, v14, v15
	v_cvt_pk_bf16_f32 v8, v8, v9
	v_cvt_pk_bf16_f32 v9, v10, v11
	v_cvt_pk_bf16_f32 v4, v4, v5
	v_cvt_pk_bf16_f32 v5, v6, v7
	s_nop 0
	v_cvt_pk_bf16_f32 v6, v0, v1
	v_cvt_pk_bf16_f32 v7, v2, v3
	s_nop 0
	v_mov_b32_dpp v19, v12 row_ror:8 row_mask:0xf bank_mask:0xf
	v_mov_b32_dpp v22, v13 row_ror:8 row_mask:0xf bank_mask:0xf
	v_mov_b32_dpp v25, v4 row_ror:8 row_mask:0xf bank_mask:0xf
	v_mov_b32_dpp v26, v5 row_ror:8 row_mask:0xf bank_mask:0xf
	v_mov_b32_dpp v27, v6 row_ror:8 row_mask:0xf bank_mask:0xf
	v_mov_b32_dpp v28, v7 row_ror:8 row_mask:0xf bank_mask:0xf
	v_mov_b32_dpp v23, v8 row_ror:8 row_mask:0xf bank_mask:0xf
	v_mov_b32_dpp v24, v9 row_ror:8 row_mask:0xf bank_mask:0xf
	v_cndmask_b32_e64 v0, v25, v12, s[6:7]
	v_cndmask_b32_e64 v1, v26, v13, s[6:7]
	v_cndmask_b32_e64 v2, v27, v8, s[6:7]
	v_cndmask_b32_e64 v3, v28, v9, s[6:7]
	v_cndmask_b32_e64 v4, v4, v19, s[6:7]
	v_cndmask_b32_e64 v5, v5, v22, s[6:7]
	v_cndmask_b32_e64 v6, v6, v23, s[6:7]
	v_cndmask_b32_e64 v7, v7, v24, s[6:7]
	global_store_dwordx4 v[16:17], v[0:3], off
	global_store_dwordx4 v[20:21], v[4:7], off
	s_cbranch_vccz .LBB0_958
	s_waitcnt vmcnt(0)
	s_cmpk_gt_u32 s52, 0xff
	s_cbranch_scc1 .LBB0_966
	s_barrier

; #define PG8_STAGE(bufoff, gbase, voff) do { _Pragma("unroll") for (int _i = 0; _i < 2; ++_i) \
;         __builtin_amdgcn_global_load_lds((const unsigned*)((const char*)(gbase) + (voff)[_i]), (LAS unsigned*)(lds + (bufoff) + ldsw + _i * 8192), 16, 0, 0); } while (0)
; #define PG8_LDA(dst, b, h) do { _Pragma("unroll") for (int m = 0; m < 4; ++m) _Pragma("unroll") for (int k = 0; k < 2; ++k) dst[m][k] = *(const LAS bf16x8*)(lds + PG8_SA(b, h) + aoff + m * 2048 + k * 1024); } while (0)
; #define PG8_LDB(dst, b, h) do { _Pragma("unroll") for (int n = 0; n < 2; ++n) _Pragma("unroll") for (int k = 0; k < 2; ++k) dst[n][k] = *(const LAS bf16x8*)(lds + PG8_SB(b, h) + boff + n * 2048 + k * 1024); } while (0)
; #define PG8_WAIT_V(n) asm volatile("s_waitcnt vmcnt(" #n ")" ::: "memory")
; #define PG8_WAIT_L(n) asm volatile("s_waitcnt lgkmcnt(" #n ")" ::: "memory")
; #define PG8_BAR __builtin_amdgcn_s_barrier()
; #define PG8_SCHED __builtin_amdgcn_sched_barrier(0)
; template <class Epi>
; __device__ __forceinline__ void gemm_phase(LAS unsigned char* lds, const Gemm g, const StaticOrder& S, const Epi& E) {
;     ...
;             PG8_LDB(B0, 0, 0); PG8_SCHED; PG8_LDA(At, 0, 0); PG8_STAGE(PG8_SA(1, 1), a1 + hstep, voffA);
;             PG8_WAIT_L(8); PG8_BAR; PG8_WAIT_L(0); PG8_MMA(0, 0, At, B0); PG8_BAR; PG8_SCHED;
;             PG8_LDB(B1, 0, 1); PG8_STAGE(PG8_SB(0, 0), b2, voffB0);
;             PG8_BAR; PG8_WAIT_L(0); PG8_MMA(0, 1, At, B1); PG8_BAR;
;             PG8_LDA(At, 0, 1); PG8_STAGE(PG8_SA(0, 0), a2, voffA);
;             PG8_BAR; PG8_WAIT_L(0); PG8_MMA(1, 0, At, B0); PG8_BAR; PG8_SCHED;
;             PG8_STAGE(PG8_SB(0, 1), b2, voffB1);
;             PG8_WAIT_V(6); PG8_BAR; PG8_MMA(1, 1, At, B1); PG8_BAR;
;             PG8_LDB(B0, 1, 0); PG8_SCHED; PG8_LDA(At, 1, 0); PG8_STAGE(PG8_SA(0, 1), a2 + hstep, voffA);
;             PG8_WAIT_L(8); PG8_BAR; PG8_WAIT_L(0); PG8_MMA(0, 0, At, B0); PG8_BAR; PG8_SCHED;
;             PG8_LDB(B1, 1, 1); PG8_STAGE(PG8_SB(1, 0), b3, voffB0);
;             PG8_BAR; PG8_WAIT_L(0); PG8_MMA(0, 1, At, B1); PG8_BAR;
;             PG8_LDA(At, 1, 1); PG8_STAGE(PG8_SA(1, 0), a3, voffA);
;             PG8_BAR; PG8_WAIT_L(0); PG8_MMA(1, 0, At, B0); PG8_BAR; PG8_SCHED;
;             PG8_STAGE(PG8_SB(1, 1), b3, voffB1);
;             PG8_WAIT_V(6); PG8_BAR; PG8_MMA(1, 1, At, B1); PG8_BAR;
.LBB0_1245:
	ds_read_b128 v[146:149], v154
	ds_read_b128 v[158:161], v154 offset:1024
	ds_read_b128 v[162:165], v154 offset:2048
	ds_read_b128 v[166:169], v154 offset:3072
	s_add_u32 s33, s46, 0xfff80080
	s_addc_u32 s48, s47, -1
	s_cmp_eq_u32 s73, 28
	s_cselect_b32 s49, s35, s48
	s_cselect_b32 s48, s43, s33
	s_cselect_b32 s51, s31, s72
	s_cselect_b32 s50, s70, s71
	v_lshl_add_u64 v[204:205], s[46:47], 0, v[140:141]
	s_add_i32 m0, s45, 0xc000
	ds_read_b128 v[170:173], v155
	ds_read_b128 v[174:177], v155 offset:1024
	ds_read_b128 v[178:181], v155 offset:2048
	ds_read_b128 v[182:185], v155 offset:3072
	ds_read_b128 v[186:189], v155 offset:4096
	ds_read_b128 v[190:193], v155 offset:5120
	ds_read_b128 v[194:197], v155 offset:6144
	ds_read_b128 v[198:201], v155 offset:7168
	global_load_lds_dwordx4 v[204:205], off
	v_lshl_add_u64 v[204:205], s[46:47], 0, v[142:143]
	s_add_i32 m0, s45, 0xe000
	s_nop 0
	global_load_lds_dwordx4 v[204:205], off
	s_waitcnt lgkmcnt(8)
	s_barrier
	s_waitcnt lgkmcnt(0)
	v_mfma_f32_16x16x32_bf16 v[124:127], v[146:149], v[170:173], v[124:127]
	v_mfma_f32_16x16x32_bf16 v[120:123], v[162:165], v[170:173], v[120:123]
	v_mfma_f32_16x16x32_bf16 v[108:111], v[146:149], v[178:181], v[108:111]
	v_mfma_f32_16x16x32_bf16 v[104:107], v[162:165], v[178:181], v[104:107]
	v_mfma_f32_16x16x32_bf16 v[92:95], v[146:149], v[186:189], v[92:95]
	v_mfma_f32_16x16x32_bf16 v[88:91], v[162:165], v[186:189], v[88:91]
	v_mfma_f32_16x16x32_bf16 v[76:79], v[146:149], v[194:197], v[76:79]
	v_mfma_f32_16x16x32_bf16 v[72:75], v[162:165], v[194:197], v[72:75]
	v_mfma_f32_16x16x32_bf16 v[124:127], v[158:161], v[174:177], v[124:127]
	v_mfma_f32_16x16x32_bf16 v[120:123], v[166:169], v[174:177], v[120:123]
	v_mfma_f32_16x16x32_bf16 v[108:111], v[158:161], v[182:185], v[108:111]
	v_mfma_f32_16x16x32_bf16 v[104:107], v[166:169], v[182:185], v[104:107]
	v_mfma_f32_16x16x32_bf16 v[92:95], v[158:161], v[190:193], v[92:95]
	v_mfma_f32_16x16x32_bf16 v[88:91], v[166:169], v[190:193], v[88:91]
	v_mfma_f32_16x16x32_bf16 v[76:79], v[158:161], v[198:201], v[76:79]
	v_mfma_f32_16x16x32_bf16 v[72:75], v[166:169], v[198:201], v[72:75]
	s_barrier
	s_add_i32 s33, s68, s57
	v_lshl_add_u64 v[220:221], s[50:51], 0, v[130:131]
	s_mov_b32 m0, s33
	ds_read_b128 v[204:207], v156
	ds_read_b128 v[208:211], v156 offset:1024
	ds_read_b128 v[212:215], v156 offset:2048
	ds_read_b128 v[216:219], v156 offset:3072
	global_load_lds_dwordx4 v[220:221], off
	v_lshl_add_u64 v[222:223], s[50:51], 0, v[136:137]
	s_add_i32 m0, s33, 0x2000
	s_nop 0
	global_load_lds_dwordx4 v[222:223], off
	s_barrier
	s_waitcnt lgkmcnt(0)
	v_mfma_f32_16x16x32_bf16 v[116:119], v[204:207], v[170:173], v[116:119]
	v_mfma_f32_16x16x32_bf16 v[112:115], v[212:215], v[170:173], v[112:115]
	v_mfma_f32_16x16x32_bf16 v[100:103], v[204:207], v[178:181], v[100:103]
	v_mfma_f32_16x16x32_bf16 v[96:99], v[212:215], v[178:181], v[96:99]
	v_mfma_f32_16x16x32_bf16 v[84:87], v[204:207], v[186:189], v[84:87]
	v_mfma_f32_16x16x32_bf16 v[80:83], v[212:215], v[186:189], v[80:83]
	v_mfma_f32_16x16x32_bf16 v[68:71], v[204:207], v[194:197], v[68:71]
	v_mfma_f32_16x16x32_bf16 v[64:67], v[212:215], v[194:197], v[64:67]
	v_mfma_f32_16x16x32_bf16 v[116:119], v[208:211], v[174:177], v[116:119]
	v_mfma_f32_16x16x32_bf16 v[112:115], v[216:219], v[174:177], v[112:115]
	v_mfma_f32_16x16x32_bf16 v[100:103], v[208:211], v[182:185], v[100:103]
	v_mfma_f32_16x16x32_bf16 v[96:99], v[216:219], v[182:185], v[96:99]
	v_mfma_f32_16x16x32_bf16 v[84:87], v[208:211], v[190:193], v[84:87]
	v_mfma_f32_16x16x32_bf16 v[80:83], v[216:219], v[190:193], v[80:83]
	v_mfma_f32_16x16x32_bf16 v[68:71], v[208:211], v[198:201], v[68:71]
	v_mfma_f32_16x16x32_bf16 v[64:67], v[216:219], v[198:201], v[64:67]
	s_mov_b32 m0, s45
	v_lshl_add_u64 v[224:225], s[48:49], 0, v[128:129]
	s_barrier
	ds_read_b128 v[170:173], v155 offset:16384
	ds_read_b128 v[174:177], v155 offset:17408
	ds_read_b128 v[178:181], v155 offset:18432
	ds_read_b128 v[182:185], v155 offset:19456
	ds_read_b128 v[186:189], v155 offset:20480
	ds_read_b128 v[190:193], v155 offset:21504
	ds_read_b128 v[194:197], v155 offset:22528
	ds_read_b128 v[198:201], v155 offset:23552
	global_load_lds_dwordx4 v[224:225], off
	v_lshl_add_u64 v[226:227], s[48:49], 0, v[134:135]
	s_mov_b32 m0, s58
	s_nop 0
	global_load_lds_dwordx4 v[226:227], off
	s_barrier
	s_waitcnt lgkmcnt(0)
	v_mfma_f32_16x16x32_bf16 v[60:63], v[146:149], v[170:173], v[60:63]
	v_mfma_f32_16x16x32_bf16 v[56:59], v[162:165], v[170:173], v[56:59]
	v_mfma_f32_16x16x32_bf16 v[44:47], v[146:149], v[178:181], v[44:47]
	v_mfma_f32_16x16x32_bf16 v[40:43], v[162:165], v[178:181], v[40:43]
	v_mfma_f32_16x16x32_bf16 v[28:31], v[146:149], v[186:189], v[28:31]
	v_mfma_f32_16x16x32_bf16 v[24:27], v[162:165], v[186:189], v[24:27]
	v_mfma_f32_16x16x32_bf16 v[12:15], v[146:149], v[194:197], v[12:15]
	v_mfma_f32_16x16x32_bf16 v[8:11], v[162:165], v[194:197], v[8:11]
	v_mfma_f32_16x16x32_bf16 v[60:63], v[158:161], v[174:177], v[60:63]
	v_mfma_f32_16x16x32_bf16 v[56:59], v[166:169], v[174:177], v[56:59]
	v_mfma_f32_16x16x32_bf16 v[44:47], v[158:161], v[182:185], v[44:47]
	v_mfma_f32_16x16x32_bf16 v[40:43], v[166:169], v[182:185], v[40:43]
	v_mfma_f32_16x16x32_bf16 v[28:31], v[158:161], v[190:193], v[28:31]
	v_mfma_f32_16x16x32_bf16 v[24:27], v[166:169], v[190:193], v[24:27]
	v_mfma_f32_16x16x32_bf16 v[12:15], v[158:161], v[198:201], v[12:15]
	v_mfma_f32_16x16x32_bf16 v[8:11], v[166:169], v[198:201], v[8:11]
	s_barrier
	s_add_i32 s33, s69, s57
	v_lshl_add_u64 v[228:229], s[50:51], 0, v[132:133]
	s_mov_b32 m0, s33
	v_lshl_add_u64 v[230:231], s[50:51], 0, v[138:139]
	global_load_lds_dwordx4 v[228:229], off
	s_add_i32 m0, s33, 0x2000
	s_nop 0
	global_load_lds_dwordx4 v[230:231], off
	s_waitcnt vmcnt(6)
	s_barrier
; #define PG8_STAGE(bufoff, gbase, voff) do { _Pragma("unroll") for (int _i = 0; _i < 2; ++_i) \
;         __builtin_amdgcn_global_load_lds((const unsigned*)((const char*)(gbase) + (voff)[_i]), (LAS unsigned*)(lds + (bufoff) + ldsw + _i * 8192), 16, 0, 0); } while (0)
; #define PG8_LDA(dst, b, h) do { _Pragma("unroll") for (int m = 0; m < 4; ++m) _Pragma("unroll") for (int k = 0; k < 2; ++k) dst[m][k] = *(const LAS bf16x8*)(lds + PG8_SA(b, h) + aoff + m * 2048 + k * 1024); } while (0)
; #define PG8_LDB(dst, b, h) do { _Pragma("unroll") for (int n = 0; n < 2; ++n) _Pragma("unroll") for (int k = 0; k < 2; ++k) dst[n][k] = *(const LAS bf16x8*)(lds + PG8_SB(b, h) + boff + n * 2048 + k * 1024); } while (0)
; #define PG8_MMA(ai, bj, At, Bt) do { __builtin_amdgcn_s_setprio(1); _Pragma("unroll") for (int m = 0; m < 4; ++m) _Pragma("unroll") for (int n = 0; n < 2; ++n) _Pragma("unroll") for (int k = 0; k < 2; ++k) \
;         acc[ai][bj][m][n] = __builtin_amdgcn_mfma_f32_16x16x32_bf16(Bt[n][k], At[m][k], acc[ai][bj][m][n], 0, 0, 0); __builtin_amdgcn_s_setprio(0); } while (0)
; #define PG8_WAIT_V(n) asm volatile("s_waitcnt vmcnt(" #n ")" ::: "memory")
; #define PG8_WAIT_L(n) asm volatile("s_waitcnt lgkmcnt(" #n ")" ::: "memory")
; #define PG8_BAR __builtin_amdgcn_s_barrier()
; #define PG8_SCHED __builtin_amdgcn_sched_barrier(0)
; template <class Epi>
; __device__ __forceinline__ void gemm_phase(LAS unsigned char* lds, const Gemm g, const StaticOrder& S, const Epi& E) {
;     ...
;             PG8_WAIT_V(6); PG8_BAR; PG8_MMA(1, 1, At, B1); PG8_BAR;
;             PG8_LDB(B0, 1, 0); PG8_SCHED; PG8_LDA(At, 1, 0); PG8_STAGE(PG8_SA(0, 1), a2 + hstep, voffA);
;             PG8_WAIT_L(8); PG8_BAR; PG8_WAIT_L(0); PG8_MMA(0, 0, At, B0); PG8_BAR; PG8_SCHED;
;             PG8_LDB(B1, 1, 1); PG8_STAGE(PG8_SB(1, 0), b3, voffB0);
;             PG8_BAR; PG8_WAIT_L(0); PG8_MMA(0, 1, At, B1); PG8_BAR;
;             PG8_LDA(At, 1, 1); PG8_STAGE(PG8_SA(1, 0), a3, voffA);
;             PG8_BAR; PG8_WAIT_L(0); PG8_MMA(1, 0, At, B0); PG8_BAR; PG8_SCHED;
;             PG8_STAGE(PG8_SB(1, 1), b3, voffB1);
;             PG8_WAIT_V(6); PG8_BAR; PG8_MMA(1, 1, At, B1); PG8_BAR;
	v_mfma_f32_16x16x32_bf16 v[52:55], v[204:207], v[170:173], v[52:55]
	v_mfma_f32_16x16x32_bf16 v[48:51], v[212:215], v[170:173], v[48:51]
	v_mfma_f32_16x16x32_bf16 v[36:39], v[204:207], v[178:181], v[36:39]
	v_mfma_f32_16x16x32_bf16 v[32:35], v[212:215], v[178:181], v[32:35]
	v_mfma_f32_16x16x32_bf16 v[20:23], v[204:207], v[186:189], v[20:23]
	v_mfma_f32_16x16x32_bf16 v[16:19], v[212:215], v[186:189], v[16:19]
	v_mfma_f32_16x16x32_bf16 v[4:7], v[204:207], v[194:197], v[4:7]
	v_mfma_f32_16x16x32_bf16 v[0:3], v[212:215], v[194:197], v[0:3]
	v_mfma_f32_16x16x32_bf16 v[52:55], v[208:211], v[174:177], v[52:55]
	v_mfma_f32_16x16x32_bf16 v[48:51], v[216:219], v[174:177], v[48:51]
	v_mfma_f32_16x16x32_bf16 v[36:39], v[208:211], v[182:185], v[36:39]
	v_mfma_f32_16x16x32_bf16 v[32:35], v[216:219], v[182:185], v[32:35]
	v_mfma_f32_16x16x32_bf16 v[20:23], v[208:211], v[190:193], v[20:23]
	v_mfma_f32_16x16x32_bf16 v[16:19], v[216:219], v[190:193], v[16:19]
	v_mfma_f32_16x16x32_bf16 v[4:7], v[208:211], v[198:201], v[4:7]
	v_mfma_f32_16x16x32_bf16 v[0:3], v[216:219], v[198:201], v[0:3]
	s_add_i32 s33, 0, 0x18000
	v_add_u32_e32 v157, s33, v151
	s_barrier
	ds_read_b128 v[146:149], v157
	ds_read_b128 v[158:161], v157 offset:1024
	ds_read_b128 v[162:165], v157 offset:2048
	ds_read_b128 v[166:169], v157 offset:3072
	s_add_u32 s48, s48, 0x80000
	s_addc_u32 s49, s49, 0
	s_mov_b32 m0, s59
	v_lshl_add_u64 v[204:205], s[48:49], 0, v[128:129]
	ds_read_b128 v[170:173], v155 offset:32768
	ds_read_b128 v[174:177], v155 offset:33792
	ds_read_b128 v[178:181], v155 offset:34816
	ds_read_b128 v[182:185], v155 offset:35840
	ds_read_b128 v[186:189], v155 offset:36864
	ds_read_b128 v[190:193], v155 offset:37888
	ds_read_b128 v[194:197], v155 offset:38912
	ds_read_b128 v[198:201], v155 offset:39936
	global_load_lds_dwordx4 v[204:205], off
	v_lshl_add_u64 v[204:205], s[48:49], 0, v[134:135]
	s_mov_b32 m0, s60
	s_nop 0
	global_load_lds_dwordx4 v[204:205], off
	s_waitcnt lgkmcnt(8)
	s_barrier
	s_waitcnt lgkmcnt(0)
	v_mfma_f32_16x16x32_bf16 v[124:127], v[146:149], v[170:173], v[124:127]
	v_mfma_f32_16x16x32_bf16 v[120:123], v[162:165], v[170:173], v[120:123]
	v_mfma_f32_16x16x32_bf16 v[108:111], v[146:149], v[178:181], v[108:111]
	v_mfma_f32_16x16x32_bf16 v[104:107], v[162:165], v[178:181], v[104:107]
	v_mfma_f32_16x16x32_bf16 v[92:95], v[146:149], v[186:189], v[92:95]
	v_mfma_f32_16x16x32_bf16 v[88:91], v[162:165], v[186:189], v[88:91]
	v_mfma_f32_16x16x32_bf16 v[76:79], v[146:149], v[194:197], v[76:79]
	v_mfma_f32_16x16x32_bf16 v[72:75], v[162:165], v[194:197], v[72:75]
	v_mfma_f32_16x16x32_bf16 v[124:127], v[158:161], v[174:177], v[124:127]
	v_mfma_f32_16x16x32_bf16 v[120:123], v[166:169], v[174:177], v[120:123]
	v_mfma_f32_16x16x32_bf16 v[108:111], v[158:161], v[182:185], v[108:111]
	v_mfma_f32_16x16x32_bf16 v[104:107], v[166:169], v[182:185], v[104:107]
	v_mfma_f32_16x16x32_bf16 v[92:95], v[158:161], v[190:193], v[92:95]
	v_mfma_f32_16x16x32_bf16 v[88:91], v[166:169], v[190:193], v[88:91]
	v_mfma_f32_16x16x32_bf16 v[76:79], v[158:161], v[198:201], v[76:79]
	v_mfma_f32_16x16x32_bf16 v[72:75], v[166:169], v[198:201], v[72:75]
	s_barrier
	s_add_i32 s48, 0, 0x1c000
	s_add_i32 s33, s33, s57
	v_add_u32_e32 v157, s48, v151
	v_lshl_add_u64 v[220:221], v[220:221], 0, s[26:27]
	s_mov_b32 m0, s33
	ds_read_b128 v[204:207], v157
	ds_read_b128 v[208:211], v157 offset:1024
	ds_read_b128 v[212:215], v157 offset:2048
	ds_read_b128 v[216:219], v157 offset:3072
	global_load_lds_dwordx4 v[220:221], off
	v_lshl_add_u64 v[220:221], v[222:223], 0, s[26:27]
	s_add_i32 m0, s33, 0x2000
	s_nop 0
	global_load_lds_dwordx4 v[220:221], off
	s_barrier
	s_waitcnt lgkmcnt(0)
	v_mfma_f32_16x16x32_bf16 v[116:119], v[204:207], v[170:173], v[116:119]
	v_mfma_f32_16x16x32_bf16 v[112:115], v[212:215], v[170:173], v[112:115]
	v_mfma_f32_16x16x32_bf16 v[100:103], v[204:207], v[178:181], v[100:103]
	v_mfma_f32_16x16x32_bf16 v[96:99], v[212:215], v[178:181], v[96:99]
	v_mfma_f32_16x16x32_bf16 v[84:87], v[204:207], v[186:189], v[84:87]
	v_mfma_f32_16x16x32_bf16 v[80:83], v[212:215], v[186:189], v[80:83]
	v_mfma_f32_16x16x32_bf16 v[68:71], v[204:207], v[194:197], v[68:71]
	v_mfma_f32_16x16x32_bf16 v[64:67], v[212:215], v[194:197], v[64:67]
	v_mfma_f32_16x16x32_bf16 v[116:119], v[208:211], v[174:177], v[116:119]
	v_mfma_f32_16x16x32_bf16 v[112:115], v[216:219], v[174:177], v[112:115]
	v_mfma_f32_16x16x32_bf16 v[100:103], v[208:211], v[182:185], v[100:103]
	v_mfma_f32_16x16x32_bf16 v[96:99], v[216:219], v[182:185], v[96:99]
	v_mfma_f32_16x16x32_bf16 v[84:87], v[208:211], v[190:193], v[84:87]
	v_mfma_f32_16x16x32_bf16 v[80:83], v[216:219], v[190:193], v[80:83]
	v_mfma_f32_16x16x32_bf16 v[68:71], v[208:211], v[198:201], v[68:71]
	v_mfma_f32_16x16x32_bf16 v[64:67], v[216:219], v[198:201], v[64:67]
	s_mov_b32 m0, s62
	v_lshl_add_u64 v[220:221], v[224:225], 0, s[26:27]
	s_barrier
	ds_read_b128 v[170:173], v155 offset:49152
	ds_read_b128 v[174:177], v155 offset:50176
	ds_read_b128 v[178:181], v155 offset:51200
	ds_read_b128 v[182:185], v155 offset:52224
	ds_read_b128 v[186:189], v155 offset:53248
	ds_read_b128 v[190:193], v155 offset:54272
	ds_read_b128 v[194:197], v155 offset:55296
	ds_read_b128 v[198:201], v155 offset:56320
	global_load_lds_dwordx4 v[220:221], off
	v_lshl_add_u64 v[220:221], v[226:227], 0, s[26:27]
	s_mov_b32 m0, s63
	s_nop 0
	global_load_lds_dwordx4 v[220:221], off
	s_barrier
; __device__ __forceinline__ unsigned dpp_ror8(unsigned x) { return (unsigned)__builtin_amdgcn_update_dpp(0, (int)x, 0x128, 0xf, 0xf, false); }
; #define PG8_STAGE(bufoff, gbase, voff) do { _Pragma("unroll") for (int _i = 0; _i < 2; ++_i) \
;         __builtin_amdgcn_global_load_lds((const unsigned*)((const char*)(gbase) + (voff)[_i]), (LAS unsigned*)(lds + (bufoff) + ldsw + _i * 8192), 16, 0, 0); } while (0)
; #define PG8_LDA(dst, b, h) do { _Pragma("unroll") for (int m = 0; m < 4; ++m) _Pragma("unroll") for (int k = 0; k < 2; ++k) dst[m][k] = *(const LAS bf16x8*)(lds + PG8_SA(b, h) + aoff + m * 2048 + k * 1024); } while (0)
; #define PG8_WAIT_V(n) asm volatile("s_waitcnt vmcnt(" #n ")" ::: "memory")
; #define PG8_WAIT_L(n) asm volatile("s_waitcnt lgkmcnt(" #n ")" ::: "memory")
;     const bool lo = fr < 8;
;     const int r1 = row - fr + (fr & 7), cb = col0 + (lo ? 0 : boff);
;     const u32x4 l1 = *(const u32x4*)(P + (size_t)r1 * ld + cb), l2 = *(const u32x4*)(P + (size_t)(r1 + 8) * ld + cb);
;     const u32x4 s1 = {dpp_ror8(l1.x), dpp_ror8(l1.y), dpp_ror8(l1.z), dpp_ror8(l1.w)}, s2 = {dpp_ror8(l2.x), dpp_ror8(l2.y), dpp_ror8(l2.z), dpp_ror8(l2.w)};
;     wA = lo ? l1 : s2; wB = lo ? s1 : l2;
; }
;     __device__ __forceinline__ void operator()(const f32x4 (&acc)[2][2][4][2], const Unit& u, int wr, int wc, int fr, int fq) const {
;     ...
;             for (int m = 0; m < 4; ++m) { const int row = row0 + ai * HALF + m * 16; const size_t off = (size_t)row * D + col0; float sq = 0.f; u32x4 w[2];
;                 const float sc = rsin ? __builtin_amdgcn_rcpf(rsin[row] * (1.f / D) + EPS) : 1.0f;
;                 u32x4 rr[2]; if (R) load_pair_lines(R, D, row, fr, col0, rr[0], rr[1]);
; template <class Epi>
; __device__ __forceinline__ void gemm_phase(LAS unsigned char* lds, const Gemm g, const StaticOrder& S, const Epi& E) {
;     ...
;             PG8_WAIT_L(8); PG8_BAR; PG8_WAIT_L(0); PG8_MMA(0, 0, At, B0); PG8_BAR; PG8_SCHED;
;             PG8_LDB(B1, 1, 1); PG8_STAGE(PG8_SB(1, 0), b3, voffB0);
;             PG8_BAR; PG8_WAIT_L(0); PG8_MMA(0, 1, At, B1); PG8_BAR;
;             PG8_LDA(At, 1, 1); PG8_STAGE(PG8_SA(1, 0), a3, voffA);
;             PG8_BAR; PG8_WAIT_L(0); PG8_MMA(1, 0, At, B0); PG8_BAR; PG8_SCHED;
;             PG8_STAGE(PG8_SB(1, 1), b3, voffB1);
;             PG8_WAIT_V(6); PG8_BAR; PG8_MMA(1, 1, At, B1); PG8_BAR;
;         }
	s_waitcnt lgkmcnt(0)
	v_mfma_f32_16x16x32_bf16 v[60:63], v[146:149], v[170:173], v[60:63]
	v_mfma_f32_16x16x32_bf16 v[56:59], v[162:165], v[170:173], v[56:59]
	v_mfma_f32_16x16x32_bf16 v[44:47], v[146:149], v[178:181], v[44:47]
	v_mfma_f32_16x16x32_bf16 v[40:43], v[162:165], v[178:181], v[40:43]
	v_mfma_f32_16x16x32_bf16 v[28:31], v[146:149], v[186:189], v[28:31]
	v_mfma_f32_16x16x32_bf16 v[24:27], v[162:165], v[186:189], v[24:27]
	v_mfma_f32_16x16x32_bf16 v[12:15], v[146:149], v[194:197], v[12:15]
	v_mfma_f32_16x16x32_bf16 v[8:11], v[162:165], v[194:197], v[8:11]
	v_mfma_f32_16x16x32_bf16 v[60:63], v[158:161], v[174:177], v[60:63]
	v_mfma_f32_16x16x32_bf16 v[56:59], v[166:169], v[174:177], v[56:59]
	v_mfma_f32_16x16x32_bf16 v[44:47], v[158:161], v[182:185], v[44:47]
	v_mfma_f32_16x16x32_bf16 v[40:43], v[166:169], v[182:185], v[40:43]
	v_mfma_f32_16x16x32_bf16 v[28:31], v[158:161], v[190:193], v[28:31]
	v_mfma_f32_16x16x32_bf16 v[24:27], v[166:169], v[190:193], v[24:27]
	v_mfma_f32_16x16x32_bf16 v[12:15], v[158:161], v[198:201], v[12:15]
	v_mfma_f32_16x16x32_bf16 v[8:11], v[166:169], v[198:201], v[8:11]
	s_barrier
	s_add_i32 s33, s48, s57
	v_lshl_add_u64 v[146:147], v[228:229], 0, s[26:27]
	s_mov_b32 m0, s33
	s_nop 0
	global_load_lds_dwordx4 v[146:147], off
	v_lshl_add_u64 v[146:147], v[230:231], 0, s[26:27]
	s_add_i32 m0, s33, 0x2000
	s_nop 0
	global_load_lds_dwordx4 v[146:147], off
	s_waitcnt vmcnt(6)
	s_barrier
	v_mfma_f32_16x16x32_bf16 v[52:55], v[204:207], v[170:173], v[52:55]
	v_mfma_f32_16x16x32_bf16 v[48:51], v[212:215], v[170:173], v[48:51]
	v_mfma_f32_16x16x32_bf16 v[36:39], v[204:207], v[178:181], v[36:39]
	v_mfma_f32_16x16x32_bf16 v[32:35], v[212:215], v[178:181], v[32:35]
	v_mfma_f32_16x16x32_bf16 v[20:23], v[204:207], v[186:189], v[20:23]
	v_mfma_f32_16x16x32_bf16 v[16:19], v[212:215], v[186:189], v[16:19]
	v_mfma_f32_16x16x32_bf16 v[4:7], v[204:207], v[194:197], v[4:7]
	v_mfma_f32_16x16x32_bf16 v[0:3], v[212:215], v[194:197], v[0:3]
	v_mfma_f32_16x16x32_bf16 v[52:55], v[208:211], v[174:177], v[52:55]
	v_mfma_f32_16x16x32_bf16 v[48:51], v[216:219], v[174:177], v[48:51]
	v_mfma_f32_16x16x32_bf16 v[36:39], v[208:211], v[182:185], v[36:39]
	v_mfma_f32_16x16x32_bf16 v[32:35], v[216:219], v[182:185], v[32:35]
	v_mfma_f32_16x16x32_bf16 v[20:23], v[208:211], v[190:193], v[20:23]
	v_mfma_f32_16x16x32_bf16 v[16:19], v[216:219], v[190:193], v[16:19]
	v_mfma_f32_16x16x32_bf16 v[4:7], v[208:211], v[198:201], v[4:7]
	v_mfma_f32_16x16x32_bf16 v[0:3], v[216:219], v[198:201], v[0:3]
	s_add_i32 s73, s73, 2
	s_add_u32 s46, s46, 0x100
	s_addc_u32 s47, s47, 0
	s_add_u32 s71, s71, 0x100
	s_addc_u32 s72, s72, 0
	s_cmp_gt_u32 s73, 29
	s_barrier
	s_cbranch_scc0 .LBB0_1245
	s_lshl_b32 s31, s44, 8
	s_add_i32 s31, s31, s64
	v_or_b32_e32 v148, s31, v152
	v_ashrrev_i32_e32 v149, 31, v148
	v_lshlrev_b64 v[166:167], 12, v[148:149]
	v_or_b32_e32 v148, 8, v148
	v_lshl_or_b32 v146, s42, 8, v153
	v_ashrrev_i32_e32 v149, 31, v148
	v_ashrrev_i32_e32 v147, 31, v146
	v_lshlrev_b64 v[168:169], 12, v[148:149]
	v_lshl_add_u64 v[158:159], s[10:11], 0, v[166:167]
	v_lshlrev_b64 v[146:147], 1, v[146:147]
	v_lshl_add_u64 v[148:149], s[10:11], 0, v[168:169]
	v_lshl_add_u64 v[158:159], v[158:159], 0, v[146:147]
	v_lshl_add_u64 v[148:149], v[148:149], 0, v[146:147]
	global_load_dwordx4 v[158:161], v[158:159], off
	global_load_dwordx4 v[162:165], v[148:149], off
	v_or_b32_e32 v194, s31, v150
	v_or_b32_e32 v184, 16, v194
	v_sub_u32_e32 v185, v184, v150
	v_add_u32_e32 v186, v185, v152
	v_ashrrev_i32_e32 v187, 31, v186
	v_lshlrev_b64 v[190:191], 12, v[186:187]
	v_lshl_add_u64 v[192:193], v[190:191], 0, s[28:29]
	v_lshl_add_u64 v[186:187], s[10:11], 0, v[190:191]
	v_lshl_add_u64 v[188:189], s[10:11], 0, v[192:193]
	v_lshl_add_u64 v[186:187], v[186:187], 0, v[146:147]
	v_lshl_add_u64 v[188:189], v[188:189], 0, v[146:147]
	global_load_dwordx4 v[196:199], v[186:187], off
	global_load_dwordx4 v[204:207], v[188:189], off
	v_or_b32_e32 v194, s31, v150
	v_or_b32_e32 v184, 32, v194
	v_sub_u32_e32 v185, v184, v150
	v_add_u32_e32 v186, v185, v152
	v_ashrrev_i32_e32 v187, 31, v186
	v_lshlrev_b64 v[190:191], 12, v[186:187]
	v_lshl_add_u64 v[192:193], v[190:191], 0, s[28:29]
	v_lshl_add_u64 v[186:187], s[10:11], 0, v[190:191]
	v_lshl_add_u64 v[188:189], s[10:11], 0, v[192:193]
	v_lshl_add_u64 v[186:187], v[186:187], 0, v[146:147]
	v_lshl_add_u64 v[188:189], v[188:189], 0, v[146:147]
	global_load_dwordx4 v[208:211], v[186:187], off
	global_load_dwordx4 v[212:215], v[188:189], off
	v_or_b32_e32 v194, s31, v150
	v_or_b32_e32 v184, 48, v194
	v_sub_u32_e32 v185, v184, v150
	v_add_u32_e32 v186, v185, v152
	v_ashrrev_i32_e32 v187, 31, v186
	v_lshlrev_b64 v[190:191], 12, v[186:187]
	v_lshl_add_u64 v[192:193], v[190:191], 0, s[28:29]
	v_lshl_add_u64 v[186:187], s[10:11], 0, v[190:191]
	v_lshl_add_u64 v[188:189], s[10:11], 0, v[192:193]
	v_lshl_add_u64 v[186:187], v[186:187], 0, v[146:147]
	v_lshl_add_u64 v[188:189], v[188:189], 0, v[146:147]
	global_load_dwordx4 v[216:219], v[186:187], off
	global_load_dwordx4 v[220:223], v[188:189], off
	v_or_b32_e32 v194, s31, v150
	v_add_u32_e32 v184, 0x80, v194
	v_sub_u32_e32 v185, v184, v150
	v_add_u32_e32 v186, v185, v152
	v_ashrrev_i32_e32 v187, 31, v186
	v_lshlrev_b64 v[190:191], 12, v[186:187]
	v_lshl_add_u64 v[192:193], v[190:191], 0, s[28:29]
	v_lshl_add_u64 v[186:187], s[10:11], 0, v[190:191]
	v_lshl_add_u64 v[188:189], s[10:11], 0, v[192:193]
	v_lshl_add_u64 v[186:187], v[186:187], 0, v[146:147]
	v_lshl_add_u64 v[188:189], v[188:189], 0, v[146:147]
	global_load_dwordx4 v[224:227], v[186:187], off
	global_load_dwordx4 v[228:231], v[188:189], off
	v_or_b32_e32 v194, s31, v150
	v_add_u32_e32 v184, 0x90, v194
	v_sub_u32_e32 v185, v184, v150
	v_add_u32_e32 v186, v185, v152
	v_ashrrev_i32_e32 v187, 31, v186
	v_lshlrev_b64 v[190:191], 12, v[186:187]
	v_lshl_add_u64 v[192:193], v[190:191], 0, s[28:29]
	v_lshl_add_u64 v[186:187], s[10:11], 0, v[190:191]
	v_lshl_add_u64 v[188:189], s[10:11], 0, v[192:193]
	v_lshl_add_u64 v[186:187], v[186:187], 0, v[146:147]
	v_lshl_add_u64 v[188:189], v[188:189], 0, v[146:147]
	global_load_dwordx4 v[232:235], v[186:187], off
	global_load_dwordx4 v[236:239], v[188:189], off
	v_or_b32_e32 v194, s31, v150
	v_add_u32_e32 v184, 0xa0, v194
	v_sub_u32_e32 v185, v184, v150
	v_add_u32_e32 v186, v185, v152
	v_ashrrev_i32_e32 v187, 31, v186
	v_lshlrev_b64 v[190:191], 12, v[186:187]
	v_lshl_add_u64 v[192:193], v[190:191], 0, s[28:29]
	v_lshl_add_u64 v[186:187], s[10:11], 0, v[190:191]
	v_lshl_add_u64 v[188:189], s[10:11], 0, v[192:193]
	v_lshl_add_u64 v[186:187], v[186:187], 0, v[146:147]
	v_lshl_add_u64 v[188:189], v[188:189], 0, v[146:147]
	global_load_dwordx4 v[240:243], v[186:187], off
	global_load_dwordx4 v[244:247], v[188:189], off
	v_or_b32_e32 v148, s31, v150
	s_waitcnt vmcnt(12)
; __device__ __forceinline__ void store_pair_lines(bf16_t* O, int ldc, int row, int fr, int col0, u32x4 wA, u32x4 wB) {
;     const u32x4 sA = {dpp_ror8(wA.x), dpp_ror8(wA.y), dpp_ror8(wA.z), dpp_ror8(wA.w)}, sB = {dpp_ror8(wB.x), dpp_ror8(wB.y), dpp_ror8(wB.z), dpp_ror8(wB.w)};
;     const bool lo = fr < 8;
;     const u32x4 o1 = lo ? wA : sB, o2 = lo ? sA : wB;
;     const int r1 = row - fr + (fr & 7), cb = col0 + (lo ? 0 : 8);
;     *(u32x4*)(O + (size_t)r1 * ldc + cb) = o1;
;     *(u32x4*)(O + (size_t)(r1 + 8) * ldc + cb) = o2;
; }
;     const bool lo = fr < 8;
;     const int r1 = row - fr + (fr & 7), cb = col0 + (lo ? 0 : boff);
;     const u32x4 l1 = *(const u32x4*)(P + (size_t)r1 * ld + cb), l2 = *(const u32x4*)(P + (size_t)(r1 + 8) * ld + cb);
;     __device__ __forceinline__ void operator()(const f32x4 (&acc)[2][2][4][2], const Unit& u, int wr, int wc, int fr, int fq) const {
;     ...
;             for (int m = 0; m < 4; ++m) { const int row = row0 + ai * HALF + m * 16; const size_t off = (size_t)row * D + col0; float sq = 0.f; u32x4 w[2];
;                 const float sc = rsin ? __builtin_amdgcn_rcpf(rsin[row] * (1.f / D) + EPS) : 1.0f;
;                 u32x4 rr[2]; if (R) load_pair_lines(R, D, row, fr, col0, rr[0], rr[1]);
; #pragma unroll
;                 for (int bj = 0; bj < 2; ++bj) { f32x4 r0, r1;
;                     if (R) { const u32x4 rw = rr[bj]; r0 = (f32x4){bflo(rw.x), bfhi(rw.x), bflo(rw.y), bfhi(rw.y)}; r1 = (f32x4){bflo(rw.z), bfhi(rw.z), bflo(rw.w), bfhi(rw.w)}; }
;                     else { const float* rp = (row < 8192 ? src_p + off : src_s + (off - (size_t)8192 * D)) + 8 * bj; r0 = *(const f32x4*)rp; r1 = *(const f32x4*)(rp + 4); }
;                     const f32x4 o0 = r0 + acc[ai][bj][m][0] * sc, o1 = r1 + acc[ai][bj][m][1] * sc;
;                     sq += (o0[0] * o0[0] + o0[1] * o0[1]) + (o0[2] * o0[2] + o0[3] * o0[3]) + (o1[0] * o1[0] + o1[1] * o1[1]) + (o1[2] * o1[2] + o1[3] * o1[3]);
;                     w[bj].x = cvt_pk_bf16(o0[0], o0[1]); w[bj].y = cvt_pk_bf16(o0[2], o0[3]); w[bj].z = cvt_pk_bf16(o1[0], o1[1]); w[bj].w = cvt_pk_bf16(o1[2], o1[3]); }
;                 store_pair_lines(O, D, row, fr, col0, w[0], w[1]);
;                 if (ssout) { sq += __shfl_xor(sq, 16); sq += __shfl_xor(sq, 32); if (fq == 0) unsafeAtomicAdd(ssout + row, sq); } }
	v_mov_b32_dpp v149, v158 row_ror:8 row_mask:0xf bank_mask:0xf
	v_mov_b32_dpp v157, v159 row_ror:8 row_mask:0xf bank_mask:0xf
	v_mov_b32_dpp v171, v161 row_ror:8 row_mask:0xf bank_mask:0xf
	v_mov_b32_dpp v172, v162 row_ror:8 row_mask:0xf bank_mask:0xf
	v_mov_b32_dpp v173, v163 row_ror:8 row_mask:0xf bank_mask:0xf
	v_mov_b32_dpp v170, v160 row_ror:8 row_mask:0xf bank_mask:0xf
	v_mov_b32_dpp v174, v164 row_ror:8 row_mask:0xf bank_mask:0xf
	v_mov_b32_dpp v175, v165 row_ror:8 row_mask:0xf bank_mask:0xf
	v_cndmask_b32_e64 v165, v165, v171, s[6:7]
	v_cndmask_b32_e64 v157, v163, v157, s[6:7]
	v_cndmask_b32_e64 v149, v162, v149, s[6:7]
	v_cndmask_b32_e64 v173, v173, v159, s[6:7]
	v_cndmask_b32_e64 v171, v172, v158, s[6:7]
	v_cndmask_b32_e64 v164, v164, v170, s[6:7]
	v_cndmask_b32_e64 v177, v175, v161, s[6:7]
	v_cndmask_b32_e64 v175, v174, v160, s[6:7]
	v_lshlrev_b32_e32 v158, 16, v149
	v_and_b32_e32 v159, 0xffff0000, v149
	v_lshlrev_b32_e32 v160, 16, v157
	v_and_b32_e32 v161, 0xffff0000, v157
	v_lshlrev_b32_e32 v170, 16, v171
	v_and_b32_e32 v171, 0xffff0000, v171
	v_lshlrev_b32_e32 v172, 16, v173
	v_and_b32_e32 v173, 0xffff0000, v173
	v_lshlrev_b32_e32 v174, 16, v175
	v_and_b32_e32 v175, 0xffff0000, v175
	v_pk_add_f32 v[160:161], v[118:119], v[160:161]
	v_pk_add_f32 v[158:159], v[116:117], v[158:159]
	v_pk_add_f32 v[116:117], v[126:127], v[172:173]
	v_pk_add_f32 v[118:119], v[124:125], v[170:171]
	v_lshlrev_b32_e32 v176, 16, v177
	v_and_b32_e32 v177, 0xffff0000, v177
	v_pk_add_f32 v[120:121], v[120:121], v[174:175]
	v_mul_f32_e32 v124, v119, v119
	v_mul_f32_e32 v125, v117, v117
	v_lshlrev_b32_e32 v162, 16, v164
	v_and_b32_e32 v163, 0xffff0000, v164
	v_lshlrev_b32_e32 v164, 16, v165
	v_and_b32_e32 v165, 0xffff0000, v165
	v_pk_add_f32 v[122:123], v[122:123], v[176:177]
	v_mul_f32_e32 v126, v121, v121
	v_fmac_f32_e32 v124, v118, v118
	v_fmac_f32_e32 v125, v116, v116
	v_pk_add_f32 v[114:115], v[114:115], v[164:165]
	v_mul_f32_e32 v127, v123, v123
	v_cvt_pk_bf16_f32 v119, v118, v119
	v_cvt_pk_bf16_f32 v117, v116, v117
	v_cvt_pk_bf16_f32 v121, v120, v121
	v_fmac_f32_e32 v126, v120, v120
	v_add_f32_e32 v116, v124, v125
	v_pk_add_f32 v[112:113], v[112:113], v[162:163]
	v_cvt_pk_bf16_f32 v123, v122, v123
	v_cvt_pk_bf16_f32 v149, v158, v159
	v_cvt_pk_bf16_f32 v157, v160, v161
	v_fmac_f32_e32 v127, v122, v122
	v_cvt_pk_bf16_f32 v162, v112, v113
	v_cvt_pk_bf16_f32 v163, v114, v115
	v_add_f32_e32 v116, v126, v116
	v_mov_b32_dpp v182, v149 row_ror:8 row_mask:0xf bank_mask:0xf
	v_mov_b32_dpp v120, v163 row_ror:8 row_mask:0xf bank_mask:0xf
	v_mul_f32_e32 v115, v115, v115
	v_mov_b32_dpp v178, v119 row_ror:8 row_mask:0xf bank_mask:0xf
	v_mov_b32_dpp v181, v123 row_ror:8 row_mask:0xf bank_mask:0xf
	v_add_f32_e32 v122, v127, v116
	v_cndmask_b32_e64 v116, v182, v119, s[6:7]
	v_cndmask_b32_e64 v119, v120, v123, s[6:7]
	v_fmac_f32_e32 v115, v114, v114
	v_mul_f32_e32 v114, v159, v159
	v_mul_f32_e32 v123, v161, v161
	v_fmac_f32_e32 v114, v158, v158
	v_fmac_f32_e32 v123, v160, v160
	v_mul_f32_e32 v113, v113, v113
	v_add_f32_e32 v114, v114, v123
	v_fmac_f32_e32 v113, v112, v112
	v_add_f32_e32 v112, v113, v114
	v_add_f32_e32 v112, v115, v112
	v_and_b32_e32 v113, 64, v203
	v_add_f32_e32 v115, v112, v122
	v_xor_b32_e32 v112, 16, v203
	v_add_u32_e32 v126, 64, v113
	v_cmp_lt_i32_e32 vcc, v112, v126
	v_mov_b32_e32 v118, 0
	v_mov_b32_dpp v183, v157 row_ror:8 row_mask:0xf bank_mask:0xf
	v_cndmask_b32_e32 v112, v203, v112, vcc
	v_lshlrev_b32_e32 v114, 2, v112
	ds_bpermute_b32 v127, v114, v115
	v_lshl_add_u64 v[112:113], s[16:17], 0, v[166:167]
	v_lshl_add_u64 v[124:125], v[112:113], 0, v[146:147]
	v_xor_b32_e32 v113, 32, v203
	v_cmp_lt_i32_e32 vcc, v113, v126
	s_waitcnt lgkmcnt(0)
	v_add_f32_e32 v112, v115, v127
	v_mov_b32_dpp v118, v162 row_ror:8 row_mask:0xf bank_mask:0xf
	v_cndmask_b32_e32 v113, v203, v113, vcc
	v_lshlrev_b32_e32 v115, 2, v113
	ds_bpermute_b32 v113, v115, v112
	v_mov_b32_dpp v179, v117 row_ror:8 row_mask:0xf bank_mask:0xf
	v_cndmask_b32_e64 v117, v183, v117, s[6:7]
	v_cndmask_b32_e64 v118, v118, v121, s[6:7]
	v_mov_b32_dpp v180, v121 row_ror:8 row_mask:0xf bank_mask:0xf
	global_store_dwordx4 v[124:125], v[116:119], off
	v_cndmask_b32_e64 v120, v149, v178, s[6:7]
	v_cndmask_b32_e64 v121, v157, v179, s[6:7]
	v_lshl_add_u64 v[116:117], s[16:17], 0, v[168:169]
	v_cndmask_b32_e64 v122, v162, v180, s[6:7]
	v_cndmask_b32_e64 v123, v163, v181, s[6:7]
	v_lshl_add_u64 v[116:117], v[116:117], 0, v[146:147]
	global_store_dwordx4 v[116:117], v[120:123], off
	s_and_saveexec_b64 s[42:43], s[8:9]
	s_cbranch_execz .LBB0_1248
	v_ashrrev_i32_e32 v149, 31, v148
	s_waitcnt lgkmcnt(0)
	v_add_f32_e32 v116, v112, v113
	v_lshl_add_u64 v[112:113], v[148:149], 2, s[18:19]
	global_atomic_add_f32 v[112:113], v116, off
; __device__ __forceinline__ void store_pair_lines(bf16_t* O, int ldc, int row, int fr, int col0, u32x4 wA, u32x4 wB) {
;     const u32x4 sA = {dpp_ror8(wA.x), dpp_ror8(wA.y), dpp_ror8(wA.z), dpp_ror8(wA.w)}, sB = {dpp_ror8(wB.x), dpp_ror8(wB.y), dpp_ror8(wB.z), dpp_ror8(wB.w)};
;     const bool lo = fr < 8;
;     const u32x4 o1 = lo ? wA : sB, o2 = lo ? sA : wB;
;     const int r1 = row - fr + (fr & 7), cb = col0 + (lo ? 0 : 8);
;     *(u32x4*)(O + (size_t)r1 * ldc + cb) = o1;
;     *(u32x4*)(O + (size_t)(r1 + 8) * ldc + cb) = o2;
; }
;     const bool lo = fr < 8;
;     const int r1 = row - fr + (fr & 7), cb = col0 + (lo ? 0 : boff);
;     const u32x4 l1 = *(const u32x4*)(P + (size_t)r1 * ld + cb), l2 = *(const u32x4*)(P + (size_t)(r1 + 8) * ld + cb);
;     __device__ __forceinline__ void operator()(const f32x4 (&acc)[2][2][4][2], const Unit& u, int wr, int wc, int fr, int fq) const {
;     ...
;             for (int m = 0; m < 4; ++m) { const int row = row0 + ai * HALF + m * 16; const size_t off = (size_t)row * D + col0; float sq = 0.f; u32x4 w[2];
;                 const float sc = rsin ? __builtin_amdgcn_rcpf(rsin[row] * (1.f / D) + EPS) : 1.0f;
;                 u32x4 rr[2]; if (R) load_pair_lines(R, D, row, fr, col0, rr[0], rr[1]);
; #pragma unroll
;                 for (int bj = 0; bj < 2; ++bj) { f32x4 r0, r1;
;                     if (R) { const u32x4 rw = rr[bj]; r0 = (f32x4){bflo(rw.x), bfhi(rw.x), bflo(rw.y), bfhi(rw.y)}; r1 = (f32x4){bflo(rw.z), bfhi(rw.z), bflo(rw.w), bfhi(rw.w)}; }
;                     else { const float* rp = (row < 8192 ? src_p + off : src_s + (off - (size_t)8192 * D)) + 8 * bj; r0 = *(const f32x4*)rp; r1 = *(const f32x4*)(rp + 4); }
;                     const f32x4 o0 = r0 + acc[ai][bj][m][0] * sc, o1 = r1 + acc[ai][bj][m][1] * sc;
;                     sq += (o0[0] * o0[0] + o0[1] * o0[1]) + (o0[2] * o0[2] + o0[3] * o0[3]) + (o1[0] * o1[0] + o1[1] * o1[1]) + (o1[2] * o1[2] + o1[3] * o1[3]);
;                     w[bj].x = cvt_pk_bf16(o0[0], o0[1]); w[bj].y = cvt_pk_bf16(o0[2], o0[3]); w[bj].z = cvt_pk_bf16(o1[0], o1[1]); w[bj].w = cvt_pk_bf16(o1[2], o1[3]); }
;                 store_pair_lines(O, D, row, fr, col0, w[0], w[1]);
;                 if (ssout) { sq += __shfl_xor(sq, 16); sq += __shfl_xor(sq, 32); if (fq == 0) unsafeAtomicAdd(ssout + row, sq); } }
.LBB0_1248:
	s_or_b64 exec, exec, s[42:43]
	v_or_b32_e32 v112, 16, v148
	s_waitcnt lgkmcnt(0)
	v_sub_u32_e32 v113, v112, v150
	v_add_u32_e32 v116, v113, v152
	v_ashrrev_i32_e32 v117, 31, v116
	v_lshlrev_b64 v[124:125], 12, v[116:117]
	v_lshl_add_u64 v[126:127], v[124:125], 0, s[28:29]
	v_lshl_add_u64 v[116:117], s[10:11], 0, v[124:125]
	v_lshl_add_u64 v[120:121], s[10:11], 0, v[126:127]
	v_lshl_add_u64 v[116:117], v[116:117], 0, v[146:147]
	v_lshl_add_u64 v[120:121], v[120:121], 0, v[146:147]
	s_waitcnt vmcnt(12)
	s_nop 0
	v_mov_b64_e32 v[116:117], v[196:197]
	v_mov_b64_e32 v[118:119], v[198:199]
	v_mov_b64_e32 v[120:121], v[204:205]
	v_mov_b64_e32 v[122:123], v[206:207]
	s_nop 1
	v_add_u32_e32 v184, 0xb0, v148
	v_sub_u32_e32 v185, v184, v150
	v_add_u32_e32 v186, v185, v152
	v_ashrrev_i32_e32 v187, 31, v186
	v_lshlrev_b64 v[190:191], 12, v[186:187]
	v_lshl_add_u64 v[192:193], v[190:191], 0, s[28:29]
	v_lshl_add_u64 v[186:187], s[10:11], 0, v[190:191]
	v_lshl_add_u64 v[188:189], s[10:11], 0, v[192:193]
	v_lshl_add_u64 v[186:187], v[186:187], 0, v[146:147]
	v_lshl_add_u64 v[188:189], v[188:189], 0, v[146:147]
	global_load_dwordx4 v[196:199], v[186:187], off
	global_load_dwordx4 v[204:207], v[188:189], off
	v_mov_b32_dpp v113, v116 row_ror:8 row_mask:0xf bank_mask:0xf
	v_mov_b32_dpp v149, v117 row_ror:8 row_mask:0xf bank_mask:0xf
	v_mov_b32_dpp v157, v118 row_ror:8 row_mask:0xf bank_mask:0xf
	v_mov_b32_dpp v158, v119 row_ror:8 row_mask:0xf bank_mask:0xf
	v_mov_b32_dpp v159, v120 row_ror:8 row_mask:0xf bank_mask:0xf
	v_mov_b32_dpp v160, v121 row_ror:8 row_mask:0xf bank_mask:0xf
	v_mov_b32_dpp v161, v122 row_ror:8 row_mask:0xf bank_mask:0xf
	v_mov_b32_dpp v162, v123 row_ror:8 row_mask:0xf bank_mask:0xf
	v_cndmask_b32_e64 v123, v123, v158, s[6:7]
	v_cndmask_b32_e64 v122, v122, v157, s[6:7]
	v_cndmask_b32_e64 v121, v121, v149, s[6:7]
	v_cndmask_b32_e64 v113, v120, v113, s[6:7]
	v_cndmask_b32_e64 v157, v161, v118, s[6:7]
	v_cndmask_b32_e64 v161, v160, v117, s[6:7]
	v_cndmask_b32_e64 v159, v159, v116, s[6:7]
	v_cndmask_b32_e64 v149, v162, v119, s[6:7]
	v_lshlrev_b32_e32 v116, 16, v113
	v_and_b32_e32 v117, 0xffff0000, v113
	v_lshlrev_b32_e32 v118, 16, v121
	v_and_b32_e32 v119, 0xffff0000, v121
	v_lshlrev_b32_e32 v120, 16, v122
	v_and_b32_e32 v121, 0xffff0000, v122
	v_lshlrev_b32_e32 v122, 16, v123
	v_and_b32_e32 v123, 0xffff0000, v123
	v_lshlrev_b32_e32 v158, 16, v159
	v_and_b32_e32 v159, 0xffff0000, v159
	v_lshlrev_b32_e32 v160, 16, v161
	v_and_b32_e32 v161, 0xffff0000, v161
	v_lshlrev_b32_e32 v162, 16, v157
	v_and_b32_e32 v163, 0xffff0000, v157
	v_lshlrev_b32_e32 v164, 16, v149
	v_and_b32_e32 v165, 0xffff0000, v149
	v_pk_add_f32 v[116:117], v[100:101], v[116:117]
	v_pk_add_f32 v[122:123], v[98:99], v[122:123]
	v_pk_add_f32 v[98:99], v[110:111], v[160:161]
	v_pk_add_f32 v[100:101], v[108:109], v[158:159]
	v_pk_add_f32 v[118:119], v[102:103], v[118:119]
	v_pk_add_f32 v[102:103], v[106:107], v[164:165]
	v_pk_add_f32 v[104:105], v[104:105], v[162:163]
	v_mul_f32_e32 v106, v101, v101
	v_mul_f32_e32 v107, v99, v99
	v_mul_f32_e32 v108, v105, v105
	v_fmac_f32_e32 v106, v100, v100
	v_fmac_f32_e32 v107, v98, v98
	v_pk_add_f32 v[96:97], v[96:97], v[120:121]
	v_mul_f32_e32 v109, v103, v103
	v_cvt_pk_bf16_f32 v101, v100, v101
	v_fmac_f32_e32 v108, v104, v104
	v_add_f32_e32 v100, v106, v107
	v_mul_f32_e32 v106, v117, v117
	v_mul_f32_e32 v107, v119, v119
	v_cvt_pk_bf16_f32 v99, v98, v99
	v_cvt_pk_bf16_f32 v105, v104, v105
	v_cvt_pk_bf16_f32 v103, v102, v103
	v_cvt_pk_bf16_f32 v110, v116, v117
	v_cvt_pk_bf16_f32 v111, v118, v119
	v_cvt_pk_bf16_f32 v113, v96, v97
	v_fmac_f32_e32 v109, v102, v102
	v_add_f32_e32 v100, v108, v100
	v_mov_b32_dpp v172, v113 row_ror:8 row_mask:0xf bank_mask:0xf
	v_fmac_f32_e32 v106, v116, v116
	v_fmac_f32_e32 v107, v118, v118
	v_mul_f32_e32 v97, v97, v97
	v_mov_b32_dpp v168, v105 row_ror:8 row_mask:0xf bank_mask:0xf
	v_add_f32_e32 v104, v109, v100
	v_cndmask_b32_e64 v100, v172, v105, s[6:7]
	v_mul_f32_e32 v105, v123, v123
	v_add_f32_e32 v106, v106, v107
	v_fmac_f32_e32 v97, v96, v96
	v_fmac_f32_e32 v105, v122, v122
	v_add_f32_e32 v96, v97, v106
	v_add_f32_e32 v96, v105, v96
	v_add_f32_e32 v108, v96, v104
	ds_bpermute_b32 v109, v114, v108
	v_lshl_add_u64 v[96:97], s[16:17], 0, v[124:125]
	v_lshl_add_u64 v[106:107], v[96:97], 0, v[146:147]
	v_cvt_pk_bf16_f32 v120, v122, v123
	v_mov_b32_dpp v170, v110 row_ror:8 row_mask:0xf bank_mask:0xf
	s_waitcnt lgkmcnt(0)
	v_add_f32_e32 v96, v108, v109
	ds_bpermute_b32 v97, v115, v96
	v_mov_b32_dpp v171, v111 row_ror:8 row_mask:0xf bank_mask:0xf
	v_mov_b32_dpp v173, v120 row_ror:8 row_mask:0xf bank_mask:0xf
	v_mov_b32_dpp v166, v101 row_ror:8 row_mask:0xf bank_mask:0xf
	v_mov_b32_dpp v167, v99 row_ror:8 row_mask:0xf bank_mask:0xf
	v_cndmask_b32_e64 v98, v170, v101, s[6:7]
	v_cndmask_b32_e64 v99, v171, v99, s[6:7]
	v_cndmask_b32_e64 v101, v173, v103, s[6:7]
	v_mov_b32_dpp v169, v103 row_ror:8 row_mask:0xf bank_mask:0xf
	global_store_dwordx4 v[106:107], v[98:101], off
	v_cndmask_b32_e64 v102, v110, v166, s[6:7]
	v_cndmask_b32_e64 v103, v111, v167, s[6:7]
	v_lshl_add_u64 v[98:99], s[16:17], 0, v[126:127]
	v_cndmask_b32_e64 v104, v113, v168, s[6:7]
	v_cndmask_b32_e64 v105, v120, v169, s[6:7]
	v_lshl_add_u64 v[98:99], v[98:99], 0, v[146:147]
	global_store_dwordx4 v[98:99], v[102:105], off
	s_and_saveexec_b64 s[42:43], s[8:9]
	s_cbranch_execz .LBB0_1250
	v_ashrrev_i32_e32 v113, 31, v112
	s_waitcnt lgkmcnt(0)
	v_add_f32_e32 v98, v96, v97
	v_lshl_add_u64 v[96:97], v[112:113], 2, s[18:19]
	global_atomic_add_f32 v[96:97], v98, off
; __device__ __forceinline__ void store_pair_lines(bf16_t* O, int ldc, int row, int fr, int col0, u32x4 wA, u32x4 wB) {
;     const u32x4 sA = {dpp_ror8(wA.x), dpp_ror8(wA.y), dpp_ror8(wA.z), dpp_ror8(wA.w)}, sB = {dpp_ror8(wB.x), dpp_ror8(wB.y), dpp_ror8(wB.z), dpp_ror8(wB.w)};
;     const bool lo = fr < 8;
;     const u32x4 o1 = lo ? wA : sB, o2 = lo ? sA : wB;
;     const int r1 = row - fr + (fr & 7), cb = col0 + (lo ? 0 : 8);
;     *(u32x4*)(O + (size_t)r1 * ldc + cb) = o1;
;     *(u32x4*)(O + (size_t)(r1 + 8) * ldc + cb) = o2;
; }
;     const bool lo = fr < 8;
;     const int r1 = row - fr + (fr & 7), cb = col0 + (lo ? 0 : boff);
;     const u32x4 l1 = *(const u32x4*)(P + (size_t)r1 * ld + cb), l2 = *(const u32x4*)(P + (size_t)(r1 + 8) * ld + cb);
;     __device__ __forceinline__ void operator()(const f32x4 (&acc)[2][2][4][2], const Unit& u, int wr, int wc, int fr, int fq) const {
;     ...
;             for (int m = 0; m < 4; ++m) { const int row = row0 + ai * HALF + m * 16; const size_t off = (size_t)row * D + col0; float sq = 0.f; u32x4 w[2];
;                 const float sc = rsin ? __builtin_amdgcn_rcpf(rsin[row] * (1.f / D) + EPS) : 1.0f;
;                 u32x4 rr[2]; if (R) load_pair_lines(R, D, row, fr, col0, rr[0], rr[1]);
; #pragma unroll
;                 for (int bj = 0; bj < 2; ++bj) { f32x4 r0, r1;
;                     if (R) { const u32x4 rw = rr[bj]; r0 = (f32x4){bflo(rw.x), bfhi(rw.x), bflo(rw.y), bfhi(rw.y)}; r1 = (f32x4){bflo(rw.z), bfhi(rw.z), bflo(rw.w), bfhi(rw.w)}; }
;                     else { const float* rp = (row < 8192 ? src_p + off : src_s + (off - (size_t)8192 * D)) + 8 * bj; r0 = *(const f32x4*)rp; r1 = *(const f32x4*)(rp + 4); }
;                     const f32x4 o0 = r0 + acc[ai][bj][m][0] * sc, o1 = r1 + acc[ai][bj][m][1] * sc;
;                     sq += (o0[0] * o0[0] + o0[1] * o0[1]) + (o0[2] * o0[2] + o0[3] * o0[3]) + (o1[0] * o1[0] + o1[1] * o1[1]) + (o1[2] * o1[2] + o1[3] * o1[3]);
;                     w[bj].x = cvt_pk_bf16(o0[0], o0[1]); w[bj].y = cvt_pk_bf16(o0[2], o0[3]); w[bj].z = cvt_pk_bf16(o1[0], o1[1]); w[bj].w = cvt_pk_bf16(o1[2], o1[3]); }
;                 store_pair_lines(O, D, row, fr, col0, w[0], w[1]);
;                 if (ssout) { sq += __shfl_xor(sq, 16); sq += __shfl_xor(sq, 32); if (fq == 0) unsafeAtomicAdd(ssout + row, sq); } }
.LBB0_1250:
	s_or_b64 exec, exec, s[42:43]
	v_or_b32_e32 v96, 32, v148
	s_waitcnt lgkmcnt(0)
	v_sub_u32_e32 v97, v96, v150
	v_add_u32_e32 v98, v97, v152
	v_ashrrev_i32_e32 v99, 31, v98
	v_lshlrev_b64 v[106:107], 12, v[98:99]
	v_lshl_add_u64 v[108:109], v[106:107], 0, s[28:29]
	v_lshl_add_u64 v[98:99], s[10:11], 0, v[106:107]
	v_lshl_add_u64 v[102:103], s[10:11], 0, v[108:109]
	v_lshl_add_u64 v[98:99], v[98:99], 0, v[146:147]
	v_lshl_add_u64 v[102:103], v[102:103], 0, v[146:147]
	s_waitcnt vmcnt(14)
	s_nop 0
	v_mov_b64_e32 v[98:99], v[208:209]
	v_mov_b64_e32 v[100:101], v[210:211]
	v_mov_b64_e32 v[102:103], v[212:213]
	v_mov_b64_e32 v[104:105], v[214:215]
	s_nop 1
	v_mov_b32_dpp v97, v98 row_ror:8 row_mask:0xf bank_mask:0xf
	v_mov_b32_dpp v110, v99 row_ror:8 row_mask:0xf bank_mask:0xf
	v_mov_b32_dpp v111, v100 row_ror:8 row_mask:0xf bank_mask:0xf
	v_mov_b32_dpp v112, v101 row_ror:8 row_mask:0xf bank_mask:0xf
	v_mov_b32_dpp v113, v102 row_ror:8 row_mask:0xf bank_mask:0xf
	v_mov_b32_dpp v116, v103 row_ror:8 row_mask:0xf bank_mask:0xf
	v_mov_b32_dpp v117, v104 row_ror:8 row_mask:0xf bank_mask:0xf
	v_mov_b32_dpp v118, v105 row_ror:8 row_mask:0xf bank_mask:0xf
	v_cndmask_b32_e64 v105, v105, v112, s[6:7]
	v_cndmask_b32_e64 v104, v104, v111, s[6:7]
	v_cndmask_b32_e64 v103, v103, v110, s[6:7]
	v_cndmask_b32_e64 v97, v102, v97, s[6:7]
	v_cndmask_b32_e64 v116, v116, v99, s[6:7]
	v_cndmask_b32_e64 v111, v113, v98, s[6:7]
	v_cndmask_b32_e64 v119, v118, v101, s[6:7]
	v_cndmask_b32_e64 v117, v117, v100, s[6:7]
	v_lshlrev_b32_e32 v98, 16, v97
	v_and_b32_e32 v99, 0xffff0000, v97
	v_lshlrev_b32_e32 v100, 16, v103
	v_and_b32_e32 v101, 0xffff0000, v103
	v_lshlrev_b32_e32 v102, 16, v104
	v_and_b32_e32 v103, 0xffff0000, v104
	v_lshlrev_b32_e32 v104, 16, v105
	v_and_b32_e32 v105, 0xffff0000, v105
	v_lshlrev_b32_e32 v110, 16, v111
	v_and_b32_e32 v111, 0xffff0000, v111
	v_lshlrev_b32_e32 v112, 16, v116
	v_and_b32_e32 v113, 0xffff0000, v116
	v_lshlrev_b32_e32 v116, 16, v117
	v_and_b32_e32 v117, 0xffff0000, v117
	v_lshlrev_b32_e32 v118, 16, v119
	v_and_b32_e32 v119, 0xffff0000, v119
	v_pk_add_f32 v[98:99], v[84:85], v[98:99]
	v_pk_add_f32 v[104:105], v[82:83], v[104:105]
	v_pk_add_f32 v[82:83], v[94:95], v[112:113]
	v_pk_add_f32 v[84:85], v[92:93], v[110:111]
	v_pk_add_f32 v[100:101], v[86:87], v[100:101]
	v_pk_add_f32 v[86:87], v[90:91], v[118:119]
	v_pk_add_f32 v[88:89], v[88:89], v[116:117]
	v_mul_f32_e32 v90, v85, v85
	v_mul_f32_e32 v91, v83, v83
	v_mul_f32_e32 v92, v89, v89
	v_fmac_f32_e32 v90, v84, v84
	v_fmac_f32_e32 v91, v82, v82
	v_pk_add_f32 v[80:81], v[80:81], v[102:103]
	v_mul_f32_e32 v93, v87, v87
	v_cvt_pk_bf16_f32 v85, v84, v85
	v_fmac_f32_e32 v92, v88, v88
	v_add_f32_e32 v84, v90, v91
	v_mul_f32_e32 v90, v99, v99
	v_mul_f32_e32 v91, v101, v101
	v_cvt_pk_bf16_f32 v83, v82, v83
	v_cvt_pk_bf16_f32 v89, v88, v89
	v_cvt_pk_bf16_f32 v87, v86, v87
	v_cvt_pk_bf16_f32 v94, v98, v99
	v_cvt_pk_bf16_f32 v95, v100, v101
	v_cvt_pk_bf16_f32 v97, v80, v81
	v_fmac_f32_e32 v93, v86, v86
	v_add_f32_e32 v84, v92, v84
	v_mov_b32_dpp v126, v97 row_ror:8 row_mask:0xf bank_mask:0xf
	v_fmac_f32_e32 v90, v98, v98
	v_fmac_f32_e32 v91, v100, v100
	v_mul_f32_e32 v81, v81, v81
	v_mov_b32_dpp v122, v89 row_ror:8 row_mask:0xf bank_mask:0xf
	v_add_f32_e32 v88, v93, v84
	v_cndmask_b32_e64 v84, v126, v89, s[6:7]
	v_mul_f32_e32 v89, v105, v105
	v_add_f32_e32 v90, v90, v91
	v_fmac_f32_e32 v81, v80, v80
	v_fmac_f32_e32 v89, v104, v104
	v_add_f32_e32 v80, v81, v90
	v_add_f32_e32 v80, v89, v80
	v_add_f32_e32 v92, v80, v88
	ds_bpermute_b32 v93, v114, v92
	v_lshl_add_u64 v[80:81], s[16:17], 0, v[106:107]
	v_lshl_add_u64 v[90:91], v[80:81], 0, v[146:147]
	v_cvt_pk_bf16_f32 v102, v104, v105
	v_mov_b32_dpp v124, v94 row_ror:8 row_mask:0xf bank_mask:0xf
	s_waitcnt lgkmcnt(0)
	v_add_f32_e32 v80, v92, v93
	ds_bpermute_b32 v81, v115, v80
	v_mov_b32_dpp v125, v95 row_ror:8 row_mask:0xf bank_mask:0xf
	v_mov_b32_dpp v127, v102 row_ror:8 row_mask:0xf bank_mask:0xf
	v_mov_b32_dpp v120, v85 row_ror:8 row_mask:0xf bank_mask:0xf
	v_mov_b32_dpp v121, v83 row_ror:8 row_mask:0xf bank_mask:0xf
	v_cndmask_b32_e64 v82, v124, v85, s[6:7]
	v_cndmask_b32_e64 v83, v125, v83, s[6:7]
	v_cndmask_b32_e64 v85, v127, v87, s[6:7]
	v_mov_b32_dpp v123, v87 row_ror:8 row_mask:0xf bank_mask:0xf
	global_store_dwordx4 v[90:91], v[82:85], off
	v_cndmask_b32_e64 v86, v94, v120, s[6:7]
	v_cndmask_b32_e64 v87, v95, v121, s[6:7]
	v_lshl_add_u64 v[82:83], s[16:17], 0, v[108:109]
	v_cndmask_b32_e64 v88, v97, v122, s[6:7]
	v_cndmask_b32_e64 v89, v102, v123, s[6:7]
	v_lshl_add_u64 v[82:83], v[82:83], 0, v[146:147]
	global_store_dwordx4 v[82:83], v[86:89], off
	s_and_saveexec_b64 s[42:43], s[8:9]
	s_cbranch_execz .LBB0_1252
	v_ashrrev_i32_e32 v97, 31, v96
	s_waitcnt lgkmcnt(0)
	v_add_f32_e32 v82, v80, v81
	v_lshl_add_u64 v[80:81], v[96:97], 2, s[18:19]
	global_atomic_add_f32 v[80:81], v82, off
; __device__ __forceinline__ void store_pair_lines(bf16_t* O, int ldc, int row, int fr, int col0, u32x4 wA, u32x4 wB) {
;     const u32x4 sA = {dpp_ror8(wA.x), dpp_ror8(wA.y), dpp_ror8(wA.z), dpp_ror8(wA.w)}, sB = {dpp_ror8(wB.x), dpp_ror8(wB.y), dpp_ror8(wB.z), dpp_ror8(wB.w)};
;     const bool lo = fr < 8;
;     const u32x4 o1 = lo ? wA : sB, o2 = lo ? sA : wB;
;     const int r1 = row - fr + (fr & 7), cb = col0 + (lo ? 0 : 8);
;     *(u32x4*)(O + (size_t)r1 * ldc + cb) = o1;
;     *(u32x4*)(O + (size_t)(r1 + 8) * ldc + cb) = o2;
; }
;     const bool lo = fr < 8;
;     const int r1 = row - fr + (fr & 7), cb = col0 + (lo ? 0 : boff);
;     const u32x4 l1 = *(const u32x4*)(P + (size_t)r1 * ld + cb), l2 = *(const u32x4*)(P + (size_t)(r1 + 8) * ld + cb);
;     __device__ __forceinline__ void operator()(const f32x4 (&acc)[2][2][4][2], const Unit& u, int wr, int wc, int fr, int fq) const {
;     ...
;             for (int m = 0; m < 4; ++m) { const int row = row0 + ai * HALF + m * 16; const size_t off = (size_t)row * D + col0; float sq = 0.f; u32x4 w[2];
;                 const float sc = rsin ? __builtin_amdgcn_rcpf(rsin[row] * (1.f / D) + EPS) : 1.0f;
;                 u32x4 rr[2]; if (R) load_pair_lines(R, D, row, fr, col0, rr[0], rr[1]);
; #pragma unroll
;                 for (int bj = 0; bj < 2; ++bj) { f32x4 r0, r1;
;                     if (R) { const u32x4 rw = rr[bj]; r0 = (f32x4){bflo(rw.x), bfhi(rw.x), bflo(rw.y), bfhi(rw.y)}; r1 = (f32x4){bflo(rw.z), bfhi(rw.z), bflo(rw.w), bfhi(rw.w)}; }
;                     else { const float* rp = (row < 8192 ? src_p + off : src_s + (off - (size_t)8192 * D)) + 8 * bj; r0 = *(const f32x4*)rp; r1 = *(const f32x4*)(rp + 4); }
;                     const f32x4 o0 = r0 + acc[ai][bj][m][0] * sc, o1 = r1 + acc[ai][bj][m][1] * sc;
;                     sq += (o0[0] * o0[0] + o0[1] * o0[1]) + (o0[2] * o0[2] + o0[3] * o0[3]) + (o1[0] * o1[0] + o1[1] * o1[1]) + (o1[2] * o1[2] + o1[3] * o1[3]);
;                     w[bj].x = cvt_pk_bf16(o0[0], o0[1]); w[bj].y = cvt_pk_bf16(o0[2], o0[3]); w[bj].z = cvt_pk_bf16(o1[0], o1[1]); w[bj].w = cvt_pk_bf16(o1[2], o1[3]); }
;                 store_pair_lines(O, D, row, fr, col0, w[0], w[1]);
;                 if (ssout) { sq += __shfl_xor(sq, 16); sq += __shfl_xor(sq, 32); if (fq == 0) unsafeAtomicAdd(ssout + row, sq); } }
.LBB0_1252:
	s_or_b64 exec, exec, s[42:43]
	v_or_b32_e32 v80, 48, v148
	s_waitcnt lgkmcnt(0)
	v_sub_u32_e32 v81, v80, v150
	v_add_u32_e32 v82, v81, v152
	v_ashrrev_i32_e32 v83, 31, v82
	v_lshlrev_b64 v[90:91], 12, v[82:83]
	v_lshl_add_u64 v[92:93], v[90:91], 0, s[28:29]
	v_lshl_add_u64 v[82:83], s[10:11], 0, v[90:91]
	v_lshl_add_u64 v[86:87], s[10:11], 0, v[92:93]
	v_lshl_add_u64 v[82:83], v[82:83], 0, v[146:147]
	v_lshl_add_u64 v[86:87], v[86:87], 0, v[146:147]
	s_waitcnt vmcnt(14)
	s_nop 0
	v_mov_b64_e32 v[82:83], v[216:217]
	v_mov_b64_e32 v[84:85], v[218:219]
	v_mov_b64_e32 v[86:87], v[220:221]
	v_mov_b64_e32 v[88:89], v[222:223]
	s_nop 1
	v_mov_b32_dpp v81, v82 row_ror:8 row_mask:0xf bank_mask:0xf
	v_mov_b32_dpp v94, v83 row_ror:8 row_mask:0xf bank_mask:0xf
	v_mov_b32_dpp v95, v84 row_ror:8 row_mask:0xf bank_mask:0xf
	v_mov_b32_dpp v96, v85 row_ror:8 row_mask:0xf bank_mask:0xf
	v_mov_b32_dpp v97, v86 row_ror:8 row_mask:0xf bank_mask:0xf
	v_mov_b32_dpp v98, v87 row_ror:8 row_mask:0xf bank_mask:0xf
	v_mov_b32_dpp v99, v88 row_ror:8 row_mask:0xf bank_mask:0xf
	v_mov_b32_dpp v100, v89 row_ror:8 row_mask:0xf bank_mask:0xf
	v_cndmask_b32_e64 v89, v89, v96, s[6:7]
	v_cndmask_b32_e64 v88, v88, v95, s[6:7]
	v_cndmask_b32_e64 v87, v87, v94, s[6:7]
	v_cndmask_b32_e64 v81, v86, v81, s[6:7]
	v_cndmask_b32_e64 v98, v98, v83, s[6:7]
	v_cndmask_b32_e64 v95, v97, v82, s[6:7]
	v_cndmask_b32_e64 v101, v100, v85, s[6:7]
	v_cndmask_b32_e64 v99, v99, v84, s[6:7]
	v_lshlrev_b32_e32 v82, 16, v81
	v_and_b32_e32 v83, 0xffff0000, v81
	v_lshlrev_b32_e32 v84, 16, v87
	v_and_b32_e32 v85, 0xffff0000, v87
	v_lshlrev_b32_e32 v86, 16, v88
	v_and_b32_e32 v87, 0xffff0000, v88
	v_lshlrev_b32_e32 v88, 16, v89
	v_and_b32_e32 v89, 0xffff0000, v89
	v_lshlrev_b32_e32 v94, 16, v95
	v_and_b32_e32 v95, 0xffff0000, v95
	v_lshlrev_b32_e32 v96, 16, v98
	v_and_b32_e32 v97, 0xffff0000, v98
	v_lshlrev_b32_e32 v98, 16, v99
	v_and_b32_e32 v99, 0xffff0000, v99
	v_lshlrev_b32_e32 v100, 16, v101
	v_and_b32_e32 v101, 0xffff0000, v101
	v_pk_add_f32 v[82:83], v[68:69], v[82:83]
	v_pk_add_f32 v[88:89], v[66:67], v[88:89]
	v_pk_add_f32 v[66:67], v[78:79], v[96:97]
	v_pk_add_f32 v[68:69], v[76:77], v[94:95]
	v_pk_add_f32 v[84:85], v[70:71], v[84:85]
	v_pk_add_f32 v[70:71], v[74:75], v[100:101]
	v_pk_add_f32 v[72:73], v[72:73], v[98:99]
	v_mul_f32_e32 v74, v69, v69
	v_mul_f32_e32 v75, v67, v67
	v_mul_f32_e32 v76, v73, v73
	v_fmac_f32_e32 v74, v68, v68
	v_fmac_f32_e32 v75, v66, v66
	v_pk_add_f32 v[64:65], v[64:65], v[86:87]
	v_mul_f32_e32 v77, v71, v71
	v_cvt_pk_bf16_f32 v69, v68, v69
	v_fmac_f32_e32 v76, v72, v72
	v_add_f32_e32 v68, v74, v75
	v_mul_f32_e32 v74, v83, v83
	v_mul_f32_e32 v75, v85, v85
	v_cvt_pk_bf16_f32 v67, v66, v67
	v_cvt_pk_bf16_f32 v73, v72, v73
	v_cvt_pk_bf16_f32 v71, v70, v71
	v_cvt_pk_bf16_f32 v78, v82, v83
	v_cvt_pk_bf16_f32 v79, v84, v85
	v_cvt_pk_bf16_f32 v81, v64, v65
	v_fmac_f32_e32 v77, v70, v70
	v_add_f32_e32 v68, v76, v68
	v_mov_b32_dpp v108, v81 row_ror:8 row_mask:0xf bank_mask:0xf
	v_fmac_f32_e32 v74, v82, v82
	v_fmac_f32_e32 v75, v84, v84
	v_mul_f32_e32 v65, v65, v65
	v_mov_b32_dpp v104, v73 row_ror:8 row_mask:0xf bank_mask:0xf
	v_add_f32_e32 v72, v77, v68
	v_cndmask_b32_e64 v68, v108, v73, s[6:7]
	v_mul_f32_e32 v73, v89, v89
	v_add_f32_e32 v74, v74, v75
	v_fmac_f32_e32 v65, v64, v64
	v_fmac_f32_e32 v73, v88, v88
	v_add_f32_e32 v64, v65, v74
	v_add_f32_e32 v64, v73, v64
	v_add_f32_e32 v76, v64, v72
	ds_bpermute_b32 v77, v114, v76
	v_lshl_add_u64 v[64:65], s[16:17], 0, v[90:91]
	v_lshl_add_u64 v[74:75], v[64:65], 0, v[146:147]
	v_cvt_pk_bf16_f32 v86, v88, v89
	v_mov_b32_dpp v106, v78 row_ror:8 row_mask:0xf bank_mask:0xf
	s_waitcnt lgkmcnt(0)
	v_add_f32_e32 v64, v76, v77
	ds_bpermute_b32 v65, v115, v64
	v_mov_b32_dpp v107, v79 row_ror:8 row_mask:0xf bank_mask:0xf
	v_mov_b32_dpp v109, v86 row_ror:8 row_mask:0xf bank_mask:0xf
	v_mov_b32_dpp v102, v69 row_ror:8 row_mask:0xf bank_mask:0xf
	v_mov_b32_dpp v103, v67 row_ror:8 row_mask:0xf bank_mask:0xf
	v_cndmask_b32_e64 v66, v106, v69, s[6:7]
	v_cndmask_b32_e64 v67, v107, v67, s[6:7]
	v_cndmask_b32_e64 v69, v109, v71, s[6:7]
	v_mov_b32_dpp v105, v71 row_ror:8 row_mask:0xf bank_mask:0xf
	global_store_dwordx4 v[74:75], v[66:69], off
	v_cndmask_b32_e64 v70, v78, v102, s[6:7]
	v_cndmask_b32_e64 v71, v79, v103, s[6:7]
	v_lshl_add_u64 v[66:67], s[16:17], 0, v[92:93]
	v_cndmask_b32_e64 v72, v81, v104, s[6:7]
	v_cndmask_b32_e64 v73, v86, v105, s[6:7]
	v_lshl_add_u64 v[66:67], v[66:67], 0, v[146:147]
	global_store_dwordx4 v[66:67], v[70:73], off
	s_and_saveexec_b64 s[42:43], s[8:9]
	s_cbranch_execz .LBB0_1254
	v_ashrrev_i32_e32 v81, 31, v80
	s_waitcnt lgkmcnt(0)
	v_add_f32_e32 v66, v64, v65
	v_lshl_add_u64 v[64:65], v[80:81], 2, s[18:19]
	global_atomic_add_f32 v[64:65], v66, off
; __device__ __forceinline__ void store_pair_lines(bf16_t* O, int ldc, int row, int fr, int col0, u32x4 wA, u32x4 wB) {
;     const u32x4 sA = {dpp_ror8(wA.x), dpp_ror8(wA.y), dpp_ror8(wA.z), dpp_ror8(wA.w)}, sB = {dpp_ror8(wB.x), dpp_ror8(wB.y), dpp_ror8(wB.z), dpp_ror8(wB.w)};
;     const bool lo = fr < 8;
;     const u32x4 o1 = lo ? wA : sB, o2 = lo ? sA : wB;
;     const int r1 = row - fr + (fr & 7), cb = col0 + (lo ? 0 : 8);
;     *(u32x4*)(O + (size_t)r1 * ldc + cb) = o1;
;     *(u32x4*)(O + (size_t)(r1 + 8) * ldc + cb) = o2;
; }
;     const bool lo = fr < 8;
;     const int r1 = row - fr + (fr & 7), cb = col0 + (lo ? 0 : boff);
;     const u32x4 l1 = *(const u32x4*)(P + (size_t)r1 * ld + cb), l2 = *(const u32x4*)(P + (size_t)(r1 + 8) * ld + cb);
;     __device__ __forceinline__ void operator()(const f32x4 (&acc)[2][2][4][2], const Unit& u, int wr, int wc, int fr, int fq) const {
;     ...
;             for (int m = 0; m < 4; ++m) { const int row = row0 + ai * HALF + m * 16; const size_t off = (size_t)row * D + col0; float sq = 0.f; u32x4 w[2];
;                 const float sc = rsin ? __builtin_amdgcn_rcpf(rsin[row] * (1.f / D) + EPS) : 1.0f;
;                 u32x4 rr[2]; if (R) load_pair_lines(R, D, row, fr, col0, rr[0], rr[1]);
; #pragma unroll
;                 for (int bj = 0; bj < 2; ++bj) { f32x4 r0, r1;
;                     if (R) { const u32x4 rw = rr[bj]; r0 = (f32x4){bflo(rw.x), bfhi(rw.x), bflo(rw.y), bfhi(rw.y)}; r1 = (f32x4){bflo(rw.z), bfhi(rw.z), bflo(rw.w), bfhi(rw.w)}; }
;                     else { const float* rp = (row < 8192 ? src_p + off : src_s + (off - (size_t)8192 * D)) + 8 * bj; r0 = *(const f32x4*)rp; r1 = *(const f32x4*)(rp + 4); }
;                     const f32x4 o0 = r0 + acc[ai][bj][m][0] * sc, o1 = r1 + acc[ai][bj][m][1] * sc;
;                     sq += (o0[0] * o0[0] + o0[1] * o0[1]) + (o0[2] * o0[2] + o0[3] * o0[3]) + (o1[0] * o1[0] + o1[1] * o1[1]) + (o1[2] * o1[2] + o1[3] * o1[3]);
;                     w[bj].x = cvt_pk_bf16(o0[0], o0[1]); w[bj].y = cvt_pk_bf16(o0[2], o0[3]); w[bj].z = cvt_pk_bf16(o1[0], o1[1]); w[bj].w = cvt_pk_bf16(o1[2], o1[3]); }
;                 store_pair_lines(O, D, row, fr, col0, w[0], w[1]);
;                 if (ssout) { sq += __shfl_xor(sq, 16); sq += __shfl_xor(sq, 32); if (fq == 0) unsafeAtomicAdd(ssout + row, sq); } }
.LBB0_1254:
	s_or_b64 exec, exec, s[42:43]
	v_add_u32_e32 v64, 0x80, v148
	s_waitcnt lgkmcnt(0)
	v_sub_u32_e32 v65, v64, v150
	v_add_u32_e32 v66, v65, v152
	v_ashrrev_i32_e32 v67, 31, v66
	v_lshlrev_b64 v[74:75], 12, v[66:67]
	v_lshl_add_u64 v[76:77], v[74:75], 0, s[28:29]
	v_lshl_add_u64 v[66:67], s[10:11], 0, v[74:75]
	v_lshl_add_u64 v[70:71], s[10:11], 0, v[76:77]
	v_lshl_add_u64 v[66:67], v[66:67], 0, v[146:147]
	v_lshl_add_u64 v[70:71], v[70:71], 0, v[146:147]
	s_waitcnt vmcnt(14)
	s_nop 0
	v_mov_b64_e32 v[66:67], v[224:225]
	v_mov_b64_e32 v[68:69], v[226:227]
	v_mov_b64_e32 v[70:71], v[228:229]
	v_mov_b64_e32 v[72:73], v[230:231]
	s_nop 1
	v_mov_b32_dpp v65, v66 row_ror:8 row_mask:0xf bank_mask:0xf
	v_mov_b32_dpp v78, v67 row_ror:8 row_mask:0xf bank_mask:0xf
	v_mov_b32_dpp v79, v68 row_ror:8 row_mask:0xf bank_mask:0xf
	v_mov_b32_dpp v80, v69 row_ror:8 row_mask:0xf bank_mask:0xf
	v_mov_b32_dpp v81, v70 row_ror:8 row_mask:0xf bank_mask:0xf
	v_mov_b32_dpp v82, v71 row_ror:8 row_mask:0xf bank_mask:0xf
	v_mov_b32_dpp v83, v72 row_ror:8 row_mask:0xf bank_mask:0xf
	v_mov_b32_dpp v84, v73 row_ror:8 row_mask:0xf bank_mask:0xf
	v_cndmask_b32_e64 v73, v73, v80, s[6:7]
	v_cndmask_b32_e64 v72, v72, v79, s[6:7]
	v_cndmask_b32_e64 v71, v71, v78, s[6:7]
	v_cndmask_b32_e64 v65, v70, v65, s[6:7]
	v_cndmask_b32_e64 v82, v82, v67, s[6:7]
	v_cndmask_b32_e64 v79, v81, v66, s[6:7]
	v_cndmask_b32_e64 v85, v84, v69, s[6:7]
	v_cndmask_b32_e64 v83, v83, v68, s[6:7]
	v_lshlrev_b32_e32 v66, 16, v65
	v_and_b32_e32 v67, 0xffff0000, v65
	v_lshlrev_b32_e32 v68, 16, v71
	v_and_b32_e32 v69, 0xffff0000, v71
	v_lshlrev_b32_e32 v70, 16, v72
	v_and_b32_e32 v71, 0xffff0000, v72
	v_lshlrev_b32_e32 v72, 16, v73
	v_and_b32_e32 v73, 0xffff0000, v73
	v_lshlrev_b32_e32 v78, 16, v79
	v_and_b32_e32 v79, 0xffff0000, v79
	v_lshlrev_b32_e32 v80, 16, v82
	v_and_b32_e32 v81, 0xffff0000, v82
	v_lshlrev_b32_e32 v82, 16, v83
	v_and_b32_e32 v83, 0xffff0000, v83
	v_lshlrev_b32_e32 v84, 16, v85
	v_and_b32_e32 v85, 0xffff0000, v85
	v_pk_add_f32 v[66:67], v[52:53], v[66:67]
	v_pk_add_f32 v[72:73], v[50:51], v[72:73]
	v_pk_add_f32 v[50:51], v[62:63], v[80:81]
	v_pk_add_f32 v[52:53], v[60:61], v[78:79]
	v_pk_add_f32 v[68:69], v[54:55], v[68:69]
	v_pk_add_f32 v[54:55], v[58:59], v[84:85]
	v_pk_add_f32 v[56:57], v[56:57], v[82:83]
	v_mul_f32_e32 v58, v53, v53
	v_mul_f32_e32 v59, v51, v51
	v_mul_f32_e32 v60, v57, v57
	v_fmac_f32_e32 v58, v52, v52
	v_fmac_f32_e32 v59, v50, v50
	v_pk_add_f32 v[48:49], v[48:49], v[70:71]
	v_mul_f32_e32 v61, v55, v55
	v_cvt_pk_bf16_f32 v53, v52, v53
	v_fmac_f32_e32 v60, v56, v56
	v_add_f32_e32 v52, v58, v59
	v_mul_f32_e32 v58, v67, v67
	v_mul_f32_e32 v59, v69, v69
	v_cvt_pk_bf16_f32 v51, v50, v51
	v_cvt_pk_bf16_f32 v57, v56, v57
	v_cvt_pk_bf16_f32 v55, v54, v55
	v_cvt_pk_bf16_f32 v62, v66, v67
	v_cvt_pk_bf16_f32 v63, v68, v69
	v_cvt_pk_bf16_f32 v65, v48, v49
	v_fmac_f32_e32 v61, v54, v54
	v_add_f32_e32 v52, v60, v52
	v_mov_b32_dpp v92, v65 row_ror:8 row_mask:0xf bank_mask:0xf
	v_fmac_f32_e32 v58, v66, v66
	v_fmac_f32_e32 v59, v68, v68
	v_mul_f32_e32 v49, v49, v49
	v_mov_b32_dpp v88, v57 row_ror:8 row_mask:0xf bank_mask:0xf
	v_add_f32_e32 v56, v61, v52
	v_cndmask_b32_e64 v52, v92, v57, s[6:7]
	v_mul_f32_e32 v57, v73, v73
	v_add_f32_e32 v58, v58, v59
	v_fmac_f32_e32 v49, v48, v48
	v_fmac_f32_e32 v57, v72, v72
	v_add_f32_e32 v48, v49, v58
	v_add_f32_e32 v48, v57, v48
	v_add_f32_e32 v60, v48, v56
	ds_bpermute_b32 v61, v114, v60
	v_lshl_add_u64 v[48:49], s[16:17], 0, v[74:75]
	v_lshl_add_u64 v[58:59], v[48:49], 0, v[146:147]
	v_cvt_pk_bf16_f32 v70, v72, v73
	v_mov_b32_dpp v90, v62 row_ror:8 row_mask:0xf bank_mask:0xf
	s_waitcnt lgkmcnt(0)
	v_add_f32_e32 v48, v60, v61
	ds_bpermute_b32 v49, v115, v48
	v_mov_b32_dpp v91, v63 row_ror:8 row_mask:0xf bank_mask:0xf
	v_mov_b32_dpp v93, v70 row_ror:8 row_mask:0xf bank_mask:0xf
	v_mov_b32_dpp v86, v53 row_ror:8 row_mask:0xf bank_mask:0xf
	v_mov_b32_dpp v87, v51 row_ror:8 row_mask:0xf bank_mask:0xf
	v_cndmask_b32_e64 v50, v90, v53, s[6:7]
	v_cndmask_b32_e64 v51, v91, v51, s[6:7]
	v_cndmask_b32_e64 v53, v93, v55, s[6:7]
	v_mov_b32_dpp v89, v55 row_ror:8 row_mask:0xf bank_mask:0xf
	global_store_dwordx4 v[58:59], v[50:53], off
	v_cndmask_b32_e64 v54, v62, v86, s[6:7]
	v_cndmask_b32_e64 v55, v63, v87, s[6:7]
	v_lshl_add_u64 v[50:51], s[16:17], 0, v[76:77]
	v_cndmask_b32_e64 v56, v65, v88, s[6:7]
	v_cndmask_b32_e64 v57, v70, v89, s[6:7]
	v_lshl_add_u64 v[50:51], v[50:51], 0, v[146:147]
	global_store_dwordx4 v[50:51], v[54:57], off
	s_and_saveexec_b64 s[42:43], s[8:9]
	s_cbranch_execz .LBB0_1256
	v_ashrrev_i32_e32 v65, 31, v64
	s_waitcnt lgkmcnt(0)
	v_add_f32_e32 v50, v48, v49
	v_lshl_add_u64 v[48:49], v[64:65], 2, s[18:19]
	global_atomic_add_f32 v[48:49], v50, off
; __device__ __forceinline__ void store_pair_lines(bf16_t* O, int ldc, int row, int fr, int col0, u32x4 wA, u32x4 wB) {
;     const u32x4 sA = {dpp_ror8(wA.x), dpp_ror8(wA.y), dpp_ror8(wA.z), dpp_ror8(wA.w)}, sB = {dpp_ror8(wB.x), dpp_ror8(wB.y), dpp_ror8(wB.z), dpp_ror8(wB.w)};
;     const bool lo = fr < 8;
;     const u32x4 o1 = lo ? wA : sB, o2 = lo ? sA : wB;
;     const int r1 = row - fr + (fr & 7), cb = col0 + (lo ? 0 : 8);
;     *(u32x4*)(O + (size_t)r1 * ldc + cb) = o1;
;     *(u32x4*)(O + (size_t)(r1 + 8) * ldc + cb) = o2;
; }
;     const bool lo = fr < 8;
;     const int r1 = row - fr + (fr & 7), cb = col0 + (lo ? 0 : boff);
;     const u32x4 l1 = *(const u32x4*)(P + (size_t)r1 * ld + cb), l2 = *(const u32x4*)(P + (size_t)(r1 + 8) * ld + cb);
;     __device__ __forceinline__ void operator()(const f32x4 (&acc)[2][2][4][2], const Unit& u, int wr, int wc, int fr, int fq) const {
;     ...
;             for (int m = 0; m < 4; ++m) { const int row = row0 + ai * HALF + m * 16; const size_t off = (size_t)row * D + col0; float sq = 0.f; u32x4 w[2];
;                 const float sc = rsin ? __builtin_amdgcn_rcpf(rsin[row] * (1.f / D) + EPS) : 1.0f;
;                 u32x4 rr[2]; if (R) load_pair_lines(R, D, row, fr, col0, rr[0], rr[1]);
; #pragma unroll
;                 for (int bj = 0; bj < 2; ++bj) { f32x4 r0, r1;
;                     if (R) { const u32x4 rw = rr[bj]; r0 = (f32x4){bflo(rw.x), bfhi(rw.x), bflo(rw.y), bfhi(rw.y)}; r1 = (f32x4){bflo(rw.z), bfhi(rw.z), bflo(rw.w), bfhi(rw.w)}; }
;                     else { const float* rp = (row < 8192 ? src_p + off : src_s + (off - (size_t)8192 * D)) + 8 * bj; r0 = *(const f32x4*)rp; r1 = *(const f32x4*)(rp + 4); }
;                     const f32x4 o0 = r0 + acc[ai][bj][m][0] * sc, o1 = r1 + acc[ai][bj][m][1] * sc;
;                     sq += (o0[0] * o0[0] + o0[1] * o0[1]) + (o0[2] * o0[2] + o0[3] * o0[3]) + (o1[0] * o1[0] + o1[1] * o1[1]) + (o1[2] * o1[2] + o1[3] * o1[3]);
;                     w[bj].x = cvt_pk_bf16(o0[0], o0[1]); w[bj].y = cvt_pk_bf16(o0[2], o0[3]); w[bj].z = cvt_pk_bf16(o1[0], o1[1]); w[bj].w = cvt_pk_bf16(o1[2], o1[3]); }
;                 store_pair_lines(O, D, row, fr, col0, w[0], w[1]);
;                 if (ssout) { sq += __shfl_xor(sq, 16); sq += __shfl_xor(sq, 32); if (fq == 0) unsafeAtomicAdd(ssout + row, sq); } }
.LBB0_1256:
	s_or_b64 exec, exec, s[42:43]
	v_add_u32_e32 v48, 0x90, v148
	s_waitcnt lgkmcnt(0)
	v_sub_u32_e32 v49, v48, v150
	v_add_u32_e32 v50, v49, v152
	v_ashrrev_i32_e32 v51, 31, v50
	v_lshlrev_b64 v[58:59], 12, v[50:51]
	v_lshl_add_u64 v[60:61], v[58:59], 0, s[28:29]
	v_lshl_add_u64 v[50:51], s[10:11], 0, v[58:59]
	v_lshl_add_u64 v[54:55], s[10:11], 0, v[60:61]
	v_lshl_add_u64 v[50:51], v[50:51], 0, v[146:147]
	v_lshl_add_u64 v[54:55], v[54:55], 0, v[146:147]
	s_waitcnt vmcnt(14)
	s_nop 0
	v_mov_b64_e32 v[50:51], v[232:233]
	v_mov_b64_e32 v[52:53], v[234:235]
	v_mov_b64_e32 v[54:55], v[236:237]
	v_mov_b64_e32 v[56:57], v[238:239]
	s_nop 1
	v_mov_b32_dpp v49, v50 row_ror:8 row_mask:0xf bank_mask:0xf
	v_mov_b32_dpp v62, v51 row_ror:8 row_mask:0xf bank_mask:0xf
	v_mov_b32_dpp v63, v52 row_ror:8 row_mask:0xf bank_mask:0xf
	v_mov_b32_dpp v64, v53 row_ror:8 row_mask:0xf bank_mask:0xf
	v_mov_b32_dpp v65, v54 row_ror:8 row_mask:0xf bank_mask:0xf
	v_mov_b32_dpp v66, v55 row_ror:8 row_mask:0xf bank_mask:0xf
	v_mov_b32_dpp v67, v56 row_ror:8 row_mask:0xf bank_mask:0xf
	v_mov_b32_dpp v68, v57 row_ror:8 row_mask:0xf bank_mask:0xf
	v_cndmask_b32_e64 v57, v57, v64, s[6:7]
	v_cndmask_b32_e64 v56, v56, v63, s[6:7]
	v_cndmask_b32_e64 v55, v55, v62, s[6:7]
	v_cndmask_b32_e64 v49, v54, v49, s[6:7]
	v_cndmask_b32_e64 v66, v66, v51, s[6:7]
	v_cndmask_b32_e64 v63, v65, v50, s[6:7]
	v_cndmask_b32_e64 v69, v68, v53, s[6:7]
	v_cndmask_b32_e64 v67, v67, v52, s[6:7]
	v_lshlrev_b32_e32 v50, 16, v49
	v_and_b32_e32 v51, 0xffff0000, v49
	v_lshlrev_b32_e32 v52, 16, v55
	v_and_b32_e32 v53, 0xffff0000, v55
	v_lshlrev_b32_e32 v54, 16, v56
	v_and_b32_e32 v55, 0xffff0000, v56
	v_lshlrev_b32_e32 v56, 16, v57
	v_and_b32_e32 v57, 0xffff0000, v57
	v_lshlrev_b32_e32 v62, 16, v63
	v_and_b32_e32 v63, 0xffff0000, v63
	v_lshlrev_b32_e32 v64, 16, v66
	v_and_b32_e32 v65, 0xffff0000, v66
	v_lshlrev_b32_e32 v66, 16, v67
	v_and_b32_e32 v67, 0xffff0000, v67
	v_lshlrev_b32_e32 v68, 16, v69
	v_and_b32_e32 v69, 0xffff0000, v69
	v_pk_add_f32 v[50:51], v[36:37], v[50:51]
	v_pk_add_f32 v[56:57], v[34:35], v[56:57]
	v_pk_add_f32 v[34:35], v[46:47], v[64:65]
	v_pk_add_f32 v[36:37], v[44:45], v[62:63]
	v_pk_add_f32 v[52:53], v[38:39], v[52:53]
	v_pk_add_f32 v[38:39], v[42:43], v[68:69]
	v_pk_add_f32 v[40:41], v[40:41], v[66:67]
	v_mul_f32_e32 v42, v37, v37
	v_mul_f32_e32 v43, v35, v35
	v_mul_f32_e32 v44, v41, v41
	v_fmac_f32_e32 v42, v36, v36
	v_fmac_f32_e32 v43, v34, v34
	v_pk_add_f32 v[32:33], v[32:33], v[54:55]
	v_mul_f32_e32 v45, v39, v39
	v_cvt_pk_bf16_f32 v37, v36, v37
	v_fmac_f32_e32 v44, v40, v40
	v_add_f32_e32 v36, v42, v43
	v_mul_f32_e32 v42, v51, v51
	v_mul_f32_e32 v43, v53, v53
	v_cvt_pk_bf16_f32 v35, v34, v35
	v_cvt_pk_bf16_f32 v41, v40, v41
	v_cvt_pk_bf16_f32 v39, v38, v39
	v_cvt_pk_bf16_f32 v46, v50, v51
	v_cvt_pk_bf16_f32 v47, v52, v53
	v_cvt_pk_bf16_f32 v49, v32, v33
	v_fmac_f32_e32 v45, v38, v38
	v_add_f32_e32 v36, v44, v36
	v_mov_b32_dpp v76, v49 row_ror:8 row_mask:0xf bank_mask:0xf
	v_fmac_f32_e32 v42, v50, v50
	v_fmac_f32_e32 v43, v52, v52
	v_mul_f32_e32 v33, v33, v33
	v_mov_b32_dpp v72, v41 row_ror:8 row_mask:0xf bank_mask:0xf
	v_add_f32_e32 v40, v45, v36
	v_cndmask_b32_e64 v36, v76, v41, s[6:7]
	v_mul_f32_e32 v41, v57, v57
	v_add_f32_e32 v42, v42, v43
	v_fmac_f32_e32 v33, v32, v32
	v_fmac_f32_e32 v41, v56, v56
	v_add_f32_e32 v32, v33, v42
	v_add_f32_e32 v32, v41, v32
	v_add_f32_e32 v44, v32, v40
	ds_bpermute_b32 v45, v114, v44
	v_lshl_add_u64 v[32:33], s[16:17], 0, v[58:59]
	v_lshl_add_u64 v[42:43], v[32:33], 0, v[146:147]
	v_cvt_pk_bf16_f32 v54, v56, v57
	v_mov_b32_dpp v74, v46 row_ror:8 row_mask:0xf bank_mask:0xf
	s_waitcnt lgkmcnt(0)
	v_add_f32_e32 v32, v44, v45
	ds_bpermute_b32 v33, v115, v32
	v_mov_b32_dpp v75, v47 row_ror:8 row_mask:0xf bank_mask:0xf
	v_mov_b32_dpp v77, v54 row_ror:8 row_mask:0xf bank_mask:0xf
	v_mov_b32_dpp v70, v37 row_ror:8 row_mask:0xf bank_mask:0xf
	v_mov_b32_dpp v71, v35 row_ror:8 row_mask:0xf bank_mask:0xf
	v_cndmask_b32_e64 v34, v74, v37, s[6:7]
	v_cndmask_b32_e64 v35, v75, v35, s[6:7]
	v_cndmask_b32_e64 v37, v77, v39, s[6:7]
	v_mov_b32_dpp v73, v39 row_ror:8 row_mask:0xf bank_mask:0xf
	global_store_dwordx4 v[42:43], v[34:37], off
	v_cndmask_b32_e64 v38, v46, v70, s[6:7]
	v_cndmask_b32_e64 v39, v47, v71, s[6:7]
	v_lshl_add_u64 v[34:35], s[16:17], 0, v[60:61]
	v_cndmask_b32_e64 v40, v49, v72, s[6:7]
	v_cndmask_b32_e64 v41, v54, v73, s[6:7]
	v_lshl_add_u64 v[34:35], v[34:35], 0, v[146:147]
	global_store_dwordx4 v[34:35], v[38:41], off
	s_and_saveexec_b64 s[42:43], s[8:9]
	s_cbranch_execz .LBB0_1258
	v_ashrrev_i32_e32 v49, 31, v48
	s_waitcnt lgkmcnt(0)
	v_add_f32_e32 v34, v32, v33
	v_lshl_add_u64 v[32:33], v[48:49], 2, s[18:19]
	global_atomic_add_f32 v[32:33], v34, off
; __device__ __forceinline__ void store_pair_lines(bf16_t* O, int ldc, int row, int fr, int col0, u32x4 wA, u32x4 wB) {
;     const u32x4 sA = {dpp_ror8(wA.x), dpp_ror8(wA.y), dpp_ror8(wA.z), dpp_ror8(wA.w)}, sB = {dpp_ror8(wB.x), dpp_ror8(wB.y), dpp_ror8(wB.z), dpp_ror8(wB.w)};
;     const bool lo = fr < 8;
;     const u32x4 o1 = lo ? wA : sB, o2 = lo ? sA : wB;
;     const int r1 = row - fr + (fr & 7), cb = col0 + (lo ? 0 : 8);
;     *(u32x4*)(O + (size_t)r1 * ldc + cb) = o1;
;     *(u32x4*)(O + (size_t)(r1 + 8) * ldc + cb) = o2;
; }
;     const bool lo = fr < 8;
;     const int r1 = row - fr + (fr & 7), cb = col0 + (lo ? 0 : boff);
;     const u32x4 l1 = *(const u32x4*)(P + (size_t)r1 * ld + cb), l2 = *(const u32x4*)(P + (size_t)(r1 + 8) * ld + cb);
;     __device__ __forceinline__ void operator()(const f32x4 (&acc)[2][2][4][2], const Unit& u, int wr, int wc, int fr, int fq) const {
;     ...
;             for (int m = 0; m < 4; ++m) { const int row = row0 + ai * HALF + m * 16; const size_t off = (size_t)row * D + col0; float sq = 0.f; u32x4 w[2];
;                 const float sc = rsin ? __builtin_amdgcn_rcpf(rsin[row] * (1.f / D) + EPS) : 1.0f;
;                 u32x4 rr[2]; if (R) load_pair_lines(R, D, row, fr, col0, rr[0], rr[1]);
; #pragma unroll
;                 for (int bj = 0; bj < 2; ++bj) { f32x4 r0, r1;
;                     if (R) { const u32x4 rw = rr[bj]; r0 = (f32x4){bflo(rw.x), bfhi(rw.x), bflo(rw.y), bfhi(rw.y)}; r1 = (f32x4){bflo(rw.z), bfhi(rw.z), bflo(rw.w), bfhi(rw.w)}; }
;                     else { const float* rp = (row < 8192 ? src_p + off : src_s + (off - (size_t)8192 * D)) + 8 * bj; r0 = *(const f32x4*)rp; r1 = *(const f32x4*)(rp + 4); }
;                     const f32x4 o0 = r0 + acc[ai][bj][m][0] * sc, o1 = r1 + acc[ai][bj][m][1] * sc;
;                     sq += (o0[0] * o0[0] + o0[1] * o0[1]) + (o0[2] * o0[2] + o0[3] * o0[3]) + (o1[0] * o1[0] + o1[1] * o1[1]) + (o1[2] * o1[2] + o1[3] * o1[3]);
;                     w[bj].x = cvt_pk_bf16(o0[0], o0[1]); w[bj].y = cvt_pk_bf16(o0[2], o0[3]); w[bj].z = cvt_pk_bf16(o1[0], o1[1]); w[bj].w = cvt_pk_bf16(o1[2], o1[3]); }
;                 store_pair_lines(O, D, row, fr, col0, w[0], w[1]);
;                 if (ssout) { sq += __shfl_xor(sq, 16); sq += __shfl_xor(sq, 32); if (fq == 0) unsafeAtomicAdd(ssout + row, sq); } }
.LBB0_1258:
	s_or_b64 exec, exec, s[42:43]
	v_add_u32_e32 v32, 0xa0, v148
	s_waitcnt lgkmcnt(0)
	v_sub_u32_e32 v33, v32, v150
	v_add_u32_e32 v34, v33, v152
	v_ashrrev_i32_e32 v35, 31, v34
	v_lshlrev_b64 v[42:43], 12, v[34:35]
	v_lshl_add_u64 v[44:45], v[42:43], 0, s[28:29]
	v_lshl_add_u64 v[34:35], s[10:11], 0, v[42:43]
	v_lshl_add_u64 v[38:39], s[10:11], 0, v[44:45]
	v_lshl_add_u64 v[34:35], v[34:35], 0, v[146:147]
	v_lshl_add_u64 v[38:39], v[38:39], 0, v[146:147]
	s_waitcnt vmcnt(14)
	s_nop 0
	v_mov_b64_e32 v[34:35], v[240:241]
	v_mov_b64_e32 v[36:37], v[242:243]
	v_mov_b64_e32 v[38:39], v[244:245]
	v_mov_b64_e32 v[40:41], v[246:247]
	s_nop 1
	v_mov_b32_dpp v33, v34 row_ror:8 row_mask:0xf bank_mask:0xf
	v_mov_b32_dpp v46, v35 row_ror:8 row_mask:0xf bank_mask:0xf
	v_mov_b32_dpp v47, v36 row_ror:8 row_mask:0xf bank_mask:0xf
	v_mov_b32_dpp v48, v37 row_ror:8 row_mask:0xf bank_mask:0xf
	v_mov_b32_dpp v49, v38 row_ror:8 row_mask:0xf bank_mask:0xf
	v_mov_b32_dpp v50, v39 row_ror:8 row_mask:0xf bank_mask:0xf
	v_mov_b32_dpp v51, v40 row_ror:8 row_mask:0xf bank_mask:0xf
	v_mov_b32_dpp v52, v41 row_ror:8 row_mask:0xf bank_mask:0xf
	v_cndmask_b32_e64 v41, v41, v48, s[6:7]
	v_cndmask_b32_e64 v40, v40, v47, s[6:7]
	v_cndmask_b32_e64 v39, v39, v46, s[6:7]
	v_cndmask_b32_e64 v33, v38, v33, s[6:7]
	v_cndmask_b32_e64 v50, v50, v35, s[6:7]
	v_cndmask_b32_e64 v47, v49, v34, s[6:7]
	v_cndmask_b32_e64 v53, v52, v37, s[6:7]
	v_cndmask_b32_e64 v51, v51, v36, s[6:7]
	v_lshlrev_b32_e32 v34, 16, v33
	v_and_b32_e32 v35, 0xffff0000, v33
	v_lshlrev_b32_e32 v36, 16, v39
	v_and_b32_e32 v37, 0xffff0000, v39
	v_lshlrev_b32_e32 v38, 16, v40
	v_and_b32_e32 v39, 0xffff0000, v40
	v_lshlrev_b32_e32 v40, 16, v41
	v_and_b32_e32 v41, 0xffff0000, v41
	v_lshlrev_b32_e32 v46, 16, v47
	v_and_b32_e32 v47, 0xffff0000, v47
	v_lshlrev_b32_e32 v48, 16, v50
	v_and_b32_e32 v49, 0xffff0000, v50
	v_lshlrev_b32_e32 v50, 16, v51
	v_and_b32_e32 v51, 0xffff0000, v51
	v_lshlrev_b32_e32 v52, 16, v53
	v_and_b32_e32 v53, 0xffff0000, v53
	v_pk_add_f32 v[34:35], v[20:21], v[34:35]
	v_pk_add_f32 v[40:41], v[18:19], v[40:41]
	v_pk_add_f32 v[18:19], v[30:31], v[48:49]
	v_pk_add_f32 v[20:21], v[28:29], v[46:47]
	v_pk_add_f32 v[36:37], v[22:23], v[36:37]
	v_pk_add_f32 v[22:23], v[26:27], v[52:53]
	v_pk_add_f32 v[24:25], v[24:25], v[50:51]
	v_mul_f32_e32 v26, v21, v21
	v_mul_f32_e32 v27, v19, v19
	v_mul_f32_e32 v28, v25, v25
	v_fmac_f32_e32 v26, v20, v20
	v_fmac_f32_e32 v27, v18, v18
	v_pk_add_f32 v[16:17], v[16:17], v[38:39]
	v_mul_f32_e32 v29, v23, v23
	v_cvt_pk_bf16_f32 v21, v20, v21
	v_fmac_f32_e32 v28, v24, v24
	v_add_f32_e32 v20, v26, v27
	v_mul_f32_e32 v26, v35, v35
	v_mul_f32_e32 v27, v37, v37
	v_cvt_pk_bf16_f32 v19, v18, v19
	v_cvt_pk_bf16_f32 v25, v24, v25
	v_cvt_pk_bf16_f32 v23, v22, v23
	v_cvt_pk_bf16_f32 v30, v34, v35
	v_cvt_pk_bf16_f32 v31, v36, v37
	v_cvt_pk_bf16_f32 v33, v16, v17
	v_fmac_f32_e32 v29, v22, v22
	v_add_f32_e32 v20, v28, v20
	v_mov_b32_dpp v60, v33 row_ror:8 row_mask:0xf bank_mask:0xf
	v_fmac_f32_e32 v26, v34, v34
	v_fmac_f32_e32 v27, v36, v36
	v_mul_f32_e32 v17, v17, v17
	v_mov_b32_dpp v56, v25 row_ror:8 row_mask:0xf bank_mask:0xf
	v_add_f32_e32 v24, v29, v20
	v_cndmask_b32_e64 v20, v60, v25, s[6:7]
	v_mul_f32_e32 v25, v41, v41
	v_add_f32_e32 v26, v26, v27
	v_fmac_f32_e32 v17, v16, v16
	v_fmac_f32_e32 v25, v40, v40
	v_add_f32_e32 v16, v17, v26
	v_add_f32_e32 v16, v25, v16
	v_add_f32_e32 v28, v16, v24
	ds_bpermute_b32 v29, v114, v28
	v_lshl_add_u64 v[16:17], s[16:17], 0, v[42:43]
	v_lshl_add_u64 v[26:27], v[16:17], 0, v[146:147]
	v_cvt_pk_bf16_f32 v38, v40, v41
	v_mov_b32_dpp v58, v30 row_ror:8 row_mask:0xf bank_mask:0xf
	s_waitcnt lgkmcnt(0)
	v_add_f32_e32 v16, v28, v29
	ds_bpermute_b32 v17, v115, v16
	v_mov_b32_dpp v59, v31 row_ror:8 row_mask:0xf bank_mask:0xf
	v_mov_b32_dpp v61, v38 row_ror:8 row_mask:0xf bank_mask:0xf
	v_mov_b32_dpp v54, v21 row_ror:8 row_mask:0xf bank_mask:0xf
	v_mov_b32_dpp v55, v19 row_ror:8 row_mask:0xf bank_mask:0xf
	v_cndmask_b32_e64 v18, v58, v21, s[6:7]
	v_cndmask_b32_e64 v19, v59, v19, s[6:7]
	v_cndmask_b32_e64 v21, v61, v23, s[6:7]
	v_mov_b32_dpp v57, v23 row_ror:8 row_mask:0xf bank_mask:0xf
	global_store_dwordx4 v[26:27], v[18:21], off
	v_cndmask_b32_e64 v22, v30, v54, s[6:7]
	v_cndmask_b32_e64 v23, v31, v55, s[6:7]
	v_lshl_add_u64 v[18:19], s[16:17], 0, v[44:45]
	v_cndmask_b32_e64 v24, v33, v56, s[6:7]
	v_cndmask_b32_e64 v25, v38, v57, s[6:7]
	v_lshl_add_u64 v[18:19], v[18:19], 0, v[146:147]
	global_store_dwordx4 v[18:19], v[22:25], off
	s_and_saveexec_b64 s[42:43], s[8:9]
	s_cbranch_execz .LBB0_1260
	v_ashrrev_i32_e32 v33, 31, v32
	s_waitcnt lgkmcnt(0)
	v_add_f32_e32 v18, v16, v17
	v_lshl_add_u64 v[16:17], v[32:33], 2, s[18:19]
	global_atomic_add_f32 v[16:17], v18, off
; __device__ __forceinline__ void store_pair_lines(bf16_t* O, int ldc, int row, int fr, int col0, u32x4 wA, u32x4 wB) {
;     const u32x4 sA = {dpp_ror8(wA.x), dpp_ror8(wA.y), dpp_ror8(wA.z), dpp_ror8(wA.w)}, sB = {dpp_ror8(wB.x), dpp_ror8(wB.y), dpp_ror8(wB.z), dpp_ror8(wB.w)};
;     const bool lo = fr < 8;
;     const u32x4 o1 = lo ? wA : sB, o2 = lo ? sA : wB;
;     const int r1 = row - fr + (fr & 7), cb = col0 + (lo ? 0 : 8);
;     *(u32x4*)(O + (size_t)r1 * ldc + cb) = o1;
;     *(u32x4*)(O + (size_t)(r1 + 8) * ldc + cb) = o2;
; }
;     const bool lo = fr < 8;
;     const int r1 = row - fr + (fr & 7), cb = col0 + (lo ? 0 : boff);
;     const u32x4 l1 = *(const u32x4*)(P + (size_t)r1 * ld + cb), l2 = *(const u32x4*)(P + (size_t)(r1 + 8) * ld + cb);
;     __device__ __forceinline__ void operator()(const f32x4 (&acc)[2][2][4][2], const Unit& u, int wr, int wc, int fr, int fq) const {
;     ...
;             for (int m = 0; m < 4; ++m) { const int row = row0 + ai * HALF + m * 16; const size_t off = (size_t)row * D + col0; float sq = 0.f; u32x4 w[2];
;                 const float sc = rsin ? __builtin_amdgcn_rcpf(rsin[row] * (1.f / D) + EPS) : 1.0f;
;                 u32x4 rr[2]; if (R) load_pair_lines(R, D, row, fr, col0, rr[0], rr[1]);
; #pragma unroll
;                 for (int bj = 0; bj < 2; ++bj) { f32x4 r0, r1;
;                     if (R) { const u32x4 rw = rr[bj]; r0 = (f32x4){bflo(rw.x), bfhi(rw.x), bflo(rw.y), bfhi(rw.y)}; r1 = (f32x4){bflo(rw.z), bfhi(rw.z), bflo(rw.w), bfhi(rw.w)}; }
;                     else { const float* rp = (row < 8192 ? src_p + off : src_s + (off - (size_t)8192 * D)) + 8 * bj; r0 = *(const f32x4*)rp; r1 = *(const f32x4*)(rp + 4); }
;                     const f32x4 o0 = r0 + acc[ai][bj][m][0] * sc, o1 = r1 + acc[ai][bj][m][1] * sc;
;                     sq += (o0[0] * o0[0] + o0[1] * o0[1]) + (o0[2] * o0[2] + o0[3] * o0[3]) + (o1[0] * o1[0] + o1[1] * o1[1]) + (o1[2] * o1[2] + o1[3] * o1[3]);
;                     w[bj].x = cvt_pk_bf16(o0[0], o0[1]); w[bj].y = cvt_pk_bf16(o0[2], o0[3]); w[bj].z = cvt_pk_bf16(o1[0], o1[1]); w[bj].w = cvt_pk_bf16(o1[2], o1[3]); }
;                 store_pair_lines(O, D, row, fr, col0, w[0], w[1]);
;                 if (ssout) { sq += __shfl_xor(sq, 16); sq += __shfl_xor(sq, 32); if (fq == 0) unsafeAtomicAdd(ssout + row, sq); } }
.LBB0_1260:
	s_or_b64 exec, exec, s[42:43]
	v_add_u32_e32 v16, 0xb0, v148
	s_waitcnt lgkmcnt(0)
	v_sub_u32_e32 v17, v16, v150
	v_add_u32_e32 v18, v17, v152
	v_ashrrev_i32_e32 v19, 31, v18
	v_lshlrev_b64 v[26:27], 12, v[18:19]
	v_lshl_add_u64 v[28:29], v[26:27], 0, s[28:29]
	v_lshl_add_u64 v[18:19], s[10:11], 0, v[26:27]
	v_lshl_add_u64 v[22:23], s[10:11], 0, v[28:29]
	v_lshl_add_u64 v[18:19], v[18:19], 0, v[146:147]
	v_lshl_add_u64 v[22:23], v[22:23], 0, v[146:147]
	s_waitcnt vmcnt(12)
	s_nop 0
	v_mov_b64_e32 v[18:19], v[196:197]
	v_mov_b64_e32 v[20:21], v[198:199]
	v_mov_b64_e32 v[22:23], v[204:205]
	v_mov_b64_e32 v[24:25], v[206:207]
	s_nop 1
	v_mov_b32_dpp v17, v18 row_ror:8 row_mask:0xf bank_mask:0xf
	v_mov_b32_dpp v30, v19 row_ror:8 row_mask:0xf bank_mask:0xf
	v_mov_b32_dpp v31, v20 row_ror:8 row_mask:0xf bank_mask:0xf
	v_mov_b32_dpp v32, v21 row_ror:8 row_mask:0xf bank_mask:0xf
	v_mov_b32_dpp v33, v22 row_ror:8 row_mask:0xf bank_mask:0xf
	v_mov_b32_dpp v34, v23 row_ror:8 row_mask:0xf bank_mask:0xf
	v_mov_b32_dpp v35, v24 row_ror:8 row_mask:0xf bank_mask:0xf
	v_mov_b32_dpp v36, v25 row_ror:8 row_mask:0xf bank_mask:0xf
	v_cndmask_b32_e64 v25, v25, v32, s[6:7]
	v_cndmask_b32_e64 v24, v24, v31, s[6:7]
	v_cndmask_b32_e64 v23, v23, v30, s[6:7]
	v_cndmask_b32_e64 v17, v22, v17, s[6:7]
	v_cndmask_b32_e64 v34, v34, v19, s[6:7]
	v_cndmask_b32_e64 v31, v33, v18, s[6:7]
	v_cndmask_b32_e64 v37, v36, v21, s[6:7]
	v_cndmask_b32_e64 v35, v35, v20, s[6:7]
	v_lshlrev_b32_e32 v18, 16, v17
	v_and_b32_e32 v19, 0xffff0000, v17
	v_lshlrev_b32_e32 v20, 16, v23
	v_and_b32_e32 v21, 0xffff0000, v23
	v_lshlrev_b32_e32 v22, 16, v24
	v_and_b32_e32 v23, 0xffff0000, v24
	v_lshlrev_b32_e32 v24, 16, v25
	v_and_b32_e32 v25, 0xffff0000, v25
	v_lshlrev_b32_e32 v30, 16, v31
	v_and_b32_e32 v31, 0xffff0000, v31
	v_lshlrev_b32_e32 v32, 16, v34
	v_and_b32_e32 v33, 0xffff0000, v34
	v_lshlrev_b32_e32 v34, 16, v35
	v_and_b32_e32 v35, 0xffff0000, v35
	v_lshlrev_b32_e32 v36, 16, v37
	v_and_b32_e32 v37, 0xffff0000, v37
	v_pk_add_f32 v[18:19], v[4:5], v[18:19]
	v_pk_add_f32 v[24:25], v[2:3], v[24:25]
	v_pk_add_f32 v[2:3], v[14:15], v[32:33]
	v_pk_add_f32 v[4:5], v[12:13], v[30:31]
	v_pk_add_f32 v[20:21], v[6:7], v[20:21]
	v_pk_add_f32 v[6:7], v[10:11], v[36:37]
	v_pk_add_f32 v[8:9], v[8:9], v[34:35]
	v_mul_f32_e32 v10, v5, v5
	v_mul_f32_e32 v11, v3, v3
	v_mul_f32_e32 v12, v9, v9
	v_fmac_f32_e32 v10, v4, v4
	v_fmac_f32_e32 v11, v2, v2
	v_pk_add_f32 v[0:1], v[0:1], v[22:23]
	v_mul_f32_e32 v13, v7, v7
	v_cvt_pk_bf16_f32 v5, v4, v5
	v_fmac_f32_e32 v12, v8, v8
	v_add_f32_e32 v4, v10, v11
	v_mul_f32_e32 v10, v19, v19
	v_mul_f32_e32 v11, v21, v21
	v_cvt_pk_bf16_f32 v3, v2, v3
	v_cvt_pk_bf16_f32 v9, v8, v9
	v_cvt_pk_bf16_f32 v7, v6, v7
	v_cvt_pk_bf16_f32 v14, v18, v19
	v_cvt_pk_bf16_f32 v15, v20, v21
	v_cvt_pk_bf16_f32 v17, v0, v1
	v_fmac_f32_e32 v13, v6, v6
	v_add_f32_e32 v4, v12, v4
	v_mov_b32_dpp v44, v17 row_ror:8 row_mask:0xf bank_mask:0xf
	v_fmac_f32_e32 v10, v18, v18
	v_fmac_f32_e32 v11, v20, v20
	v_mul_f32_e32 v1, v1, v1
	v_mov_b32_dpp v40, v9 row_ror:8 row_mask:0xf bank_mask:0xf
	v_add_f32_e32 v8, v13, v4
	v_cndmask_b32_e64 v4, v44, v9, s[6:7]
	v_mul_f32_e32 v9, v25, v25
	v_add_f32_e32 v10, v10, v11
	v_fmac_f32_e32 v1, v0, v0
	v_fmac_f32_e32 v9, v24, v24
	v_add_f32_e32 v0, v1, v10
	v_add_f32_e32 v0, v9, v0
	v_add_f32_e32 v12, v0, v8
	ds_bpermute_b32 v13, v114, v12
	v_lshl_add_u64 v[0:1], s[16:17], 0, v[26:27]
	v_lshl_add_u64 v[10:11], v[0:1], 0, v[146:147]
	v_cvt_pk_bf16_f32 v22, v24, v25
	v_mov_b32_dpp v42, v14 row_ror:8 row_mask:0xf bank_mask:0xf
	s_waitcnt lgkmcnt(0)
	v_add_f32_e32 v0, v12, v13
	ds_bpermute_b32 v1, v115, v0
	v_mov_b32_dpp v43, v15 row_ror:8 row_mask:0xf bank_mask:0xf
	v_mov_b32_dpp v45, v22 row_ror:8 row_mask:0xf bank_mask:0xf
	v_mov_b32_dpp v38, v5 row_ror:8 row_mask:0xf bank_mask:0xf
	v_mov_b32_dpp v39, v3 row_ror:8 row_mask:0xf bank_mask:0xf
	v_cndmask_b32_e64 v2, v42, v5, s[6:7]
	v_cndmask_b32_e64 v3, v43, v3, s[6:7]
	v_cndmask_b32_e64 v5, v45, v7, s[6:7]
	v_mov_b32_dpp v41, v7 row_ror:8 row_mask:0xf bank_mask:0xf
	global_store_dwordx4 v[10:11], v[2:5], off
	v_cndmask_b32_e64 v6, v14, v38, s[6:7]
	v_cndmask_b32_e64 v7, v15, v39, s[6:7]
	v_lshl_add_u64 v[2:3], s[16:17], 0, v[28:29]
	v_cndmask_b32_e64 v8, v17, v40, s[6:7]
	v_cndmask_b32_e64 v9, v22, v41, s[6:7]
	v_lshl_add_u64 v[2:3], v[2:3], 0, v[146:147]
	global_store_dwordx4 v[2:3], v[6:9], off
	s_and_saveexec_b64 s[42:43], s[8:9]
	s_cbranch_execz .LBB0_1236
	v_ashrrev_i32_e32 v17, 31, v16
	s_waitcnt lgkmcnt(0)
	v_add_f32_e32 v2, v0, v1
	v_lshl_add_u64 v[0:1], v[16:17], 2, s[18:19]
	global_atomic_add_f32 v[0:1], v2, off
	s_branch .LBB0_1236

; #define PG8_STAGE(bufoff, gbase, voff) do { _Pragma("unroll") for (int _i = 0; _i < 2; ++_i) \
;         __builtin_amdgcn_global_load_lds((const unsigned*)((const char*)(gbase) + (voff)[_i]), (LAS unsigned*)(lds + (bufoff) + ldsw + _i * 8192), 16, 0, 0); } while (0)
; #define PG8_LDA(dst, b, h) do { _Pragma("unroll") for (int m = 0; m < 4; ++m) _Pragma("unroll") for (int k = 0; k < 2; ++k) dst[m][k] = *(const LAS bf16x8*)(lds + PG8_SA(b, h) + aoff + m * 2048 + k * 1024); } while (0)
; #define PG8_LDB(dst, b, h) do { _Pragma("unroll") for (int n = 0; n < 2; ++n) _Pragma("unroll") for (int k = 0; k < 2; ++k) dst[n][k] = *(const LAS bf16x8*)(lds + PG8_SB(b, h) + boff + n * 2048 + k * 1024); } while (0)
; #define PG8_WAIT_V(n) asm volatile("s_waitcnt vmcnt(" #n ")" ::: "memory")
; #define PG8_WAIT_L(n) asm volatile("s_waitcnt lgkmcnt(" #n ")" ::: "memory")
; #define PG8_BAR __builtin_amdgcn_s_barrier()
; #define PG8_SCHED __builtin_amdgcn_sched_barrier(0)
; template <class Epi>
; __device__ __forceinline__ void gemm_phase(LAS unsigned char* lds, const Gemm g, const StaticOrder& S, const Epi& E) {
;     ...
;             PG8_LDB(B0, 0, 0); PG8_SCHED; PG8_LDA(At, 0, 0); PG8_STAGE(PG8_SA(1, 1), a1 + hstep, voffA);
;             PG8_WAIT_L(8); PG8_BAR; PG8_WAIT_L(0); PG8_MMA(0, 0, At, B0); PG8_BAR; PG8_SCHED;
;             PG8_LDB(B1, 0, 1); PG8_STAGE(PG8_SB(0, 0), b2, voffB0);
;             PG8_BAR; PG8_WAIT_L(0); PG8_MMA(0, 1, At, B1); PG8_BAR;
;             PG8_LDA(At, 0, 1); PG8_STAGE(PG8_SA(0, 0), a2, voffA);
;             PG8_BAR; PG8_WAIT_L(0); PG8_MMA(1, 0, At, B0); PG8_BAR; PG8_SCHED;
;             PG8_STAGE(PG8_SB(0, 1), b2, voffB1);
;             PG8_WAIT_V(6); PG8_BAR; PG8_MMA(1, 1, At, B1); PG8_BAR;
;             PG8_LDB(B0, 1, 0); PG8_SCHED; PG8_LDA(At, 1, 0); PG8_STAGE(PG8_SA(0, 1), a2 + hstep, voffA);
;             PG8_WAIT_L(8); PG8_BAR; PG8_WAIT_L(0); PG8_MMA(0, 0, At, B0); PG8_BAR; PG8_SCHED;
;             PG8_LDB(B1, 1, 1); PG8_STAGE(PG8_SB(1, 0), b3, voffB0);
;             PG8_BAR; PG8_WAIT_L(0); PG8_MMA(0, 1, At, B1); PG8_BAR;
;             PG8_LDA(At, 1, 1); PG8_STAGE(PG8_SA(1, 0), a3, voffA);
;             PG8_BAR; PG8_WAIT_L(0); PG8_MMA(1, 0, At, B0); PG8_BAR; PG8_SCHED;
;             PG8_STAGE(PG8_SB(1, 1), b3, voffB1);
;             PG8_WAIT_V(6); PG8_BAR; PG8_MMA(1, 1, At, B1); PG8_BAR;
.LBB0_1277:
	s_add_u32 s33, s44, s52
	s_addc_u32 s53, s45, 0
	s_add_u32 s50, s33, 0x100
	s_addc_u32 s51, s53, 0
	v_cndmask_b32_e64 v153, 0, 1, s[48:49]
	s_and_b64 s[48:49], s[46:47], exec
	s_cselect_b32 s51, s29, s51
	s_cselect_b32 s50, s39, s50
	s_add_u32 s48, s42, s52
	s_addc_u32 s49, s43, 0
	s_add_u32 s48, s48, 0x100
	s_addc_u32 s49, s49, 0
	s_and_b64 s[46:47], s[46:47], exec
	ds_read_b128 v[142:145], v150
	ds_read_b128 v[154:157], v150 offset:1024
	ds_read_b128 v[158:161], v150 offset:2048
	ds_read_b128 v[162:165], v150 offset:3072
	s_cselect_b32 s48, s73, s48
	s_cselect_b32 s49, s27, s49
	s_add_u32 s52, s33, 0x10080
	s_addc_u32 s53, s53, 0
	s_add_i32 s82, s71, s59
	s_add_i32 s78, s72, s59
	s_add_i32 m0, s41, 0xc000
	s_add_i32 s33, s41, 0xe000
	s_add_i32 s81, s82, 0x2000
	s_add_i32 s77, s78, 0x2000
	s_add_i32 s76, 0, 0x18000
	s_add_u32 s46, s50, 0x10000
	s_addc_u32 s47, s51, 0
	s_add_i32 s74, 0, 0x1c000
	s_add_i32 s75, s76, s59
	s_add_i32 s80, s74, s59
	s_add_i32 s83, s75, 0x2000
	s_add_i32 s79, s80, 0x2000
	v_cmp_ne_u32_e32 vcc, 1, v153
	v_lshl_add_u64 v[198:199], s[52:53], 0, v[128:129]
	ds_read_b128 v[166:169], v151
	ds_read_b128 v[170:173], v151 offset:1024
	ds_read_b128 v[174:177], v151 offset:2048
	ds_read_b128 v[178:181], v151 offset:3072
	ds_read_b128 v[182:185], v151 offset:4096
	ds_read_b128 v[186:189], v151 offset:5120
	ds_read_b128 v[190:193], v151 offset:6144
	ds_read_b128 v[194:197], v151 offset:7168
	global_load_lds_dwordx4 v[198:199], off
	v_lshl_add_u64 v[198:199], s[52:53], 0, v[134:135]
	s_mov_b32 m0, s33
	s_nop 0
	global_load_lds_dwordx4 v[198:199], off
	s_waitcnt lgkmcnt(8)
	s_barrier
	s_waitcnt lgkmcnt(0)
	v_mfma_f32_16x16x32_bf16 v[124:127], v[142:145], v[166:169], v[124:127]
	v_mfma_f32_16x16x32_bf16 v[120:123], v[158:161], v[166:169], v[120:123]
	v_mfma_f32_16x16x32_bf16 v[108:111], v[142:145], v[174:177], v[108:111]
	v_mfma_f32_16x16x32_bf16 v[104:107], v[158:161], v[174:177], v[104:107]
	v_mfma_f32_16x16x32_bf16 v[92:95], v[142:145], v[182:185], v[92:95]
	v_mfma_f32_16x16x32_bf16 v[88:91], v[158:161], v[182:185], v[88:91]
	v_mfma_f32_16x16x32_bf16 v[76:79], v[142:145], v[190:193], v[76:79]
	v_mfma_f32_16x16x32_bf16 v[72:75], v[158:161], v[190:193], v[72:75]
	v_mfma_f32_16x16x32_bf16 v[124:127], v[154:157], v[170:173], v[124:127]
	v_mfma_f32_16x16x32_bf16 v[120:123], v[162:165], v[170:173], v[120:123]
	v_mfma_f32_16x16x32_bf16 v[108:111], v[154:157], v[178:181], v[108:111]
	v_mfma_f32_16x16x32_bf16 v[104:107], v[162:165], v[178:181], v[104:107]
	v_mfma_f32_16x16x32_bf16 v[92:95], v[154:157], v[186:189], v[92:95]
	v_mfma_f32_16x16x32_bf16 v[88:91], v[162:165], v[186:189], v[88:91]
	v_mfma_f32_16x16x32_bf16 v[76:79], v[154:157], v[194:197], v[76:79]
	v_mfma_f32_16x16x32_bf16 v[72:75], v[162:165], v[194:197], v[72:75]
	s_barrier
	s_mov_b32 m0, s82
	v_lshl_add_u64 v[216:217], s[48:49], 0, v[130:131]
	ds_read_b128 v[198:201], v152
	ds_read_b128 v[204:207], v152 offset:1024
	ds_read_b128 v[208:211], v152 offset:2048
	ds_read_b128 v[212:215], v152 offset:3072
	global_load_lds_dwordx4 v[216:217], off
	v_lshl_add_u64 v[218:219], s[48:49], 0, v[136:137]
	s_mov_b32 m0, s81
	s_nop 0
	global_load_lds_dwordx4 v[218:219], off
	s_barrier
	s_waitcnt lgkmcnt(0)
	v_mfma_f32_16x16x32_bf16 v[116:119], v[198:201], v[166:169], v[116:119]
	v_mfma_f32_16x16x32_bf16 v[112:115], v[208:211], v[166:169], v[112:115]
	v_mfma_f32_16x16x32_bf16 v[100:103], v[198:201], v[174:177], v[100:103]
	v_mfma_f32_16x16x32_bf16 v[96:99], v[208:211], v[174:177], v[96:99]
	v_mfma_f32_16x16x32_bf16 v[84:87], v[198:201], v[182:185], v[84:87]
	v_mfma_f32_16x16x32_bf16 v[80:83], v[208:211], v[182:185], v[80:83]
	v_mfma_f32_16x16x32_bf16 v[68:71], v[198:201], v[190:193], v[68:71]
	v_mfma_f32_16x16x32_bf16 v[64:67], v[208:211], v[190:193], v[64:67]
	v_mfma_f32_16x16x32_bf16 v[116:119], v[204:207], v[170:173], v[116:119]
	v_mfma_f32_16x16x32_bf16 v[112:115], v[212:215], v[170:173], v[112:115]
	v_mfma_f32_16x16x32_bf16 v[100:103], v[204:207], v[178:181], v[100:103]
	v_mfma_f32_16x16x32_bf16 v[96:99], v[212:215], v[178:181], v[96:99]
	v_mfma_f32_16x16x32_bf16 v[84:87], v[204:207], v[186:189], v[84:87]
	v_mfma_f32_16x16x32_bf16 v[80:83], v[212:215], v[186:189], v[80:83]
	v_mfma_f32_16x16x32_bf16 v[68:71], v[204:207], v[194:197], v[68:71]
	v_mfma_f32_16x16x32_bf16 v[64:67], v[212:215], v[194:197], v[64:67]
	s_mov_b32 m0, s41
	v_lshl_add_u64 v[220:221], s[50:51], 0, v[128:129]
	s_barrier
	ds_read_b128 v[166:169], v151 offset:16384
	ds_read_b128 v[170:173], v151 offset:17408
	ds_read_b128 v[174:177], v151 offset:18432
	ds_read_b128 v[178:181], v151 offset:19456
	ds_read_b128 v[182:185], v151 offset:20480
	ds_read_b128 v[186:189], v151 offset:21504
	ds_read_b128 v[190:193], v151 offset:22528
	ds_read_b128 v[194:197], v151 offset:23552
	global_load_lds_dwordx4 v[220:221], off
	v_lshl_add_u64 v[222:223], s[50:51], 0, v[134:135]
	s_mov_b32 m0, s60
	s_nop 0
	global_load_lds_dwordx4 v[222:223], off
	s_barrier
	s_waitcnt lgkmcnt(0)
	v_mfma_f32_16x16x32_bf16 v[60:63], v[142:145], v[166:169], v[60:63]
	v_mfma_f32_16x16x32_bf16 v[56:59], v[158:161], v[166:169], v[56:59]
	v_mfma_f32_16x16x32_bf16 v[44:47], v[142:145], v[174:177], v[44:47]
	v_mfma_f32_16x16x32_bf16 v[40:43], v[158:161], v[174:177], v[40:43]
	v_mfma_f32_16x16x32_bf16 v[28:31], v[142:145], v[182:185], v[28:31]
	v_mfma_f32_16x16x32_bf16 v[24:27], v[158:161], v[182:185], v[24:27]
	v_mfma_f32_16x16x32_bf16 v[12:15], v[142:145], v[190:193], v[12:15]
	v_mfma_f32_16x16x32_bf16 v[8:11], v[158:161], v[190:193], v[8:11]
	v_mfma_f32_16x16x32_bf16 v[60:63], v[154:157], v[170:173], v[60:63]
	v_mfma_f32_16x16x32_bf16 v[56:59], v[162:165], v[170:173], v[56:59]
	v_mfma_f32_16x16x32_bf16 v[44:47], v[154:157], v[178:181], v[44:47]
	v_mfma_f32_16x16x32_bf16 v[40:43], v[162:165], v[178:181], v[40:43]
	v_mfma_f32_16x16x32_bf16 v[28:31], v[154:157], v[186:189], v[28:31]
	v_mfma_f32_16x16x32_bf16 v[24:27], v[162:165], v[186:189], v[24:27]
	v_mfma_f32_16x16x32_bf16 v[12:15], v[154:157], v[194:197], v[12:15]
	v_mfma_f32_16x16x32_bf16 v[8:11], v[162:165], v[194:197], v[8:11]
	s_barrier
; #define PG8_STAGE(bufoff, gbase, voff) do { _Pragma("unroll") for (int _i = 0; _i < 2; ++_i) \
;         __builtin_amdgcn_global_load_lds((const unsigned*)((const char*)(gbase) + (voff)[_i]), (LAS unsigned*)(lds + (bufoff) + ldsw + _i * 8192), 16, 0, 0); } while (0)
; #define PG8_LDA(dst, b, h) do { _Pragma("unroll") for (int m = 0; m < 4; ++m) _Pragma("unroll") for (int k = 0; k < 2; ++k) dst[m][k] = *(const LAS bf16x8*)(lds + PG8_SA(b, h) + aoff + m * 2048 + k * 1024); } while (0)
; #define PG8_LDB(dst, b, h) do { _Pragma("unroll") for (int n = 0; n < 2; ++n) _Pragma("unroll") for (int k = 0; k < 2; ++k) dst[n][k] = *(const LAS bf16x8*)(lds + PG8_SB(b, h) + boff + n * 2048 + k * 1024); } while (0)
; #define PG8_WAIT_V(n) asm volatile("s_waitcnt vmcnt(" #n ")" ::: "memory")
; #define PG8_WAIT_L(n) asm volatile("s_waitcnt lgkmcnt(" #n ")" ::: "memory")
; #define PG8_BAR __builtin_amdgcn_s_barrier()
; #define PG8_SCHED __builtin_amdgcn_sched_barrier(0)
; template <class Epi>
; __device__ __forceinline__ void gemm_phase(LAS unsigned char* lds, const Gemm g, const StaticOrder& S, const Epi& E) {
;     ...
;             PG8_LDB(B0, 0, 0); PG8_SCHED; PG8_LDA(At, 0, 0); PG8_STAGE(PG8_SA(1, 1), a1 + hstep, voffA);
;             PG8_WAIT_L(8); PG8_BAR; PG8_WAIT_L(0); PG8_MMA(0, 0, At, B0); PG8_BAR; PG8_SCHED;
;             PG8_LDB(B1, 0, 1); PG8_STAGE(PG8_SB(0, 0), b2, voffB0);
;             PG8_BAR; PG8_WAIT_L(0); PG8_MMA(0, 1, At, B1); PG8_BAR;
;             PG8_LDA(At, 0, 1); PG8_STAGE(PG8_SA(0, 0), a2, voffA);
;             PG8_BAR; PG8_WAIT_L(0); PG8_MMA(1, 0, At, B0); PG8_BAR; PG8_SCHED;
;             PG8_STAGE(PG8_SB(0, 1), b2, voffB1);
;             PG8_WAIT_V(6); PG8_BAR; PG8_MMA(1, 1, At, B1); PG8_BAR;
;             PG8_LDB(B0, 1, 0); PG8_SCHED; PG8_LDA(At, 1, 0); PG8_STAGE(PG8_SA(0, 1), a2 + hstep, voffA);
;             PG8_WAIT_L(8); PG8_BAR; PG8_WAIT_L(0); PG8_MMA(0, 0, At, B0); PG8_BAR; PG8_SCHED;
;             PG8_LDB(B1, 1, 1); PG8_STAGE(PG8_SB(1, 0), b3, voffB0);
;             PG8_BAR; PG8_WAIT_L(0); PG8_MMA(0, 1, At, B1); PG8_BAR;
;             PG8_LDA(At, 1, 1); PG8_STAGE(PG8_SA(1, 0), a3, voffA);
;             PG8_BAR; PG8_WAIT_L(0); PG8_MMA(1, 0, At, B0); PG8_BAR; PG8_SCHED;
;             PG8_STAGE(PG8_SB(1, 1), b3, voffB1);
;             PG8_WAIT_V(6); PG8_BAR; PG8_MMA(1, 1, At, B1); PG8_BAR;
	s_mov_b32 m0, s78
	v_lshl_add_u64 v[224:225], s[48:49], 0, v[132:133]
	global_load_lds_dwordx4 v[224:225], off
	v_lshl_add_u64 v[226:227], s[48:49], 0, v[138:139]
	s_mov_b32 m0, s77
	s_nop 0
	global_load_lds_dwordx4 v[226:227], off
	s_waitcnt vmcnt(6)
	s_barrier
	v_mfma_f32_16x16x32_bf16 v[52:55], v[198:201], v[166:169], v[52:55]
	v_mfma_f32_16x16x32_bf16 v[48:51], v[208:211], v[166:169], v[48:51]
	v_mfma_f32_16x16x32_bf16 v[36:39], v[198:201], v[174:177], v[36:39]
	v_mfma_f32_16x16x32_bf16 v[32:35], v[208:211], v[174:177], v[32:35]
	v_mfma_f32_16x16x32_bf16 v[20:23], v[198:201], v[182:185], v[20:23]
	v_mfma_f32_16x16x32_bf16 v[16:19], v[208:211], v[182:185], v[16:19]
	v_mfma_f32_16x16x32_bf16 v[4:7], v[198:201], v[190:193], v[4:7]
	v_mfma_f32_16x16x32_bf16 v[0:3], v[208:211], v[190:193], v[0:3]
	v_mfma_f32_16x16x32_bf16 v[52:55], v[204:207], v[170:173], v[52:55]
	v_mfma_f32_16x16x32_bf16 v[48:51], v[212:215], v[170:173], v[48:51]
	v_mfma_f32_16x16x32_bf16 v[36:39], v[204:207], v[178:181], v[36:39]
	v_mfma_f32_16x16x32_bf16 v[32:35], v[212:215], v[178:181], v[32:35]
	v_mfma_f32_16x16x32_bf16 v[20:23], v[204:207], v[186:189], v[20:23]
	v_mfma_f32_16x16x32_bf16 v[16:19], v[212:215], v[186:189], v[16:19]
	v_mfma_f32_16x16x32_bf16 v[4:7], v[204:207], v[194:197], v[4:7]
	v_mfma_f32_16x16x32_bf16 v[0:3], v[212:215], v[194:197], v[0:3]
	v_add_u32_e32 v153, s76, v147
	s_barrier
	ds_read_b128 v[142:145], v153
	ds_read_b128 v[154:157], v153 offset:1024
	ds_read_b128 v[158:161], v153 offset:2048
	ds_read_b128 v[162:165], v153 offset:3072
	s_mov_b32 m0, s61
	v_lshl_add_u64 v[198:199], s[46:47], 0, v[128:129]
	ds_read_b128 v[166:169], v151 offset:32768
	ds_read_b128 v[170:173], v151 offset:33792
	ds_read_b128 v[174:177], v151 offset:34816
	ds_read_b128 v[178:181], v151 offset:35840
	ds_read_b128 v[182:185], v151 offset:36864
	ds_read_b128 v[186:189], v151 offset:37888
	ds_read_b128 v[190:193], v151 offset:38912
	ds_read_b128 v[194:197], v151 offset:39936
	global_load_lds_dwordx4 v[198:199], off
	v_lshl_add_u64 v[198:199], s[46:47], 0, v[134:135]
	s_mov_b32 m0, s62
	s_nop 0
	global_load_lds_dwordx4 v[198:199], off
	s_waitcnt lgkmcnt(8)
	s_barrier
	s_waitcnt lgkmcnt(0)
	v_mfma_f32_16x16x32_bf16 v[124:127], v[142:145], v[166:169], v[124:127]
	v_mfma_f32_16x16x32_bf16 v[120:123], v[158:161], v[166:169], v[120:123]
	v_mfma_f32_16x16x32_bf16 v[108:111], v[142:145], v[174:177], v[108:111]
	v_mfma_f32_16x16x32_bf16 v[104:107], v[158:161], v[174:177], v[104:107]
	v_mfma_f32_16x16x32_bf16 v[92:95], v[142:145], v[182:185], v[92:95]
	v_mfma_f32_16x16x32_bf16 v[88:91], v[158:161], v[182:185], v[88:91]
	v_mfma_f32_16x16x32_bf16 v[76:79], v[142:145], v[190:193], v[76:79]
	v_mfma_f32_16x16x32_bf16 v[72:75], v[158:161], v[190:193], v[72:75]
	v_mfma_f32_16x16x32_bf16 v[124:127], v[154:157], v[170:173], v[124:127]
	v_mfma_f32_16x16x32_bf16 v[120:123], v[162:165], v[170:173], v[120:123]
	v_mfma_f32_16x16x32_bf16 v[108:111], v[154:157], v[178:181], v[108:111]
	v_mfma_f32_16x16x32_bf16 v[104:107], v[162:165], v[178:181], v[104:107]
	v_mfma_f32_16x16x32_bf16 v[92:95], v[154:157], v[186:189], v[92:95]
	v_mfma_f32_16x16x32_bf16 v[88:91], v[162:165], v[186:189], v[88:91]
	v_mfma_f32_16x16x32_bf16 v[76:79], v[154:157], v[194:197], v[76:79]
	v_mfma_f32_16x16x32_bf16 v[72:75], v[162:165], v[194:197], v[72:75]
	s_barrier
	s_mov_b32 m0, s75
	v_add_u32_e32 v153, s74, v147
	v_lshl_add_u64 v[216:217], v[216:217], 0, s[18:19]
	ds_read_b128 v[198:201], v153
	ds_read_b128 v[204:207], v153 offset:1024
	ds_read_b128 v[208:211], v153 offset:2048
	ds_read_b128 v[212:215], v153 offset:3072
	global_load_lds_dwordx4 v[216:217], off
	v_lshl_add_u64 v[216:217], v[218:219], 0, s[18:19]
	s_mov_b32 m0, s83
	s_nop 0
	global_load_lds_dwordx4 v[216:217], off
	s_barrier
	s_waitcnt lgkmcnt(0)
	v_mfma_f32_16x16x32_bf16 v[116:119], v[198:201], v[166:169], v[116:119]
	v_mfma_f32_16x16x32_bf16 v[112:115], v[208:211], v[166:169], v[112:115]
	v_mfma_f32_16x16x32_bf16 v[100:103], v[198:201], v[174:177], v[100:103]
	v_mfma_f32_16x16x32_bf16 v[96:99], v[208:211], v[174:177], v[96:99]
	v_mfma_f32_16x16x32_bf16 v[84:87], v[198:201], v[182:185], v[84:87]
	v_mfma_f32_16x16x32_bf16 v[80:83], v[208:211], v[182:185], v[80:83]
	v_mfma_f32_16x16x32_bf16 v[68:71], v[198:201], v[190:193], v[68:71]
	v_mfma_f32_16x16x32_bf16 v[64:67], v[208:211], v[190:193], v[64:67]
	v_mfma_f32_16x16x32_bf16 v[116:119], v[204:207], v[170:173], v[116:119]
	v_mfma_f32_16x16x32_bf16 v[112:115], v[212:215], v[170:173], v[112:115]
	v_mfma_f32_16x16x32_bf16 v[100:103], v[204:207], v[178:181], v[100:103]
	v_mfma_f32_16x16x32_bf16 v[96:99], v[212:215], v[178:181], v[96:99]
	v_mfma_f32_16x16x32_bf16 v[84:87], v[204:207], v[186:189], v[84:87]
	v_mfma_f32_16x16x32_bf16 v[80:83], v[212:215], v[186:189], v[80:83]
	v_mfma_f32_16x16x32_bf16 v[68:71], v[204:207], v[194:197], v[68:71]
	v_mfma_f32_16x16x32_bf16 v[64:67], v[212:215], v[194:197], v[64:67]
	s_mov_b32 m0, s64
	v_lshl_add_u64 v[216:217], v[220:221], 0, s[18:19]
	s_barrier
	ds_read_b128 v[166:169], v151 offset:49152
	ds_read_b128 v[170:173], v151 offset:50176
	ds_read_b128 v[174:177], v151 offset:51200
	ds_read_b128 v[178:181], v151 offset:52224
	ds_read_b128 v[182:185], v151 offset:53248
	ds_read_b128 v[186:189], v151 offset:54272
	ds_read_b128 v[190:193], v151 offset:55296
	ds_read_b128 v[194:197], v151 offset:56320
	global_load_lds_dwordx4 v[216:217], off
	v_lshl_add_u64 v[216:217], v[222:223], 0, s[18:19]
	s_mov_b32 m0, s65
	s_nop 0
	global_load_lds_dwordx4 v[216:217], off
	s_barrier
; __device__ __forceinline__ unsigned cvt_pk_bf16(float lo, float hi) { unsigned r; asm volatile("v_cvt_pk_bf16_f32 %0, %1, %2" : "=v"(r) : "v"(lo), "v"(hi)); return r; }
; #define PG8_WAIT_V(n) asm volatile("s_waitcnt vmcnt(" #n ")" ::: "memory")
; #define PG8_WAIT_L(n) asm volatile("s_waitcnt lgkmcnt(" #n ")" ::: "memory")
;     __device__ __forceinline__ void operator()(const f32x4 (&acc)[2][2][4][2], const Unit& u, int wr, int wc, int fr, int fq) const {
;     ...
;             for (int m = 0; m < 4; ++m) { const int row = row0 + ai * HALF + m * 16;
;                 const float rs = ssin ? __builtin_amdgcn_rsqf(ssin[row] * (1.f / D) + EPS) : 1.0f; float sq = 0.f; u32x4 w[2];
; #pragma unroll
;                 for (int bj = 0; bj < 2; ++bj) { f32x4 v0 = acc[ai][bj][m][0] * rs, v1 = acc[ai][bj][m][1] * rs;
;                     if (ACT == 1) {
; #pragma unroll
;                         for (int j = 0; j < 4; ++j) { const float a = fmaxf(v0[j], 0.f), b = fmaxf(v1[j], 0.f); v0[j] = a * a; v1[j] = b * b; } }
;                     sq += (v0[0] * v0[0] + v0[1] * v0[1]) + (v0[2] * v0[2] + v0[3] * v0[3]) + (v1[0] * v1[0] + v1[1] * v1[1]) + (v1[2] * v1[2] + v1[3] * v1[3]);
;                     w[bj].x = cvt_pk_bf16(v0[0], v0[1]); w[bj].y = cvt_pk_bf16(v0[2], v0[3]); w[bj].z = cvt_pk_bf16(v1[0], v1[1]); w[bj].w = cvt_pk_bf16(v1[2], v1[3]); }
;                 store_pair_lines(O, ldc, row, fr, col0, w[0], w[1]);
;                 if (ssout) { sq += __shfl_xor(sq, 16); sq += __shfl_xor(sq, 32); if (fq == 0) unsafeAtomicAdd(ssout + row, sq); } }
; template <class Epi>
; __device__ __forceinline__ void gemm_phase(LAS unsigned char* lds, const Gemm g, const StaticOrder& S, const Epi& E) {
;     ...
;             PG8_WAIT_V(6); PG8_BAR; PG8_MMA(1, 1, At, B1); PG8_BAR;
;             PG8_LDB(B0, 1, 0); PG8_SCHED; PG8_LDA(At, 1, 0); PG8_STAGE(PG8_SA(0, 1), a2 + hstep, voffA);
;             PG8_WAIT_L(8); PG8_BAR; PG8_WAIT_L(0); PG8_MMA(0, 0, At, B0); PG8_BAR; PG8_SCHED;
;             PG8_LDB(B1, 1, 1); PG8_STAGE(PG8_SB(1, 0), b3, voffB0);
;             PG8_BAR; PG8_WAIT_L(0); PG8_MMA(0, 1, At, B1); PG8_BAR;
;             PG8_LDA(At, 1, 1); PG8_STAGE(PG8_SA(1, 0), a3, voffA);
;             PG8_BAR; PG8_WAIT_L(0); PG8_MMA(1, 0, At, B0); PG8_BAR; PG8_SCHED;
;             PG8_STAGE(PG8_SB(1, 1), b3, voffB1);
;             PG8_WAIT_V(6); PG8_BAR; PG8_MMA(1, 1, At, B1); PG8_BAR;
	s_waitcnt lgkmcnt(0)
	v_mfma_f32_16x16x32_bf16 v[60:63], v[142:145], v[166:169], v[60:63]
	v_mfma_f32_16x16x32_bf16 v[56:59], v[158:161], v[166:169], v[56:59]
	v_mfma_f32_16x16x32_bf16 v[44:47], v[142:145], v[174:177], v[44:47]
	v_mfma_f32_16x16x32_bf16 v[40:43], v[158:161], v[174:177], v[40:43]
	v_mfma_f32_16x16x32_bf16 v[28:31], v[142:145], v[182:185], v[28:31]
	v_mfma_f32_16x16x32_bf16 v[24:27], v[158:161], v[182:185], v[24:27]
	v_mfma_f32_16x16x32_bf16 v[12:15], v[142:145], v[190:193], v[12:15]
	v_mfma_f32_16x16x32_bf16 v[8:11], v[158:161], v[190:193], v[8:11]
	v_mfma_f32_16x16x32_bf16 v[60:63], v[154:157], v[170:173], v[60:63]
	v_mfma_f32_16x16x32_bf16 v[56:59], v[162:165], v[170:173], v[56:59]
	v_mfma_f32_16x16x32_bf16 v[44:47], v[154:157], v[178:181], v[44:47]
	v_mfma_f32_16x16x32_bf16 v[40:43], v[162:165], v[178:181], v[40:43]
	v_mfma_f32_16x16x32_bf16 v[28:31], v[154:157], v[186:189], v[28:31]
	v_mfma_f32_16x16x32_bf16 v[24:27], v[162:165], v[186:189], v[24:27]
	v_mfma_f32_16x16x32_bf16 v[12:15], v[154:157], v[194:197], v[12:15]
	v_mfma_f32_16x16x32_bf16 v[8:11], v[162:165], v[194:197], v[8:11]
	s_barrier
	s_mov_b32 m0, s80
	v_lshl_add_u64 v[142:143], v[224:225], 0, s[18:19]
	global_load_lds_dwordx4 v[142:143], off
	v_lshl_add_u64 v[142:143], v[226:227], 0, s[18:19]
	s_mov_b32 m0, s79
	s_nop 0
	global_load_lds_dwordx4 v[142:143], off
	s_waitcnt vmcnt(6)
	s_barrier
	v_mfma_f32_16x16x32_bf16 v[52:55], v[198:201], v[166:169], v[52:55]
	v_mfma_f32_16x16x32_bf16 v[48:51], v[208:211], v[166:169], v[48:51]
	v_mfma_f32_16x16x32_bf16 v[36:39], v[198:201], v[174:177], v[36:39]
	v_mfma_f32_16x16x32_bf16 v[32:35], v[208:211], v[174:177], v[32:35]
	v_mfma_f32_16x16x32_bf16 v[20:23], v[198:201], v[182:185], v[20:23]
	v_mfma_f32_16x16x32_bf16 v[16:19], v[208:211], v[182:185], v[16:19]
	v_mfma_f32_16x16x32_bf16 v[4:7], v[198:201], v[190:193], v[4:7]
	v_mfma_f32_16x16x32_bf16 v[0:3], v[208:211], v[190:193], v[0:3]
	v_mfma_f32_16x16x32_bf16 v[52:55], v[204:207], v[170:173], v[52:55]
	v_mfma_f32_16x16x32_bf16 v[48:51], v[212:215], v[170:173], v[48:51]
	v_mfma_f32_16x16x32_bf16 v[36:39], v[204:207], v[178:181], v[36:39]
	v_mfma_f32_16x16x32_bf16 v[32:35], v[212:215], v[178:181], v[32:35]
	v_mfma_f32_16x16x32_bf16 v[20:23], v[204:207], v[186:189], v[20:23]
	v_mfma_f32_16x16x32_bf16 v[16:19], v[212:215], v[186:189], v[16:19]
	v_mfma_f32_16x16x32_bf16 v[4:7], v[204:207], v[194:197], v[4:7]
	v_mfma_f32_16x16x32_bf16 v[0:3], v[212:215], v[194:197], v[0:3]
	s_movk_i32 s52, 0x100
	s_mov_b64 s[48:49], 0
	s_mov_b64 s[46:47], -1
	s_barrier
	s_cbranch_vccz .LBB0_1277
	v_cvt_pk_bf16_f32 v145, v124, v125
	v_cvt_pk_bf16_f32 v153, v126, v127
	v_cvt_pk_bf16_f32 v156, v120, v121
	v_cvt_pk_bf16_f32 v157, v122, v123
	v_cvt_pk_bf16_f32 v158, v116, v117
	v_cvt_pk_bf16_f32 v159, v118, v119
	v_cvt_pk_bf16_f32 v160, v112, v113
	v_cvt_pk_bf16_f32 v161, v114, v115
	v_mul_f32_e32 v123, v123, v123
	v_mul_f32_e32 v115, v115, v115
	v_fmac_f32_e32 v123, v122, v122
	v_mul_f32_e32 v122, v125, v125
	v_fmac_f32_e32 v115, v114, v114
	v_mul_f32_e32 v114, v117, v117
	v_fmac_f32_e32 v122, v124, v124
	v_mul_f32_e32 v124, v127, v127
	v_fmac_f32_e32 v114, v116, v116
	v_mul_f32_e32 v116, v119, v119
	v_fmac_f32_e32 v124, v126, v126
	v_mul_f32_e32 v121, v121, v121
	v_fmac_f32_e32 v116, v118, v118
	v_mul_f32_e32 v113, v113, v113
	v_add_f32_e32 v122, v122, v124
	v_fmac_f32_e32 v121, v120, v120
	v_add_f32_e32 v114, v114, v116
	v_fmac_f32_e32 v113, v112, v112
	v_add_f32_e32 v120, v122, v121
	v_add_f32_e32 v112, v114, v113
	s_lshl_b32 s27, s40, 8
	v_add_f32_e32 v120, v123, v120
	v_add_f32_e32 v112, v115, v112
	v_and_b32_e32 v113, 64, v203
	s_add_i32 s27, s27, s66
	v_mov_b32_dpp v162, v145 row_ror:8 row_mask:0xf bank_mask:0xf
	v_add_f32_e32 v115, v120, v112
	v_xor_b32_e32 v112, 16, v203
	v_add_u32_e32 v118, 64, v113
	v_mov_b32_dpp v163, v153 row_ror:8 row_mask:0xf bank_mask:0xf
	v_mov_b32_dpp v154, v158 row_ror:8 row_mask:0xf bank_mask:0xf
	v_cndmask_b32_e64 v158, v158, v162, s[6:7]
	v_or_b32_e32 v162, s27, v148
	v_cmp_lt_i32_e32 vcc, v112, v118
	v_lshl_or_b32 v142, s38, 8, v149
	v_mov_b32_dpp v164, v156 row_ror:8 row_mask:0xf bank_mask:0xf
	v_mov_b32_dpp v165, v157 row_ror:8 row_mask:0xf bank_mask:0xf
	v_mov_b32_dpp v155, v159 row_ror:8 row_mask:0xf bank_mask:0xf
	v_cndmask_b32_e64 v159, v159, v163, s[6:7]
	v_ashrrev_i32_e32 v163, 31, v162
	v_cndmask_b32_e32 v112, v203, v112, vcc
	v_ashrrev_i32_e32 v143, 31, v142
	v_mov_b32_dpp v166, v160 row_ror:8 row_mask:0xf bank_mask:0xf
	v_mov_b32_dpp v167, v161 row_ror:8 row_mask:0xf bank_mask:0xf
	v_cndmask_b32_e64 v160, v160, v164, s[6:7]
	v_cndmask_b32_e64 v161, v161, v165, s[6:7]
	v_lshlrev_b64 v[164:165], 12, v[162:163]
	v_lshlrev_b32_e32 v114, 2, v112
	v_cndmask_b32_e64 v156, v166, v156, s[6:7]
	v_cndmask_b32_e64 v157, v167, v157, s[6:7]
	v_lshl_add_u64 v[164:165], s[10:11], 0, v[164:165]
	v_lshlrev_b64 v[166:167], 1, v[142:143]
	ds_bpermute_b32 v119, v114, v115
	v_cndmask_b32_e64 v154, v154, v145, s[6:7]
	v_cndmask_b32_e64 v155, v155, v153, s[6:7]
	v_lshl_add_u64 v[112:113], v[164:165], 0, v[166:167]
	global_store_dwordx4 v[112:113], v[154:157], off
	v_xor_b32_e32 v113, 32, v203
	v_cmp_lt_i32_e32 vcc, v113, v118
	s_waitcnt lgkmcnt(0)
	v_add_f32_e32 v112, v115, v119
	v_or_b32_e32 v116, 8, v162
	v_cndmask_b32_e32 v113, v203, v113, vcc
	v_lshlrev_b32_e32 v115, 2, v113
	ds_bpermute_b32 v113, v115, v112
	v_ashrrev_i32_e32 v117, 31, v116
	v_lshlrev_b64 v[116:117], 12, v[116:117]
	v_lshl_add_u64 v[116:117], s[10:11], 0, v[116:117]
	v_or_b32_e32 v144, s27, v146
	v_lshl_add_u64 v[116:117], v[116:117], 0, v[166:167]
	global_store_dwordx4 v[116:117], v[158:161], off
	s_and_saveexec_b64 s[38:39], s[8:9]
	s_cbranch_execz .LBB0_1280
	v_ashrrev_i32_e32 v145, 31, v144
	s_waitcnt lgkmcnt(0)
	v_add_f32_e32 v116, v112, v113
	v_lshl_add_u64 v[112:113], v[144:145], 2, s[16:17]
	global_atomic_add_f32 v[112:113], v116, off
; __device__ __forceinline__ unsigned cvt_pk_bf16(float lo, float hi) { unsigned r; asm volatile("v_cvt_pk_bf16_f32 %0, %1, %2" : "=v"(r) : "v"(lo), "v"(hi)); return r; }
; __device__ __forceinline__ unsigned dpp_ror8(unsigned x) { return (unsigned)__builtin_amdgcn_update_dpp(0, (int)x, 0x128, 0xf, 0xf, false); }
; __device__ __forceinline__ void store_pair_lines(bf16_t* O, int ldc, int row, int fr, int col0, u32x4 wA, u32x4 wB) {
;     const u32x4 sA = {dpp_ror8(wA.x), dpp_ror8(wA.y), dpp_ror8(wA.z), dpp_ror8(wA.w)}, sB = {dpp_ror8(wB.x), dpp_ror8(wB.y), dpp_ror8(wB.z), dpp_ror8(wB.w)};
;     const bool lo = fr < 8;
;     const u32x4 o1 = lo ? wA : sB, o2 = lo ? sA : wB;
;     const int r1 = row - fr + (fr & 7), cb = col0 + (lo ? 0 : 8);
;     *(u32x4*)(O + (size_t)r1 * ldc + cb) = o1;
;     *(u32x4*)(O + (size_t)(r1 + 8) * ldc + cb) = o2;
; }
;     __device__ __forceinline__ void operator()(const f32x4 (&acc)[2][2][4][2], const Unit& u, int wr, int wc, int fr, int fq) const {
;     ...
;             for (int m = 0; m < 4; ++m) { const int row = row0 + ai * HALF + m * 16;
;                 const float rs = ssin ? __builtin_amdgcn_rsqf(ssin[row] * (1.f / D) + EPS) : 1.0f; float sq = 0.f; u32x4 w[2];
; #pragma unroll
;                 for (int bj = 0; bj < 2; ++bj) { f32x4 v0 = acc[ai][bj][m][0] * rs, v1 = acc[ai][bj][m][1] * rs;
;                     if (ACT == 1) {
; #pragma unroll
;                         for (int j = 0; j < 4; ++j) { const float a = fmaxf(v0[j], 0.f), b = fmaxf(v1[j], 0.f); v0[j] = a * a; v1[j] = b * b; } }
;                     sq += (v0[0] * v0[0] + v0[1] * v0[1]) + (v0[2] * v0[2] + v0[3] * v0[3]) + (v1[0] * v1[0] + v1[1] * v1[1]) + (v1[2] * v1[2] + v1[3] * v1[3]);
;                     w[bj].x = cvt_pk_bf16(v0[0], v0[1]); w[bj].y = cvt_pk_bf16(v0[2], v0[3]); w[bj].z = cvt_pk_bf16(v1[0], v1[1]); w[bj].w = cvt_pk_bf16(v1[2], v1[3]); }
;                 store_pair_lines(O, ldc, row, fr, col0, w[0], w[1]);
;                 if (ssout) { sq += __shfl_xor(sq, 16); sq += __shfl_xor(sq, 32); if (fq == 0) unsafeAtomicAdd(ssout + row, sq); } }
.LBB0_1280:
	s_or_b64 exec, exec, s[38:39]
	s_waitcnt lgkmcnt(0)
	v_cvt_pk_bf16_f32 v113, v108, v109
	v_cvt_pk_bf16_f32 v117, v110, v111
	v_cvt_pk_bf16_f32 v118, v104, v105
	v_cvt_pk_bf16_f32 v119, v106, v107
	v_cvt_pk_bf16_f32 v120, v100, v101
	v_cvt_pk_bf16_f32 v121, v102, v103
	v_cvt_pk_bf16_f32 v122, v96, v97
	v_cvt_pk_bf16_f32 v123, v98, v99
	v_mul_f32_e32 v107, v107, v107
	v_mul_f32_e32 v99, v99, v99
	v_fmac_f32_e32 v107, v106, v106
	v_mul_f32_e32 v106, v109, v109
	v_fmac_f32_e32 v99, v98, v98
	v_mul_f32_e32 v98, v101, v101
	v_fmac_f32_e32 v106, v108, v108
	v_mul_f32_e32 v108, v111, v111
	v_fmac_f32_e32 v98, v100, v100
	v_mul_f32_e32 v100, v103, v103
	v_fmac_f32_e32 v108, v110, v110
	v_mul_f32_e32 v105, v105, v105
	v_fmac_f32_e32 v100, v102, v102
	v_mul_f32_e32 v97, v97, v97
	v_add_f32_e32 v106, v106, v108
	v_fmac_f32_e32 v105, v104, v104
	v_add_f32_e32 v98, v98, v100
	v_fmac_f32_e32 v97, v96, v96
	v_add_f32_e32 v104, v106, v105
	v_add_f32_e32 v96, v98, v97
	v_add_f32_e32 v104, v107, v104
	v_add_f32_e32 v96, v99, v96
	v_or_b32_e32 v112, 16, v144
	v_mov_b32_dpp v116, v120 row_ror:8 row_mask:0xf bank_mask:0xf
	v_add_f32_e32 v100, v104, v96
	v_mov_b32_dpp v124, v113 row_ror:8 row_mask:0xf bank_mask:0xf
	v_cndmask_b32_e64 v116, v116, v113, s[6:7]
	v_sub_u32_e32 v113, v112, v146
	ds_bpermute_b32 v101, v114, v100
	v_mov_b32_dpp v125, v117 row_ror:8 row_mask:0xf bank_mask:0xf
	v_cndmask_b32_e64 v120, v120, v124, s[6:7]
	v_add_u32_e32 v124, v113, v148
	v_mov_b32_dpp v145, v121 row_ror:8 row_mask:0xf bank_mask:0xf
	v_cndmask_b32_e64 v121, v121, v125, s[6:7]
	v_ashrrev_i32_e32 v125, 31, v124
	v_lshlrev_b64 v[96:97], 12, v[124:125]
	v_lshl_add_u64 v[96:97], s[10:11], 0, v[96:97]
	v_lshl_add_u64 v[98:99], v[142:143], 1, v[96:97]
	s_waitcnt lgkmcnt(0)
	v_add_f32_e32 v96, v100, v101
	ds_bpermute_b32 v97, v115, v96
	v_mov_b32_dpp v153, v122 row_ror:8 row_mask:0xf bank_mask:0xf
	v_mov_b32_dpp v154, v123 row_ror:8 row_mask:0xf bank_mask:0xf
	v_mov_b32_dpp v126, v118 row_ror:8 row_mask:0xf bank_mask:0xf
	v_mov_b32_dpp v127, v119 row_ror:8 row_mask:0xf bank_mask:0xf
	v_cndmask_b32_e64 v117, v145, v117, s[6:7]
	v_cndmask_b32_e64 v118, v153, v118, s[6:7]
	v_cndmask_b32_e64 v119, v154, v119, s[6:7]
	global_store_dwordx4 v[98:99], v[116:119], off
	v_add_co_u32_e32 v98, vcc, s67, v98
	v_cndmask_b32_e64 v122, v122, v126, s[6:7]
	v_cndmask_b32_e64 v123, v123, v127, s[6:7]
	v_addc_co_u32_e32 v99, vcc, 0, v99, vcc
	global_store_dwordx4 v[98:99], v[120:123], off
	s_and_saveexec_b64 s[38:39], s[8:9]
	s_cbranch_execz .LBB0_1282
	v_ashrrev_i32_e32 v113, 31, v112
	s_waitcnt lgkmcnt(0)
	v_add_f32_e32 v98, v96, v97
	v_lshl_add_u64 v[96:97], v[112:113], 2, s[16:17]
	global_atomic_add_f32 v[96:97], v98, off
.LBB0_1282:
	s_or_b64 exec, exec, s[38:39]
	s_waitcnt lgkmcnt(0)
	v_cvt_pk_bf16_f32 v97, v92, v93
	v_cvt_pk_bf16_f32 v99, v94, v95
	v_cvt_pk_bf16_f32 v100, v88, v89
	v_cvt_pk_bf16_f32 v101, v90, v91
	v_cvt_pk_bf16_f32 v102, v84, v85
	v_cvt_pk_bf16_f32 v103, v86, v87
	v_cvt_pk_bf16_f32 v104, v80, v81
	v_cvt_pk_bf16_f32 v105, v82, v83
	v_mul_f32_e32 v91, v91, v91
	v_mul_f32_e32 v83, v83, v83
	v_fmac_f32_e32 v91, v90, v90
	v_mul_f32_e32 v90, v93, v93
	v_fmac_f32_e32 v83, v82, v82
	v_mul_f32_e32 v82, v85, v85
	v_fmac_f32_e32 v90, v92, v92
	v_mul_f32_e32 v92, v95, v95
	v_fmac_f32_e32 v82, v84, v84
	v_mul_f32_e32 v84, v87, v87
	v_fmac_f32_e32 v92, v94, v94
	v_mul_f32_e32 v89, v89, v89
	v_fmac_f32_e32 v84, v86, v86
	v_mul_f32_e32 v81, v81, v81
	v_add_f32_e32 v90, v90, v92
	v_fmac_f32_e32 v89, v88, v88
	v_add_f32_e32 v82, v82, v84
	v_fmac_f32_e32 v81, v80, v80
	v_add_f32_e32 v88, v90, v89
	v_add_f32_e32 v80, v82, v81
	v_add_f32_e32 v88, v91, v88
	v_add_f32_e32 v80, v83, v80
	v_or_b32_e32 v96, 32, v144
	v_mov_b32_dpp v98, v102 row_ror:8 row_mask:0xf bank_mask:0xf
	v_add_f32_e32 v84, v88, v80
	v_mov_b32_dpp v106, v97 row_ror:8 row_mask:0xf bank_mask:0xf
	v_cndmask_b32_e64 v98, v98, v97, s[6:7]
	v_sub_u32_e32 v97, v96, v146
	ds_bpermute_b32 v85, v114, v84
	v_mov_b32_dpp v107, v99 row_ror:8 row_mask:0xf bank_mask:0xf
	v_cndmask_b32_e64 v102, v102, v106, s[6:7]
	v_add_u32_e32 v106, v97, v148
	v_mov_b32_dpp v110, v103 row_ror:8 row_mask:0xf bank_mask:0xf
	v_cndmask_b32_e64 v103, v103, v107, s[6:7]
	v_ashrrev_i32_e32 v107, 31, v106
	v_lshlrev_b64 v[80:81], 12, v[106:107]
	v_lshl_add_u64 v[80:81], s[10:11], 0, v[80:81]
	v_lshl_add_u64 v[82:83], v[142:143], 1, v[80:81]
	s_waitcnt lgkmcnt(0)
	v_add_f32_e32 v80, v84, v85
	ds_bpermute_b32 v81, v115, v80
	v_mov_b32_dpp v111, v104 row_ror:8 row_mask:0xf bank_mask:0xf
	v_mov_b32_dpp v112, v105 row_ror:8 row_mask:0xf bank_mask:0xf
	v_mov_b32_dpp v108, v100 row_ror:8 row_mask:0xf bank_mask:0xf
	v_mov_b32_dpp v109, v101 row_ror:8 row_mask:0xf bank_mask:0xf
	v_cndmask_b32_e64 v99, v110, v99, s[6:7]
	v_cndmask_b32_e64 v100, v111, v100, s[6:7]
	v_cndmask_b32_e64 v101, v112, v101, s[6:7]
	global_store_dwordx4 v[82:83], v[98:101], off
	v_add_co_u32_e32 v82, vcc, s67, v82
	v_cndmask_b32_e64 v104, v104, v108, s[6:7]
	v_cndmask_b32_e64 v105, v105, v109, s[6:7]
	v_addc_co_u32_e32 v83, vcc, 0, v83, vcc
	global_store_dwordx4 v[82:83], v[102:105], off
	s_and_saveexec_b64 s[38:39], s[8:9]
	s_cbranch_execz .LBB0_1284
	v_ashrrev_i32_e32 v97, 31, v96
	s_waitcnt lgkmcnt(0)
	v_add_f32_e32 v82, v80, v81
	v_lshl_add_u64 v[80:81], v[96:97], 2, s[16:17]
	global_atomic_add_f32 v[80:81], v82, off
; __device__ __forceinline__ unsigned cvt_pk_bf16(float lo, float hi) { unsigned r; asm volatile("v_cvt_pk_bf16_f32 %0, %1, %2" : "=v"(r) : "v"(lo), "v"(hi)); return r; }
; __device__ __forceinline__ unsigned dpp_ror8(unsigned x) { return (unsigned)__builtin_amdgcn_update_dpp(0, (int)x, 0x128, 0xf, 0xf, false); }
; __device__ __forceinline__ void store_pair_lines(bf16_t* O, int ldc, int row, int fr, int col0, u32x4 wA, u32x4 wB) {
;     const u32x4 sA = {dpp_ror8(wA.x), dpp_ror8(wA.y), dpp_ror8(wA.z), dpp_ror8(wA.w)}, sB = {dpp_ror8(wB.x), dpp_ror8(wB.y), dpp_ror8(wB.z), dpp_ror8(wB.w)};
;     const bool lo = fr < 8;
;     const u32x4 o1 = lo ? wA : sB, o2 = lo ? sA : wB;
;     const int r1 = row - fr + (fr & 7), cb = col0 + (lo ? 0 : 8);
;     *(u32x4*)(O + (size_t)r1 * ldc + cb) = o1;
;     *(u32x4*)(O + (size_t)(r1 + 8) * ldc + cb) = o2;
; }
;     __device__ __forceinline__ void operator()(const f32x4 (&acc)[2][2][4][2], const Unit& u, int wr, int wc, int fr, int fq) const {
;     ...
;             for (int m = 0; m < 4; ++m) { const int row = row0 + ai * HALF + m * 16;
;                 const float rs = ssin ? __builtin_amdgcn_rsqf(ssin[row] * (1.f / D) + EPS) : 1.0f; float sq = 0.f; u32x4 w[2];
; #pragma unroll
;                 for (int bj = 0; bj < 2; ++bj) { f32x4 v0 = acc[ai][bj][m][0] * rs, v1 = acc[ai][bj][m][1] * rs;
;                     if (ACT == 1) {
; #pragma unroll
;                         for (int j = 0; j < 4; ++j) { const float a = fmaxf(v0[j], 0.f), b = fmaxf(v1[j], 0.f); v0[j] = a * a; v1[j] = b * b; } }
;                     sq += (v0[0] * v0[0] + v0[1] * v0[1]) + (v0[2] * v0[2] + v0[3] * v0[3]) + (v1[0] * v1[0] + v1[1] * v1[1]) + (v1[2] * v1[2] + v1[3] * v1[3]);
;                     w[bj].x = cvt_pk_bf16(v0[0], v0[1]); w[bj].y = cvt_pk_bf16(v0[2], v0[3]); w[bj].z = cvt_pk_bf16(v1[0], v1[1]); w[bj].w = cvt_pk_bf16(v1[2], v1[3]); }
;                 store_pair_lines(O, ldc, row, fr, col0, w[0], w[1]);
;                 if (ssout) { sq += __shfl_xor(sq, 16); sq += __shfl_xor(sq, 32); if (fq == 0) unsafeAtomicAdd(ssout + row, sq); } }
.LBB0_1284:
	s_or_b64 exec, exec, s[38:39]
	s_waitcnt lgkmcnt(0)
	v_cvt_pk_bf16_f32 v81, v76, v77
	v_cvt_pk_bf16_f32 v83, v78, v79
	v_cvt_pk_bf16_f32 v84, v72, v73
	v_cvt_pk_bf16_f32 v85, v74, v75
	v_cvt_pk_bf16_f32 v86, v68, v69
	v_cvt_pk_bf16_f32 v87, v70, v71
	v_cvt_pk_bf16_f32 v88, v64, v65
	v_cvt_pk_bf16_f32 v89, v66, v67
	v_mul_f32_e32 v75, v75, v75
	v_mul_f32_e32 v67, v67, v67
	v_fmac_f32_e32 v75, v74, v74
	v_mul_f32_e32 v74, v77, v77
	v_fmac_f32_e32 v67, v66, v66
	v_mul_f32_e32 v66, v69, v69
	v_fmac_f32_e32 v74, v76, v76
	v_mul_f32_e32 v76, v79, v79
	v_fmac_f32_e32 v66, v68, v68
	v_mul_f32_e32 v68, v71, v71
	v_fmac_f32_e32 v76, v78, v78
	v_mul_f32_e32 v73, v73, v73
	v_fmac_f32_e32 v68, v70, v70
	v_mul_f32_e32 v65, v65, v65
	v_add_f32_e32 v74, v74, v76
	v_fmac_f32_e32 v73, v72, v72
	v_add_f32_e32 v66, v66, v68
	v_fmac_f32_e32 v65, v64, v64
	v_add_f32_e32 v72, v74, v73
	v_add_f32_e32 v64, v66, v65
	v_add_f32_e32 v72, v75, v72
	v_add_f32_e32 v64, v67, v64
	v_or_b32_e32 v80, 48, v144
	v_mov_b32_dpp v82, v86 row_ror:8 row_mask:0xf bank_mask:0xf
	v_add_f32_e32 v68, v72, v64
	v_mov_b32_dpp v90, v81 row_ror:8 row_mask:0xf bank_mask:0xf
	v_cndmask_b32_e64 v82, v82, v81, s[6:7]
	v_sub_u32_e32 v81, v80, v146
	ds_bpermute_b32 v69, v114, v68
	v_mov_b32_dpp v91, v83 row_ror:8 row_mask:0xf bank_mask:0xf
	v_cndmask_b32_e64 v86, v86, v90, s[6:7]
	v_add_u32_e32 v90, v81, v148
	v_mov_b32_dpp v94, v87 row_ror:8 row_mask:0xf bank_mask:0xf
	v_cndmask_b32_e64 v87, v87, v91, s[6:7]
	v_ashrrev_i32_e32 v91, 31, v90
	v_lshlrev_b64 v[64:65], 12, v[90:91]
	v_lshl_add_u64 v[64:65], s[10:11], 0, v[64:65]
	v_lshl_add_u64 v[66:67], v[142:143], 1, v[64:65]
	s_waitcnt lgkmcnt(0)
	v_add_f32_e32 v64, v68, v69
	ds_bpermute_b32 v65, v115, v64
	v_mov_b32_dpp v95, v88 row_ror:8 row_mask:0xf bank_mask:0xf
	v_mov_b32_dpp v96, v89 row_ror:8 row_mask:0xf bank_mask:0xf
	v_mov_b32_dpp v92, v84 row_ror:8 row_mask:0xf bank_mask:0xf
	v_mov_b32_dpp v93, v85 row_ror:8 row_mask:0xf bank_mask:0xf
	v_cndmask_b32_e64 v83, v94, v83, s[6:7]
	v_cndmask_b32_e64 v84, v95, v84, s[6:7]
	v_cndmask_b32_e64 v85, v96, v85, s[6:7]
	global_store_dwordx4 v[66:67], v[82:85], off
	v_add_co_u32_e32 v66, vcc, s67, v66
	v_cndmask_b32_e64 v88, v88, v92, s[6:7]
	v_cndmask_b32_e64 v89, v89, v93, s[6:7]
	v_addc_co_u32_e32 v67, vcc, 0, v67, vcc
	global_store_dwordx4 v[66:67], v[86:89], off
	s_and_saveexec_b64 s[38:39], s[8:9]
	s_cbranch_execz .LBB0_1286
	v_ashrrev_i32_e32 v81, 31, v80
	s_waitcnt lgkmcnt(0)
	v_add_f32_e32 v66, v64, v65
	v_lshl_add_u64 v[64:65], v[80:81], 2, s[16:17]
	global_atomic_add_f32 v[64:65], v66, off
.LBB0_1286:
	s_or_b64 exec, exec, s[38:39]
	s_waitcnt lgkmcnt(0)
	v_cvt_pk_bf16_f32 v65, v60, v61
	v_cvt_pk_bf16_f32 v67, v62, v63
	v_cvt_pk_bf16_f32 v68, v56, v57
	v_cvt_pk_bf16_f32 v69, v58, v59
	v_cvt_pk_bf16_f32 v70, v52, v53
	v_cvt_pk_bf16_f32 v71, v54, v55
	v_cvt_pk_bf16_f32 v72, v48, v49
	v_cvt_pk_bf16_f32 v73, v50, v51
	v_mul_f32_e32 v59, v59, v59
	v_mul_f32_e32 v51, v51, v51
	v_fmac_f32_e32 v59, v58, v58
	v_mul_f32_e32 v58, v61, v61
	v_fmac_f32_e32 v51, v50, v50
	v_mul_f32_e32 v50, v53, v53
	v_fmac_f32_e32 v58, v60, v60
	v_mul_f32_e32 v60, v63, v63
	v_fmac_f32_e32 v50, v52, v52
	v_mul_f32_e32 v52, v55, v55
	v_fmac_f32_e32 v60, v62, v62
	v_mul_f32_e32 v57, v57, v57
	v_fmac_f32_e32 v52, v54, v54
	v_mul_f32_e32 v49, v49, v49
	v_add_f32_e32 v58, v58, v60
	v_fmac_f32_e32 v57, v56, v56
	v_add_f32_e32 v50, v50, v52
	v_fmac_f32_e32 v49, v48, v48
	v_add_f32_e32 v56, v58, v57
	v_add_f32_e32 v48, v50, v49
	v_add_f32_e32 v56, v59, v56
	v_add_f32_e32 v48, v51, v48
	v_add_u32_e32 v64, 0x80, v144
	v_mov_b32_dpp v66, v70 row_ror:8 row_mask:0xf bank_mask:0xf
	v_add_f32_e32 v52, v56, v48
	v_mov_b32_dpp v74, v65 row_ror:8 row_mask:0xf bank_mask:0xf
	v_cndmask_b32_e64 v66, v66, v65, s[6:7]
	v_sub_u32_e32 v65, v64, v146
	ds_bpermute_b32 v53, v114, v52
	v_mov_b32_dpp v75, v67 row_ror:8 row_mask:0xf bank_mask:0xf
	v_cndmask_b32_e64 v70, v70, v74, s[6:7]
	v_add_u32_e32 v74, v65, v148
	v_mov_b32_dpp v78, v71 row_ror:8 row_mask:0xf bank_mask:0xf
	v_cndmask_b32_e64 v71, v71, v75, s[6:7]
	v_ashrrev_i32_e32 v75, 31, v74
	v_lshlrev_b64 v[48:49], 12, v[74:75]
	v_lshl_add_u64 v[48:49], s[10:11], 0, v[48:49]
	v_lshl_add_u64 v[50:51], v[142:143], 1, v[48:49]
	s_waitcnt lgkmcnt(0)
	v_add_f32_e32 v48, v52, v53
	ds_bpermute_b32 v49, v115, v48
	v_mov_b32_dpp v79, v72 row_ror:8 row_mask:0xf bank_mask:0xf
	v_mov_b32_dpp v80, v73 row_ror:8 row_mask:0xf bank_mask:0xf
	v_mov_b32_dpp v76, v68 row_ror:8 row_mask:0xf bank_mask:0xf
	v_mov_b32_dpp v77, v69 row_ror:8 row_mask:0xf bank_mask:0xf
	v_cndmask_b32_e64 v67, v78, v67, s[6:7]
	v_cndmask_b32_e64 v68, v79, v68, s[6:7]
	v_cndmask_b32_e64 v69, v80, v69, s[6:7]
	global_store_dwordx4 v[50:51], v[66:69], off
	v_add_co_u32_e32 v50, vcc, s67, v50
	v_cndmask_b32_e64 v72, v72, v76, s[6:7]
	v_cndmask_b32_e64 v73, v73, v77, s[6:7]
	v_addc_co_u32_e32 v51, vcc, 0, v51, vcc
	global_store_dwordx4 v[50:51], v[70:73], off
	s_and_saveexec_b64 s[38:39], s[8:9]
	s_cbranch_execz .LBB0_1288
	v_ashrrev_i32_e32 v65, 31, v64
	s_waitcnt lgkmcnt(0)
	v_add_f32_e32 v50, v48, v49
	v_lshl_add_u64 v[48:49], v[64:65], 2, s[16:17]
	global_atomic_add_f32 v[48:49], v50, off
; __device__ __forceinline__ unsigned cvt_pk_bf16(float lo, float hi) { unsigned r; asm volatile("v_cvt_pk_bf16_f32 %0, %1, %2" : "=v"(r) : "v"(lo), "v"(hi)); return r; }
; __device__ __forceinline__ unsigned dpp_ror8(unsigned x) { return (unsigned)__builtin_amdgcn_update_dpp(0, (int)x, 0x128, 0xf, 0xf, false); }
; __device__ __forceinline__ void store_pair_lines(bf16_t* O, int ldc, int row, int fr, int col0, u32x4 wA, u32x4 wB) {
;     const u32x4 sA = {dpp_ror8(wA.x), dpp_ror8(wA.y), dpp_ror8(wA.z), dpp_ror8(wA.w)}, sB = {dpp_ror8(wB.x), dpp_ror8(wB.y), dpp_ror8(wB.z), dpp_ror8(wB.w)};
;     const bool lo = fr < 8;
;     const u32x4 o1 = lo ? wA : sB, o2 = lo ? sA : wB;
;     const int r1 = row - fr + (fr & 7), cb = col0 + (lo ? 0 : 8);
;     *(u32x4*)(O + (size_t)r1 * ldc + cb) = o1;
;     *(u32x4*)(O + (size_t)(r1 + 8) * ldc + cb) = o2;
; }
;     __device__ __forceinline__ void operator()(const f32x4 (&acc)[2][2][4][2], const Unit& u, int wr, int wc, int fr, int fq) const {
;     ...
;             for (int m = 0; m < 4; ++m) { const int row = row0 + ai * HALF + m * 16;
;                 const float rs = ssin ? __builtin_amdgcn_rsqf(ssin[row] * (1.f / D) + EPS) : 1.0f; float sq = 0.f; u32x4 w[2];
; #pragma unroll
;                 for (int bj = 0; bj < 2; ++bj) { f32x4 v0 = acc[ai][bj][m][0] * rs, v1 = acc[ai][bj][m][1] * rs;
;                     if (ACT == 1) {
; #pragma unroll
;                         for (int j = 0; j < 4; ++j) { const float a = fmaxf(v0[j], 0.f), b = fmaxf(v1[j], 0.f); v0[j] = a * a; v1[j] = b * b; } }
;                     sq += (v0[0] * v0[0] + v0[1] * v0[1]) + (v0[2] * v0[2] + v0[3] * v0[3]) + (v1[0] * v1[0] + v1[1] * v1[1]) + (v1[2] * v1[2] + v1[3] * v1[3]);
;                     w[bj].x = cvt_pk_bf16(v0[0], v0[1]); w[bj].y = cvt_pk_bf16(v0[2], v0[3]); w[bj].z = cvt_pk_bf16(v1[0], v1[1]); w[bj].w = cvt_pk_bf16(v1[2], v1[3]); }
;                 store_pair_lines(O, ldc, row, fr, col0, w[0], w[1]);
;                 if (ssout) { sq += __shfl_xor(sq, 16); sq += __shfl_xor(sq, 32); if (fq == 0) unsafeAtomicAdd(ssout + row, sq); } }
.LBB0_1288:
	s_or_b64 exec, exec, s[38:39]
	s_waitcnt lgkmcnt(0)
	v_cvt_pk_bf16_f32 v49, v44, v45
	v_cvt_pk_bf16_f32 v51, v46, v47
	v_cvt_pk_bf16_f32 v52, v40, v41
	v_cvt_pk_bf16_f32 v53, v42, v43
	v_cvt_pk_bf16_f32 v54, v36, v37
	v_cvt_pk_bf16_f32 v55, v38, v39
	v_cvt_pk_bf16_f32 v56, v32, v33
	v_cvt_pk_bf16_f32 v57, v34, v35
	v_mul_f32_e32 v43, v43, v43
	v_mul_f32_e32 v35, v35, v35
	v_fmac_f32_e32 v43, v42, v42
	v_mul_f32_e32 v42, v45, v45
	v_fmac_f32_e32 v35, v34, v34
	v_mul_f32_e32 v34, v37, v37
	v_fmac_f32_e32 v42, v44, v44
	v_mul_f32_e32 v44, v47, v47
	v_fmac_f32_e32 v34, v36, v36
	v_mul_f32_e32 v36, v39, v39
	v_fmac_f32_e32 v44, v46, v46
	v_mul_f32_e32 v41, v41, v41
	v_fmac_f32_e32 v36, v38, v38
	v_mul_f32_e32 v33, v33, v33
	v_add_f32_e32 v42, v42, v44
	v_fmac_f32_e32 v41, v40, v40
	v_add_f32_e32 v34, v34, v36
	v_fmac_f32_e32 v33, v32, v32
	v_add_f32_e32 v40, v42, v41
	v_add_f32_e32 v32, v34, v33
	v_add_f32_e32 v40, v43, v40
	v_add_f32_e32 v32, v35, v32
	v_add_u32_e32 v48, 0x90, v144
	v_mov_b32_dpp v50, v54 row_ror:8 row_mask:0xf bank_mask:0xf
	v_add_f32_e32 v36, v40, v32
	v_mov_b32_dpp v58, v49 row_ror:8 row_mask:0xf bank_mask:0xf
	v_cndmask_b32_e64 v50, v50, v49, s[6:7]
	v_sub_u32_e32 v49, v48, v146
	ds_bpermute_b32 v37, v114, v36
	v_mov_b32_dpp v59, v51 row_ror:8 row_mask:0xf bank_mask:0xf
	v_cndmask_b32_e64 v54, v54, v58, s[6:7]
	v_add_u32_e32 v58, v49, v148
	v_mov_b32_dpp v62, v55 row_ror:8 row_mask:0xf bank_mask:0xf
	v_cndmask_b32_e64 v55, v55, v59, s[6:7]
	v_ashrrev_i32_e32 v59, 31, v58
	v_lshlrev_b64 v[32:33], 12, v[58:59]
	v_lshl_add_u64 v[32:33], s[10:11], 0, v[32:33]
	v_lshl_add_u64 v[34:35], v[142:143], 1, v[32:33]
	s_waitcnt lgkmcnt(0)
	v_add_f32_e32 v32, v36, v37
	ds_bpermute_b32 v33, v115, v32
	v_mov_b32_dpp v63, v56 row_ror:8 row_mask:0xf bank_mask:0xf
	v_mov_b32_dpp v64, v57 row_ror:8 row_mask:0xf bank_mask:0xf
	v_mov_b32_dpp v60, v52 row_ror:8 row_mask:0xf bank_mask:0xf
	v_mov_b32_dpp v61, v53 row_ror:8 row_mask:0xf bank_mask:0xf
	v_cndmask_b32_e64 v51, v62, v51, s[6:7]
	v_cndmask_b32_e64 v52, v63, v52, s[6:7]
	v_cndmask_b32_e64 v53, v64, v53, s[6:7]
	global_store_dwordx4 v[34:35], v[50:53], off
	v_add_co_u32_e32 v34, vcc, s67, v34
	v_cndmask_b32_e64 v56, v56, v60, s[6:7]
	v_cndmask_b32_e64 v57, v57, v61, s[6:7]
	v_addc_co_u32_e32 v35, vcc, 0, v35, vcc
	global_store_dwordx4 v[34:35], v[54:57], off
	s_and_saveexec_b64 s[38:39], s[8:9]
	s_cbranch_execz .LBB0_1290
	v_ashrrev_i32_e32 v49, 31, v48
	s_waitcnt lgkmcnt(0)
	v_add_f32_e32 v34, v32, v33
	v_lshl_add_u64 v[32:33], v[48:49], 2, s[16:17]
	global_atomic_add_f32 v[32:33], v34, off
; __device__ __forceinline__ unsigned cvt_pk_bf16(float lo, float hi) { unsigned r; asm volatile("v_cvt_pk_bf16_f32 %0, %1, %2" : "=v"(r) : "v"(lo), "v"(hi)); return r; }
; __device__ __forceinline__ unsigned dpp_ror8(unsigned x) { return (unsigned)__builtin_amdgcn_update_dpp(0, (int)x, 0x128, 0xf, 0xf, false); }
; __device__ __forceinline__ void store_pair_lines(bf16_t* O, int ldc, int row, int fr, int col0, u32x4 wA, u32x4 wB) {
;     const u32x4 sA = {dpp_ror8(wA.x), dpp_ror8(wA.y), dpp_ror8(wA.z), dpp_ror8(wA.w)}, sB = {dpp_ror8(wB.x), dpp_ror8(wB.y), dpp_ror8(wB.z), dpp_ror8(wB.w)};
;     const bool lo = fr < 8;
;     const u32x4 o1 = lo ? wA : sB, o2 = lo ? sA : wB;
;     const int r1 = row - fr + (fr & 7), cb = col0 + (lo ? 0 : 8);
;     *(u32x4*)(O + (size_t)r1 * ldc + cb) = o1;
;     *(u32x4*)(O + (size_t)(r1 + 8) * ldc + cb) = o2;
; }
;     __device__ __forceinline__ void operator()(const f32x4 (&acc)[2][2][4][2], const Unit& u, int wr, int wc, int fr, int fq) const {
;     ...
;             for (int m = 0; m < 4; ++m) { const int row = row0 + ai * HALF + m * 16;
;                 const float rs = ssin ? __builtin_amdgcn_rsqf(ssin[row] * (1.f / D) + EPS) : 1.0f; float sq = 0.f; u32x4 w[2];
; #pragma unroll
;                 for (int bj = 0; bj < 2; ++bj) { f32x4 v0 = acc[ai][bj][m][0] * rs, v1 = acc[ai][bj][m][1] * rs;
;                     if (ACT == 1) {
; #pragma unroll
;                         for (int j = 0; j < 4; ++j) { const float a = fmaxf(v0[j], 0.f), b = fmaxf(v1[j], 0.f); v0[j] = a * a; v1[j] = b * b; } }
;                     sq += (v0[0] * v0[0] + v0[1] * v0[1]) + (v0[2] * v0[2] + v0[3] * v0[3]) + (v1[0] * v1[0] + v1[1] * v1[1]) + (v1[2] * v1[2] + v1[3] * v1[3]);
;                     w[bj].x = cvt_pk_bf16(v0[0], v0[1]); w[bj].y = cvt_pk_bf16(v0[2], v0[3]); w[bj].z = cvt_pk_bf16(v1[0], v1[1]); w[bj].w = cvt_pk_bf16(v1[2], v1[3]); }
;                 store_pair_lines(O, ldc, row, fr, col0, w[0], w[1]);
;                 if (ssout) { sq += __shfl_xor(sq, 16); sq += __shfl_xor(sq, 32); if (fq == 0) unsafeAtomicAdd(ssout + row, sq); } }
.LBB0_1290:
	s_or_b64 exec, exec, s[38:39]
	s_waitcnt lgkmcnt(0)
	v_cvt_pk_bf16_f32 v33, v28, v29
	v_cvt_pk_bf16_f32 v35, v30, v31
	v_cvt_pk_bf16_f32 v36, v24, v25
	v_cvt_pk_bf16_f32 v37, v26, v27
	v_cvt_pk_bf16_f32 v38, v20, v21
	v_cvt_pk_bf16_f32 v39, v22, v23
	v_cvt_pk_bf16_f32 v40, v16, v17
	v_cvt_pk_bf16_f32 v41, v18, v19
	v_mul_f32_e32 v27, v27, v27
	v_mul_f32_e32 v19, v19, v19
	v_fmac_f32_e32 v27, v26, v26
	v_mul_f32_e32 v26, v29, v29
	v_fmac_f32_e32 v19, v18, v18
	v_mul_f32_e32 v18, v21, v21
	v_fmac_f32_e32 v26, v28, v28
	v_mul_f32_e32 v28, v31, v31
	v_fmac_f32_e32 v18, v20, v20
	v_mul_f32_e32 v20, v23, v23
	v_fmac_f32_e32 v28, v30, v30
	v_mul_f32_e32 v25, v25, v25
	v_fmac_f32_e32 v20, v22, v22
	v_mul_f32_e32 v17, v17, v17
	v_add_f32_e32 v26, v26, v28
	v_fmac_f32_e32 v25, v24, v24
	v_add_f32_e32 v18, v18, v20
	v_fmac_f32_e32 v17, v16, v16
	v_add_f32_e32 v24, v26, v25
	v_add_f32_e32 v16, v18, v17
	v_add_f32_e32 v24, v27, v24
	v_add_f32_e32 v16, v19, v16
	v_add_u32_e32 v32, 0xa0, v144
	v_mov_b32_dpp v34, v38 row_ror:8 row_mask:0xf bank_mask:0xf
	v_add_f32_e32 v20, v24, v16
	v_mov_b32_dpp v42, v33 row_ror:8 row_mask:0xf bank_mask:0xf
	v_cndmask_b32_e64 v34, v34, v33, s[6:7]
	v_sub_u32_e32 v33, v32, v146
	ds_bpermute_b32 v21, v114, v20
	v_mov_b32_dpp v43, v35 row_ror:8 row_mask:0xf bank_mask:0xf
	v_cndmask_b32_e64 v38, v38, v42, s[6:7]
	v_add_u32_e32 v42, v33, v148
	v_mov_b32_dpp v46, v39 row_ror:8 row_mask:0xf bank_mask:0xf
	v_cndmask_b32_e64 v39, v39, v43, s[6:7]
	v_ashrrev_i32_e32 v43, 31, v42
	v_lshlrev_b64 v[16:17], 12, v[42:43]
	v_lshl_add_u64 v[16:17], s[10:11], 0, v[16:17]
	v_lshl_add_u64 v[18:19], v[142:143], 1, v[16:17]
	s_waitcnt lgkmcnt(0)
	v_add_f32_e32 v16, v20, v21
	ds_bpermute_b32 v17, v115, v16
	v_mov_b32_dpp v47, v40 row_ror:8 row_mask:0xf bank_mask:0xf
	v_mov_b32_dpp v48, v41 row_ror:8 row_mask:0xf bank_mask:0xf
	v_mov_b32_dpp v44, v36 row_ror:8 row_mask:0xf bank_mask:0xf
	v_mov_b32_dpp v45, v37 row_ror:8 row_mask:0xf bank_mask:0xf
	v_cndmask_b32_e64 v35, v46, v35, s[6:7]
	v_cndmask_b32_e64 v36, v47, v36, s[6:7]
	v_cndmask_b32_e64 v37, v48, v37, s[6:7]
	global_store_dwordx4 v[18:19], v[34:37], off
	v_add_co_u32_e32 v18, vcc, s67, v18
	v_cndmask_b32_e64 v40, v40, v44, s[6:7]
	v_cndmask_b32_e64 v41, v41, v45, s[6:7]
	v_addc_co_u32_e32 v19, vcc, 0, v19, vcc
	global_store_dwordx4 v[18:19], v[38:41], off
	s_and_saveexec_b64 s[38:39], s[8:9]
	s_cbranch_execz .LBB0_1292
	v_ashrrev_i32_e32 v33, 31, v32
	s_waitcnt lgkmcnt(0)
	v_add_f32_e32 v18, v16, v17
	v_lshl_add_u64 v[16:17], v[32:33], 2, s[16:17]
	global_atomic_add_f32 v[16:17], v18, off
.LBB0_1292:
	s_or_b64 exec, exec, s[38:39]
	s_waitcnt lgkmcnt(0)
	v_cvt_pk_bf16_f32 v17, v12, v13
	v_cvt_pk_bf16_f32 v19, v14, v15
	v_cvt_pk_bf16_f32 v20, v8, v9
	v_cvt_pk_bf16_f32 v21, v10, v11
	v_cvt_pk_bf16_f32 v22, v4, v5
	v_cvt_pk_bf16_f32 v23, v6, v7
	v_cvt_pk_bf16_f32 v24, v0, v1
	v_cvt_pk_bf16_f32 v25, v2, v3
	v_mul_f32_e32 v11, v11, v11
	v_mul_f32_e32 v3, v3, v3
	v_fmac_f32_e32 v11, v10, v10
	v_mul_f32_e32 v10, v13, v13
	v_fmac_f32_e32 v3, v2, v2
	v_mul_f32_e32 v2, v5, v5
	v_fmac_f32_e32 v10, v12, v12
	v_mul_f32_e32 v12, v15, v15
	v_fmac_f32_e32 v2, v4, v4
	v_mul_f32_e32 v4, v7, v7
	v_fmac_f32_e32 v12, v14, v14
	v_mul_f32_e32 v9, v9, v9
	v_fmac_f32_e32 v4, v6, v6
	v_mul_f32_e32 v1, v1, v1
	v_add_f32_e32 v10, v10, v12
	v_fmac_f32_e32 v9, v8, v8
	v_add_f32_e32 v2, v2, v4
	v_fmac_f32_e32 v1, v0, v0
	v_add_f32_e32 v8, v10, v9
	v_add_f32_e32 v0, v2, v1
	v_add_f32_e32 v8, v11, v8
	v_add_f32_e32 v0, v3, v0
	v_add_u32_e32 v16, 0xb0, v144
	v_mov_b32_dpp v18, v22 row_ror:8 row_mask:0xf bank_mask:0xf
	v_add_f32_e32 v4, v8, v0
	v_mov_b32_dpp v26, v17 row_ror:8 row_mask:0xf bank_mask:0xf
	v_cndmask_b32_e64 v18, v18, v17, s[6:7]
	v_sub_u32_e32 v17, v16, v146
	ds_bpermute_b32 v5, v114, v4
	v_mov_b32_dpp v27, v19 row_ror:8 row_mask:0xf bank_mask:0xf
	v_cndmask_b32_e64 v22, v22, v26, s[6:7]
	v_add_u32_e32 v26, v17, v148
	v_mov_b32_dpp v30, v23 row_ror:8 row_mask:0xf bank_mask:0xf
	v_cndmask_b32_e64 v23, v23, v27, s[6:7]
	v_ashrrev_i32_e32 v27, 31, v26
	v_lshlrev_b64 v[0:1], 12, v[26:27]
	v_lshl_add_u64 v[0:1], s[10:11], 0, v[0:1]
	v_lshl_add_u64 v[2:3], v[142:143], 1, v[0:1]
	s_waitcnt lgkmcnt(0)
	v_add_f32_e32 v0, v4, v5
	ds_bpermute_b32 v1, v115, v0
	v_mov_b32_dpp v31, v24 row_ror:8 row_mask:0xf bank_mask:0xf
	v_mov_b32_dpp v32, v25 row_ror:8 row_mask:0xf bank_mask:0xf
	v_mov_b32_dpp v28, v20 row_ror:8 row_mask:0xf bank_mask:0xf
	v_mov_b32_dpp v29, v21 row_ror:8 row_mask:0xf bank_mask:0xf
	v_cndmask_b32_e64 v19, v30, v19, s[6:7]
	v_cndmask_b32_e64 v20, v31, v20, s[6:7]
	v_cndmask_b32_e64 v21, v32, v21, s[6:7]
	global_store_dwordx4 v[2:3], v[18:21], off
	v_add_co_u32_e32 v2, vcc, s67, v2
	v_cndmask_b32_e64 v24, v24, v28, s[6:7]
	v_cndmask_b32_e64 v25, v25, v29, s[6:7]
	v_addc_co_u32_e32 v3, vcc, 0, v3, vcc
	global_store_dwordx4 v[2:3], v[22:25], off
	s_and_saveexec_b64 s[38:39], s[8:9]
	s_cbranch_execz .LBB0_1271
	v_ashrrev_i32_e32 v17, 31, v16
	s_waitcnt lgkmcnt(0)
	v_add_f32_e32 v2, v0, v1
	v_lshl_add_u64 v[0:1], v[16:17], 2, s[16:17]
	global_atomic_add_f32 v[0:1], v2, off
	s_branch .LBB0_1271

; #define PG8_STAGE(bufoff, gbase, voff) do { _Pragma("unroll") for (int _i = 0; _i < 2; ++_i) \
;         __builtin_amdgcn_global_load_lds((const unsigned*)((const char*)(gbase) + (voff)[_i]), (LAS unsigned*)(lds + (bufoff) + ldsw + _i * 8192), 16, 0, 0); } while (0)
; #define PG8_LDA(dst, b, h) do { _Pragma("unroll") for (int m = 0; m < 4; ++m) _Pragma("unroll") for (int k = 0; k < 2; ++k) dst[m][k] = *(const LAS bf16x8*)(lds + PG8_SA(b, h) + aoff + m * 2048 + k * 1024); } while (0)
; #define PG8_LDB(dst, b, h) do { _Pragma("unroll") for (int n = 0; n < 2; ++n) _Pragma("unroll") for (int k = 0; k < 2; ++k) dst[n][k] = *(const LAS bf16x8*)(lds + PG8_SB(b, h) + boff + n * 2048 + k * 1024); } while (0)
; #define PG8_WAIT_V(n) asm volatile("s_waitcnt vmcnt(" #n ")" ::: "memory")
; #define PG8_WAIT_L(n) asm volatile("s_waitcnt lgkmcnt(" #n ")" ::: "memory")
; #define PG8_BAR __builtin_amdgcn_s_barrier()
; #define PG8_SCHED __builtin_amdgcn_sched_barrier(0)
; template <class Epi>
; __device__ __forceinline__ void gemm_phase(LAS unsigned char* lds, const Gemm g, const StaticOrder& S, const Epi& E) {
;     ...
;             PG8_LDB(B0, 0, 0); PG8_SCHED; PG8_LDA(At, 0, 0); PG8_STAGE(PG8_SA(1, 1), a1 + hstep, voffA);
;             PG8_WAIT_L(8); PG8_BAR; PG8_WAIT_L(0); PG8_MMA(0, 0, At, B0); PG8_BAR; PG8_SCHED;
;             PG8_LDB(B1, 0, 1); PG8_STAGE(PG8_SB(0, 0), b2, voffB0);
;             PG8_BAR; PG8_WAIT_L(0); PG8_MMA(0, 1, At, B1); PG8_BAR;
;             PG8_LDA(At, 0, 1); PG8_STAGE(PG8_SA(0, 0), a2, voffA);
;             PG8_BAR; PG8_WAIT_L(0); PG8_MMA(1, 0, At, B0); PG8_BAR; PG8_SCHED;
;             PG8_STAGE(PG8_SB(0, 1), b2, voffB1);
;             PG8_WAIT_V(6); PG8_BAR; PG8_MMA(1, 1, At, B1); PG8_BAR;
;             PG8_LDB(B0, 1, 0); PG8_SCHED; PG8_LDA(At, 1, 0); PG8_STAGE(PG8_SA(0, 1), a2 + hstep, voffA);
;             PG8_WAIT_L(8); PG8_BAR; PG8_WAIT_L(0); PG8_MMA(0, 0, At, B0); PG8_BAR; PG8_SCHED;
;             PG8_LDB(B1, 1, 1); PG8_STAGE(PG8_SB(1, 0), b3, voffB0);
;             PG8_BAR; PG8_WAIT_L(0); PG8_MMA(0, 1, At, B1); PG8_BAR;
;             PG8_LDA(At, 1, 1); PG8_STAGE(PG8_SA(1, 0), a3, voffA);
;             PG8_BAR; PG8_WAIT_L(0); PG8_MMA(1, 0, At, B0); PG8_BAR; PG8_SCHED;
;             PG8_STAGE(PG8_SB(1, 1), b3, voffB1);
;             PG8_WAIT_V(6); PG8_BAR; PG8_MMA(1, 1, At, B1); PG8_BAR;
.LBB0_1365:
	ds_read_b128 v[160:163], v157
	ds_read_b128 v[164:167], v157 offset:1024
	ds_read_b128 v[168:171], v157 offset:2048
	ds_read_b128 v[172:175], v157 offset:3072
	s_add_u32 s33, s38, 0xfff80080
	s_addc_u32 s40, s39, -1
	s_cmp_eq_u32 s64, 28
	s_cselect_b32 s41, s27, s40
	s_cselect_b32 s40, s60, s33
	s_cselect_b32 s43, s19, s63
	s_cselect_b32 s42, s61, s62
	v_lshl_add_u64 v[200:201], s[38:39], 0, v[140:141]
	s_add_i32 m0, s37, 0xc000
	ds_read_b128 v[176:179], v158
	ds_read_b128 v[180:183], v158 offset:1024
	ds_read_b128 v[184:187], v158 offset:2048
	ds_read_b128 v[188:191], v158 offset:3072
	ds_read_b128 v[192:195], v158 offset:4096
	ds_read_b128 v[196:199], v158 offset:5120
	ds_read_b128 v[204:207], v158 offset:6144
	ds_read_b128 v[208:211], v158 offset:7168
	global_load_lds_dwordx4 v[200:201], off
	v_lshl_add_u64 v[200:201], s[38:39], 0, v[142:143]
	s_add_i32 m0, s37, 0xe000
	s_nop 0
	global_load_lds_dwordx4 v[200:201], off
	s_waitcnt lgkmcnt(8)
	s_barrier
	s_waitcnt lgkmcnt(0)
	v_mfma_f32_16x16x32_bf16 v[124:127], v[160:163], v[176:179], v[124:127]
	v_mfma_f32_16x16x32_bf16 v[120:123], v[168:171], v[176:179], v[120:123]
	v_mfma_f32_16x16x32_bf16 v[108:111], v[160:163], v[184:187], v[108:111]
	v_mfma_f32_16x16x32_bf16 v[104:107], v[168:171], v[184:187], v[104:107]
	v_mfma_f32_16x16x32_bf16 v[92:95], v[160:163], v[192:195], v[92:95]
	v_mfma_f32_16x16x32_bf16 v[88:91], v[168:171], v[192:195], v[88:91]
	v_mfma_f32_16x16x32_bf16 v[76:79], v[160:163], v[204:207], v[76:79]
	v_mfma_f32_16x16x32_bf16 v[72:75], v[168:171], v[204:207], v[72:75]
	v_mfma_f32_16x16x32_bf16 v[124:127], v[164:167], v[180:183], v[124:127]
	v_mfma_f32_16x16x32_bf16 v[120:123], v[172:175], v[180:183], v[120:123]
	v_mfma_f32_16x16x32_bf16 v[108:111], v[164:167], v[188:191], v[108:111]
	v_mfma_f32_16x16x32_bf16 v[104:107], v[172:175], v[188:191], v[104:107]
	v_mfma_f32_16x16x32_bf16 v[92:95], v[164:167], v[196:199], v[92:95]
	v_mfma_f32_16x16x32_bf16 v[88:91], v[172:175], v[196:199], v[88:91]
	v_mfma_f32_16x16x32_bf16 v[76:79], v[164:167], v[208:211], v[76:79]
	v_mfma_f32_16x16x32_bf16 v[72:75], v[172:175], v[208:211], v[72:75]
	s_barrier
	s_add_i32 s33, s56, s46
	v_lshl_add_u64 v[200:201], s[42:43], 0, v[130:131]
	s_mov_b32 m0, s33
	ds_read_b128 v[212:215], v159
	ds_read_b128 v[216:219], v159 offset:1024
	ds_read_b128 v[220:223], v159 offset:2048
	ds_read_b128 v[224:227], v159 offset:3072
	global_load_lds_dwordx4 v[200:201], off
	v_lshl_add_u64 v[228:229], s[42:43], 0, v[136:137]
	s_add_i32 m0, s33, 0x2000
	s_nop 0
	global_load_lds_dwordx4 v[228:229], off
	s_barrier
	s_waitcnt lgkmcnt(0)
	v_mfma_f32_16x16x32_bf16 v[116:119], v[212:215], v[176:179], v[116:119]
	v_mfma_f32_16x16x32_bf16 v[112:115], v[220:223], v[176:179], v[112:115]
	v_mfma_f32_16x16x32_bf16 v[100:103], v[212:215], v[184:187], v[100:103]
	v_mfma_f32_16x16x32_bf16 v[96:99], v[220:223], v[184:187], v[96:99]
	v_mfma_f32_16x16x32_bf16 v[84:87], v[212:215], v[192:195], v[84:87]
	v_mfma_f32_16x16x32_bf16 v[80:83], v[220:223], v[192:195], v[80:83]
	v_mfma_f32_16x16x32_bf16 v[68:71], v[212:215], v[204:207], v[68:71]
	v_mfma_f32_16x16x32_bf16 v[64:67], v[220:223], v[204:207], v[64:67]
	v_mfma_f32_16x16x32_bf16 v[116:119], v[216:219], v[180:183], v[116:119]
	v_mfma_f32_16x16x32_bf16 v[112:115], v[224:227], v[180:183], v[112:115]
	v_mfma_f32_16x16x32_bf16 v[100:103], v[216:219], v[188:191], v[100:103]
	v_mfma_f32_16x16x32_bf16 v[96:99], v[224:227], v[188:191], v[96:99]
	v_mfma_f32_16x16x32_bf16 v[84:87], v[216:219], v[196:199], v[84:87]
	v_mfma_f32_16x16x32_bf16 v[80:83], v[224:227], v[196:199], v[80:83]
	v_mfma_f32_16x16x32_bf16 v[68:71], v[216:219], v[208:211], v[68:71]
	v_mfma_f32_16x16x32_bf16 v[64:67], v[224:227], v[208:211], v[64:67]
	s_mov_b32 m0, s37
	v_lshl_add_u64 v[230:231], s[40:41], 0, v[128:129]
	s_barrier
	ds_read_b128 v[176:179], v158 offset:16384
	ds_read_b128 v[180:183], v158 offset:17408
	ds_read_b128 v[184:187], v158 offset:18432
	ds_read_b128 v[188:191], v158 offset:19456
	ds_read_b128 v[192:195], v158 offset:20480
	ds_read_b128 v[196:199], v158 offset:21504
	ds_read_b128 v[204:207], v158 offset:22528
	ds_read_b128 v[208:211], v158 offset:23552
	global_load_lds_dwordx4 v[230:231], off
	v_lshl_add_u64 v[232:233], s[40:41], 0, v[134:135]
	s_mov_b32 m0, s47
	s_nop 0
	global_load_lds_dwordx4 v[232:233], off
	s_barrier
	s_waitcnt lgkmcnt(0)
	v_mfma_f32_16x16x32_bf16 v[60:63], v[160:163], v[176:179], v[60:63]
	v_mfma_f32_16x16x32_bf16 v[56:59], v[168:171], v[176:179], v[56:59]
	v_mfma_f32_16x16x32_bf16 v[44:47], v[160:163], v[184:187], v[44:47]
	v_mfma_f32_16x16x32_bf16 v[40:43], v[168:171], v[184:187], v[40:43]
	v_mfma_f32_16x16x32_bf16 v[28:31], v[160:163], v[192:195], v[28:31]
	v_mfma_f32_16x16x32_bf16 v[24:27], v[168:171], v[192:195], v[24:27]
	v_mfma_f32_16x16x32_bf16 v[12:15], v[160:163], v[204:207], v[12:15]
	v_mfma_f32_16x16x32_bf16 v[8:11], v[168:171], v[204:207], v[8:11]
	v_mfma_f32_16x16x32_bf16 v[60:63], v[164:167], v[180:183], v[60:63]
	v_mfma_f32_16x16x32_bf16 v[56:59], v[172:175], v[180:183], v[56:59]
	v_mfma_f32_16x16x32_bf16 v[44:47], v[164:167], v[188:191], v[44:47]
	v_mfma_f32_16x16x32_bf16 v[40:43], v[172:175], v[188:191], v[40:43]
	v_mfma_f32_16x16x32_bf16 v[28:31], v[164:167], v[196:199], v[28:31]
	v_mfma_f32_16x16x32_bf16 v[24:27], v[172:175], v[196:199], v[24:27]
	v_mfma_f32_16x16x32_bf16 v[12:15], v[164:167], v[208:211], v[12:15]
	v_mfma_f32_16x16x32_bf16 v[8:11], v[172:175], v[208:211], v[8:11]
	s_barrier
	s_add_i32 s33, s57, s46
	v_lshl_add_u64 v[234:235], s[42:43], 0, v[132:133]
	s_mov_b32 m0, s33
	v_lshl_add_u64 v[236:237], s[42:43], 0, v[138:139]
	global_load_lds_dwordx4 v[234:235], off
	s_add_i32 m0, s33, 0x2000
	s_nop 0
	global_load_lds_dwordx4 v[236:237], off
	s_waitcnt vmcnt(6)
	s_barrier
; #define PG8_STAGE(bufoff, gbase, voff) do { _Pragma("unroll") for (int _i = 0; _i < 2; ++_i) \
;         __builtin_amdgcn_global_load_lds((const unsigned*)((const char*)(gbase) + (voff)[_i]), (LAS unsigned*)(lds + (bufoff) + ldsw + _i * 8192), 16, 0, 0); } while (0)
; #define PG8_LDA(dst, b, h) do { _Pragma("unroll") for (int m = 0; m < 4; ++m) _Pragma("unroll") for (int k = 0; k < 2; ++k) dst[m][k] = *(const LAS bf16x8*)(lds + PG8_SA(b, h) + aoff + m * 2048 + k * 1024); } while (0)
; #define PG8_LDB(dst, b, h) do { _Pragma("unroll") for (int n = 0; n < 2; ++n) _Pragma("unroll") for (int k = 0; k < 2; ++k) dst[n][k] = *(const LAS bf16x8*)(lds + PG8_SB(b, h) + boff + n * 2048 + k * 1024); } while (0)
; #define PG8_WAIT_V(n) asm volatile("s_waitcnt vmcnt(" #n ")" ::: "memory")
; #define PG8_WAIT_L(n) asm volatile("s_waitcnt lgkmcnt(" #n ")" ::: "memory")
; #define PG8_BAR __builtin_amdgcn_s_barrier()
; #define PG8_SCHED __builtin_amdgcn_sched_barrier(0)
; template <class Epi>
; __device__ __forceinline__ void gemm_phase(LAS unsigned char* lds, const Gemm g, const StaticOrder& S, const Epi& E) {
;     ...
;             PG8_LDB(B0, 0, 0); PG8_SCHED; PG8_LDA(At, 0, 0); PG8_STAGE(PG8_SA(1, 1), a1 + hstep, voffA);
;             PG8_WAIT_L(8); PG8_BAR; PG8_WAIT_L(0); PG8_MMA(0, 0, At, B0); PG8_BAR; PG8_SCHED;
;             PG8_LDB(B1, 0, 1); PG8_STAGE(PG8_SB(0, 0), b2, voffB0);
;             PG8_BAR; PG8_WAIT_L(0); PG8_MMA(0, 1, At, B1); PG8_BAR;
;             PG8_LDA(At, 0, 1); PG8_STAGE(PG8_SA(0, 0), a2, voffA);
;             PG8_BAR; PG8_WAIT_L(0); PG8_MMA(1, 0, At, B0); PG8_BAR; PG8_SCHED;
;             PG8_STAGE(PG8_SB(0, 1), b2, voffB1);
;             PG8_WAIT_V(6); PG8_BAR; PG8_MMA(1, 1, At, B1); PG8_BAR;
;             PG8_LDB(B0, 1, 0); PG8_SCHED; PG8_LDA(At, 1, 0); PG8_STAGE(PG8_SA(0, 1), a2 + hstep, voffA);
;             PG8_WAIT_L(8); PG8_BAR; PG8_WAIT_L(0); PG8_MMA(0, 0, At, B0); PG8_BAR; PG8_SCHED;
;             PG8_LDB(B1, 1, 1); PG8_STAGE(PG8_SB(1, 0), b3, voffB0);
;             PG8_BAR; PG8_WAIT_L(0); PG8_MMA(0, 1, At, B1); PG8_BAR;
;             PG8_LDA(At, 1, 1); PG8_STAGE(PG8_SA(1, 0), a3, voffA);
;             PG8_BAR; PG8_WAIT_L(0); PG8_MMA(1, 0, At, B0); PG8_BAR; PG8_SCHED;
;             PG8_STAGE(PG8_SB(1, 1), b3, voffB1);
;             PG8_WAIT_V(6); PG8_BAR; PG8_MMA(1, 1, At, B1); PG8_BAR;
	v_mfma_f32_16x16x32_bf16 v[52:55], v[212:215], v[176:179], v[52:55]
	v_mfma_f32_16x16x32_bf16 v[48:51], v[220:223], v[176:179], v[48:51]
	v_mfma_f32_16x16x32_bf16 v[36:39], v[212:215], v[184:187], v[36:39]
	v_mfma_f32_16x16x32_bf16 v[32:35], v[220:223], v[184:187], v[32:35]
	v_mfma_f32_16x16x32_bf16 v[20:23], v[212:215], v[192:195], v[20:23]
	v_mfma_f32_16x16x32_bf16 v[16:19], v[220:223], v[192:195], v[16:19]
	v_mfma_f32_16x16x32_bf16 v[4:7], v[212:215], v[204:207], v[4:7]
	v_mfma_f32_16x16x32_bf16 v[0:3], v[220:223], v[204:207], v[0:3]
	v_mfma_f32_16x16x32_bf16 v[52:55], v[216:219], v[180:183], v[52:55]
	v_mfma_f32_16x16x32_bf16 v[48:51], v[224:227], v[180:183], v[48:51]
	v_mfma_f32_16x16x32_bf16 v[36:39], v[216:219], v[188:191], v[36:39]
	v_mfma_f32_16x16x32_bf16 v[32:35], v[224:227], v[188:191], v[32:35]
	v_mfma_f32_16x16x32_bf16 v[20:23], v[216:219], v[196:199], v[20:23]
	v_mfma_f32_16x16x32_bf16 v[16:19], v[224:227], v[196:199], v[16:19]
	v_mfma_f32_16x16x32_bf16 v[4:7], v[216:219], v[208:211], v[4:7]
	v_mfma_f32_16x16x32_bf16 v[0:3], v[224:227], v[208:211], v[0:3]
	s_add_i32 s33, 0, 0x18000
	v_add_u32_e32 v172, s33, v147
	s_barrier
	ds_read_b128 v[160:163], v172
	ds_read_b128 v[164:167], v172 offset:1024
	ds_read_b128 v[168:171], v172 offset:2048
	ds_read_b128 v[172:175], v172 offset:3072
	s_add_u32 s40, s40, 0x80000
	s_addc_u32 s41, s41, 0
	s_mov_b32 m0, s48
	v_lshl_add_u64 v[212:213], s[40:41], 0, v[128:129]
	ds_read_b128 v[176:179], v158 offset:32768
	ds_read_b128 v[180:183], v158 offset:33792
	ds_read_b128 v[184:187], v158 offset:34816
	ds_read_b128 v[188:191], v158 offset:35840
	ds_read_b128 v[192:195], v158 offset:36864
	ds_read_b128 v[196:199], v158 offset:37888
	ds_read_b128 v[204:207], v158 offset:38912
	ds_read_b128 v[208:211], v158 offset:39936
	global_load_lds_dwordx4 v[212:213], off
	v_lshl_add_u64 v[212:213], s[40:41], 0, v[134:135]
	s_mov_b32 m0, s49
	s_nop 0
	global_load_lds_dwordx4 v[212:213], off
	s_waitcnt lgkmcnt(8)
	s_barrier
	s_waitcnt lgkmcnt(0)
	v_mfma_f32_16x16x32_bf16 v[124:127], v[160:163], v[176:179], v[124:127]
	v_mfma_f32_16x16x32_bf16 v[120:123], v[168:171], v[176:179], v[120:123]
	v_mfma_f32_16x16x32_bf16 v[108:111], v[160:163], v[184:187], v[108:111]
	v_mfma_f32_16x16x32_bf16 v[104:107], v[168:171], v[184:187], v[104:107]
	v_mfma_f32_16x16x32_bf16 v[92:95], v[160:163], v[192:195], v[92:95]
	v_mfma_f32_16x16x32_bf16 v[88:91], v[168:171], v[192:195], v[88:91]
	v_mfma_f32_16x16x32_bf16 v[76:79], v[160:163], v[204:207], v[76:79]
	v_mfma_f32_16x16x32_bf16 v[72:75], v[168:171], v[204:207], v[72:75]
	v_mfma_f32_16x16x32_bf16 v[124:127], v[164:167], v[180:183], v[124:127]
	v_mfma_f32_16x16x32_bf16 v[120:123], v[172:175], v[180:183], v[120:123]
	v_mfma_f32_16x16x32_bf16 v[108:111], v[164:167], v[188:191], v[108:111]
	v_mfma_f32_16x16x32_bf16 v[104:107], v[172:175], v[188:191], v[104:107]
	v_mfma_f32_16x16x32_bf16 v[92:95], v[164:167], v[196:199], v[92:95]
	v_mfma_f32_16x16x32_bf16 v[88:91], v[172:175], v[196:199], v[88:91]
	v_mfma_f32_16x16x32_bf16 v[76:79], v[164:167], v[208:211], v[76:79]
	v_mfma_f32_16x16x32_bf16 v[72:75], v[172:175], v[208:211], v[72:75]
	s_barrier
	s_add_i32 s40, 0, 0x1c000
	s_add_i32 s33, s33, s46
	v_add_u32_e32 v203, s40, v147
	v_lshl_add_u64 v[200:201], v[200:201], 0, s[16:17]
	s_mov_b32 m0, s33
	ds_read_b128 v[212:215], v203
	ds_read_b128 v[216:219], v203 offset:1024
	ds_read_b128 v[220:223], v203 offset:2048
	ds_read_b128 v[224:227], v203 offset:3072
	global_load_lds_dwordx4 v[200:201], off
	v_lshl_add_u64 v[200:201], v[228:229], 0, s[16:17]
	s_add_i32 m0, s33, 0x2000
	s_nop 0
	global_load_lds_dwordx4 v[200:201], off
	s_barrier
	s_waitcnt lgkmcnt(0)
	v_mfma_f32_16x16x32_bf16 v[116:119], v[212:215], v[176:179], v[116:119]
	v_mfma_f32_16x16x32_bf16 v[112:115], v[220:223], v[176:179], v[112:115]
	v_mfma_f32_16x16x32_bf16 v[100:103], v[212:215], v[184:187], v[100:103]
	v_mfma_f32_16x16x32_bf16 v[96:99], v[220:223], v[184:187], v[96:99]
	v_mfma_f32_16x16x32_bf16 v[84:87], v[212:215], v[192:195], v[84:87]
	v_mfma_f32_16x16x32_bf16 v[80:83], v[220:223], v[192:195], v[80:83]
	v_mfma_f32_16x16x32_bf16 v[68:71], v[212:215], v[204:207], v[68:71]
	v_mfma_f32_16x16x32_bf16 v[64:67], v[220:223], v[204:207], v[64:67]
	v_mfma_f32_16x16x32_bf16 v[116:119], v[216:219], v[180:183], v[116:119]
	v_mfma_f32_16x16x32_bf16 v[112:115], v[224:227], v[180:183], v[112:115]
	v_mfma_f32_16x16x32_bf16 v[100:103], v[216:219], v[188:191], v[100:103]
	v_mfma_f32_16x16x32_bf16 v[96:99], v[224:227], v[188:191], v[96:99]
	v_mfma_f32_16x16x32_bf16 v[84:87], v[216:219], v[196:199], v[84:87]
	v_mfma_f32_16x16x32_bf16 v[80:83], v[224:227], v[196:199], v[80:83]
	v_mfma_f32_16x16x32_bf16 v[68:71], v[216:219], v[208:211], v[68:71]
	v_mfma_f32_16x16x32_bf16 v[64:67], v[224:227], v[208:211], v[64:67]
	s_mov_b32 m0, s51
	v_lshl_add_u64 v[200:201], v[230:231], 0, s[16:17]
	s_barrier
	ds_read_b128 v[176:179], v158 offset:49152
	ds_read_b128 v[180:183], v158 offset:50176
	ds_read_b128 v[184:187], v158 offset:51200
	ds_read_b128 v[188:191], v158 offset:52224
	ds_read_b128 v[192:195], v158 offset:53248
	ds_read_b128 v[196:199], v158 offset:54272
	ds_read_b128 v[204:207], v158 offset:55296
	ds_read_b128 v[208:211], v158 offset:56320
	global_load_lds_dwordx4 v[200:201], off
	v_lshl_add_u64 v[200:201], v[232:233], 0, s[16:17]
	s_mov_b32 m0, s52
	s_nop 0
	global_load_lds_dwordx4 v[200:201], off
	s_barrier
; __device__ __forceinline__ unsigned cvt_pk_bf16(float lo, float hi) { unsigned r; asm volatile("v_cvt_pk_bf16_f32 %0, %1, %2" : "=v"(r) : "v"(lo), "v"(hi)); return r; }
; #define PG8_STAGE(bufoff, gbase, voff) do { _Pragma("unroll") for (int _i = 0; _i < 2; ++_i) \
;         __builtin_amdgcn_global_load_lds((const unsigned*)((const char*)(gbase) + (voff)[_i]), (LAS unsigned*)(lds + (bufoff) + ldsw + _i * 8192), 16, 0, 0); } while (0)
; #define PG8_WAIT_V(n) asm volatile("s_waitcnt vmcnt(" #n ")" ::: "memory")
;     __device__ __forceinline__ void operator()(const f32x4 (&acc)[2][2][4][2], const Unit& u, int wr, int wc, int fr, int fq) const {
;     ...
;             for (int m = 0; m < 4; ++m) { const int row = row0 + ai * HALF + m * 16;
;                 const float rs = ssin ? __builtin_amdgcn_rsqf(ssin[row] * (1.f / D) + EPS) : 1.0f; float sq = 0.f; u32x4 w[2];
; #pragma unroll
;                 for (int bj = 0; bj < 2; ++bj) { f32x4 v0 = acc[ai][bj][m][0] * rs, v1 = acc[ai][bj][m][1] * rs;
;                     if (ACT == 1) {
; #pragma unroll
;                         for (int j = 0; j < 4; ++j) { const float a = fmaxf(v0[j], 0.f), b = fmaxf(v1[j], 0.f); v0[j] = a * a; v1[j] = b * b; } }
;                     sq += (v0[0] * v0[0] + v0[1] * v0[1]) + (v0[2] * v0[2] + v0[3] * v0[3]) + (v1[0] * v1[0] + v1[1] * v1[1]) + (v1[2] * v1[2] + v1[3] * v1[3]);
;                     w[bj].x = cvt_pk_bf16(v0[0], v0[1]); w[bj].y = cvt_pk_bf16(v0[2], v0[3]); w[bj].z = cvt_pk_bf16(v1[0], v1[1]); w[bj].w = cvt_pk_bf16(v1[2], v1[3]); }
; template <class Epi>
; __device__ __forceinline__ void gemm_phase(LAS unsigned char* lds, const Gemm g, const StaticOrder& S, const Epi& E) {
;     ...
;             PG8_WAIT_V(6); PG8_BAR; PG8_MMA(1, 1, At, B1); PG8_BAR;
;             PG8_LDB(B0, 1, 0); PG8_SCHED; PG8_LDA(At, 1, 0); PG8_STAGE(PG8_SA(0, 1), a2 + hstep, voffA);
;             PG8_WAIT_L(8); PG8_BAR; PG8_WAIT_L(0); PG8_MMA(0, 0, At, B0); PG8_BAR; PG8_SCHED;
;             PG8_LDB(B1, 1, 1); PG8_STAGE(PG8_SB(1, 0), b3, voffB0);
;             PG8_BAR; PG8_WAIT_L(0); PG8_MMA(0, 1, At, B1); PG8_BAR;
;             PG8_LDA(At, 1, 1); PG8_STAGE(PG8_SA(1, 0), a3, voffA);
;             PG8_BAR; PG8_WAIT_L(0); PG8_MMA(1, 0, At, B0); PG8_BAR; PG8_SCHED;
;             PG8_STAGE(PG8_SB(1, 1), b3, voffB1);
;             PG8_WAIT_V(6); PG8_BAR; PG8_MMA(1, 1, At, B1); PG8_BAR;
	s_waitcnt lgkmcnt(0)
	v_mfma_f32_16x16x32_bf16 v[60:63], v[160:163], v[176:179], v[60:63]
	v_mfma_f32_16x16x32_bf16 v[56:59], v[168:171], v[176:179], v[56:59]
	v_mfma_f32_16x16x32_bf16 v[44:47], v[160:163], v[184:187], v[44:47]
	v_mfma_f32_16x16x32_bf16 v[40:43], v[168:171], v[184:187], v[40:43]
	v_mfma_f32_16x16x32_bf16 v[28:31], v[160:163], v[192:195], v[28:31]
	v_mfma_f32_16x16x32_bf16 v[24:27], v[168:171], v[192:195], v[24:27]
	v_mfma_f32_16x16x32_bf16 v[12:15], v[160:163], v[204:207], v[12:15]
	v_mfma_f32_16x16x32_bf16 v[8:11], v[168:171], v[204:207], v[8:11]
	v_mfma_f32_16x16x32_bf16 v[60:63], v[164:167], v[180:183], v[60:63]
	v_mfma_f32_16x16x32_bf16 v[56:59], v[172:175], v[180:183], v[56:59]
	v_mfma_f32_16x16x32_bf16 v[44:47], v[164:167], v[188:191], v[44:47]
	v_mfma_f32_16x16x32_bf16 v[40:43], v[172:175], v[188:191], v[40:43]
	v_mfma_f32_16x16x32_bf16 v[28:31], v[164:167], v[196:199], v[28:31]
	v_mfma_f32_16x16x32_bf16 v[24:27], v[172:175], v[196:199], v[24:27]
	v_mfma_f32_16x16x32_bf16 v[12:15], v[164:167], v[208:211], v[12:15]
	v_mfma_f32_16x16x32_bf16 v[8:11], v[172:175], v[208:211], v[8:11]
	s_barrier
	s_add_i32 s33, s40, s46
	v_lshl_add_u64 v[160:161], v[234:235], 0, s[16:17]
	s_mov_b32 m0, s33
	s_nop 0
	global_load_lds_dwordx4 v[160:161], off
	v_lshl_add_u64 v[160:161], v[236:237], 0, s[16:17]
	s_add_i32 m0, s33, 0x2000
	s_nop 0
	global_load_lds_dwordx4 v[160:161], off
	s_waitcnt vmcnt(6)
	s_barrier
	v_mfma_f32_16x16x32_bf16 v[52:55], v[212:215], v[176:179], v[52:55]
	v_mfma_f32_16x16x32_bf16 v[48:51], v[220:223], v[176:179], v[48:51]
	v_mfma_f32_16x16x32_bf16 v[36:39], v[212:215], v[184:187], v[36:39]
	v_mfma_f32_16x16x32_bf16 v[32:35], v[220:223], v[184:187], v[32:35]
	v_mfma_f32_16x16x32_bf16 v[20:23], v[212:215], v[192:195], v[20:23]
	v_mfma_f32_16x16x32_bf16 v[16:19], v[220:223], v[192:195], v[16:19]
	v_mfma_f32_16x16x32_bf16 v[4:7], v[212:215], v[204:207], v[4:7]
	v_mfma_f32_16x16x32_bf16 v[0:3], v[220:223], v[204:207], v[0:3]
	v_mfma_f32_16x16x32_bf16 v[52:55], v[216:219], v[180:183], v[52:55]
	v_mfma_f32_16x16x32_bf16 v[48:51], v[224:227], v[180:183], v[48:51]
	v_mfma_f32_16x16x32_bf16 v[36:39], v[216:219], v[188:191], v[36:39]
	v_mfma_f32_16x16x32_bf16 v[32:35], v[224:227], v[188:191], v[32:35]
	v_mfma_f32_16x16x32_bf16 v[20:23], v[216:219], v[196:199], v[20:23]
	v_mfma_f32_16x16x32_bf16 v[16:19], v[224:227], v[196:199], v[16:19]
	v_mfma_f32_16x16x32_bf16 v[4:7], v[216:219], v[208:211], v[4:7]
	v_mfma_f32_16x16x32_bf16 v[0:3], v[224:227], v[208:211], v[0:3]
	s_add_i32 s64, s64, 2
	s_add_u32 s38, s38, 0x100
	s_addc_u32 s39, s39, 0
	s_add_u32 s62, s62, 0x100
	s_addc_u32 s63, s63, 0
	s_cmp_gt_u32 s64, 29
	s_barrier
	s_cbranch_scc0 .LBB0_1365
	v_max_f32_e32 v124, 0, v124
	v_max_f32_e32 v120, 0, v120
	v_max_f32_e32 v125, 0, v125
	v_max_f32_e32 v121, 0, v121
	v_max_f32_e32 v122, 0, v122
	v_max_f32_e32 v118, 0, v118
	v_max_f32_e32 v119, 0, v119
	v_mul_f32_e32 v124, v124, v124
	v_mul_f32_e32 v120, v120, v120
	v_mul_f32_e32 v125, v125, v125
	v_mul_f32_e32 v121, v121, v121
	v_max_f32_e32 v126, 0, v126
	v_mul_f32_e32 v122, v122, v122
	v_max_f32_e32 v127, 0, v127
	v_max_f32_e32 v123, 0, v123
	v_max_f32_e32 v116, 0, v116
	v_max_f32_e32 v112, 0, v112
	v_max_f32_e32 v117, 0, v117
	v_max_f32_e32 v113, 0, v113
	v_max_f32_e32 v114, 0, v114
	v_mul_f32_e32 v118, v118, v118
	v_mul_f32_e32 v119, v119, v119
	s_lshl_b32 s19, s36, 8
	v_mul_f32_e32 v126, v126, v126
	v_mul_f32_e32 v127, v127, v127
	v_mul_f32_e32 v123, v123, v123
	v_cvt_pk_bf16_f32 v124, v124, v125
	v_cvt_pk_bf16_f32 v125, v126, v127
	v_cvt_pk_bf16_f32 v120, v120, v121
	v_cvt_pk_bf16_f32 v121, v122, v123
	v_mul_f32_e32 v116, v116, v116
	v_mul_f32_e32 v112, v112, v112
	v_mul_f32_e32 v117, v117, v117
	v_mul_f32_e32 v113, v113, v113
	v_mul_f32_e32 v114, v114, v114
	v_max_f32_e32 v115, 0, v115
	v_cvt_pk_bf16_f32 v122, v116, v117
	v_cvt_pk_bf16_f32 v119, v118, v119
	s_add_i32 s19, s19, s53
	v_mul_f32_e32 v115, v115, v115
	v_cvt_pk_bf16_f32 v112, v112, v113
	v_cvt_pk_bf16_f32 v113, v114, v115
	v_mov_b32_dpp v118, v124 row_ror:8 row_mask:0xf bank_mask:0xf
	v_mov_b32_dpp v123, v125 row_ror:8 row_mask:0xf bank_mask:0xf
	v_mov_b32_dpp v114, v122 row_ror:8 row_mask:0xf bank_mask:0xf
	v_cndmask_b32_e64 v118, v122, v118, s[6:7]
	v_or_b32_e32 v122, s19, v148
	v_lshl_or_b32 v162, s59, 8, v156
	v_mov_b32_dpp v126, v120 row_ror:8 row_mask:0xf bank_mask:0xf
	v_mov_b32_dpp v127, v121 row_ror:8 row_mask:0xf bank_mask:0xf
	v_mov_b32_dpp v115, v119 row_ror:8 row_mask:0xf bank_mask:0xf
	v_mov_b32_dpp v116, v112 row_ror:8 row_mask:0xf bank_mask:0xf
	v_mov_b32_dpp v117, v113 row_ror:8 row_mask:0xf bank_mask:0xf
	v_cndmask_b32_e64 v119, v119, v123, s[6:7]
	v_ashrrev_i32_e32 v123, 31, v122
	v_ashrrev_i32_e32 v163, 31, v162
	v_cndmask_b32_e64 v116, v116, v120, s[6:7]
	v_cndmask_b32_e64 v117, v117, v121, s[6:7]
	v_cndmask_b32_e64 v120, v112, v126, s[6:7]
	v_cndmask_b32_e64 v121, v113, v127, s[6:7]
	v_lshlrev_b64 v[112:113], 14, v[122:123]
	v_cndmask_b32_e64 v114, v114, v124, s[6:7]
	v_cndmask_b32_e64 v115, v115, v125, s[6:7]
	v_lshl_add_u64 v[124:125], s[12:13], 0, v[112:113]
	v_lshlrev_b64 v[112:113], 1, v[162:163]
	v_lshl_add_u64 v[124:125], v[124:125], 0, v[112:113]
	global_store_dwordx4 v[124:125], v[114:117], off
	v_max_f32_e32 v108, v108, v108
	v_max_f32_e32 v104, v104, v104
	v_or_b32_e32 v114, 8, v122
	v_ashrrev_i32_e32 v115, 31, v114
	v_lshlrev_b64 v[114:115], 14, v[114:115]
	v_lshl_add_u64 v[114:115], s[12:13], 0, v[114:115]
	v_max_f32_e32 v108, 0, v108
	v_max_f32_e32 v104, 0, v104
	v_max_f32_e32 v109, 0, v109
	v_max_f32_e32 v105, 0, v105
	v_max_f32_e32 v100, 0, v100
	v_max_f32_e32 v101, 0, v101
; __device__ __forceinline__ unsigned cvt_pk_bf16(float lo, float hi) { unsigned r; asm volatile("v_cvt_pk_bf16_f32 %0, %1, %2" : "=v"(r) : "v"(lo), "v"(hi)); return r; }
; __device__ __forceinline__ unsigned dpp_ror8(unsigned x) { return (unsigned)__builtin_amdgcn_update_dpp(0, (int)x, 0x128, 0xf, 0xf, false); }
; __device__ __forceinline__ void store_pair_lines(bf16_t* O, int ldc, int row, int fr, int col0, u32x4 wA, u32x4 wB) {
;     const u32x4 sA = {dpp_ror8(wA.x), dpp_ror8(wA.y), dpp_ror8(wA.z), dpp_ror8(wA.w)}, sB = {dpp_ror8(wB.x), dpp_ror8(wB.y), dpp_ror8(wB.z), dpp_ror8(wB.w)};
;     const bool lo = fr < 8;
;     const u32x4 o1 = lo ? wA : sB, o2 = lo ? sA : wB;
;     const int r1 = row - fr + (fr & 7), cb = col0 + (lo ? 0 : 8);
;     *(u32x4*)(O + (size_t)r1 * ldc + cb) = o1;
;     *(u32x4*)(O + (size_t)(r1 + 8) * ldc + cb) = o2;
; }
;     __device__ __forceinline__ void operator()(const f32x4 (&acc)[2][2][4][2], const Unit& u, int wr, int wc, int fr, int fq) const {
;     ...
;             for (int m = 0; m < 4; ++m) { const int row = row0 + ai * HALF + m * 16;
;                 const float rs = ssin ? __builtin_amdgcn_rsqf(ssin[row] * (1.f / D) + EPS) : 1.0f; float sq = 0.f; u32x4 w[2];
; #pragma unroll
;                 for (int bj = 0; bj < 2; ++bj) { f32x4 v0 = acc[ai][bj][m][0] * rs, v1 = acc[ai][bj][m][1] * rs;
;                     if (ACT == 1) {
; #pragma unroll
;                         for (int j = 0; j < 4; ++j) { const float a = fmaxf(v0[j], 0.f), b = fmaxf(v1[j], 0.f); v0[j] = a * a; v1[j] = b * b; } }
;                     sq += (v0[0] * v0[0] + v0[1] * v0[1]) + (v0[2] * v0[2] + v0[3] * v0[3]) + (v1[0] * v1[0] + v1[1] * v1[1]) + (v1[2] * v1[2] + v1[3] * v1[3]);
;                     w[bj].x = cvt_pk_bf16(v0[0], v0[1]); w[bj].y = cvt_pk_bf16(v0[2], v0[3]); w[bj].z = cvt_pk_bf16(v1[0], v1[1]); w[bj].w = cvt_pk_bf16(v1[2], v1[3]); }
;                 store_pair_lines(O, ldc, row, fr, col0, w[0], w[1]);
	v_max_f32_e32 v102, 0, v102
	v_max_f32_e32 v98, 0, v98
	v_max_f32_e32 v103, 0, v103
	v_lshl_add_u64 v[114:115], v[114:115], 0, v[112:113]
	v_mul_f32_e32 v108, v108, v108
	v_mul_f32_e32 v104, v104, v104
	v_mul_f32_e32 v109, v109, v109
	v_mul_f32_e32 v105, v105, v105
	v_max_f32_e32 v110, 0, v110
	v_max_f32_e32 v106, 0, v106
	v_max_f32_e32 v111, 0, v111
	v_max_f32_e32 v107, 0, v107
	v_max_f32_e32 v96, 0, v96
	v_mul_f32_e32 v100, v100, v100
	v_max_f32_e32 v97, 0, v97
	v_mul_f32_e32 v101, v101, v101
	v_mul_f32_e32 v102, v102, v102
	v_mul_f32_e32 v98, v98, v98
	v_max_f32_e32 v99, 0, v99
	v_mul_f32_e32 v103, v103, v103
	global_store_dwordx4 v[114:115], v[118:121], off
	v_mul_f32_e32 v110, v110, v110
	v_mul_f32_e32 v106, v106, v106
	v_mul_f32_e32 v111, v111, v111
	v_mul_f32_e32 v107, v107, v107
	v_cvt_pk_bf16_f32 v108, v108, v109
	v_cvt_pk_bf16_f32 v109, v110, v111
	v_cvt_pk_bf16_f32 v104, v104, v105
	v_cvt_pk_bf16_f32 v105, v106, v107
	v_mul_f32_e32 v96, v96, v96
	v_mul_f32_e32 v97, v97, v97
	v_mul_f32_e32 v99, v99, v99
	v_cvt_pk_bf16_f32 v100, v100, v101
	v_cvt_pk_bf16_f32 v101, v102, v103
	v_cvt_pk_bf16_f32 v102, v96, v97
	v_cvt_pk_bf16_f32 v103, v98, v99
	v_or_b32_e32 v160, s19, v146
	v_mov_b32_dpp v98, v102 row_ror:8 row_mask:0xf bank_mask:0xf
	v_mov_b32_dpp v110, v104 row_ror:8 row_mask:0xf bank_mask:0xf
	v_mov_b32_dpp v99, v103 row_ror:8 row_mask:0xf bank_mask:0xf
	v_cndmask_b32_e64 v98, v98, v104, s[6:7]
	v_add_u32_e32 v104, v149, v160
	v_mov_b32_dpp v111, v105 row_ror:8 row_mask:0xf bank_mask:0xf
	v_cndmask_b32_e64 v99, v99, v105, s[6:7]
	v_ashrrev_i32_e32 v105, 31, v104
	v_lshlrev_b64 v[104:105], 14, v[104:105]
	v_mov_b32_dpp v96, v100 row_ror:8 row_mask:0xf bank_mask:0xf
	v_mov_b32_dpp v97, v101 row_ror:8 row_mask:0xf bank_mask:0xf
	v_lshl_add_u64 v[104:105], s[12:13], 0, v[104:105]
	v_cndmask_b32_e64 v96, v96, v108, s[6:7]
	v_cndmask_b32_e64 v97, v97, v109, s[6:7]
	v_lshl_add_u64 v[104:105], v[104:105], 0, v[112:113]
	v_mov_b32_dpp v106, v108 row_ror:8 row_mask:0xf bank_mask:0xf
	v_mov_b32_dpp v107, v109 row_ror:8 row_mask:0xf bank_mask:0xf
	global_store_dwordx4 v[104:105], v[96:99], off
	v_max_f32_e32 v92, 0, v92
	v_max_f32_e32 v88, 0, v88
	v_add_co_u32_e32 v96, vcc, s58, v104
	v_max_f32_e32 v93, 0, v93
	v_max_f32_e32 v89, 0, v89
	v_max_f32_e32 v84, 0, v84
	v_max_f32_e32 v85, 0, v85
	v_max_f32_e32 v86, 0, v86
	v_max_f32_e32 v82, 0, v82
	v_max_f32_e32 v87, 0, v87
	v_cndmask_b32_e64 v100, v100, v106, s[6:7]
	v_cndmask_b32_e64 v101, v101, v107, s[6:7]
	v_cndmask_b32_e64 v102, v102, v110, s[6:7]
	v_cndmask_b32_e64 v103, v103, v111, s[6:7]
	v_addc_co_u32_e32 v97, vcc, 0, v105, vcc
	v_mul_f32_e32 v92, v92, v92
	v_mul_f32_e32 v88, v88, v88
	v_mul_f32_e32 v93, v93, v93
	v_mul_f32_e32 v89, v89, v89
	v_max_f32_e32 v94, 0, v94
	v_max_f32_e32 v90, 0, v90
	v_max_f32_e32 v95, 0, v95
	v_max_f32_e32 v91, 0, v91
	v_max_f32_e32 v80, 0, v80
	v_mul_f32_e32 v84, v84, v84
	v_max_f32_e32 v81, 0, v81
	v_mul_f32_e32 v85, v85, v85
	v_mul_f32_e32 v86, v86, v86
	v_mul_f32_e32 v82, v82, v82
	v_max_f32_e32 v83, 0, v83
	v_mul_f32_e32 v87, v87, v87
	global_store_dwordx4 v[96:97], v[100:103], off
	v_mul_f32_e32 v94, v94, v94
	v_mul_f32_e32 v90, v90, v90
	v_mul_f32_e32 v95, v95, v95
	v_mul_f32_e32 v91, v91, v91
	v_cvt_pk_bf16_f32 v92, v92, v93
	v_cvt_pk_bf16_f32 v93, v94, v95
	v_cvt_pk_bf16_f32 v88, v88, v89
	v_cvt_pk_bf16_f32 v89, v90, v91
	v_mul_f32_e32 v80, v80, v80
	v_mul_f32_e32 v81, v81, v81
	v_mul_f32_e32 v83, v83, v83
	v_cvt_pk_bf16_f32 v84, v84, v85
	v_cvt_pk_bf16_f32 v85, v86, v87
	v_cvt_pk_bf16_f32 v86, v80, v81
	v_cvt_pk_bf16_f32 v87, v82, v83
	v_mov_b32_e32 v82, 0
	v_mov_b32_dpp v82, v86 row_ror:8 row_mask:0xf bank_mask:0xf
	v_mov_b32_dpp v94, v88 row_ror:8 row_mask:0xf bank_mask:0xf
	v_mov_b32_dpp v83, v87 row_ror:8 row_mask:0xf bank_mask:0xf
	v_cndmask_b32_e64 v82, v82, v88, s[6:7]
	v_add_u32_e32 v88, v150, v160
	v_mov_b32_dpp v95, v89 row_ror:8 row_mask:0xf bank_mask:0xf
	v_cndmask_b32_e64 v83, v83, v89, s[6:7]
	v_ashrrev_i32_e32 v89, 31, v88
	v_lshlrev_b64 v[88:89], 14, v[88:89]
	v_mov_b32_dpp v80, v84 row_ror:8 row_mask:0xf bank_mask:0xf
	v_mov_b32_dpp v81, v85 row_ror:8 row_mask:0xf bank_mask:0xf
	v_lshl_add_u64 v[88:89], s[12:13], 0, v[88:89]
	v_cndmask_b32_e64 v80, v80, v92, s[6:7]
	v_cndmask_b32_e64 v81, v81, v93, s[6:7]
	v_lshl_add_u64 v[88:89], v[88:89], 0, v[112:113]
	v_mov_b32_dpp v90, v92 row_ror:8 row_mask:0xf bank_mask:0xf
	v_mov_b32_dpp v91, v93 row_ror:8 row_mask:0xf bank_mask:0xf
	global_store_dwordx4 v[88:89], v[80:83], off
	v_max_f32_e32 v76, 0, v76
	v_max_f32_e32 v72, 0, v72
	v_add_co_u32_e32 v80, vcc, s58, v88
	v_max_f32_e32 v77, 0, v77
	v_max_f32_e32 v73, 0, v73
	v_max_f32_e32 v68, 0, v68
	v_max_f32_e32 v69, 0, v69
	v_max_f32_e32 v70, 0, v70
	v_max_f32_e32 v66, 0, v66
	v_max_f32_e32 v71, 0, v71
	v_cndmask_b32_e64 v84, v84, v90, s[6:7]
	v_cndmask_b32_e64 v85, v85, v91, s[6:7]
	v_cndmask_b32_e64 v86, v86, v94, s[6:7]
	v_cndmask_b32_e64 v87, v87, v95, s[6:7]
	v_addc_co_u32_e32 v81, vcc, 0, v89, vcc
	v_mul_f32_e32 v76, v76, v76
	v_mul_f32_e32 v72, v72, v72
	v_mul_f32_e32 v77, v77, v77
	v_mul_f32_e32 v73, v73, v73
	v_max_f32_e32 v78, 0, v78
	v_max_f32_e32 v74, 0, v74
	v_max_f32_e32 v79, 0, v79
	v_max_f32_e32 v75, 0, v75
	v_max_f32_e32 v64, 0, v64
	v_mul_f32_e32 v68, v68, v68
	v_max_f32_e32 v65, 0, v65
	v_mul_f32_e32 v69, v69, v69
	v_mul_f32_e32 v70, v70, v70
	v_mul_f32_e32 v66, v66, v66
	v_max_f32_e32 v67, 0, v67
	v_mul_f32_e32 v71, v71, v71
	global_store_dwordx4 v[80:81], v[84:87], off
	v_mul_f32_e32 v78, v78, v78
	v_mul_f32_e32 v74, v74, v74
	v_mul_f32_e32 v79, v79, v79
	v_mul_f32_e32 v75, v75, v75
	v_cvt_pk_bf16_f32 v76, v76, v77
; __device__ __forceinline__ unsigned cvt_pk_bf16(float lo, float hi) { unsigned r; asm volatile("v_cvt_pk_bf16_f32 %0, %1, %2" : "=v"(r) : "v"(lo), "v"(hi)); return r; }
; __device__ __forceinline__ unsigned dpp_ror8(unsigned x) { return (unsigned)__builtin_amdgcn_update_dpp(0, (int)x, 0x128, 0xf, 0xf, false); }
; __device__ __forceinline__ void store_pair_lines(bf16_t* O, int ldc, int row, int fr, int col0, u32x4 wA, u32x4 wB) {
;     const u32x4 sA = {dpp_ror8(wA.x), dpp_ror8(wA.y), dpp_ror8(wA.z), dpp_ror8(wA.w)}, sB = {dpp_ror8(wB.x), dpp_ror8(wB.y), dpp_ror8(wB.z), dpp_ror8(wB.w)};
;     const bool lo = fr < 8;
;     const u32x4 o1 = lo ? wA : sB, o2 = lo ? sA : wB;
;     const int r1 = row - fr + (fr & 7), cb = col0 + (lo ? 0 : 8);
;     *(u32x4*)(O + (size_t)r1 * ldc + cb) = o1;
;     *(u32x4*)(O + (size_t)(r1 + 8) * ldc + cb) = o2;
; }
;     __device__ __forceinline__ void operator()(const f32x4 (&acc)[2][2][4][2], const Unit& u, int wr, int wc, int fr, int fq) const {
;     ...
;             for (int m = 0; m < 4; ++m) { const int row = row0 + ai * HALF + m * 16;
;                 const float rs = ssin ? __builtin_amdgcn_rsqf(ssin[row] * (1.f / D) + EPS) : 1.0f; float sq = 0.f; u32x4 w[2];
; #pragma unroll
;                 for (int bj = 0; bj < 2; ++bj) { f32x4 v0 = acc[ai][bj][m][0] * rs, v1 = acc[ai][bj][m][1] * rs;
;                     if (ACT == 1) {
; #pragma unroll
;                         for (int j = 0; j < 4; ++j) { const float a = fmaxf(v0[j], 0.f), b = fmaxf(v1[j], 0.f); v0[j] = a * a; v1[j] = b * b; } }
;                     sq += (v0[0] * v0[0] + v0[1] * v0[1]) + (v0[2] * v0[2] + v0[3] * v0[3]) + (v1[0] * v1[0] + v1[1] * v1[1]) + (v1[2] * v1[2] + v1[3] * v1[3]);
;                     w[bj].x = cvt_pk_bf16(v0[0], v0[1]); w[bj].y = cvt_pk_bf16(v0[2], v0[3]); w[bj].z = cvt_pk_bf16(v1[0], v1[1]); w[bj].w = cvt_pk_bf16(v1[2], v1[3]); }
;                 store_pair_lines(O, ldc, row, fr, col0, w[0], w[1]);
	v_cvt_pk_bf16_f32 v77, v78, v79
	v_cvt_pk_bf16_f32 v72, v72, v73
	v_cvt_pk_bf16_f32 v73, v74, v75
	v_mul_f32_e32 v64, v64, v64
	v_mul_f32_e32 v65, v65, v65
	v_mul_f32_e32 v67, v67, v67
	v_cvt_pk_bf16_f32 v68, v68, v69
	v_cvt_pk_bf16_f32 v69, v70, v71
	v_cvt_pk_bf16_f32 v70, v64, v65
	v_cvt_pk_bf16_f32 v71, v66, v67
	v_mov_b32_e32 v66, 0
	v_mov_b32_dpp v66, v70 row_ror:8 row_mask:0xf bank_mask:0xf
	v_mov_b32_dpp v78, v72 row_ror:8 row_mask:0xf bank_mask:0xf
	v_mov_b32_dpp v67, v71 row_ror:8 row_mask:0xf bank_mask:0xf
	v_cndmask_b32_e64 v66, v66, v72, s[6:7]
	v_add_u32_e32 v72, v151, v160
	v_mov_b32_dpp v79, v73 row_ror:8 row_mask:0xf bank_mask:0xf
	v_cndmask_b32_e64 v67, v67, v73, s[6:7]
	v_ashrrev_i32_e32 v73, 31, v72
	v_lshlrev_b64 v[72:73], 14, v[72:73]
	v_mov_b32_dpp v64, v68 row_ror:8 row_mask:0xf bank_mask:0xf
	v_mov_b32_dpp v65, v69 row_ror:8 row_mask:0xf bank_mask:0xf
	v_lshl_add_u64 v[72:73], s[12:13], 0, v[72:73]
	v_cndmask_b32_e64 v64, v64, v76, s[6:7]
	v_cndmask_b32_e64 v65, v65, v77, s[6:7]
	v_lshl_add_u64 v[72:73], v[72:73], 0, v[112:113]
	v_mov_b32_dpp v74, v76 row_ror:8 row_mask:0xf bank_mask:0xf
	v_mov_b32_dpp v75, v77 row_ror:8 row_mask:0xf bank_mask:0xf
	global_store_dwordx4 v[72:73], v[64:67], off
	v_max_f32_e32 v60, 0, v60
	v_max_f32_e32 v56, 0, v56
	v_add_co_u32_e32 v64, vcc, s58, v72
	v_max_f32_e32 v61, 0, v61
	v_max_f32_e32 v57, 0, v57
	v_max_f32_e32 v52, 0, v52
	v_max_f32_e32 v53, 0, v53
	v_max_f32_e32 v54, 0, v54
	v_max_f32_e32 v50, 0, v50
	v_max_f32_e32 v55, 0, v55
	v_cndmask_b32_e64 v68, v68, v74, s[6:7]
	v_cndmask_b32_e64 v69, v69, v75, s[6:7]
	v_cndmask_b32_e64 v70, v70, v78, s[6:7]
	v_cndmask_b32_e64 v71, v71, v79, s[6:7]
	v_addc_co_u32_e32 v65, vcc, 0, v73, vcc
	v_mul_f32_e32 v60, v60, v60
	v_mul_f32_e32 v56, v56, v56
	v_mul_f32_e32 v61, v61, v61
	v_mul_f32_e32 v57, v57, v57
	v_max_f32_e32 v62, 0, v62
	v_max_f32_e32 v58, 0, v58
	v_max_f32_e32 v63, 0, v63
	v_max_f32_e32 v59, 0, v59
	v_max_f32_e32 v48, 0, v48
	v_mul_f32_e32 v52, v52, v52
	v_max_f32_e32 v49, 0, v49
	v_mul_f32_e32 v53, v53, v53
	v_mul_f32_e32 v54, v54, v54
	v_mul_f32_e32 v50, v50, v50
	v_max_f32_e32 v51, 0, v51
	v_mul_f32_e32 v55, v55, v55
	global_store_dwordx4 v[64:65], v[68:71], off
	v_mul_f32_e32 v62, v62, v62
	v_mul_f32_e32 v58, v58, v58
	v_mul_f32_e32 v63, v63, v63
	v_mul_f32_e32 v59, v59, v59
	v_cvt_pk_bf16_f32 v60, v60, v61
	v_cvt_pk_bf16_f32 v61, v62, v63
	v_cvt_pk_bf16_f32 v56, v56, v57
	v_cvt_pk_bf16_f32 v57, v58, v59
	v_mul_f32_e32 v48, v48, v48
	v_mul_f32_e32 v49, v49, v49
	v_mul_f32_e32 v51, v51, v51
	v_cvt_pk_bf16_f32 v52, v52, v53
	v_cvt_pk_bf16_f32 v53, v54, v55
	v_cvt_pk_bf16_f32 v54, v48, v49
	v_cvt_pk_bf16_f32 v55, v50, v51
	v_mov_b32_e32 v50, 0
	v_mov_b32_dpp v50, v54 row_ror:8 row_mask:0xf bank_mask:0xf
	v_mov_b32_dpp v62, v56 row_ror:8 row_mask:0xf bank_mask:0xf
	v_mov_b32_dpp v51, v55 row_ror:8 row_mask:0xf bank_mask:0xf
	v_cndmask_b32_e64 v50, v50, v56, s[6:7]
	v_add_u32_e32 v56, v152, v160
	v_mov_b32_dpp v63, v57 row_ror:8 row_mask:0xf bank_mask:0xf
	v_cndmask_b32_e64 v51, v51, v57, s[6:7]
	v_ashrrev_i32_e32 v57, 31, v56
	v_lshlrev_b64 v[56:57], 14, v[56:57]
	v_mov_b32_dpp v48, v52 row_ror:8 row_mask:0xf bank_mask:0xf
	v_mov_b32_dpp v49, v53 row_ror:8 row_mask:0xf bank_mask:0xf
	v_lshl_add_u64 v[56:57], s[12:13], 0, v[56:57]
	v_cndmask_b32_e64 v48, v48, v60, s[6:7]
	v_cndmask_b32_e64 v49, v49, v61, s[6:7]
	v_lshl_add_u64 v[56:57], v[56:57], 0, v[112:113]
	v_mov_b32_dpp v58, v60 row_ror:8 row_mask:0xf bank_mask:0xf
	v_mov_b32_dpp v59, v61 row_ror:8 row_mask:0xf bank_mask:0xf
	global_store_dwordx4 v[56:57], v[48:51], off
	v_max_f32_e32 v44, 0, v44
	v_max_f32_e32 v40, 0, v40
	v_add_co_u32_e32 v48, vcc, s58, v56
	v_max_f32_e32 v45, 0, v45
	v_max_f32_e32 v41, 0, v41
	v_max_f32_e32 v36, 0, v36
	v_max_f32_e32 v37, 0, v37
	v_max_f32_e32 v38, 0, v38
	v_max_f32_e32 v34, 0, v34
	v_max_f32_e32 v39, 0, v39
	v_cndmask_b32_e64 v52, v52, v58, s[6:7]
	v_cndmask_b32_e64 v53, v53, v59, s[6:7]
	v_cndmask_b32_e64 v54, v54, v62, s[6:7]
	v_cndmask_b32_e64 v55, v55, v63, s[6:7]
	v_addc_co_u32_e32 v49, vcc, 0, v57, vcc
	v_mul_f32_e32 v44, v44, v44
	v_mul_f32_e32 v40, v40, v40
	v_mul_f32_e32 v45, v45, v45
	v_mul_f32_e32 v41, v41, v41
	v_max_f32_e32 v46, 0, v46
	v_max_f32_e32 v42, 0, v42
	v_max_f32_e32 v47, 0, v47
	v_max_f32_e32 v43, 0, v43
	v_max_f32_e32 v32, 0, v32
	v_mul_f32_e32 v36, v36, v36
	v_max_f32_e32 v33, 0, v33
	v_mul_f32_e32 v37, v37, v37
	v_mul_f32_e32 v38, v38, v38
	v_mul_f32_e32 v34, v34, v34
	v_max_f32_e32 v35, 0, v35
	v_mul_f32_e32 v39, v39, v39
	global_store_dwordx4 v[48:49], v[52:55], off
	v_mul_f32_e32 v46, v46, v46
	v_mul_f32_e32 v42, v42, v42
	v_mul_f32_e32 v47, v47, v47
	v_mul_f32_e32 v43, v43, v43
	v_cvt_pk_bf16_f32 v44, v44, v45
	v_cvt_pk_bf16_f32 v45, v46, v47
	v_cvt_pk_bf16_f32 v40, v40, v41
	v_cvt_pk_bf16_f32 v41, v42, v43
	v_mul_f32_e32 v32, v32, v32
	v_mul_f32_e32 v33, v33, v33
	v_mul_f32_e32 v35, v35, v35
	v_cvt_pk_bf16_f32 v36, v36, v37
	v_cvt_pk_bf16_f32 v37, v38, v39
	v_cvt_pk_bf16_f32 v38, v32, v33
	v_cvt_pk_bf16_f32 v39, v34, v35
	v_mov_b32_e32 v34, 0
	v_mov_b32_dpp v34, v38 row_ror:8 row_mask:0xf bank_mask:0xf
	v_mov_b32_dpp v46, v40 row_ror:8 row_mask:0xf bank_mask:0xf
	v_mov_b32_dpp v35, v39 row_ror:8 row_mask:0xf bank_mask:0xf
	v_cndmask_b32_e64 v34, v34, v40, s[6:7]
	v_add_u32_e32 v40, v153, v160
	v_mov_b32_dpp v47, v41 row_ror:8 row_mask:0xf bank_mask:0xf
	v_cndmask_b32_e64 v35, v35, v41, s[6:7]
	v_ashrrev_i32_e32 v41, 31, v40
	v_lshlrev_b64 v[40:41], 14, v[40:41]
	v_mov_b32_dpp v32, v36 row_ror:8 row_mask:0xf bank_mask:0xf
; __device__ __forceinline__ unsigned cvt_pk_bf16(float lo, float hi) { unsigned r; asm volatile("v_cvt_pk_bf16_f32 %0, %1, %2" : "=v"(r) : "v"(lo), "v"(hi)); return r; }
; __device__ __forceinline__ unsigned dpp_ror8(unsigned x) { return (unsigned)__builtin_amdgcn_update_dpp(0, (int)x, 0x128, 0xf, 0xf, false); }
; __device__ __forceinline__ void store_pair_lines(bf16_t* O, int ldc, int row, int fr, int col0, u32x4 wA, u32x4 wB) {
;     const u32x4 sA = {dpp_ror8(wA.x), dpp_ror8(wA.y), dpp_ror8(wA.z), dpp_ror8(wA.w)}, sB = {dpp_ror8(wB.x), dpp_ror8(wB.y), dpp_ror8(wB.z), dpp_ror8(wB.w)};
;     const bool lo = fr < 8;
;     const u32x4 o1 = lo ? wA : sB, o2 = lo ? sA : wB;
;     const int r1 = row - fr + (fr & 7), cb = col0 + (lo ? 0 : 8);
;     *(u32x4*)(O + (size_t)r1 * ldc + cb) = o1;
;     *(u32x4*)(O + (size_t)(r1 + 8) * ldc + cb) = o2;
; }
;     __device__ __forceinline__ void operator()(const f32x4 (&acc)[2][2][4][2], const Unit& u, int wr, int wc, int fr, int fq) const {
;     ...
;             for (int m = 0; m < 4; ++m) { const int row = row0 + ai * HALF + m * 16;
;                 const float rs = ssin ? __builtin_amdgcn_rsqf(ssin[row] * (1.f / D) + EPS) : 1.0f; float sq = 0.f; u32x4 w[2];
; #pragma unroll
;                 for (int bj = 0; bj < 2; ++bj) { f32x4 v0 = acc[ai][bj][m][0] * rs, v1 = acc[ai][bj][m][1] * rs;
;                     if (ACT == 1) {
; #pragma unroll
;                         for (int j = 0; j < 4; ++j) { const float a = fmaxf(v0[j], 0.f), b = fmaxf(v1[j], 0.f); v0[j] = a * a; v1[j] = b * b; } }
;                     sq += (v0[0] * v0[0] + v0[1] * v0[1]) + (v0[2] * v0[2] + v0[3] * v0[3]) + (v1[0] * v1[0] + v1[1] * v1[1]) + (v1[2] * v1[2] + v1[3] * v1[3]);
;                     w[bj].x = cvt_pk_bf16(v0[0], v0[1]); w[bj].y = cvt_pk_bf16(v0[2], v0[3]); w[bj].z = cvt_pk_bf16(v1[0], v1[1]); w[bj].w = cvt_pk_bf16(v1[2], v1[3]); }
;                 store_pair_lines(O, ldc, row, fr, col0, w[0], w[1]);
	v_mov_b32_dpp v33, v37 row_ror:8 row_mask:0xf bank_mask:0xf
	v_lshl_add_u64 v[40:41], s[12:13], 0, v[40:41]
	v_cndmask_b32_e64 v32, v32, v44, s[6:7]
	v_cndmask_b32_e64 v33, v33, v45, s[6:7]
	v_lshl_add_u64 v[40:41], v[40:41], 0, v[112:113]
	v_mov_b32_dpp v42, v44 row_ror:8 row_mask:0xf bank_mask:0xf
	v_mov_b32_dpp v43, v45 row_ror:8 row_mask:0xf bank_mask:0xf
	global_store_dwordx4 v[40:41], v[32:35], off
	v_max_f32_e32 v28, 0, v28
	v_max_f32_e32 v24, 0, v24
	v_add_co_u32_e32 v32, vcc, s58, v40
	v_max_f32_e32 v29, 0, v29
	v_max_f32_e32 v25, 0, v25
	v_max_f32_e32 v20, 0, v20
	v_max_f32_e32 v21, 0, v21
	v_max_f32_e32 v22, 0, v22
	v_max_f32_e32 v18, 0, v18
	v_max_f32_e32 v23, 0, v23
	v_cndmask_b32_e64 v36, v36, v42, s[6:7]
	v_cndmask_b32_e64 v37, v37, v43, s[6:7]
	v_cndmask_b32_e64 v38, v38, v46, s[6:7]
	v_cndmask_b32_e64 v39, v39, v47, s[6:7]
	v_addc_co_u32_e32 v33, vcc, 0, v41, vcc
	v_mul_f32_e32 v28, v28, v28
	v_mul_f32_e32 v24, v24, v24
	v_mul_f32_e32 v29, v29, v29
	v_mul_f32_e32 v25, v25, v25
	v_max_f32_e32 v30, 0, v30
	v_max_f32_e32 v26, 0, v26
	v_max_f32_e32 v31, 0, v31
	v_max_f32_e32 v27, 0, v27
	v_max_f32_e32 v16, 0, v16
	v_mul_f32_e32 v20, v20, v20
	v_max_f32_e32 v17, 0, v17
	v_mul_f32_e32 v21, v21, v21
	v_mul_f32_e32 v22, v22, v22
	v_mul_f32_e32 v18, v18, v18
	v_max_f32_e32 v19, 0, v19
	v_mul_f32_e32 v23, v23, v23
	global_store_dwordx4 v[32:33], v[36:39], off
	v_mul_f32_e32 v30, v30, v30
	v_mul_f32_e32 v26, v26, v26
	v_mul_f32_e32 v31, v31, v31
	v_mul_f32_e32 v27, v27, v27
	v_cvt_pk_bf16_f32 v28, v28, v29
	v_cvt_pk_bf16_f32 v29, v30, v31
	v_cvt_pk_bf16_f32 v24, v24, v25
	v_cvt_pk_bf16_f32 v25, v26, v27
	v_mul_f32_e32 v16, v16, v16
	v_mul_f32_e32 v17, v17, v17
	v_mul_f32_e32 v19, v19, v19
	v_cvt_pk_bf16_f32 v20, v20, v21
	v_cvt_pk_bf16_f32 v21, v22, v23
	v_cvt_pk_bf16_f32 v22, v16, v17
	v_cvt_pk_bf16_f32 v23, v18, v19
	v_mov_b32_e32 v18, 0
	v_mov_b32_dpp v18, v22 row_ror:8 row_mask:0xf bank_mask:0xf
	v_mov_b32_dpp v30, v24 row_ror:8 row_mask:0xf bank_mask:0xf
	v_mov_b32_dpp v19, v23 row_ror:8 row_mask:0xf bank_mask:0xf
	v_cndmask_b32_e64 v18, v18, v24, s[6:7]
	v_add_u32_e32 v24, v154, v160
	v_mov_b32_dpp v31, v25 row_ror:8 row_mask:0xf bank_mask:0xf
	v_cndmask_b32_e64 v19, v19, v25, s[6:7]
	v_ashrrev_i32_e32 v25, 31, v24
	v_lshlrev_b64 v[24:25], 14, v[24:25]
	v_mov_b32_dpp v16, v20 row_ror:8 row_mask:0xf bank_mask:0xf
	v_mov_b32_dpp v17, v21 row_ror:8 row_mask:0xf bank_mask:0xf
	v_lshl_add_u64 v[24:25], s[12:13], 0, v[24:25]
	v_cndmask_b32_e64 v16, v16, v28, s[6:7]
	v_cndmask_b32_e64 v17, v17, v29, s[6:7]
	v_lshl_add_u64 v[24:25], v[24:25], 0, v[112:113]
	v_mov_b32_dpp v26, v28 row_ror:8 row_mask:0xf bank_mask:0xf
	v_mov_b32_dpp v27, v29 row_ror:8 row_mask:0xf bank_mask:0xf
	global_store_dwordx4 v[24:25], v[16:19], off
	v_max_f32_e32 v12, 0, v12
	v_max_f32_e32 v8, 0, v8
	v_add_co_u32_e32 v16, vcc, s58, v24
	v_max_f32_e32 v13, 0, v13
	v_max_f32_e32 v9, 0, v9
	v_max_f32_e32 v4, 0, v4
	v_max_f32_e32 v5, 0, v5
	v_max_f32_e32 v6, 0, v6
	v_max_f32_e32 v2, 0, v2
	v_max_f32_e32 v7, 0, v7
	v_cndmask_b32_e64 v20, v20, v26, s[6:7]
	v_cndmask_b32_e64 v21, v21, v27, s[6:7]
	v_cndmask_b32_e64 v22, v22, v30, s[6:7]
	v_cndmask_b32_e64 v23, v23, v31, s[6:7]
	v_addc_co_u32_e32 v17, vcc, 0, v25, vcc
	v_mul_f32_e32 v12, v12, v12
	v_mul_f32_e32 v8, v8, v8
	v_mul_f32_e32 v13, v13, v13
	v_mul_f32_e32 v9, v9, v9
	v_max_f32_e32 v14, 0, v14
	v_max_f32_e32 v10, 0, v10
	v_max_f32_e32 v15, 0, v15
	v_max_f32_e32 v11, 0, v11
	v_max_f32_e32 v0, 0, v0
	v_mul_f32_e32 v4, v4, v4
	v_max_f32_e32 v1, 0, v1
	v_mul_f32_e32 v5, v5, v5
	v_mul_f32_e32 v6, v6, v6
	v_mul_f32_e32 v2, v2, v2
	v_max_f32_e32 v3, 0, v3
	v_mul_f32_e32 v7, v7, v7
	global_store_dwordx4 v[16:17], v[20:23], off
	v_mul_f32_e32 v14, v14, v14
	v_mul_f32_e32 v10, v10, v10
	v_mul_f32_e32 v15, v15, v15
	v_mul_f32_e32 v11, v11, v11
	v_cvt_pk_bf16_f32 v12, v12, v13
	v_cvt_pk_bf16_f32 v13, v14, v15
	v_cvt_pk_bf16_f32 v8, v8, v9
	v_cvt_pk_bf16_f32 v9, v10, v11
	v_mul_f32_e32 v0, v0, v0
	v_mul_f32_e32 v1, v1, v1
	v_mul_f32_e32 v3, v3, v3
	v_cvt_pk_bf16_f32 v4, v4, v5
	v_cvt_pk_bf16_f32 v5, v6, v7
	v_cvt_pk_bf16_f32 v6, v0, v1
	v_cvt_pk_bf16_f32 v7, v2, v3
	v_mov_b32_e32 v2, 0
	v_mov_b32_dpp v2, v6 row_ror:8 row_mask:0xf bank_mask:0xf
	v_mov_b32_dpp v14, v8 row_ror:8 row_mask:0xf bank_mask:0xf
	v_mov_b32_dpp v3, v7 row_ror:8 row_mask:0xf bank_mask:0xf
	v_cndmask_b32_e64 v2, v2, v8, s[6:7]
	v_add_u32_e32 v8, v155, v160
	v_mov_b32_dpp v15, v9 row_ror:8 row_mask:0xf bank_mask:0xf
	v_cndmask_b32_e64 v3, v3, v9, s[6:7]
	v_ashrrev_i32_e32 v9, 31, v8
	v_lshlrev_b64 v[8:9], 14, v[8:9]
	v_mov_b32_dpp v0, v4 row_ror:8 row_mask:0xf bank_mask:0xf
	v_mov_b32_dpp v1, v5 row_ror:8 row_mask:0xf bank_mask:0xf
	v_lshl_add_u64 v[8:9], s[12:13], 0, v[8:9]
	v_cndmask_b32_e64 v0, v0, v12, s[6:7]
	v_cndmask_b32_e64 v1, v1, v13, s[6:7]
	v_lshl_add_u64 v[8:9], v[8:9], 0, v[112:113]
	global_store_dwordx4 v[8:9], v[0:3], off
	v_mov_b32_dpp v10, v12 row_ror:8 row_mask:0xf bank_mask:0xf
	v_mov_b32_dpp v11, v13 row_ror:8 row_mask:0xf bank_mask:0xf
	v_add_co_u32_e32 v0, vcc, 0x20000, v8
	v_cndmask_b32_e64 v4, v4, v10, s[6:7]
	s_nop 0
	v_addc_co_u32_e32 v1, vcc, 0, v9, vcc
	v_cndmask_b32_e64 v5, v5, v11, s[6:7]
	v_cndmask_b32_e64 v6, v6, v14, s[6:7]
	v_cndmask_b32_e64 v7, v7, v15, s[6:7]
	s_and_b64 vcc, exec, s[30:31]
	s_mov_b32 s59, s18
	s_mov_b32 s36, s26
	s_mov_b64 s[40:41], s[34:35]
	s_mov_b64 s[38:39], s[28:29]
	global_store_dwordx4 v[0:1], v[4:7], off
	s_cbranch_vccz .LBB0_1357
	s_waitcnt vmcnt(0)
	s_cmpk_gt_u32 s44, 0xff
	s_cbranch_scc1 .LBB0_1369
	s_barrier

; __device__ __forceinline__ unsigned cvt_pk_bf16(float lo, float hi) { unsigned r; asm volatile("v_cvt_pk_bf16_f32 %0, %1, %2" : "=v"(r) : "v"(lo), "v"(hi)); return r; }
; __device__ __forceinline__ float bflo(unsigned w) { return __uint_as_float(w << 16); }
; __device__ __forceinline__ float bfhi(unsigned w) { return __uint_as_float(w & 0xffff0000u); }
; __device__ __forceinline__ void store_pair_lines(bf16_t* O, int ldc, int row, int fr, int col0, u32x4 wA, u32x4 wB) {
;     const u32x4 sA = {dpp_ror8(wA.x), dpp_ror8(wA.y), dpp_ror8(wA.z), dpp_ror8(wA.w)}, sB = {dpp_ror8(wB.x), dpp_ror8(wB.y), dpp_ror8(wB.z), dpp_ror8(wB.w)};
;     const bool lo = fr < 8;
;     const u32x4 o1 = lo ? wA : sB, o2 = lo ? sA : wB;
;     const int r1 = row - fr + (fr & 7), cb = col0 + (lo ? 0 : 8);
;     *(u32x4*)(O + (size_t)r1 * ldc + cb) = o1;
;     *(u32x4*)(O + (size_t)(r1 + 8) * ldc + cb) = o2;
; }
;     __device__ __forceinline__ void operator()(const f32x4 (&acc)[2][2][4][2], const Unit& u, int wr, int wc, int fr, int fq) const {
;     ...
;             for (int m = 0; m < 4; ++m) { const int row = row0 + ai * HALF + m * 16; const size_t off = (size_t)row * D + col0; float sq = 0.f; u32x4 w[2];
;                 const float sc = rsin ? __builtin_amdgcn_rcpf(rsin[row] * (1.f / D) + EPS) : 1.0f;
;                 u32x4 rr[2]; if (R) load_pair_lines(R, D, row, fr, col0, rr[0], rr[1]);
; #pragma unroll
;                 for (int bj = 0; bj < 2; ++bj) { f32x4 r0, r1;
;                     if (R) { const u32x4 rw = rr[bj]; r0 = (f32x4){bflo(rw.x), bfhi(rw.x), bflo(rw.y), bfhi(rw.y)}; r1 = (f32x4){bflo(rw.z), bfhi(rw.z), bflo(rw.w), bfhi(rw.w)}; }
;                     else { const float* rp = (row < 8192 ? src_p + off : src_s + (off - (size_t)8192 * D)) + 8 * bj; r0 = *(const f32x4*)rp; r1 = *(const f32x4*)(rp + 4); }
;                     const f32x4 o0 = r0 + acc[ai][bj][m][0] * sc, o1 = r1 + acc[ai][bj][m][1] * sc;
;                     sq += (o0[0] * o0[0] + o0[1] * o0[1]) + (o0[2] * o0[2] + o0[3] * o0[3]) + (o1[0] * o1[0] + o1[1] * o1[1]) + (o1[2] * o1[2] + o1[3] * o1[3]);
;                     w[bj].x = cvt_pk_bf16(o0[0], o0[1]); w[bj].y = cvt_pk_bf16(o0[2], o0[3]); w[bj].z = cvt_pk_bf16(o1[0], o1[1]); w[bj].w = cvt_pk_bf16(o1[2], o1[3]); }
;                 store_pair_lines(O, D, row, fr, col0, w[0], w[1]);
.LBB0_1433:
	v_mov_b32_e32 v27, v26
	v_mov_b32_e32 v20, v26
	v_mov_b32_e32 v21, v26
	s_waitcnt vmcnt(0) lgkmcnt(0)
	v_pk_fma_f32 v[6:7], v[6:7], v[20:21], v[10:11]
	v_pk_fma_f32 v[4:5], v[4:5], v[26:27], v[8:9]
	v_pk_fma_f32 v[0:1], v[0:1], v[26:27], v[12:13]
	v_pk_fma_f32 v[2:3], v[2:3], v[20:21], v[14:15]
	v_cvt_pk_bf16_f32 v4, v4, v5
	v_cvt_pk_bf16_f32 v5, v6, v7
	v_cvt_pk_bf16_f32 v6, v0, v1
	v_mov_b32_dpp v8, v16 row_ror:8 row_mask:0xf bank_mask:0xf
	v_mov_b32_dpp v9, v18 row_ror:8 row_mask:0xf bank_mask:0xf
	v_ashrrev_i32_e32 v25, 31, v24
	v_cvt_pk_bf16_f32 v7, v2, v3
	v_mov_b32_dpp v0, v4 row_ror:8 row_mask:0xf bank_mask:0xf
	v_mov_b32_dpp v1, v5 row_ror:8 row_mask:0xf bank_mask:0xf
	v_cndmask_b32_e64 v5, v5, v9, s[6:7]
	v_cndmask_b32_e64 v4, v4, v8, s[6:7]
	v_lshlrev_b64 v[8:9], 12, v[24:25]
	v_mov_b32_dpp v2, v6 row_ror:8 row_mask:0xf bank_mask:0xf
	v_mov_b32_dpp v3, v7 row_ror:8 row_mask:0xf bank_mask:0xf
	v_lshl_add_u64 v[8:9], s[12:13], 0, v[8:9]
	v_cndmask_b32_e64 v1, v1, v18, s[6:7]
	v_cndmask_b32_e64 v3, v3, v19, s[6:7]
	v_cndmask_b32_e64 v0, v0, v16, s[6:7]
	v_cndmask_b32_e64 v2, v2, v17, s[6:7]
	v_lshl_add_u64 v[8:9], v[154:155], 1, v[8:9]
	global_store_dwordx4 v[8:9], v[0:3], off
	v_mov_b32_dpp v10, v17 row_ror:8 row_mask:0xf bank_mask:0xf
	v_mov_b32_dpp v11, v19 row_ror:8 row_mask:0xf bank_mask:0xf
	v_add_co_u32_e32 v0, vcc, 0x8000, v8
	v_cndmask_b32_e64 v7, v7, v11, s[6:7]
	s_nop 0
	v_addc_co_u32_e32 v1, vcc, 0, v9, vcc
	v_cndmask_b32_e64 v6, v6, v10, s[6:7]
	s_and_b64 vcc, exec, s[38:39]
	s_mov_b32 s8, s30
	s_mov_b32 s10, s34
	s_mov_b64 s[44:45], s[40:41]
	s_mov_b64 s[42:43], s[36:37]
	global_store_dwordx4 v[0:1], v[4:7], off
	s_cbranch_vccnz .LBB0_1531

; #define PG8_STAGE(bufoff, gbase, voff) do { _Pragma("unroll") for (int _i = 0; _i < 2; ++_i) \
;         __builtin_amdgcn_global_load_lds((const unsigned*)((const char*)(gbase) + (voff)[_i]), (LAS unsigned*)(lds + (bufoff) + ldsw + _i * 8192), 16, 0, 0); } while (0)
; #define PG8_LDA(dst, b, h) do { _Pragma("unroll") for (int m = 0; m < 4; ++m) _Pragma("unroll") for (int k = 0; k < 2; ++k) dst[m][k] = *(const LAS bf16x8*)(lds + PG8_SA(b, h) + aoff + m * 2048 + k * 1024); } while (0)
; #define PG8_LDB(dst, b, h) do { _Pragma("unroll") for (int n = 0; n < 2; ++n) _Pragma("unroll") for (int k = 0; k < 2; ++k) dst[n][k] = *(const LAS bf16x8*)(lds + PG8_SB(b, h) + boff + n * 2048 + k * 1024); } while (0)
; #define PG8_WAIT_V(n) asm volatile("s_waitcnt vmcnt(" #n ")" ::: "memory")
; #define PG8_WAIT_L(n) asm volatile("s_waitcnt lgkmcnt(" #n ")" ::: "memory")
; #define PG8_BAR __builtin_amdgcn_s_barrier()
; #define PG8_SCHED __builtin_amdgcn_sched_barrier(0)
; template <class Epi>
; __device__ __forceinline__ void gemm_phase(LAS unsigned char* lds, const Gemm g, const StaticOrder& S, const Epi& E) {
;     ...
;             PG8_LDB(B0, 0, 0); PG8_SCHED; PG8_LDA(At, 0, 0); PG8_STAGE(PG8_SA(1, 1), a1 + hstep, voffA);
;             PG8_WAIT_L(8); PG8_BAR; PG8_WAIT_L(0); PG8_MMA(0, 0, At, B0); PG8_BAR; PG8_SCHED;
;             PG8_LDB(B1, 0, 1); PG8_STAGE(PG8_SB(0, 0), b2, voffB0);
;             PG8_BAR; PG8_WAIT_L(0); PG8_MMA(0, 1, At, B1); PG8_BAR;
;             PG8_LDA(At, 0, 1); PG8_STAGE(PG8_SA(0, 0), a2, voffA);
;             PG8_BAR; PG8_WAIT_L(0); PG8_MMA(1, 0, At, B0); PG8_BAR; PG8_SCHED;
;             PG8_STAGE(PG8_SB(0, 1), b2, voffB1);
;             PG8_WAIT_V(6); PG8_BAR; PG8_MMA(1, 1, At, B1); PG8_BAR;
;             PG8_LDB(B0, 1, 0); PG8_SCHED; PG8_LDA(At, 1, 0); PG8_STAGE(PG8_SA(0, 1), a2 + hstep, voffA);
;             PG8_WAIT_L(8); PG8_BAR; PG8_WAIT_L(0); PG8_MMA(0, 0, At, B0); PG8_BAR; PG8_SCHED;
;             PG8_LDB(B1, 1, 1); PG8_STAGE(PG8_SB(1, 0), b3, voffB0);
;             PG8_BAR; PG8_WAIT_L(0); PG8_MMA(0, 1, At, B1); PG8_BAR;
;             PG8_LDA(At, 1, 1); PG8_STAGE(PG8_SA(1, 0), a3, voffA);
;             PG8_BAR; PG8_WAIT_L(0); PG8_MMA(1, 0, At, B0); PG8_BAR; PG8_SCHED;
;             PG8_STAGE(PG8_SB(1, 1), b3, voffB1);
;             PG8_WAIT_V(6); PG8_BAR; PG8_MMA(1, 1, At, B1); PG8_BAR;
.LBB0_1443:
	ds_read_b128 v[128:131], v179
	ds_read_b128 v[132:135], v179 offset:1024
	ds_read_b128 v[154:157], v179 offset:2048
	ds_read_b128 v[158:161], v179 offset:3072
	s_add_u32 s33, s42, 0xffe00080
	s_addc_u32 s44, s43, -1
	s_cmpk_eq_i32 s74, 0x7c
	s_cselect_b32 s45, s9, s44
	s_cselect_b32 s44, s11, s33
	s_cselect_b32 s47, s31, s73
	s_cselect_b32 s46, s35, s72
	v_lshl_add_u64 v[200:201], s[42:43], 0, v[148:149]
	s_add_i32 m0, s54, 0xc000
	ds_read_b128 v[162:165], v180
	ds_read_b128 v[166:169], v180 offset:1024
	ds_read_b128 v[170:173], v180 offset:2048
	ds_read_b128 v[184:187], v180 offset:3072
	ds_read_b128 v[188:191], v180 offset:4096
	ds_read_b128 v[192:195], v180 offset:5120
	ds_read_b128 v[196:199], v180 offset:6144
	ds_read_b128 v[204:207], v180 offset:7168
	global_load_lds_dwordx4 v[200:201], off
	v_lshl_add_u64 v[200:201], s[42:43], 0, v[150:151]
	s_add_i32 m0, s54, 0xe000
	s_nop 0
	global_load_lds_dwordx4 v[200:201], off
	s_waitcnt lgkmcnt(8)
	s_barrier
	s_waitcnt lgkmcnt(0)
	v_mfma_f32_16x16x32_bf16 v[124:127], v[128:131], v[162:165], v[124:127]
	v_mfma_f32_16x16x32_bf16 v[120:123], v[154:157], v[162:165], v[120:123]
	v_mfma_f32_16x16x32_bf16 v[108:111], v[128:131], v[170:173], v[108:111]
	v_mfma_f32_16x16x32_bf16 v[104:107], v[154:157], v[170:173], v[104:107]
	v_mfma_f32_16x16x32_bf16 v[92:95], v[128:131], v[188:191], v[92:95]
	v_mfma_f32_16x16x32_bf16 v[88:91], v[154:157], v[188:191], v[88:91]
	v_mfma_f32_16x16x32_bf16 v[76:79], v[128:131], v[196:199], v[76:79]
	v_mfma_f32_16x16x32_bf16 v[72:75], v[154:157], v[196:199], v[72:75]
	v_mfma_f32_16x16x32_bf16 v[124:127], v[132:135], v[166:169], v[124:127]
	v_mfma_f32_16x16x32_bf16 v[120:123], v[158:161], v[166:169], v[120:123]
	v_mfma_f32_16x16x32_bf16 v[108:111], v[132:135], v[184:187], v[108:111]
	v_mfma_f32_16x16x32_bf16 v[104:107], v[158:161], v[184:187], v[104:107]
	v_mfma_f32_16x16x32_bf16 v[92:95], v[132:135], v[192:195], v[92:95]
	v_mfma_f32_16x16x32_bf16 v[88:91], v[158:161], v[192:195], v[88:91]
	v_mfma_f32_16x16x32_bf16 v[76:79], v[132:135], v[204:207], v[76:79]
	v_mfma_f32_16x16x32_bf16 v[72:75], v[158:161], v[204:207], v[72:75]
	s_barrier
	s_add_i32 s33, s66, s53
	v_lshl_add_u64 v[200:201], s[46:47], 0, v[138:139]
	s_mov_b32 m0, s33
	ds_read_b128 v[208:211], v181
	ds_read_b128 v[212:215], v181 offset:1024
	ds_read_b128 v[216:219], v181 offset:2048
	ds_read_b128 v[220:223], v181 offset:3072
	global_load_lds_dwordx4 v[200:201], off
	v_lshl_add_u64 v[224:225], s[46:47], 0, v[144:145]
	s_add_i32 m0, s33, 0x2000
	s_nop 0
	global_load_lds_dwordx4 v[224:225], off
	s_barrier
	s_waitcnt lgkmcnt(0)
	v_mfma_f32_16x16x32_bf16 v[116:119], v[208:211], v[162:165], v[116:119]
	v_mfma_f32_16x16x32_bf16 v[112:115], v[216:219], v[162:165], v[112:115]
	v_mfma_f32_16x16x32_bf16 v[100:103], v[208:211], v[170:173], v[100:103]
	v_mfma_f32_16x16x32_bf16 v[96:99], v[216:219], v[170:173], v[96:99]
	v_mfma_f32_16x16x32_bf16 v[84:87], v[208:211], v[188:191], v[84:87]
	v_mfma_f32_16x16x32_bf16 v[80:83], v[216:219], v[188:191], v[80:83]
	v_mfma_f32_16x16x32_bf16 v[68:71], v[208:211], v[196:199], v[68:71]
	v_mfma_f32_16x16x32_bf16 v[64:67], v[216:219], v[196:199], v[64:67]
	v_mfma_f32_16x16x32_bf16 v[116:119], v[212:215], v[166:169], v[116:119]
	v_mfma_f32_16x16x32_bf16 v[112:115], v[220:223], v[166:169], v[112:115]
	v_mfma_f32_16x16x32_bf16 v[100:103], v[212:215], v[184:187], v[100:103]
	v_mfma_f32_16x16x32_bf16 v[96:99], v[220:223], v[184:187], v[96:99]
	v_mfma_f32_16x16x32_bf16 v[84:87], v[212:215], v[192:195], v[84:87]
	v_mfma_f32_16x16x32_bf16 v[80:83], v[220:223], v[192:195], v[80:83]
	v_mfma_f32_16x16x32_bf16 v[68:71], v[212:215], v[204:207], v[68:71]
	v_mfma_f32_16x16x32_bf16 v[64:67], v[220:223], v[204:207], v[64:67]
	s_mov_b32 m0, s54
	v_lshl_add_u64 v[226:227], s[44:45], 0, v[136:137]
	s_barrier
	ds_read_b128 v[162:165], v180 offset:16384
	ds_read_b128 v[166:169], v180 offset:17408
	ds_read_b128 v[170:173], v180 offset:18432
	ds_read_b128 v[184:187], v180 offset:19456
	ds_read_b128 v[188:191], v180 offset:20480
	ds_read_b128 v[192:195], v180 offset:21504
	ds_read_b128 v[196:199], v180 offset:22528
	ds_read_b128 v[204:207], v180 offset:23552
	global_load_lds_dwordx4 v[226:227], off
	v_lshl_add_u64 v[228:229], s[44:45], 0, v[142:143]
	s_mov_b32 m0, s55
	s_nop 0
	global_load_lds_dwordx4 v[228:229], off
	s_barrier
	s_waitcnt lgkmcnt(0)
	v_mfma_f32_16x16x32_bf16 v[60:63], v[128:131], v[162:165], v[60:63]
	v_mfma_f32_16x16x32_bf16 v[56:59], v[154:157], v[162:165], v[56:59]
	v_mfma_f32_16x16x32_bf16 v[44:47], v[128:131], v[170:173], v[44:47]
	v_mfma_f32_16x16x32_bf16 v[40:43], v[154:157], v[170:173], v[40:43]
	v_mfma_f32_16x16x32_bf16 v[28:31], v[128:131], v[188:191], v[28:31]
	v_mfma_f32_16x16x32_bf16 v[24:27], v[154:157], v[188:191], v[24:27]
	v_mfma_f32_16x16x32_bf16 v[12:15], v[128:131], v[196:199], v[12:15]
	v_mfma_f32_16x16x32_bf16 v[8:11], v[154:157], v[196:199], v[8:11]
	v_mfma_f32_16x16x32_bf16 v[60:63], v[132:135], v[166:169], v[60:63]
	v_mfma_f32_16x16x32_bf16 v[56:59], v[158:161], v[166:169], v[56:59]
	v_mfma_f32_16x16x32_bf16 v[44:47], v[132:135], v[184:187], v[44:47]
	v_mfma_f32_16x16x32_bf16 v[40:43], v[158:161], v[184:187], v[40:43]
	v_mfma_f32_16x16x32_bf16 v[28:31], v[132:135], v[192:195], v[28:31]
	v_mfma_f32_16x16x32_bf16 v[24:27], v[158:161], v[192:195], v[24:27]
	v_mfma_f32_16x16x32_bf16 v[12:15], v[132:135], v[204:207], v[12:15]
	v_mfma_f32_16x16x32_bf16 v[8:11], v[158:161], v[204:207], v[8:11]
	s_barrier
	s_add_i32 s33, s67, s53
	v_lshl_add_u64 v[230:231], s[46:47], 0, v[140:141]
	s_mov_b32 m0, s33
	v_lshl_add_u64 v[232:233], s[46:47], 0, v[146:147]
	global_load_lds_dwordx4 v[230:231], off
	s_add_i32 m0, s33, 0x2000
	s_nop 0
	global_load_lds_dwordx4 v[232:233], off
	s_waitcnt vmcnt(6)
	s_barrier
; #define PG8_STAGE(bufoff, gbase, voff) do { _Pragma("unroll") for (int _i = 0; _i < 2; ++_i) \
;         __builtin_amdgcn_global_load_lds((const unsigned*)((const char*)(gbase) + (voff)[_i]), (LAS unsigned*)(lds + (bufoff) + ldsw + _i * 8192), 16, 0, 0); } while (0)
; #define PG8_LDA(dst, b, h) do { _Pragma("unroll") for (int m = 0; m < 4; ++m) _Pragma("unroll") for (int k = 0; k < 2; ++k) dst[m][k] = *(const LAS bf16x8*)(lds + PG8_SA(b, h) + aoff + m * 2048 + k * 1024); } while (0)
; #define PG8_LDB(dst, b, h) do { _Pragma("unroll") for (int n = 0; n < 2; ++n) _Pragma("unroll") for (int k = 0; k < 2; ++k) dst[n][k] = *(const LAS bf16x8*)(lds + PG8_SB(b, h) + boff + n * 2048 + k * 1024); } while (0)
; #define PG8_WAIT_V(n) asm volatile("s_waitcnt vmcnt(" #n ")" ::: "memory")
; #define PG8_WAIT_L(n) asm volatile("s_waitcnt lgkmcnt(" #n ")" ::: "memory")
; #define PG8_BAR __builtin_amdgcn_s_barrier()
; #define PG8_SCHED __builtin_amdgcn_sched_barrier(0)
; template <class Epi>
; __device__ __forceinline__ void gemm_phase(LAS unsigned char* lds, const Gemm g, const StaticOrder& S, const Epi& E) {
;     ...
;             PG8_LDB(B0, 0, 0); PG8_SCHED; PG8_LDA(At, 0, 0); PG8_STAGE(PG8_SA(1, 1), a1 + hstep, voffA);
;             PG8_WAIT_L(8); PG8_BAR; PG8_WAIT_L(0); PG8_MMA(0, 0, At, B0); PG8_BAR; PG8_SCHED;
;             PG8_LDB(B1, 0, 1); PG8_STAGE(PG8_SB(0, 0), b2, voffB0);
;             PG8_BAR; PG8_WAIT_L(0); PG8_MMA(0, 1, At, B1); PG8_BAR;
;             PG8_LDA(At, 0, 1); PG8_STAGE(PG8_SA(0, 0), a2, voffA);
;             PG8_BAR; PG8_WAIT_L(0); PG8_MMA(1, 0, At, B0); PG8_BAR; PG8_SCHED;
;             PG8_STAGE(PG8_SB(0, 1), b2, voffB1);
;             PG8_WAIT_V(6); PG8_BAR; PG8_MMA(1, 1, At, B1); PG8_BAR;
;             PG8_LDB(B0, 1, 0); PG8_SCHED; PG8_LDA(At, 1, 0); PG8_STAGE(PG8_SA(0, 1), a2 + hstep, voffA);
;             PG8_WAIT_L(8); PG8_BAR; PG8_WAIT_L(0); PG8_MMA(0, 0, At, B0); PG8_BAR; PG8_SCHED;
;             PG8_LDB(B1, 1, 1); PG8_STAGE(PG8_SB(1, 0), b3, voffB0);
;             PG8_BAR; PG8_WAIT_L(0); PG8_MMA(0, 1, At, B1); PG8_BAR;
;             PG8_LDA(At, 1, 1); PG8_STAGE(PG8_SA(1, 0), a3, voffA);
;             PG8_BAR; PG8_WAIT_L(0); PG8_MMA(1, 0, At, B0); PG8_BAR; PG8_SCHED;
;             PG8_STAGE(PG8_SB(1, 1), b3, voffB1);
;             PG8_WAIT_V(6); PG8_BAR; PG8_MMA(1, 1, At, B1); PG8_BAR;
	v_mfma_f32_16x16x32_bf16 v[52:55], v[208:211], v[162:165], v[52:55]
	v_mfma_f32_16x16x32_bf16 v[48:51], v[216:219], v[162:165], v[48:51]
	v_mfma_f32_16x16x32_bf16 v[36:39], v[208:211], v[170:173], v[36:39]
	v_mfma_f32_16x16x32_bf16 v[32:35], v[216:219], v[170:173], v[32:35]
	v_mfma_f32_16x16x32_bf16 v[20:23], v[208:211], v[188:191], v[20:23]
	v_mfma_f32_16x16x32_bf16 v[16:19], v[216:219], v[188:191], v[16:19]
	v_mfma_f32_16x16x32_bf16 v[4:7], v[208:211], v[196:199], v[4:7]
	v_mfma_f32_16x16x32_bf16 v[0:3], v[216:219], v[196:199], v[0:3]
	v_mfma_f32_16x16x32_bf16 v[52:55], v[212:215], v[166:169], v[52:55]
	v_mfma_f32_16x16x32_bf16 v[48:51], v[220:223], v[166:169], v[48:51]
	v_mfma_f32_16x16x32_bf16 v[36:39], v[212:215], v[184:187], v[36:39]
	v_mfma_f32_16x16x32_bf16 v[32:35], v[220:223], v[184:187], v[32:35]
	v_mfma_f32_16x16x32_bf16 v[20:23], v[212:215], v[192:195], v[20:23]
	v_mfma_f32_16x16x32_bf16 v[16:19], v[220:223], v[192:195], v[16:19]
	v_mfma_f32_16x16x32_bf16 v[4:7], v[212:215], v[204:207], v[4:7]
	v_mfma_f32_16x16x32_bf16 v[0:3], v[220:223], v[204:207], v[0:3]
	s_add_i32 s33, 0, 0x18000
	v_add_u32_e32 v158, s33, v175
	s_barrier
	ds_read_b128 v[128:131], v158
	ds_read_b128 v[132:135], v158 offset:1024
	ds_read_b128 v[154:157], v158 offset:2048
	ds_read_b128 v[158:161], v158 offset:3072
	s_add_u32 s44, s44, 0x200000
	s_addc_u32 s45, s45, 0
	s_mov_b32 m0, s56
	v_lshl_add_u64 v[208:209], s[44:45], 0, v[136:137]
	ds_read_b128 v[162:165], v180 offset:32768
	ds_read_b128 v[166:169], v180 offset:33792
	ds_read_b128 v[170:173], v180 offset:34816
	ds_read_b128 v[184:187], v180 offset:35840
	ds_read_b128 v[188:191], v180 offset:36864
	ds_read_b128 v[192:195], v180 offset:37888
	ds_read_b128 v[196:199], v180 offset:38912
	ds_read_b128 v[204:207], v180 offset:39936
	global_load_lds_dwordx4 v[208:209], off
	v_lshl_add_u64 v[208:209], s[44:45], 0, v[142:143]
	s_mov_b32 m0, s57
	s_nop 0
	global_load_lds_dwordx4 v[208:209], off
	s_waitcnt lgkmcnt(8)
	s_barrier
	s_waitcnt lgkmcnt(0)
	v_mfma_f32_16x16x32_bf16 v[124:127], v[128:131], v[162:165], v[124:127]
	v_mfma_f32_16x16x32_bf16 v[120:123], v[154:157], v[162:165], v[120:123]
	v_mfma_f32_16x16x32_bf16 v[108:111], v[128:131], v[170:173], v[108:111]
	v_mfma_f32_16x16x32_bf16 v[104:107], v[154:157], v[170:173], v[104:107]
	v_mfma_f32_16x16x32_bf16 v[92:95], v[128:131], v[188:191], v[92:95]
	v_mfma_f32_16x16x32_bf16 v[88:91], v[154:157], v[188:191], v[88:91]
	v_mfma_f32_16x16x32_bf16 v[76:79], v[128:131], v[196:199], v[76:79]
	v_mfma_f32_16x16x32_bf16 v[72:75], v[154:157], v[196:199], v[72:75]
	v_mfma_f32_16x16x32_bf16 v[124:127], v[132:135], v[166:169], v[124:127]
	v_mfma_f32_16x16x32_bf16 v[120:123], v[158:161], v[166:169], v[120:123]
	v_mfma_f32_16x16x32_bf16 v[108:111], v[132:135], v[184:187], v[108:111]
	v_mfma_f32_16x16x32_bf16 v[104:107], v[158:161], v[184:187], v[104:107]
	v_mfma_f32_16x16x32_bf16 v[92:95], v[132:135], v[192:195], v[92:95]
	v_mfma_f32_16x16x32_bf16 v[88:91], v[158:161], v[192:195], v[88:91]
	v_mfma_f32_16x16x32_bf16 v[76:79], v[132:135], v[204:207], v[76:79]
	v_mfma_f32_16x16x32_bf16 v[72:75], v[158:161], v[204:207], v[72:75]
	s_barrier
	s_add_i32 s44, 0, 0x1c000
	s_add_i32 s33, s33, s53
	v_add_u32_e32 v203, s44, v175
	v_lshl_add_u64 v[200:201], v[200:201], 0, s[26:27]
	s_mov_b32 m0, s33
	ds_read_b128 v[208:211], v203
	ds_read_b128 v[212:215], v203 offset:1024
	ds_read_b128 v[216:219], v203 offset:2048
	ds_read_b128 v[220:223], v203 offset:3072
	global_load_lds_dwordx4 v[200:201], off
	v_lshl_add_u64 v[200:201], v[224:225], 0, s[26:27]
	s_add_i32 m0, s33, 0x2000
	s_nop 0
	global_load_lds_dwordx4 v[200:201], off
	s_barrier
	s_waitcnt lgkmcnt(0)
	v_mfma_f32_16x16x32_bf16 v[116:119], v[208:211], v[162:165], v[116:119]
	v_mfma_f32_16x16x32_bf16 v[112:115], v[216:219], v[162:165], v[112:115]
	v_mfma_f32_16x16x32_bf16 v[100:103], v[208:211], v[170:173], v[100:103]
	v_mfma_f32_16x16x32_bf16 v[96:99], v[216:219], v[170:173], v[96:99]
	v_mfma_f32_16x16x32_bf16 v[84:87], v[208:211], v[188:191], v[84:87]
	v_mfma_f32_16x16x32_bf16 v[80:83], v[216:219], v[188:191], v[80:83]
	v_mfma_f32_16x16x32_bf16 v[68:71], v[208:211], v[196:199], v[68:71]
	v_mfma_f32_16x16x32_bf16 v[64:67], v[216:219], v[196:199], v[64:67]
	v_mfma_f32_16x16x32_bf16 v[116:119], v[212:215], v[166:169], v[116:119]
	v_mfma_f32_16x16x32_bf16 v[112:115], v[220:223], v[166:169], v[112:115]
	v_mfma_f32_16x16x32_bf16 v[100:103], v[212:215], v[184:187], v[100:103]
	v_mfma_f32_16x16x32_bf16 v[96:99], v[220:223], v[184:187], v[96:99]
	v_mfma_f32_16x16x32_bf16 v[84:87], v[212:215], v[192:195], v[84:87]
	v_mfma_f32_16x16x32_bf16 v[80:83], v[220:223], v[192:195], v[80:83]
	v_mfma_f32_16x16x32_bf16 v[68:71], v[212:215], v[204:207], v[68:71]
	v_mfma_f32_16x16x32_bf16 v[64:67], v[220:223], v[204:207], v[64:67]
	s_mov_b32 m0, s60
	v_lshl_add_u64 v[200:201], v[226:227], 0, s[26:27]
	s_barrier
; __device__ __forceinline__ unsigned cvt_pk_bf16(float lo, float hi) { unsigned r; asm volatile("v_cvt_pk_bf16_f32 %0, %1, %2" : "=v"(r) : "v"(lo), "v"(hi)); return r; }
; __device__ __forceinline__ float bflo(unsigned w) { return __uint_as_float(w << 16); }
; __device__ __forceinline__ float bfhi(unsigned w) { return __uint_as_float(w & 0xffff0000u); }
; __device__ __forceinline__ unsigned dpp_ror8(unsigned x) { return (unsigned)__builtin_amdgcn_update_dpp(0, (int)x, 0x128, 0xf, 0xf, false); }
;     const bool lo = fr < 8;
;     const int r1 = row - fr + (fr & 7), cb = col0 + (lo ? 0 : boff);
;     const u32x4 l1 = *(const u32x4*)(P + (size_t)r1 * ld + cb), l2 = *(const u32x4*)(P + (size_t)(r1 + 8) * ld + cb);
;     const u32x4 s1 = {dpp_ror8(l1.x), dpp_ror8(l1.y), dpp_ror8(l1.z), dpp_ror8(l1.w)}, s2 = {dpp_ror8(l2.x), dpp_ror8(l2.y), dpp_ror8(l2.z), dpp_ror8(l2.w)};
;     wA = lo ? l1 : s2; wB = lo ? s1 : l2;
; }
;     __device__ __forceinline__ void operator()(const f32x4 (&acc)[2][2][4][2], const Unit& u, int wr, int wc, int fr, int fq) const {
;     ...
;             for (int m = 0; m < 4; ++m) { const int row = row0 + ai * HALF + m * 16; const size_t off = (size_t)row * D + col0; float sq = 0.f; u32x4 w[2];
;                 const float sc = rsin ? __builtin_amdgcn_rcpf(rsin[row] * (1.f / D) + EPS) : 1.0f;
;                 u32x4 rr[2]; if (R) load_pair_lines(R, D, row, fr, col0, rr[0], rr[1]);
; #pragma unroll
;                 for (int bj = 0; bj < 2; ++bj) { f32x4 r0, r1;
;                     if (R) { const u32x4 rw = rr[bj]; r0 = (f32x4){bflo(rw.x), bfhi(rw.x), bflo(rw.y), bfhi(rw.y)}; r1 = (f32x4){bflo(rw.z), bfhi(rw.z), bflo(rw.w), bfhi(rw.w)}; }
;                     else { const float* rp = (row < 8192 ? src_p + off : src_s + (off - (size_t)8192 * D)) + 8 * bj; r0 = *(const f32x4*)rp; r1 = *(const f32x4*)(rp + 4); }
;                     const f32x4 o0 = r0 + acc[ai][bj][m][0] * sc, o1 = r1 + acc[ai][bj][m][1] * sc;
;                     sq += (o0[0] * o0[0] + o0[1] * o0[1]) + (o0[2] * o0[2] + o0[3] * o0[3]) + (o1[0] * o1[0] + o1[1] * o1[1]) + (o1[2] * o1[2] + o1[3] * o1[3]);
;                     w[bj].x = cvt_pk_bf16(o0[0], o0[1]); w[bj].y = cvt_pk_bf16(o0[2], o0[3]); w[bj].z = cvt_pk_bf16(o1[0], o1[1]); w[bj].w = cvt_pk_bf16(o1[2], o1[3]); }
	ds_read_b128 v[162:165], v180 offset:49152
	ds_read_b128 v[166:169], v180 offset:50176
	ds_read_b128 v[170:173], v180 offset:51200
	ds_read_b128 v[184:187], v180 offset:52224
	ds_read_b128 v[188:191], v180 offset:53248
	ds_read_b128 v[192:195], v180 offset:54272
	ds_read_b128 v[196:199], v180 offset:55296
	ds_read_b128 v[204:207], v180 offset:56320
	global_load_lds_dwordx4 v[200:201], off
	v_lshl_add_u64 v[200:201], v[228:229], 0, s[26:27]
	s_mov_b32 m0, s61
	s_nop 0
	global_load_lds_dwordx4 v[200:201], off
	s_barrier
	s_waitcnt lgkmcnt(0)
	v_mfma_f32_16x16x32_bf16 v[60:63], v[128:131], v[162:165], v[60:63]
	v_mfma_f32_16x16x32_bf16 v[56:59], v[154:157], v[162:165], v[56:59]
	v_mfma_f32_16x16x32_bf16 v[44:47], v[128:131], v[170:173], v[44:47]
	v_mfma_f32_16x16x32_bf16 v[40:43], v[154:157], v[170:173], v[40:43]
	v_mfma_f32_16x16x32_bf16 v[28:31], v[128:131], v[188:191], v[28:31]
	v_mfma_f32_16x16x32_bf16 v[24:27], v[154:157], v[188:191], v[24:27]
	v_mfma_f32_16x16x32_bf16 v[12:15], v[128:131], v[196:199], v[12:15]
	v_mfma_f32_16x16x32_bf16 v[8:11], v[154:157], v[196:199], v[8:11]
	v_mfma_f32_16x16x32_bf16 v[60:63], v[132:135], v[166:169], v[60:63]
	v_mfma_f32_16x16x32_bf16 v[56:59], v[158:161], v[166:169], v[56:59]
	v_mfma_f32_16x16x32_bf16 v[44:47], v[132:135], v[184:187], v[44:47]
	v_mfma_f32_16x16x32_bf16 v[40:43], v[158:161], v[184:187], v[40:43]
	v_mfma_f32_16x16x32_bf16 v[28:31], v[132:135], v[192:195], v[28:31]
	v_mfma_f32_16x16x32_bf16 v[24:27], v[158:161], v[192:195], v[24:27]
	v_mfma_f32_16x16x32_bf16 v[12:15], v[132:135], v[204:207], v[12:15]
	v_mfma_f32_16x16x32_bf16 v[8:11], v[158:161], v[204:207], v[8:11]
	s_barrier
	s_add_i32 s33, s44, s53
	v_lshl_add_u64 v[128:129], v[230:231], 0, s[26:27]
	s_mov_b32 m0, s33
	s_nop 0
	global_load_lds_dwordx4 v[128:129], off
	v_lshl_add_u64 v[128:129], v[232:233], 0, s[26:27]
	s_add_i32 m0, s33, 0x2000
	s_nop 0
	global_load_lds_dwordx4 v[128:129], off
	s_waitcnt vmcnt(6)
	s_barrier
	v_mfma_f32_16x16x32_bf16 v[52:55], v[208:211], v[162:165], v[52:55]
	v_mfma_f32_16x16x32_bf16 v[48:51], v[216:219], v[162:165], v[48:51]
	v_mfma_f32_16x16x32_bf16 v[36:39], v[208:211], v[170:173], v[36:39]
	v_mfma_f32_16x16x32_bf16 v[32:35], v[216:219], v[170:173], v[32:35]
	v_mfma_f32_16x16x32_bf16 v[20:23], v[208:211], v[188:191], v[20:23]
	v_mfma_f32_16x16x32_bf16 v[16:19], v[216:219], v[188:191], v[16:19]
	v_mfma_f32_16x16x32_bf16 v[4:7], v[208:211], v[196:199], v[4:7]
	v_mfma_f32_16x16x32_bf16 v[0:3], v[216:219], v[196:199], v[0:3]
	v_mfma_f32_16x16x32_bf16 v[52:55], v[212:215], v[166:169], v[52:55]
	v_mfma_f32_16x16x32_bf16 v[48:51], v[220:223], v[166:169], v[48:51]
	v_mfma_f32_16x16x32_bf16 v[36:39], v[212:215], v[184:187], v[36:39]
	v_mfma_f32_16x16x32_bf16 v[32:35], v[220:223], v[184:187], v[32:35]
	v_mfma_f32_16x16x32_bf16 v[20:23], v[212:215], v[192:195], v[20:23]
	v_mfma_f32_16x16x32_bf16 v[16:19], v[220:223], v[192:195], v[16:19]
	v_mfma_f32_16x16x32_bf16 v[4:7], v[212:215], v[204:207], v[4:7]
	v_mfma_f32_16x16x32_bf16 v[0:3], v[220:223], v[204:207], v[0:3]
	s_add_i32 s74, s74, 2
	s_add_u32 s42, s42, 0x100
	s_addc_u32 s43, s43, 0
	s_add_u32 s72, s72, 0x100
	s_addc_u32 s73, s73, 0
	s_cmpk_gt_u32 s74, 0x7d
	s_barrier
	s_cbranch_scc0 .LBB0_1443
	s_lshl_b32 s9, s10, 8
	s_add_i32 s10, s9, s62
	v_or_b32_e32 v158, s10, v174
	v_ashrrev_i32_e32 v159, 31, v158
	v_lshl_add_u64 v[160:161], v[158:159], 2, s[18:19]
	global_load_dword v168, v[160:161], off
	v_lshl_or_b32 v156, s8, 8, v178
	v_or_b32_e32 v154, v156, v177
	v_ashrrev_i32_e32 v155, 31, v154
	v_cndmask_b32_e64 v128, 0, 1, s[28:29]
	v_or_b32_e32 v166, s10, v176
	v_cmp_ne_u32_e64 s[8:9], 1, v128
	s_andn2_b64 vcc, exec, s[28:29]
	v_lshlrev_b64 v[162:163], 1, v[154:155]
	v_ashrrev_i32_e32 v167, 31, v166
	v_or_b32_e32 v164, 8, v166
	s_cbranch_vccnz .LBB0_1447
	v_ashrrev_i32_e32 v165, 31, v164
	v_lshlrev_b64 v[128:129], 12, v[166:167]
	v_lshlrev_b64 v[132:133], 12, v[164:165]
	v_lshl_add_u64 v[128:129], s[16:17], 0, v[128:129]
	v_lshl_add_u64 v[132:133], s[16:17], 0, v[132:133]
	v_lshl_add_u64 v[128:129], v[128:129], 0, v[162:163]
	v_lshl_add_u64 v[132:133], v[132:133], 0, v[162:163]
	global_load_dwordx4 v[128:131], v[128:129], off
	global_load_dwordx4 v[132:135], v[132:133], off
	s_waitcnt vmcnt(0)
	v_mov_b32_dpp v157, v128 row_ror:8 row_mask:0xf bank_mask:0xf
	v_mov_b32_dpp v165, v129 row_ror:8 row_mask:0xf bank_mask:0xf
	v_mov_b32_dpp v169, v130 row_ror:8 row_mask:0xf bank_mask:0xf
	v_mov_b32_dpp v170, v131 row_ror:8 row_mask:0xf bank_mask:0xf
	v_mov_b32_dpp v171, v132 row_ror:8 row_mask:0xf bank_mask:0xf
	v_mov_b32_dpp v172, v133 row_ror:8 row_mask:0xf bank_mask:0xf
	v_mov_b32_dpp v173, v134 row_ror:8 row_mask:0xf bank_mask:0xf
	v_mov_b32_dpp v187, v135 row_ror:8 row_mask:0xf bank_mask:0xf
	v_cndmask_b32_e64 v184, v132, v157, s[6:7]
	v_cndmask_b32_e64 v185, v133, v165, s[6:7]
	v_cndmask_b32_e64 v186, v134, v169, s[6:7]
	v_cndmask_b32_e64 v188, v171, v128, s[6:7]
	v_cndmask_b32_e64 v189, v172, v129, s[6:7]
	v_cndmask_b32_e64 v190, v173, v130, s[6:7]
	v_cndmask_b32_e64 v191, v187, v131, s[6:7]
	v_cndmask_b32_e64 v187, v135, v170, s[6:7]
	s_and_b64 vcc, exec, s[8:9]
	v_cmp_gt_i32_e64 s[10:11], s58, v158
	s_cbranch_vccnz .LBB0_1448

; __device__ __forceinline__ void store_pair_lines(bf16_t* O, int ldc, int row, int fr, int col0, u32x4 wA, u32x4 wB) {
;     const u32x4 sA = {dpp_ror8(wA.x), dpp_ror8(wA.y), dpp_ror8(wA.z), dpp_ror8(wA.w)}, sB = {dpp_ror8(wB.x), dpp_ror8(wB.y), dpp_ror8(wB.z), dpp_ror8(wB.w)};
;     const bool lo = fr < 8;
;     const u32x4 o1 = lo ? wA : sB, o2 = lo ? sA : wB;
;     const int r1 = row - fr + (fr & 7), cb = col0 + (lo ? 0 : 8);
;     *(u32x4*)(O + (size_t)r1 * ldc + cb) = o1;
;     *(u32x4*)(O + (size_t)(r1 + 8) * ldc + cb) = o2;
; }
;     const bool lo = fr < 8;
;     const int r1 = row - fr + (fr & 7), cb = col0 + (lo ? 0 : boff);
;     const u32x4 l1 = *(const u32x4*)(P + (size_t)r1 * ld + cb), l2 = *(const u32x4*)(P + (size_t)(r1 + 8) * ld + cb);
;     __device__ __forceinline__ void operator()(const f32x4 (&acc)[2][2][4][2], const Unit& u, int wr, int wc, int fr, int fq) const {
;     ...
;             for (int m = 0; m < 4; ++m) { const int row = row0 + ai * HALF + m * 16; const size_t off = (size_t)row * D + col0; float sq = 0.f; u32x4 w[2];
;                 const float sc = rsin ? __builtin_amdgcn_rcpf(rsin[row] * (1.f / D) + EPS) : 1.0f;
;                 u32x4 rr[2]; if (R) load_pair_lines(R, D, row, fr, col0, rr[0], rr[1]);
; #pragma unroll
;                 for (int bj = 0; bj < 2; ++bj) { f32x4 r0, r1;
;                     if (R) { const u32x4 rw = rr[bj]; r0 = (f32x4){bflo(rw.x), bfhi(rw.x), bflo(rw.y), bfhi(rw.y)}; r1 = (f32x4){bflo(rw.z), bfhi(rw.z), bflo(rw.w), bfhi(rw.w)}; }
;                     else { const float* rp = (row < 8192 ? src_p + off : src_s + (off - (size_t)8192 * D)) + 8 * bj; r0 = *(const f32x4*)rp; r1 = *(const f32x4*)(rp + 4); }
;                     const f32x4 o0 = r0 + acc[ai][bj][m][0] * sc, o1 = r1 + acc[ai][bj][m][1] * sc;
;                     sq += (o0[0] * o0[0] + o0[1] * o0[1]) + (o0[2] * o0[2] + o0[3] * o0[3]) + (o1[0] * o1[0] + o1[1] * o1[1]) + (o1[2] * o1[2] + o1[3] * o1[3]);
;                     w[bj].x = cvt_pk_bf16(o0[0], o0[1]); w[bj].y = cvt_pk_bf16(o0[2], o0[3]); w[bj].z = cvt_pk_bf16(o1[0], o1[1]); w[bj].w = cvt_pk_bf16(o1[2], o1[3]); }
;                 store_pair_lines(O, D, row, fr, col0, w[0], w[1]);
;                 if (ssout) { sq += __shfl_xor(sq, 16); sq += __shfl_xor(sq, 32); if (fq == 0) unsafeAtomicAdd(ssout + row, sq); } }
.LBB0_1454:
	v_mov_b32_e32 v169, v168
	v_mov_b32_e32 v132, v168
	v_mov_b32_e32 v133, v168
	s_waitcnt vmcnt(0) lgkmcnt(0)
	v_pk_fma_f32 v[118:119], v[118:119], v[132:133], v[122:123]
	v_pk_fma_f32 v[116:117], v[116:117], v[168:169], v[120:121]
	v_pk_fma_f32 v[112:113], v[112:113], v[168:169], v[124:125]
	v_pk_fma_f32 v[114:115], v[114:115], v[132:133], v[126:127]
	v_cvt_pk_bf16_f32 v116, v116, v117
	v_cvt_pk_bf16_f32 v117, v118, v119
	v_cvt_pk_bf16_f32 v118, v112, v113
	v_mov_b32_dpp v120, v128 row_ror:8 row_mask:0xf bank_mask:0xf
	v_mov_b32_dpp v121, v130 row_ror:8 row_mask:0xf bank_mask:0xf
	v_cvt_pk_bf16_f32 v119, v114, v115
	v_mov_b32_dpp v112, v116 row_ror:8 row_mask:0xf bank_mask:0xf
	v_mov_b32_dpp v113, v117 row_ror:8 row_mask:0xf bank_mask:0xf
	v_cndmask_b32_e64 v117, v117, v121, s[6:7]
	v_cndmask_b32_e64 v116, v116, v120, s[6:7]
	v_lshlrev_b64 v[120:121], 12, v[166:167]
	v_mov_b32_dpp v114, v118 row_ror:8 row_mask:0xf bank_mask:0xf
	v_mov_b32_dpp v115, v119 row_ror:8 row_mask:0xf bank_mask:0xf
	v_lshl_add_u64 v[120:121], s[12:13], 0, v[120:121]
	v_cndmask_b32_e64 v113, v113, v130, s[6:7]
	v_cndmask_b32_e64 v115, v115, v131, s[6:7]
	v_cndmask_b32_e64 v112, v112, v128, s[6:7]
	v_cndmask_b32_e64 v114, v114, v129, s[6:7]
	v_lshl_add_u64 v[120:121], v[120:121], 0, v[162:163]
	v_ashrrev_i32_e32 v165, 31, v164
	v_mov_b32_dpp v122, v129 row_ror:8 row_mask:0xf bank_mask:0xf
	global_store_dwordx4 v[120:121], v[112:115], off
	v_cndmask_b32_e64 v118, v118, v122, s[6:7]
	v_mov_b32_dpp v123, v131 row_ror:8 row_mask:0xf bank_mask:0xf
	v_lshlrev_b64 v[112:113], 12, v[164:165]
	v_lshl_add_u64 v[112:113], s[12:13], 0, v[112:113]
	v_or_b32_e32 v122, 16, v158
	v_cndmask_b32_e64 v119, v119, v123, s[6:7]
	v_lshl_add_u64 v[112:113], v[112:113], 0, v[162:163]
	v_ashrrev_i32_e32 v123, 31, v122
	global_store_dwordx4 v[112:113], v[116:119], off
	v_lshl_add_u64 v[112:113], v[122:123], 2, s[18:19]
	global_load_dword v128, v[112:113], off
	v_sub_u32_e32 v112, v122, v174
	s_and_b64 vcc, exec, s[8:9]
	v_add_u32_e32 v120, v112, v176
	s_cbranch_vccnz .LBB0_1456
	v_ashrrev_i32_e32 v121, 31, v120
	v_lshlrev_b64 v[112:113], 12, v[120:121]
	v_lshl_add_u64 v[112:113], s[16:17], 0, v[112:113]
	v_lshl_add_u64 v[116:117], v[154:155], 1, v[112:113]
	global_load_dwordx4 v[112:115], v[116:117], off
	v_add_co_u32_e32 v116, vcc, 0x8000, v116
	v_mov_b32_e32 v121, 0
	s_nop 0
	v_addc_co_u32_e32 v117, vcc, 0, v117, vcc
	global_load_dwordx4 v[116:119], v[116:117], off
	s_waitcnt vmcnt(1)
	v_mov_b32_dpp v121, v112 row_ror:8 row_mask:0xf bank_mask:0xf
	v_mov_b32_dpp v124, v113 row_ror:8 row_mask:0xf bank_mask:0xf
	v_mov_b32_dpp v125, v114 row_ror:8 row_mask:0xf bank_mask:0xf
	v_mov_b32_dpp v126, v115 row_ror:8 row_mask:0xf bank_mask:0xf
	s_waitcnt vmcnt(0)
	v_mov_b32_dpp v127, v116 row_ror:8 row_mask:0xf bank_mask:0xf
	v_mov_b32_dpp v129, v117 row_ror:8 row_mask:0xf bank_mask:0xf
	v_mov_b32_dpp v130, v118 row_ror:8 row_mask:0xf bank_mask:0xf
	v_mov_b32_dpp v131, v119 row_ror:8 row_mask:0xf bank_mask:0xf
	v_cndmask_b32_e64 v184, v116, v121, s[6:7]
	v_cndmask_b32_e64 v185, v117, v124, s[6:7]
	v_cndmask_b32_e64 v186, v118, v125, s[6:7]
	v_cndmask_b32_e64 v188, v127, v112, s[6:7]
	v_cndmask_b32_e64 v189, v129, v113, s[6:7]
	v_cndmask_b32_e64 v190, v130, v114, s[6:7]
	v_cndmask_b32_e64 v191, v131, v115, s[6:7]
	v_cndmask_b32_e64 v187, v119, v126, s[6:7]

; __device__ __forceinline__ void store_pair_lines(bf16_t* O, int ldc, int row, int fr, int col0, u32x4 wA, u32x4 wB) {
;     const u32x4 sA = {dpp_ror8(wA.x), dpp_ror8(wA.y), dpp_ror8(wA.z), dpp_ror8(wA.w)}, sB = {dpp_ror8(wB.x), dpp_ror8(wB.y), dpp_ror8(wB.z), dpp_ror8(wB.w)};
;     const bool lo = fr < 8;
;     const u32x4 o1 = lo ? wA : sB, o2 = lo ? sA : wB;
;     const int r1 = row - fr + (fr & 7), cb = col0 + (lo ? 0 : 8);
;     *(u32x4*)(O + (size_t)r1 * ldc + cb) = o1;
;     *(u32x4*)(O + (size_t)(r1 + 8) * ldc + cb) = o2;
; }
;     const bool lo = fr < 8;
;     const int r1 = row - fr + (fr & 7), cb = col0 + (lo ? 0 : boff);
;     const u32x4 l1 = *(const u32x4*)(P + (size_t)r1 * ld + cb), l2 = *(const u32x4*)(P + (size_t)(r1 + 8) * ld + cb);
;     __device__ __forceinline__ void operator()(const f32x4 (&acc)[2][2][4][2], const Unit& u, int wr, int wc, int fr, int fq) const {
;     ...
;             for (int m = 0; m < 4; ++m) { const int row = row0 + ai * HALF + m * 16; const size_t off = (size_t)row * D + col0; float sq = 0.f; u32x4 w[2];
;                 const float sc = rsin ? __builtin_amdgcn_rcpf(rsin[row] * (1.f / D) + EPS) : 1.0f;
;                 u32x4 rr[2]; if (R) load_pair_lines(R, D, row, fr, col0, rr[0], rr[1]);
; #pragma unroll
;                 for (int bj = 0; bj < 2; ++bj) { f32x4 r0, r1;
;                     if (R) { const u32x4 rw = rr[bj]; r0 = (f32x4){bflo(rw.x), bfhi(rw.x), bflo(rw.y), bfhi(rw.y)}; r1 = (f32x4){bflo(rw.z), bfhi(rw.z), bflo(rw.w), bfhi(rw.w)}; }
;                     else { const float* rp = (row < 8192 ? src_p + off : src_s + (off - (size_t)8192 * D)) + 8 * bj; r0 = *(const f32x4*)rp; r1 = *(const f32x4*)(rp + 4); }
;                     const f32x4 o0 = r0 + acc[ai][bj][m][0] * sc, o1 = r1 + acc[ai][bj][m][1] * sc;
;                     sq += (o0[0] * o0[0] + o0[1] * o0[1]) + (o0[2] * o0[2] + o0[3] * o0[3]) + (o1[0] * o1[0] + o1[1] * o1[1]) + (o1[2] * o1[2] + o1[3] * o1[3]);
;                     w[bj].x = cvt_pk_bf16(o0[0], o0[1]); w[bj].y = cvt_pk_bf16(o0[2], o0[3]); w[bj].z = cvt_pk_bf16(o1[0], o1[1]); w[bj].w = cvt_pk_bf16(o1[2], o1[3]); }
;                 store_pair_lines(O, D, row, fr, col0, w[0], w[1]);
;                 if (ssout) { sq += __shfl_xor(sq, 16); sq += __shfl_xor(sq, 32); if (fq == 0) unsafeAtomicAdd(ssout + row, sq); } }
.LBB0_1465:
	v_mov_b32_e32 v123, v122
	v_mov_b32_e32 v116, v122
	v_mov_b32_e32 v117, v122
	s_waitcnt vmcnt(0) lgkmcnt(0)
	v_pk_fma_f32 v[102:103], v[102:103], v[116:117], v[106:107]
	v_pk_fma_f32 v[100:101], v[100:101], v[122:123], v[104:105]
	v_pk_fma_f32 v[96:97], v[96:97], v[122:123], v[108:109]
	v_pk_fma_f32 v[98:99], v[98:99], v[116:117], v[110:111]
	v_cvt_pk_bf16_f32 v100, v100, v101
	v_cvt_pk_bf16_f32 v101, v102, v103
	v_cvt_pk_bf16_f32 v102, v96, v97
	v_mov_b32_dpp v104, v112 row_ror:8 row_mask:0xf bank_mask:0xf
	v_mov_b32_dpp v105, v114 row_ror:8 row_mask:0xf bank_mask:0xf
	v_ashrrev_i32_e32 v121, 31, v120
	v_cvt_pk_bf16_f32 v103, v98, v99
	v_mov_b32_dpp v96, v100 row_ror:8 row_mask:0xf bank_mask:0xf
	v_mov_b32_dpp v97, v101 row_ror:8 row_mask:0xf bank_mask:0xf
	v_cndmask_b32_e64 v101, v101, v105, s[6:7]
	v_cndmask_b32_e64 v100, v100, v104, s[6:7]
	v_lshlrev_b64 v[104:105], 12, v[120:121]
	v_mov_b32_dpp v98, v102 row_ror:8 row_mask:0xf bank_mask:0xf
	v_mov_b32_dpp v99, v103 row_ror:8 row_mask:0xf bank_mask:0xf
	v_lshl_add_u64 v[104:105], s[12:13], 0, v[104:105]
	v_mov_b32_dpp v106, v113 row_ror:8 row_mask:0xf bank_mask:0xf
	v_cndmask_b32_e64 v97, v97, v114, s[6:7]
	v_cndmask_b32_e64 v99, v99, v115, s[6:7]
	v_cndmask_b32_e64 v96, v96, v112, s[6:7]
	v_cndmask_b32_e64 v98, v98, v113, s[6:7]
	v_lshl_add_u64 v[104:105], v[154:155], 1, v[104:105]
	v_mov_b32_dpp v107, v115 row_ror:8 row_mask:0xf bank_mask:0xf
	v_cndmask_b32_e64 v102, v102, v106, s[6:7]
	global_store_dwordx4 v[104:105], v[96:99], off
	v_or_b32_e32 v106, 32, v158
	v_cndmask_b32_e64 v103, v103, v107, s[6:7]
	v_add_co_u32_e32 v96, vcc, 0x8000, v104
	v_ashrrev_i32_e32 v107, 31, v106
	s_nop 0
	v_addc_co_u32_e32 v97, vcc, 0, v105, vcc
	global_store_dwordx4 v[96:97], v[100:103], off
	v_lshl_add_u64 v[96:97], v[106:107], 2, s[18:19]
	global_load_dword v112, v[96:97], off
	v_sub_u32_e32 v96, v106, v174
	s_and_b64 vcc, exec, s[8:9]
	v_add_u32_e32 v104, v96, v176
	s_cbranch_vccnz .LBB0_1467
	v_ashrrev_i32_e32 v105, 31, v104
	v_lshlrev_b64 v[96:97], 12, v[104:105]
	v_lshl_add_u64 v[96:97], s[16:17], 0, v[96:97]
	v_lshl_add_u64 v[100:101], v[154:155], 1, v[96:97]
	global_load_dwordx4 v[96:99], v[100:101], off
	v_add_co_u32_e32 v100, vcc, 0x8000, v100
	v_mov_b32_e32 v105, 0
	s_nop 0
	v_addc_co_u32_e32 v101, vcc, 0, v101, vcc
	global_load_dwordx4 v[100:103], v[100:101], off
	s_waitcnt vmcnt(1)
	v_mov_b32_dpp v105, v96 row_ror:8 row_mask:0xf bank_mask:0xf
	v_mov_b32_dpp v108, v97 row_ror:8 row_mask:0xf bank_mask:0xf
	v_mov_b32_dpp v109, v98 row_ror:8 row_mask:0xf bank_mask:0xf
	v_mov_b32_dpp v110, v99 row_ror:8 row_mask:0xf bank_mask:0xf
	s_waitcnt vmcnt(0)
	v_mov_b32_dpp v111, v100 row_ror:8 row_mask:0xf bank_mask:0xf
	v_mov_b32_dpp v113, v101 row_ror:8 row_mask:0xf bank_mask:0xf
	v_mov_b32_dpp v114, v102 row_ror:8 row_mask:0xf bank_mask:0xf
	v_mov_b32_dpp v115, v103 row_ror:8 row_mask:0xf bank_mask:0xf
	v_cndmask_b32_e64 v184, v100, v105, s[6:7]
	v_cndmask_b32_e64 v185, v101, v108, s[6:7]
	v_cndmask_b32_e64 v186, v102, v109, s[6:7]
	v_cndmask_b32_e64 v188, v111, v96, s[6:7]
	v_cndmask_b32_e64 v189, v113, v97, s[6:7]
	v_cndmask_b32_e64 v190, v114, v98, s[6:7]
	v_cndmask_b32_e64 v191, v115, v99, s[6:7]
	v_cndmask_b32_e64 v187, v103, v110, s[6:7]

; __device__ __forceinline__ void store_pair_lines(bf16_t* O, int ldc, int row, int fr, int col0, u32x4 wA, u32x4 wB) {
;     const u32x4 sA = {dpp_ror8(wA.x), dpp_ror8(wA.y), dpp_ror8(wA.z), dpp_ror8(wA.w)}, sB = {dpp_ror8(wB.x), dpp_ror8(wB.y), dpp_ror8(wB.z), dpp_ror8(wB.w)};
;     const bool lo = fr < 8;
;     const u32x4 o1 = lo ? wA : sB, o2 = lo ? sA : wB;
;     const int r1 = row - fr + (fr & 7), cb = col0 + (lo ? 0 : 8);
;     *(u32x4*)(O + (size_t)r1 * ldc + cb) = o1;
;     *(u32x4*)(O + (size_t)(r1 + 8) * ldc + cb) = o2;
; }
;     const bool lo = fr < 8;
;     const int r1 = row - fr + (fr & 7), cb = col0 + (lo ? 0 : boff);
;     const u32x4 l1 = *(const u32x4*)(P + (size_t)r1 * ld + cb), l2 = *(const u32x4*)(P + (size_t)(r1 + 8) * ld + cb);
;     __device__ __forceinline__ void operator()(const f32x4 (&acc)[2][2][4][2], const Unit& u, int wr, int wc, int fr, int fq) const {
;     ...
;             for (int m = 0; m < 4; ++m) { const int row = row0 + ai * HALF + m * 16; const size_t off = (size_t)row * D + col0; float sq = 0.f; u32x4 w[2];
;                 const float sc = rsin ? __builtin_amdgcn_rcpf(rsin[row] * (1.f / D) + EPS) : 1.0f;
;                 u32x4 rr[2]; if (R) load_pair_lines(R, D, row, fr, col0, rr[0], rr[1]);
; #pragma unroll
;                 for (int bj = 0; bj < 2; ++bj) { f32x4 r0, r1;
;                     if (R) { const u32x4 rw = rr[bj]; r0 = (f32x4){bflo(rw.x), bfhi(rw.x), bflo(rw.y), bfhi(rw.y)}; r1 = (f32x4){bflo(rw.z), bfhi(rw.z), bflo(rw.w), bfhi(rw.w)}; }
;                     else { const float* rp = (row < 8192 ? src_p + off : src_s + (off - (size_t)8192 * D)) + 8 * bj; r0 = *(const f32x4*)rp; r1 = *(const f32x4*)(rp + 4); }
;                     const f32x4 o0 = r0 + acc[ai][bj][m][0] * sc, o1 = r1 + acc[ai][bj][m][1] * sc;
;                     sq += (o0[0] * o0[0] + o0[1] * o0[1]) + (o0[2] * o0[2] + o0[3] * o0[3]) + (o1[0] * o1[0] + o1[1] * o1[1]) + (o1[2] * o1[2] + o1[3] * o1[3]);
;                     w[bj].x = cvt_pk_bf16(o0[0], o0[1]); w[bj].y = cvt_pk_bf16(o0[2], o0[3]); w[bj].z = cvt_pk_bf16(o1[0], o1[1]); w[bj].w = cvt_pk_bf16(o1[2], o1[3]); }
;                 store_pair_lines(O, D, row, fr, col0, w[0], w[1]);
;                 if (ssout) { sq += __shfl_xor(sq, 16); sq += __shfl_xor(sq, 32); if (fq == 0) unsafeAtomicAdd(ssout + row, sq); } }
.LBB0_1476:
	v_mov_b32_e32 v107, v106
	v_mov_b32_e32 v100, v106
	v_mov_b32_e32 v101, v106
	s_waitcnt vmcnt(0) lgkmcnt(0)
	v_pk_fma_f32 v[86:87], v[86:87], v[100:101], v[90:91]
	v_pk_fma_f32 v[84:85], v[84:85], v[106:107], v[88:89]
	v_pk_fma_f32 v[80:81], v[80:81], v[106:107], v[92:93]
	v_pk_fma_f32 v[82:83], v[82:83], v[100:101], v[94:95]
	v_cvt_pk_bf16_f32 v84, v84, v85
	v_cvt_pk_bf16_f32 v85, v86, v87
	v_cvt_pk_bf16_f32 v86, v80, v81
	v_mov_b32_dpp v88, v96 row_ror:8 row_mask:0xf bank_mask:0xf
	v_mov_b32_dpp v89, v98 row_ror:8 row_mask:0xf bank_mask:0xf
	v_ashrrev_i32_e32 v105, 31, v104
	v_cvt_pk_bf16_f32 v87, v82, v83
	v_mov_b32_dpp v80, v84 row_ror:8 row_mask:0xf bank_mask:0xf
	v_mov_b32_dpp v81, v85 row_ror:8 row_mask:0xf bank_mask:0xf
	v_cndmask_b32_e64 v85, v85, v89, s[6:7]
	v_cndmask_b32_e64 v84, v84, v88, s[6:7]
	v_lshlrev_b64 v[88:89], 12, v[104:105]
	v_mov_b32_dpp v82, v86 row_ror:8 row_mask:0xf bank_mask:0xf
	v_mov_b32_dpp v83, v87 row_ror:8 row_mask:0xf bank_mask:0xf
	v_lshl_add_u64 v[88:89], s[12:13], 0, v[88:89]
	v_mov_b32_dpp v90, v97 row_ror:8 row_mask:0xf bank_mask:0xf
	v_cndmask_b32_e64 v81, v81, v98, s[6:7]
	v_cndmask_b32_e64 v83, v83, v99, s[6:7]
	v_cndmask_b32_e64 v80, v80, v96, s[6:7]
	v_cndmask_b32_e64 v82, v82, v97, s[6:7]
	v_lshl_add_u64 v[88:89], v[154:155], 1, v[88:89]
	v_mov_b32_dpp v91, v99 row_ror:8 row_mask:0xf bank_mask:0xf
	v_cndmask_b32_e64 v86, v86, v90, s[6:7]
	global_store_dwordx4 v[88:89], v[80:83], off
	v_or_b32_e32 v90, 48, v158
	v_cndmask_b32_e64 v87, v87, v91, s[6:7]
	v_add_co_u32_e32 v80, vcc, 0x8000, v88
	v_ashrrev_i32_e32 v91, 31, v90
	s_nop 0
	v_addc_co_u32_e32 v81, vcc, 0, v89, vcc
	global_store_dwordx4 v[80:81], v[84:87], off
	v_lshl_add_u64 v[80:81], v[90:91], 2, s[18:19]
	global_load_dword v96, v[80:81], off
	v_sub_u32_e32 v80, v90, v174
	s_and_b64 vcc, exec, s[8:9]
	v_add_u32_e32 v88, v80, v176
	s_cbranch_vccnz .LBB0_1478
	v_ashrrev_i32_e32 v89, 31, v88
	v_lshlrev_b64 v[80:81], 12, v[88:89]
	v_lshl_add_u64 v[80:81], s[16:17], 0, v[80:81]
	v_lshl_add_u64 v[84:85], v[154:155], 1, v[80:81]
	global_load_dwordx4 v[80:83], v[84:85], off
	v_add_co_u32_e32 v84, vcc, 0x8000, v84
	v_mov_b32_e32 v89, 0
	s_nop 0
	v_addc_co_u32_e32 v85, vcc, 0, v85, vcc
	global_load_dwordx4 v[84:87], v[84:85], off
	s_waitcnt vmcnt(1)
	v_mov_b32_dpp v89, v80 row_ror:8 row_mask:0xf bank_mask:0xf
	v_mov_b32_dpp v92, v81 row_ror:8 row_mask:0xf bank_mask:0xf
	v_mov_b32_dpp v93, v82 row_ror:8 row_mask:0xf bank_mask:0xf
	v_mov_b32_dpp v94, v83 row_ror:8 row_mask:0xf bank_mask:0xf
	s_waitcnt vmcnt(0)
	v_mov_b32_dpp v95, v84 row_ror:8 row_mask:0xf bank_mask:0xf
	v_mov_b32_dpp v97, v85 row_ror:8 row_mask:0xf bank_mask:0xf
	v_mov_b32_dpp v98, v86 row_ror:8 row_mask:0xf bank_mask:0xf
	v_mov_b32_dpp v99, v87 row_ror:8 row_mask:0xf bank_mask:0xf
	v_cndmask_b32_e64 v184, v84, v89, s[6:7]
	v_cndmask_b32_e64 v185, v85, v92, s[6:7]
	v_cndmask_b32_e64 v186, v86, v93, s[6:7]
	v_cndmask_b32_e64 v188, v95, v80, s[6:7]
	v_cndmask_b32_e64 v189, v97, v81, s[6:7]
	v_cndmask_b32_e64 v190, v98, v82, s[6:7]
	v_cndmask_b32_e64 v191, v99, v83, s[6:7]
	v_cndmask_b32_e64 v187, v87, v94, s[6:7]

; __device__ __forceinline__ void store_pair_lines(bf16_t* O, int ldc, int row, int fr, int col0, u32x4 wA, u32x4 wB) {
;     const u32x4 sA = {dpp_ror8(wA.x), dpp_ror8(wA.y), dpp_ror8(wA.z), dpp_ror8(wA.w)}, sB = {dpp_ror8(wB.x), dpp_ror8(wB.y), dpp_ror8(wB.z), dpp_ror8(wB.w)};
;     const bool lo = fr < 8;
;     const u32x4 o1 = lo ? wA : sB, o2 = lo ? sA : wB;
;     const int r1 = row - fr + (fr & 7), cb = col0 + (lo ? 0 : 8);
;     *(u32x4*)(O + (size_t)r1 * ldc + cb) = o1;
;     *(u32x4*)(O + (size_t)(r1 + 8) * ldc + cb) = o2;
; }
;     const bool lo = fr < 8;
;     const int r1 = row - fr + (fr & 7), cb = col0 + (lo ? 0 : boff);
;     const u32x4 l1 = *(const u32x4*)(P + (size_t)r1 * ld + cb), l2 = *(const u32x4*)(P + (size_t)(r1 + 8) * ld + cb);
;     __device__ __forceinline__ void operator()(const f32x4 (&acc)[2][2][4][2], const Unit& u, int wr, int wc, int fr, int fq) const {
;     ...
;             for (int m = 0; m < 4; ++m) { const int row = row0 + ai * HALF + m * 16; const size_t off = (size_t)row * D + col0; float sq = 0.f; u32x4 w[2];
;                 const float sc = rsin ? __builtin_amdgcn_rcpf(rsin[row] * (1.f / D) + EPS) : 1.0f;
;                 u32x4 rr[2]; if (R) load_pair_lines(R, D, row, fr, col0, rr[0], rr[1]);
; #pragma unroll
;                 for (int bj = 0; bj < 2; ++bj) { f32x4 r0, r1;
;                     if (R) { const u32x4 rw = rr[bj]; r0 = (f32x4){bflo(rw.x), bfhi(rw.x), bflo(rw.y), bfhi(rw.y)}; r1 = (f32x4){bflo(rw.z), bfhi(rw.z), bflo(rw.w), bfhi(rw.w)}; }
;                     else { const float* rp = (row < 8192 ? src_p + off : src_s + (off - (size_t)8192 * D)) + 8 * bj; r0 = *(const f32x4*)rp; r1 = *(const f32x4*)(rp + 4); }
;                     const f32x4 o0 = r0 + acc[ai][bj][m][0] * sc, o1 = r1 + acc[ai][bj][m][1] * sc;
;                     sq += (o0[0] * o0[0] + o0[1] * o0[1]) + (o0[2] * o0[2] + o0[3] * o0[3]) + (o1[0] * o1[0] + o1[1] * o1[1]) + (o1[2] * o1[2] + o1[3] * o1[3]);
;                     w[bj].x = cvt_pk_bf16(o0[0], o0[1]); w[bj].y = cvt_pk_bf16(o0[2], o0[3]); w[bj].z = cvt_pk_bf16(o1[0], o1[1]); w[bj].w = cvt_pk_bf16(o1[2], o1[3]); }
;                 store_pair_lines(O, D, row, fr, col0, w[0], w[1]);
;                 if (ssout) { sq += __shfl_xor(sq, 16); sq += __shfl_xor(sq, 32); if (fq == 0) unsafeAtomicAdd(ssout + row, sq); } }
.LBB0_1487:
	v_mov_b32_e32 v91, v90
	v_mov_b32_e32 v84, v90
	v_mov_b32_e32 v85, v90
	s_waitcnt vmcnt(0) lgkmcnt(0)
	v_pk_fma_f32 v[70:71], v[70:71], v[84:85], v[74:75]
	v_pk_fma_f32 v[68:69], v[68:69], v[90:91], v[72:73]
	v_pk_fma_f32 v[64:65], v[64:65], v[90:91], v[76:77]
	v_pk_fma_f32 v[66:67], v[66:67], v[84:85], v[78:79]
	v_cvt_pk_bf16_f32 v68, v68, v69
	v_cvt_pk_bf16_f32 v69, v70, v71
	v_cvt_pk_bf16_f32 v70, v64, v65
	v_mov_b32_dpp v72, v80 row_ror:8 row_mask:0xf bank_mask:0xf
	v_mov_b32_dpp v73, v82 row_ror:8 row_mask:0xf bank_mask:0xf
	v_ashrrev_i32_e32 v89, 31, v88
	v_cvt_pk_bf16_f32 v71, v66, v67
	v_mov_b32_dpp v64, v68 row_ror:8 row_mask:0xf bank_mask:0xf
	v_mov_b32_dpp v65, v69 row_ror:8 row_mask:0xf bank_mask:0xf
	v_cndmask_b32_e64 v69, v69, v73, s[6:7]
	v_cndmask_b32_e64 v68, v68, v72, s[6:7]
	v_lshlrev_b64 v[72:73], 12, v[88:89]
	v_mov_b32_dpp v66, v70 row_ror:8 row_mask:0xf bank_mask:0xf
	v_mov_b32_dpp v67, v71 row_ror:8 row_mask:0xf bank_mask:0xf
	v_lshl_add_u64 v[72:73], s[12:13], 0, v[72:73]
	v_cndmask_b32_e64 v65, v65, v82, s[6:7]
	v_cndmask_b32_e64 v67, v67, v83, s[6:7]
	v_cndmask_b32_e64 v64, v64, v80, s[6:7]
	v_cndmask_b32_e64 v66, v66, v81, s[6:7]
	v_lshl_add_u64 v[72:73], v[154:155], 1, v[72:73]
	v_mov_b32_dpp v74, v81 row_ror:8 row_mask:0xf bank_mask:0xf
	v_mov_b32_dpp v75, v83 row_ror:8 row_mask:0xf bank_mask:0xf
	global_store_dwordx4 v[72:73], v[64:67], off
	v_cndmask_b32_e64 v71, v71, v75, s[6:7]
	v_cndmask_b32_e64 v70, v70, v74, s[6:7]
	v_add_co_u32_e32 v64, vcc, 0x8000, v72
	v_add_u32_e32 v74, 0x80, v158
	s_nop 0
	v_addc_co_u32_e32 v65, vcc, 0, v73, vcc
	global_store_dwordx4 v[64:65], v[68:71], off
	global_load_dword v80, v[160:161], off offset:512
	v_sub_u32_e32 v64, v74, v174
	s_and_b64 vcc, exec, s[8:9]
	v_add_u32_e32 v72, v64, v176
	s_cbranch_vccnz .LBB0_1489
	v_ashrrev_i32_e32 v73, 31, v72
	v_lshlrev_b64 v[64:65], 12, v[72:73]
	v_lshl_add_u64 v[64:65], s[16:17], 0, v[64:65]
	v_lshl_add_u64 v[68:69], v[154:155], 1, v[64:65]
	global_load_dwordx4 v[64:67], v[68:69], off
	v_add_co_u32_e32 v68, vcc, 0x8000, v68
	v_mov_b32_e32 v73, 0
	s_nop 0
	v_addc_co_u32_e32 v69, vcc, 0, v69, vcc
	global_load_dwordx4 v[68:71], v[68:69], off
	s_waitcnt vmcnt(1)
	v_mov_b32_dpp v73, v64 row_ror:8 row_mask:0xf bank_mask:0xf
	v_mov_b32_dpp v75, v65 row_ror:8 row_mask:0xf bank_mask:0xf
	v_mov_b32_dpp v76, v66 row_ror:8 row_mask:0xf bank_mask:0xf
	v_mov_b32_dpp v77, v67 row_ror:8 row_mask:0xf bank_mask:0xf
	s_waitcnt vmcnt(0)
	v_mov_b32_dpp v78, v68 row_ror:8 row_mask:0xf bank_mask:0xf
	v_mov_b32_dpp v79, v69 row_ror:8 row_mask:0xf bank_mask:0xf
	v_mov_b32_dpp v81, v70 row_ror:8 row_mask:0xf bank_mask:0xf
	v_mov_b32_dpp v82, v71 row_ror:8 row_mask:0xf bank_mask:0xf
	v_cndmask_b32_e64 v184, v68, v73, s[6:7]
	v_cndmask_b32_e64 v185, v69, v75, s[6:7]
	v_cndmask_b32_e64 v186, v70, v76, s[6:7]
	v_cndmask_b32_e64 v188, v78, v64, s[6:7]
	v_cndmask_b32_e64 v189, v79, v65, s[6:7]
	v_cndmask_b32_e64 v190, v81, v66, s[6:7]
	v_cndmask_b32_e64 v191, v82, v67, s[6:7]
	v_cndmask_b32_e64 v187, v71, v77, s[6:7]

; __device__ __forceinline__ void store_pair_lines(bf16_t* O, int ldc, int row, int fr, int col0, u32x4 wA, u32x4 wB) {
;     const u32x4 sA = {dpp_ror8(wA.x), dpp_ror8(wA.y), dpp_ror8(wA.z), dpp_ror8(wA.w)}, sB = {dpp_ror8(wB.x), dpp_ror8(wB.y), dpp_ror8(wB.z), dpp_ror8(wB.w)};
;     const bool lo = fr < 8;
;     const u32x4 o1 = lo ? wA : sB, o2 = lo ? sA : wB;
;     const int r1 = row - fr + (fr & 7), cb = col0 + (lo ? 0 : 8);
;     *(u32x4*)(O + (size_t)r1 * ldc + cb) = o1;
;     *(u32x4*)(O + (size_t)(r1 + 8) * ldc + cb) = o2;
; }
;     const bool lo = fr < 8;
;     const int r1 = row - fr + (fr & 7), cb = col0 + (lo ? 0 : boff);
;     const u32x4 l1 = *(const u32x4*)(P + (size_t)r1 * ld + cb), l2 = *(const u32x4*)(P + (size_t)(r1 + 8) * ld + cb);
;     __device__ __forceinline__ void operator()(const f32x4 (&acc)[2][2][4][2], const Unit& u, int wr, int wc, int fr, int fq) const {
;     ...
;             for (int m = 0; m < 4; ++m) { const int row = row0 + ai * HALF + m * 16; const size_t off = (size_t)row * D + col0; float sq = 0.f; u32x4 w[2];
;                 const float sc = rsin ? __builtin_amdgcn_rcpf(rsin[row] * (1.f / D) + EPS) : 1.0f;
;                 u32x4 rr[2]; if (R) load_pair_lines(R, D, row, fr, col0, rr[0], rr[1]);
; #pragma unroll
;                 for (int bj = 0; bj < 2; ++bj) { f32x4 r0, r1;
;                     if (R) { const u32x4 rw = rr[bj]; r0 = (f32x4){bflo(rw.x), bfhi(rw.x), bflo(rw.y), bfhi(rw.y)}; r1 = (f32x4){bflo(rw.z), bfhi(rw.z), bflo(rw.w), bfhi(rw.w)}; }
;                     else { const float* rp = (row < 8192 ? src_p + off : src_s + (off - (size_t)8192 * D)) + 8 * bj; r0 = *(const f32x4*)rp; r1 = *(const f32x4*)(rp + 4); }
;                     const f32x4 o0 = r0 + acc[ai][bj][m][0] * sc, o1 = r1 + acc[ai][bj][m][1] * sc;
;                     sq += (o0[0] * o0[0] + o0[1] * o0[1]) + (o0[2] * o0[2] + o0[3] * o0[3]) + (o1[0] * o1[0] + o1[1] * o1[1]) + (o1[2] * o1[2] + o1[3] * o1[3]);
;                     w[bj].x = cvt_pk_bf16(o0[0], o0[1]); w[bj].y = cvt_pk_bf16(o0[2], o0[3]); w[bj].z = cvt_pk_bf16(o1[0], o1[1]); w[bj].w = cvt_pk_bf16(o1[2], o1[3]); }
;                 store_pair_lines(O, D, row, fr, col0, w[0], w[1]);
;                 if (ssout) { sq += __shfl_xor(sq, 16); sq += __shfl_xor(sq, 32); if (fq == 0) unsafeAtomicAdd(ssout + row, sq); } }
.LBB0_1498:
	v_mov_b32_e32 v75, v74
	v_mov_b32_e32 v68, v74
	v_mov_b32_e32 v69, v74
	s_waitcnt vmcnt(0) lgkmcnt(0)
	v_pk_fma_f32 v[54:55], v[54:55], v[68:69], v[58:59]
	v_pk_fma_f32 v[52:53], v[52:53], v[74:75], v[56:57]
	v_pk_fma_f32 v[48:49], v[48:49], v[74:75], v[60:61]
	v_pk_fma_f32 v[50:51], v[50:51], v[68:69], v[62:63]
	v_cvt_pk_bf16_f32 v52, v52, v53
	v_cvt_pk_bf16_f32 v53, v54, v55
	v_cvt_pk_bf16_f32 v54, v48, v49
	v_mov_b32_dpp v56, v64 row_ror:8 row_mask:0xf bank_mask:0xf
	v_mov_b32_dpp v57, v66 row_ror:8 row_mask:0xf bank_mask:0xf
	v_ashrrev_i32_e32 v73, 31, v72
	v_cvt_pk_bf16_f32 v55, v50, v51
	v_mov_b32_dpp v48, v52 row_ror:8 row_mask:0xf bank_mask:0xf
	v_mov_b32_dpp v49, v53 row_ror:8 row_mask:0xf bank_mask:0xf
	v_cndmask_b32_e64 v53, v53, v57, s[6:7]
	v_cndmask_b32_e64 v52, v52, v56, s[6:7]
	v_lshlrev_b64 v[56:57], 12, v[72:73]
	v_mov_b32_dpp v50, v54 row_ror:8 row_mask:0xf bank_mask:0xf
	v_mov_b32_dpp v51, v55 row_ror:8 row_mask:0xf bank_mask:0xf
	v_lshl_add_u64 v[56:57], s[12:13], 0, v[56:57]
	v_cndmask_b32_e64 v49, v49, v66, s[6:7]
	v_cndmask_b32_e64 v51, v51, v67, s[6:7]
	v_cndmask_b32_e64 v48, v48, v64, s[6:7]
	v_cndmask_b32_e64 v50, v50, v65, s[6:7]
	v_lshl_add_u64 v[56:57], v[154:155], 1, v[56:57]
	v_mov_b32_dpp v58, v65 row_ror:8 row_mask:0xf bank_mask:0xf
	v_mov_b32_dpp v59, v67 row_ror:8 row_mask:0xf bank_mask:0xf
	global_store_dwordx4 v[56:57], v[48:51], off
	v_cndmask_b32_e64 v55, v55, v59, s[6:7]
	v_cndmask_b32_e64 v54, v54, v58, s[6:7]
	v_add_co_u32_e32 v48, vcc, 0x8000, v56
	v_add_u32_e32 v58, 0x90, v158
	s_nop 0
	v_addc_co_u32_e32 v49, vcc, 0, v57, vcc
	global_store_dwordx4 v[48:49], v[52:55], off
	global_load_dword v64, v[160:161], off offset:576
	v_sub_u32_e32 v48, v58, v174
	s_and_b64 vcc, exec, s[8:9]
	v_add_u32_e32 v56, v48, v176
	s_cbranch_vccnz .LBB0_1500
	v_ashrrev_i32_e32 v57, 31, v56
	v_lshlrev_b64 v[48:49], 12, v[56:57]
	v_lshl_add_u64 v[48:49], s[16:17], 0, v[48:49]
	v_lshl_add_u64 v[52:53], v[154:155], 1, v[48:49]
	global_load_dwordx4 v[48:51], v[52:53], off
	v_add_co_u32_e32 v52, vcc, 0x8000, v52
	v_mov_b32_e32 v57, 0
	s_nop 0
	v_addc_co_u32_e32 v53, vcc, 0, v53, vcc
	global_load_dwordx4 v[52:55], v[52:53], off
	s_waitcnt vmcnt(1)
	v_mov_b32_dpp v57, v48 row_ror:8 row_mask:0xf bank_mask:0xf
	v_mov_b32_dpp v59, v49 row_ror:8 row_mask:0xf bank_mask:0xf
	v_mov_b32_dpp v60, v50 row_ror:8 row_mask:0xf bank_mask:0xf
	v_mov_b32_dpp v61, v51 row_ror:8 row_mask:0xf bank_mask:0xf
	s_waitcnt vmcnt(0)
	v_mov_b32_dpp v62, v52 row_ror:8 row_mask:0xf bank_mask:0xf
	v_mov_b32_dpp v63, v53 row_ror:8 row_mask:0xf bank_mask:0xf
	v_mov_b32_dpp v65, v54 row_ror:8 row_mask:0xf bank_mask:0xf
	v_mov_b32_dpp v66, v55 row_ror:8 row_mask:0xf bank_mask:0xf
	v_cndmask_b32_e64 v184, v52, v57, s[6:7]
	v_cndmask_b32_e64 v185, v53, v59, s[6:7]
	v_cndmask_b32_e64 v186, v54, v60, s[6:7]
	v_cndmask_b32_e64 v188, v62, v48, s[6:7]
	v_cndmask_b32_e64 v189, v63, v49, s[6:7]
	v_cndmask_b32_e64 v190, v65, v50, s[6:7]
	v_cndmask_b32_e64 v191, v66, v51, s[6:7]
	v_cndmask_b32_e64 v187, v55, v61, s[6:7]

; __device__ __forceinline__ void store_pair_lines(bf16_t* O, int ldc, int row, int fr, int col0, u32x4 wA, u32x4 wB) {
;     const u32x4 sA = {dpp_ror8(wA.x), dpp_ror8(wA.y), dpp_ror8(wA.z), dpp_ror8(wA.w)}, sB = {dpp_ror8(wB.x), dpp_ror8(wB.y), dpp_ror8(wB.z), dpp_ror8(wB.w)};
;     const bool lo = fr < 8;
;     const u32x4 o1 = lo ? wA : sB, o2 = lo ? sA : wB;
;     const int r1 = row - fr + (fr & 7), cb = col0 + (lo ? 0 : 8);
;     *(u32x4*)(O + (size_t)r1 * ldc + cb) = o1;
;     *(u32x4*)(O + (size_t)(r1 + 8) * ldc + cb) = o2;
; }
;     const bool lo = fr < 8;
;     const int r1 = row - fr + (fr & 7), cb = col0 + (lo ? 0 : boff);
;     const u32x4 l1 = *(const u32x4*)(P + (size_t)r1 * ld + cb), l2 = *(const u32x4*)(P + (size_t)(r1 + 8) * ld + cb);
;     __device__ __forceinline__ void operator()(const f32x4 (&acc)[2][2][4][2], const Unit& u, int wr, int wc, int fr, int fq) const {
;     ...
;             for (int m = 0; m < 4; ++m) { const int row = row0 + ai * HALF + m * 16; const size_t off = (size_t)row * D + col0; float sq = 0.f; u32x4 w[2];
;                 const float sc = rsin ? __builtin_amdgcn_rcpf(rsin[row] * (1.f / D) + EPS) : 1.0f;
;                 u32x4 rr[2]; if (R) load_pair_lines(R, D, row, fr, col0, rr[0], rr[1]);
; #pragma unroll
;                 for (int bj = 0; bj < 2; ++bj) { f32x4 r0, r1;
;                     if (R) { const u32x4 rw = rr[bj]; r0 = (f32x4){bflo(rw.x), bfhi(rw.x), bflo(rw.y), bfhi(rw.y)}; r1 = (f32x4){bflo(rw.z), bfhi(rw.z), bflo(rw.w), bfhi(rw.w)}; }
;                     else { const float* rp = (row < 8192 ? src_p + off : src_s + (off - (size_t)8192 * D)) + 8 * bj; r0 = *(const f32x4*)rp; r1 = *(const f32x4*)(rp + 4); }
;                     const f32x4 o0 = r0 + acc[ai][bj][m][0] * sc, o1 = r1 + acc[ai][bj][m][1] * sc;
;                     sq += (o0[0] * o0[0] + o0[1] * o0[1]) + (o0[2] * o0[2] + o0[3] * o0[3]) + (o1[0] * o1[0] + o1[1] * o1[1]) + (o1[2] * o1[2] + o1[3] * o1[3]);
;                     w[bj].x = cvt_pk_bf16(o0[0], o0[1]); w[bj].y = cvt_pk_bf16(o0[2], o0[3]); w[bj].z = cvt_pk_bf16(o1[0], o1[1]); w[bj].w = cvt_pk_bf16(o1[2], o1[3]); }
;                 store_pair_lines(O, D, row, fr, col0, w[0], w[1]);
;                 if (ssout) { sq += __shfl_xor(sq, 16); sq += __shfl_xor(sq, 32); if (fq == 0) unsafeAtomicAdd(ssout + row, sq); } }
.LBB0_1509:
	v_mov_b32_e32 v59, v58
	v_mov_b32_e32 v52, v58
	v_mov_b32_e32 v53, v58
	s_waitcnt vmcnt(0) lgkmcnt(0)
	v_pk_fma_f32 v[38:39], v[38:39], v[52:53], v[42:43]
	v_pk_fma_f32 v[36:37], v[36:37], v[58:59], v[40:41]
	v_pk_fma_f32 v[32:33], v[32:33], v[58:59], v[44:45]
	v_pk_fma_f32 v[34:35], v[34:35], v[52:53], v[46:47]
	v_cvt_pk_bf16_f32 v36, v36, v37
	v_cvt_pk_bf16_f32 v37, v38, v39
	v_cvt_pk_bf16_f32 v38, v32, v33
	v_mov_b32_dpp v40, v48 row_ror:8 row_mask:0xf bank_mask:0xf
	v_mov_b32_dpp v41, v50 row_ror:8 row_mask:0xf bank_mask:0xf
	v_ashrrev_i32_e32 v57, 31, v56
	v_cvt_pk_bf16_f32 v39, v34, v35
	v_mov_b32_dpp v32, v36 row_ror:8 row_mask:0xf bank_mask:0xf
	v_mov_b32_dpp v33, v37 row_ror:8 row_mask:0xf bank_mask:0xf
	v_cndmask_b32_e64 v37, v37, v41, s[6:7]
	v_cndmask_b32_e64 v36, v36, v40, s[6:7]
	v_lshlrev_b64 v[40:41], 12, v[56:57]
	v_mov_b32_dpp v34, v38 row_ror:8 row_mask:0xf bank_mask:0xf
	v_mov_b32_dpp v35, v39 row_ror:8 row_mask:0xf bank_mask:0xf
	v_lshl_add_u64 v[40:41], s[12:13], 0, v[40:41]
	v_cndmask_b32_e64 v33, v33, v50, s[6:7]
	v_cndmask_b32_e64 v35, v35, v51, s[6:7]
	v_cndmask_b32_e64 v32, v32, v48, s[6:7]
	v_cndmask_b32_e64 v34, v34, v49, s[6:7]
	v_lshl_add_u64 v[40:41], v[154:155], 1, v[40:41]
	v_mov_b32_dpp v42, v49 row_ror:8 row_mask:0xf bank_mask:0xf
	v_mov_b32_dpp v43, v51 row_ror:8 row_mask:0xf bank_mask:0xf
	global_store_dwordx4 v[40:41], v[32:35], off
	v_cndmask_b32_e64 v39, v39, v43, s[6:7]
	v_cndmask_b32_e64 v38, v38, v42, s[6:7]
	v_add_co_u32_e32 v32, vcc, 0x8000, v40
	v_add_u32_e32 v42, 0xa0, v158
	s_nop 0
	v_addc_co_u32_e32 v33, vcc, 0, v41, vcc
	global_store_dwordx4 v[32:33], v[36:39], off
	global_load_dword v48, v[160:161], off offset:640
	v_sub_u32_e32 v32, v42, v174
	s_and_b64 vcc, exec, s[8:9]
	v_add_u32_e32 v40, v32, v176
	s_cbranch_vccnz .LBB0_1511
	v_ashrrev_i32_e32 v41, 31, v40
	v_lshlrev_b64 v[32:33], 12, v[40:41]
	v_lshl_add_u64 v[32:33], s[16:17], 0, v[32:33]
	v_lshl_add_u64 v[36:37], v[154:155], 1, v[32:33]
	global_load_dwordx4 v[32:35], v[36:37], off
	v_add_co_u32_e32 v36, vcc, 0x8000, v36
	v_mov_b32_e32 v41, 0
	s_nop 0
	v_addc_co_u32_e32 v37, vcc, 0, v37, vcc
	global_load_dwordx4 v[36:39], v[36:37], off
	s_waitcnt vmcnt(1)
	v_mov_b32_dpp v41, v32 row_ror:8 row_mask:0xf bank_mask:0xf
	v_mov_b32_dpp v43, v33 row_ror:8 row_mask:0xf bank_mask:0xf
	v_mov_b32_dpp v44, v34 row_ror:8 row_mask:0xf bank_mask:0xf
	v_mov_b32_dpp v45, v35 row_ror:8 row_mask:0xf bank_mask:0xf
	s_waitcnt vmcnt(0)
	v_mov_b32_dpp v46, v36 row_ror:8 row_mask:0xf bank_mask:0xf
	v_mov_b32_dpp v47, v37 row_ror:8 row_mask:0xf bank_mask:0xf
	v_mov_b32_dpp v49, v38 row_ror:8 row_mask:0xf bank_mask:0xf
	v_mov_b32_dpp v50, v39 row_ror:8 row_mask:0xf bank_mask:0xf
	v_cndmask_b32_e64 v184, v36, v41, s[6:7]
	v_cndmask_b32_e64 v185, v37, v43, s[6:7]
	v_cndmask_b32_e64 v186, v38, v44, s[6:7]
	v_cndmask_b32_e64 v188, v46, v32, s[6:7]
	v_cndmask_b32_e64 v189, v47, v33, s[6:7]
	v_cndmask_b32_e64 v190, v49, v34, s[6:7]
	v_cndmask_b32_e64 v191, v50, v35, s[6:7]
	v_cndmask_b32_e64 v187, v39, v45, s[6:7]

; __device__ __forceinline__ void store_pair_lines(bf16_t* O, int ldc, int row, int fr, int col0, u32x4 wA, u32x4 wB) {
;     const u32x4 sA = {dpp_ror8(wA.x), dpp_ror8(wA.y), dpp_ror8(wA.z), dpp_ror8(wA.w)}, sB = {dpp_ror8(wB.x), dpp_ror8(wB.y), dpp_ror8(wB.z), dpp_ror8(wB.w)};
;     const bool lo = fr < 8;
;     const u32x4 o1 = lo ? wA : sB, o2 = lo ? sA : wB;
;     const int r1 = row - fr + (fr & 7), cb = col0 + (lo ? 0 : 8);
;     *(u32x4*)(O + (size_t)r1 * ldc + cb) = o1;
;     *(u32x4*)(O + (size_t)(r1 + 8) * ldc + cb) = o2;
; }
;     const bool lo = fr < 8;
;     const int r1 = row - fr + (fr & 7), cb = col0 + (lo ? 0 : boff);
;     const u32x4 l1 = *(const u32x4*)(P + (size_t)r1 * ld + cb), l2 = *(const u32x4*)(P + (size_t)(r1 + 8) * ld + cb);
;     __device__ __forceinline__ void operator()(const f32x4 (&acc)[2][2][4][2], const Unit& u, int wr, int wc, int fr, int fq) const {
;     ...
;             for (int m = 0; m < 4; ++m) { const int row = row0 + ai * HALF + m * 16; const size_t off = (size_t)row * D + col0; float sq = 0.f; u32x4 w[2];
;                 const float sc = rsin ? __builtin_amdgcn_rcpf(rsin[row] * (1.f / D) + EPS) : 1.0f;
;                 u32x4 rr[2]; if (R) load_pair_lines(R, D, row, fr, col0, rr[0], rr[1]);
; #pragma unroll
;                 for (int bj = 0; bj < 2; ++bj) { f32x4 r0, r1;
;                     if (R) { const u32x4 rw = rr[bj]; r0 = (f32x4){bflo(rw.x), bfhi(rw.x), bflo(rw.y), bfhi(rw.y)}; r1 = (f32x4){bflo(rw.z), bfhi(rw.z), bflo(rw.w), bfhi(rw.w)}; }
;                     else { const float* rp = (row < 8192 ? src_p + off : src_s + (off - (size_t)8192 * D)) + 8 * bj; r0 = *(const f32x4*)rp; r1 = *(const f32x4*)(rp + 4); }
;                     const f32x4 o0 = r0 + acc[ai][bj][m][0] * sc, o1 = r1 + acc[ai][bj][m][1] * sc;
;                     sq += (o0[0] * o0[0] + o0[1] * o0[1]) + (o0[2] * o0[2] + o0[3] * o0[3]) + (o1[0] * o1[0] + o1[1] * o1[1]) + (o1[2] * o1[2] + o1[3] * o1[3]);
;                     w[bj].x = cvt_pk_bf16(o0[0], o0[1]); w[bj].y = cvt_pk_bf16(o0[2], o0[3]); w[bj].z = cvt_pk_bf16(o1[0], o1[1]); w[bj].w = cvt_pk_bf16(o1[2], o1[3]); }
;                 store_pair_lines(O, D, row, fr, col0, w[0], w[1]);
;                 if (ssout) { sq += __shfl_xor(sq, 16); sq += __shfl_xor(sq, 32); if (fq == 0) unsafeAtomicAdd(ssout + row, sq); } }
.LBB0_1520:
	v_mov_b32_e32 v43, v42
	v_mov_b32_e32 v36, v42
	v_mov_b32_e32 v37, v42
	s_waitcnt vmcnt(0) lgkmcnt(0)
	v_pk_fma_f32 v[22:23], v[22:23], v[36:37], v[26:27]
	v_pk_fma_f32 v[20:21], v[20:21], v[42:43], v[24:25]
	v_pk_fma_f32 v[16:17], v[16:17], v[42:43], v[28:29]
	v_pk_fma_f32 v[18:19], v[18:19], v[36:37], v[30:31]
	v_cvt_pk_bf16_f32 v20, v20, v21
	v_cvt_pk_bf16_f32 v21, v22, v23
	v_cvt_pk_bf16_f32 v22, v16, v17
	v_mov_b32_dpp v24, v32 row_ror:8 row_mask:0xf bank_mask:0xf
	v_mov_b32_dpp v25, v34 row_ror:8 row_mask:0xf bank_mask:0xf
	v_ashrrev_i32_e32 v41, 31, v40
	v_cvt_pk_bf16_f32 v23, v18, v19
	v_mov_b32_dpp v16, v20 row_ror:8 row_mask:0xf bank_mask:0xf
	v_mov_b32_dpp v17, v21 row_ror:8 row_mask:0xf bank_mask:0xf
	v_cndmask_b32_e64 v21, v21, v25, s[6:7]
	v_cndmask_b32_e64 v20, v20, v24, s[6:7]
	v_lshlrev_b64 v[24:25], 12, v[40:41]
	v_mov_b32_dpp v18, v22 row_ror:8 row_mask:0xf bank_mask:0xf
	v_mov_b32_dpp v19, v23 row_ror:8 row_mask:0xf bank_mask:0xf
	v_lshl_add_u64 v[24:25], s[12:13], 0, v[24:25]
	v_cndmask_b32_e64 v17, v17, v34, s[6:7]
	v_cndmask_b32_e64 v19, v19, v35, s[6:7]
	v_cndmask_b32_e64 v16, v16, v32, s[6:7]
	v_cndmask_b32_e64 v18, v18, v33, s[6:7]
	v_lshl_add_u64 v[24:25], v[154:155], 1, v[24:25]
	v_mov_b32_dpp v26, v33 row_ror:8 row_mask:0xf bank_mask:0xf
	v_mov_b32_dpp v27, v35 row_ror:8 row_mask:0xf bank_mask:0xf
	global_store_dwordx4 v[24:25], v[16:19], off
	v_cndmask_b32_e64 v23, v23, v27, s[6:7]
	v_cndmask_b32_e64 v22, v22, v26, s[6:7]
	v_add_co_u32_e32 v16, vcc, 0x8000, v24
	v_add_u32_e32 v26, 0xb0, v158
	s_nop 0
	v_addc_co_u32_e32 v17, vcc, 0, v25, vcc
	global_store_dwordx4 v[16:17], v[20:23], off
	global_load_dword v32, v[160:161], off offset:704
	v_sub_u32_e32 v16, v26, v174
	s_and_b64 vcc, exec, s[8:9]
	v_add_u32_e32 v24, v16, v176
	s_cbranch_vccnz .LBB0_1522
	v_ashrrev_i32_e32 v25, 31, v24
	v_lshlrev_b64 v[16:17], 12, v[24:25]
	v_lshl_add_u64 v[16:17], s[16:17], 0, v[16:17]
	v_lshl_add_u64 v[20:21], v[154:155], 1, v[16:17]
	global_load_dwordx4 v[16:19], v[20:21], off
	v_add_co_u32_e32 v20, vcc, 0x8000, v20
	v_mov_b32_e32 v25, 0
	s_nop 0
	v_addc_co_u32_e32 v21, vcc, 0, v21, vcc
	global_load_dwordx4 v[20:23], v[20:21], off
	s_waitcnt vmcnt(1)
	v_mov_b32_dpp v25, v16 row_ror:8 row_mask:0xf bank_mask:0xf
	v_mov_b32_dpp v27, v17 row_ror:8 row_mask:0xf bank_mask:0xf
	v_mov_b32_dpp v28, v18 row_ror:8 row_mask:0xf bank_mask:0xf
	v_mov_b32_dpp v29, v19 row_ror:8 row_mask:0xf bank_mask:0xf
	s_waitcnt vmcnt(0)
	v_mov_b32_dpp v30, v20 row_ror:8 row_mask:0xf bank_mask:0xf
	v_mov_b32_dpp v31, v21 row_ror:8 row_mask:0xf bank_mask:0xf
	v_mov_b32_dpp v33, v22 row_ror:8 row_mask:0xf bank_mask:0xf
	v_mov_b32_dpp v34, v23 row_ror:8 row_mask:0xf bank_mask:0xf
	v_cndmask_b32_e64 v184, v20, v25, s[6:7]
	v_cndmask_b32_e64 v185, v21, v27, s[6:7]
	v_cndmask_b32_e64 v186, v22, v28, s[6:7]
	v_cndmask_b32_e64 v188, v30, v16, s[6:7]
	v_cndmask_b32_e64 v189, v31, v17, s[6:7]
	v_cndmask_b32_e64 v190, v33, v18, s[6:7]
	v_cndmask_b32_e64 v191, v34, v19, s[6:7]
	v_cndmask_b32_e64 v187, v23, v29, s[6:7]

; #define PG8_STAGE(bufoff, gbase, voff) do { _Pragma("unroll") for (int _i = 0; _i < 2; ++_i) \
;         __builtin_amdgcn_global_load_lds((const unsigned*)((const char*)(gbase) + (voff)[_i]), (LAS unsigned*)(lds + (bufoff) + ldsw + _i * 8192), 16, 0, 0); } while (0)
; #define PG8_LDA(dst, b, h) do { _Pragma("unroll") for (int m = 0; m < 4; ++m) _Pragma("unroll") for (int k = 0; k < 2; ++k) dst[m][k] = *(const LAS bf16x8*)(lds + PG8_SA(b, h) + aoff + m * 2048 + k * 1024); } while (0)
; #define PG8_LDB(dst, b, h) do { _Pragma("unroll") for (int n = 0; n < 2; ++n) _Pragma("unroll") for (int k = 0; k < 2; ++k) dst[n][k] = *(const LAS bf16x8*)(lds + PG8_SB(b, h) + boff + n * 2048 + k * 1024); } while (0)
; #define PG8_WAIT_V(n) asm volatile("s_waitcnt vmcnt(" #n ")" ::: "memory")
; #define PG8_WAIT_L(n) asm volatile("s_waitcnt lgkmcnt(" #n ")" ::: "memory")
; #define PG8_BAR __builtin_amdgcn_s_barrier()
; #define PG8_SCHED __builtin_amdgcn_sched_barrier(0)
; template <class Epi>
; __device__ __forceinline__ void gemm_phase(LAS unsigned char* lds, const Gemm g, const StaticOrder& S, const Epi& E) {
;     ...
;             PG8_LDB(B0, 0, 0); PG8_SCHED; PG8_LDA(At, 0, 0); PG8_STAGE(PG8_SA(1, 1), a1 + hstep, voffA);
;             PG8_WAIT_L(8); PG8_BAR; PG8_WAIT_L(0); PG8_MMA(0, 0, At, B0); PG8_BAR; PG8_SCHED;
;             PG8_LDB(B1, 0, 1); PG8_STAGE(PG8_SB(0, 0), b2, voffB0);
;             PG8_BAR; PG8_WAIT_L(0); PG8_MMA(0, 1, At, B1); PG8_BAR;
;             PG8_LDA(At, 0, 1); PG8_STAGE(PG8_SA(0, 0), a2, voffA);
;             PG8_BAR; PG8_WAIT_L(0); PG8_MMA(1, 0, At, B0); PG8_BAR; PG8_SCHED;
;             PG8_STAGE(PG8_SB(0, 1), b2, voffB1);
;             PG8_WAIT_V(6); PG8_BAR; PG8_MMA(1, 1, At, B1); PG8_BAR;
;             PG8_LDB(B0, 1, 0); PG8_SCHED; PG8_LDA(At, 1, 0); PG8_STAGE(PG8_SA(0, 1), a2 + hstep, voffA);
;             PG8_WAIT_L(8); PG8_BAR; PG8_WAIT_L(0); PG8_MMA(0, 0, At, B0); PG8_BAR; PG8_SCHED;
;             PG8_LDB(B1, 1, 1); PG8_STAGE(PG8_SB(1, 0), b3, voffB0);
;             PG8_BAR; PG8_WAIT_L(0); PG8_MMA(0, 1, At, B1); PG8_BAR;
;             PG8_LDA(At, 1, 1); PG8_STAGE(PG8_SA(1, 0), a3, voffA);
;             PG8_BAR; PG8_WAIT_L(0); PG8_MMA(1, 0, At, B0); PG8_BAR; PG8_SCHED;
;             PG8_STAGE(PG8_SB(1, 1), b3, voffB1);
;             PG8_WAIT_V(6); PG8_BAR; PG8_MMA(1, 1, At, B1); PG8_BAR;
.LBB0_1603:
	ds_read_b128 v[40:43], v179
	ds_read_b128 v[44:47], v179 offset:1024
	ds_read_b128 v[56:59], v179 offset:2048
	ds_read_b128 v[60:63], v179 offset:3072
	s_add_u32 s36, s34, 0xfff80080
	s_addc_u32 s37, s35, -1
	s_cmp_eq_u32 s58, 28
	s_cselect_b32 s37, s23, s37
	s_cselect_b32 s36, s54, s36
	s_cselect_b32 s39, s19, s57
	s_cselect_b32 s38, s55, s56
	v_lshl_add_u64 v[172:173], s[34:35], 0, v[158:159]
	s_add_i32 m0, s31, 0xc000
	ds_read_b128 v[164:167], v180
	ds_read_b128 v[168:171], v180 offset:1024
	ds_read_b128 v[184:187], v180 offset:2048
	ds_read_b128 v[188:191], v180 offset:3072
	ds_read_b128 v[192:195], v180 offset:4096
	ds_read_b128 v[196:199], v180 offset:5120
	ds_read_b128 v[200:203], v180 offset:6144
	ds_read_b128 v[204:207], v180 offset:7168
	global_load_lds_dwordx4 v[172:173], off
	v_lshl_add_u64 v[172:173], s[34:35], 0, v[160:161]
	s_add_i32 m0, s31, 0xe000
	s_nop 0
	global_load_lds_dwordx4 v[172:173], off
	s_waitcnt lgkmcnt(8)
	s_barrier
	s_waitcnt lgkmcnt(0)
	v_mfma_f32_16x16x32_bf16 v[140:143], v[40:43], v[164:167], v[140:143]
	v_mfma_f32_16x16x32_bf16 v[136:139], v[56:59], v[164:167], v[136:139]
	v_mfma_f32_16x16x32_bf16 v[124:127], v[40:43], v[184:187], v[124:127]
	v_mfma_f32_16x16x32_bf16 v[120:123], v[56:59], v[184:187], v[120:123]
	v_mfma_f32_16x16x32_bf16 v[108:111], v[40:43], v[192:195], v[108:111]
	v_mfma_f32_16x16x32_bf16 v[104:107], v[56:59], v[192:195], v[104:107]
	v_mfma_f32_16x16x32_bf16 v[92:95], v[40:43], v[200:203], v[92:95]
	v_mfma_f32_16x16x32_bf16 v[88:91], v[56:59], v[200:203], v[88:91]
	v_mfma_f32_16x16x32_bf16 v[140:143], v[44:47], v[168:171], v[140:143]
	v_mfma_f32_16x16x32_bf16 v[136:139], v[60:63], v[168:171], v[136:139]
	v_mfma_f32_16x16x32_bf16 v[124:127], v[44:47], v[188:191], v[124:127]
	v_mfma_f32_16x16x32_bf16 v[120:123], v[60:63], v[188:191], v[120:123]
	v_mfma_f32_16x16x32_bf16 v[108:111], v[44:47], v[196:199], v[108:111]
	v_mfma_f32_16x16x32_bf16 v[104:107], v[60:63], v[196:199], v[104:107]
	v_mfma_f32_16x16x32_bf16 v[92:95], v[44:47], v[204:207], v[92:95]
	v_mfma_f32_16x16x32_bf16 v[88:91], v[60:63], v[204:207], v[88:91]
	s_barrier
	s_add_i32 s59, s51, s41
	v_lshl_add_u64 v[172:173], s[38:39], 0, v[146:147]
	s_mov_b32 m0, s59
	ds_read_b128 v[208:211], v181
	ds_read_b128 v[212:215], v181 offset:1024
	ds_read_b128 v[216:219], v181 offset:2048
	ds_read_b128 v[220:223], v181 offset:3072
	global_load_lds_dwordx4 v[172:173], off
	v_lshl_add_u64 v[224:225], s[38:39], 0, v[152:153]
	s_add_i32 m0, s59, 0x2000
	s_nop 0
	global_load_lds_dwordx4 v[224:225], off
	s_barrier
	s_waitcnt lgkmcnt(0)
	v_mfma_f32_16x16x32_bf16 v[132:135], v[208:211], v[164:167], v[132:135]
	v_mfma_f32_16x16x32_bf16 v[128:131], v[216:219], v[164:167], v[128:131]
	v_mfma_f32_16x16x32_bf16 v[116:119], v[208:211], v[184:187], v[116:119]
	v_mfma_f32_16x16x32_bf16 v[112:115], v[216:219], v[184:187], v[112:115]
	v_mfma_f32_16x16x32_bf16 v[100:103], v[208:211], v[192:195], v[100:103]
	v_mfma_f32_16x16x32_bf16 v[96:99], v[216:219], v[192:195], v[96:99]
	v_mfma_f32_16x16x32_bf16 v[84:87], v[208:211], v[200:203], v[84:87]
	v_mfma_f32_16x16x32_bf16 v[80:83], v[216:219], v[200:203], v[80:83]
	v_mfma_f32_16x16x32_bf16 v[132:135], v[212:215], v[168:171], v[132:135]
	v_mfma_f32_16x16x32_bf16 v[128:131], v[220:223], v[168:171], v[128:131]
	v_mfma_f32_16x16x32_bf16 v[116:119], v[212:215], v[188:191], v[116:119]
	v_mfma_f32_16x16x32_bf16 v[112:115], v[220:223], v[188:191], v[112:115]
	v_mfma_f32_16x16x32_bf16 v[100:103], v[212:215], v[196:199], v[100:103]
	v_mfma_f32_16x16x32_bf16 v[96:99], v[220:223], v[196:199], v[96:99]
	v_mfma_f32_16x16x32_bf16 v[84:87], v[212:215], v[204:207], v[84:87]
	v_mfma_f32_16x16x32_bf16 v[80:83], v[220:223], v[204:207], v[80:83]
	s_mov_b32 m0, s31
	v_lshl_add_u64 v[226:227], s[36:37], 0, v[144:145]
	s_barrier
	ds_read_b128 v[164:167], v180 offset:16384
	ds_read_b128 v[168:171], v180 offset:17408
	ds_read_b128 v[184:187], v180 offset:18432
	ds_read_b128 v[188:191], v180 offset:19456
	ds_read_b128 v[192:195], v180 offset:20480
	ds_read_b128 v[196:199], v180 offset:21504
	ds_read_b128 v[200:203], v180 offset:22528
	ds_read_b128 v[204:207], v180 offset:23552
	global_load_lds_dwordx4 v[226:227], off
	v_lshl_add_u64 v[228:229], s[36:37], 0, v[150:151]
	s_mov_b32 m0, s42
	s_nop 0
	global_load_lds_dwordx4 v[228:229], off
	s_barrier
	s_waitcnt lgkmcnt(0)
	v_mfma_f32_16x16x32_bf16 v[76:79], v[40:43], v[164:167], v[76:79]
	v_mfma_f32_16x16x32_bf16 v[72:75], v[56:59], v[164:167], v[72:75]
	v_mfma_f32_16x16x32_bf16 v[52:55], v[40:43], v[184:187], v[52:55]
	v_mfma_f32_16x16x32_bf16 v[48:51], v[56:59], v[184:187], v[48:51]
	v_mfma_f32_16x16x32_bf16 v[28:31], v[40:43], v[192:195], v[28:31]
	v_mfma_f32_16x16x32_bf16 v[24:27], v[56:59], v[192:195], v[24:27]
	v_mfma_f32_16x16x32_bf16 v[12:15], v[40:43], v[200:203], v[12:15]
	v_mfma_f32_16x16x32_bf16 v[8:11], v[56:59], v[200:203], v[8:11]
	v_mfma_f32_16x16x32_bf16 v[76:79], v[44:47], v[168:171], v[76:79]
	v_mfma_f32_16x16x32_bf16 v[72:75], v[60:63], v[168:171], v[72:75]
	v_mfma_f32_16x16x32_bf16 v[52:55], v[44:47], v[188:191], v[52:55]
	v_mfma_f32_16x16x32_bf16 v[48:51], v[60:63], v[188:191], v[48:51]
	v_mfma_f32_16x16x32_bf16 v[28:31], v[44:47], v[196:199], v[28:31]
	v_mfma_f32_16x16x32_bf16 v[24:27], v[60:63], v[196:199], v[24:27]
	v_mfma_f32_16x16x32_bf16 v[12:15], v[44:47], v[204:207], v[12:15]
	v_mfma_f32_16x16x32_bf16 v[8:11], v[60:63], v[204:207], v[8:11]
	s_barrier
	s_add_i32 s59, s52, s41
	v_lshl_add_u64 v[230:231], s[38:39], 0, v[148:149]
	s_mov_b32 m0, s59
	v_lshl_add_u64 v[232:233], s[38:39], 0, v[154:155]
	global_load_lds_dwordx4 v[230:231], off
	s_add_i32 m0, s59, 0x2000
	s_nop 0
	global_load_lds_dwordx4 v[232:233], off
	s_waitcnt vmcnt(6)
	s_barrier
; #define PG8_STAGE(bufoff, gbase, voff) do { _Pragma("unroll") for (int _i = 0; _i < 2; ++_i) \
;         __builtin_amdgcn_global_load_lds((const unsigned*)((const char*)(gbase) + (voff)[_i]), (LAS unsigned*)(lds + (bufoff) + ldsw + _i * 8192), 16, 0, 0); } while (0)
; #define PG8_LDA(dst, b, h) do { _Pragma("unroll") for (int m = 0; m < 4; ++m) _Pragma("unroll") for (int k = 0; k < 2; ++k) dst[m][k] = *(const LAS bf16x8*)(lds + PG8_SA(b, h) + aoff + m * 2048 + k * 1024); } while (0)
; #define PG8_LDB(dst, b, h) do { _Pragma("unroll") for (int n = 0; n < 2; ++n) _Pragma("unroll") for (int k = 0; k < 2; ++k) dst[n][k] = *(const LAS bf16x8*)(lds + PG8_SB(b, h) + boff + n * 2048 + k * 1024); } while (0)
; #define PG8_WAIT_V(n) asm volatile("s_waitcnt vmcnt(" #n ")" ::: "memory")
; #define PG8_WAIT_L(n) asm volatile("s_waitcnt lgkmcnt(" #n ")" ::: "memory")
; #define PG8_BAR __builtin_amdgcn_s_barrier()
; #define PG8_SCHED __builtin_amdgcn_sched_barrier(0)
; template <class Epi>
; __device__ __forceinline__ void gemm_phase(LAS unsigned char* lds, const Gemm g, const StaticOrder& S, const Epi& E) {
;     ...
;             PG8_LDB(B0, 0, 0); PG8_SCHED; PG8_LDA(At, 0, 0); PG8_STAGE(PG8_SA(1, 1), a1 + hstep, voffA);
;             PG8_WAIT_L(8); PG8_BAR; PG8_WAIT_L(0); PG8_MMA(0, 0, At, B0); PG8_BAR; PG8_SCHED;
;             PG8_LDB(B1, 0, 1); PG8_STAGE(PG8_SB(0, 0), b2, voffB0);
;             PG8_BAR; PG8_WAIT_L(0); PG8_MMA(0, 1, At, B1); PG8_BAR;
;             PG8_LDA(At, 0, 1); PG8_STAGE(PG8_SA(0, 0), a2, voffA);
;             PG8_BAR; PG8_WAIT_L(0); PG8_MMA(1, 0, At, B0); PG8_BAR; PG8_SCHED;
;             PG8_STAGE(PG8_SB(0, 1), b2, voffB1);
;             PG8_WAIT_V(6); PG8_BAR; PG8_MMA(1, 1, At, B1); PG8_BAR;
;             PG8_LDB(B0, 1, 0); PG8_SCHED; PG8_LDA(At, 1, 0); PG8_STAGE(PG8_SA(0, 1), a2 + hstep, voffA);
;             PG8_WAIT_L(8); PG8_BAR; PG8_WAIT_L(0); PG8_MMA(0, 0, At, B0); PG8_BAR; PG8_SCHED;
;             PG8_LDB(B1, 1, 1); PG8_STAGE(PG8_SB(1, 0), b3, voffB0);
;             PG8_BAR; PG8_WAIT_L(0); PG8_MMA(0, 1, At, B1); PG8_BAR;
;             PG8_LDA(At, 1, 1); PG8_STAGE(PG8_SA(1, 0), a3, voffA);
;             PG8_BAR; PG8_WAIT_L(0); PG8_MMA(1, 0, At, B0); PG8_BAR; PG8_SCHED;
;             PG8_STAGE(PG8_SB(1, 1), b3, voffB1);
;             PG8_WAIT_V(6); PG8_BAR; PG8_MMA(1, 1, At, B1); PG8_BAR;
	v_mfma_f32_16x16x32_bf16 v[36:39], v[208:211], v[184:187], v[36:39]
	v_mfma_f32_16x16x32_bf16 v[32:35], v[216:219], v[184:187], v[32:35]
	v_mfma_f32_16x16x32_bf16 v[20:23], v[208:211], v[192:195], v[20:23]
	v_mfma_f32_16x16x32_bf16 v[16:19], v[216:219], v[192:195], v[16:19]
	v_mfma_f32_16x16x32_bf16 v[4:7], v[208:211], v[200:203], v[4:7]
	v_mfma_f32_16x16x32_bf16 v[0:3], v[216:219], v[200:203], v[0:3]
	v_mfma_f32_16x16x32_bf16 v[40:43], v[208:211], v[164:167], v[68:71]
	v_mfma_f32_16x16x32_bf16 v[44:47], v[216:219], v[164:167], v[64:67]
	v_mfma_f32_16x16x32_bf16 v[36:39], v[212:215], v[188:191], v[36:39]
	v_mfma_f32_16x16x32_bf16 v[32:35], v[220:223], v[188:191], v[32:35]
	v_mfma_f32_16x16x32_bf16 v[20:23], v[212:215], v[196:199], v[20:23]
	v_mfma_f32_16x16x32_bf16 v[16:19], v[220:223], v[196:199], v[16:19]
	v_mfma_f32_16x16x32_bf16 v[4:7], v[212:215], v[204:207], v[4:7]
	v_mfma_f32_16x16x32_bf16 v[0:3], v[220:223], v[204:207], v[0:3]
	v_mfma_f32_16x16x32_bf16 v[40:43], v[212:215], v[168:171], v[40:43]
	v_mfma_f32_16x16x32_bf16 v[44:47], v[220:223], v[168:171], v[44:47]
	s_add_i32 s38, 0, 0x18000
	v_add_u32_e32 v68, s38, v175
	s_barrier
	ds_read_b128 v[56:59], v68
	ds_read_b128 v[60:63], v68 offset:1024
	ds_read_b128 v[64:67], v68 offset:2048
	ds_read_b128 v[68:71], v68 offset:3072
	s_add_u32 s36, s36, 0x80000
	s_addc_u32 s37, s37, 0
	s_mov_b32 m0, s43
	v_lshl_add_u64 v[208:209], s[36:37], 0, v[144:145]
	ds_read_b128 v[164:167], v180 offset:32768
	ds_read_b128 v[168:171], v180 offset:33792
	ds_read_b128 v[184:187], v180 offset:34816
	ds_read_b128 v[188:191], v180 offset:35840
	ds_read_b128 v[192:195], v180 offset:36864
	ds_read_b128 v[196:199], v180 offset:37888
	ds_read_b128 v[200:203], v180 offset:38912
	ds_read_b128 v[204:207], v180 offset:39936
	global_load_lds_dwordx4 v[208:209], off
	v_lshl_add_u64 v[208:209], s[36:37], 0, v[150:151]
	s_mov_b32 m0, s44
	s_nop 0
	global_load_lds_dwordx4 v[208:209], off
	s_waitcnt lgkmcnt(8)
	s_barrier
	s_waitcnt lgkmcnt(0)
	v_mfma_f32_16x16x32_bf16 v[140:143], v[56:59], v[164:167], v[140:143]
	v_mfma_f32_16x16x32_bf16 v[136:139], v[64:67], v[164:167], v[136:139]
	v_mfma_f32_16x16x32_bf16 v[124:127], v[56:59], v[184:187], v[124:127]
	v_mfma_f32_16x16x32_bf16 v[120:123], v[64:67], v[184:187], v[120:123]
	v_mfma_f32_16x16x32_bf16 v[108:111], v[56:59], v[192:195], v[108:111]
	v_mfma_f32_16x16x32_bf16 v[104:107], v[64:67], v[192:195], v[104:107]
	v_mfma_f32_16x16x32_bf16 v[92:95], v[56:59], v[200:203], v[92:95]
	v_mfma_f32_16x16x32_bf16 v[88:91], v[64:67], v[200:203], v[88:91]
	v_mfma_f32_16x16x32_bf16 v[140:143], v[60:63], v[168:171], v[140:143]
	v_mfma_f32_16x16x32_bf16 v[136:139], v[68:71], v[168:171], v[136:139]
	v_mfma_f32_16x16x32_bf16 v[124:127], v[60:63], v[188:191], v[124:127]
	v_mfma_f32_16x16x32_bf16 v[120:123], v[68:71], v[188:191], v[120:123]
	v_mfma_f32_16x16x32_bf16 v[108:111], v[60:63], v[196:199], v[108:111]
	v_mfma_f32_16x16x32_bf16 v[104:107], v[68:71], v[196:199], v[104:107]
	v_mfma_f32_16x16x32_bf16 v[92:95], v[60:63], v[204:207], v[92:95]
	v_mfma_f32_16x16x32_bf16 v[88:91], v[68:71], v[204:207], v[88:91]
	s_barrier
	s_add_i32 s36, 0, 0x1c000
	s_add_i32 s37, s38, s41
	v_add_u32_e32 v183, s36, v175
	v_lshl_add_u64 v[172:173], v[172:173], 0, s[14:15]
	s_mov_b32 m0, s37
	ds_read_b128 v[208:211], v183
	ds_read_b128 v[212:215], v183 offset:1024
	ds_read_b128 v[216:219], v183 offset:2048
	ds_read_b128 v[220:223], v183 offset:3072
	global_load_lds_dwordx4 v[172:173], off
	v_lshl_add_u64 v[172:173], v[224:225], 0, s[14:15]
	s_add_i32 m0, s37, 0x2000
	s_nop 0
	global_load_lds_dwordx4 v[172:173], off
	s_barrier
	s_waitcnt lgkmcnt(0)
	v_mfma_f32_16x16x32_bf16 v[132:135], v[208:211], v[164:167], v[132:135]
	v_mfma_f32_16x16x32_bf16 v[128:131], v[216:219], v[164:167], v[128:131]
	v_mfma_f32_16x16x32_bf16 v[116:119], v[208:211], v[184:187], v[116:119]
	v_mfma_f32_16x16x32_bf16 v[112:115], v[216:219], v[184:187], v[112:115]
	v_mfma_f32_16x16x32_bf16 v[100:103], v[208:211], v[192:195], v[100:103]
	v_mfma_f32_16x16x32_bf16 v[96:99], v[216:219], v[192:195], v[96:99]
	v_mfma_f32_16x16x32_bf16 v[84:87], v[208:211], v[200:203], v[84:87]
	v_mfma_f32_16x16x32_bf16 v[80:83], v[216:219], v[200:203], v[80:83]
	v_mfma_f32_16x16x32_bf16 v[132:135], v[212:215], v[168:171], v[132:135]
	v_mfma_f32_16x16x32_bf16 v[128:131], v[220:223], v[168:171], v[128:131]
	v_mfma_f32_16x16x32_bf16 v[116:119], v[212:215], v[188:191], v[116:119]
	v_mfma_f32_16x16x32_bf16 v[112:115], v[220:223], v[188:191], v[112:115]
	v_mfma_f32_16x16x32_bf16 v[100:103], v[212:215], v[196:199], v[100:103]
	v_mfma_f32_16x16x32_bf16 v[96:99], v[220:223], v[196:199], v[96:99]
	v_mfma_f32_16x16x32_bf16 v[84:87], v[212:215], v[204:207], v[84:87]
	v_mfma_f32_16x16x32_bf16 v[80:83], v[220:223], v[204:207], v[80:83]
	s_mov_b32 m0, s47
	v_lshl_add_u64 v[172:173], v[226:227], 0, s[14:15]
	s_barrier
	ds_read_b128 v[164:167], v180 offset:49152
	ds_read_b128 v[168:171], v180 offset:50176
	ds_read_b128 v[184:187], v180 offset:51200
	ds_read_b128 v[188:191], v180 offset:52224
	ds_read_b128 v[192:195], v180 offset:53248
	ds_read_b128 v[196:199], v180 offset:54272
	ds_read_b128 v[200:203], v180 offset:55296
	ds_read_b128 v[204:207], v180 offset:56320
	global_load_lds_dwordx4 v[172:173], off
	v_lshl_add_u64 v[172:173], v[228:229], 0, s[14:15]
	s_mov_b32 m0, s48
	s_nop 0
	global_load_lds_dwordx4 v[172:173], off
	s_barrier
; #define PG8_BAR __builtin_amdgcn_s_barrier()
;     __device__ __forceinline__ void operator()(const f32x4 (&acc)[2][2][4][2], const Unit& u, int wr, int wc, int fr, int fq) const {
;         const int row0 = u.pm * BM + wr * 64 + fr, col0 = u.pn * BM + wc * 64 + 8 * fq;
;         f32x4 gv[2][2];
; #pragma unroll
;         for (int bj = 0; bj < 2; ++bj) { gv[bj][0] = *(const f32x4*)(g + col0 + 32 * bj); gv[bj][1] = *(const f32x4*)(g + col0 + 32 * bj + 4); }
;         const bool lo = fr < 8;
; #pragma unroll
;         for (int ai = 0; ai < 2; ++ai)
; #pragma unroll
;             for (int m = 0; m < 4; ++m) { const int row = row0 + ai * HALF + m * 16; const float ri = __builtin_amdgcn_rsqf(sse[row] * (1.f / D) + EPS);
;                 u32x4 rr[2], ee[2]; load_pair_lines(R, D, row, fr, col0, rr[0], rr[1], 32); load_pair_lines(E, D, row, fr, col0, ee[0], ee[1], 32);
;                 float* orow = OUT + (size_t)(row - fr + (fr & 7)) * D + col0 + (lo ? 0 : 4);
; #pragma unroll
;                 for (int bj = 0; bj < 2; ++bj) { const u32x4 rw = rr[bj], ew = ee[bj];
;                     const float r[8] = {bflo(rw.x), bfhi(rw.x), bflo(rw.y), bfhi(rw.y), bflo(rw.z), bfhi(rw.z), bflo(rw.w), bfhi(rw.w)};
;                     const float e[8] = {bflo(ew.x), bfhi(ew.x), bflo(ew.y), bfhi(ew.y), bflo(ew.z), bfhi(ew.z), bflo(ew.w), bfhi(ew.w)};
;                     float o[8];
; #pragma unroll
;                     for (int j = 0; j < 8; ++j) { const float a = acc[ai][bj][m][j >> 2][j & 3]; const float gg = gv[bj][j >> 2][j & 3];
; template <class Epi>
; __device__ __forceinline__ void gemm_phase(LAS unsigned char* lds, const Gemm g, const StaticOrder& S, const Epi& E) {
;     ...
;             PG8_WAIT_V(6); PG8_BAR; PG8_MMA(1, 1, At, B1); PG8_BAR;
;             PG8_LDB(B0, 1, 0); PG8_SCHED; PG8_LDA(At, 1, 0); PG8_STAGE(PG8_SA(0, 1), a2 + hstep, voffA);
;             PG8_WAIT_L(8); PG8_BAR; PG8_WAIT_L(0); PG8_MMA(0, 0, At, B0); PG8_BAR; PG8_SCHED;
;             PG8_LDB(B1, 1, 1); PG8_STAGE(PG8_SB(1, 0), b3, voffB0);
;             PG8_BAR; PG8_WAIT_L(0); PG8_MMA(0, 1, At, B1); PG8_BAR;
;             PG8_LDA(At, 1, 1); PG8_STAGE(PG8_SA(1, 0), a3, voffA);
;             PG8_BAR; PG8_WAIT_L(0); PG8_MMA(1, 0, At, B0); PG8_BAR; PG8_SCHED;
;             PG8_STAGE(PG8_SB(1, 1), b3, voffB1);
;             PG8_WAIT_V(6); PG8_BAR; PG8_MMA(1, 1, At, B1); PG8_BAR;
	s_waitcnt lgkmcnt(0)
	v_mfma_f32_16x16x32_bf16 v[76:79], v[56:59], v[164:167], v[76:79]
	v_mfma_f32_16x16x32_bf16 v[72:75], v[64:67], v[164:167], v[72:75]
	v_mfma_f32_16x16x32_bf16 v[52:55], v[56:59], v[184:187], v[52:55]
	v_mfma_f32_16x16x32_bf16 v[48:51], v[64:67], v[184:187], v[48:51]
	v_mfma_f32_16x16x32_bf16 v[28:31], v[56:59], v[192:195], v[28:31]
	v_mfma_f32_16x16x32_bf16 v[24:27], v[64:67], v[192:195], v[24:27]
	v_mfma_f32_16x16x32_bf16 v[12:15], v[56:59], v[200:203], v[12:15]
	v_mfma_f32_16x16x32_bf16 v[8:11], v[64:67], v[200:203], v[8:11]
	v_mfma_f32_16x16x32_bf16 v[76:79], v[60:63], v[168:171], v[76:79]
	v_mfma_f32_16x16x32_bf16 v[72:75], v[68:71], v[168:171], v[72:75]
	v_mfma_f32_16x16x32_bf16 v[52:55], v[60:63], v[188:191], v[52:55]
	v_mfma_f32_16x16x32_bf16 v[48:51], v[68:71], v[188:191], v[48:51]
	v_mfma_f32_16x16x32_bf16 v[28:31], v[60:63], v[196:199], v[28:31]
	v_mfma_f32_16x16x32_bf16 v[24:27], v[68:71], v[196:199], v[24:27]
	v_mfma_f32_16x16x32_bf16 v[12:15], v[60:63], v[204:207], v[12:15]
	v_mfma_f32_16x16x32_bf16 v[8:11], v[68:71], v[204:207], v[8:11]
	s_barrier
	s_add_i32 s36, s36, s41
	v_lshl_add_u64 v[56:57], v[230:231], 0, s[14:15]
	s_mov_b32 m0, s36
	s_nop 0
	global_load_lds_dwordx4 v[56:57], off
	v_lshl_add_u64 v[56:57], v[232:233], 0, s[14:15]
	s_add_i32 m0, s36, 0x2000
	s_nop 0
	global_load_lds_dwordx4 v[56:57], off
	s_waitcnt vmcnt(6)
	s_barrier
	v_mfma_f32_16x16x32_bf16 v[40:43], v[208:211], v[164:167], v[40:43]
	v_mfma_f32_16x16x32_bf16 v[68:71], v[212:215], v[168:171], v[40:43]
	v_mfma_f32_16x16x32_bf16 v[40:43], v[216:219], v[164:167], v[44:47]
	v_mfma_f32_16x16x32_bf16 v[36:39], v[208:211], v[184:187], v[36:39]
	v_mfma_f32_16x16x32_bf16 v[32:35], v[216:219], v[184:187], v[32:35]
	v_mfma_f32_16x16x32_bf16 v[20:23], v[208:211], v[192:195], v[20:23]
	v_mfma_f32_16x16x32_bf16 v[16:19], v[216:219], v[192:195], v[16:19]
	v_mfma_f32_16x16x32_bf16 v[4:7], v[208:211], v[200:203], v[4:7]
	v_mfma_f32_16x16x32_bf16 v[0:3], v[216:219], v[200:203], v[0:3]
	v_mfma_f32_16x16x32_bf16 v[64:67], v[220:223], v[168:171], v[40:43]
	v_mfma_f32_16x16x32_bf16 v[36:39], v[212:215], v[188:191], v[36:39]
	v_mfma_f32_16x16x32_bf16 v[32:35], v[220:223], v[188:191], v[32:35]
	v_mfma_f32_16x16x32_bf16 v[20:23], v[212:215], v[196:199], v[20:23]
	v_mfma_f32_16x16x32_bf16 v[16:19], v[220:223], v[196:199], v[16:19]
	v_mfma_f32_16x16x32_bf16 v[4:7], v[212:215], v[204:207], v[4:7]
	v_mfma_f32_16x16x32_bf16 v[0:3], v[220:223], v[204:207], v[0:3]
	s_add_i32 s58, s58, 2
	s_add_u32 s34, s34, 0x100
	s_addc_u32 s35, s35, 0
	s_add_u32 s56, s56, 0x100
	s_addc_u32 s57, s57, 0
	s_cmp_gt_u32 s58, 29
	s_barrier
	s_cbranch_scc0 .LBB0_1603
	s_lshl_b32 s19, s30, 8
	s_add_i32 s19, s19, s49
	v_lshl_or_b32 v40, s53, 8, v178
	v_or_b32_e32 v172, s19, v176
	v_or_b32_e32 v42, v40, v177
	v_ashrrev_i32_e32 v173, 31, v172
	v_or_b32_e32 v170, s19, v174
	v_ashrrev_i32_e32 v43, 31, v42
	v_lshlrev_b64 v[44:45], 12, v[172:173]
	v_ashrrev_i32_e32 v171, 31, v170
	v_lshl_add_u64 v[46:47], s[8:9], 0, v[44:45]
	v_lshlrev_b64 v[164:165], 1, v[42:43]
	v_lshl_add_u64 v[168:169], v[170:171], 2, s[6:7]
	v_lshl_add_u64 v[42:43], v[46:47], 0, v[164:165]
	global_load_dword v171, v[168:169], off
	global_load_dwordx4 v[184:187], v[42:43], off
	v_or_b32_e32 v42, 8, v172
	v_ashrrev_i32_e32 v43, 31, v42
	v_lshlrev_b64 v[42:43], 12, v[42:43]
	v_lshl_add_u64 v[46:47], s[8:9], 0, v[42:43]
	v_lshl_add_u64 v[44:45], s[10:11], 0, v[44:45]
	v_lshl_add_u64 v[42:43], s[10:11], 0, v[42:43]
	v_lshl_add_u64 v[46:47], v[46:47], 0, v[164:165]
	v_lshl_add_u64 v[44:45], v[44:45], 0, v[164:165]
	v_lshl_add_u64 v[42:43], v[42:43], 0, v[164:165]
	global_load_dwordx4 v[188:191], v[46:47], off
	global_load_dwordx4 v[192:195], v[44:45], off
	global_load_dwordx4 v[196:199], v[42:43], off
	v_ashrrev_i32_e32 v41, 31, v40
	v_lshlrev_b64 v[166:167], 2, v[40:41]
	v_lshl_add_u64 v[44:45], s[12:13], 0, v[166:167]
	global_load_dwordx4 v[56:59], v[44:45], off
	global_load_dwordx4 v[60:63], v[44:45], off offset:16
	v_mul_f32_e32 v40, 0xbfb8aa3b, v140
	v_exp_f32_e32 v215, v40
	global_load_dwordx4 v[40:43], v[44:45], off offset:128
	s_nop 0
	global_load_dwordx4 v[44:47], v[44:45], off offset:144
	v_or_b32_e32 v216, 16, v170
	v_ashrrev_i32_e32 v217, 31, v216
	v_lshl_add_u64 v[218:219], v[216:217], 2, s[6:7]
	v_sub_u32_e32 v216, v216, v174
	v_add_u32_e32 v222, v216, v176
	v_ashrrev_i32_e32 v223, 31, v222
	v_lshlrev_b64 v[216:217], 12, v[222:223]
	v_lshl_add_u64 v[224:225], v[216:217], 0, s[16:17]
	global_load_dword v228, v[218:219], off
	v_lshl_add_u64 v[218:219], s[8:9], 0, v[216:217]
	v_lshl_add_u64 v[220:221], s[8:9], 0, v[224:225]
	v_lshl_add_u64 v[216:217], s[10:11], 0, v[216:217]
	v_lshl_add_u64 v[218:219], v[218:219], 0, v[164:165]
	v_lshl_add_u64 v[220:221], v[220:221], 0, v[164:165]
	v_lshl_add_u64 v[216:217], v[216:217], 0, v[164:165]
	global_load_dwordx4 v[232:235], v[218:219], off
	global_load_dwordx4 v[236:239], v[220:221], off
	global_load_dwordx4 v[240:243], v[216:217], off
	v_lshl_add_u64 v[216:217], s[10:11], 0, v[224:225]
	v_lshl_add_u64 v[216:217], v[216:217], 0, v[164:165]
	global_load_dwordx4 v[244:247], v[216:217], off
	v_mul_f32_e32 v141, 0xbfb8aa3b, v141
	v_mul_f32_e32 v136, 0xbfb8aa3b, v136
	v_mul_f32_e32 v137, 0xbfb8aa3b, v137
	v_exp_f32_e32 v141, v141
	v_mul_f32_e32 v142, 0xbfb8aa3b, v142
	v_exp_f32_e32 v136, v136
	v_exp_f32_e32 v137, v137
	v_exp_f32_e32 v142, v142
	v_mul_f32_e32 v143, 0xbfb8aa3b, v143
	v_exp_f32_e32 v143, v143
	v_add_f32_e32 v141, 1.0, v141
	v_add_f32_e32 v136, 1.0, v136
	v_add_f32_e32 v137, 1.0, v137
	v_rcp_f32_e32 v136, v136
	v_rcp_f32_e32 v137, v137
	v_mul_f32_e32 v138, 0xbfb8aa3b, v138
	v_mul_f32_e32 v139, 0xbfb8aa3b, v139
	v_exp_f32_e32 v138, v138
	v_exp_f32_e32 v139, v139
	v_add_f32_e32 v138, 1.0, v138
	v_add_f32_e32 v139, 1.0, v139
	v_rcp_f32_e32 v138, v138
	v_rcp_f32_e32 v139, v139
	v_mul_f32_e32 v128, 0xbfb8aa3b, v128
	v_mul_f32_e32 v129, 0xbfb8aa3b, v129
	v_exp_f32_e32 v128, v128
	v_exp_f32_e32 v129, v129
	v_mul_f32_e32 v132, 0xbfb8aa3b, v132
	v_mul_f32_e32 v133, 0xbfb8aa3b, v133
	v_exp_f32_e32 v132, v132
	v_exp_f32_e32 v133, v133
	v_lshlrev_b64 v[172:173], 13, v[172:173]
	v_add_f32_e32 v128, 1.0, v128
	v_add_f32_e32 v129, 1.0, v129
	v_lshl_add_u64 v[172:173], s[4:5], 0, v[172:173]
	v_rcp_f32_e32 v128, v128
	v_mul_f32_e32 v130, 0xbfb8aa3b, v130
	v_mul_f32_e32 v131, 0xbfb8aa3b, v131
	v_rcp_f32_e32 v129, v129
	v_lshl_add_u64 v[172:173], v[172:173], 0, v[166:167]
	v_exp_f32_e32 v130, v130
	v_exp_f32_e32 v131, v131
	v_lshl_add_u64 v[172:173], v[172:173], 0, v[156:157]
	s_waitcnt vmcnt(5)
; __device__ __forceinline__ float bflo(unsigned w) { return __uint_as_float(w << 16); }
;     const bool lo = fr < 8;
;     const int r1 = row - fr + (fr & 7), cb = col0 + (lo ? 0 : boff);
;     const u32x4 l1 = *(const u32x4*)(P + (size_t)r1 * ld + cb), l2 = *(const u32x4*)(P + (size_t)(r1 + 8) * ld + cb);
;     __device__ __forceinline__ void operator()(const f32x4 (&acc)[2][2][4][2], const Unit& u, int wr, int wc, int fr, int fq) const {
;         const int row0 = u.pm * BM + wr * 64 + fr, col0 = u.pn * BM + wc * 64 + 8 * fq;
;         f32x4 gv[2][2];
; #pragma unroll
;         for (int bj = 0; bj < 2; ++bj) { gv[bj][0] = *(const f32x4*)(g + col0 + 32 * bj); gv[bj][1] = *(const f32x4*)(g + col0 + 32 * bj + 4); }
;         const bool lo = fr < 8;
; #pragma unroll
;         for (int ai = 0; ai < 2; ++ai)
; #pragma unroll
;             for (int m = 0; m < 4; ++m) { const int row = row0 + ai * HALF + m * 16; const float ri = __builtin_amdgcn_rsqf(sse[row] * (1.f / D) + EPS);
;                 u32x4 rr[2], ee[2]; load_pair_lines(R, D, row, fr, col0, rr[0], rr[1], 32); load_pair_lines(E, D, row, fr, col0, ee[0], ee[1], 32);
;                 float* orow = OUT + (size_t)(row - fr + (fr & 7)) * D + col0 + (lo ? 0 : 4);
; #pragma unroll
;                 for (int bj = 0; bj < 2; ++bj) { const u32x4 rw = rr[bj], ew = ee[bj];
;                     const float r[8] = {bflo(rw.x), bfhi(rw.x), bflo(rw.y), bfhi(rw.y), bflo(rw.z), bfhi(rw.z), bflo(rw.w), bfhi(rw.w)};
;                     const float e[8] = {bflo(ew.x), bfhi(ew.x), bflo(ew.y), bfhi(ew.y), bflo(ew.z), bfhi(ew.z), bflo(ew.w), bfhi(ew.w)};
;                     float o[8];
; #pragma unroll
;                     for (int j = 0; j < 8; ++j) { const float a = acc[ai][bj][m][j >> 2][j & 3]; const float gg = gv[bj][j >> 2][j & 3];
;                         o[j] = r[j] + e[j] * ri * gg * __builtin_amdgcn_rcpf(1.f + __builtin_amdgcn_exp2f(-a * LOG2E)); }
;                     f32x4 o1, o2;
; #pragma unroll
;                     for (int j = 0; j < 4; ++j) { const unsigned a = __float_as_uint(o[j]), b = __float_as_uint(o[4 + j]); const unsigned sa = dpp_ror8(a), sb = dpp_ror8(b);
;                         o1[j] = __uint_as_float(lo ? a : sb); o2[j] = __uint_as_float(lo ? sa : b); }
;                     *(f32x4*)(orow + 32 * bj) = o1; *(f32x4*)(orow + (size_t)8 * D + 32 * bj) = o2; } }
	v_fmamk_f32 v140, v171, 0x3a000000, v182
	v_rsq_f32_e32 v140, v140
	v_mov_b32_dpp v200, v185 row_ror:8 row_mask:0xf bank_mask:0xf
	v_mov_b32_dpp v183, v184 row_ror:8 row_mask:0xf bank_mask:0xf
	v_mov_b32_dpp v201, v186 row_ror:8 row_mask:0xf bank_mask:0xf
	v_mov_b32_dpp v202, v187 row_ror:8 row_mask:0xf bank_mask:0xf
	v_add_f32_e32 v132, 1.0, v132
	v_add_f32_e32 v133, 1.0, v133
	v_rcp_f32_e32 v132, v132
	v_mul_f32_e32 v134, 0xbfb8aa3b, v134
	v_mul_f32_e32 v135, 0xbfb8aa3b, v135
	v_mov_b32_dpp v204, v189 row_ror:8 row_mask:0xf bank_mask:0xf
	v_cndmask_b32_e64 v171, v189, v200, s[0:1]
	v_mov_b32_dpp v213, v198 row_ror:8 row_mask:0xf bank_mask:0xf
	v_cndmask_b32_e64 v200, v204, v185, s[0:1]
	v_cndmask_b32_e64 v189, v213, v194, s[0:1]
	v_rcp_f32_e32 v185, v141
	v_add_f32_e32 v141, 1.0, v142
	v_mov_b32_dpp v203, v188 row_ror:8 row_mask:0xf bank_mask:0xf
	v_mov_b32_dpp v205, v190 row_ror:8 row_mask:0xf bank_mask:0xf
	v_mov_b32_dpp v206, v191 row_ror:8 row_mask:0xf bank_mask:0xf
	v_cndmask_b32_e64 v183, v188, v183, s[0:1]
	v_rcp_f32_e32 v142, v141
	v_add_f32_e32 v141, 1.0, v143
	v_lshlrev_b32_e32 v188, 16, v189
	v_and_b32_e32 v189, 0xffff0000, v189
	v_cndmask_b32_e64 v190, v190, v201, s[0:1]
	v_cndmask_b32_e64 v201, v206, v187, s[0:1]
	v_cndmask_b32_e64 v187, v205, v186, s[0:1]
	v_pk_mul_f32 v[188:189], v[140:141], v[188:189] op_sel_hi:[0,1]
	v_cndmask_b32_e64 v191, v191, v202, s[0:1]
	v_mov_b32_dpp v211, v196 row_ror:8 row_mask:0xf bank_mask:0xf
	v_cndmask_b32_e64 v202, v203, v184, s[0:1]
	v_add_f32_e32 v184, 1.0, v215
	v_lshlrev_b32_e32 v186, 16, v187
	v_and_b32_e32 v187, 0xffff0000, v187
	v_pk_mul_f32 v[188:189], v[60:61], v[188:189]
	v_mov_b32_dpp v207, v192 row_ror:8 row_mask:0xf bank_mask:0xf
	v_cndmask_b32_e64 v192, v211, v192, s[0:1]
	v_rcp_f32_e32 v184, v184
	v_rcp_f32_e32 v143, v141
	v_pk_fma_f32 v[188:189], v[136:137], v[188:189], v[186:187]
	v_mov_b32_e32 v141, v157
	v_lshlrev_b32_e32 v186, 16, v192
	v_and_b32_e32 v187, 0xffff0000, v192
	v_mov_b32_dpp v141, v188 row_ror:8 row_mask:0xf bank_mask:0xf
	v_mov_b32_dpp v214, v199 row_ror:8 row_mask:0xf bank_mask:0xf
	v_pk_mul_f32 v[186:187], v[140:141], v[186:187] op_sel_hi:[0,1]
	v_mov_b32_dpp v210, v195 row_ror:8 row_mask:0xf bank_mask:0xf
	v_cndmask_b32_e64 v195, v214, v195, s[0:1]
	v_lshlrev_b32_e32 v136, 16, v202
	v_and_b32_e32 v137, 0xffff0000, v202
	v_pk_mul_f32 v[186:187], v[56:57], v[186:187]
	v_mov_b32_dpp v212, v197 row_ror:8 row_mask:0xf bank_mask:0xf
	v_pk_fma_f32 v[136:137], v[184:185], v[186:187], v[136:137]
	v_lshlrev_b32_e32 v186, 16, v195
	v_and_b32_e32 v187, 0xffff0000, v195
	v_pk_mul_f32 v[186:187], v[140:141], v[186:187] op_sel_hi:[0,1]
	v_mov_b32_dpp v208, v193 row_ror:8 row_mask:0xf bank_mask:0xf
	v_cndmask_b32_e64 v193, v212, v193, s[0:1]
	v_lshlrev_b32_e32 v184, 16, v201
	v_and_b32_e32 v185, 0xffff0000, v201
	v_pk_mul_f32 v[186:187], v[62:63], v[186:187]
	v_mov_b32_dpp v209, v194 row_ror:8 row_mask:0xf bank_mask:0xf
	v_pk_fma_f32 v[184:185], v[138:139], v[186:187], v[184:185]
	v_lshlrev_b32_e32 v186, 16, v193
	v_and_b32_e32 v187, 0xffff0000, v193
	v_pk_mul_f32 v[186:187], v[140:141], v[186:187] op_sel_hi:[0,1]
	v_lshlrev_b32_e32 v138, 16, v200
	v_and_b32_e32 v139, 0xffff0000, v200
	v_pk_mul_f32 v[186:187], v[58:59], v[186:187]
	v_cndmask_b32_e64 v194, v197, v208, s[0:1]
	v_pk_fma_f32 v[138:139], v[142:143], v[186:187], v[138:139]
	v_mov_b32_e32 v142, v157
	v_mov_b32_e32 v143, v157
	v_cndmask_b32_e64 v197, v199, v210, s[0:1]
	v_cndmask_b32_e64 v198, v198, v209, s[0:1]
	v_mov_b32_e32 v199, v157
	v_mov_b32_e32 v195, v157
	v_mov_b32_e32 v201, v157
	v_mov_b32_dpp v142, v138 row_ror:8 row_mask:0xf bank_mask:0xf
	v_mov_b32_dpp v143, v139 row_ror:8 row_mask:0xf bank_mask:0xf
	v_mov_b32_dpp v199, v189 row_ror:8 row_mask:0xf bank_mask:0xf
	v_mov_b32_e32 v192, v157
	v_mov_b32_e32 v202, v157
	v_mov_b32_dpp v195, v184 row_ror:8 row_mask:0xf bank_mask:0xf
	v_mov_b32_dpp v201, v185 row_ror:8 row_mask:0xf bank_mask:0xf
	v_cndmask_b32_e64 v187, v185, v143, s[0:1]
	v_cndmask_b32_e64 v186, v184, v142, s[0:1]
	v_lshlrev_b32_e32 v142, 16, v198
	v_and_b32_e32 v143, 0xffff0000, v198
	v_mov_b32_dpp v192, v136 row_ror:8 row_mask:0xf bank_mask:0xf
	v_mov_b32_dpp v202, v137 row_ror:8 row_mask:0xf bank_mask:0xf
	v_cndmask_b32_e64 v139, v201, v139, s[0:1]
	v_cndmask_b32_e64 v138, v195, v138, s[0:1]
	v_cndmask_b32_e64 v137, v199, v137, s[0:1]
	v_cndmask_b32_e64 v136, v141, v136, s[0:1]
	v_pk_mul_f32 v[142:143], v[140:141], v[142:143] op_sel_hi:[0,1]
	v_cndmask_b32_e64 v196, v196, v207, s[0:1]
	global_store_dwordx4 v[172:173], v[136:139], off
	v_rcp_f32_e32 v133, v133
	v_pk_mul_f32 v[142:143], v[44:45], v[142:143]
	v_lshlrev_b32_e32 v138, 16, v190
	v_and_b32_e32 v139, 0xffff0000, v190
	v_exp_f32_e32 v134, v134
	v_exp_f32_e32 v135, v135
	v_pk_fma_f32 v[138:139], v[128:129], v[142:143], v[138:139]
	v_lshlrev_b32_e32 v142, 16, v196
	v_and_b32_e32 v143, 0xffff0000, v196
	v_add_f32_e32 v130, 1.0, v130
	v_add_f32_e32 v131, 1.0, v131
	v_pk_mul_f32 v[142:143], v[140:141], v[142:143] op_sel_hi:[0,1]
	v_rcp_f32_e32 v130, v130
	v_rcp_f32_e32 v131, v131
	v_lshlrev_b32_e32 v128, 16, v183
	v_and_b32_e32 v129, 0xffff0000, v183
	v_pk_mul_f32 v[142:143], v[40:41], v[142:143]
	v_add_f32_e32 v134, 1.0, v134
	v_pk_fma_f32 v[128:129], v[132:133], v[142:143], v[128:129]
	v_lshlrev_b32_e32 v142, 16, v197
	v_and_b32_e32 v143, 0xffff0000, v197
	v_add_f32_e32 v135, 1.0, v135
	v_pk_mul_f32 v[142:143], v[140:141], v[142:143] op_sel_hi:[0,1]
	v_rcp_f32_e32 v134, v134
	v_rcp_f32_e32 v135, v135
	v_lshlrev_b32_e32 v132, 16, v191
	v_and_b32_e32 v133, 0xffff0000, v191
	v_pk_mul_f32 v[142:143], v[46:47], v[142:143]
; __device__ __forceinline__ float bflo(unsigned w) { return __uint_as_float(w << 16); }
;     const bool lo = fr < 8;
;     const int r1 = row - fr + (fr & 7), cb = col0 + (lo ? 0 : boff);
;     const u32x4 l1 = *(const u32x4*)(P + (size_t)r1 * ld + cb), l2 = *(const u32x4*)(P + (size_t)(r1 + 8) * ld + cb);
;     __device__ __forceinline__ void operator()(const f32x4 (&acc)[2][2][4][2], const Unit& u, int wr, int wc, int fr, int fq) const {
;         const int row0 = u.pm * BM + wr * 64 + fr, col0 = u.pn * BM + wc * 64 + 8 * fq;
;         f32x4 gv[2][2];
; #pragma unroll
;         for (int bj = 0; bj < 2; ++bj) { gv[bj][0] = *(const f32x4*)(g + col0 + 32 * bj); gv[bj][1] = *(const f32x4*)(g + col0 + 32 * bj + 4); }
;         const bool lo = fr < 8;
; #pragma unroll
;         for (int ai = 0; ai < 2; ++ai)
; #pragma unroll
;             for (int m = 0; m < 4; ++m) { const int row = row0 + ai * HALF + m * 16; const float ri = __builtin_amdgcn_rsqf(sse[row] * (1.f / D) + EPS);
;                 u32x4 rr[2], ee[2]; load_pair_lines(R, D, row, fr, col0, rr[0], rr[1], 32); load_pair_lines(E, D, row, fr, col0, ee[0], ee[1], 32);
;                 float* orow = OUT + (size_t)(row - fr + (fr & 7)) * D + col0 + (lo ? 0 : 4);
; #pragma unroll
;                 for (int bj = 0; bj < 2; ++bj) { const u32x4 rw = rr[bj], ew = ee[bj];
;                     const float r[8] = {bflo(rw.x), bfhi(rw.x), bflo(rw.y), bfhi(rw.y), bflo(rw.z), bfhi(rw.z), bflo(rw.w), bfhi(rw.w)};
;                     const float e[8] = {bflo(ew.x), bfhi(ew.x), bflo(ew.y), bfhi(ew.y), bflo(ew.z), bfhi(ew.z), bflo(ew.w), bfhi(ew.w)};
;                     float o[8];
; #pragma unroll
;                     for (int j = 0; j < 8; ++j) { const float a = acc[ai][bj][m][j >> 2][j & 3]; const float gg = gv[bj][j >> 2][j & 3];
;                         o[j] = r[j] + e[j] * ri * gg * __builtin_amdgcn_rcpf(1.f + __builtin_amdgcn_exp2f(-a * LOG2E)); }
;                     f32x4 o1, o2;
; #pragma unroll
;                     for (int j = 0; j < 4; ++j) { const unsigned a = __float_as_uint(o[j]), b = __float_as_uint(o[4 + j]); const unsigned sa = dpp_ror8(a), sb = dpp_ror8(b);
;                         o1[j] = __uint_as_float(lo ? a : sb); o2[j] = __uint_as_float(lo ? sa : b); }
;                     *(f32x4*)(orow + 32 * bj) = o1; *(f32x4*)(orow + (size_t)8 * D + 32 * bj) = o2; } }
	v_add_co_u32_e32 v136, vcc, s45, v172
	v_pk_fma_f32 v[132:133], v[130:131], v[142:143], v[132:133]
	v_lshlrev_b32_e32 v142, 16, v194
	v_and_b32_e32 v143, 0xffff0000, v194
	v_cndmask_b32_e64 v185, v189, v202, s[0:1]
	v_cndmask_b32_e64 v184, v188, v192, s[0:1]
	v_addc_co_u32_e32 v137, vcc, 0, v173, vcc
	v_pk_mul_f32 v[140:141], v[140:141], v[142:143] op_sel_hi:[0,1]
	global_store_dwordx4 v[136:137], v[184:187], off
	v_mov_b32_e32 v188, v157
	v_lshlrev_b32_e32 v130, 16, v171
	v_mov_b32_e32 v184, v157
	v_mov_b32_e32 v185, v157
	v_mov_b32_e32 v187, v157
	v_and_b32_e32 v131, 0xffff0000, v171
	v_pk_mul_f32 v[140:141], v[42:43], v[140:141]
	v_mov_b32_dpp v184, v138 row_ror:8 row_mask:0xf bank_mask:0xf
	v_mov_b32_dpp v185, v139 row_ror:8 row_mask:0xf bank_mask:0xf
	v_mov_b32_e32 v183, v157
	v_mov_b32_e32 v186, v157
	v_mov_b32_dpp v187, v132 row_ror:8 row_mask:0xf bank_mask:0xf
	v_mov_b32_dpp v188, v133 row_ror:8 row_mask:0xf bank_mask:0xf
	v_pk_fma_f32 v[130:131], v[134:135], v[140:141], v[130:131]
	v_mov_b32_e32 v134, v157
	v_mov_b32_e32 v135, v157
	v_mov_b32_dpp v183, v128 row_ror:8 row_mask:0xf bank_mask:0xf
	v_mov_b32_dpp v186, v129 row_ror:8 row_mask:0xf bank_mask:0xf
	v_mov_b32_dpp v134, v130 row_ror:8 row_mask:0xf bank_mask:0xf
	v_mov_b32_dpp v135, v131 row_ror:8 row_mask:0xf bank_mask:0xf
	v_cndmask_b32_e64 v131, v188, v131, s[0:1]
	v_cndmask_b32_e64 v130, v187, v130, s[0:1]
	v_cndmask_b32_e64 v129, v185, v129, s[0:1]
	v_cndmask_b32_e64 v128, v184, v128, s[0:1]
	v_cndmask_b32_e64 v135, v133, v135, s[0:1]
	v_cndmask_b32_e64 v134, v132, v134, s[0:1]
	v_cndmask_b32_e64 v133, v139, v186, s[0:1]
	v_cndmask_b32_e64 v132, v138, v183, s[0:1]
	global_store_dwordx4 v[172:173], v[128:131], off offset:128
	global_store_dwordx4 v[136:137], v[132:135], off offset:128
	v_mov_b32_e32 v183, v157
	v_or_b32_e32 v128, 16, v170
	v_ashrrev_i32_e32 v129, 31, v128
	v_lshl_add_u64 v[130:131], v[128:129], 2, s[6:7]
	v_sub_u32_e32 v128, v128, v174
	v_add_u32_e32 v142, v128, v176
	v_ashrrev_i32_e32 v143, 31, v142
	v_lshlrev_b64 v[128:129], 12, v[142:143]
	v_lshl_add_u64 v[172:173], v[128:129], 0, s[16:17]
	s_waitcnt vmcnt(4)
	s_nop 0
	v_mov_b32_e32 v171, v228
	v_lshl_add_u64 v[130:131], s[8:9], 0, v[128:129]
	v_lshl_add_u64 v[134:135], s[8:9], 0, v[172:173]
	v_lshl_add_u64 v[128:129], s[10:11], 0, v[128:129]
	v_lshl_add_u64 v[130:131], v[130:131], 0, v[164:165]
	v_lshl_add_u64 v[134:135], v[134:135], 0, v[164:165]
	v_lshl_add_u64 v[128:129], v[128:129], 0, v[164:165]
	v_mov_b64_e32 v[130:131], v[232:233]
	v_mov_b64_e32 v[132:133], v[234:235]
	v_mov_b32_e32 v189, v157
	v_mov_b64_e32 v[134:135], v[236:237]
	v_mov_b64_e32 v[136:137], v[238:239]
	v_mov_b32_e32 v190, v157
	v_mov_b64_e32 v[138:139], v[240:241]
	v_mov_b64_e32 v[140:141], v[242:243]
	v_lshl_add_u64 v[128:129], s[10:11], 0, v[172:173]
	v_lshl_add_u64 v[128:129], v[128:129], 0, v[164:165]
	v_mov_b64_e32 v[184:185], v[244:245]
	v_mov_b64_e32 v[186:187], v[246:247]
	s_nop 1
	v_or_b32_e32 v216, 32, v170
	v_ashrrev_i32_e32 v217, 31, v216
	v_lshl_add_u64 v[218:219], v[216:217], 2, s[6:7]
	v_sub_u32_e32 v216, v216, v174
	v_add_u32_e32 v224, v216, v176
	v_ashrrev_i32_e32 v225, 31, v224
	v_lshlrev_b64 v[216:217], 12, v[224:225]
	v_lshl_add_u64 v[222:223], v[216:217], 0, s[16:17]
	v_lshl_add_u64 v[220:221], s[8:9], 0, v[222:223]
	global_load_dword v228, v[218:219], off
	v_lshl_add_u64 v[218:219], s[8:9], 0, v[216:217]
	v_lshl_add_u64 v[220:221], v[220:221], 0, v[164:165]
	v_lshl_add_u64 v[216:217], s[10:11], 0, v[216:217]
	v_lshl_add_u64 v[218:219], v[218:219], 0, v[164:165]
	global_load_dwordx4 v[232:235], v[220:221], off
	v_lshl_add_u64 v[216:217], v[216:217], 0, v[164:165]
	global_load_dwordx4 v[236:239], v[218:219], off
	global_load_dwordx4 v[240:243], v[216:217], off
	v_lshl_add_u64 v[216:217], s[10:11], 0, v[222:223]
	v_lshl_add_u64 v[216:217], v[216:217], 0, v[164:165]
	global_load_dwordx4 v[244:247], v[216:217], off
	v_mov_b32_e32 v173, v157
	v_mov_b32_e32 v129, v157
	v_mov_b32_e32 v172, v157
	v_mov_b32_e32 v188, v157
	v_mul_f32_e32 v120, 0xbfb8aa3b, v120
	v_mul_f32_e32 v121, 0xbfb8aa3b, v121
	v_mul_f32_e32 v124, 0xbfb8aa3b, v124
	v_exp_f32_e32 v120, v120
	v_exp_f32_e32 v121, v121
	v_mul_f32_e32 v122, 0xbfb8aa3b, v122
	v_mul_f32_e32 v123, 0xbfb8aa3b, v123
	v_add_f32_e32 v120, 1.0, v120
	v_add_f32_e32 v121, 1.0, v121
	v_rcp_f32_e32 v120, v120
	v_rcp_f32_e32 v121, v121
	v_exp_f32_e32 v122, v122
	v_exp_f32_e32 v123, v123
	v_mul_f32_e32 v126, 0xbfb8aa3b, v126
	v_mul_f32_e32 v127, 0xbfb8aa3b, v127
	v_exp_f32_e32 v126, v126
	v_exp_f32_e32 v127, v127
	v_add_f32_e32 v122, 1.0, v122
	v_add_f32_e32 v123, 1.0, v123
	v_rcp_f32_e32 v122, v122
	v_rcp_f32_e32 v123, v123
	v_add_f32_e32 v126, 1.0, v126
	v_add_f32_e32 v127, 1.0, v127
	v_mul_f32_e32 v112, 0xbfb8aa3b, v112
	v_mul_f32_e32 v113, 0xbfb8aa3b, v113
	v_rcp_f32_e32 v126, v126
	v_rcp_f32_e32 v127, v127
	v_exp_f32_e32 v112, v112
	v_exp_f32_e32 v113, v113
	v_mul_f32_e32 v116, 0xbfb8aa3b, v116
	v_mul_f32_e32 v117, 0xbfb8aa3b, v117
	v_exp_f32_e32 v116, v116
	v_exp_f32_e32 v117, v117
	v_add_f32_e32 v112, 1.0, v112
	v_add_f32_e32 v113, 1.0, v113
	v_rcp_f32_e32 v112, v112
	v_rcp_f32_e32 v113, v113
	v_mul_f32_e32 v114, 0xbfb8aa3b, v114
	v_mul_f32_e32 v115, 0xbfb8aa3b, v115
	v_add_f32_e32 v116, 1.0, v116
	v_add_f32_e32 v117, 1.0, v117
	v_exp_f32_e32 v114, v114
	v_exp_f32_e32 v115, v115
	v_rcp_f32_e32 v116, v116
	v_rcp_f32_e32 v117, v117
	v_mul_f32_e32 v118, 0xbfb8aa3b, v118
	v_mul_f32_e32 v119, 0xbfb8aa3b, v119
	v_exp_f32_e32 v118, v118
	v_exp_f32_e32 v119, v119
	v_add_f32_e32 v114, 1.0, v114
	v_add_f32_e32 v115, 1.0, v115
	v_rcp_f32_e32 v114, v114
	v_rcp_f32_e32 v115, v115
; __device__ __forceinline__ float bflo(unsigned w) { return __uint_as_float(w << 16); }
;     const bool lo = fr < 8;
;     const int r1 = row - fr + (fr & 7), cb = col0 + (lo ? 0 : boff);
;     const u32x4 l1 = *(const u32x4*)(P + (size_t)r1 * ld + cb), l2 = *(const u32x4*)(P + (size_t)(r1 + 8) * ld + cb);
;     __device__ __forceinline__ void operator()(const f32x4 (&acc)[2][2][4][2], const Unit& u, int wr, int wc, int fr, int fq) const {
;         const int row0 = u.pm * BM + wr * 64 + fr, col0 = u.pn * BM + wc * 64 + 8 * fq;
;         f32x4 gv[2][2];
; #pragma unroll
;         for (int bj = 0; bj < 2; ++bj) { gv[bj][0] = *(const f32x4*)(g + col0 + 32 * bj); gv[bj][1] = *(const f32x4*)(g + col0 + 32 * bj + 4); }
;         const bool lo = fr < 8;
; #pragma unroll
;         for (int ai = 0; ai < 2; ++ai)
; #pragma unroll
;             for (int m = 0; m < 4; ++m) { const int row = row0 + ai * HALF + m * 16; const float ri = __builtin_amdgcn_rsqf(sse[row] * (1.f / D) + EPS);
;                 u32x4 rr[2], ee[2]; load_pair_lines(R, D, row, fr, col0, rr[0], rr[1], 32); load_pair_lines(E, D, row, fr, col0, ee[0], ee[1], 32);
;                 float* orow = OUT + (size_t)(row - fr + (fr & 7)) * D + col0 + (lo ? 0 : 4);
; #pragma unroll
;                 for (int bj = 0; bj < 2; ++bj) { const u32x4 rw = rr[bj], ew = ee[bj];
;                     const float r[8] = {bflo(rw.x), bfhi(rw.x), bflo(rw.y), bfhi(rw.y), bflo(rw.z), bfhi(rw.z), bflo(rw.w), bfhi(rw.w)};
;                     const float e[8] = {bflo(ew.x), bfhi(ew.x), bflo(ew.y), bfhi(ew.y), bflo(ew.z), bfhi(ew.z), bflo(ew.w), bfhi(ew.w)};
;                     float o[8];
; #pragma unroll
;                     for (int j = 0; j < 8; ++j) { const float a = acc[ai][bj][m][j >> 2][j & 3]; const float gg = gv[bj][j >> 2][j & 3];
;                         o[j] = r[j] + e[j] * ri * gg * __builtin_amdgcn_rcpf(1.f + __builtin_amdgcn_exp2f(-a * LOG2E)); }
;                     f32x4 o1, o2;
; #pragma unroll
;                     for (int j = 0; j < 4; ++j) { const unsigned a = __float_as_uint(o[j]), b = __float_as_uint(o[4 + j]); const unsigned sa = dpp_ror8(a), sb = dpp_ror8(b);
;                         o1[j] = __uint_as_float(lo ? a : sb); o2[j] = __uint_as_float(lo ? sa : b); }
;                     *(f32x4*)(orow + 32 * bj) = o1; *(f32x4*)(orow + (size_t)8 * D + 32 * bj) = o2; } }
	v_add_f32_e32 v118, 1.0, v118
	v_add_f32_e32 v119, 1.0, v119
	v_rcp_f32_e32 v118, v118
	v_rcp_f32_e32 v119, v119
	v_mul_f32_e32 v104, 0xbfb8aa3b, v104
	v_mul_f32_e32 v105, 0xbfb8aa3b, v105
	v_mul_f32_e32 v108, 0xbfb8aa3b, v108
	v_exp_f32_e32 v104, v104
	v_fmamk_f32 v128, v171, 0x3a000000, v182
	v_mov_b32_e32 v171, v157
	v_rsq_f32_e32 v128, v128
	v_exp_f32_e32 v105, v105
	v_add_f32_e32 v104, 1.0, v104
	v_rcp_f32_e32 v104, v104
	v_mul_f32_e32 v106, 0xbfb8aa3b, v106
	v_mov_b32_dpp v171, v131 row_ror:8 row_mask:0xf bank_mask:0xf
	v_mov_b32_dpp v173, v133 row_ror:8 row_mask:0xf bank_mask:0xf
	v_mov_b32_dpp v183, v134 row_ror:8 row_mask:0xf bank_mask:0xf
	v_mov_b32_dpp v189, v136 row_ror:8 row_mask:0xf bank_mask:0xf
	v_mov_b32_dpp v190, v137 row_ror:8 row_mask:0xf bank_mask:0xf
	v_mov_b32_dpp v129, v130 row_ror:8 row_mask:0xf bank_mask:0xf
	v_mov_b32_dpp v172, v132 row_ror:8 row_mask:0xf bank_mask:0xf
	v_mov_b32_dpp v188, v135 row_ror:8 row_mask:0xf bank_mask:0xf
	v_cndmask_b32_e64 v190, v190, v133, s[0:1]
	v_cndmask_b32_e64 v183, v183, v130, s[0:1]
	v_cndmask_b32_e64 v133, v189, v132, s[0:1]
	v_cndmask_b32_e64 v171, v135, v171, s[0:1]
	v_cndmask_b32_e64 v137, v137, v173, s[0:1]
	v_mov_b32_e32 v130, v157
	v_mov_b32_e32 v132, v157
	v_mov_b32_e32 v135, v157
	v_mov_b32_e32 v173, v157
	v_cndmask_b32_e64 v129, v134, v129, s[0:1]
	v_cndmask_b32_e64 v136, v136, v172, s[0:1]
	v_mov_b32_dpp v130, v138 row_ror:8 row_mask:0xf bank_mask:0xf
	v_mov_b32_dpp v132, v140 row_ror:8 row_mask:0xf bank_mask:0xf
	v_mov_b32_e32 v134, v157
	v_mov_b32_dpp v135, v184 row_ror:8 row_mask:0xf bank_mask:0xf
	v_mov_b32_e32 v172, v157
	v_mov_b32_dpp v173, v186 row_ror:8 row_mask:0xf bank_mask:0xf
	v_cndmask_b32_e64 v188, v188, v131, s[0:1]
	v_mov_b32_e32 v131, v157
	v_mov_b32_dpp v134, v141 row_ror:8 row_mask:0xf bank_mask:0xf
	v_mov_b32_dpp v172, v185 row_ror:8 row_mask:0xf bank_mask:0xf
	v_cndmask_b32_e64 v138, v135, v138, s[0:1]
	v_cndmask_b32_e64 v135, v173, v140, s[0:1]
	v_cndmask_b32_e64 v173, v184, v130, s[0:1]
	v_cndmask_b32_e64 v184, v186, v132, s[0:1]
	v_exp_f32_e32 v132, v124
	v_mul_f32_e32 v124, 0xbfb8aa3b, v125
	v_mov_b32_dpp v131, v139 row_ror:8 row_mask:0xf bank_mask:0xf
	v_cndmask_b32_e64 v139, v172, v139, s[0:1]
	v_cndmask_b32_e64 v172, v187, v134, s[0:1]
	v_exp_f32_e32 v134, v124
	v_cndmask_b32_e64 v140, v185, v131, s[0:1]
	v_lshlrev_b64 v[130:131], 13, v[142:143]
	v_lshl_add_u64 v[130:131], s[4:5], 0, v[130:131]
	v_lshl_add_u64 v[130:131], v[130:131], 0, v[166:167]
	v_lshl_add_u64 v[124:125], v[130:131], 0, v[156:157]
	v_add_f32_e32 v131, 1.0, v134
	v_lshlrev_b32_e32 v134, 16, v135
	v_and_b32_e32 v135, 0xffff0000, v135
	v_add_f32_e32 v130, 1.0, v132
	v_pk_mul_f32 v[134:135], v[128:129], v[134:135] op_sel_hi:[0,1]
	v_rcp_f32_e32 v130, v130
	v_rcp_f32_e32 v131, v131
	v_lshlrev_b32_e32 v132, 16, v133
	v_and_b32_e32 v133, 0xffff0000, v133
	v_pk_mul_f32 v[134:135], v[60:61], v[134:135]
	v_mov_b32_e32 v189, v157
	v_pk_fma_f32 v[134:135], v[120:121], v[134:135], v[132:133]
	v_lshlrev_b32_e32 v132, 16, v138
	v_and_b32_e32 v133, 0xffff0000, v138
	v_mov_b32_dpp v189, v187 row_ror:8 row_mask:0xf bank_mask:0xf
	v_pk_mul_f32 v[132:133], v[128:129], v[132:133] op_sel_hi:[0,1]
	v_cndmask_b32_e64 v141, v189, v141, s[0:1]
	v_lshlrev_b32_e32 v120, 16, v183
	v_and_b32_e32 v121, 0xffff0000, v183
	v_pk_mul_f32 v[132:133], v[56:57], v[132:133]
	v_mov_b32_e32 v142, v157
	v_pk_fma_f32 v[120:121], v[130:131], v[132:133], v[120:121]
	v_lshlrev_b32_e32 v132, 16, v141
	v_and_b32_e32 v133, 0xffff0000, v141
	v_pk_mul_f32 v[132:133], v[128:129], v[132:133] op_sel_hi:[0,1]
	v_lshlrev_b32_e32 v130, 16, v190
	v_and_b32_e32 v131, 0xffff0000, v190
	v_pk_mul_f32 v[132:133], v[62:63], v[132:133]
	v_mov_b32_e32 v143, v157
	v_pk_fma_f32 v[130:131], v[122:123], v[132:133], v[130:131]
	v_lshlrev_b32_e32 v132, 16, v139
	v_and_b32_e32 v133, 0xffff0000, v139
	v_pk_mul_f32 v[132:133], v[128:129], v[132:133] op_sel_hi:[0,1]
	v_lshlrev_b32_e32 v122, 16, v188
	v_and_b32_e32 v123, 0xffff0000, v188
	v_pk_mul_f32 v[132:133], v[58:59], v[132:133]
	v_mov_b32_e32 v141, v157
	v_pk_fma_f32 v[122:123], v[126:127], v[132:133], v[122:123]
	v_mov_b32_e32 v126, v157
	v_mov_b32_e32 v127, v157
	v_mov_b32_e32 v185, v157
	v_mov_b32_dpp v126, v122 row_ror:8 row_mask:0xf bank_mask:0xf
	v_mov_b32_dpp v127, v123 row_ror:8 row_mask:0xf bank_mask:0xf
	v_mov_b32_dpp v142, v134 row_ror:8 row_mask:0xf bank_mask:0xf
	v_mov_b32_dpp v143, v135 row_ror:8 row_mask:0xf bank_mask:0xf
	v_mov_b32_e32 v138, v157
	v_mov_b32_e32 v183, v157
	v_mov_b32_dpp v141, v130 row_ror:8 row_mask:0xf bank_mask:0xf
	v_mov_b32_dpp v185, v131 row_ror:8 row_mask:0xf bank_mask:0xf
	v_cndmask_b32_e64 v133, v131, v127, s[0:1]
	v_cndmask_b32_e64 v132, v130, v126, s[0:1]
	v_lshlrev_b32_e32 v126, 16, v184
	v_and_b32_e32 v127, 0xffff0000, v184
	v_mov_b32_dpp v138, v120 row_ror:8 row_mask:0xf bank_mask:0xf
	v_mov_b32_dpp v183, v121 row_ror:8 row_mask:0xf bank_mask:0xf
	v_cndmask_b32_e64 v123, v185, v123, s[0:1]
	v_cndmask_b32_e64 v122, v141, v122, s[0:1]
	v_cndmask_b32_e64 v121, v143, v121, s[0:1]
	v_cndmask_b32_e64 v120, v142, v120, s[0:1]
	v_pk_mul_f32 v[126:127], v[128:129], v[126:127] op_sel_hi:[0,1]
	global_store_dwordx4 v[124:125], v[120:123], off
	v_pk_mul_f32 v[126:127], v[44:45], v[126:127]
	v_cndmask_b32_e64 v131, v135, v183, s[0:1]
	v_lshlrev_b32_e32 v122, 16, v136
	v_and_b32_e32 v123, 0xffff0000, v136
	v_pk_fma_f32 v[122:123], v[112:113], v[126:127], v[122:123]
	v_lshlrev_b32_e32 v126, 16, v173
	v_and_b32_e32 v127, 0xffff0000, v173
	v_pk_mul_f32 v[126:127], v[128:129], v[126:127] op_sel_hi:[0,1]
	v_lshlrev_b32_e32 v112, 16, v129
	v_and_b32_e32 v113, 0xffff0000, v129
; __device__ __forceinline__ float bflo(unsigned w) { return __uint_as_float(w << 16); }
;     const bool lo = fr < 8;
;     const int r1 = row - fr + (fr & 7), cb = col0 + (lo ? 0 : boff);
;     const u32x4 l1 = *(const u32x4*)(P + (size_t)r1 * ld + cb), l2 = *(const u32x4*)(P + (size_t)(r1 + 8) * ld + cb);
;     __device__ __forceinline__ void operator()(const f32x4 (&acc)[2][2][4][2], const Unit& u, int wr, int wc, int fr, int fq) const {
;         const int row0 = u.pm * BM + wr * 64 + fr, col0 = u.pn * BM + wc * 64 + 8 * fq;
;         f32x4 gv[2][2];
; #pragma unroll
;         for (int bj = 0; bj < 2; ++bj) { gv[bj][0] = *(const f32x4*)(g + col0 + 32 * bj); gv[bj][1] = *(const f32x4*)(g + col0 + 32 * bj + 4); }
;         const bool lo = fr < 8;
; #pragma unroll
;         for (int ai = 0; ai < 2; ++ai)
; #pragma unroll
;             for (int m = 0; m < 4; ++m) { const int row = row0 + ai * HALF + m * 16; const float ri = __builtin_amdgcn_rsqf(sse[row] * (1.f / D) + EPS);
;                 u32x4 rr[2], ee[2]; load_pair_lines(R, D, row, fr, col0, rr[0], rr[1], 32); load_pair_lines(E, D, row, fr, col0, ee[0], ee[1], 32);
;                 float* orow = OUT + (size_t)(row - fr + (fr & 7)) * D + col0 + (lo ? 0 : 4);
; #pragma unroll
;                 for (int bj = 0; bj < 2; ++bj) { const u32x4 rw = rr[bj], ew = ee[bj];
;                     const float r[8] = {bflo(rw.x), bfhi(rw.x), bflo(rw.y), bfhi(rw.y), bflo(rw.z), bfhi(rw.z), bflo(rw.w), bfhi(rw.w)};
;                     const float e[8] = {bflo(ew.x), bfhi(ew.x), bflo(ew.y), bfhi(ew.y), bflo(ew.z), bfhi(ew.z), bflo(ew.w), bfhi(ew.w)};
;                     float o[8];
; #pragma unroll
;                     for (int j = 0; j < 8; ++j) { const float a = acc[ai][bj][m][j >> 2][j & 3]; const float gg = gv[bj][j >> 2][j & 3];
;                         o[j] = r[j] + e[j] * ri * gg * __builtin_amdgcn_rcpf(1.f + __builtin_amdgcn_exp2f(-a * LOG2E)); }
;                     f32x4 o1, o2;
; #pragma unroll
;                     for (int j = 0; j < 4; ++j) { const unsigned a = __float_as_uint(o[j]), b = __float_as_uint(o[4 + j]); const unsigned sa = dpp_ror8(a), sb = dpp_ror8(b);
;                         o1[j] = __uint_as_float(lo ? a : sb); o2[j] = __uint_as_float(lo ? sa : b); }
;                     *(f32x4*)(orow + 32 * bj) = o1; *(f32x4*)(orow + (size_t)8 * D + 32 * bj) = o2; } }
	v_pk_mul_f32 v[126:127], v[40:41], v[126:127]
	v_mov_b32_e32 v129, v157
	v_pk_fma_f32 v[112:113], v[116:117], v[126:127], v[112:113]
	v_lshlrev_b32_e32 v126, 16, v172
	v_and_b32_e32 v127, 0xffff0000, v172
	v_mov_b32_dpp v129, v112 row_ror:8 row_mask:0xf bank_mask:0xf
	v_pk_mul_f32 v[126:127], v[128:129], v[126:127] op_sel_hi:[0,1]
	v_lshlrev_b32_e32 v116, 16, v137
	v_and_b32_e32 v117, 0xffff0000, v137
	v_pk_mul_f32 v[126:127], v[46:47], v[126:127]
	v_add_co_u32_e32 v120, vcc, s45, v124
	v_pk_fma_f32 v[116:117], v[114:115], v[126:127], v[116:117]
	v_lshlrev_b32_e32 v126, 16, v140
	v_and_b32_e32 v127, 0xffff0000, v140
	v_cndmask_b32_e64 v130, v134, v138, s[0:1]
	v_addc_co_u32_e32 v121, vcc, 0, v125, vcc
	v_pk_mul_f32 v[126:127], v[128:129], v[126:127] op_sel_hi:[0,1]
	global_store_dwordx4 v[120:121], v[130:133], off
	v_mov_b32_e32 v134, v157
	v_lshlrev_b32_e32 v114, 16, v171
	v_mov_b32_e32 v130, v157
	v_mov_b32_e32 v131, v157
	v_mov_b32_e32 v133, v157
	v_and_b32_e32 v115, 0xffff0000, v171
	v_pk_mul_f32 v[126:127], v[42:43], v[126:127]
	v_mov_b32_dpp v130, v122 row_ror:8 row_mask:0xf bank_mask:0xf
	v_mov_b32_dpp v131, v123 row_ror:8 row_mask:0xf bank_mask:0xf
	v_mov_b32_e32 v132, v157
	v_mov_b32_dpp v133, v116 row_ror:8 row_mask:0xf bank_mask:0xf
	v_mov_b32_dpp v134, v117 row_ror:8 row_mask:0xf bank_mask:0xf
	v_pk_fma_f32 v[114:115], v[118:119], v[126:127], v[114:115]
	v_mov_b32_e32 v118, v157
	v_mov_b32_e32 v119, v157
	v_mov_b32_dpp v132, v113 row_ror:8 row_mask:0xf bank_mask:0xf
	v_mov_b32_dpp v118, v114 row_ror:8 row_mask:0xf bank_mask:0xf
	v_mov_b32_dpp v119, v115 row_ror:8 row_mask:0xf bank_mask:0xf
	v_cndmask_b32_e64 v115, v134, v115, s[0:1]
	v_cndmask_b32_e64 v114, v133, v114, s[0:1]
	v_cndmask_b32_e64 v113, v131, v113, s[0:1]
	v_cndmask_b32_e64 v112, v130, v112, s[0:1]
	v_cndmask_b32_e64 v119, v117, v119, s[0:1]
	v_cndmask_b32_e64 v118, v116, v118, s[0:1]
	v_cndmask_b32_e64 v117, v123, v132, s[0:1]
	v_cndmask_b32_e64 v116, v122, v129, s[0:1]
	global_store_dwordx4 v[124:125], v[112:115], off offset:128
	global_store_dwordx4 v[120:121], v[116:119], off offset:128
	v_mov_b32_e32 v137, v157
	v_or_b32_e32 v112, 32, v170
	v_ashrrev_i32_e32 v113, 31, v112
	v_lshl_add_u64 v[114:115], v[112:113], 2, s[6:7]
	v_sub_u32_e32 v112, v112, v174
	v_add_u32_e32 v130, v112, v176
	v_ashrrev_i32_e32 v131, 31, v130
	v_lshlrev_b64 v[112:113], 12, v[130:131]
	v_lshl_add_u64 v[126:127], v[112:113], 0, s[16:17]
	v_lshl_add_u64 v[118:119], s[8:9], 0, v[126:127]
	s_waitcnt vmcnt(4)
	s_nop 0
	v_mov_b32_e32 v132, v228
	v_lshl_add_u64 v[114:115], s[8:9], 0, v[112:113]
	v_lshl_add_u64 v[118:119], v[118:119], 0, v[164:165]
	v_lshl_add_u64 v[112:113], s[10:11], 0, v[112:113]
	v_lshl_add_u64 v[114:115], v[114:115], 0, v[164:165]
	v_mov_b64_e32 v[118:119], v[232:233]
	v_mov_b64_e32 v[120:121], v[234:235]
	v_lshl_add_u64 v[112:113], v[112:113], 0, v[164:165]
	v_mov_b64_e32 v[114:115], v[236:237]
	v_mov_b64_e32 v[116:117], v[238:239]
	v_mov_b32_e32 v138, v157
	v_mov_b64_e32 v[122:123], v[240:241]
	v_mov_b64_e32 v[124:125], v[242:243]
	v_lshl_add_u64 v[112:113], s[10:11], 0, v[126:127]
	v_lshl_add_u64 v[112:113], v[112:113], 0, v[164:165]
	v_mov_b64_e32 v[126:127], v[244:245]
	v_mov_b64_e32 v[128:129], v[246:247]
	s_nop 1
	v_or_b32_e32 v216, 48, v170
	v_ashrrev_i32_e32 v217, 31, v216
	v_lshl_add_u64 v[218:219], v[216:217], 2, s[6:7]
	v_sub_u32_e32 v216, v216, v174
	v_add_u32_e32 v224, v216, v176
	v_ashrrev_i32_e32 v225, 31, v224
	v_lshlrev_b64 v[216:217], 12, v[224:225]
	v_lshl_add_u64 v[222:223], v[216:217], 0, s[16:17]
	v_lshl_add_u64 v[220:221], s[8:9], 0, v[222:223]
	global_load_dword v228, v[218:219], off
	v_lshl_add_u64 v[218:219], s[8:9], 0, v[216:217]
	v_lshl_add_u64 v[220:221], v[220:221], 0, v[164:165]
	v_lshl_add_u64 v[216:217], s[10:11], 0, v[216:217]
	v_lshl_add_u64 v[218:219], v[218:219], 0, v[164:165]
	global_load_dwordx4 v[232:235], v[220:221], off
	v_lshl_add_u64 v[216:217], v[216:217], 0, v[164:165]
	global_load_dwordx4 v[236:239], v[218:219], off
	global_load_dwordx4 v[240:243], v[216:217], off
	v_lshl_add_u64 v[216:217], s[10:11], 0, v[222:223]
	v_lshl_add_u64 v[216:217], v[216:217], 0, v[164:165]
	global_load_dwordx4 v[244:247], v[216:217], off
	v_mov_b32_e32 v113, v157
	v_mov_b32_e32 v133, v157
	v_mov_b32_e32 v134, v157
	v_mov_b32_e32 v136, v157
	v_mov_b32_e32 v135, v157
	v_add_f32_e32 v105, 1.0, v105
	v_mul_f32_e32 v107, 0xbfb8aa3b, v107
	v_rcp_f32_e32 v105, v105
	v_exp_f32_e32 v106, v106
	v_exp_f32_e32 v107, v107
	v_mul_f32_e32 v110, 0xbfb8aa3b, v110
	v_mul_f32_e32 v111, 0xbfb8aa3b, v111
	v_exp_f32_e32 v110, v110
	v_exp_f32_e32 v111, v111
	v_add_f32_e32 v106, 1.0, v106
	v_add_f32_e32 v107, 1.0, v107
	v_rcp_f32_e32 v106, v106
	v_rcp_f32_e32 v107, v107
	v_add_f32_e32 v110, 1.0, v110
	v_add_f32_e32 v111, 1.0, v111
	v_mul_f32_e32 v96, 0xbfb8aa3b, v96
	v_mul_f32_e32 v97, 0xbfb8aa3b, v97
	v_rcp_f32_e32 v110, v110
	v_rcp_f32_e32 v111, v111
	v_exp_f32_e32 v96, v96
	v_exp_f32_e32 v97, v97
	v_mul_f32_e32 v100, 0xbfb8aa3b, v100
	v_mul_f32_e32 v101, 0xbfb8aa3b, v101
	v_exp_f32_e32 v100, v100
	v_exp_f32_e32 v101, v101
	v_add_f32_e32 v96, 1.0, v96
	v_add_f32_e32 v97, 1.0, v97
	v_rcp_f32_e32 v96, v96
	v_rcp_f32_e32 v97, v97
	v_mul_f32_e32 v98, 0xbfb8aa3b, v98
	v_mul_f32_e32 v99, 0xbfb8aa3b, v99
	v_add_f32_e32 v100, 1.0, v100
	v_add_f32_e32 v101, 1.0, v101
	v_exp_f32_e32 v98, v98
	v_exp_f32_e32 v99, v99
	v_rcp_f32_e32 v100, v100
	v_rcp_f32_e32 v101, v101
	v_mul_f32_e32 v102, 0xbfb8aa3b, v102
	v_mul_f32_e32 v103, 0xbfb8aa3b, v103
	v_exp_f32_e32 v102, v102
	v_exp_f32_e32 v103, v103
	v_add_f32_e32 v98, 1.0, v98
	v_add_f32_e32 v99, 1.0, v99
	v_rcp_f32_e32 v98, v98
; __device__ __forceinline__ float bflo(unsigned w) { return __uint_as_float(w << 16); }
;     const bool lo = fr < 8;
;     const int r1 = row - fr + (fr & 7), cb = col0 + (lo ? 0 : boff);
;     const u32x4 l1 = *(const u32x4*)(P + (size_t)r1 * ld + cb), l2 = *(const u32x4*)(P + (size_t)(r1 + 8) * ld + cb);
;     __device__ __forceinline__ void operator()(const f32x4 (&acc)[2][2][4][2], const Unit& u, int wr, int wc, int fr, int fq) const {
;         const int row0 = u.pm * BM + wr * 64 + fr, col0 = u.pn * BM + wc * 64 + 8 * fq;
;         f32x4 gv[2][2];
; #pragma unroll
;         for (int bj = 0; bj < 2; ++bj) { gv[bj][0] = *(const f32x4*)(g + col0 + 32 * bj); gv[bj][1] = *(const f32x4*)(g + col0 + 32 * bj + 4); }
;         const bool lo = fr < 8;
; #pragma unroll
;         for (int ai = 0; ai < 2; ++ai)
; #pragma unroll
;             for (int m = 0; m < 4; ++m) { const int row = row0 + ai * HALF + m * 16; const float ri = __builtin_amdgcn_rsqf(sse[row] * (1.f / D) + EPS);
;                 u32x4 rr[2], ee[2]; load_pair_lines(R, D, row, fr, col0, rr[0], rr[1], 32); load_pair_lines(E, D, row, fr, col0, ee[0], ee[1], 32);
;                 float* orow = OUT + (size_t)(row - fr + (fr & 7)) * D + col0 + (lo ? 0 : 4);
; #pragma unroll
;                 for (int bj = 0; bj < 2; ++bj) { const u32x4 rw = rr[bj], ew = ee[bj];
;                     const float r[8] = {bflo(rw.x), bfhi(rw.x), bflo(rw.y), bfhi(rw.y), bflo(rw.z), bfhi(rw.z), bflo(rw.w), bfhi(rw.w)};
;                     const float e[8] = {bflo(ew.x), bfhi(ew.x), bflo(ew.y), bfhi(ew.y), bflo(ew.z), bfhi(ew.z), bflo(ew.w), bfhi(ew.w)};
;                     float o[8];
; #pragma unroll
;                     for (int j = 0; j < 8; ++j) { const float a = acc[ai][bj][m][j >> 2][j & 3]; const float gg = gv[bj][j >> 2][j & 3];
;                         o[j] = r[j] + e[j] * ri * gg * __builtin_amdgcn_rcpf(1.f + __builtin_amdgcn_exp2f(-a * LOG2E)); }
;                     f32x4 o1, o2;
; #pragma unroll
;                     for (int j = 0; j < 4; ++j) { const unsigned a = __float_as_uint(o[j]), b = __float_as_uint(o[4 + j]); const unsigned sa = dpp_ror8(a), sb = dpp_ror8(b);
;                         o1[j] = __uint_as_float(lo ? a : sb); o2[j] = __uint_as_float(lo ? sa : b); }
;                     *(f32x4*)(orow + 32 * bj) = o1; *(f32x4*)(orow + (size_t)8 * D + 32 * bj) = o2; } }
	v_rcp_f32_e32 v99, v99
	v_add_f32_e32 v102, 1.0, v102
	v_add_f32_e32 v103, 1.0, v103
	v_rcp_f32_e32 v102, v102
	v_rcp_f32_e32 v103, v103
	v_mul_f32_e32 v88, 0xbfb8aa3b, v88
	v_mul_f32_e32 v89, 0xbfb8aa3b, v89
	v_mul_f32_e32 v92, 0xbfb8aa3b, v92
	v_exp_f32_e32 v88, v88
	v_exp_f32_e32 v89, v89
	v_mul_f32_e32 v90, 0xbfb8aa3b, v90
	v_mul_f32_e32 v91, 0xbfb8aa3b, v91
	v_add_f32_e32 v88, 1.0, v88
	v_add_f32_e32 v89, 1.0, v89
	v_rcp_f32_e32 v88, v88
	v_rcp_f32_e32 v89, v89
	v_exp_f32_e32 v90, v90
	v_exp_f32_e32 v91, v91
	v_fmamk_f32 v112, v132, 0x3a000000, v182
	v_mov_b32_e32 v132, v157
	v_rsq_f32_e32 v112, v112
	v_mul_f32_e32 v94, 0xbfb8aa3b, v94
	v_mul_f32_e32 v95, 0xbfb8aa3b, v95
	v_mov_b32_dpp v137, v120 row_ror:8 row_mask:0xf bank_mask:0xf
	v_mov_b32_dpp v138, v121 row_ror:8 row_mask:0xf bank_mask:0xf
	v_mov_b32_dpp v113, v114 row_ror:8 row_mask:0xf bank_mask:0xf
	v_mov_b32_dpp v132, v115 row_ror:8 row_mask:0xf bank_mask:0xf
	v_mov_b32_dpp v133, v116 row_ror:8 row_mask:0xf bank_mask:0xf
	v_mov_b32_dpp v134, v117 row_ror:8 row_mask:0xf bank_mask:0xf
	v_mov_b32_dpp v136, v119 row_ror:8 row_mask:0xf bank_mask:0xf
	v_cndmask_b32_e64 v138, v138, v117, s[0:1]
	v_cndmask_b32_e64 v117, v137, v116, s[0:1]
	v_mov_b32_e32 v116, v157
	v_mov_b32_dpp v135, v118 row_ror:8 row_mask:0xf bank_mask:0xf
	v_cndmask_b32_e64 v136, v136, v115, s[0:1]
	v_cndmask_b32_e64 v132, v119, v132, s[0:1]
	v_cndmask_b32_e64 v121, v121, v134, s[0:1]
	v_cndmask_b32_e64 v113, v118, v113, s[0:1]
	v_mov_b32_e32 v115, v157
	v_mov_b32_dpp v116, v124 row_ror:8 row_mask:0xf bank_mask:0xf
	v_mov_b32_e32 v118, v157
	v_mov_b32_e32 v119, v157
	v_mov_b32_e32 v134, v157
	v_cndmask_b32_e64 v135, v135, v114, s[0:1]
	v_cndmask_b32_e64 v120, v120, v133, s[0:1]
	v_mov_b32_e32 v114, v157
	v_mov_b32_dpp v115, v123 row_ror:8 row_mask:0xf bank_mask:0xf
	v_mov_b32_dpp v118, v125 row_ror:8 row_mask:0xf bank_mask:0xf
	v_mov_b32_dpp v119, v126 row_ror:8 row_mask:0xf bank_mask:0xf
	v_mov_b32_e32 v133, v157
	v_mov_b32_dpp v134, v128 row_ror:8 row_mask:0xf bank_mask:0xf
	v_cndmask_b32_e64 v128, v128, v116, s[0:1]
	v_exp_f32_e32 v116, v108
	v_mul_f32_e32 v108, 0xbfb8aa3b, v109
	v_mov_b32_dpp v114, v122 row_ror:8 row_mask:0xf bank_mask:0xf
	v_mov_b32_dpp v133, v127 row_ror:8 row_mask:0xf bank_mask:0xf
	v_cndmask_b32_e64 v122, v119, v122, s[0:1]
	v_cndmask_b32_e64 v119, v134, v124, s[0:1]
	v_cndmask_b32_e64 v124, v127, v115, s[0:1]
	v_cndmask_b32_e64 v127, v129, v118, s[0:1]
	v_exp_f32_e32 v118, v108
	v_cndmask_b32_e64 v126, v126, v114, s[0:1]
	v_lshlrev_b64 v[114:115], 13, v[130:131]
	v_lshl_add_u64 v[114:115], s[4:5], 0, v[114:115]
	v_lshl_add_u64 v[114:115], v[114:115], 0, v[166:167]
	v_lshl_add_u64 v[108:109], v[114:115], 0, v[156:157]
	v_add_f32_e32 v115, 1.0, v118
	v_lshlrev_b32_e32 v118, 16, v119
	v_and_b32_e32 v119, 0xffff0000, v119
	v_add_f32_e32 v114, 1.0, v116
	v_pk_mul_f32 v[118:119], v[112:113], v[118:119] op_sel_hi:[0,1]
	v_rcp_f32_e32 v114, v114
	v_rcp_f32_e32 v115, v115
	v_lshlrev_b32_e32 v116, 16, v117
	v_and_b32_e32 v117, 0xffff0000, v117
	v_pk_mul_f32 v[118:119], v[60:61], v[118:119]
	v_mov_b32_e32 v137, v157
	v_pk_fma_f32 v[118:119], v[104:105], v[118:119], v[116:117]
	v_lshlrev_b32_e32 v116, 16, v122
	v_and_b32_e32 v117, 0xffff0000, v122
	v_mov_b32_dpp v137, v129 row_ror:8 row_mask:0xf bank_mask:0xf
	v_pk_mul_f32 v[116:117], v[112:113], v[116:117] op_sel_hi:[0,1]
	v_cndmask_b32_e64 v125, v137, v125, s[0:1]
	v_lshlrev_b32_e32 v104, 16, v135
	v_and_b32_e32 v105, 0xffff0000, v135
	v_pk_mul_f32 v[116:117], v[56:57], v[116:117]
	v_cndmask_b32_e64 v123, v133, v123, s[0:1]
	v_pk_fma_f32 v[104:105], v[114:115], v[116:117], v[104:105]
	v_lshlrev_b32_e32 v116, 16, v125
	v_and_b32_e32 v117, 0xffff0000, v125
	v_pk_mul_f32 v[116:117], v[112:113], v[116:117] op_sel_hi:[0,1]
	v_lshlrev_b32_e32 v114, 16, v138
	v_and_b32_e32 v115, 0xffff0000, v138
	v_pk_mul_f32 v[116:117], v[62:63], v[116:117]
	v_mov_b32_e32 v129, v157
	v_pk_fma_f32 v[114:115], v[106:107], v[116:117], v[114:115]
	v_lshlrev_b32_e32 v116, 16, v123
	v_and_b32_e32 v117, 0xffff0000, v123
	v_pk_mul_f32 v[116:117], v[112:113], v[116:117] op_sel_hi:[0,1]
	v_lshlrev_b32_e32 v106, 16, v136
	v_and_b32_e32 v107, 0xffff0000, v136
	v_pk_mul_f32 v[116:117], v[58:59], v[116:117]
	v_mov_b32_e32 v130, v157
	v_pk_fma_f32 v[106:107], v[110:111], v[116:117], v[106:107]
	v_mov_b32_e32 v110, v157
	v_mov_b32_e32 v111, v157
	v_mov_b32_e32 v125, v157
	v_mov_b32_e32 v133, v157
	v_mov_b32_dpp v110, v106 row_ror:8 row_mask:0xf bank_mask:0xf
	v_mov_b32_dpp v111, v107 row_ror:8 row_mask:0xf bank_mask:0xf
	v_mov_b32_dpp v129, v118 row_ror:8 row_mask:0xf bank_mask:0xf
	v_mov_b32_dpp v130, v119 row_ror:8 row_mask:0xf bank_mask:0xf
	v_mov_b32_e32 v122, v157
	v_mov_b32_e32 v131, v157
	v_mov_b32_dpp v125, v114 row_ror:8 row_mask:0xf bank_mask:0xf
	v_mov_b32_dpp v133, v115 row_ror:8 row_mask:0xf bank_mask:0xf
	v_cndmask_b32_e64 v117, v115, v111, s[0:1]
	v_cndmask_b32_e64 v116, v114, v110, s[0:1]
	v_lshlrev_b32_e32 v110, 16, v128
	v_and_b32_e32 v111, 0xffff0000, v128
	v_mov_b32_dpp v122, v104 row_ror:8 row_mask:0xf bank_mask:0xf
	v_mov_b32_dpp v131, v105 row_ror:8 row_mask:0xf bank_mask:0xf
	v_cndmask_b32_e64 v107, v133, v107, s[0:1]
	v_cndmask_b32_e64 v106, v125, v106, s[0:1]
	v_cndmask_b32_e64 v105, v130, v105, s[0:1]
	v_cndmask_b32_e64 v104, v129, v104, s[0:1]
	v_pk_mul_f32 v[110:111], v[112:113], v[110:111] op_sel_hi:[0,1]
	global_store_dwordx4 v[108:109], v[104:107], off
	v_pk_mul_f32 v[110:111], v[44:45], v[110:111]
	v_cndmask_b32_e64 v115, v119, v131, s[0:1]
	v_lshlrev_b32_e32 v106, 16, v120
	v_and_b32_e32 v107, 0xffff0000, v120
	v_pk_fma_f32 v[106:107], v[96:97], v[110:111], v[106:107]
; __device__ __forceinline__ float bflo(unsigned w) { return __uint_as_float(w << 16); }
;     const bool lo = fr < 8;
;     const int r1 = row - fr + (fr & 7), cb = col0 + (lo ? 0 : boff);
;     const u32x4 l1 = *(const u32x4*)(P + (size_t)r1 * ld + cb), l2 = *(const u32x4*)(P + (size_t)(r1 + 8) * ld + cb);
;     __device__ __forceinline__ void operator()(const f32x4 (&acc)[2][2][4][2], const Unit& u, int wr, int wc, int fr, int fq) const {
;         const int row0 = u.pm * BM + wr * 64 + fr, col0 = u.pn * BM + wc * 64 + 8 * fq;
;         f32x4 gv[2][2];
; #pragma unroll
;         for (int bj = 0; bj < 2; ++bj) { gv[bj][0] = *(const f32x4*)(g + col0 + 32 * bj); gv[bj][1] = *(const f32x4*)(g + col0 + 32 * bj + 4); }
;         const bool lo = fr < 8;
; #pragma unroll
;         for (int ai = 0; ai < 2; ++ai)
; #pragma unroll
;             for (int m = 0; m < 4; ++m) { const int row = row0 + ai * HALF + m * 16; const float ri = __builtin_amdgcn_rsqf(sse[row] * (1.f / D) + EPS);
;                 u32x4 rr[2], ee[2]; load_pair_lines(R, D, row, fr, col0, rr[0], rr[1], 32); load_pair_lines(E, D, row, fr, col0, ee[0], ee[1], 32);
;                 float* orow = OUT + (size_t)(row - fr + (fr & 7)) * D + col0 + (lo ? 0 : 4);
; #pragma unroll
;                 for (int bj = 0; bj < 2; ++bj) { const u32x4 rw = rr[bj], ew = ee[bj];
;                     const float r[8] = {bflo(rw.x), bfhi(rw.x), bflo(rw.y), bfhi(rw.y), bflo(rw.z), bfhi(rw.z), bflo(rw.w), bfhi(rw.w)};
;                     const float e[8] = {bflo(ew.x), bfhi(ew.x), bflo(ew.y), bfhi(ew.y), bflo(ew.z), bfhi(ew.z), bflo(ew.w), bfhi(ew.w)};
;                     float o[8];
; #pragma unroll
;                     for (int j = 0; j < 8; ++j) { const float a = acc[ai][bj][m][j >> 2][j & 3]; const float gg = gv[bj][j >> 2][j & 3];
;                         o[j] = r[j] + e[j] * ri * gg * __builtin_amdgcn_rcpf(1.f + __builtin_amdgcn_exp2f(-a * LOG2E)); }
;                     f32x4 o1, o2;
; #pragma unroll
;                     for (int j = 0; j < 4; ++j) { const unsigned a = __float_as_uint(o[j]), b = __float_as_uint(o[4 + j]); const unsigned sa = dpp_ror8(a), sb = dpp_ror8(b);
;                         o1[j] = __uint_as_float(lo ? a : sb); o2[j] = __uint_as_float(lo ? sa : b); }
;                     *(f32x4*)(orow + 32 * bj) = o1; *(f32x4*)(orow + (size_t)8 * D + 32 * bj) = o2; } }
	v_lshlrev_b32_e32 v110, 16, v126
	v_and_b32_e32 v111, 0xffff0000, v126
	v_pk_mul_f32 v[110:111], v[112:113], v[110:111] op_sel_hi:[0,1]
	v_lshlrev_b32_e32 v96, 16, v113
	v_and_b32_e32 v97, 0xffff0000, v113
	v_pk_mul_f32 v[110:111], v[40:41], v[110:111]
	v_mov_b32_e32 v113, v157
	v_pk_fma_f32 v[96:97], v[100:101], v[110:111], v[96:97]
	v_lshlrev_b32_e32 v110, 16, v127
	v_and_b32_e32 v111, 0xffff0000, v127
	v_mov_b32_dpp v113, v96 row_ror:8 row_mask:0xf bank_mask:0xf
	v_pk_mul_f32 v[110:111], v[112:113], v[110:111] op_sel_hi:[0,1]
	v_lshlrev_b32_e32 v100, 16, v121
	v_and_b32_e32 v101, 0xffff0000, v121
	v_pk_mul_f32 v[110:111], v[46:47], v[110:111]
	v_add_co_u32_e32 v104, vcc, s45, v108
	v_pk_fma_f32 v[100:101], v[98:99], v[110:111], v[100:101]
	v_lshlrev_b32_e32 v110, 16, v124
	v_and_b32_e32 v111, 0xffff0000, v124
	v_cndmask_b32_e64 v114, v118, v122, s[0:1]
	v_addc_co_u32_e32 v105, vcc, 0, v109, vcc
	v_pk_mul_f32 v[110:111], v[112:113], v[110:111] op_sel_hi:[0,1]
	global_store_dwordx4 v[104:105], v[114:117], off
	v_mov_b32_e32 v118, v157
	v_lshlrev_b32_e32 v98, 16, v132
	v_mov_b32_e32 v114, v157
	v_mov_b32_e32 v115, v157
	v_mov_b32_e32 v117, v157
	v_and_b32_e32 v99, 0xffff0000, v132
	v_pk_mul_f32 v[110:111], v[42:43], v[110:111]
	v_mov_b32_dpp v114, v106 row_ror:8 row_mask:0xf bank_mask:0xf
	v_mov_b32_dpp v115, v107 row_ror:8 row_mask:0xf bank_mask:0xf
	v_mov_b32_e32 v116, v157
	v_mov_b32_dpp v117, v100 row_ror:8 row_mask:0xf bank_mask:0xf
	v_mov_b32_dpp v118, v101 row_ror:8 row_mask:0xf bank_mask:0xf
	v_pk_fma_f32 v[98:99], v[102:103], v[110:111], v[98:99]
	v_mov_b32_e32 v102, v157
	v_mov_b32_e32 v103, v157
	v_mov_b32_dpp v116, v97 row_ror:8 row_mask:0xf bank_mask:0xf
	v_mov_b32_dpp v102, v98 row_ror:8 row_mask:0xf bank_mask:0xf
	v_mov_b32_dpp v103, v99 row_ror:8 row_mask:0xf bank_mask:0xf
	v_cndmask_b32_e64 v99, v118, v99, s[0:1]
	v_cndmask_b32_e64 v98, v117, v98, s[0:1]
	v_cndmask_b32_e64 v97, v115, v97, s[0:1]
	v_cndmask_b32_e64 v96, v114, v96, s[0:1]
	v_cndmask_b32_e64 v103, v101, v103, s[0:1]
	v_cndmask_b32_e64 v102, v100, v102, s[0:1]
	v_cndmask_b32_e64 v101, v107, v116, s[0:1]
	v_cndmask_b32_e64 v100, v106, v113, s[0:1]
	global_store_dwordx4 v[108:109], v[96:99], off offset:128
	global_store_dwordx4 v[104:105], v[100:103], off offset:128
	v_mov_b32_e32 v121, v157
	v_or_b32_e32 v96, 48, v170
	v_ashrrev_i32_e32 v97, 31, v96
	v_lshl_add_u64 v[98:99], v[96:97], 2, s[6:7]
	v_sub_u32_e32 v96, v96, v174
	v_add_u32_e32 v114, v96, v176
	v_ashrrev_i32_e32 v115, 31, v114
	v_lshlrev_b64 v[96:97], 12, v[114:115]
	v_lshl_add_u64 v[110:111], v[96:97], 0, s[16:17]
	v_lshl_add_u64 v[102:103], s[8:9], 0, v[110:111]
	s_waitcnt vmcnt(4)
	s_nop 0
	v_mov_b32_e32 v116, v228
	v_lshl_add_u64 v[98:99], s[8:9], 0, v[96:97]
	v_lshl_add_u64 v[102:103], v[102:103], 0, v[164:165]
	v_lshl_add_u64 v[96:97], s[10:11], 0, v[96:97]
	v_lshl_add_u64 v[98:99], v[98:99], 0, v[164:165]
	v_mov_b64_e32 v[102:103], v[232:233]
	v_mov_b64_e32 v[104:105], v[234:235]
	v_lshl_add_u64 v[96:97], v[96:97], 0, v[164:165]
	v_mov_b64_e32 v[98:99], v[236:237]
	v_mov_b64_e32 v[100:101], v[238:239]
	v_mov_b32_e32 v122, v157
	v_mov_b64_e32 v[106:107], v[240:241]
	v_mov_b64_e32 v[108:109], v[242:243]
	v_lshl_add_u64 v[96:97], s[10:11], 0, v[110:111]
	v_lshl_add_u64 v[96:97], v[96:97], 0, v[164:165]
	v_mov_b64_e32 v[110:111], v[244:245]
	v_mov_b64_e32 v[112:113], v[246:247]
	s_nop 1
	global_load_dword v228, v[168:169], off offset:512
	v_sub_u32_e32 v217, v170, v174
	v_add_u32_e32 v217, v217, v176
	v_add_u32_e32 v226, 0x80, v217
	v_ashrrev_i32_e32 v227, 31, v226
	v_lshlrev_b64 v[222:223], 12, v[226:227]
	v_lshl_add_u64 v[224:225], v[222:223], 0, s[16:17]
	v_lshl_add_u64 v[218:219], s[8:9], 0, v[222:223]
	v_lshl_add_u64 v[220:221], s[8:9], 0, v[224:225]
	v_lshl_add_u64 v[218:219], v[218:219], 0, v[164:165]
	v_lshl_add_u64 v[220:221], v[220:221], 0, v[164:165]
	global_load_dwordx4 v[232:235], v[218:219], off
	v_lshl_add_u64 v[222:223], s[10:11], 0, v[222:223]
	global_load_dwordx4 v[236:239], v[220:221], off
	v_lshl_add_u64 v[222:223], v[222:223], 0, v[164:165]
	v_lshl_add_u64 v[224:225], s[10:11], 0, v[224:225]
	global_load_dwordx4 v[240:243], v[222:223], off
	v_lshl_add_u64 v[224:225], v[224:225], 0, v[164:165]
	global_load_dwordx4 v[244:247], v[224:225], off
	v_mov_b32_e32 v97, v157
	v_mov_b32_e32 v117, v157
	v_mov_b32_e32 v118, v157
	v_mov_b32_e32 v120, v157
	v_mov_b32_e32 v119, v157
	v_exp_f32_e32 v94, v94
	v_exp_f32_e32 v95, v95
	v_add_f32_e32 v90, 1.0, v90
	v_add_f32_e32 v91, 1.0, v91
	v_rcp_f32_e32 v90, v90
	v_rcp_f32_e32 v91, v91
	v_add_f32_e32 v94, 1.0, v94
	v_add_f32_e32 v95, 1.0, v95
	v_mul_f32_e32 v80, 0xbfb8aa3b, v80
	v_mul_f32_e32 v81, 0xbfb8aa3b, v81
	v_rcp_f32_e32 v94, v94
	v_rcp_f32_e32 v95, v95
	v_exp_f32_e32 v80, v80
	v_exp_f32_e32 v81, v81
	v_mul_f32_e32 v84, 0xbfb8aa3b, v84
	v_mul_f32_e32 v85, 0xbfb8aa3b, v85
	v_exp_f32_e32 v84, v84
	v_exp_f32_e32 v85, v85
	v_add_f32_e32 v80, 1.0, v80
	v_add_f32_e32 v81, 1.0, v81
	v_rcp_f32_e32 v80, v80
	v_rcp_f32_e32 v81, v81
	v_mul_f32_e32 v82, 0xbfb8aa3b, v82
	v_mul_f32_e32 v83, 0xbfb8aa3b, v83
	v_add_f32_e32 v84, 1.0, v84
	v_add_f32_e32 v85, 1.0, v85
	v_exp_f32_e32 v82, v82
	v_exp_f32_e32 v83, v83
	v_rcp_f32_e32 v84, v84
	v_rcp_f32_e32 v85, v85
	v_mul_f32_e32 v86, 0xbfb8aa3b, v86
	v_mul_f32_e32 v87, 0xbfb8aa3b, v87
	v_exp_f32_e32 v86, v86
	v_exp_f32_e32 v87, v87
	v_add_f32_e32 v82, 1.0, v82
	v_add_f32_e32 v83, 1.0, v83
	v_rcp_f32_e32 v82, v82
	v_rcp_f32_e32 v83, v83
	v_add_f32_e32 v86, 1.0, v86
	v_add_f32_e32 v87, 1.0, v87
	v_rcp_f32_e32 v86, v86
	v_rcp_f32_e32 v87, v87
	v_mul_f32_e32 v72, 0xbfb8aa3b, v72
	v_mul_f32_e32 v73, 0xbfb8aa3b, v73
; __device__ __forceinline__ float bflo(unsigned w) { return __uint_as_float(w << 16); }
;     const bool lo = fr < 8;
;     const int r1 = row - fr + (fr & 7), cb = col0 + (lo ? 0 : boff);
;     const u32x4 l1 = *(const u32x4*)(P + (size_t)r1 * ld + cb), l2 = *(const u32x4*)(P + (size_t)(r1 + 8) * ld + cb);
;     __device__ __forceinline__ void operator()(const f32x4 (&acc)[2][2][4][2], const Unit& u, int wr, int wc, int fr, int fq) const {
;         const int row0 = u.pm * BM + wr * 64 + fr, col0 = u.pn * BM + wc * 64 + 8 * fq;
;         f32x4 gv[2][2];
; #pragma unroll
;         for (int bj = 0; bj < 2; ++bj) { gv[bj][0] = *(const f32x4*)(g + col0 + 32 * bj); gv[bj][1] = *(const f32x4*)(g + col0 + 32 * bj + 4); }
;         const bool lo = fr < 8;
; #pragma unroll
;         for (int ai = 0; ai < 2; ++ai)
; #pragma unroll
;             for (int m = 0; m < 4; ++m) { const int row = row0 + ai * HALF + m * 16; const float ri = __builtin_amdgcn_rsqf(sse[row] * (1.f / D) + EPS);
;                 u32x4 rr[2], ee[2]; load_pair_lines(R, D, row, fr, col0, rr[0], rr[1], 32); load_pair_lines(E, D, row, fr, col0, ee[0], ee[1], 32);
;                 float* orow = OUT + (size_t)(row - fr + (fr & 7)) * D + col0 + (lo ? 0 : 4);
; #pragma unroll
;                 for (int bj = 0; bj < 2; ++bj) { const u32x4 rw = rr[bj], ew = ee[bj];
;                     const float r[8] = {bflo(rw.x), bfhi(rw.x), bflo(rw.y), bfhi(rw.y), bflo(rw.z), bfhi(rw.z), bflo(rw.w), bfhi(rw.w)};
;                     const float e[8] = {bflo(ew.x), bfhi(ew.x), bflo(ew.y), bfhi(ew.y), bflo(ew.z), bfhi(ew.z), bflo(ew.w), bfhi(ew.w)};
;                     float o[8];
; #pragma unroll
;                     for (int j = 0; j < 8; ++j) { const float a = acc[ai][bj][m][j >> 2][j & 3]; const float gg = gv[bj][j >> 2][j & 3];
;                         o[j] = r[j] + e[j] * ri * gg * __builtin_amdgcn_rcpf(1.f + __builtin_amdgcn_exp2f(-a * LOG2E)); }
;                     f32x4 o1, o2;
; #pragma unroll
;                     for (int j = 0; j < 4; ++j) { const unsigned a = __float_as_uint(o[j]), b = __float_as_uint(o[4 + j]); const unsigned sa = dpp_ror8(a), sb = dpp_ror8(b);
;                         o1[j] = __uint_as_float(lo ? a : sb); o2[j] = __uint_as_float(lo ? sa : b); }
;                     *(f32x4*)(orow + 32 * bj) = o1; *(f32x4*)(orow + (size_t)8 * D + 32 * bj) = o2; } }
	v_mul_f32_e32 v76, 0xbfb8aa3b, v76
	v_exp_f32_e32 v72, v72
	v_exp_f32_e32 v73, v73
	v_mul_f32_e32 v74, 0xbfb8aa3b, v74
	v_mul_f32_e32 v75, 0xbfb8aa3b, v75
	v_add_f32_e32 v72, 1.0, v72
	v_add_f32_e32 v73, 1.0, v73
	v_rcp_f32_e32 v72, v72
	v_rcp_f32_e32 v73, v73
	v_exp_f32_e32 v74, v74
	v_exp_f32_e32 v75, v75
	v_mul_f32_e32 v78, 0xbfb8aa3b, v78
	v_mul_f32_e32 v79, 0xbfb8aa3b, v79
	v_exp_f32_e32 v78, v78
	v_exp_f32_e32 v79, v79
	v_add_f32_e32 v74, 1.0, v74
	v_add_f32_e32 v75, 1.0, v75
	v_rcp_f32_e32 v74, v74
	v_fmamk_f32 v96, v116, 0x3a000000, v182
	v_mov_b32_e32 v116, v157
	v_rsq_f32_e32 v96, v96
	v_rcp_f32_e32 v75, v75
	v_add_f32_e32 v78, 1.0, v78
	v_mov_b32_dpp v121, v104 row_ror:8 row_mask:0xf bank_mask:0xf
	v_mov_b32_dpp v122, v105 row_ror:8 row_mask:0xf bank_mask:0xf
	v_mov_b32_dpp v97, v98 row_ror:8 row_mask:0xf bank_mask:0xf
	v_mov_b32_dpp v116, v99 row_ror:8 row_mask:0xf bank_mask:0xf
	v_mov_b32_dpp v117, v100 row_ror:8 row_mask:0xf bank_mask:0xf
	v_mov_b32_dpp v118, v101 row_ror:8 row_mask:0xf bank_mask:0xf
	v_mov_b32_dpp v120, v103 row_ror:8 row_mask:0xf bank_mask:0xf
	v_cndmask_b32_e64 v122, v122, v101, s[0:1]
	v_cndmask_b32_e64 v101, v121, v100, s[0:1]
	v_mov_b32_e32 v100, v157
	v_mov_b32_dpp v119, v102 row_ror:8 row_mask:0xf bank_mask:0xf
	v_cndmask_b32_e64 v120, v120, v99, s[0:1]
	v_cndmask_b32_e64 v116, v103, v116, s[0:1]
	v_cndmask_b32_e64 v105, v105, v118, s[0:1]
	v_cndmask_b32_e64 v97, v102, v97, s[0:1]
	v_mov_b32_e32 v99, v157
	v_mov_b32_dpp v100, v108 row_ror:8 row_mask:0xf bank_mask:0xf
	v_mov_b32_e32 v102, v157
	v_mov_b32_e32 v103, v157
	v_mov_b32_e32 v118, v157
	v_cndmask_b32_e64 v119, v119, v98, s[0:1]
	v_cndmask_b32_e64 v104, v104, v117, s[0:1]
	v_mov_b32_e32 v98, v157
	v_mov_b32_dpp v99, v107 row_ror:8 row_mask:0xf bank_mask:0xf
	v_mov_b32_dpp v102, v109 row_ror:8 row_mask:0xf bank_mask:0xf
	v_mov_b32_dpp v103, v110 row_ror:8 row_mask:0xf bank_mask:0xf
	v_mov_b32_e32 v117, v157
	v_mov_b32_dpp v118, v112 row_ror:8 row_mask:0xf bank_mask:0xf
	v_cndmask_b32_e64 v112, v112, v100, s[0:1]
	v_exp_f32_e32 v100, v92
	v_mul_f32_e32 v92, 0xbfb8aa3b, v93
	v_mov_b32_dpp v98, v106 row_ror:8 row_mask:0xf bank_mask:0xf
	v_mov_b32_dpp v117, v111 row_ror:8 row_mask:0xf bank_mask:0xf
	v_cndmask_b32_e64 v106, v103, v106, s[0:1]
	v_cndmask_b32_e64 v103, v118, v108, s[0:1]
	v_cndmask_b32_e64 v108, v111, v99, s[0:1]
	v_cndmask_b32_e64 v111, v113, v102, s[0:1]
	v_exp_f32_e32 v102, v92
	v_cndmask_b32_e64 v110, v110, v98, s[0:1]
	v_lshlrev_b64 v[98:99], 13, v[114:115]
	v_lshl_add_u64 v[98:99], s[4:5], 0, v[98:99]
	v_lshl_add_u64 v[98:99], v[98:99], 0, v[166:167]
	v_lshl_add_u64 v[92:93], v[98:99], 0, v[156:157]
	v_add_f32_e32 v99, 1.0, v102
	v_lshlrev_b32_e32 v102, 16, v103
	v_and_b32_e32 v103, 0xffff0000, v103
	v_add_f32_e32 v98, 1.0, v100
	v_pk_mul_f32 v[102:103], v[96:97], v[102:103] op_sel_hi:[0,1]
	v_rcp_f32_e32 v98, v98
	v_rcp_f32_e32 v99, v99
	v_lshlrev_b32_e32 v100, 16, v101
	v_and_b32_e32 v101, 0xffff0000, v101
	v_pk_mul_f32 v[102:103], v[60:61], v[102:103]
	v_mov_b32_e32 v121, v157
	v_pk_fma_f32 v[102:103], v[88:89], v[102:103], v[100:101]
	v_lshlrev_b32_e32 v100, 16, v106
	v_and_b32_e32 v101, 0xffff0000, v106
	v_mov_b32_dpp v121, v113 row_ror:8 row_mask:0xf bank_mask:0xf
	v_pk_mul_f32 v[100:101], v[96:97], v[100:101] op_sel_hi:[0,1]
	v_cndmask_b32_e64 v109, v121, v109, s[0:1]
	v_lshlrev_b32_e32 v88, 16, v119
	v_and_b32_e32 v89, 0xffff0000, v119
	v_pk_mul_f32 v[100:101], v[56:57], v[100:101]
	v_cndmask_b32_e64 v107, v117, v107, s[0:1]
	v_pk_fma_f32 v[88:89], v[98:99], v[100:101], v[88:89]
	v_lshlrev_b32_e32 v100, 16, v109
	v_and_b32_e32 v101, 0xffff0000, v109
	v_pk_mul_f32 v[100:101], v[96:97], v[100:101] op_sel_hi:[0,1]
	v_lshlrev_b32_e32 v98, 16, v122
	v_and_b32_e32 v99, 0xffff0000, v122
	v_pk_mul_f32 v[100:101], v[62:63], v[100:101]
	v_mov_b32_e32 v113, v157
	v_pk_fma_f32 v[98:99], v[90:91], v[100:101], v[98:99]
	v_lshlrev_b32_e32 v100, 16, v107
	v_and_b32_e32 v101, 0xffff0000, v107
	v_pk_mul_f32 v[100:101], v[96:97], v[100:101] op_sel_hi:[0,1]
	v_lshlrev_b32_e32 v90, 16, v120
	v_and_b32_e32 v91, 0xffff0000, v120
	v_pk_mul_f32 v[100:101], v[58:59], v[100:101]
	v_mov_b32_e32 v114, v157
	v_pk_fma_f32 v[90:91], v[94:95], v[100:101], v[90:91]
	v_mov_b32_e32 v94, v157
	v_mov_b32_e32 v95, v157
	v_mov_b32_e32 v109, v157
	v_mov_b32_e32 v117, v157
	v_mov_b32_dpp v94, v90 row_ror:8 row_mask:0xf bank_mask:0xf
	v_mov_b32_dpp v95, v91 row_ror:8 row_mask:0xf bank_mask:0xf
	v_mov_b32_dpp v113, v102 row_ror:8 row_mask:0xf bank_mask:0xf
	v_mov_b32_dpp v114, v103 row_ror:8 row_mask:0xf bank_mask:0xf
	v_mov_b32_e32 v106, v157
	v_mov_b32_e32 v115, v157
	v_mov_b32_dpp v109, v98 row_ror:8 row_mask:0xf bank_mask:0xf
	v_mov_b32_dpp v117, v99 row_ror:8 row_mask:0xf bank_mask:0xf
	v_cndmask_b32_e64 v101, v99, v95, s[0:1]
	v_cndmask_b32_e64 v100, v98, v94, s[0:1]
	v_lshlrev_b32_e32 v94, 16, v112
	v_and_b32_e32 v95, 0xffff0000, v112
	v_mov_b32_dpp v106, v88 row_ror:8 row_mask:0xf bank_mask:0xf
	v_mov_b32_dpp v115, v89 row_ror:8 row_mask:0xf bank_mask:0xf
	v_cndmask_b32_e64 v91, v117, v91, s[0:1]
	v_cndmask_b32_e64 v90, v109, v90, s[0:1]
	v_cndmask_b32_e64 v89, v114, v89, s[0:1]
	v_cndmask_b32_e64 v88, v113, v88, s[0:1]
	v_pk_mul_f32 v[94:95], v[96:97], v[94:95] op_sel_hi:[0,1]
	global_store_dwordx4 v[92:93], v[88:91], off
	v_pk_mul_f32 v[94:95], v[44:45], v[94:95]
	v_cndmask_b32_e64 v99, v103, v115, s[0:1]
	v_lshlrev_b32_e32 v90, 16, v104
	v_and_b32_e32 v91, 0xffff0000, v104
	v_pk_fma_f32 v[90:91], v[80:81], v[94:95], v[90:91]
	v_lshlrev_b32_e32 v94, 16, v110
	v_and_b32_e32 v95, 0xffff0000, v110
	v_pk_mul_f32 v[94:95], v[96:97], v[94:95] op_sel_hi:[0,1]
; __device__ __forceinline__ float bflo(unsigned w) { return __uint_as_float(w << 16); }
;     const bool lo = fr < 8;
;     const int r1 = row - fr + (fr & 7), cb = col0 + (lo ? 0 : boff);
;     const u32x4 l1 = *(const u32x4*)(P + (size_t)r1 * ld + cb), l2 = *(const u32x4*)(P + (size_t)(r1 + 8) * ld + cb);
;     __device__ __forceinline__ void operator()(const f32x4 (&acc)[2][2][4][2], const Unit& u, int wr, int wc, int fr, int fq) const {
;         const int row0 = u.pm * BM + wr * 64 + fr, col0 = u.pn * BM + wc * 64 + 8 * fq;
;         f32x4 gv[2][2];
; #pragma unroll
;         for (int bj = 0; bj < 2; ++bj) { gv[bj][0] = *(const f32x4*)(g + col0 + 32 * bj); gv[bj][1] = *(const f32x4*)(g + col0 + 32 * bj + 4); }
;         const bool lo = fr < 8;
; #pragma unroll
;         for (int ai = 0; ai < 2; ++ai)
; #pragma unroll
;             for (int m = 0; m < 4; ++m) { const int row = row0 + ai * HALF + m * 16; const float ri = __builtin_amdgcn_rsqf(sse[row] * (1.f / D) + EPS);
;                 u32x4 rr[2], ee[2]; load_pair_lines(R, D, row, fr, col0, rr[0], rr[1], 32); load_pair_lines(E, D, row, fr, col0, ee[0], ee[1], 32);
;                 float* orow = OUT + (size_t)(row - fr + (fr & 7)) * D + col0 + (lo ? 0 : 4);
; #pragma unroll
;                 for (int bj = 0; bj < 2; ++bj) { const u32x4 rw = rr[bj], ew = ee[bj];
;                     const float r[8] = {bflo(rw.x), bfhi(rw.x), bflo(rw.y), bfhi(rw.y), bflo(rw.z), bfhi(rw.z), bflo(rw.w), bfhi(rw.w)};
;                     const float e[8] = {bflo(ew.x), bfhi(ew.x), bflo(ew.y), bfhi(ew.y), bflo(ew.z), bfhi(ew.z), bflo(ew.w), bfhi(ew.w)};
;                     float o[8];
; #pragma unroll
;                     for (int j = 0; j < 8; ++j) { const float a = acc[ai][bj][m][j >> 2][j & 3]; const float gg = gv[bj][j >> 2][j & 3];
;                         o[j] = r[j] + e[j] * ri * gg * __builtin_amdgcn_rcpf(1.f + __builtin_amdgcn_exp2f(-a * LOG2E)); }
;                     f32x4 o1, o2;
; #pragma unroll
;                     for (int j = 0; j < 4; ++j) { const unsigned a = __float_as_uint(o[j]), b = __float_as_uint(o[4 + j]); const unsigned sa = dpp_ror8(a), sb = dpp_ror8(b);
;                         o1[j] = __uint_as_float(lo ? a : sb); o2[j] = __uint_as_float(lo ? sa : b); }
;                     *(f32x4*)(orow + 32 * bj) = o1; *(f32x4*)(orow + (size_t)8 * D + 32 * bj) = o2; } }
	v_lshlrev_b32_e32 v80, 16, v97
	v_and_b32_e32 v81, 0xffff0000, v97
	v_pk_mul_f32 v[94:95], v[40:41], v[94:95]
	v_mov_b32_e32 v97, v157
	v_pk_fma_f32 v[80:81], v[84:85], v[94:95], v[80:81]
	v_lshlrev_b32_e32 v94, 16, v111
	v_and_b32_e32 v95, 0xffff0000, v111
	v_mov_b32_dpp v97, v80 row_ror:8 row_mask:0xf bank_mask:0xf
	v_pk_mul_f32 v[94:95], v[96:97], v[94:95] op_sel_hi:[0,1]
	v_lshlrev_b32_e32 v84, 16, v105
	v_and_b32_e32 v85, 0xffff0000, v105
	v_pk_mul_f32 v[94:95], v[46:47], v[94:95]
	v_add_co_u32_e32 v88, vcc, s45, v92
	v_pk_fma_f32 v[84:85], v[82:83], v[94:95], v[84:85]
	v_lshlrev_b32_e32 v94, 16, v108
	v_and_b32_e32 v95, 0xffff0000, v108
	v_cndmask_b32_e64 v98, v102, v106, s[0:1]
	v_addc_co_u32_e32 v89, vcc, 0, v93, vcc
	v_pk_mul_f32 v[94:95], v[96:97], v[94:95] op_sel_hi:[0,1]
	global_store_dwordx4 v[88:89], v[98:101], off
	v_mov_b32_e32 v102, v157
	v_lshlrev_b32_e32 v82, 16, v116
	v_mov_b32_e32 v98, v157
	v_mov_b32_e32 v99, v157
	v_mov_b32_e32 v101, v157
	v_and_b32_e32 v83, 0xffff0000, v116
	v_pk_mul_f32 v[94:95], v[42:43], v[94:95]
	v_mov_b32_dpp v98, v90 row_ror:8 row_mask:0xf bank_mask:0xf
	v_mov_b32_dpp v99, v91 row_ror:8 row_mask:0xf bank_mask:0xf
	v_mov_b32_e32 v100, v157
	v_mov_b32_dpp v101, v84 row_ror:8 row_mask:0xf bank_mask:0xf
	v_mov_b32_dpp v102, v85 row_ror:8 row_mask:0xf bank_mask:0xf
	v_pk_fma_f32 v[82:83], v[86:87], v[94:95], v[82:83]
	v_mov_b32_e32 v86, v157
	v_mov_b32_e32 v87, v157
	v_mov_b32_dpp v100, v81 row_ror:8 row_mask:0xf bank_mask:0xf
	v_mov_b32_dpp v86, v82 row_ror:8 row_mask:0xf bank_mask:0xf
	v_mov_b32_dpp v87, v83 row_ror:8 row_mask:0xf bank_mask:0xf
	v_cndmask_b32_e64 v83, v102, v83, s[0:1]
	v_cndmask_b32_e64 v82, v101, v82, s[0:1]
	v_cndmask_b32_e64 v81, v99, v81, s[0:1]
	v_cndmask_b32_e64 v80, v98, v80, s[0:1]
	v_cndmask_b32_e64 v87, v85, v87, s[0:1]
	v_cndmask_b32_e64 v86, v84, v86, s[0:1]
	v_cndmask_b32_e64 v85, v91, v100, s[0:1]
	v_cndmask_b32_e64 v84, v90, v97, s[0:1]
	global_store_dwordx4 v[92:93], v[80:83], off offset:128
	global_store_dwordx4 v[88:89], v[84:87], off offset:128
	s_waitcnt vmcnt(4)
	s_nop 0
	v_mov_b32_e32 v80, v228
	v_sub_u32_e32 v81, v170, v174
	v_add_u32_e32 v81, v81, v176
	v_add_u32_e32 v98, 0x80, v81
	v_ashrrev_i32_e32 v99, 31, v98
	v_lshlrev_b64 v[90:91], 12, v[98:99]
	v_lshl_add_u64 v[94:95], v[90:91], 0, s[16:17]
	v_lshl_add_u64 v[82:83], s[8:9], 0, v[90:91]
	v_lshl_add_u64 v[86:87], s[8:9], 0, v[94:95]
	v_lshl_add_u64 v[82:83], v[82:83], 0, v[164:165]
	v_lshl_add_u64 v[86:87], v[86:87], 0, v[164:165]
	v_mov_b64_e32 v[82:83], v[232:233]
	v_mov_b64_e32 v[84:85], v[234:235]
	v_lshl_add_u64 v[90:91], s[10:11], 0, v[90:91]
	v_mov_b64_e32 v[86:87], v[236:237]
	v_mov_b64_e32 v[88:89], v[238:239]
	v_lshl_add_u64 v[90:91], v[90:91], 0, v[164:165]
	v_lshl_add_u64 v[94:95], s[10:11], 0, v[94:95]
	v_mov_b64_e32 v[90:91], v[240:241]
	v_mov_b64_e32 v[92:93], v[242:243]
	v_lshl_add_u64 v[94:95], v[94:95], 0, v[164:165]
	v_mov_b64_e32 v[94:95], v[244:245]
	v_mov_b64_e32 v[96:97], v[246:247]
	s_nop 1
	v_add_u32_e32 v222, 0x90, v81
	v_ashrrev_i32_e32 v223, 31, v222
	global_load_dword v228, v[168:169], off offset:576
	v_lshlrev_b64 v[216:217], 12, v[222:223]
	v_lshl_add_u64 v[224:225], v[216:217], 0, s[16:17]
	v_lshl_add_u64 v[220:221], s[8:9], 0, v[224:225]
	v_lshl_add_u64 v[218:219], s[8:9], 0, v[216:217]
	v_lshl_add_u64 v[220:221], v[220:221], 0, v[164:165]
	v_lshl_add_u64 v[216:217], s[10:11], 0, v[216:217]
	v_lshl_add_u64 v[218:219], v[218:219], 0, v[164:165]
	global_load_dwordx4 v[232:235], v[220:221], off
	v_lshl_add_u64 v[216:217], v[216:217], 0, v[164:165]
	global_load_dwordx4 v[236:239], v[218:219], off
	global_load_dwordx4 v[240:243], v[216:217], off
	v_lshl_add_u64 v[216:217], s[10:11], 0, v[224:225]
	v_lshl_add_u64 v[216:217], v[216:217], 0, v[164:165]
	global_load_dwordx4 v[244:247], v[216:217], off
	v_mov_b32_e32 v106, v157
	v_mov_b32_e32 v107, v157
	v_mov_b32_e32 v100, v157
	v_mov_b32_e32 v101, v157
	v_mov_b32_e32 v102, v157
	v_mov_b32_e32 v103, v157
	v_mov_b32_e32 v105, v157
	v_mov_b32_e32 v104, v157
	v_add_f32_e32 v79, 1.0, v79
	v_mul_f32_e32 v64, 0xbfb8aa3b, v64
	v_mul_f32_e32 v65, 0xbfb8aa3b, v65
	v_rcp_f32_e32 v78, v78
	v_rcp_f32_e32 v79, v79
	v_exp_f32_e32 v64, v64
	v_exp_f32_e32 v65, v65
	v_mul_f32_e32 v68, 0xbfb8aa3b, v68
	v_mul_f32_e32 v69, 0xbfb8aa3b, v69
	v_exp_f32_e32 v68, v68
	v_exp_f32_e32 v69, v69
	v_add_f32_e32 v64, 1.0, v64
	v_add_f32_e32 v65, 1.0, v65
	v_rcp_f32_e32 v64, v64
	v_mul_f32_e32 v66, 0xbfb8aa3b, v66
	v_mul_f32_e32 v67, 0xbfb8aa3b, v67
	v_rcp_f32_e32 v65, v65
	v_exp_f32_e32 v66, v66
	v_exp_f32_e32 v67, v67
	v_add_f32_e32 v68, 1.0, v68
	v_add_f32_e32 v69, 1.0, v69
	v_rcp_f32_e32 v68, v68
	v_mul_f32_e32 v70, 0xbfb8aa3b, v70
	v_mul_f32_e32 v71, 0xbfb8aa3b, v71
	v_rcp_f32_e32 v69, v69
	v_exp_f32_e32 v70, v70
	v_exp_f32_e32 v71, v71
	v_add_f32_e32 v66, 1.0, v66
	v_add_f32_e32 v67, 1.0, v67
	v_rcp_f32_e32 v66, v66
	v_rcp_f32_e32 v67, v67
	v_add_f32_e32 v70, 1.0, v70
	v_add_f32_e32 v71, 1.0, v71
	v_rcp_f32_e32 v70, v70
	v_rcp_f32_e32 v71, v71
	v_mul_f32_e32 v48, 0xbfb8aa3b, v48
	v_mul_f32_e32 v49, 0xbfb8aa3b, v49
	v_mul_f32_e32 v52, 0xbfb8aa3b, v52
	v_exp_f32_e32 v48, v48
	v_exp_f32_e32 v49, v49
	v_mul_f32_e32 v50, 0xbfb8aa3b, v50
	v_mul_f32_e32 v51, 0xbfb8aa3b, v51
	v_add_f32_e32 v48, 1.0, v48
	v_add_f32_e32 v49, 1.0, v49
	v_rcp_f32_e32 v48, v48
	v_rcp_f32_e32 v49, v49
	v_exp_f32_e32 v50, v50
	v_exp_f32_e32 v51, v51
	v_mul_f32_e32 v54, 0xbfb8aa3b, v54
	v_mul_f32_e32 v55, 0xbfb8aa3b, v55
	v_exp_f32_e32 v54, v54
	v_exp_f32_e32 v55, v55
	v_add_f32_e32 v50, 1.0, v50
	v_fmamk_f32 v80, v80, 0x3a000000, v182
	v_rsq_f32_e32 v80, v80
	v_add_f32_e32 v51, 1.0, v51
; __device__ __forceinline__ float bflo(unsigned w) { return __uint_as_float(w << 16); }
;     const bool lo = fr < 8;
;     const int r1 = row - fr + (fr & 7), cb = col0 + (lo ? 0 : boff);
;     const u32x4 l1 = *(const u32x4*)(P + (size_t)r1 * ld + cb), l2 = *(const u32x4*)(P + (size_t)(r1 + 8) * ld + cb);
;     __device__ __forceinline__ void operator()(const f32x4 (&acc)[2][2][4][2], const Unit& u, int wr, int wc, int fr, int fq) const {
;         const int row0 = u.pm * BM + wr * 64 + fr, col0 = u.pn * BM + wc * 64 + 8 * fq;
;         f32x4 gv[2][2];
; #pragma unroll
;         for (int bj = 0; bj < 2; ++bj) { gv[bj][0] = *(const f32x4*)(g + col0 + 32 * bj); gv[bj][1] = *(const f32x4*)(g + col0 + 32 * bj + 4); }
;         const bool lo = fr < 8;
; #pragma unroll
;         for (int ai = 0; ai < 2; ++ai)
; #pragma unroll
;             for (int m = 0; m < 4; ++m) { const int row = row0 + ai * HALF + m * 16; const float ri = __builtin_amdgcn_rsqf(sse[row] * (1.f / D) + EPS);
;                 u32x4 rr[2], ee[2]; load_pair_lines(R, D, row, fr, col0, rr[0], rr[1], 32); load_pair_lines(E, D, row, fr, col0, ee[0], ee[1], 32);
;                 float* orow = OUT + (size_t)(row - fr + (fr & 7)) * D + col0 + (lo ? 0 : 4);
; #pragma unroll
;                 for (int bj = 0; bj < 2; ++bj) { const u32x4 rw = rr[bj], ew = ee[bj];
;                     const float r[8] = {bflo(rw.x), bfhi(rw.x), bflo(rw.y), bfhi(rw.y), bflo(rw.z), bfhi(rw.z), bflo(rw.w), bfhi(rw.w)};
;                     const float e[8] = {bflo(ew.x), bfhi(ew.x), bflo(ew.y), bfhi(ew.y), bflo(ew.z), bfhi(ew.z), bflo(ew.w), bfhi(ew.w)};
;                     float o[8];
; #pragma unroll
;                     for (int j = 0; j < 8; ++j) { const float a = acc[ai][bj][m][j >> 2][j & 3]; const float gg = gv[bj][j >> 2][j & 3];
;                         o[j] = r[j] + e[j] * ri * gg * __builtin_amdgcn_rcpf(1.f + __builtin_amdgcn_exp2f(-a * LOG2E)); }
;                     f32x4 o1, o2;
; #pragma unroll
;                     for (int j = 0; j < 4; ++j) { const unsigned a = __float_as_uint(o[j]), b = __float_as_uint(o[4 + j]); const unsigned sa = dpp_ror8(a), sb = dpp_ror8(b);
;                         o1[j] = __uint_as_float(lo ? a : sb); o2[j] = __uint_as_float(lo ? sa : b); }
;                     *(f32x4*)(orow + 32 * bj) = o1; *(f32x4*)(orow + (size_t)8 * D + 32 * bj) = o2; } }
	v_rcp_f32_e32 v50, v50
	v_rcp_f32_e32 v51, v51
	v_add_f32_e32 v54, 1.0, v54
	v_add_f32_e32 v55, 1.0, v55
	v_mul_f32_e32 v32, 0xbfb8aa3b, v32
	v_mul_f32_e32 v33, 0xbfb8aa3b, v33
	v_rcp_f32_e32 v54, v54
	v_rcp_f32_e32 v55, v55
	v_mov_b32_dpp v100, v82 row_ror:8 row_mask:0xf bank_mask:0xf
	v_mov_b32_dpp v101, v83 row_ror:8 row_mask:0xf bank_mask:0xf
	v_mov_b32_dpp v106, v88 row_ror:8 row_mask:0xf bank_mask:0xf
	v_mov_b32_dpp v107, v89 row_ror:8 row_mask:0xf bank_mask:0xf
	v_mov_b32_dpp v102, v84 row_ror:8 row_mask:0xf bank_mask:0xf
	v_mov_b32_dpp v103, v85 row_ror:8 row_mask:0xf bank_mask:0xf
	v_mov_b32_dpp v105, v87 row_ror:8 row_mask:0xf bank_mask:0xf
	v_cndmask_b32_e64 v107, v107, v85, s[0:1]
	v_cndmask_b32_e64 v85, v106, v84, s[0:1]
	v_mov_b32_e32 v84, v157
	v_mov_b32_dpp v104, v86 row_ror:8 row_mask:0xf bank_mask:0xf
	v_cndmask_b32_e64 v105, v105, v83, s[0:1]
	v_cndmask_b32_e64 v101, v87, v101, s[0:1]
	v_cndmask_b32_e64 v89, v89, v103, s[0:1]
	v_cndmask_b32_e64 v100, v86, v100, s[0:1]
	v_mov_b32_e32 v83, v157
	v_mov_b32_dpp v84, v92 row_ror:8 row_mask:0xf bank_mask:0xf
	v_mov_b32_e32 v86, v157
	v_mov_b32_e32 v87, v157
	v_mov_b32_e32 v103, v157
	v_cndmask_b32_e64 v104, v104, v82, s[0:1]
	v_cndmask_b32_e64 v88, v88, v102, s[0:1]
	v_mov_b32_e32 v82, v157
	v_mov_b32_dpp v83, v91 row_ror:8 row_mask:0xf bank_mask:0xf
	v_mov_b32_dpp v86, v93 row_ror:8 row_mask:0xf bank_mask:0xf
	v_mov_b32_dpp v87, v94 row_ror:8 row_mask:0xf bank_mask:0xf
	v_mov_b32_e32 v102, v157
	v_mov_b32_dpp v103, v96 row_ror:8 row_mask:0xf bank_mask:0xf
	v_cndmask_b32_e64 v96, v96, v84, s[0:1]
	v_exp_f32_e32 v84, v76
	v_mul_f32_e32 v76, 0xbfb8aa3b, v77
	v_mov_b32_dpp v82, v90 row_ror:8 row_mask:0xf bank_mask:0xf
	v_mov_b32_dpp v102, v95 row_ror:8 row_mask:0xf bank_mask:0xf
	v_cndmask_b32_e64 v90, v87, v90, s[0:1]
	v_cndmask_b32_e64 v87, v103, v92, s[0:1]
	v_cndmask_b32_e64 v92, v95, v83, s[0:1]
	v_cndmask_b32_e64 v95, v97, v86, s[0:1]
	v_exp_f32_e32 v86, v76
	v_cndmask_b32_e64 v94, v94, v82, s[0:1]
	v_lshlrev_b64 v[82:83], 13, v[98:99]
	v_lshl_add_u64 v[82:83], s[4:5], 0, v[82:83]
	v_lshl_add_u64 v[82:83], v[82:83], 0, v[166:167]
	v_lshl_add_u64 v[76:77], v[82:83], 0, v[156:157]
	v_add_f32_e32 v83, 1.0, v86
	v_lshlrev_b32_e32 v86, 16, v87
	v_and_b32_e32 v87, 0xffff0000, v87
	v_add_f32_e32 v82, 1.0, v84
	v_pk_mul_f32 v[86:87], v[80:81], v[86:87] op_sel_hi:[0,1]
	v_rcp_f32_e32 v82, v82
	v_rcp_f32_e32 v83, v83
	v_lshlrev_b32_e32 v84, 16, v85
	v_and_b32_e32 v85, 0xffff0000, v85
	v_pk_mul_f32 v[86:87], v[60:61], v[86:87]
	v_mov_b32_e32 v106, v157
	v_pk_fma_f32 v[86:87], v[72:73], v[86:87], v[84:85]
	v_lshlrev_b32_e32 v84, 16, v90
	v_and_b32_e32 v85, 0xffff0000, v90
	v_mov_b32_dpp v106, v97 row_ror:8 row_mask:0xf bank_mask:0xf
	v_pk_mul_f32 v[84:85], v[80:81], v[84:85] op_sel_hi:[0,1]
	v_cndmask_b32_e64 v93, v106, v93, s[0:1]
	v_lshlrev_b32_e32 v72, 16, v104
	v_and_b32_e32 v73, 0xffff0000, v104
	v_pk_mul_f32 v[84:85], v[56:57], v[84:85]
	v_cndmask_b32_e64 v91, v102, v91, s[0:1]
	v_pk_fma_f32 v[72:73], v[82:83], v[84:85], v[72:73]
	v_lshlrev_b32_e32 v84, 16, v93
	v_and_b32_e32 v85, 0xffff0000, v93
	v_pk_mul_f32 v[84:85], v[80:81], v[84:85] op_sel_hi:[0,1]
	v_lshlrev_b32_e32 v82, 16, v107
	v_and_b32_e32 v83, 0xffff0000, v107
	v_pk_mul_f32 v[84:85], v[62:63], v[84:85]
	v_mov_b32_e32 v97, v157
	v_pk_fma_f32 v[82:83], v[74:75], v[84:85], v[82:83]
	v_lshlrev_b32_e32 v84, 16, v91
	v_and_b32_e32 v85, 0xffff0000, v91
	v_pk_mul_f32 v[84:85], v[80:81], v[84:85] op_sel_hi:[0,1]
	v_lshlrev_b32_e32 v74, 16, v105
	v_and_b32_e32 v75, 0xffff0000, v105
	v_pk_mul_f32 v[84:85], v[58:59], v[84:85]
	v_mov_b32_e32 v98, v157
	v_pk_fma_f32 v[74:75], v[78:79], v[84:85], v[74:75]
	v_mov_b32_e32 v78, v157
	v_mov_b32_e32 v79, v157
	v_mov_b32_e32 v93, v157
	v_mov_b32_e32 v102, v157
	v_mov_b32_dpp v78, v74 row_ror:8 row_mask:0xf bank_mask:0xf
	v_mov_b32_dpp v79, v75 row_ror:8 row_mask:0xf bank_mask:0xf
	v_mov_b32_dpp v97, v86 row_ror:8 row_mask:0xf bank_mask:0xf
	v_mov_b32_dpp v98, v87 row_ror:8 row_mask:0xf bank_mask:0xf
	v_mov_b32_e32 v90, v157
	v_mov_b32_e32 v99, v157
	v_mov_b32_dpp v93, v82 row_ror:8 row_mask:0xf bank_mask:0xf
	v_mov_b32_dpp v102, v83 row_ror:8 row_mask:0xf bank_mask:0xf
	v_cndmask_b32_e64 v85, v83, v79, s[0:1]
	v_cndmask_b32_e64 v84, v82, v78, s[0:1]
	v_lshlrev_b32_e32 v78, 16, v96
	v_and_b32_e32 v79, 0xffff0000, v96
	v_mov_b32_dpp v90, v72 row_ror:8 row_mask:0xf bank_mask:0xf
	v_mov_b32_dpp v99, v73 row_ror:8 row_mask:0xf bank_mask:0xf
	v_cndmask_b32_e64 v75, v102, v75, s[0:1]
	v_cndmask_b32_e64 v74, v93, v74, s[0:1]
	v_cndmask_b32_e64 v73, v98, v73, s[0:1]
	v_cndmask_b32_e64 v72, v97, v72, s[0:1]
	v_pk_mul_f32 v[78:79], v[80:81], v[78:79] op_sel_hi:[0,1]
	global_store_dwordx4 v[76:77], v[72:75], off
	v_pk_mul_f32 v[78:79], v[44:45], v[78:79]
	v_cndmask_b32_e64 v83, v87, v99, s[0:1]
	v_lshlrev_b32_e32 v74, 16, v88
	v_and_b32_e32 v75, 0xffff0000, v88
	v_pk_fma_f32 v[74:75], v[64:65], v[78:79], v[74:75]
	v_lshlrev_b32_e32 v78, 16, v94
	v_and_b32_e32 v79, 0xffff0000, v94
	v_pk_mul_f32 v[78:79], v[80:81], v[78:79] op_sel_hi:[0,1]
	v_lshlrev_b32_e32 v64, 16, v100
	v_and_b32_e32 v65, 0xffff0000, v100
	v_pk_mul_f32 v[78:79], v[40:41], v[78:79]
	v_add_co_u32_e32 v72, vcc, s45, v76
	v_pk_fma_f32 v[64:65], v[68:69], v[78:79], v[64:65]
	v_lshlrev_b32_e32 v78, 16, v95
	v_and_b32_e32 v79, 0xffff0000, v95
	v_pk_mul_f32 v[78:79], v[80:81], v[78:79] op_sel_hi:[0,1]
	v_lshlrev_b32_e32 v68, 16, v89
	v_and_b32_e32 v69, 0xffff0000, v89
	v_pk_mul_f32 v[78:79], v[46:47], v[78:79]
	v_cndmask_b32_e64 v82, v86, v90, s[0:1]
	v_pk_fma_f32 v[68:69], v[66:67], v[78:79], v[68:69]
	v_lshlrev_b32_e32 v78, 16, v92
; __device__ __forceinline__ float bflo(unsigned w) { return __uint_as_float(w << 16); }
;     const bool lo = fr < 8;
;     const int r1 = row - fr + (fr & 7), cb = col0 + (lo ? 0 : boff);
;     const u32x4 l1 = *(const u32x4*)(P + (size_t)r1 * ld + cb), l2 = *(const u32x4*)(P + (size_t)(r1 + 8) * ld + cb);
;     __device__ __forceinline__ void operator()(const f32x4 (&acc)[2][2][4][2], const Unit& u, int wr, int wc, int fr, int fq) const {
;         const int row0 = u.pm * BM + wr * 64 + fr, col0 = u.pn * BM + wc * 64 + 8 * fq;
;         f32x4 gv[2][2];
; #pragma unroll
;         for (int bj = 0; bj < 2; ++bj) { gv[bj][0] = *(const f32x4*)(g + col0 + 32 * bj); gv[bj][1] = *(const f32x4*)(g + col0 + 32 * bj + 4); }
;         const bool lo = fr < 8;
; #pragma unroll
;         for (int ai = 0; ai < 2; ++ai)
; #pragma unroll
;             for (int m = 0; m < 4; ++m) { const int row = row0 + ai * HALF + m * 16; const float ri = __builtin_amdgcn_rsqf(sse[row] * (1.f / D) + EPS);
;                 u32x4 rr[2], ee[2]; load_pair_lines(R, D, row, fr, col0, rr[0], rr[1], 32); load_pair_lines(E, D, row, fr, col0, ee[0], ee[1], 32);
;                 float* orow = OUT + (size_t)(row - fr + (fr & 7)) * D + col0 + (lo ? 0 : 4);
; #pragma unroll
;                 for (int bj = 0; bj < 2; ++bj) { const u32x4 rw = rr[bj], ew = ee[bj];
;                     const float r[8] = {bflo(rw.x), bfhi(rw.x), bflo(rw.y), bfhi(rw.y), bflo(rw.z), bfhi(rw.z), bflo(rw.w), bfhi(rw.w)};
;                     const float e[8] = {bflo(ew.x), bfhi(ew.x), bflo(ew.y), bfhi(ew.y), bflo(ew.z), bfhi(ew.z), bflo(ew.w), bfhi(ew.w)};
;                     float o[8];
; #pragma unroll
;                     for (int j = 0; j < 8; ++j) { const float a = acc[ai][bj][m][j >> 2][j & 3]; const float gg = gv[bj][j >> 2][j & 3];
;                         o[j] = r[j] + e[j] * ri * gg * __builtin_amdgcn_rcpf(1.f + __builtin_amdgcn_exp2f(-a * LOG2E)); }
;                     f32x4 o1, o2;
; #pragma unroll
;                     for (int j = 0; j < 4; ++j) { const unsigned a = __float_as_uint(o[j]), b = __float_as_uint(o[4 + j]); const unsigned sa = dpp_ror8(a), sb = dpp_ror8(b);
;                         o1[j] = __uint_as_float(lo ? a : sb); o2[j] = __uint_as_float(lo ? sa : b); }
;                     *(f32x4*)(orow + 32 * bj) = o1; *(f32x4*)(orow + (size_t)8 * D + 32 * bj) = o2; } }
	v_and_b32_e32 v79, 0xffff0000, v92
	v_addc_co_u32_e32 v73, vcc, 0, v77, vcc
	v_pk_mul_f32 v[78:79], v[80:81], v[78:79] op_sel_hi:[0,1]
	global_store_dwordx4 v[72:73], v[82:85], off
	v_mov_b32_e32 v86, v157
	v_mov_b32_e32 v87, v157
	v_mov_b32_e32 v82, v157
	v_mov_b32_e32 v83, v157
	v_lshlrev_b32_e32 v66, 16, v101
	v_and_b32_e32 v67, 0xffff0000, v101
	v_pk_mul_f32 v[78:79], v[42:43], v[78:79]
	v_mov_b32_dpp v82, v74 row_ror:8 row_mask:0xf bank_mask:0xf
	v_mov_b32_dpp v83, v75 row_ror:8 row_mask:0xf bank_mask:0xf
	v_mov_b32_e32 v84, v157
	v_mov_b32_e32 v85, v157
	v_mov_b32_dpp v86, v68 row_ror:8 row_mask:0xf bank_mask:0xf
	v_mov_b32_dpp v87, v69 row_ror:8 row_mask:0xf bank_mask:0xf
	v_pk_fma_f32 v[66:67], v[70:71], v[78:79], v[66:67]
	v_mov_b32_e32 v70, v157
	v_mov_b32_e32 v71, v157
	v_add_u32_e32 v78, 0x90, v81
	v_mov_b32_dpp v84, v64 row_ror:8 row_mask:0xf bank_mask:0xf
	v_mov_b32_dpp v85, v65 row_ror:8 row_mask:0xf bank_mask:0xf
	v_mov_b32_dpp v70, v66 row_ror:8 row_mask:0xf bank_mask:0xf
	v_mov_b32_dpp v71, v67 row_ror:8 row_mask:0xf bank_mask:0xf
	v_cndmask_b32_e64 v67, v87, v67, s[0:1]
	v_cndmask_b32_e64 v66, v86, v66, s[0:1]
	v_cndmask_b32_e64 v65, v83, v65, s[0:1]
	v_cndmask_b32_e64 v64, v82, v64, s[0:1]
	v_ashrrev_i32_e32 v79, 31, v78
	v_cndmask_b32_e64 v71, v69, v71, s[0:1]
	v_cndmask_b32_e64 v70, v68, v70, s[0:1]
	v_cndmask_b32_e64 v69, v75, v85, s[0:1]
	v_cndmask_b32_e64 v68, v74, v84, s[0:1]
	global_store_dwordx4 v[76:77], v[64:67], off offset:128
	global_store_dwordx4 v[72:73], v[68:71], off offset:128
	s_waitcnt vmcnt(4)
	s_nop 0
	v_mov_b32_e32 v80, v228
	v_lshlrev_b64 v[64:65], 12, v[78:79]
	v_lshl_add_u64 v[82:83], v[64:65], 0, s[16:17]
	v_lshl_add_u64 v[70:71], s[8:9], 0, v[82:83]
	v_lshl_add_u64 v[66:67], s[8:9], 0, v[64:65]
	v_lshl_add_u64 v[70:71], v[70:71], 0, v[164:165]
	v_lshl_add_u64 v[64:65], s[10:11], 0, v[64:65]
	v_lshl_add_u64 v[66:67], v[66:67], 0, v[164:165]
	v_mov_b64_e32 v[70:71], v[232:233]
	v_mov_b64_e32 v[72:73], v[234:235]
	v_lshl_add_u64 v[64:65], v[64:65], 0, v[164:165]
	v_mov_b64_e32 v[66:67], v[236:237]
	v_mov_b64_e32 v[68:69], v[238:239]
	v_mov_b32_e32 v90, v157
	v_mov_b64_e32 v[74:75], v[240:241]
	v_mov_b64_e32 v[76:77], v[242:243]
	v_lshl_add_u64 v[64:65], s[10:11], 0, v[82:83]
	v_lshl_add_u64 v[64:65], v[64:65], 0, v[164:165]
	v_mov_b64_e32 v[82:83], v[244:245]
	v_mov_b64_e32 v[84:85], v[246:247]
	s_nop 1
	global_load_dword v228, v[168:169], off offset:640
	v_add_u32_e32 v220, 0xa0, v81
	v_ashrrev_i32_e32 v221, 31, v220
	v_lshlrev_b64 v[216:217], 12, v[220:221]
	v_lshl_add_u64 v[224:225], v[216:217], 0, s[16:17]
	v_lshl_add_u64 v[222:223], s[8:9], 0, v[224:225]
	v_lshl_add_u64 v[218:219], s[8:9], 0, v[216:217]
	v_lshl_add_u64 v[222:223], v[222:223], 0, v[164:165]
	v_lshl_add_u64 v[216:217], s[10:11], 0, v[216:217]
	v_lshl_add_u64 v[218:219], v[218:219], 0, v[164:165]
	global_load_dwordx4 v[232:235], v[222:223], off
	v_lshl_add_u64 v[216:217], v[216:217], 0, v[164:165]
	global_load_dwordx4 v[236:239], v[218:219], off
	global_load_dwordx4 v[240:243], v[216:217], off
	v_lshl_add_u64 v[216:217], s[10:11], 0, v[224:225]
	v_lshl_add_u64 v[216:217], v[216:217], 0, v[164:165]
	global_load_dwordx4 v[244:247], v[216:217], off
	v_mov_b32_e32 v91, v157
	v_mov_b32_e32 v65, v157
	v_mov_b32_e32 v86, v157
	v_mov_b32_e32 v87, v157
	v_mov_b32_e32 v89, v157
	v_mov_b32_e32 v88, v157
	v_exp_f32_e32 v32, v32
	v_exp_f32_e32 v33, v33
	v_mul_f32_e32 v36, 0xbfb8aa3b, v36
	v_mul_f32_e32 v37, 0xbfb8aa3b, v37
	v_exp_f32_e32 v36, v36
	v_exp_f32_e32 v37, v37
	v_add_f32_e32 v32, 1.0, v32
	v_add_f32_e32 v33, 1.0, v33
	v_rcp_f32_e32 v32, v32
	v_rcp_f32_e32 v33, v33
	v_mul_f32_e32 v34, 0xbfb8aa3b, v34
	v_mul_f32_e32 v35, 0xbfb8aa3b, v35
	v_add_f32_e32 v36, 1.0, v36
	v_add_f32_e32 v37, 1.0, v37
	v_exp_f32_e32 v34, v34
	v_exp_f32_e32 v35, v35
	v_rcp_f32_e32 v36, v36
	v_rcp_f32_e32 v37, v37
	v_mul_f32_e32 v38, 0xbfb8aa3b, v38
	v_mul_f32_e32 v39, 0xbfb8aa3b, v39
	v_exp_f32_e32 v38, v38
	v_exp_f32_e32 v39, v39
	v_add_f32_e32 v34, 1.0, v34
	v_add_f32_e32 v35, 1.0, v35
	v_rcp_f32_e32 v34, v34
	v_rcp_f32_e32 v35, v35
	v_add_f32_e32 v38, 1.0, v38
	v_add_f32_e32 v39, 1.0, v39
	v_rcp_f32_e32 v38, v38
	v_rcp_f32_e32 v39, v39
	v_mul_f32_e32 v24, 0xbfb8aa3b, v24
	v_mul_f32_e32 v25, 0xbfb8aa3b, v25
	v_mul_f32_e32 v28, 0xbfb8aa3b, v28
	v_exp_f32_e32 v24, v24
	v_exp_f32_e32 v25, v25
	v_mul_f32_e32 v26, 0xbfb8aa3b, v26
	v_mul_f32_e32 v27, 0xbfb8aa3b, v27
	v_add_f32_e32 v24, 1.0, v24
	v_add_f32_e32 v25, 1.0, v25
	v_rcp_f32_e32 v24, v24
	v_rcp_f32_e32 v25, v25
	v_exp_f32_e32 v26, v26
	v_exp_f32_e32 v27, v27
	v_mul_f32_e32 v30, 0xbfb8aa3b, v30
	v_mul_f32_e32 v31, 0xbfb8aa3b, v31
	v_exp_f32_e32 v30, v30
	v_exp_f32_e32 v31, v31
	v_add_f32_e32 v26, 1.0, v26
	v_add_f32_e32 v27, 1.0, v27
	v_rcp_f32_e32 v26, v26
	v_rcp_f32_e32 v27, v27
	v_add_f32_e32 v30, 1.0, v30
	v_add_f32_e32 v31, 1.0, v31
	v_mul_f32_e32 v16, 0xbfb8aa3b, v16
	v_mul_f32_e32 v17, 0xbfb8aa3b, v17
	v_rcp_f32_e32 v30, v30
	v_rcp_f32_e32 v31, v31
	v_exp_f32_e32 v16, v16
	v_fmamk_f32 v64, v80, 0x3a000000, v182
	v_mov_b32_e32 v80, v157
	v_rsq_f32_e32 v64, v64
	v_exp_f32_e32 v17, v17
	v_mul_f32_e32 v20, 0xbfb8aa3b, v20
	v_mul_f32_e32 v21, 0xbfb8aa3b, v21
	v_exp_f32_e32 v20, v20
	v_exp_f32_e32 v21, v21
	v_mov_b32_dpp v90, v72 row_ror:8 row_mask:0xf bank_mask:0xf
	v_mov_b32_dpp v91, v73 row_ror:8 row_mask:0xf bank_mask:0xf
	v_mov_b32_dpp v65, v66 row_ror:8 row_mask:0xf bank_mask:0xf
	v_mov_b32_dpp v80, v67 row_ror:8 row_mask:0xf bank_mask:0xf
	v_mov_b32_dpp v86, v68 row_ror:8 row_mask:0xf bank_mask:0xf
	v_mov_b32_dpp v87, v69 row_ror:8 row_mask:0xf bank_mask:0xf
	v_mov_b32_dpp v89, v71 row_ror:8 row_mask:0xf bank_mask:0xf
; __device__ __forceinline__ float bflo(unsigned w) { return __uint_as_float(w << 16); }
;     const bool lo = fr < 8;
;     const int r1 = row - fr + (fr & 7), cb = col0 + (lo ? 0 : boff);
;     const u32x4 l1 = *(const u32x4*)(P + (size_t)r1 * ld + cb), l2 = *(const u32x4*)(P + (size_t)(r1 + 8) * ld + cb);
;     __device__ __forceinline__ void operator()(const f32x4 (&acc)[2][2][4][2], const Unit& u, int wr, int wc, int fr, int fq) const {
;         const int row0 = u.pm * BM + wr * 64 + fr, col0 = u.pn * BM + wc * 64 + 8 * fq;
;         f32x4 gv[2][2];
; #pragma unroll
;         for (int bj = 0; bj < 2; ++bj) { gv[bj][0] = *(const f32x4*)(g + col0 + 32 * bj); gv[bj][1] = *(const f32x4*)(g + col0 + 32 * bj + 4); }
;         const bool lo = fr < 8;
; #pragma unroll
;         for (int ai = 0; ai < 2; ++ai)
; #pragma unroll
;             for (int m = 0; m < 4; ++m) { const int row = row0 + ai * HALF + m * 16; const float ri = __builtin_amdgcn_rsqf(sse[row] * (1.f / D) + EPS);
;                 u32x4 rr[2], ee[2]; load_pair_lines(R, D, row, fr, col0, rr[0], rr[1], 32); load_pair_lines(E, D, row, fr, col0, ee[0], ee[1], 32);
;                 float* orow = OUT + (size_t)(row - fr + (fr & 7)) * D + col0 + (lo ? 0 : 4);
; #pragma unroll
;                 for (int bj = 0; bj < 2; ++bj) { const u32x4 rw = rr[bj], ew = ee[bj];
;                     const float r[8] = {bflo(rw.x), bfhi(rw.x), bflo(rw.y), bfhi(rw.y), bflo(rw.z), bfhi(rw.z), bflo(rw.w), bfhi(rw.w)};
;                     const float e[8] = {bflo(ew.x), bfhi(ew.x), bflo(ew.y), bfhi(ew.y), bflo(ew.z), bfhi(ew.z), bflo(ew.w), bfhi(ew.w)};
;                     float o[8];
; #pragma unroll
;                     for (int j = 0; j < 8; ++j) { const float a = acc[ai][bj][m][j >> 2][j & 3]; const float gg = gv[bj][j >> 2][j & 3];
;                         o[j] = r[j] + e[j] * ri * gg * __builtin_amdgcn_rcpf(1.f + __builtin_amdgcn_exp2f(-a * LOG2E)); }
;                     f32x4 o1, o2;
; #pragma unroll
;                     for (int j = 0; j < 4; ++j) { const unsigned a = __float_as_uint(o[j]), b = __float_as_uint(o[4 + j]); const unsigned sa = dpp_ror8(a), sb = dpp_ror8(b);
;                         o1[j] = __uint_as_float(lo ? a : sb); o2[j] = __uint_as_float(lo ? sa : b); }
;                     *(f32x4*)(orow + 32 * bj) = o1; *(f32x4*)(orow + (size_t)8 * D + 32 * bj) = o2; } }
	v_cndmask_b32_e64 v91, v91, v69, s[0:1]
	v_cndmask_b32_e64 v69, v90, v68, s[0:1]
	v_mov_b32_e32 v68, v157
	v_mov_b32_dpp v88, v70 row_ror:8 row_mask:0xf bank_mask:0xf
	v_cndmask_b32_e64 v89, v89, v67, s[0:1]
	v_cndmask_b32_e64 v80, v71, v80, s[0:1]
	v_cndmask_b32_e64 v73, v73, v87, s[0:1]
	v_cndmask_b32_e64 v65, v70, v65, s[0:1]
	v_mov_b32_e32 v67, v157
	v_mov_b32_dpp v68, v76 row_ror:8 row_mask:0xf bank_mask:0xf
	v_mov_b32_e32 v70, v157
	v_mov_b32_e32 v71, v157
	v_mov_b32_e32 v87, v157
	v_cndmask_b32_e64 v88, v88, v66, s[0:1]
	v_cndmask_b32_e64 v72, v72, v86, s[0:1]
	v_mov_b32_e32 v66, v157
	v_mov_b32_dpp v67, v75 row_ror:8 row_mask:0xf bank_mask:0xf
	v_mov_b32_dpp v70, v77 row_ror:8 row_mask:0xf bank_mask:0xf
	v_mov_b32_dpp v71, v82 row_ror:8 row_mask:0xf bank_mask:0xf
	v_mov_b32_e32 v86, v157
	v_mov_b32_dpp v87, v84 row_ror:8 row_mask:0xf bank_mask:0xf
	v_cndmask_b32_e64 v84, v84, v68, s[0:1]
	v_exp_f32_e32 v68, v52
	v_mul_f32_e32 v52, 0xbfb8aa3b, v53
	v_mov_b32_dpp v66, v74 row_ror:8 row_mask:0xf bank_mask:0xf
	v_mov_b32_dpp v86, v83 row_ror:8 row_mask:0xf bank_mask:0xf
	v_cndmask_b32_e64 v74, v71, v74, s[0:1]
	v_cndmask_b32_e64 v71, v87, v76, s[0:1]
	v_cndmask_b32_e64 v76, v83, v67, s[0:1]
	v_cndmask_b32_e64 v83, v85, v70, s[0:1]
	v_exp_f32_e32 v70, v52
	v_cndmask_b32_e64 v82, v82, v66, s[0:1]
	v_lshlrev_b64 v[66:67], 13, v[78:79]
	v_lshl_add_u64 v[66:67], s[4:5], 0, v[66:67]
	v_lshl_add_u64 v[66:67], v[66:67], 0, v[166:167]
	v_lshl_add_u64 v[52:53], v[66:67], 0, v[156:157]
	v_add_f32_e32 v67, 1.0, v70
	v_lshlrev_b32_e32 v70, 16, v71
	v_and_b32_e32 v71, 0xffff0000, v71
	v_add_f32_e32 v66, 1.0, v68
	v_pk_mul_f32 v[70:71], v[64:65], v[70:71] op_sel_hi:[0,1]
	v_rcp_f32_e32 v66, v66
	v_rcp_f32_e32 v67, v67
	v_lshlrev_b32_e32 v68, 16, v69
	v_and_b32_e32 v69, 0xffff0000, v69
	v_pk_mul_f32 v[70:71], v[60:61], v[70:71]
	v_mov_b32_e32 v90, v157
	v_pk_fma_f32 v[70:71], v[48:49], v[70:71], v[68:69]
	v_lshlrev_b32_e32 v68, 16, v74
	v_and_b32_e32 v69, 0xffff0000, v74
	v_mov_b32_dpp v90, v85 row_ror:8 row_mask:0xf bank_mask:0xf
	v_pk_mul_f32 v[68:69], v[64:65], v[68:69] op_sel_hi:[0,1]
	v_cndmask_b32_e64 v77, v90, v77, s[0:1]
	v_lshlrev_b32_e32 v48, 16, v88
	v_and_b32_e32 v49, 0xffff0000, v88
	v_pk_mul_f32 v[68:69], v[56:57], v[68:69]
	v_cndmask_b32_e64 v75, v86, v75, s[0:1]
	v_pk_fma_f32 v[48:49], v[66:67], v[68:69], v[48:49]
	v_lshlrev_b32_e32 v68, 16, v77
	v_and_b32_e32 v69, 0xffff0000, v77
	v_pk_mul_f32 v[68:69], v[64:65], v[68:69] op_sel_hi:[0,1]
	v_lshlrev_b32_e32 v66, 16, v91
	v_and_b32_e32 v67, 0xffff0000, v91
	v_pk_mul_f32 v[68:69], v[62:63], v[68:69]
	v_mov_b32_e32 v78, v157
	v_pk_fma_f32 v[66:67], v[50:51], v[68:69], v[66:67]
	v_lshlrev_b32_e32 v68, 16, v75
	v_and_b32_e32 v69, 0xffff0000, v75
	v_pk_mul_f32 v[68:69], v[64:65], v[68:69] op_sel_hi:[0,1]
	v_lshlrev_b32_e32 v50, 16, v89
	v_and_b32_e32 v51, 0xffff0000, v89
	v_pk_mul_f32 v[68:69], v[58:59], v[68:69]
	v_mov_b32_e32 v79, v157
	v_pk_fma_f32 v[50:51], v[54:55], v[68:69], v[50:51]
	v_mov_b32_e32 v54, v157
	v_mov_b32_e32 v55, v157
	v_mov_b32_e32 v77, v157
	v_mov_b32_e32 v86, v157
	v_mov_b32_dpp v54, v50 row_ror:8 row_mask:0xf bank_mask:0xf
	v_mov_b32_dpp v55, v51 row_ror:8 row_mask:0xf bank_mask:0xf
	v_mov_b32_dpp v78, v70 row_ror:8 row_mask:0xf bank_mask:0xf
	v_mov_b32_dpp v79, v71 row_ror:8 row_mask:0xf bank_mask:0xf
	v_mov_b32_e32 v74, v157
	v_mov_b32_e32 v85, v157
	v_mov_b32_dpp v77, v66 row_ror:8 row_mask:0xf bank_mask:0xf
	v_mov_b32_dpp v86, v67 row_ror:8 row_mask:0xf bank_mask:0xf
	v_cndmask_b32_e64 v69, v67, v55, s[0:1]
	v_cndmask_b32_e64 v68, v66, v54, s[0:1]
	v_lshlrev_b32_e32 v54, 16, v84
	v_and_b32_e32 v55, 0xffff0000, v84
	v_mov_b32_dpp v74, v48 row_ror:8 row_mask:0xf bank_mask:0xf
	v_mov_b32_dpp v85, v49 row_ror:8 row_mask:0xf bank_mask:0xf
	v_cndmask_b32_e64 v51, v86, v51, s[0:1]
	v_cndmask_b32_e64 v50, v77, v50, s[0:1]
	v_cndmask_b32_e64 v49, v79, v49, s[0:1]
	v_cndmask_b32_e64 v48, v78, v48, s[0:1]
	v_pk_mul_f32 v[54:55], v[64:65], v[54:55] op_sel_hi:[0,1]
	global_store_dwordx4 v[52:53], v[48:51], off
	v_pk_mul_f32 v[54:55], v[44:45], v[54:55]
	v_cndmask_b32_e64 v67, v71, v85, s[0:1]
	v_lshlrev_b32_e32 v50, 16, v72
	v_and_b32_e32 v51, 0xffff0000, v72
	v_pk_fma_f32 v[50:51], v[32:33], v[54:55], v[50:51]
	v_lshlrev_b32_e32 v54, 16, v82
	v_and_b32_e32 v55, 0xffff0000, v82
	v_pk_mul_f32 v[54:55], v[64:65], v[54:55] op_sel_hi:[0,1]
	v_lshlrev_b32_e32 v32, 16, v65
	v_and_b32_e32 v33, 0xffff0000, v65
	v_pk_mul_f32 v[54:55], v[40:41], v[54:55]
	v_mov_b32_e32 v65, v157
	v_pk_fma_f32 v[32:33], v[36:37], v[54:55], v[32:33]
	v_lshlrev_b32_e32 v54, 16, v83
	v_and_b32_e32 v55, 0xffff0000, v83
	v_mov_b32_dpp v65, v32 row_ror:8 row_mask:0xf bank_mask:0xf
	v_pk_mul_f32 v[54:55], v[64:65], v[54:55] op_sel_hi:[0,1]
	v_lshlrev_b32_e32 v36, 16, v73
	v_and_b32_e32 v37, 0xffff0000, v73
	v_pk_mul_f32 v[54:55], v[46:47], v[54:55]
	v_add_co_u32_e32 v48, vcc, s45, v52
	v_pk_fma_f32 v[36:37], v[34:35], v[54:55], v[36:37]
	v_lshlrev_b32_e32 v54, 16, v76
	v_and_b32_e32 v55, 0xffff0000, v76
	v_pk_mul_f32 v[54:55], v[64:65], v[54:55] op_sel_hi:[0,1]
	v_cndmask_b32_e64 v66, v70, v74, s[0:1]
	v_addc_co_u32_e32 v49, vcc, 0, v53, vcc
	v_lshlrev_b32_e32 v34, 16, v80
	v_and_b32_e32 v35, 0xffff0000, v80
	v_pk_mul_f32 v[54:55], v[42:43], v[54:55]
	global_store_dwordx4 v[48:49], v[66:69], off
	v_mov_b32_e32 v70, v157
	v_pk_fma_f32 v[34:35], v[38:39], v[54:55], v[34:35]
	v_mov_b32_e32 v66, v157
	v_mov_b32_e32 v67, v157
	v_mov_b32_e32 v69, v157
	v_mov_b32_e32 v38, v157
	v_mov_b32_dpp v66, v50 row_ror:8 row_mask:0xf bank_mask:0xf
	v_mov_b32_dpp v67, v51 row_ror:8 row_mask:0xf bank_mask:0xf
	v_mov_b32_e32 v68, v157
	v_mov_b32_dpp v69, v36 row_ror:8 row_mask:0xf bank_mask:0xf
	v_mov_b32_dpp v70, v37 row_ror:8 row_mask:0xf bank_mask:0xf
	v_mov_b32_dpp v38, v34 row_ror:8 row_mask:0xf bank_mask:0xf
	v_mov_b32_e32 v39, v157
	v_mov_b32_dpp v68, v33 row_ror:8 row_mask:0xf bank_mask:0xf
	v_cndmask_b32_e64 v34, v69, v34, s[0:1]
	v_mov_b32_dpp v39, v35 row_ror:8 row_mask:0xf bank_mask:0xf
	v_cndmask_b32_e64 v35, v70, v35, s[0:1]
	v_cndmask_b32_e64 v33, v67, v33, s[0:1]
	v_cndmask_b32_e64 v32, v66, v32, s[0:1]
	v_cndmask_b32_e64 v38, v36, v38, s[0:1]
	v_cndmask_b32_e64 v39, v37, v39, s[0:1]
	v_cndmask_b32_e64 v37, v51, v68, s[0:1]
	v_cndmask_b32_e64 v36, v50, v65, s[0:1]
	global_store_dwordx4 v[52:53], v[32:35], off offset:128
	global_store_dwordx4 v[48:49], v[36:39], off offset:128
	s_waitcnt vmcnt(4)
; __device__ __forceinline__ float bflo(unsigned w) { return __uint_as_float(w << 16); }
; __device__ __forceinline__ float bfhi(unsigned w) { return __uint_as_float(w & 0xffff0000u); }
;     const bool lo = fr < 8;
;     const int r1 = row - fr + (fr & 7), cb = col0 + (lo ? 0 : boff);
;     const u32x4 l1 = *(const u32x4*)(P + (size_t)r1 * ld + cb), l2 = *(const u32x4*)(P + (size_t)(r1 + 8) * ld + cb);
;     const u32x4 s1 = {dpp_ror8(l1.x), dpp_ror8(l1.y), dpp_ror8(l1.z), dpp_ror8(l1.w)}, s2 = {dpp_ror8(l2.x), dpp_ror8(l2.y), dpp_ror8(l2.z), dpp_ror8(l2.w)};
;     wA = lo ? l1 : s2; wB = lo ? s1 : l2;
; }
;     __device__ __forceinline__ void operator()(const f32x4 (&acc)[2][2][4][2], const Unit& u, int wr, int wc, int fr, int fq) const {
;     ...
;             for (int m = 0; m < 4; ++m) { const int row = row0 + ai * HALF + m * 16; const float ri = __builtin_amdgcn_rsqf(sse[row] * (1.f / D) + EPS);
;                 u32x4 rr[2], ee[2]; load_pair_lines(R, D, row, fr, col0, rr[0], rr[1], 32); load_pair_lines(E, D, row, fr, col0, ee[0], ee[1], 32);
;                 float* orow = OUT + (size_t)(row - fr + (fr & 7)) * D + col0 + (lo ? 0 : 4);
; #pragma unroll
;                 for (int bj = 0; bj < 2; ++bj) { const u32x4 rw = rr[bj], ew = ee[bj];
;                     const float r[8] = {bflo(rw.x), bfhi(rw.x), bflo(rw.y), bfhi(rw.y), bflo(rw.z), bfhi(rw.z), bflo(rw.w), bfhi(rw.w)};
;                     const float e[8] = {bflo(ew.x), bfhi(ew.x), bflo(ew.y), bfhi(ew.y), bflo(ew.z), bfhi(ew.z), bflo(ew.w), bfhi(ew.w)};
;                     float o[8];
; #pragma unroll
;                     for (int j = 0; j < 8; ++j) { const float a = acc[ai][bj][m][j >> 2][j & 3]; const float gg = gv[bj][j >> 2][j & 3];
;                         o[j] = r[j] + e[j] * ri * gg * __builtin_amdgcn_rcpf(1.f + __builtin_amdgcn_exp2f(-a * LOG2E)); }
;                     f32x4 o1, o2;
; #pragma unroll
;                     for (int j = 0; j < 4; ++j) { const unsigned a = __float_as_uint(o[j]), b = __float_as_uint(o[4 + j]); const unsigned sa = dpp_ror8(a), sb = dpp_ror8(b);
;                         o1[j] = __uint_as_float(lo ? a : sb); o2[j] = __uint_as_float(lo ? sa : b); }
;                     *(f32x4*)(orow + 32 * bj) = o1; *(f32x4*)(orow + (size_t)8 * D + 32 * bj) = o2; } }
	s_nop 0
	v_mov_b32_e32 v68, v228
	v_mov_b32_e32 v73, v157
	v_add_u32_e32 v38, 0xa0, v81
	v_ashrrev_i32_e32 v39, 31, v38
	v_lshlrev_b64 v[32:33], 12, v[38:39]
	v_lshl_add_u64 v[64:65], v[32:33], 0, s[16:17]
	v_lshl_add_u64 v[48:49], s[8:9], 0, v[64:65]
	v_lshl_add_u64 v[34:35], s[8:9], 0, v[32:33]
	v_lshl_add_u64 v[48:49], v[48:49], 0, v[164:165]
	v_lshl_add_u64 v[32:33], s[10:11], 0, v[32:33]
	v_lshl_add_u64 v[34:35], v[34:35], 0, v[164:165]
	v_mov_b64_e32 v[48:49], v[232:233]
	v_mov_b64_e32 v[50:51], v[234:235]
	v_lshl_add_u64 v[32:33], v[32:33], 0, v[164:165]
	v_mov_b64_e32 v[34:35], v[236:237]
	v_mov_b64_e32 v[36:37], v[238:239]
	v_mov_b32_e32 v74, v157
	v_mov_b64_e32 v[52:53], v[240:241]
	v_mov_b64_e32 v[54:55], v[242:243]
	v_lshl_add_u64 v[32:33], s[10:11], 0, v[64:65]
	v_lshl_add_u64 v[32:33], v[32:33], 0, v[164:165]
	v_mov_b64_e32 v[64:65], v[244:245]
	v_mov_b64_e32 v[66:67], v[246:247]
	s_nop 1
	v_add_u32_e32 v224, 0xb0, v81
	v_ashrrev_i32_e32 v225, 31, v224
	global_load_dword v228, v[168:169], off offset:704
	v_lshlrev_b64 v[216:217], 12, v[224:225]
	v_lshl_add_u64 v[222:223], v[216:217], 0, s[16:17]
	v_lshl_add_u64 v[220:221], s[8:9], 0, v[222:223]
	v_lshl_add_u64 v[218:219], s[8:9], 0, v[216:217]
	v_lshl_add_u64 v[220:221], v[220:221], 0, v[164:165]
	v_lshl_add_u64 v[216:217], s[10:11], 0, v[216:217]
	v_lshl_add_u64 v[218:219], v[218:219], 0, v[164:165]
	global_load_dwordx4 v[232:235], v[220:221], off
	v_lshl_add_u64 v[216:217], v[216:217], 0, v[164:165]
	global_load_dwordx4 v[236:239], v[218:219], off
	global_load_dwordx4 v[240:243], v[216:217], off
	v_lshl_add_u64 v[216:217], s[10:11], 0, v[222:223]
	v_lshl_add_u64 v[216:217], v[216:217], 0, v[164:165]
	global_load_dwordx4 v[244:247], v[216:217], off
	v_mov_b32_e32 v69, v157
	v_mov_b32_e32 v70, v157
	v_mov_b32_e32 v71, v157
	v_mov_b32_e32 v72, v157
	v_mov_b32_e32 v33, v157
	v_add_f32_e32 v16, 1.0, v16
	v_add_f32_e32 v17, 1.0, v17
	v_rcp_f32_e32 v16, v16
	v_rcp_f32_e32 v17, v17
	v_mul_f32_e32 v18, 0xbfb8aa3b, v18
	v_mul_f32_e32 v19, 0xbfb8aa3b, v19
	v_add_f32_e32 v20, 1.0, v20
	v_add_f32_e32 v21, 1.0, v21
	v_exp_f32_e32 v18, v18
	v_exp_f32_e32 v19, v19
	v_rcp_f32_e32 v20, v20
	v_rcp_f32_e32 v21, v21
	v_mul_f32_e32 v22, 0xbfb8aa3b, v22
	v_mul_f32_e32 v23, 0xbfb8aa3b, v23
	v_exp_f32_e32 v22, v22
	v_exp_f32_e32 v23, v23
	v_add_f32_e32 v18, 1.0, v18
	v_add_f32_e32 v19, 1.0, v19
	v_rcp_f32_e32 v18, v18
	v_rcp_f32_e32 v19, v19
	v_add_f32_e32 v22, 1.0, v22
	v_add_f32_e32 v23, 1.0, v23
	v_rcp_f32_e32 v22, v22
	v_rcp_f32_e32 v23, v23
	v_mul_f32_e32 v8, 0xbfb8aa3b, v8
	v_mul_f32_e32 v9, 0xbfb8aa3b, v9
	v_mul_f32_e32 v12, 0xbfb8aa3b, v12
	v_exp_f32_e32 v8, v8
	v_exp_f32_e32 v9, v9
	v_mul_f32_e32 v10, 0xbfb8aa3b, v10
	v_mul_f32_e32 v11, 0xbfb8aa3b, v11
	v_add_f32_e32 v8, 1.0, v8
	v_add_f32_e32 v9, 1.0, v9
	v_rcp_f32_e32 v8, v8
	v_rcp_f32_e32 v9, v9
	v_exp_f32_e32 v10, v10
	v_exp_f32_e32 v11, v11
	v_mul_f32_e32 v14, 0xbfb8aa3b, v14
	v_mul_f32_e32 v15, 0xbfb8aa3b, v15
	v_exp_f32_e32 v14, v14
	v_exp_f32_e32 v15, v15
	v_add_f32_e32 v10, 1.0, v10
	v_add_f32_e32 v11, 1.0, v11
	v_rcp_f32_e32 v10, v10
	v_rcp_f32_e32 v11, v11
	v_add_f32_e32 v14, 1.0, v14
	v_add_f32_e32 v15, 1.0, v15
	v_mul_f32_e32 v0, 0xbfb8aa3b, v0
	v_mul_f32_e32 v1, 0xbfb8aa3b, v1
	v_rcp_f32_e32 v14, v14
	v_rcp_f32_e32 v15, v15
	v_exp_f32_e32 v0, v0
	v_exp_f32_e32 v1, v1
	v_mul_f32_e32 v4, 0xbfb8aa3b, v4
	v_mul_f32_e32 v5, 0xbfb8aa3b, v5
	v_exp_f32_e32 v4, v4
	v_fmamk_f32 v32, v68, 0x3a000000, v182
	v_mov_b32_e32 v68, v157
	v_rsq_f32_e32 v32, v32
	v_exp_f32_e32 v5, v5
	v_add_f32_e32 v0, 1.0, v0
	v_add_f32_e32 v1, 1.0, v1
	v_rcp_f32_e32 v0, v0
	v_rcp_f32_e32 v1, v1
	v_mul_f32_e32 v2, 0xbfb8aa3b, v2
	v_mul_f32_e32 v3, 0xbfb8aa3b, v3
	v_add_f32_e32 v4, 1.0, v4
	v_mov_b32_dpp v73, v50 row_ror:8 row_mask:0xf bank_mask:0xf
	v_mov_b32_dpp v74, v51 row_ror:8 row_mask:0xf bank_mask:0xf
	v_mov_b32_dpp v69, v36 row_ror:8 row_mask:0xf bank_mask:0xf
	v_mov_b32_dpp v70, v37 row_ror:8 row_mask:0xf bank_mask:0xf
	v_mov_b32_dpp v71, v48 row_ror:8 row_mask:0xf bank_mask:0xf
	v_mov_b32_dpp v72, v49 row_ror:8 row_mask:0xf bank_mask:0xf
	v_cndmask_b32_e64 v74, v74, v37, s[0:1]
	v_cndmask_b32_e64 v37, v73, v36, s[0:1]
	v_mov_b32_e32 v36, v157
	v_mov_b32_dpp v33, v34 row_ror:8 row_mask:0xf bank_mask:0xf
	v_mov_b32_dpp v68, v35 row_ror:8 row_mask:0xf bank_mask:0xf
	v_cndmask_b32_e64 v72, v72, v35, s[0:1]
	v_cndmask_b32_e64 v71, v71, v34, s[0:1]
	v_cndmask_b32_e64 v51, v51, v70, s[0:1]
	v_mov_b32_e32 v34, v157
	v_mov_b32_e32 v35, v157
	v_mov_b32_dpp v36, v54 row_ror:8 row_mask:0xf bank_mask:0xf
	v_mov_b32_e32 v70, v157
	v_cndmask_b32_e64 v49, v49, v68, s[0:1]
	v_cndmask_b32_e64 v33, v48, v33, s[0:1]
	v_cndmask_b32_e64 v48, v50, v69, s[0:1]
	v_mov_b32_dpp v34, v52 row_ror:8 row_mask:0xf bank_mask:0xf
	v_mov_b32_dpp v35, v53 row_ror:8 row_mask:0xf bank_mask:0xf
	v_mov_b32_e32 v68, v157
	v_mov_b32_e32 v69, v157
	v_mov_b32_dpp v70, v66 row_ror:8 row_mask:0xf bank_mask:0xf
	v_cndmask_b32_e64 v66, v66, v36, s[0:1]
	v_exp_f32_e32 v36, v28
	v_mul_f32_e32 v28, 0xbfb8aa3b, v29
	v_mov_b32_dpp v68, v64 row_ror:8 row_mask:0xf bank_mask:0xf
	v_mov_b32_dpp v69, v65 row_ror:8 row_mask:0xf bank_mask:0xf
	v_cndmask_b32_e64 v65, v65, v35, s[0:1]
	v_cndmask_b32_e64 v64, v64, v34, s[0:1]
	v_lshlrev_b64 v[34:35], 13, v[38:39]
	v_exp_f32_e32 v38, v28
	v_lshl_add_u64 v[34:35], s[4:5], 0, v[34:35]
	v_cndmask_b32_e64 v54, v70, v54, s[0:1]
	v_lshl_add_u64 v[34:35], v[34:35], 0, v[166:167]
	v_lshl_add_u64 v[28:29], v[34:35], 0, v[156:157]
	v_add_f32_e32 v35, 1.0, v38
	v_lshlrev_b32_e32 v38, 16, v54
	v_and_b32_e32 v39, 0xffff0000, v54
	v_add_f32_e32 v34, 1.0, v36
; __device__ __forceinline__ float bflo(unsigned w) { return __uint_as_float(w << 16); }
; __device__ __forceinline__ float bfhi(unsigned w) { return __uint_as_float(w & 0xffff0000u); }
; __device__ __forceinline__ unsigned dpp_ror8(unsigned x) { return (unsigned)__builtin_amdgcn_update_dpp(0, (int)x, 0x128, 0xf, 0xf, false); }
;     __device__ __forceinline__ void operator()(const f32x4 (&acc)[2][2][4][2], const Unit& u, int wr, int wc, int fr, int fq) const {
;     ...
;                 for (int bj = 0; bj < 2; ++bj) { const u32x4 rw = rr[bj], ew = ee[bj];
;                     const float r[8] = {bflo(rw.x), bfhi(rw.x), bflo(rw.y), bfhi(rw.y), bflo(rw.z), bfhi(rw.z), bflo(rw.w), bfhi(rw.w)};
;                     const float e[8] = {bflo(ew.x), bfhi(ew.x), bflo(ew.y), bfhi(ew.y), bflo(ew.z), bfhi(ew.z), bflo(ew.w), bfhi(ew.w)};
;                     float o[8];
; #pragma unroll
;                     for (int j = 0; j < 8; ++j) { const float a = acc[ai][bj][m][j >> 2][j & 3]; const float gg = gv[bj][j >> 2][j & 3];
;                         o[j] = r[j] + e[j] * ri * gg * __builtin_amdgcn_rcpf(1.f + __builtin_amdgcn_exp2f(-a * LOG2E)); }
;                     f32x4 o1, o2;
; #pragma unroll
;                     for (int j = 0; j < 4; ++j) { const unsigned a = __float_as_uint(o[j]), b = __float_as_uint(o[4 + j]); const unsigned sa = dpp_ror8(a), sb = dpp_ror8(b);
;                         o1[j] = __uint_as_float(lo ? a : sb); o2[j] = __uint_as_float(lo ? sa : b); }
;                     *(f32x4*)(orow + 32 * bj) = o1; *(f32x4*)(orow + (size_t)8 * D + 32 * bj) = o2; } }
	v_pk_mul_f32 v[38:39], v[32:33], v[38:39] op_sel_hi:[0,1]
	v_cndmask_b32_e64 v52, v68, v52, s[0:1]
	v_rcp_f32_e32 v34, v34
	v_rcp_f32_e32 v35, v35
	v_lshlrev_b32_e32 v36, 16, v37
	v_and_b32_e32 v37, 0xffff0000, v37
	v_pk_mul_f32 v[38:39], v[60:61], v[38:39]
	v_mov_b32_e32 v73, v157
	v_pk_fma_f32 v[38:39], v[24:25], v[38:39], v[36:37]
	v_lshlrev_b32_e32 v36, 16, v52
	v_and_b32_e32 v37, 0xffff0000, v52
	v_mov_b32_e32 v50, v157
	v_mov_b32_dpp v73, v67 row_ror:8 row_mask:0xf bank_mask:0xf
	v_pk_mul_f32 v[36:37], v[32:33], v[36:37] op_sel_hi:[0,1]
	v_mov_b32_dpp v50, v55 row_ror:8 row_mask:0xf bank_mask:0xf
	v_cndmask_b32_e64 v55, v73, v55, s[0:1]
	v_lshlrev_b32_e32 v24, 16, v71
	v_and_b32_e32 v25, 0xffff0000, v71
	v_pk_mul_f32 v[36:37], v[56:57], v[36:37]
	v_cndmask_b32_e64 v53, v69, v53, s[0:1]
	v_pk_fma_f32 v[24:25], v[34:35], v[36:37], v[24:25]
	v_lshlrev_b32_e32 v36, 16, v55
	v_and_b32_e32 v37, 0xffff0000, v55
	v_pk_mul_f32 v[36:37], v[32:33], v[36:37] op_sel_hi:[0,1]
	v_lshlrev_b32_e32 v34, 16, v74
	v_and_b32_e32 v35, 0xffff0000, v74
	v_pk_mul_f32 v[36:37], v[62:63], v[36:37]
	v_cndmask_b32_e64 v50, v67, v50, s[0:1]
	v_pk_fma_f32 v[34:35], v[26:27], v[36:37], v[34:35]
	v_lshlrev_b32_e32 v36, 16, v53
	v_and_b32_e32 v37, 0xffff0000, v53
	v_pk_mul_f32 v[36:37], v[32:33], v[36:37] op_sel_hi:[0,1]
	v_lshlrev_b32_e32 v26, 16, v72
	v_and_b32_e32 v27, 0xffff0000, v72
	v_pk_mul_f32 v[36:37], v[58:59], v[36:37]
	v_mov_b32_e32 v54, v157
	v_pk_fma_f32 v[26:27], v[30:31], v[36:37], v[26:27]
	v_mov_b32_e32 v30, v157
	v_mov_b32_e32 v31, v157
	v_mov_b32_e32 v67, v157
	v_mov_b32_e32 v55, v157
	v_mov_b32_e32 v69, v157
	v_mov_b32_dpp v30, v26 row_ror:8 row_mask:0xf bank_mask:0xf
	v_mov_b32_dpp v31, v27 row_ror:8 row_mask:0xf bank_mask:0xf
	v_mov_b32_dpp v54, v38 row_ror:8 row_mask:0xf bank_mask:0xf
	v_mov_b32_dpp v67, v39 row_ror:8 row_mask:0xf bank_mask:0xf
	v_mov_b32_e32 v52, v157
	v_mov_b32_e32 v68, v157
	v_mov_b32_dpp v55, v34 row_ror:8 row_mask:0xf bank_mask:0xf
	v_mov_b32_dpp v69, v35 row_ror:8 row_mask:0xf bank_mask:0xf
	v_cndmask_b32_e64 v37, v35, v31, s[0:1]
	v_cndmask_b32_e64 v36, v34, v30, s[0:1]
	v_lshlrev_b32_e32 v30, 16, v66
	v_and_b32_e32 v31, 0xffff0000, v66
	v_mov_b32_dpp v52, v24 row_ror:8 row_mask:0xf bank_mask:0xf
	v_mov_b32_dpp v68, v25 row_ror:8 row_mask:0xf bank_mask:0xf
	v_cndmask_b32_e64 v27, v69, v27, s[0:1]
	v_cndmask_b32_e64 v26, v55, v26, s[0:1]
	v_cndmask_b32_e64 v25, v67, v25, s[0:1]
	v_cndmask_b32_e64 v24, v54, v24, s[0:1]
	v_pk_mul_f32 v[30:31], v[32:33], v[30:31] op_sel_hi:[0,1]
	global_store_dwordx4 v[28:29], v[24:27], off
	v_pk_mul_f32 v[30:31], v[44:45], v[30:31]
	v_cndmask_b32_e64 v35, v39, v68, s[0:1]
	v_lshlrev_b32_e32 v26, 16, v48
	v_and_b32_e32 v27, 0xffff0000, v48
	v_pk_fma_f32 v[26:27], v[16:17], v[30:31], v[26:27]
	v_lshlrev_b32_e32 v30, 16, v64
	v_and_b32_e32 v31, 0xffff0000, v64
	v_pk_mul_f32 v[30:31], v[32:33], v[30:31] op_sel_hi:[0,1]
	v_lshlrev_b32_e32 v16, 16, v33
	v_and_b32_e32 v17, 0xffff0000, v33
	v_pk_mul_f32 v[30:31], v[40:41], v[30:31]
	v_mov_b32_e32 v33, v157
	v_pk_fma_f32 v[16:17], v[20:21], v[30:31], v[16:17]
	v_lshlrev_b32_e32 v30, 16, v50
	v_and_b32_e32 v31, 0xffff0000, v50
	v_mov_b32_dpp v33, v16 row_ror:8 row_mask:0xf bank_mask:0xf
	v_pk_mul_f32 v[30:31], v[32:33], v[30:31] op_sel_hi:[0,1]
	v_add_co_u32_e32 v24, vcc, s45, v28
	v_lshlrev_b32_e32 v20, 16, v51
	v_and_b32_e32 v21, 0xffff0000, v51
	v_pk_mul_f32 v[30:31], v[46:47], v[30:31]
	v_cndmask_b32_e64 v34, v38, v52, s[0:1]
	v_addc_co_u32_e32 v25, vcc, 0, v29, vcc
	v_pk_fma_f32 v[20:21], v[18:19], v[30:31], v[20:21]
	v_lshlrev_b32_e32 v30, 16, v65
	v_and_b32_e32 v31, 0xffff0000, v65
	global_store_dwordx4 v[24:25], v[34:37], off
	v_pk_mul_f32 v[30:31], v[32:33], v[30:31] op_sel_hi:[0,1]
	v_mov_b32_e32 v38, v157
	v_mov_b32_e32 v34, v157
	v_mov_b32_e32 v35, v157
	v_mov_b32_e32 v37, v157
	v_mov_b32_dpp v34, v26 row_ror:8 row_mask:0xf bank_mask:0xf
	v_lshlrev_b32_e32 v18, 16, v49
	v_and_b32_e32 v19, 0xffff0000, v49
	v_pk_mul_f32 v[30:31], v[42:43], v[30:31]
	v_mov_b32_dpp v35, v27 row_ror:8 row_mask:0xf bank_mask:0xf
	v_mov_b32_e32 v36, v157
	v_mov_b32_dpp v37, v20 row_ror:8 row_mask:0xf bank_mask:0xf
	v_mov_b32_dpp v38, v21 row_ror:8 row_mask:0xf bank_mask:0xf
	v_pk_fma_f32 v[18:19], v[22:23], v[30:31], v[18:19]
	v_mov_b32_e32 v22, v157
	v_mov_b32_e32 v23, v157
	v_cndmask_b32_e64 v16, v34, v16, s[0:1]
	v_add_u32_e32 v34, 0xb0, v81
	v_mov_b32_dpp v36, v17 row_ror:8 row_mask:0xf bank_mask:0xf
	v_mov_b32_dpp v22, v18 row_ror:8 row_mask:0xf bank_mask:0xf
	v_mov_b32_dpp v23, v19 row_ror:8 row_mask:0xf bank_mask:0xf
	v_cndmask_b32_e64 v19, v38, v19, s[0:1]
	v_cndmask_b32_e64 v18, v37, v18, s[0:1]
	v_cndmask_b32_e64 v17, v35, v17, s[0:1]
	v_ashrrev_i32_e32 v35, 31, v34
	v_cndmask_b32_e64 v23, v21, v23, s[0:1]
	v_cndmask_b32_e64 v22, v20, v22, s[0:1]
	v_cndmask_b32_e64 v21, v27, v36, s[0:1]
	v_cndmask_b32_e64 v20, v26, v33, s[0:1]
	global_store_dwordx4 v[28:29], v[16:19], off offset:128
	global_store_dwordx4 v[24:25], v[20:23], off offset:128
	s_waitcnt vmcnt(4)
; __device__ __forceinline__ float bflo(unsigned w) { return __uint_as_float(w << 16); }
; __device__ __forceinline__ float bfhi(unsigned w) { return __uint_as_float(w & 0xffff0000u); }
;     const bool lo = fr < 8;
;     const int r1 = row - fr + (fr & 7), cb = col0 + (lo ? 0 : boff);
;     const u32x4 l1 = *(const u32x4*)(P + (size_t)r1 * ld + cb), l2 = *(const u32x4*)(P + (size_t)(r1 + 8) * ld + cb);
;     const u32x4 s1 = {dpp_ror8(l1.x), dpp_ror8(l1.y), dpp_ror8(l1.z), dpp_ror8(l1.w)}, s2 = {dpp_ror8(l2.x), dpp_ror8(l2.y), dpp_ror8(l2.z), dpp_ror8(l2.w)};
;     wA = lo ? l1 : s2; wB = lo ? s1 : l2;
; }
;     __device__ __forceinline__ void operator()(const f32x4 (&acc)[2][2][4][2], const Unit& u, int wr, int wc, int fr, int fq) const {
;     ...
;             for (int m = 0; m < 4; ++m) { const int row = row0 + ai * HALF + m * 16; const float ri = __builtin_amdgcn_rsqf(sse[row] * (1.f / D) + EPS);
;                 u32x4 rr[2], ee[2]; load_pair_lines(R, D, row, fr, col0, rr[0], rr[1], 32); load_pair_lines(E, D, row, fr, col0, ee[0], ee[1], 32);
;                 float* orow = OUT + (size_t)(row - fr + (fr & 7)) * D + col0 + (lo ? 0 : 4);
; #pragma unroll
;                 for (int bj = 0; bj < 2; ++bj) { const u32x4 rw = rr[bj], ew = ee[bj];
;                     const float r[8] = {bflo(rw.x), bfhi(rw.x), bflo(rw.y), bfhi(rw.y), bflo(rw.z), bfhi(rw.z), bflo(rw.w), bfhi(rw.w)};
;                     const float e[8] = {bflo(ew.x), bfhi(ew.x), bflo(ew.y), bfhi(ew.y), bflo(ew.z), bfhi(ew.z), bflo(ew.w), bfhi(ew.w)};
;                     float o[8];
; #pragma unroll
;                     for (int j = 0; j < 8; ++j) { const float a = acc[ai][bj][m][j >> 2][j & 3]; const float gg = gv[bj][j >> 2][j & 3];
;                         o[j] = r[j] + e[j] * ri * gg * __builtin_amdgcn_rcpf(1.f + __builtin_amdgcn_exp2f(-a * LOG2E)); }
;                     f32x4 o1, o2;
; #pragma unroll
;                     for (int j = 0; j < 4; ++j) { const unsigned a = __float_as_uint(o[j]), b = __float_as_uint(o[4 + j]); const unsigned sa = dpp_ror8(a), sb = dpp_ror8(b);
;                         o1[j] = __uint_as_float(lo ? a : sb); o2[j] = __uint_as_float(lo ? sa : b); }
;                     *(f32x4*)(orow + 32 * bj) = o1; *(f32x4*)(orow + (size_t)8 * D + 32 * bj) = o2; } }
	s_nop 0
	v_mov_b32_e32 v36, v228
	v_lshlrev_b64 v[16:17], 12, v[34:35]
	v_lshl_add_u64 v[30:31], v[16:17], 0, s[16:17]
	v_lshl_add_u64 v[22:23], s[8:9], 0, v[30:31]
	v_lshl_add_u64 v[18:19], s[8:9], 0, v[16:17]
	v_lshl_add_u64 v[22:23], v[22:23], 0, v[164:165]
	v_lshl_add_u64 v[16:17], s[10:11], 0, v[16:17]
	v_lshl_add_u64 v[18:19], v[18:19], 0, v[164:165]
	v_mov_b64_e32 v[22:23], v[232:233]
	v_mov_b64_e32 v[24:25], v[234:235]
	v_lshl_add_u64 v[16:17], v[16:17], 0, v[164:165]
	v_mov_b64_e32 v[18:19], v[236:237]
	v_mov_b64_e32 v[20:21], v[238:239]
	v_mov_b32_e32 v49, v157
	v_mov_b64_e32 v[26:27], v[240:241]
	v_mov_b64_e32 v[28:29], v[242:243]
	v_lshl_add_u64 v[16:17], s[10:11], 0, v[30:31]
	v_lshl_add_u64 v[16:17], v[16:17], 0, v[164:165]
	v_mov_b64_e32 v[30:31], v[244:245]
	v_mov_b64_e32 v[32:33], v[246:247]
	s_nop 1
	v_mov_b32_e32 v50, v157
	v_mov_b32_e32 v17, v157
	v_mov_b32_e32 v37, v157
	v_mov_b32_e32 v38, v157
	v_mov_b32_e32 v48, v157
	v_mov_b32_e32 v39, v157
	v_add_f32_e32 v5, 1.0, v5
	v_exp_f32_e32 v2, v2
	v_exp_f32_e32 v3, v3
	v_rcp_f32_e32 v4, v4
	v_rcp_f32_e32 v5, v5
	v_mul_f32_e32 v6, 0xbfb8aa3b, v6
	v_mul_f32_e32 v7, 0xbfb8aa3b, v7
	v_exp_f32_e32 v6, v6
	v_exp_f32_e32 v7, v7
	v_add_f32_e32 v2, 1.0, v2
	v_add_f32_e32 v3, 1.0, v3
	v_rcp_f32_e32 v2, v2
	v_rcp_f32_e32 v3, v3
	v_add_f32_e32 v6, 1.0, v6
	v_add_f32_e32 v7, 1.0, v7
	v_rcp_f32_e32 v6, v6
	v_rcp_f32_e32 v7, v7
	s_mov_b32 s53, s18
	s_mov_b32 s30, s22
	s_mov_b64 s[36:37], s[28:29]
	s_mov_b64 s[34:35], s[24:25]
	v_fmamk_f32 v16, v36, 0x3a000000, v182
	v_mov_b32_e32 v36, v157
	v_rsq_f32_e32 v16, v16
	v_mov_b32_dpp v49, v24 row_ror:8 row_mask:0xf bank_mask:0xf
	v_mov_b32_dpp v50, v25 row_ror:8 row_mask:0xf bank_mask:0xf
	v_mov_b32_dpp v17, v18 row_ror:8 row_mask:0xf bank_mask:0xf
	v_mov_b32_dpp v36, v19 row_ror:8 row_mask:0xf bank_mask:0xf
	v_mov_b32_dpp v37, v20 row_ror:8 row_mask:0xf bank_mask:0xf
	v_mov_b32_dpp v38, v21 row_ror:8 row_mask:0xf bank_mask:0xf
	v_mov_b32_dpp v48, v23 row_ror:8 row_mask:0xf bank_mask:0xf
	v_cndmask_b32_e64 v50, v50, v21, s[0:1]
	v_cndmask_b32_e64 v21, v49, v20, s[0:1]
	v_mov_b32_e32 v20, v157
	v_mov_b32_dpp v39, v22 row_ror:8 row_mask:0xf bank_mask:0xf
	v_cndmask_b32_e64 v48, v48, v19, s[0:1]
	v_cndmask_b32_e64 v36, v23, v36, s[0:1]
	v_cndmask_b32_e64 v25, v25, v38, s[0:1]
	v_cndmask_b32_e64 v17, v22, v17, s[0:1]
	v_mov_b32_e32 v19, v157
	v_mov_b32_dpp v20, v28 row_ror:8 row_mask:0xf bank_mask:0xf
	v_mov_b32_e32 v22, v157
	v_mov_b32_e32 v23, v157
	v_mov_b32_e32 v38, v157
	v_cndmask_b32_e64 v39, v39, v18, s[0:1]
	v_cndmask_b32_e64 v24, v24, v37, s[0:1]
	v_mov_b32_e32 v18, v157
	v_mov_b32_dpp v19, v27 row_ror:8 row_mask:0xf bank_mask:0xf
	v_mov_b32_dpp v22, v29 row_ror:8 row_mask:0xf bank_mask:0xf
	v_mov_b32_dpp v23, v30 row_ror:8 row_mask:0xf bank_mask:0xf
	v_mov_b32_e32 v37, v157
	v_mov_b32_dpp v38, v32 row_ror:8 row_mask:0xf bank_mask:0xf
	v_cndmask_b32_e64 v32, v32, v20, s[0:1]
	v_exp_f32_e32 v20, v12
	v_mul_f32_e32 v12, 0xbfb8aa3b, v13
	v_mov_b32_dpp v18, v26 row_ror:8 row_mask:0xf bank_mask:0xf
	v_mov_b32_dpp v37, v31 row_ror:8 row_mask:0xf bank_mask:0xf
	v_cndmask_b32_e64 v26, v23, v26, s[0:1]
	v_cndmask_b32_e64 v23, v38, v28, s[0:1]
	v_cndmask_b32_e64 v28, v31, v19, s[0:1]
	v_cndmask_b32_e64 v31, v33, v22, s[0:1]
	v_exp_f32_e32 v22, v12
	v_cndmask_b32_e64 v30, v30, v18, s[0:1]
	v_lshlrev_b64 v[18:19], 13, v[34:35]
	v_lshl_add_u64 v[18:19], s[4:5], 0, v[18:19]
	v_lshl_add_u64 v[18:19], v[18:19], 0, v[166:167]
	v_lshl_add_u64 v[12:13], v[18:19], 0, v[156:157]
	v_add_f32_e32 v19, 1.0, v22
	v_lshlrev_b32_e32 v22, 16, v23
	v_and_b32_e32 v23, 0xffff0000, v23
	v_add_f32_e32 v18, 1.0, v20
	v_pk_mul_f32 v[22:23], v[16:17], v[22:23] op_sel_hi:[0,1]
	v_rcp_f32_e32 v18, v18
	v_rcp_f32_e32 v19, v19
	v_lshlrev_b32_e32 v20, 16, v21
	v_and_b32_e32 v21, 0xffff0000, v21
	v_pk_mul_f32 v[22:23], v[60:61], v[22:23]
	v_mov_b32_e32 v49, v157
	v_pk_fma_f32 v[22:23], v[8:9], v[22:23], v[20:21]
	v_lshlrev_b32_e32 v20, 16, v26
	v_and_b32_e32 v21, 0xffff0000, v26
	v_mov_b32_dpp v49, v33 row_ror:8 row_mask:0xf bank_mask:0xf
	v_pk_mul_f32 v[20:21], v[16:17], v[20:21] op_sel_hi:[0,1]
	v_cndmask_b32_e64 v29, v49, v29, s[0:1]
	v_lshlrev_b32_e32 v8, 16, v39
	v_and_b32_e32 v9, 0xffff0000, v39
; __device__ __forceinline__ float bflo(unsigned w) { return __uint_as_float(w << 16); }
; __device__ __forceinline__ float bfhi(unsigned w) { return __uint_as_float(w & 0xffff0000u); }
; __device__ __forceinline__ unsigned dpp_ror8(unsigned x) { return (unsigned)__builtin_amdgcn_update_dpp(0, (int)x, 0x128, 0xf, 0xf, false); }
; #define PG8_WAIT_V(n) asm volatile("s_waitcnt vmcnt(" #n ")" ::: "memory")
; #define PG8_BAR __builtin_amdgcn_s_barrier()
;     __device__ __forceinline__ void operator()(const f32x4 (&acc)[2][2][4][2], const Unit& u, int wr, int wc, int fr, int fq) const {
;     ...
;                 for (int bj = 0; bj < 2; ++bj) { const u32x4 rw = rr[bj], ew = ee[bj];
;                     const float r[8] = {bflo(rw.x), bfhi(rw.x), bflo(rw.y), bfhi(rw.y), bflo(rw.z), bfhi(rw.z), bflo(rw.w), bfhi(rw.w)};
;                     const float e[8] = {bflo(ew.x), bfhi(ew.x), bflo(ew.y), bfhi(ew.y), bflo(ew.z), bfhi(ew.z), bflo(ew.w), bfhi(ew.w)};
;                     float o[8];
; #pragma unroll
;                     for (int j = 0; j < 8; ++j) { const float a = acc[ai][bj][m][j >> 2][j & 3]; const float gg = gv[bj][j >> 2][j & 3];
;                         o[j] = r[j] + e[j] * ri * gg * __builtin_amdgcn_rcpf(1.f + __builtin_amdgcn_exp2f(-a * LOG2E)); }
;                     f32x4 o1, o2;
; #pragma unroll
;                     for (int j = 0; j < 4; ++j) { const unsigned a = __float_as_uint(o[j]), b = __float_as_uint(o[4 + j]); const unsigned sa = dpp_ror8(a), sb = dpp_ror8(b);
;                         o1[j] = __uint_as_float(lo ? a : sb); o2[j] = __uint_as_float(lo ? sa : b); }
;                     *(f32x4*)(orow + 32 * bj) = o1; *(f32x4*)(orow + (size_t)8 * D + 32 * bj) = o2; } }
; template <class Epi>
; __device__ __forceinline__ void gemm_phase(LAS unsigned char* lds, const Gemm g, const StaticOrder& S, const Epi& E) {
;     ...
;     PG8_WAIT_V(0);
;     if (wr == 0) PG8_BAR;
;     PG8_BAR;
	v_pk_mul_f32 v[20:21], v[56:57], v[20:21]
	v_cndmask_b32_e64 v27, v37, v27, s[0:1]
	v_pk_fma_f32 v[8:9], v[18:19], v[20:21], v[8:9]
	v_lshlrev_b32_e32 v20, 16, v29
	v_and_b32_e32 v21, 0xffff0000, v29
	v_pk_mul_f32 v[20:21], v[16:17], v[20:21] op_sel_hi:[0,1]
	v_lshlrev_b32_e32 v18, 16, v50
	v_and_b32_e32 v19, 0xffff0000, v50
	v_pk_mul_f32 v[20:21], v[62:63], v[20:21]
	v_mov_b32_e32 v33, v157
	v_pk_fma_f32 v[18:19], v[10:11], v[20:21], v[18:19]
	v_lshlrev_b32_e32 v20, 16, v27
	v_and_b32_e32 v21, 0xffff0000, v27
	v_pk_mul_f32 v[20:21], v[16:17], v[20:21] op_sel_hi:[0,1]
	v_lshlrev_b32_e32 v10, 16, v48
	v_and_b32_e32 v11, 0xffff0000, v48
	v_pk_mul_f32 v[20:21], v[58:59], v[20:21]
	v_mov_b32_e32 v34, v157
	v_pk_fma_f32 v[10:11], v[14:15], v[20:21], v[10:11]
	v_mov_b32_e32 v14, v157
	v_mov_b32_e32 v15, v157
	v_mov_b32_e32 v29, v157
	v_mov_b32_e32 v37, v157
	v_mov_b32_dpp v14, v10 row_ror:8 row_mask:0xf bank_mask:0xf
	v_mov_b32_dpp v15, v11 row_ror:8 row_mask:0xf bank_mask:0xf
	v_mov_b32_dpp v33, v22 row_ror:8 row_mask:0xf bank_mask:0xf
	v_mov_b32_dpp v34, v23 row_ror:8 row_mask:0xf bank_mask:0xf
	v_mov_b32_e32 v26, v157
	v_mov_b32_e32 v35, v157
	v_mov_b32_dpp v29, v18 row_ror:8 row_mask:0xf bank_mask:0xf
	v_mov_b32_dpp v37, v19 row_ror:8 row_mask:0xf bank_mask:0xf
	v_cndmask_b32_e64 v21, v19, v15, s[0:1]
	v_cndmask_b32_e64 v20, v18, v14, s[0:1]
	v_lshlrev_b32_e32 v14, 16, v32
	v_and_b32_e32 v15, 0xffff0000, v32
	v_mov_b32_dpp v26, v8 row_ror:8 row_mask:0xf bank_mask:0xf
	v_mov_b32_dpp v35, v9 row_ror:8 row_mask:0xf bank_mask:0xf
	v_cndmask_b32_e64 v11, v37, v11, s[0:1]
	v_cndmask_b32_e64 v10, v29, v10, s[0:1]
	v_cndmask_b32_e64 v9, v34, v9, s[0:1]
	v_cndmask_b32_e64 v8, v33, v8, s[0:1]
	v_pk_mul_f32 v[14:15], v[16:17], v[14:15] op_sel_hi:[0,1]
	global_store_dwordx4 v[12:13], v[8:11], off
	v_pk_mul_f32 v[14:15], v[44:45], v[14:15]
	v_cndmask_b32_e64 v19, v23, v35, s[0:1]
	v_lshlrev_b32_e32 v10, 16, v24
	v_and_b32_e32 v11, 0xffff0000, v24
	v_pk_fma_f32 v[10:11], v[0:1], v[14:15], v[10:11]
	v_lshlrev_b32_e32 v14, 16, v30
	v_and_b32_e32 v15, 0xffff0000, v30
	v_pk_mul_f32 v[14:15], v[16:17], v[14:15] op_sel_hi:[0,1]
	v_lshlrev_b32_e32 v0, 16, v17
	v_and_b32_e32 v1, 0xffff0000, v17
	v_pk_mul_f32 v[14:15], v[40:41], v[14:15]
	v_mov_b32_e32 v17, v157
	v_pk_fma_f32 v[0:1], v[4:5], v[14:15], v[0:1]
	v_lshlrev_b32_e32 v14, 16, v31
	v_and_b32_e32 v15, 0xffff0000, v31
	v_mov_b32_dpp v17, v0 row_ror:8 row_mask:0xf bank_mask:0xf
	v_pk_mul_f32 v[14:15], v[16:17], v[14:15] op_sel_hi:[0,1]
	v_lshlrev_b32_e32 v4, 16, v25
	v_and_b32_e32 v5, 0xffff0000, v25
	v_pk_mul_f32 v[14:15], v[46:47], v[14:15]
	v_add_co_u32_e32 v8, vcc, s45, v12
	v_pk_fma_f32 v[4:5], v[2:3], v[14:15], v[4:5]
	v_lshlrev_b32_e32 v14, 16, v28
	v_and_b32_e32 v15, 0xffff0000, v28
	v_cndmask_b32_e64 v18, v22, v26, s[0:1]
	v_addc_co_u32_e32 v9, vcc, 0, v13, vcc
	v_pk_mul_f32 v[14:15], v[16:17], v[14:15] op_sel_hi:[0,1]
	global_store_dwordx4 v[8:9], v[18:21], off
	v_mov_b32_e32 v22, v157
	v_lshlrev_b32_e32 v2, 16, v36
	v_mov_b32_e32 v18, v157
	v_mov_b32_e32 v19, v157
	v_mov_b32_e32 v21, v157
	v_and_b32_e32 v3, 0xffff0000, v36
	v_pk_mul_f32 v[14:15], v[42:43], v[14:15]
	v_mov_b32_dpp v18, v10 row_ror:8 row_mask:0xf bank_mask:0xf
	v_mov_b32_dpp v19, v11 row_ror:8 row_mask:0xf bank_mask:0xf
	v_mov_b32_e32 v20, v157
	v_mov_b32_dpp v21, v4 row_ror:8 row_mask:0xf bank_mask:0xf
	v_mov_b32_dpp v22, v5 row_ror:8 row_mask:0xf bank_mask:0xf
	v_pk_fma_f32 v[2:3], v[6:7], v[14:15], v[2:3]
	v_mov_b32_e32 v6, v157
	v_mov_b32_e32 v7, v157
	v_mov_b32_dpp v20, v1 row_ror:8 row_mask:0xf bank_mask:0xf
	v_mov_b32_dpp v6, v2 row_ror:8 row_mask:0xf bank_mask:0xf
	v_mov_b32_dpp v7, v3 row_ror:8 row_mask:0xf bank_mask:0xf
	v_cndmask_b32_e64 v3, v22, v3, s[0:1]
	v_cndmask_b32_e64 v2, v21, v2, s[0:1]
	v_cndmask_b32_e64 v1, v19, v1, s[0:1]
	v_cndmask_b32_e64 v0, v18, v0, s[0:1]
	s_and_b64 vcc, exec, s[26:27]
	v_cndmask_b32_e64 v7, v5, v7, s[0:1]
	v_cndmask_b32_e64 v6, v4, v6, s[0:1]
	v_cndmask_b32_e64 v5, v11, v20, s[0:1]
	v_cndmask_b32_e64 v4, v10, v17, s[0:1]
	global_store_dwordx4 v[12:13], v[0:3], off offset:128
	global_store_dwordx4 v[8:9], v[4:7], off offset:128
	s_cbranch_vccz .LBB0_1595
	s_waitcnt vmcnt(0)
	s_cmpk_gt_u32 s3, 0xff
	s_cbranch_scc1 .LBB0_1607
	s_barrier
